# same as previous plus s_nop 0 re-inserted at the 34 sites where a deletion made a packed producer (op_sel_hi[0]=1) and its consumer adjacent (compiler dst-forwarding pad rule)
# baseline (speedup 1.0000x reference)
.LBB0_134:
	global_load_dword v6, v[22:23], off
	v_lshrrev_b32_e32 v26, 2, v11
	v_add_u32_e32 v25, 0x200, v25
	v_and_b32_e32 v26, 0x3ffffff8, v26
	v_cmp_lt_u32_e32 vcc, s34, v25
	v_add_u32_e32 v11, 8, v11
	v_lshl_add_u64 v[22:23], v[22:23], 0, s[26:27]
	v_add_u32_e32 v26, v24, v26
	v_add_u32_e32 v24, 64, v24
	s_or_b64 s[62:63], vcc, s[62:63]
	s_waitcnt vmcnt(0)
	ds_write_b64 v26, v[6:7]
	s_andn2_b64 exec, exec, s[62:63]
	s_cbranch_execnz .LBB0_134
	s_or_b64 exec, exec, s[62:63]
	v_mov_b32_e32 v6, v62
	s_waitcnt lgkmcnt(0)
	s_barrier
	s_mov_b32 s43, s40
	v_and_b32_e32 v11, 15, v6
	v_cvt_f32_ubyte0_e32 v22, v11
	v_mul_f32_e32 v23, 0x3b800000, v22
	v_sin_f32_e32 v22, v23
	v_cos_f32_e32 v24, v23
	v_lshlrev_b32_e32 v6, 4, v6
	v_and_b32_e32 v6, 0xffffff00, v6
	v_xor_b32_e32 v25, 0x80000000, v22
	v_mov_b32_e32 v23, v25
	v_pk_mul_f32 v[26:27], v[24:25], v[22:23] op_sel:[1,0] op_sel_hi:[0,1]
	v_pk_fma_f32 v[26:27], v[24:25], v[24:25], v[26:27] op_sel_hi:[1,0,1]
	v_lshlrev_b32_e32 v11, 3, v11
	v_xor_b32_e32 v32, 0x80000000, v27
	v_mov_b32_e32 v33, v27
	v_pk_mul_f32 v[30:31], v[26:27], v[32:33] op_sel:[1,0] op_sel_hi:[0,1]
	v_pk_fma_f32 v[30:31], v[26:27], v[26:27], v[30:31] op_sel_hi:[1,0,1]
	v_pk_mul_f32 v[28:29], v[22:23], v[26:27] op_sel:[0,1] op_sel_hi:[1,0]
	v_xor_b32_e32 v34, 0x80000000, v31
	v_mov_b32_e32 v35, v31
	v_pk_mul_f32 v[50:51], v[30:31], v[34:35] op_sel:[1,0] op_sel_hi:[0,1]
	v_pk_fma_f32 v[50:51], v[30:31], v[30:31], v[50:51] op_sel_hi:[1,0,1]
	v_pk_mul_f32 v[36:37], v[22:23], v[30:31] op_sel:[0,1] op_sel_hi:[1,0]
	v_pk_mul_f32 v[70:71], v[34:35], v[50:51] op_sel:[0,1] op_sel_hi:[1,0]
	v_pk_mul_f32 v[54:55], v[22:23], v[50:51] op_sel:[0,1] op_sel_hi:[1,0]
	v_pk_fma_f32 v[70:71], v[30:31], v[50:51], v[70:71] op_sel_hi:[0,1,1]
	v_pk_mul_f32 v[74:75], v[22:23], v[70:71] op_sel:[0,1] op_sel_hi:[1,0]
	v_pk_fma_f32 v[28:29], v[24:25], v[26:27], v[28:29] op_sel_hi:[0,1,1]
	v_pk_fma_f32 v[36:37], v[24:25], v[30:31], v[36:37] op_sel_hi:[0,1,1]
	v_pk_fma_f32 v[54:55], v[24:25], v[50:51], v[54:55] op_sel_hi:[0,1,1]
	v_pk_fma_f32 v[74:75], v[24:25], v[70:71], v[74:75] op_sel_hi:[0,1,1]
	v_lshlrev_b32_e32 v25, 3, v6
	v_add3_u32 v11, 0, v11, v25
	v_ashrrev_i32_e32 v25, 2, v6
	v_add_u32_e32 v25, v11, v25
	ds_read2_b64 v[92:95], v25 offset1:16
	ds_read2_b64 v[96:99], v25 offset0:33 offset1:49
	ds_read2_b64 v[100:103], v25 offset0:66 offset1:82
	ds_read2_b64 v[104:107], v25 offset0:132 offset1:148
	ds_read2_b64 v[108:111], v25 offset0:99 offset1:115
	ds_read2_b64 v[112:115], v25 offset0:165 offset1:181
	ds_read2_b64 v[116:119], v25 offset0:198 offset1:214
	ds_read2_b64 v[120:123], v25 offset0:231 offset1:247
	s_waitcnt lgkmcnt(4)
	v_pk_add_f32 v[124:125], v[92:93], v[104:105]
	v_pk_add_f32 v[92:93], v[92:93], v[104:105] neg_lo:[0,1] neg_hi:[0,1]
	v_pk_add_f32 v[104:105], v[94:95], v[106:107]
	v_pk_add_f32 v[94:95], v[94:95], v[106:107] neg_lo:[0,1] neg_hi:[0,1]
	s_mov_b32 s45, s36
	v_pk_mul_f32 v[106:107], v[94:95], s[38:39]
	s_waitcnt lgkmcnt(1)
	v_pk_add_f32 v[126:127], v[102:103], v[118:119]
	v_pk_fma_f32 v[94:95], v[94:95], s[36:37], v[106:107] op_sel:[0,0,1] op_sel_hi:[1,0,0]
	v_pk_add_f32 v[106:107], v[96:97], v[112:113]
	v_pk_add_f32 v[96:97], v[96:97], v[112:113] neg_lo:[0,1] neg_hi:[0,1]
	v_pk_add_f32 v[102:103], v[102:103], v[118:119] neg_lo:[0,1] neg_hi:[0,1]
	v_pk_mul_f32 v[112:113], v[96:97], s[42:43]
	s_mov_b32 s62, s39
	v_pk_mul_f32 v[118:119], v[102:103], s[44:45]
	v_pk_fma_f32 v[96:97], v[96:97], s[40:41], v[112:113] op_sel:[0,0,1] op_sel_hi:[1,0,0]
	v_pk_add_f32 v[112:113], v[98:99], v[114:115]
	v_pk_add_f32 v[98:99], v[98:99], v[114:115] neg_lo:[0,1] neg_hi:[0,1]
	v_pk_fma_f32 v[102:103], v[102:103], s[62:63], v[118:119] op_sel:[0,0,1] op_sel_hi:[1,0,0] neg_lo:[1,0,0] neg_hi:[1,0,0]
	s_waitcnt lgkmcnt(0)
	v_pk_add_f32 v[118:119], v[108:109], v[120:121]
	v_pk_add_f32 v[108:109], v[108:109], v[120:121] neg_lo:[0,1] neg_hi:[0,1]
	v_pk_mul_f32 v[114:115], v[98:99], s[44:45]
	v_pk_mul_f32 v[120:121], v[108:109], s[42:43]
	v_pk_fma_f32 v[98:99], v[98:99], s[62:63], v[114:115] op_sel:[0,0,1] op_sel_hi:[1,0,0]
	v_pk_add_f32 v[114:115], v[100:101], v[116:117]
	v_pk_add_f32 v[116:117], v[100:101], v[116:117] neg_lo:[0,1] neg_hi:[0,1]
	v_pk_fma_f32 v[108:109], v[108:109], s[40:41], v[120:121] op_sel:[0,0,1] op_sel_hi:[1,0,0] neg_lo:[1,0,0] neg_hi:[1,0,0]
	v_pk_add_f32 v[120:121], v[110:111], v[122:123]
	v_pk_add_f32 v[110:111], v[110:111], v[122:123] neg_lo:[0,1] neg_hi:[0,1]
	s_nop 0
	v_pk_mul_f32 v[122:123], v[110:111], s[38:39]
	s_nop 0
	v_pk_fma_f32 v[110:111], v[110:111], s[36:37], v[122:123] op_sel:[0,0,1] op_sel_hi:[1,0,0] neg_lo:[1,0,0] neg_hi:[1,0,0]
	v_pk_add_f32 v[122:123], v[124:125], v[114:115]
	v_pk_add_f32 v[114:115], v[124:125], v[114:115] neg_lo:[0,1] neg_hi:[0,1]
	v_pk_add_f32 v[124:125], v[104:105], v[126:127]
	v_pk_add_f32 v[104:105], v[104:105], v[126:127] neg_lo:[0,1] neg_hi:[0,1]
	v_pk_add_f32 v[128:129], v[112:113], v[120:121]
	v_pk_add_f32 v[112:113], v[112:113], v[120:121] neg_lo:[0,1] neg_hi:[0,1]
	v_pk_add_f32 v[100:101], v[92:93], v[116:117] op_sel:[0,1] op_sel_hi:[1,0] neg_hi:[0,1]
	v_pk_add_f32 v[92:93], v[92:93], v[116:117] op_sel:[0,1] op_sel_hi:[1,0] neg_lo:[0,1]
	v_pk_add_f32 v[116:117], v[94:95], v[102:103]
	v_pk_add_f32 v[94:95], v[94:95], v[102:103] neg_lo:[0,1] neg_hi:[0,1]
	v_pk_mul_f32 v[126:127], v[104:105], s[42:43]
	v_pk_mul_f32 v[120:121], v[112:113], s[42:43]
	v_pk_mul_f32 v[102:103], v[94:95], s[42:43]
	v_pk_fma_f32 v[104:105], v[104:105], s[40:41], v[126:127] op_sel:[0,0,1] op_sel_hi:[1,0,0]
	v_pk_add_f32 v[126:127], v[106:107], v[118:119]
	v_pk_add_f32 v[118:119], v[106:107], v[118:119] neg_lo:[0,1] neg_hi:[0,1]
	v_pk_fma_f32 v[112:113], v[112:113], s[40:41], v[120:121] op_sel:[0,0,1] op_sel_hi:[1,0,0] neg_lo:[1,0,0] neg_hi:[1,0,0]
	v_pk_fma_f32 v[94:95], v[94:95], s[40:41], v[102:103] op_sel:[0,0,1] op_sel_hi:[1,0,0]
	v_pk_add_f32 v[102:103], v[96:97], v[108:109]
	v_pk_add_f32 v[120:121], v[98:99], v[110:111]
	v_pk_add_f32 v[98:99], v[98:99], v[110:111] neg_lo:[0,1] neg_hi:[0,1]
	v_pk_add_f32 v[96:97], v[96:97], v[108:109] neg_lo:[0,1] neg_hi:[0,1]
	v_pk_mul_f32 v[110:111], v[98:99], s[42:43]
	v_pk_add_f32 v[130:131], v[100:101], v[102:103]
	v_pk_add_f32 v[100:101], v[100:101], v[102:103] neg_lo:[0,1] neg_hi:[0,1]
	v_pk_add_f32 v[102:103], v[116:117], v[120:121]
	v_pk_add_f32 v[120:121], v[116:117], v[120:121] neg_lo:[0,1] neg_hi:[0,1]
	v_xor_b32_e32 v38, 0x80000000, v29
	v_mov_b32_e32 v39, v29
	v_pk_mul_f32 v[42:43], v[32:33], v[30:31] op_sel:[0,1] op_sel_hi:[1,0]
	v_xor_b32_e32 v109, 0x80000000, v96
	v_pk_fma_f32 v[98:99], v[98:99], s[40:41], v[110:111] op_sel:[0,0,1] op_sel_hi:[1,0,0] neg_lo:[1,0,0] neg_hi:[1,0,0]
	v_pk_add_f32 v[106:107], v[114:115], v[118:119] op_sel:[0,1] op_sel_hi:[1,0] neg_hi:[0,1]
	v_pk_add_f32 v[114:115], v[114:115], v[118:119] op_sel:[0,1] op_sel_hi:[1,0] neg_lo:[0,1]
	v_pk_add_f32 v[118:119], v[104:105], v[112:113]
	v_pk_add_f32 v[112:113], v[104:105], v[112:113] neg_lo:[0,1] neg_hi:[0,1]
	v_mov_b32_e32 v108, v97
	v_xor_b32_e32 v40, 0x80000000, v37
	v_mov_b32_e32 v41, v37
	v_pk_fma_f32 v[42:43], v[26:27], v[30:31], v[42:43] op_sel_hi:[0,1,1]
	v_pk_mul_f32 v[46:47], v[30:31], v[38:39] op_sel:[1,0] op_sel_hi:[0,1]
	v_pk_add_f32 v[96:97], v[92:93], v[108:109]
	v_pk_add_f32 v[92:93], v[92:93], v[108:109] neg_lo:[0,1] neg_hi:[0,1]
	v_pk_add_f32 v[108:109], v[94:95], v[98:99]
	v_pk_add_f32 v[98:99], v[94:95], v[98:99] neg_lo:[0,1] neg_hi:[0,1]
	v_pk_add_f32 v[116:117], v[100:101], v[120:121] op_sel:[0,1] op_sel_hi:[1,0] neg_hi:[0,1]
	v_xor_b32_e32 v44, 0x80000000, v43
	v_mov_b32_e32 v45, v43
	v_pk_fma_f32 v[46:47], v[30:31], v[28:29], v[46:47] op_sel_hi:[1,0,1]
	v_pk_add_f32 v[104:105], v[114:115], v[112:113] op_sel:[0,1] op_sel_hi:[1,0] neg_hi:[0,1]
	v_pk_add_f32 v[100:101], v[100:101], v[120:121] op_sel:[0,1] op_sel_hi:[1,0] neg_lo:[0,1]
	v_pk_mul_f32 v[120:121], v[40:41], v[116:117] op_sel:[0,1] op_sel_hi:[1,0]
	v_xor_b32_e32 v48, 0x80000000, v47
	v_mov_b32_e32 v49, v47
	v_pk_add_f32 v[110:111], v[122:123], v[126:127]
	v_pk_add_f32 v[122:123], v[122:123], v[126:127] neg_lo:[0,1] neg_hi:[0,1]
	v_pk_add_f32 v[126:127], v[124:125], v[128:129]
	v_pk_add_f32 v[94:95], v[92:93], v[98:99] op_sel:[0,1] op_sel_hi:[1,0] neg_hi:[0,1]
	v_pk_fma_f32 v[116:117], v[36:37], v[116:117], v[120:121] op_sel_hi:[0,1,1]
	v_pk_mul_f32 v[120:121], v[44:45], v[104:105] op_sel:[0,1] op_sel_hi:[1,0]
	v_xor_b32_e32 v52, 0x80000000, v51
	v_mov_b32_e32 v53, v51
	v_pk_mul_f32 v[58:59], v[32:33], v[50:51] op_sel:[0,1] op_sel_hi:[1,0]
	v_pk_add_f32 v[132:133], v[110:111], v[126:127]
	v_pk_add_f32 v[110:111], v[110:111], v[126:127] neg_lo:[0,1] neg_hi:[0,1]
	v_pk_fma_f32 v[104:105], v[42:43], v[104:105], v[120:121] op_sel_hi:[0,1,1]
	v_pk_mul_f32 v[120:121], v[48:49], v[94:95] op_sel:[0,1] op_sel_hi:[1,0]
	v_xor_b32_e32 v56, 0x80000000, v55
	v_mov_b32_e32 v57, v55
	v_pk_fma_f32 v[58:59], v[26:27], v[50:51], v[58:59] op_sel_hi:[0,1,1]
	v_pk_mul_f32 v[66:67], v[38:39], v[50:51] op_sel:[0,1] op_sel_hi:[1,0]
	v_pk_add_f32 v[112:113], v[114:115], v[112:113] op_sel:[0,1] op_sel_hi:[1,0] neg_lo:[0,1]
	v_pk_add_f32 v[114:115], v[130:131], v[102:103]
	v_pk_add_f32 v[102:103], v[130:131], v[102:103] neg_lo:[0,1] neg_hi:[0,1]
	v_pk_fma_f32 v[94:95], v[46:47], v[94:95], v[120:121] op_sel_hi:[0,1,1]
	v_pk_mul_f32 v[120:121], v[52:53], v[110:111] op_sel:[0,1] op_sel_hi:[1,0]
	v_xor_b32_e32 v60, 0x80000000, v59
	v_mov_b32_e32 v61, v59
	v_pk_fma_f32 v[66:67], v[28:29], v[50:51], v[66:67] op_sel_hi:[0,1,1]
	v_pk_add_f32 v[128:129], v[124:125], v[128:129] neg_lo:[0,1] neg_hi:[0,1]
	v_pk_add_f32 v[126:127], v[106:107], v[118:119]
	v_pk_add_f32 v[106:107], v[106:107], v[118:119] neg_lo:[0,1] neg_hi:[0,1]
	v_pk_fma_f32 v[110:111], v[50:51], v[110:111], v[120:121] op_sel_hi:[0,1,1]
	v_pk_mul_f32 v[120:121], v[56:57], v[102:103] op_sel:[0,1] op_sel_hi:[1,0]
	v_xor_b32_e32 v68, 0x80000000, v67
	v_mov_b32_e32 v69, v67
	v_pk_add_f32 v[118:119], v[96:97], v[108:109]
	v_pk_add_f32 v[96:97], v[96:97], v[108:109] neg_lo:[0,1] neg_hi:[0,1]
	v_pk_fma_f32 v[102:103], v[54:55], v[102:103], v[120:121] op_sel_hi:[0,1,1]
	v_pk_mul_f32 v[120:121], v[60:61], v[106:107] op_sel:[0,1] op_sel_hi:[1,0]
	v_xor_b32_e32 v72, 0x80000000, v71
	v_mov_b32_e32 v73, v71
	v_pk_mul_f32 v[78:79], v[32:33], v[70:71] op_sel:[0,1] op_sel_hi:[1,0]
	v_pk_add_f32 v[124:125], v[122:123], v[128:129] op_sel:[0,1] op_sel_hi:[1,0] neg_hi:[0,1]
	v_pk_add_f32 v[122:123], v[122:123], v[128:129] op_sel:[0,1] op_sel_hi:[1,0] neg_lo:[0,1]
	v_pk_fma_f32 v[106:107], v[58:59], v[106:107], v[120:121] op_sel_hi:[0,1,1]
	v_pk_mul_f32 v[120:121], v[68:69], v[96:97] op_sel:[0,1] op_sel_hi:[1,0]
	v_xor_b32_e32 v76, 0x80000000, v75
	v_mov_b32_e32 v77, v75
	v_pk_fma_f32 v[78:79], v[26:27], v[70:71], v[78:79] op_sel_hi:[0,1,1]
	v_pk_mul_f32 v[82:83], v[38:39], v[70:71] op_sel:[0,1] op_sel_hi:[1,0]
	v_pk_fma_f32 v[96:97], v[66:67], v[96:97], v[120:121] op_sel_hi:[0,1,1]
	v_pk_mul_f32 v[120:121], v[72:73], v[122:123] op_sel:[0,1] op_sel_hi:[1,0]
	v_xor_b32_e32 v80, 0x80000000, v79
	v_mov_b32_e32 v81, v79
	v_pk_fma_f32 v[82:83], v[28:29], v[70:71], v[82:83] op_sel_hi:[0,1,1]
	v_pk_add_f32 v[92:93], v[92:93], v[98:99] op_sel:[0,1] op_sel_hi:[1,0] neg_lo:[0,1]
	v_pk_mul_f32 v[98:99], v[22:23], v[114:115] op_sel:[0,1] op_sel_hi:[1,0]
	v_pk_fma_f32 v[120:121], v[70:71], v[122:123], v[120:121] op_sel_hi:[0,1,1]
	v_pk_mul_f32 v[122:123], v[76:77], v[100:101] op_sel:[0,1] op_sel_hi:[1,0]
	v_xor_b32_e32 v84, 0x80000000, v83
	v_mov_b32_e32 v85, v83
	v_pk_fma_f32 v[98:99], v[24:25], v[114:115], v[98:99] op_sel_hi:[0,1,1]
	v_pk_mul_f32 v[114:115], v[38:39], v[118:119] op_sel:[0,1] op_sel_hi:[1,0]
	v_pk_fma_f32 v[100:101], v[74:75], v[100:101], v[122:123] op_sel_hi:[0,1,1]
	v_pk_mul_f32 v[122:123], v[80:81], v[112:113] op_sel:[0,1] op_sel_hi:[1,0]
	v_add_u32_e32 v6, 0x2000, v6
	v_pk_mul_f32 v[108:109], v[32:33], v[126:127] op_sel:[0,1] op_sel_hi:[1,0]
	v_pk_fma_f32 v[114:115], v[28:29], v[118:119], v[114:115] op_sel_hi:[0,1,1]
	v_pk_mul_f32 v[118:119], v[34:35], v[124:125] op_sel:[0,1] op_sel_hi:[1,0]
	v_pk_fma_f32 v[112:113], v[78:79], v[112:113], v[122:123] op_sel_hi:[0,1,1]
	v_pk_mul_f32 v[122:123], v[84:85], v[92:93] op_sel:[0,1] op_sel_hi:[1,0]
	v_ashrrev_i32_e32 v6, 2, v6
	v_pk_fma_f32 v[108:109], v[26:27], v[126:127], v[108:109] op_sel_hi:[0,1,1]
	v_pk_fma_f32 v[118:119], v[30:31], v[124:125], v[118:119] op_sel_hi:[0,1,1]
	v_pk_fma_f32 v[92:93], v[82:83], v[92:93], v[122:123] op_sel_hi:[0,1,1]
	ds_write2_b64 v25, v[132:133], v[110:111] offset1:16
	ds_write2_b64 v25, v[118:119], v[120:121] offset0:33 offset1:49
	ds_write2_b64 v25, v[108:109], v[106:107] offset0:66 offset1:82
	ds_write2_b64 v25, v[104:105], v[112:113] offset0:99 offset1:115
	ds_write2_b64 v25, v[98:99], v[102:103] offset0:132 offset1:148
	ds_write2_b64 v25, v[116:117], v[100:101] offset0:165 offset1:181
	ds_write2_b64 v25, v[114:115], v[96:97] offset0:198 offset1:214
	ds_write2_b64 v25, v[94:95], v[92:93] offset0:231 offset1:247
	v_add3_u32 v6, v11, v6, s35
	ds_read2_b64 v[92:95], v6 offset1:16
	ds_read2_b64 v[96:99], v6 offset0:33 offset1:49
	ds_read2_b64 v[100:103], v6 offset0:66 offset1:82
	ds_read2_b64 v[104:107], v6 offset0:132 offset1:148
	ds_read2_b64 v[108:111], v6 offset0:99 offset1:115
	ds_read2_b64 v[112:115], v6 offset0:165 offset1:181
	ds_read2_b64 v[116:119], v6 offset0:198 offset1:214
	ds_read2_b64 v[120:123], v6 offset0:231 offset1:247
	s_waitcnt lgkmcnt(4)
	v_pk_add_f32 v[124:125], v[92:93], v[104:105]
	v_pk_add_f32 v[92:93], v[92:93], v[104:105] neg_lo:[0,1] neg_hi:[0,1]
	v_pk_add_f32 v[104:105], v[94:95], v[106:107]
	v_pk_add_f32 v[94:95], v[94:95], v[106:107] neg_lo:[0,1] neg_hi:[0,1]
	s_waitcnt lgkmcnt(1)
	v_pk_add_f32 v[126:127], v[102:103], v[118:119]
	v_pk_mul_f32 v[106:107], v[94:95], s[38:39]
	v_pk_add_f32 v[102:103], v[102:103], v[118:119] neg_lo:[0,1] neg_hi:[0,1]
	v_pk_fma_f32 v[94:95], v[94:95], s[36:37], v[106:107] op_sel:[0,0,1] op_sel_hi:[1,0,0]
	v_pk_add_f32 v[106:107], v[96:97], v[112:113]
	v_pk_add_f32 v[96:97], v[96:97], v[112:113] neg_lo:[0,1] neg_hi:[0,1]
	v_pk_mul_f32 v[118:119], v[102:103], s[44:45]
	v_pk_mul_f32 v[112:113], v[96:97], s[42:43]
	v_pk_fma_f32 v[102:103], v[102:103], s[62:63], v[118:119] op_sel:[0,0,1] op_sel_hi:[1,0,0] neg_lo:[1,0,0] neg_hi:[1,0,0]
	s_waitcnt lgkmcnt(0)
	v_pk_add_f32 v[118:119], v[108:109], v[120:121]
	v_pk_add_f32 v[108:109], v[108:109], v[120:121] neg_lo:[0,1] neg_hi:[0,1]
	v_pk_fma_f32 v[96:97], v[96:97], s[40:41], v[112:113] op_sel:[0,0,1] op_sel_hi:[1,0,0]
	v_pk_add_f32 v[112:113], v[98:99], v[114:115]
	v_pk_add_f32 v[98:99], v[98:99], v[114:115] neg_lo:[0,1] neg_hi:[0,1]
	v_pk_mul_f32 v[120:121], v[108:109], s[42:43]
	v_pk_mul_f32 v[114:115], v[98:99], s[44:45]
	v_pk_fma_f32 v[108:109], v[108:109], s[40:41], v[120:121] op_sel:[0,0,1] op_sel_hi:[1,0,0] neg_lo:[1,0,0] neg_hi:[1,0,0]
	v_pk_add_f32 v[120:121], v[110:111], v[122:123]
	v_pk_add_f32 v[110:111], v[110:111], v[122:123] neg_lo:[0,1] neg_hi:[0,1]
	v_pk_fma_f32 v[98:99], v[98:99], s[62:63], v[114:115] op_sel:[0,0,1] op_sel_hi:[1,0,0]
	v_pk_add_f32 v[114:115], v[100:101], v[116:117]
	v_pk_mul_f32 v[122:123], v[110:111], s[38:39]
	v_pk_add_f32 v[116:117], v[100:101], v[116:117] neg_lo:[0,1] neg_hi:[0,1]
	v_pk_fma_f32 v[110:111], v[110:111], s[36:37], v[122:123] op_sel:[0,0,1] op_sel_hi:[1,0,0] neg_lo:[1,0,0] neg_hi:[1,0,0]
	v_pk_add_f32 v[122:123], v[124:125], v[114:115]
	v_pk_add_f32 v[114:115], v[124:125], v[114:115] neg_lo:[0,1] neg_hi:[0,1]
	v_pk_add_f32 v[124:125], v[104:105], v[126:127]
	v_pk_add_f32 v[104:105], v[104:105], v[126:127] neg_lo:[0,1] neg_hi:[0,1]
	s_nop 0
	v_pk_mul_f32 v[126:127], v[104:105], s[42:43]
	v_pk_add_f32 v[128:129], v[112:113], v[120:121]
	v_pk_add_f32 v[112:113], v[112:113], v[120:121] neg_lo:[0,1] neg_hi:[0,1]
	v_pk_fma_f32 v[104:105], v[104:105], s[40:41], v[126:127] op_sel:[0,0,1] op_sel_hi:[1,0,0]
	v_pk_add_f32 v[126:127], v[106:107], v[118:119]
	v_pk_add_f32 v[118:119], v[106:107], v[118:119] neg_lo:[0,1] neg_hi:[0,1]
	v_pk_mul_f32 v[120:121], v[112:113], s[42:43]
	v_pk_add_f32 v[100:101], v[92:93], v[116:117] op_sel:[0,1] op_sel_hi:[1,0] neg_hi:[0,1]
	v_pk_add_f32 v[92:93], v[92:93], v[116:117] op_sel:[0,1] op_sel_hi:[1,0] neg_lo:[0,1]
	v_pk_add_f32 v[116:117], v[94:95], v[102:103]
	v_pk_add_f32 v[94:95], v[94:95], v[102:103] neg_lo:[0,1] neg_hi:[0,1]
	v_pk_fma_f32 v[112:113], v[112:113], s[40:41], v[120:121] op_sel:[0,0,1] op_sel_hi:[1,0,0] neg_lo:[1,0,0] neg_hi:[1,0,0]
	v_pk_mul_f32 v[102:103], v[94:95], s[42:43]
	s_nop 0
	v_pk_fma_f32 v[94:95], v[94:95], s[40:41], v[102:103] op_sel:[0,0,1] op_sel_hi:[1,0,0]
	v_pk_add_f32 v[102:103], v[96:97], v[108:109]
	v_pk_add_f32 v[120:121], v[98:99], v[110:111]
	v_pk_add_f32 v[98:99], v[98:99], v[110:111] neg_lo:[0,1] neg_hi:[0,1]
	v_pk_add_f32 v[106:107], v[114:115], v[118:119] op_sel:[0,1] op_sel_hi:[1,0] neg_hi:[0,1]
	v_pk_add_f32 v[114:115], v[114:115], v[118:119] op_sel:[0,1] op_sel_hi:[1,0] neg_lo:[0,1]
	v_pk_add_f32 v[118:119], v[104:105], v[112:113]
	v_pk_add_f32 v[112:113], v[104:105], v[112:113] neg_lo:[0,1] neg_hi:[0,1]
	v_pk_add_f32 v[108:109], v[96:97], v[108:109] neg_lo:[0,1] neg_hi:[0,1]
	v_pk_mul_f32 v[110:111], v[98:99], s[42:43]
	v_pk_add_f32 v[130:131], v[100:101], v[102:103]
	v_pk_add_f32 v[100:101], v[100:101], v[102:103] neg_lo:[0,1] neg_hi:[0,1]
	v_pk_add_f32 v[102:103], v[116:117], v[120:121]
	v_pk_fma_f32 v[98:99], v[98:99], s[40:41], v[110:111] op_sel:[0,0,1] op_sel_hi:[1,0,0] neg_lo:[1,0,0] neg_hi:[1,0,0]
	v_pk_add_f32 v[110:111], v[122:123], v[126:127]
	v_pk_add_f32 v[122:123], v[122:123], v[126:127] neg_lo:[0,1] neg_hi:[0,1]
	v_pk_add_f32 v[126:127], v[124:125], v[128:129]
	v_pk_add_f32 v[104:105], v[114:115], v[112:113] op_sel:[0,1] op_sel_hi:[1,0] neg_hi:[0,1]
	v_pk_add_f32 v[112:113], v[114:115], v[112:113] op_sel:[0,1] op_sel_hi:[1,0] neg_lo:[0,1]
	v_pk_add_f32 v[114:115], v[130:131], v[102:103]
	v_pk_add_f32 v[124:125], v[124:125], v[128:129] neg_lo:[0,1] neg_hi:[0,1]
	v_pk_add_f32 v[96:97], v[92:93], v[108:109] op_sel:[0,1] op_sel_hi:[1,0] neg_hi:[0,1]
	v_pk_add_f32 v[92:93], v[92:93], v[108:109] op_sel:[0,1] op_sel_hi:[1,0] neg_lo:[0,1]
	v_pk_add_f32 v[108:109], v[94:95], v[98:99]
	v_pk_add_f32 v[132:133], v[110:111], v[126:127]
	v_pk_add_f32 v[110:111], v[110:111], v[126:127] neg_lo:[0,1] neg_hi:[0,1]
	v_pk_add_f32 v[126:127], v[106:107], v[118:119]
	v_pk_mul_f32 v[22:23], v[22:23], v[114:115] op_sel:[0,1] op_sel_hi:[1,0]
	v_xor_b32_e32 v129, 0x80000000, v124
	v_pk_add_f32 v[116:117], v[116:117], v[120:121] neg_lo:[0,1] neg_hi:[0,1]
	v_mov_b32_e32 v128, v125
	v_pk_add_f32 v[106:107], v[106:107], v[118:119] neg_lo:[0,1] neg_hi:[0,1]
	v_pk_add_f32 v[118:119], v[96:97], v[108:109]
	v_pk_fma_f32 v[22:23], v[24:25], v[114:115], v[22:23] op_sel_hi:[0,1,1]
	v_pk_mul_f32 v[24:25], v[32:33], v[126:127] op_sel:[0,1] op_sel_hi:[1,0]
	v_xor_b32_e32 v121, 0x80000000, v116
	v_pk_add_f32 v[94:95], v[94:95], v[98:99] neg_lo:[0,1] neg_hi:[0,1]
	v_pk_add_f32 v[124:125], v[122:123], v[128:129]
	v_mov_b32_e32 v120, v117
	v_pk_fma_f32 v[24:25], v[26:27], v[126:127], v[24:25] op_sel_hi:[0,1,1]
	v_pk_mul_f32 v[26:27], v[38:39], v[118:119] op_sel:[0,1] op_sel_hi:[1,0]
	v_xor_b32_e32 v99, 0x80000000, v94
	v_pk_add_f32 v[116:117], v[100:101], v[120:121]
	v_mov_b32_e32 v98, v95
	v_pk_fma_f32 v[26:27], v[28:29], v[118:119], v[26:27] op_sel_hi:[0,1,1]
	v_pk_mul_f32 v[28:29], v[34:35], v[124:125] op_sel:[0,1] op_sel_hi:[1,0]
	v_pk_add_f32 v[94:95], v[92:93], v[98:99]
	v_pk_fma_f32 v[28:29], v[30:31], v[124:125], v[28:29] op_sel_hi:[0,1,1]
	v_pk_mul_f32 v[30:31], v[40:41], v[116:117] op_sel:[0,1] op_sel_hi:[1,0]
	v_pk_add_f32 v[122:123], v[122:123], v[128:129] neg_lo:[0,1] neg_hi:[0,1]
	v_pk_add_f32 v[102:103], v[130:131], v[102:103] neg_lo:[0,1] neg_hi:[0,1]
	v_pk_add_f32 v[100:101], v[100:101], v[120:121] neg_lo:[0,1] neg_hi:[0,1]
	v_pk_add_f32 v[96:97], v[96:97], v[108:109] neg_lo:[0,1] neg_hi:[0,1]
	v_pk_add_f32 v[92:93], v[92:93], v[98:99] neg_lo:[0,1] neg_hi:[0,1]
	v_pk_fma_f32 v[30:31], v[36:37], v[116:117], v[30:31] op_sel_hi:[0,1,1]
	v_pk_mul_f32 v[32:33], v[44:45], v[104:105] op_sel:[0,1] op_sel_hi:[1,0]
	v_pk_mul_f32 v[34:35], v[48:49], v[94:95] op_sel:[0,1] op_sel_hi:[1,0]
	v_pk_mul_f32 v[36:37], v[52:53], v[110:111] op_sel:[0,1] op_sel_hi:[1,0]
	v_pk_fma_f32 v[32:33], v[42:43], v[104:105], v[32:33] op_sel_hi:[0,1,1]
	v_pk_fma_f32 v[34:35], v[46:47], v[94:95], v[34:35] op_sel_hi:[0,1,1]
	v_pk_fma_f32 v[36:37], v[50:51], v[110:111], v[36:37] op_sel_hi:[0,1,1]
	v_pk_mul_f32 v[38:39], v[56:57], v[102:103] op_sel:[0,1] op_sel_hi:[1,0]
	v_pk_mul_f32 v[40:41], v[60:61], v[106:107] op_sel:[0,1] op_sel_hi:[1,0]
	v_pk_mul_f32 v[42:43], v[68:69], v[96:97] op_sel:[0,1] op_sel_hi:[1,0]
	v_pk_mul_f32 v[44:45], v[72:73], v[122:123] op_sel:[0,1] op_sel_hi:[1,0]
	v_pk_mul_f32 v[46:47], v[76:77], v[100:101] op_sel:[0,1] op_sel_hi:[1,0]
	v_pk_mul_f32 v[48:49], v[80:81], v[112:113] op_sel:[0,1] op_sel_hi:[1,0]
	v_pk_mul_f32 v[50:51], v[84:85], v[92:93] op_sel:[0,1] op_sel_hi:[1,0]
	v_pk_fma_f32 v[38:39], v[54:55], v[102:103], v[38:39] op_sel_hi:[0,1,1]
	v_pk_fma_f32 v[40:41], v[58:59], v[106:107], v[40:41] op_sel_hi:[0,1,1]
	v_pk_fma_f32 v[42:43], v[66:67], v[96:97], v[42:43] op_sel_hi:[0,1,1]
	v_pk_fma_f32 v[44:45], v[70:71], v[122:123], v[44:45] op_sel_hi:[0,1,1]
	v_pk_fma_f32 v[46:47], v[74:75], v[100:101], v[46:47] op_sel_hi:[0,1,1]
	v_pk_fma_f32 v[48:49], v[78:79], v[112:113], v[48:49] op_sel_hi:[0,1,1]
	v_pk_fma_f32 v[50:51], v[82:83], v[92:93], v[50:51] op_sel_hi:[0,1,1]
	ds_write2_b64 v6, v[132:133], v[36:37] offset1:16
	ds_write2_b64 v6, v[28:29], v[44:45] offset0:33 offset1:49
	ds_write2_b64 v6, v[24:25], v[40:41] offset0:66 offset1:82
	ds_write2_b64 v6, v[32:33], v[48:49] offset0:99 offset1:115
	ds_write2_b64 v6, v[22:23], v[38:39] offset0:132 offset1:148
	ds_write2_b64 v6, v[30:31], v[46:47] offset0:165 offset1:181
	ds_write2_b64 v6, v[26:27], v[42:43] offset0:198 offset1:214
	ds_write2_b64 v6, v[34:35], v[50:51] offset0:231 offset1:247
	v_mov_b32_e32 v6, v62
	s_waitcnt lgkmcnt(0)
	s_barrier
	s_lshl_b32 s24, s71, 6
	v_bfe_i32 v11, v6, 1, 27
	v_lshl_add_u32 v68, v6, 7, 0
	v_lshl_add_u32 v11, v11, 3, v68
	ds_read2_b64 v[22:25], v11 offset1:1
	ds_read2_b64 v[26:29], v11 offset0:2 offset1:3
	ds_read2_b64 v[30:33], v11 offset0:8 offset1:9
	ds_read2_b64 v[34:37], v11 offset0:4 offset1:5
	ds_read2_b64 v[38:41], v11 offset0:6 offset1:7
	ds_read2_b64 v[42:45], v11 offset0:10 offset1:11
	ds_read2_b64 v[46:49], v11 offset0:12 offset1:13
	ds_read2_b64 v[50:53], v11 offset0:14 offset1:15
	s_waitcnt lgkmcnt(5)
	v_pk_add_f32 v[54:55], v[22:23], v[30:31]
	v_pk_add_f32 v[22:23], v[22:23], v[30:31] neg_lo:[0,1] neg_hi:[0,1]
	v_pk_add_f32 v[30:31], v[24:25], v[32:33]
	v_pk_add_f32 v[24:25], v[24:25], v[32:33] neg_lo:[0,1] neg_hi:[0,1]
	s_waitcnt lgkmcnt(1)
	v_pk_add_f32 v[56:57], v[36:37], v[48:49]
	v_pk_mul_f32 v[32:33], v[24:25], s[38:39]
	v_pk_add_f32 v[36:37], v[36:37], v[48:49] neg_lo:[0,1] neg_hi:[0,1]
	v_pk_fma_f32 v[24:25], v[24:25], s[36:37], v[32:33] op_sel:[0,0,1] op_sel_hi:[1,0,0]
	v_pk_add_f32 v[32:33], v[26:27], v[42:43]
	v_pk_add_f32 v[26:27], v[26:27], v[42:43] neg_lo:[0,1] neg_hi:[0,1]
	v_pk_mul_f32 v[48:49], v[36:37], s[44:45]
	v_pk_mul_f32 v[42:43], v[26:27], s[42:43]
	v_pk_fma_f32 v[36:37], v[36:37], s[62:63], v[48:49] op_sel:[0,0,1] op_sel_hi:[1,0,0] neg_lo:[1,0,0] neg_hi:[1,0,0]
	v_pk_fma_f32 v[26:27], v[26:27], s[40:41], v[42:43] op_sel:[0,0,1] op_sel_hi:[1,0,0]
	v_pk_add_f32 v[42:43], v[28:29], v[44:45]
	v_pk_add_f32 v[28:29], v[28:29], v[44:45] neg_lo:[0,1] neg_hi:[0,1]
	s_waitcnt lgkmcnt(0)
	v_pk_add_f32 v[48:49], v[38:39], v[50:51]
	v_pk_add_f32 v[38:39], v[38:39], v[50:51] neg_lo:[0,1] neg_hi:[0,1]
	v_pk_mul_f32 v[44:45], v[28:29], s[44:45]
	v_pk_mul_f32 v[50:51], v[38:39], s[42:43]
	v_pk_fma_f32 v[28:29], v[28:29], s[62:63], v[44:45] op_sel:[0,0,1] op_sel_hi:[1,0,0]
	v_pk_add_f32 v[44:45], v[34:35], v[46:47]
	v_pk_add_f32 v[46:47], v[34:35], v[46:47] neg_lo:[0,1] neg_hi:[0,1]
	v_pk_fma_f32 v[38:39], v[38:39], s[40:41], v[50:51] op_sel:[0,0,1] op_sel_hi:[1,0,0] neg_lo:[1,0,0] neg_hi:[1,0,0]
	v_pk_add_f32 v[50:51], v[40:41], v[52:53]
	v_pk_add_f32 v[40:41], v[40:41], v[52:53] neg_lo:[0,1] neg_hi:[0,1]
	s_nop 0
	v_pk_mul_f32 v[52:53], v[40:41], s[38:39]
	v_pk_add_f32 v[58:59], v[42:43], v[50:51]
	v_pk_add_f32 v[42:43], v[42:43], v[50:51] neg_lo:[0,1] neg_hi:[0,1]
	v_pk_fma_f32 v[40:41], v[40:41], s[36:37], v[52:53] op_sel:[0,0,1] op_sel_hi:[1,0,0] neg_lo:[1,0,0] neg_hi:[1,0,0]
	v_pk_add_f32 v[52:53], v[54:55], v[44:45]
	v_pk_add_f32 v[44:45], v[54:55], v[44:45] neg_lo:[0,1] neg_hi:[0,1]
	v_pk_add_f32 v[54:55], v[30:31], v[56:57]
	v_pk_add_f32 v[30:31], v[30:31], v[56:57] neg_lo:[0,1] neg_hi:[0,1]
	v_pk_mul_f32 v[50:51], v[42:43], s[42:43]
	v_pk_add_f32 v[34:35], v[22:23], v[46:47] op_sel:[0,1] op_sel_hi:[1,0] neg_hi:[0,1]
	v_pk_add_f32 v[22:23], v[22:23], v[46:47] op_sel:[0,1] op_sel_hi:[1,0] neg_lo:[0,1]
	v_pk_add_f32 v[46:47], v[24:25], v[36:37]
	v_pk_add_f32 v[24:25], v[24:25], v[36:37] neg_lo:[0,1] neg_hi:[0,1]
	v_pk_mul_f32 v[56:57], v[30:31], s[42:43]
	v_pk_fma_f32 v[42:43], v[42:43], s[40:41], v[50:51] op_sel:[0,0,1] op_sel_hi:[1,0,0] neg_lo:[1,0,0] neg_hi:[1,0,0]
	v_pk_mul_f32 v[36:37], v[24:25], s[42:43]
	v_pk_add_f32 v[50:51], v[28:29], v[40:41]
	v_pk_add_f32 v[28:29], v[28:29], v[40:41] neg_lo:[0,1] neg_hi:[0,1]
	v_pk_fma_f32 v[30:31], v[30:31], s[40:41], v[56:57] op_sel:[0,0,1] op_sel_hi:[1,0,0]
	v_pk_add_f32 v[56:57], v[32:33], v[48:49]
	v_pk_add_f32 v[48:49], v[32:33], v[48:49] neg_lo:[0,1] neg_hi:[0,1]
	v_pk_fma_f32 v[24:25], v[24:25], s[40:41], v[36:37] op_sel:[0,0,1] op_sel_hi:[1,0,0]
	v_pk_add_f32 v[36:37], v[26:27], v[38:39]
	v_pk_add_f32 v[38:39], v[26:27], v[38:39] neg_lo:[0,1] neg_hi:[0,1]
	v_pk_mul_f32 v[40:41], v[28:29], s[42:43]
	s_nop 0
	v_pk_fma_f32 v[28:29], v[28:29], s[40:41], v[40:41] op_sel:[0,0,1] op_sel_hi:[1,0,0] neg_lo:[1,0,0] neg_hi:[1,0,0]
	v_lshl_add_u32 v6, v6, 4, v90
	v_pk_add_f32 v[40:41], v[52:53], v[56:57]
	v_pk_add_f32 v[52:53], v[52:53], v[56:57] neg_lo:[0,1] neg_hi:[0,1]
	v_pk_add_f32 v[56:57], v[54:55], v[58:59]
	v_pk_add_f32 v[58:59], v[54:55], v[58:59] neg_lo:[0,1] neg_hi:[0,1]
	v_pk_add_f32 v[32:33], v[44:45], v[48:49] op_sel:[0,1] op_sel_hi:[1,0] neg_hi:[0,1]
	v_pk_add_f32 v[44:45], v[44:45], v[48:49] op_sel:[0,1] op_sel_hi:[1,0] neg_lo:[0,1]
	v_pk_add_f32 v[48:49], v[30:31], v[42:43]
	v_pk_add_f32 v[42:43], v[30:31], v[42:43] neg_lo:[0,1] neg_hi:[0,1]
	v_pk_add_f32 v[60:61], v[34:35], v[36:37]
	v_pk_add_f32 v[34:35], v[34:35], v[36:37] neg_lo:[0,1] neg_hi:[0,1]
	v_pk_add_f32 v[36:37], v[46:47], v[50:51]
	v_pk_add_f32 v[50:51], v[46:47], v[50:51] neg_lo:[0,1] neg_hi:[0,1]
	v_pk_add_f32 v[26:27], v[22:23], v[38:39] op_sel:[0,1] op_sel_hi:[1,0] neg_hi:[0,1]
	v_pk_add_f32 v[22:23], v[22:23], v[38:39] op_sel:[0,1] op_sel_hi:[1,0] neg_lo:[0,1]
	v_pk_add_f32 v[38:39], v[24:25], v[28:29]
	v_pk_add_f32 v[28:29], v[24:25], v[28:29] neg_lo:[0,1] neg_hi:[0,1]
	v_ashrrev_i32_e32 v6, 5, v6
	v_pk_add_f32 v[66:67], v[40:41], v[56:57]
	v_pk_add_f32 v[40:41], v[40:41], v[56:57] neg_lo:[0,1] neg_hi:[0,1]
	v_lshlrev_b32_e32 v6, 3, v6
	v_pk_add_f32 v[54:55], v[52:53], v[58:59] op_sel:[0,1] op_sel_hi:[1,0] neg_hi:[0,1]
	v_pk_add_f32 v[52:53], v[52:53], v[58:59] op_sel:[0,1] op_sel_hi:[1,0] neg_lo:[0,1]
	v_pk_add_f32 v[56:57], v[32:33], v[48:49]
	v_pk_add_f32 v[32:33], v[32:33], v[48:49] neg_lo:[0,1] neg_hi:[0,1]
	v_pk_add_f32 v[30:31], v[44:45], v[42:43] op_sel:[0,1] op_sel_hi:[1,0] neg_hi:[0,1]
	v_pk_add_f32 v[42:43], v[44:45], v[42:43] op_sel:[0,1] op_sel_hi:[1,0] neg_lo:[0,1]
	v_pk_add_f32 v[44:45], v[60:61], v[36:37]
	v_pk_add_f32 v[36:37], v[60:61], v[36:37] neg_lo:[0,1] neg_hi:[0,1]
	v_pk_add_f32 v[46:47], v[34:35], v[50:51] op_sel:[0,1] op_sel_hi:[1,0] neg_hi:[0,1]
	v_pk_add_f32 v[34:35], v[34:35], v[50:51] op_sel:[0,1] op_sel_hi:[1,0] neg_lo:[0,1]
	v_pk_add_f32 v[48:49], v[26:27], v[38:39]
	v_pk_add_f32 v[26:27], v[26:27], v[38:39] neg_lo:[0,1] neg_hi:[0,1]
	v_pk_add_f32 v[24:25], v[22:23], v[28:29] op_sel:[0,1] op_sel_hi:[1,0] neg_hi:[0,1]
	v_pk_add_f32 v[22:23], v[22:23], v[28:29] op_sel:[0,1] op_sel_hi:[1,0] neg_lo:[0,1]
	ds_write2_b64 v11, v[66:67], v[40:41] offset1:1
	ds_write2_b64 v11, v[54:55], v[52:53] offset0:2 offset1:3
	ds_write2_b64 v11, v[56:57], v[32:33] offset0:4 offset1:5
	ds_write2_b64 v11, v[30:31], v[42:43] offset0:6 offset1:7
	ds_write2_b64 v11, v[44:45], v[36:37] offset0:8 offset1:9
	ds_write2_b64 v11, v[46:47], v[34:35] offset0:10 offset1:11
	ds_write2_b64 v11, v[48:49], v[26:27] offset0:12 offset1:13
	ds_write2_b64 v11, v[24:25], v[22:23] offset0:14 offset1:15
	v_add3_u32 v6, v68, v6, s35
	ds_read2_b64 v[22:25], v6 offset1:1
	ds_read2_b64 v[26:29], v6 offset0:2 offset1:3
	ds_read2_b64 v[30:33], v6 offset0:8 offset1:9
	ds_read2_b64 v[34:37], v6 offset0:4 offset1:5
	ds_read2_b64 v[38:41], v6 offset0:6 offset1:7
	ds_read2_b64 v[42:45], v6 offset0:10 offset1:11
	ds_read2_b64 v[46:49], v6 offset0:12 offset1:13
	ds_read2_b64 v[50:53], v6 offset0:14 offset1:15
	s_waitcnt lgkmcnt(5)
	v_pk_add_f32 v[54:55], v[22:23], v[30:31]
	v_pk_add_f32 v[22:23], v[22:23], v[30:31] neg_lo:[0,1] neg_hi:[0,1]
	v_pk_add_f32 v[30:31], v[24:25], v[32:33]
	v_pk_add_f32 v[24:25], v[24:25], v[32:33] neg_lo:[0,1] neg_hi:[0,1]
	s_waitcnt lgkmcnt(1)
	v_pk_add_f32 v[56:57], v[36:37], v[48:49]
	v_pk_mul_f32 v[32:33], v[24:25], s[38:39]
	v_pk_add_f32 v[36:37], v[36:37], v[48:49] neg_lo:[0,1] neg_hi:[0,1]
	v_pk_fma_f32 v[24:25], v[24:25], s[36:37], v[32:33] op_sel:[0,0,1] op_sel_hi:[1,0,0]
	v_pk_add_f32 v[32:33], v[26:27], v[42:43]
	v_pk_add_f32 v[26:27], v[26:27], v[42:43] neg_lo:[0,1] neg_hi:[0,1]
	v_pk_mul_f32 v[48:49], v[36:37], s[44:45]
	v_pk_mul_f32 v[42:43], v[26:27], s[42:43]
	v_pk_fma_f32 v[36:37], v[36:37], s[62:63], v[48:49] op_sel:[0,0,1] op_sel_hi:[1,0,0] neg_lo:[1,0,0] neg_hi:[1,0,0]
	v_pk_fma_f32 v[26:27], v[26:27], s[40:41], v[42:43] op_sel:[0,0,1] op_sel_hi:[1,0,0]
	v_pk_add_f32 v[42:43], v[28:29], v[44:45]
	v_pk_add_f32 v[28:29], v[28:29], v[44:45] neg_lo:[0,1] neg_hi:[0,1]
	s_waitcnt lgkmcnt(0)
	v_pk_add_f32 v[48:49], v[38:39], v[50:51]
	v_pk_add_f32 v[38:39], v[38:39], v[50:51] neg_lo:[0,1] neg_hi:[0,1]
	v_pk_mul_f32 v[44:45], v[28:29], s[44:45]
	v_pk_mul_f32 v[50:51], v[38:39], s[42:43]
	v_pk_fma_f32 v[28:29], v[28:29], s[62:63], v[44:45] op_sel:[0,0,1] op_sel_hi:[1,0,0]
	v_pk_add_f32 v[44:45], v[34:35], v[46:47]
	v_pk_add_f32 v[46:47], v[34:35], v[46:47] neg_lo:[0,1] neg_hi:[0,1]
	v_pk_fma_f32 v[38:39], v[38:39], s[40:41], v[50:51] op_sel:[0,0,1] op_sel_hi:[1,0,0] neg_lo:[1,0,0] neg_hi:[1,0,0]
	v_pk_add_f32 v[50:51], v[40:41], v[52:53]
	v_pk_add_f32 v[40:41], v[40:41], v[52:53] neg_lo:[0,1] neg_hi:[0,1]
	s_nop 0
	v_pk_mul_f32 v[52:53], v[40:41], s[38:39]
	v_pk_add_f32 v[58:59], v[42:43], v[50:51]
	v_pk_add_f32 v[42:43], v[42:43], v[50:51] neg_lo:[0,1] neg_hi:[0,1]
	v_pk_fma_f32 v[40:41], v[40:41], s[36:37], v[52:53] op_sel:[0,0,1] op_sel_hi:[1,0,0] neg_lo:[1,0,0] neg_hi:[1,0,0]
	v_pk_mul_f32 v[50:51], v[42:43], s[42:43]
	v_pk_add_f32 v[34:35], v[22:23], v[46:47] op_sel:[0,1] op_sel_hi:[1,0] neg_hi:[0,1]
	v_pk_add_f32 v[22:23], v[22:23], v[46:47] op_sel:[0,1] op_sel_hi:[1,0] neg_lo:[0,1]
	v_pk_add_f32 v[46:47], v[24:25], v[36:37]
	v_pk_add_f32 v[24:25], v[24:25], v[36:37] neg_lo:[0,1] neg_hi:[0,1]
	v_pk_add_f32 v[52:53], v[54:55], v[44:45]
	v_pk_add_f32 v[44:45], v[54:55], v[44:45] neg_lo:[0,1] neg_hi:[0,1]
	v_pk_add_f32 v[54:55], v[30:31], v[56:57]
	v_pk_add_f32 v[30:31], v[30:31], v[56:57] neg_lo:[0,1] neg_hi:[0,1]
	v_pk_fma_f32 v[42:43], v[42:43], s[40:41], v[50:51] op_sel:[0,0,1] op_sel_hi:[1,0,0] neg_lo:[1,0,0] neg_hi:[1,0,0]
	v_pk_mul_f32 v[36:37], v[24:25], s[42:43]
	v_pk_add_f32 v[50:51], v[28:29], v[40:41]
	v_pk_add_f32 v[28:29], v[28:29], v[40:41] neg_lo:[0,1] neg_hi:[0,1]
	s_and_b32 s24, s24, 0xc0
	v_pk_mul_f32 v[56:57], v[30:31], s[42:43]
	v_pk_fma_f32 v[24:25], v[24:25], s[40:41], v[36:37] op_sel:[0,0,1] op_sel_hi:[1,0,0]
	v_pk_add_f32 v[36:37], v[26:27], v[38:39]
	v_pk_add_f32 v[38:39], v[26:27], v[38:39] neg_lo:[0,1] neg_hi:[0,1]
	v_pk_mul_f32 v[40:41], v[28:29], s[42:43]
	s_lshl_b64 s[62:63], s[50:51], 19
	v_pk_fma_f32 v[30:31], v[30:31], s[40:41], v[56:57] op_sel:[0,0,1] op_sel_hi:[1,0,0]
	v_pk_add_f32 v[56:57], v[32:33], v[48:49]
	v_pk_add_f32 v[48:49], v[32:33], v[48:49] neg_lo:[0,1] neg_hi:[0,1]
	s_nop 0
	v_pk_fma_f32 v[28:29], v[28:29], s[40:41], v[40:41] op_sel:[0,0,1] op_sel_hi:[1,0,0] neg_lo:[1,0,0] neg_hi:[1,0,0]
	s_add_u32 s43, s3, s62
	s_nop 0
	s_nop 0
	v_pk_add_f32 v[26:27], v[22:23], v[38:39] op_sel:[0,1] op_sel_hi:[1,0] neg_hi:[0,1]
	v_pk_add_f32 v[22:23], v[22:23], v[38:39] op_sel:[0,1] op_sel_hi:[1,0] neg_lo:[0,1]
	v_pk_add_f32 v[38:39], v[24:25], v[28:29]
	v_pk_add_f32 v[24:25], v[24:25], v[28:29] neg_lo:[0,1] neg_hi:[0,1]
	s_addc_u32 s45, s29, s63
	s_lshl_b32 s64, s24, 2
	v_pk_add_f32 v[40:41], v[52:53], v[56:57]
	v_pk_add_f32 v[52:53], v[52:53], v[56:57] neg_lo:[0,1] neg_hi:[0,1]
	v_pk_add_f32 v[56:57], v[54:55], v[58:59]
	v_pk_add_f32 v[54:55], v[54:55], v[58:59] neg_lo:[0,1] neg_hi:[0,1]
	v_pk_add_f32 v[32:33], v[44:45], v[48:49] op_sel:[0,1] op_sel_hi:[1,0] neg_hi:[0,1]
	v_pk_add_f32 v[44:45], v[44:45], v[48:49] op_sel:[0,1] op_sel_hi:[1,0] neg_lo:[0,1]
	v_pk_add_f32 v[48:49], v[30:31], v[42:43]
	v_pk_add_f32 v[42:43], v[30:31], v[42:43] neg_lo:[0,1] neg_hi:[0,1]
	v_pk_add_f32 v[60:61], v[34:35], v[36:37]
	v_pk_add_f32 v[34:35], v[34:35], v[36:37] neg_lo:[0,1] neg_hi:[0,1]
	v_pk_add_f32 v[36:37], v[46:47], v[50:51]
	v_pk_add_f32 v[46:47], v[46:47], v[50:51] neg_lo:[0,1] neg_hi:[0,1]
	v_xor_b32_e32 v29, 0x80000000, v24
	v_mov_b32_e32 v28, v25
	s_add_u32 s64, s43, s64
	v_xor_b32_e32 v59, 0x80000000, v54
	s_nop 0
	v_xor_b32_e32 v51, 0x80000000, v46
	v_pk_add_f32 v[66:67], v[40:41], v[56:57]
	v_pk_add_f32 v[40:41], v[40:41], v[56:57] neg_lo:[0,1] neg_hi:[0,1]
	v_mov_b32_e32 v58, v55
	v_mov_b32_e32 v50, v47
	v_pk_add_f32 v[24:25], v[22:23], v[28:29]
	v_pk_add_f32 v[22:23], v[22:23], v[28:29] neg_lo:[0,1] neg_hi:[0,1]
	s_addc_u32 s65, s45, 0
	v_pk_add_f32 v[54:55], v[52:53], v[58:59]
	v_pk_add_f32 v[52:53], v[52:53], v[58:59] neg_lo:[0,1] neg_hi:[0,1]
	v_pk_add_f32 v[56:57], v[32:33], v[48:49]
	v_pk_add_f32 v[32:33], v[32:33], v[48:49] neg_lo:[0,1] neg_hi:[0,1]
	v_pk_add_f32 v[30:31], v[44:45], v[42:43] op_sel:[0,1] op_sel_hi:[1,0] neg_hi:[0,1]
	v_pk_add_f32 v[42:43], v[44:45], v[42:43] op_sel:[0,1] op_sel_hi:[1,0] neg_lo:[0,1]
	v_pk_add_f32 v[44:45], v[60:61], v[36:37]
	v_pk_add_f32 v[36:37], v[60:61], v[36:37] neg_lo:[0,1] neg_hi:[0,1]
	v_pk_add_f32 v[46:47], v[34:35], v[50:51]
	v_pk_add_f32 v[34:35], v[34:35], v[50:51] neg_lo:[0,1] neg_hi:[0,1]
	v_pk_add_f32 v[48:49], v[26:27], v[38:39]
	v_pk_add_f32 v[26:27], v[26:27], v[38:39] neg_lo:[0,1] neg_hi:[0,1]
	ds_write2_b64 v6, v[66:67], v[40:41] offset1:1
	ds_write2_b64 v6, v[54:55], v[52:53] offset0:2 offset1:3
	ds_write2_b64 v6, v[56:57], v[32:33] offset0:4 offset1:5
	ds_write2_b64 v6, v[30:31], v[42:43] offset0:6 offset1:7
	ds_write2_b64 v6, v[44:45], v[36:37] offset0:8 offset1:9
	ds_write2_b64 v6, v[46:47], v[34:35] offset0:10 offset1:11
	ds_write2_b64 v6, v[48:49], v[26:27] offset0:12 offset1:13
	ds_write2_b64 v6, v[24:25], v[22:23] offset0:14 offset1:15
	v_lshl_add_u64 v[22:23], s[64:65], 0, v[20:21]
	s_mov_b64 s[64:65], 0
	v_mov_b32_e32 v11, v9
	v_mov_b64_e32 v[24:25], v[62:63]
	s_waitcnt lgkmcnt(0)
	s_barrier

.LBB0_275:
	s_or_b64 exec, exec, s[10:11]
	v_mov_b32_e32 v40, v1
	s_mov_b32 s73, s50
	v_ashrrev_i32_e32 v42, 31, v40
	v_lshrrev_b32_e32 v42, 23, v42
	v_add_u32_e32 v42, v40, v42
	v_ashrrev_i32_e32 v42, 9, v42
	v_mul_i32_i24_e32 v44, 0x200, v42
	v_sub_u32_e32 v70, v40, v44
	v_lshlrev_b32_e32 v40, 14, v42
	v_lshlrev_b32_e32 v42, 1, v70
	v_bfrev_b32_e32 v42, v42
	v_lshrrev_b32_e32 v42, 22, v42
	v_sub_u32_e32 v42, 0x400, v42
	v_bfrev_b32_e32 v42, v42
	v_lshrrev_b32_e32 v42, 18, v42
	v_and_b32_e32 v42, 0x3ff0, v42
	v_cmp_eq_u32_e64 s[10:11], 0, v70
	v_lshl_add_u32 v44, v70, 5, v40
	v_lshlrev_b32_e32 v45, 3, v44
	v_cndmask_b32_e64 v42, v42, 16, s[10:11]
	v_or_b32_e32 v40, v42, v40
	v_ashrrev_i32_e32 v44, 2, v44
	v_ashrrev_i32_e32 v42, 5, v40
	v_add3_u32 v44, 0, v45, v44
	v_lshlrev_b32_e32 v40, 3, v40
	v_lshlrev_b32_e32 v42, 3, v42
	v_add3_u32 v40, 0, v40, v42
	ds_read2_b64 v[46:49], v44 offset1:1
	ds_read2_b64 v[50:53], v44 offset0:2 offset1:3
	ds_read2_b64 v[76:79], v40 offset1:1
	ds_read2_b64 v[80:83], v40 offset0:2 offset1:3
	ds_read2_b64 v[54:57], v44 offset0:4 offset1:5
	ds_read2_b64 v[58:61], v44 offset0:6 offset1:7
	ds_read2_b64 v[84:87], v40 offset0:4 offset1:5
	ds_read2_b64 v[88:91], v40 offset0:6 offset1:7
	ds_read2_b64 v[62:65], v44 offset0:8 offset1:9
	ds_read2_b64 v[66:69], v44 offset0:10 offset1:11
	ds_read2_b64 v[100:103], v40 offset0:8 offset1:9
	ds_read2_b64 v[104:107], v40 offset0:10 offset1:11
	ds_read2_b64 v[72:75], v44 offset0:12 offset1:13
	ds_read2_b64 v[92:95], v44 offset0:14 offset1:15
	ds_read2_b64 v[108:111], v40 offset0:12 offset1:13
	ds_read2_b64 v[112:115], v40 offset0:14 offset1:15
	s_waitcnt lgkmcnt(7)
	v_pk_add_f32 v[96:97], v[46:47], v[62:63]
	v_pk_add_f32 v[46:47], v[46:47], v[62:63] neg_lo:[0,1] neg_hi:[0,1]
	v_pk_add_f32 v[62:63], v[48:49], v[64:65]
	v_pk_add_f32 v[48:49], v[48:49], v[64:65] neg_lo:[0,1] neg_hi:[0,1]
	s_waitcnt lgkmcnt(3)
	v_pk_add_f32 v[98:99], v[56:57], v[74:75]
	v_pk_mul_f32 v[64:65], v[48:49], s[62:63]
	v_pk_add_f32 v[56:57], v[56:57], v[74:75] neg_lo:[0,1] neg_hi:[0,1]
	v_pk_fma_f32 v[48:49], v[48:49], s[50:51], v[64:65] op_sel:[0,0,1] op_sel_hi:[1,0,0]
	v_pk_add_f32 v[64:65], v[50:51], v[66:67]
	v_pk_add_f32 v[50:51], v[50:51], v[66:67] neg_lo:[0,1] neg_hi:[0,1]
	s_mov_b32 s80, s63
	v_pk_mul_f32 v[74:75], v[56:57], s[72:73]
	s_mov_b32 s78, s69
	v_pk_mul_f32 v[66:67], v[50:51], s[68:69]
	v_pk_fma_f32 v[56:57], v[56:57], s[80:81], v[74:75] op_sel:[0,0,1] op_sel_hi:[1,0,0] neg_lo:[1,0,0] neg_hi:[1,0,0]
	s_waitcnt lgkmcnt(2)
	v_pk_add_f32 v[74:75], v[58:59], v[92:93]
	v_pk_add_f32 v[58:59], v[58:59], v[92:93] neg_lo:[0,1] neg_hi:[0,1]
	v_pk_fma_f32 v[50:51], v[50:51], s[78:79], v[66:67] op_sel:[0,0,1] op_sel_hi:[1,0,0]
	v_pk_add_f32 v[66:67], v[52:53], v[68:69]
	v_pk_add_f32 v[52:53], v[52:53], v[68:69] neg_lo:[0,1] neg_hi:[0,1]
	v_pk_mul_f32 v[92:93], v[58:59], s[68:69]
	v_pk_mul_f32 v[68:69], v[52:53], s[72:73]
	v_pk_fma_f32 v[58:59], v[58:59], s[78:79], v[92:93] op_sel:[0,0,1] op_sel_hi:[1,0,0] neg_lo:[1,0,0] neg_hi:[1,0,0]
	v_pk_add_f32 v[92:93], v[60:61], v[94:95]
	v_pk_add_f32 v[60:61], v[60:61], v[94:95] neg_lo:[0,1] neg_hi:[0,1]
	v_pk_fma_f32 v[52:53], v[52:53], s[80:81], v[68:69] op_sel:[0,0,1] op_sel_hi:[1,0,0]
	v_pk_add_f32 v[68:69], v[54:55], v[72:73]
	v_pk_add_f32 v[54:55], v[54:55], v[72:73] neg_lo:[0,1] neg_hi:[0,1]
	v_pk_mul_f32 v[94:95], v[60:61], s[62:63]
	v_pk_add_f32 v[116:117], v[66:67], v[92:93]
	v_pk_add_f32 v[66:67], v[66:67], v[92:93] neg_lo:[0,1] neg_hi:[0,1]
	v_xor_b32_e32 v73, 0x80000000, v54
	v_pk_fma_f32 v[60:61], v[60:61], s[50:51], v[94:95] op_sel:[0,0,1] op_sel_hi:[1,0,0] neg_lo:[1,0,0] neg_hi:[1,0,0]
	v_pk_add_f32 v[94:95], v[96:97], v[68:69]
	v_pk_add_f32 v[68:69], v[96:97], v[68:69] neg_lo:[0,1] neg_hi:[0,1]
	v_pk_add_f32 v[96:97], v[62:63], v[98:99]
	v_pk_add_f32 v[62:63], v[62:63], v[98:99] neg_lo:[0,1] neg_hi:[0,1]
	v_pk_mul_f32 v[92:93], v[66:67], s[68:69]
	v_mov_b32_e32 v72, v55
	v_pk_mul_f32 v[98:99], v[62:63], s[68:69]
	v_pk_fma_f32 v[66:67], v[66:67], s[78:79], v[92:93] op_sel:[0,0,1] op_sel_hi:[1,0,0] neg_lo:[1,0,0] neg_hi:[1,0,0]
	v_pk_add_f32 v[54:55], v[46:47], v[72:73]
	v_pk_add_f32 v[46:47], v[46:47], v[72:73] neg_lo:[0,1] neg_hi:[0,1]
	v_pk_add_f32 v[72:73], v[48:49], v[56:57]
	v_pk_add_f32 v[48:49], v[48:49], v[56:57] neg_lo:[0,1] neg_hi:[0,1]
	v_pk_add_f32 v[92:93], v[52:53], v[60:61]
	v_pk_add_f32 v[52:53], v[52:53], v[60:61] neg_lo:[0,1] neg_hi:[0,1]
	v_pk_fma_f32 v[62:63], v[62:63], s[78:79], v[98:99] op_sel:[0,0,1] op_sel_hi:[1,0,0]
	v_pk_add_f32 v[98:99], v[64:65], v[74:75]
	v_pk_mul_f32 v[56:57], v[48:49], s[68:69]
	v_pk_mul_f32 v[60:61], v[52:53], s[68:69]
	v_pk_fma_f32 v[48:49], v[48:49], s[78:79], v[56:57] op_sel:[0,0,1] op_sel_hi:[1,0,0]
	v_pk_add_f32 v[56:57], v[50:51], v[58:59]
	v_pk_fma_f32 v[52:53], v[52:53], s[78:79], v[60:61] op_sel:[0,0,1] op_sel_hi:[1,0,0] neg_lo:[1,0,0] neg_hi:[1,0,0]
	v_pk_add_f32 v[60:61], v[94:95], v[98:99]
	v_pk_add_f32 v[118:119], v[94:95], v[98:99] neg_lo:[0,1] neg_hi:[0,1]
	v_pk_add_f32 v[94:95], v[96:97], v[116:117]
	v_pk_add_f32 v[116:117], v[96:97], v[116:117] neg_lo:[0,1] neg_hi:[0,1]
	v_pk_add_f32 v[128:129], v[54:55], v[56:57]
	v_pk_add_f32 v[54:55], v[54:55], v[56:57] neg_lo:[0,1] neg_hi:[0,1]
	v_pk_add_f32 v[56:57], v[72:73], v[92:93]
	v_pk_add_f32 v[92:93], v[72:73], v[92:93] neg_lo:[0,1] neg_hi:[0,1]
	v_pk_add_f32 v[96:97], v[78:79], v[102:103]
	v_pk_add_f32 v[78:79], v[78:79], v[102:103] neg_lo:[0,1] neg_hi:[0,1]
	v_xor_b32_e32 v131, 0x80000000, v92
	v_mov_b32_e32 v130, v93
	v_pk_add_f32 v[92:93], v[76:77], v[100:101]
	v_pk_add_f32 v[76:77], v[76:77], v[100:101] neg_lo:[0,1] neg_hi:[0,1]
	v_pk_mul_f32 v[100:101], v[78:79], s[62:63]
	v_bfrev_b32_e32 v40, v70
	v_pk_fma_f32 v[78:79], v[78:79], s[50:51], v[100:101] op_sel:[0,0,1] op_sel_hi:[1,0,0]
	v_pk_add_f32 v[100:101], v[80:81], v[104:105]
	v_pk_add_f32 v[80:81], v[80:81], v[104:105] neg_lo:[0,1] neg_hi:[0,1]
	v_lshrrev_b32_e32 v40, 23, v40
	v_pk_mul_f32 v[102:103], v[80:81], s[68:69]
	v_cvt_f32_u32_e32 v40, v40
	v_pk_fma_f32 v[80:81], v[80:81], s[78:79], v[102:103] op_sel:[0,0,1] op_sel_hi:[1,0,0]
	v_pk_add_f32 v[102:103], v[82:83], v[106:107]
	v_pk_add_f32 v[82:83], v[82:83], v[106:107] neg_lo:[0,1] neg_hi:[0,1]
	v_mul_f32_e32 v40, 0x38000000, v40
	v_pk_mul_f32 v[104:105], v[82:83], s[72:73]
	v_ashrrev_i32_e32 v71, 31, v70
	v_pk_fma_f32 v[82:83], v[82:83], s[80:81], v[104:105] op_sel:[0,0,1] op_sel_hi:[1,0,0]
	s_waitcnt lgkmcnt(1)
	v_pk_add_f32 v[104:105], v[84:85], v[108:109]
	v_pk_add_f32 v[106:107], v[84:85], v[108:109] neg_lo:[0,1] neg_hi:[0,1]
	v_pk_add_f32 v[74:75], v[64:65], v[74:75] neg_lo:[0,1] neg_hi:[0,1]
	v_pk_add_f32 v[84:85], v[86:87], v[110:111]
	v_pk_add_f32 v[86:87], v[86:87], v[110:111] neg_lo:[0,1] neg_hi:[0,1]
	v_cndmask_b32_e64 v40, v40, v154, s[10:11]
	v_pk_mul_f32 v[108:109], v[86:87], s[72:73]
	v_lshl_add_u64 v[44:45], v[70:71], 3, s[26:27]
	v_pk_fma_f32 v[86:87], v[86:87], s[80:81], v[108:109] op_sel:[0,0,1] op_sel_hi:[1,0,0] neg_lo:[1,0,0] neg_hi:[1,0,0]
	s_waitcnt lgkmcnt(0)
	v_pk_add_f32 v[108:109], v[88:89], v[112:113]
	v_pk_add_f32 v[88:89], v[88:89], v[112:113] neg_lo:[0,1] neg_hi:[0,1]
	s_nop 0
	v_pk_mul_f32 v[110:111], v[88:89], s[68:69]
	v_pk_add_f32 v[50:51], v[50:51], v[58:59] neg_lo:[0,1] neg_hi:[0,1]
	v_pk_fma_f32 v[88:89], v[88:89], s[78:79], v[110:111] op_sel:[0,0,1] op_sel_hi:[1,0,0] neg_lo:[1,0,0] neg_hi:[1,0,0]
	v_pk_add_f32 v[110:111], v[90:91], v[114:115]
	v_pk_add_f32 v[90:91], v[90:91], v[114:115] neg_lo:[0,1] neg_hi:[0,1]
	s_nop 0
	v_pk_mul_f32 v[112:113], v[90:91], s[62:63]
	v_pk_add_f32 v[124:125], v[62:63], v[66:67]
	v_pk_fma_f32 v[90:91], v[90:91], s[50:51], v[112:113] op_sel:[0,0,1] op_sel_hi:[1,0,0] neg_lo:[1,0,0] neg_hi:[1,0,0]
	v_pk_add_f32 v[112:113], v[92:93], v[104:105]
	v_pk_add_f32 v[92:93], v[92:93], v[104:105] neg_lo:[0,1] neg_hi:[0,1]
	v_pk_add_f32 v[104:105], v[96:97], v[84:85]
	v_pk_add_f32 v[84:85], v[96:97], v[84:85] neg_lo:[0,1] neg_hi:[0,1]
	v_pk_add_f32 v[66:67], v[62:63], v[66:67] neg_lo:[0,1] neg_hi:[0,1]
	v_pk_mul_f32 v[96:97], v[84:85], s[68:69]
	v_cos_f32_e32 v71, v40
	v_pk_fma_f32 v[84:85], v[84:85], s[78:79], v[96:97] op_sel:[0,0,1] op_sel_hi:[1,0,0]
	v_pk_add_f32 v[96:97], v[100:101], v[108:109]
	v_pk_add_f32 v[108:109], v[100:101], v[108:109] neg_lo:[0,1] neg_hi:[0,1]
	v_cmp_ne_u32_e32 vcc, 0, v70
	s_nop 0
	s_nop 0
	v_pk_add_f32 v[100:101], v[102:103], v[110:111]
	v_pk_add_f32 v[102:103], v[102:103], v[110:111] neg_lo:[0,1] neg_hi:[0,1]
	v_xor_b32_e32 v59, 0x80000000, v50
	v_pk_mul_f32 v[110:111], v[102:103], s[68:69]
	v_pk_add_f32 v[64:65], v[68:69], v[74:75] op_sel:[0,1] op_sel_hi:[1,0] neg_hi:[0,1]
	v_pk_fma_f32 v[102:103], v[102:103], s[78:79], v[110:111] op_sel:[0,0,1] op_sel_hi:[1,0,0] neg_lo:[1,0,0] neg_hi:[1,0,0]
	v_pk_add_f32 v[110:111], v[76:77], v[106:107] op_sel:[0,1] op_sel_hi:[1,0] neg_hi:[0,1]
	v_pk_add_f32 v[76:77], v[76:77], v[106:107] op_sel:[0,1] op_sel_hi:[1,0] neg_lo:[0,1]
	v_pk_add_f32 v[106:107], v[78:79], v[86:87]
	v_pk_add_f32 v[78:79], v[78:79], v[86:87] neg_lo:[0,1] neg_hi:[0,1]
	v_pk_add_f32 v[122:123], v[68:69], v[74:75] op_sel:[0,1] op_sel_hi:[1,0] neg_lo:[0,1]
	v_pk_mul_f32 v[86:87], v[78:79], s[68:69]
	v_xor_b32_e32 v127, 0x80000000, v66
	v_pk_fma_f32 v[78:79], v[78:79], s[78:79], v[86:87] op_sel:[0,0,1] op_sel_hi:[1,0,0]
	v_pk_add_f32 v[86:87], v[80:81], v[88:89]
	v_pk_add_f32 v[88:89], v[80:81], v[88:89] neg_lo:[0,1] neg_hi:[0,1]
	v_mov_b32_e32 v58, v51
	v_pk_add_f32 v[80:81], v[82:83], v[90:91]
	v_pk_add_f32 v[82:83], v[82:83], v[90:91] neg_lo:[0,1] neg_hi:[0,1]
	v_mov_b32_e32 v126, v67
	v_pk_mul_f32 v[90:91], v[82:83], s[68:69]
	v_sin_f32_e32 v70, v40
	v_pk_fma_f32 v[82:83], v[82:83], s[78:79], v[90:91] op_sel:[0,0,1] op_sel_hi:[1,0,0] neg_lo:[1,0,0] neg_hi:[1,0,0]
	v_pk_add_f32 v[132:133], v[46:47], v[58:59]
	v_pk_add_f32 v[156:157], v[46:47], v[58:59] neg_lo:[0,1] neg_hi:[0,1]
	v_pk_add_f32 v[46:47], v[48:49], v[52:53]
	v_pk_add_f32 v[52:53], v[48:49], v[52:53] neg_lo:[0,1] neg_hi:[0,1]
	v_pk_add_f32 v[98:99], v[60:61], v[94:95]
	v_pk_add_f32 v[94:95], v[60:61], v[94:95] neg_lo:[0,1] neg_hi:[0,1]
	v_pk_add_f32 v[74:75], v[118:119], v[116:117] op_sel:[0,1] op_sel_hi:[1,0] neg_hi:[0,1]
	v_pk_add_f32 v[68:69], v[118:119], v[116:117] op_sel:[0,1] op_sel_hi:[1,0] neg_lo:[0,1]
	v_pk_add_f32 v[72:73], v[64:65], v[124:125]
	v_pk_add_f32 v[62:63], v[64:65], v[124:125] neg_lo:[0,1] neg_hi:[0,1]
	v_pk_add_f32 v[60:61], v[122:123], v[126:127]
	v_pk_add_f32 v[66:67], v[122:123], v[126:127] neg_lo:[0,1] neg_hi:[0,1]
	v_pk_add_f32 v[114:115], v[112:113], v[96:97]
	v_pk_add_f32 v[96:97], v[112:113], v[96:97] neg_lo:[0,1] neg_hi:[0,1]
	v_pk_add_f32 v[112:113], v[104:105], v[100:101]
	v_pk_add_f32 v[100:101], v[104:105], v[100:101] neg_lo:[0,1] neg_hi:[0,1]
	v_pk_add_f32 v[104:105], v[92:93], v[108:109] op_sel:[0,1] op_sel_hi:[1,0] neg_hi:[0,1]
	v_pk_add_f32 v[92:93], v[92:93], v[108:109] op_sel:[0,1] op_sel_hi:[1,0] neg_lo:[0,1]
	v_pk_add_f32 v[108:109], v[84:85], v[102:103]
	v_pk_add_f32 v[102:103], v[84:85], v[102:103] neg_lo:[0,1] neg_hi:[0,1]
	v_pk_add_f32 v[118:119], v[106:107], v[80:81]
	v_pk_add_f32 v[106:107], v[106:107], v[80:81] neg_lo:[0,1] neg_hi:[0,1]
	v_pk_add_f32 v[122:123], v[76:77], v[88:89] op_sel:[0,1] op_sel_hi:[1,0] neg_hi:[0,1]
	v_pk_add_f32 v[124:125], v[76:77], v[88:89] op_sel:[0,1] op_sel_hi:[1,0] neg_lo:[0,1]
	v_pk_add_f32 v[76:77], v[78:79], v[82:83] neg_lo:[0,1] neg_hi:[0,1]
	v_xor_b32_e32 v159, 0x80000000, v52
	v_pk_add_f32 v[64:65], v[128:129], v[56:57]
	v_pk_add_f32 v[50:51], v[128:129], v[56:57] neg_lo:[0,1] neg_hi:[0,1]
	v_mov_b32_e32 v158, v53
	v_pk_add_f32 v[116:117], v[110:111], v[86:87]
	v_pk_add_f32 v[110:111], v[110:111], v[86:87] neg_lo:[0,1] neg_hi:[0,1]
	v_pk_add_f32 v[126:127], v[78:79], v[82:83]
	v_xor_b32_e32 v129, 0x80000000, v76
	v_mov_b32_e32 v128, v77
	v_pk_add_f32 v[56:57], v[54:55], v[130:131]
	v_pk_add_f32 v[58:59], v[54:55], v[130:131] neg_lo:[0,1] neg_hi:[0,1]
	v_pk_add_f32 v[54:55], v[132:133], v[46:47]
	v_pk_add_f32 v[48:49], v[132:133], v[46:47] neg_lo:[0,1] neg_hi:[0,1]
	v_pk_add_f32 v[46:47], v[156:157], v[158:159]
	v_pk_add_f32 v[52:53], v[156:157], v[158:159] neg_lo:[0,1] neg_hi:[0,1]
	v_pk_add_f32 v[90:91], v[114:115], v[112:113]
	v_pk_add_f32 v[86:87], v[114:115], v[112:113] neg_lo:[0,1] neg_hi:[0,1]
	v_pk_add_f32 v[80:81], v[96:97], v[100:101] op_sel:[0,1] op_sel_hi:[1,0] neg_hi:[0,1]
	v_pk_add_f32 v[84:85], v[96:97], v[100:101] op_sel:[0,1] op_sel_hi:[1,0] neg_lo:[0,1]
	v_pk_add_f32 v[76:77], v[104:105], v[108:109]
	v_pk_add_f32 v[78:79], v[104:105], v[108:109] neg_lo:[0,1] neg_hi:[0,1]
	v_pk_add_f32 v[82:83], v[92:93], v[102:103] op_sel:[0,1] op_sel_hi:[1,0] neg_hi:[0,1]
	v_pk_add_f32 v[88:89], v[92:93], v[102:103] op_sel:[0,1] op_sel_hi:[1,0] neg_lo:[0,1]
	v_pk_add_f32 v[92:93], v[116:117], v[118:119]
	v_pk_add_f32 v[100:101], v[116:117], v[118:119] neg_lo:[0,1] neg_hi:[0,1]
	v_pk_add_f32 v[102:103], v[110:111], v[106:107] op_sel:[0,1] op_sel_hi:[1,0] neg_hi:[0,1]
	v_pk_add_f32 v[106:107], v[110:111], v[106:107] op_sel:[0,1] op_sel_hi:[1,0] neg_lo:[0,1]
	v_pk_add_f32 v[108:109], v[122:123], v[126:127]
	v_pk_add_f32 v[110:111], v[122:123], v[126:127] neg_lo:[0,1] neg_hi:[0,1]
	v_pk_add_f32 v[112:113], v[124:125], v[128:129]
	v_pk_add_f32 v[118:119], v[124:125], v[128:129] neg_lo:[0,1] neg_hi:[0,1]
	v_mul_f32_e32 v40, 0x3f3504f3, v71
	v_mul_f32_e32 v104, 0xbec3ef15, v71
	v_mul_f32_e32 v96, 0xbf6c835e, v71
	s_and_saveexec_b64 s[10:11], vcc
	s_xor_b64 s[10:11], exec, s[10:11]
	s_cbranch_execz .LBB0_277
	v_pk_add_f32 v[114:115], v[98:99], v[118:119]
	v_pk_add_f32 v[98:99], v[98:99], v[118:119] neg_lo:[0,1] neg_hi:[0,1]
	v_mul_f32_e32 v42, 0.5, v114
	v_pk_fma_f32 v[116:117], v[70:71], 0, v[70:71] op_sel:[0,0,1] op_sel_hi:[1,0,0] neg_lo:[1,0,0]
	v_mov_b32_e32 v114, v98
	v_pk_mul_f32 v[114:115], v[114:115], s[74:75]
	s_mov_b32 s78, s63
	v_pk_mul_f32 v[118:119], v[116:117], v[114:115] op_sel:[0,1] op_sel_hi:[1,0]
	v_pk_mul_f32 v[114:115], v[116:117], v[114:115]
	s_mov_b32 s79, s50
	v_sub_f32_e32 v97, v114, v115
	v_fma_mixlo_f16 v105, v99, s75, v97
	v_fma_f32 v97, v99, 0.5, -v97
	v_cvt_f16_f32_sdwa v97, -v97 dst_sel:WORD_1 dst_unused:UNUSED_PAD src0_sel:DWORD
	v_pk_add_f32 v[98:99], v[118:119], v[118:119] op_sel:[0,1] op_sel_hi:[0,1]
	s_waitcnt vmcnt(0)
	v_pk_add_f32 v[114:115], v[42:43], v[98:99]
	v_pk_add_f32 v[98:99], v[42:43], v[98:99] op_sel_hi:[0,1] neg_lo:[0,1] neg_hi:[0,1]
	v_cvt_pk_f16_f32 v42, v114, v99
	v_lshlrev_b32_e32 v98, 16, v105
	v_or_b32_sdwa v99, v97, v42 dst_sel:DWORD dst_unused:UNUSED_PAD src0_sel:DWORD src1_sel:WORD_1
	v_or_b32_sdwa v98, v98, v42 dst_sel:DWORD dst_unused:UNUSED_PAD src0_sel:DWORD src1_sel:WORD_0
	global_store_dwordx2 v[44:45], v[98:99], off
	v_pk_add_f32 v[98:99], v[94:95], v[112:113]
	v_pk_add_f32 v[94:95], v[94:95], v[112:113] neg_lo:[0,1] neg_hi:[0,1]
	v_mul_f32_e32 v42, 0.5, v98
	v_mov_b32_e32 v98, v71
	v_mov_b32_e32 v112, v71
	v_mov_b32_e32 v113, v70
	v_pk_fma_f32 v[114:115], v[70:71], 0, v[112:113] op_sel_hi:[1,0,1] neg_lo:[0,0,1] neg_hi:[0,0,1]
	v_pk_fma_f32 v[116:117], v[70:71], 0, v[98:99] op_sel_hi:[1,0,1]
	v_mov_b32_e32 v98, v94
	v_pk_mov_b32 v[114:115], v[114:115], v[116:117] op_sel:[1,0]
	v_pk_mul_f32 v[98:99], v[98:99], s[74:75]
	s_mov_b32 s51, s63
	v_pk_mul_f32 v[116:117], v[114:115], v[98:99] op_sel:[0,1] op_sel_hi:[1,0]
	v_pk_mul_f32 v[98:99], v[114:115], v[98:99]
	v_pk_add_f32 v[114:115], v[74:75], v[110:111]
	v_sub_f32_e32 v94, v98, v99
	v_fma_mixlo_f16 v97, v95, s75, v94
	v_fma_f32 v94, v95, 0.5, -v94
	v_cvt_f16_f32_sdwa v105, -v94 dst_sel:WORD_1 dst_unused:UNUSED_PAD src0_sel:DWORD
	v_pk_add_f32 v[94:95], v[116:117], v[116:117] op_sel:[0,1] op_sel_hi:[0,1]
	v_pk_add_f32 v[98:99], v[42:43], v[94:95]
	v_pk_add_f32 v[94:95], v[42:43], v[94:95] op_sel_hi:[0,1] neg_lo:[0,1] neg_hi:[0,1]
	v_cvt_pk_f16_f32 v42, v98, v95
	v_lshlrev_b32_e32 v94, 16, v97
	v_add_co_u32_e32 v98, vcc, s31, v44
	v_or_b32_sdwa v95, v105, v42 dst_sel:DWORD dst_unused:UNUSED_PAD src0_sel:DWORD src1_sel:WORD_1
	v_or_b32_sdwa v94, v94, v42 dst_sel:DWORD dst_unused:UNUSED_PAD src0_sel:DWORD src1_sel:WORD_0
	v_addc_co_u32_e32 v99, vcc, 0, v45, vcc
	global_store_dwordx2 v[98:99], v[94:95], off offset:-4096
	v_pk_mul_f32 v[94:95], v[112:113], s[68:69]
	v_pk_add_f32 v[74:75], v[74:75], v[110:111] neg_lo:[0,1] neg_hi:[0,1]
	v_mul_f32_e32 v42, 0.5, v114
	v_pk_add_f32 v[110:111], v[40:41], v[94:95] op_sel:[0,1] op_sel_hi:[0,1] neg_lo:[0,1] neg_hi:[0,1]
	v_pk_fma_f32 v[116:117], v[112:113], s[68:69], v[40:41] op_sel_hi:[1,1,0]
	v_mov_b32_e32 v114, v74
	v_mov_b32_e32 v111, v117
	v_pk_mul_f32 v[114:115], v[114:115], s[74:75]
	s_mov_b32 s45, s41
	v_pk_mul_f32 v[116:117], v[110:111], v[114:115] op_sel:[0,1] op_sel_hi:[1,0]
	v_pk_mul_f32 v[114:115], v[110:111], v[114:115]
	s_mov_b32 s65, s67
	v_sub_f32_e32 v40, v114, v115
	v_fma_mixlo_f16 v97, v75, s75, v40
	v_fma_f32 v40, v75, 0.5, -v40
	v_cvt_f16_f32_sdwa v40, -v40 dst_sel:WORD_1 dst_unused:UNUSED_PAD src0_sel:DWORD
	v_pk_add_f32 v[74:75], v[116:117], v[116:117] op_sel:[0,1] op_sel_hi:[0,1]
	v_pk_add_f32 v[114:115], v[42:43], v[74:75]
	v_pk_add_f32 v[74:75], v[42:43], v[74:75] op_sel_hi:[0,1] neg_lo:[0,1] neg_hi:[0,1]
	v_cvt_pk_f16_f32 v42, v114, v75
	v_lshlrev_b32_e32 v74, 16, v97
	v_or_b32_sdwa v75, v40, v42 dst_sel:DWORD dst_unused:UNUSED_PAD src0_sel:DWORD src1_sel:WORD_1
	v_or_b32_sdwa v74, v74, v42 dst_sel:DWORD dst_unused:UNUSED_PAD src0_sel:DWORD src1_sel:WORD_0
	global_store_dwordx2 v[98:99], v[74:75], off
	v_pk_fma_f32 v[74:75], v[112:113], s[68:69], v[94:95] op_sel:[0,0,1] op_sel_hi:[1,1,0] neg_lo:[0,0,1] neg_hi:[0,0,1]
	v_pk_add_f32 v[94:95], v[68:69], v[108:109]
	v_pk_add_f32 v[68:69], v[68:69], v[108:109] neg_lo:[0,1] neg_hi:[0,1]
	v_mul_f32_e32 v40, 0.5, v94
	v_mov_b32_e32 v94, v68
	v_pk_mul_f32 v[94:95], v[94:95], s[74:75]
	v_mov_b32_e32 v75, v110
	v_mov_b32_e32 v111, v74
	v_pk_mul_f32 v[74:75], v[74:75], v[94:95]
	v_pk_mul_f32 v[98:99], v[110:111], v[94:95]
	v_sub_f32_e32 v42, v74, v75
	v_fma_mixlo_f16 v94, v69, s75, v42
	v_fma_f32 v42, v69, 0.5, -v42
	v_cvt_f16_f32_sdwa v42, -v42 dst_sel:WORD_1 dst_unused:UNUSED_PAD src0_sel:DWORD
	v_pk_add_f32 v[68:69], v[98:99], v[98:99] op_sel:[1,0] op_sel_hi:[1,0]
	s_nop 0
	v_pk_add_f32 v[74:75], v[40:41], v[68:69]
	v_pk_add_f32 v[68:69], v[40:41], v[68:69] op_sel_hi:[0,1] neg_lo:[0,1] neg_hi:[0,1]
	v_cvt_pk_f16_f32 v40, v74, v69
	v_lshlrev_b32_e32 v68, 16, v94
	v_add_co_u32_e32 v74, vcc, s30, v44
	v_or_b32_sdwa v69, v42, v40 dst_sel:DWORD dst_unused:UNUSED_PAD src0_sel:DWORD src1_sel:WORD_1
	v_or_b32_sdwa v68, v68, v40 dst_sel:DWORD dst_unused:UNUSED_PAD src0_sel:DWORD src1_sel:WORD_0
	v_addc_co_u32_e32 v75, vcc, 0, v45, vcc
	global_store_dwordx2 v[74:75], v[68:69], off offset:-4096
	v_mov_b32_e32 v42, v71
	v_pk_mul_f32 v[68:69], v[70:71], s[78:79] op_sel_hi:[0,1]
	v_pk_add_f32 v[94:95], v[72:73], v[106:107]
	v_pk_add_f32 v[72:73], v[72:73], v[106:107] neg_lo:[0,1] neg_hi:[0,1]
	v_mul_f32_e32 v40, 0.5, v94
	v_pk_fma_f32 v[98:99], v[42:43], s[50:51], v[68:69] op_sel_hi:[0,1,1] neg_lo:[0,0,1] neg_hi:[0,0,1]
	v_pk_fma_f32 v[106:107], v[42:43], s[50:51], v[68:69] op_sel_hi:[0,1,1]
	v_mov_b32_e32 v94, v72
	v_mov_b32_e32 v108, v98
	v_mov_b32_e32 v109, v107
	v_pk_mul_f32 v[94:95], v[94:95], s[74:75]
	s_mov_b32 s78, s41
	v_pk_mul_f32 v[110:111], v[108:109], v[94:95] op_sel:[0,1] op_sel_hi:[1,0]
	v_pk_mul_f32 v[94:95], v[108:109], v[94:95]
	s_mov_b32 s79, s44
	v_sub_f32_e32 v72, v94, v95
	v_fma_mixlo_f16 v97, v73, s75, v72
	v_fma_f32 v72, v73, 0.5, -v72
	v_cvt_f16_f32_sdwa v105, -v72 dst_sel:WORD_1 dst_unused:UNUSED_PAD src0_sel:DWORD
	v_pk_add_f32 v[72:73], v[110:111], v[110:111] op_sel:[0,1] op_sel_hi:[0,1]
	v_pk_add_f32 v[94:95], v[40:41], v[72:73]
	v_pk_add_f32 v[72:73], v[40:41], v[72:73] op_sel_hi:[0,1] neg_lo:[0,1] neg_hi:[0,1]
	v_cvt_pk_f16_f32 v40, v94, v73
	v_lshlrev_b32_e32 v72, 16, v97
	v_or_b32_sdwa v73, v105, v40 dst_sel:DWORD dst_unused:UNUSED_PAD src0_sel:DWORD src1_sel:WORD_1
	v_or_b32_sdwa v72, v72, v40 dst_sel:DWORD dst_unused:UNUSED_PAD src0_sel:DWORD src1_sel:WORD_0
	global_store_dwordx2 v[74:75], v[72:73], off
	v_pk_add_f32 v[72:73], v[62:63], v[102:103]
	v_sub_f32_e32 v75, v63, v103
	v_mov_b32_e32 v105, v62
	v_pk_mov_b32 v[62:63], v[68:69], v[102:103] op_sel:[1,0]
	v_mul_f32_e32 v40, 0.5, v73
	v_pk_add_f32 v[62:63], v[104:105], v[62:63] neg_lo:[0,1] neg_hi:[0,1]
	v_mul_f32_e32 v74, 0.5, v72
	v_pk_mul_f32 v[94:95], v[62:63], v[40:41]
	s_nop 0
	v_mul_f32_e32 v62, v62, v95
	v_fma_f32 v40, -v98, v40, v62
	v_fma_mixlo_f16 v69, v75, s75, v40
	v_fma_f32 v40, v75, 0.5, -v40
	v_pk_fma_f32 v[102:103], v[98:99], v[94:95], v[94:95] op_sel:[0,1,0] op_sel_hi:[1,0,1]
	v_cvt_f16_f32_sdwa v40, -v40 dst_sel:WORD_1 dst_unused:UNUSED_PAD src0_sel:DWORD
	v_pk_add_f32 v[62:63], v[74:75], v[102:103]
	v_lshlrev_b32_e32 v69, 16, v69
	v_fma_f32 v63, v72, 0.5, -v102
	v_cvt_pk_f16_f32 v62, v62, v63
	v_add_co_u32_e32 v72, vcc, s33, v44
	v_or_b32_sdwa v63, v40, v62 dst_sel:DWORD dst_unused:UNUSED_PAD src0_sel:DWORD src1_sel:WORD_1
	v_or_b32_sdwa v62, v69, v62 dst_sel:DWORD dst_unused:UNUSED_PAD src0_sel:DWORD src1_sel:WORD_0
	v_addc_co_u32_e32 v73, vcc, 0, v45, vcc
	global_store_dwordx2 v[72:73], v[62:63], off offset:-4096
	v_pk_add_f32 v[62:63], v[100:101], v[60:61]
	v_pk_add_f32 v[60:61], v[60:61], v[100:101] neg_lo:[0,1] neg_hi:[0,1]
	v_mul_f32_e32 v40, 0.5, v62
	v_mov_b32_e32 v62, v60
	v_pk_mov_b32 v[74:75], v[98:99], v[106:107] op_sel:[1,0]
	v_pk_mul_f32 v[62:63], v[62:63], s[74:75]
	s_nop 0
	v_pk_mul_f32 v[94:95], v[74:75], v[62:63] op_sel:[0,1] op_sel_hi:[1,0]
	v_pk_mul_f32 v[62:63], v[74:75], v[62:63]
	s_nop 0
	v_sub_f32_e32 v60, v62, v63
	v_fma_mixlo_f16 v69, v61, s75, v60
	v_fma_f32 v60, v61, 0.5, -v60
	v_cvt_f16_f32_sdwa v97, -v60 dst_sel:WORD_1 dst_unused:UNUSED_PAD src0_sel:DWORD
	v_pk_add_f32 v[60:61], v[94:95], v[94:95] op_sel:[0,1] op_sel_hi:[0,1]
	v_pk_add_f32 v[62:63], v[40:41], v[60:61]
	v_pk_add_f32 v[60:61], v[40:41], v[60:61] op_sel_hi:[0,1] neg_lo:[0,1] neg_hi:[0,1]
	v_cvt_pk_f16_f32 v40, v62, v61
	v_lshlrev_b32_e32 v60, 16, v69
	v_or_b32_sdwa v61, v97, v40 dst_sel:DWORD dst_unused:UNUSED_PAD src0_sel:DWORD src1_sel:WORD_1
	v_or_b32_sdwa v60, v60, v40 dst_sel:DWORD dst_unused:UNUSED_PAD src0_sel:DWORD src1_sel:WORD_0
	global_store_dwordx2 v[72:73], v[60:61], off
	v_pk_add_f32 v[60:61], v[92:93], v[66:67]
	v_mov_b32_e32 v97, v66
	v_mov_b32_e32 v69, v92
	v_sub_f32_e32 v63, v67, v93
	v_mul_f32_e32 v40, 0.5, v61
	v_pk_add_f32 v[66:67], v[96:97], v[68:69] neg_lo:[0,1] neg_hi:[0,1]
	v_mul_f32_e32 v62, 0.5, v60
	v_pk_mul_f32 v[68:69], v[66:67], v[40:41]
	s_nop 0
	v_mul_f32_e32 v61, v66, v69
	v_fma_f32 v40, -v99, v40, v61
	v_fma_mixlo_f16 v61, v63, s75, v40
	v_fma_f32 v40, v63, 0.5, -v40
	v_cvt_f16_f32_sdwa v40, -v40 dst_sel:WORD_1 dst_unused:UNUSED_PAD src0_sel:DWORD
	v_pk_fma_f32 v[72:73], v[74:75], v[68:69], v[68:69] op_sel:[0,1,0] op_sel_hi:[1,0,1]
	v_pk_add_f32 v[66:67], v[64:65], v[88:89]
	v_pk_add_f32 v[62:63], v[62:63], v[72:73]
	v_fma_f32 v60, v60, 0.5, -v72
	v_cvt_pk_f16_f32 v60, v62, v60
	v_lshlrev_b32_e32 v62, 16, v61
	v_or_b32_sdwa v61, v40, v60 dst_sel:DWORD dst_unused:UNUSED_PAD src0_sel:DWORD src1_sel:WORD_1
	v_or_b32_sdwa v60, v62, v60 dst_sel:DWORD dst_unused:UNUSED_PAD src0_sel:DWORD src1_sel:WORD_0
	v_add_co_u32_e32 v62, vcc, s34, v44
	v_pk_add_f32 v[64:65], v[64:65], v[88:89] neg_lo:[0,1] neg_hi:[0,1]
	s_nop 0
	v_addc_co_u32_e32 v63, vcc, 0, v45, vcc
	global_store_dwordx2 v[62:63], v[60:61], off offset:-4096
	v_pk_mul_f32 v[60:61], v[70:71], s[44:45] op_sel_hi:[0,1]
	v_mul_f32_e32 v40, 0.5, v66
	v_pk_fma_f32 v[68:69], v[42:43], s[78:79], v[60:61] op_sel_hi:[0,1,1] neg_lo:[0,0,1] neg_hi:[0,0,1]
	v_pk_fma_f32 v[72:73], v[42:43], s[78:79], v[60:61] op_sel_hi:[0,1,1]
	v_mov_b32_e32 v66, v64
	v_mov_b32_e32 v74, v68
	v_mov_b32_e32 v75, v73
	v_pk_mul_f32 v[66:67], v[66:67], s[74:75]
	s_mov_b32 s78, s67
	v_pk_mul_f32 v[88:89], v[74:75], v[66:67] op_sel:[0,1] op_sel_hi:[1,0]
	v_pk_mul_f32 v[66:67], v[74:75], v[66:67]
	s_mov_b32 s79, s64
	v_sub_f32_e32 v64, v66, v67
	v_fma_mixlo_f16 v74, v65, s75, v64
	v_fma_f32 v64, v65, 0.5, -v64
	v_cvt_f16_f32_sdwa v75, -v64 dst_sel:WORD_1 dst_unused:UNUSED_PAD src0_sel:DWORD
	v_pk_add_f32 v[64:65], v[88:89], v[88:89] op_sel:[0,1] op_sel_hi:[0,1]
	v_pk_add_f32 v[66:67], v[40:41], v[64:65]
	v_pk_add_f32 v[64:65], v[40:41], v[64:65] op_sel_hi:[0,1] neg_lo:[0,1] neg_hi:[0,1]
	v_cvt_pk_f16_f32 v40, v66, v65
	v_lshlrev_b32_e32 v64, 16, v74
	v_or_b32_sdwa v65, v75, v40 dst_sel:DWORD dst_unused:UNUSED_PAD src0_sel:DWORD src1_sel:WORD_1
	v_or_b32_sdwa v64, v64, v40 dst_sel:DWORD dst_unused:UNUSED_PAD src0_sel:DWORD src1_sel:WORD_0
	global_store_dwordx2 v[62:63], v[64:65], off
	v_mul_f32_e32 v62, 0xbe47c5c2, v71
	v_pk_add_f32 v[64:65], v[50:51], v[82:83]
	v_sub_f32_e32 v67, v51, v83
	v_mov_b32_e32 v63, v50
	v_pk_mov_b32 v[50:51], v[60:61], v[82:83] op_sel:[1,0]
	v_mul_f32_e32 v40, 0.5, v65
	v_pk_add_f32 v[50:51], v[62:63], v[50:51] neg_lo:[0,1] neg_hi:[0,1]
	v_mul_f32_e32 v66, 0.5, v64
	v_pk_mul_f32 v[62:63], v[50:51], v[40:41]
	s_nop 0
	v_mul_f32_e32 v50, v50, v63
	v_fma_f32 v40, -v68, v40, v50
	v_fma_mixlo_f16 v61, v67, s75, v40
	v_fma_f32 v40, v67, 0.5, -v40
	v_pk_fma_f32 v[74:75], v[68:69], v[62:63], v[62:63] op_sel:[0,1,0] op_sel_hi:[1,0,1]
	v_cvt_f16_f32_sdwa v40, -v40 dst_sel:WORD_1 dst_unused:UNUSED_PAD src0_sel:DWORD
	v_pk_add_f32 v[50:51], v[66:67], v[74:75]
	v_lshlrev_b32_e32 v61, 16, v61
	v_fma_f32 v51, v64, 0.5, -v74
	v_cvt_pk_f16_f32 v50, v50, v51
	v_add_co_u32_e32 v62, vcc, s35, v44
	v_or_b32_sdwa v51, v40, v50 dst_sel:DWORD dst_unused:UNUSED_PAD src0_sel:DWORD src1_sel:WORD_1
	v_or_b32_sdwa v50, v61, v50 dst_sel:DWORD dst_unused:UNUSED_PAD src0_sel:DWORD src1_sel:WORD_0
	v_addc_co_u32_e32 v63, vcc, 0, v45, vcc
	global_store_dwordx2 v[62:63], v[50:51], off offset:-4096
	v_pk_mul_f32 v[50:51], v[70:71], s[64:65] op_sel_hi:[0,1]
	v_pk_add_f32 v[64:65], v[78:79], v[56:57]
	v_pk_add_f32 v[56:57], v[56:57], v[78:79] neg_lo:[0,1] neg_hi:[0,1]
	v_mul_f32_e32 v40, 0.5, v64
	v_pk_fma_f32 v[66:67], v[42:43], s[78:79], v[50:51] op_sel_hi:[0,1,1] neg_lo:[0,0,1] neg_hi:[0,0,1]
	v_pk_fma_f32 v[74:75], v[42:43], s[78:79], v[50:51] op_sel_hi:[0,1,1]
	v_mov_b32_e32 v64, v56
	v_mov_b32_e32 v78, v66
	v_mov_b32_e32 v79, v75
	v_pk_mul_f32 v[64:65], v[64:65], s[74:75]
	s_nop 0
	v_pk_mul_f32 v[82:83], v[78:79], v[64:65] op_sel:[0,1] op_sel_hi:[1,0]
	v_pk_mul_f32 v[64:65], v[78:79], v[64:65]
	s_nop 0
	v_sub_f32_e32 v42, v64, v65
	v_fma_mixlo_f16 v61, v57, s75, v42
	v_fma_f32 v42, v57, 0.5, -v42
	v_cvt_f16_f32_sdwa v42, -v42 dst_sel:WORD_1 dst_unused:UNUSED_PAD src0_sel:DWORD
	v_pk_add_f32 v[56:57], v[82:83], v[82:83] op_sel:[0,1] op_sel_hi:[0,1]
	v_pk_add_f32 v[64:65], v[40:41], v[56:57]
	v_pk_add_f32 v[56:57], v[40:41], v[56:57] op_sel_hi:[0,1] neg_lo:[0,1] neg_hi:[0,1]
	v_cvt_pk_f16_f32 v40, v64, v57
	v_lshlrev_b32_e32 v56, 16, v61
	v_or_b32_sdwa v57, v42, v40 dst_sel:DWORD dst_unused:UNUSED_PAD src0_sel:DWORD src1_sel:WORD_1
	v_or_b32_sdwa v56, v56, v40 dst_sel:DWORD dst_unused:UNUSED_PAD src0_sel:DWORD src1_sel:WORD_0
	global_store_dwordx2 v[62:63], v[56:57], off
	v_mul_f32_e32 v56, 0xbf54db31, v71
	v_pk_add_f32 v[62:63], v[76:77], v[58:59]
	v_sub_f32_e32 v61, v59, v77
	v_mov_b32_e32 v57, v58
	v_pk_mov_b32 v[58:59], v[50:51], v[76:77] op_sel:[1,0]
	v_mul_f32_e32 v40, 0.5, v63
	v_pk_add_f32 v[56:57], v[56:57], v[58:59] neg_lo:[0,1] neg_hi:[0,1]
	v_mul_f32_e32 v42, 0.5, v62
	v_pk_mul_f32 v[58:59], v[56:57], v[40:41]
	s_nop 0
	v_mul_f32_e32 v51, v56, v59
	v_fma_f32 v40, -v66, v40, v51
	v_fma_mixlo_f16 v51, v61, s75, v40
	v_fma_f32 v40, v61, 0.5, -v40
	v_cvt_f16_f32_sdwa v40, -v40 dst_sel:WORD_1 dst_unused:UNUSED_PAD src0_sel:DWORD
	v_pk_fma_f32 v[64:65], v[66:67], v[58:59], v[58:59] op_sel:[0,1,0] op_sel_hi:[1,0,1]
	v_lshlrev_b32_e32 v51, 16, v51
	v_pk_add_f32 v[56:57], v[42:43], v[64:65]
	v_fma_f32 v42, v62, 0.5, -v64
	v_cvt_pk_f16_f32 v42, v56, v42
	v_add_co_u32_e32 v58, vcc, s39, v44
	v_or_b32_sdwa v57, v40, v42 dst_sel:DWORD dst_unused:UNUSED_PAD src0_sel:DWORD src1_sel:WORD_1
	v_or_b32_sdwa v56, v51, v42 dst_sel:DWORD dst_unused:UNUSED_PAD src0_sel:DWORD src1_sel:WORD_0
	v_addc_co_u32_e32 v59, vcc, 0, v45, vcc
	global_store_dwordx2 v[58:59], v[56:57], off offset:-4096
	v_pk_add_f32 v[56:57], v[84:85], v[54:55]
	v_pk_add_f32 v[54:55], v[54:55], v[84:85] neg_lo:[0,1] neg_hi:[0,1]
	v_mul_f32_e32 v40, 0.5, v56
	v_mov_b32_e32 v56, v54
	v_pk_mov_b32 v[62:63], v[66:67], v[74:75] op_sel:[1,0]
	v_pk_mul_f32 v[56:57], v[56:57], s[74:75]
	s_nop 0
	v_pk_mul_f32 v[64:65], v[62:63], v[56:57] op_sel:[0,1] op_sel_hi:[1,0]
	v_pk_mul_f32 v[56:57], v[62:63], v[56:57]
	s_nop 0
	v_sub_f32_e32 v42, v56, v57
	v_fma_mixlo_f16 v51, v55, s75, v42
	v_fma_f32 v42, v55, 0.5, -v42
	v_cvt_f16_f32_sdwa v42, -v42 dst_sel:WORD_1 dst_unused:UNUSED_PAD src0_sel:DWORD
	v_pk_add_f32 v[54:55], v[64:65], v[64:65] op_sel:[0,1] op_sel_hi:[0,1]
	v_pk_add_f32 v[56:57], v[40:41], v[54:55]
	v_pk_add_f32 v[54:55], v[40:41], v[54:55] op_sel_hi:[0,1] neg_lo:[0,1] neg_hi:[0,1]
	v_cvt_pk_f16_f32 v40, v56, v55
	v_lshlrev_b32_e32 v51, 16, v51
	v_or_b32_sdwa v55, v42, v40 dst_sel:DWORD dst_unused:UNUSED_PAD src0_sel:DWORD src1_sel:WORD_1
	v_or_b32_sdwa v54, v51, v40 dst_sel:DWORD dst_unused:UNUSED_PAD src0_sel:DWORD src1_sel:WORD_0
	global_store_dwordx2 v[58:59], v[54:55], off
	v_mul_f32_e32 v54, 0xbf0e39da, v71
	v_pk_add_f32 v[56:57], v[80:81], v[48:49]
	v_mov_b32_e32 v55, v48
	v_mov_b32_e32 v51, v80
	v_sub_f32_e32 v58, v49, v81
	v_mul_f32_e32 v40, 0.5, v57
	v_pk_add_f32 v[48:49], v[54:55], v[50:51] neg_lo:[0,1] neg_hi:[0,1]
	v_mul_f32_e32 v42, 0.5, v56
	v_pk_mul_f32 v[50:51], v[48:49], v[40:41]
	s_nop 0
	v_mul_f32_e32 v48, v48, v51
	v_fma_f32 v40, -v67, v40, v48
	v_pk_fma_f32 v[54:55], v[62:63], v[50:51], v[50:51] op_sel:[0,1,0] op_sel_hi:[1,0,1]
	v_fma_mixlo_f16 v50, v58, s75, v40
	v_fma_f32 v40, v58, 0.5, -v40
	v_cvt_f16_f32_sdwa v40, -v40 dst_sel:WORD_1 dst_unused:UNUSED_PAD src0_sel:DWORD
	v_pk_add_f32 v[48:49], v[42:43], v[54:55]
	v_fma_f32 v42, v56, 0.5, -v54
	v_cvt_pk_f16_f32 v42, v48, v42
	v_lshlrev_b32_e32 v48, 16, v50
	v_add_co_u32_e32 v50, vcc, s43, v44
	v_or_b32_sdwa v49, v40, v42 dst_sel:DWORD dst_unused:UNUSED_PAD src0_sel:DWORD src1_sel:WORD_1
	v_or_b32_sdwa v48, v48, v42 dst_sel:DWORD dst_unused:UNUSED_PAD src0_sel:DWORD src1_sel:WORD_0
	v_addc_co_u32_e32 v51, vcc, 0, v45, vcc
	global_store_dwordx2 v[50:51], v[48:49], off offset:-4096
	v_pk_add_f32 v[48:49], v[86:87], v[46:47]
	v_pk_add_f32 v[46:47], v[46:47], v[86:87] neg_lo:[0,1] neg_hi:[0,1]
	v_mul_f32_e32 v40, 0.5, v48
	v_mov_b32_e32 v48, v46
	v_pk_mov_b32 v[54:55], v[68:69], v[72:73] op_sel:[1,0]
	v_pk_mul_f32 v[48:49], v[48:49], s[74:75]
	s_nop 0
	v_pk_mul_f32 v[56:57], v[54:55], v[48:49] op_sel:[0,1] op_sel_hi:[1,0]
	v_pk_mul_f32 v[48:49], v[54:55], v[48:49]
	s_nop 0
	v_sub_f32_e32 v42, v48, v49
	v_fma_mixlo_f16 v54, v47, s75, v42
	v_fma_f32 v42, v47, 0.5, -v42
	v_pk_add_f32 v[46:47], v[56:57], v[56:57] op_sel:[0,1] op_sel_hi:[0,1]
	v_pk_add_f32 v[48:49], v[40:41], v[46:47]
	v_pk_add_f32 v[46:47], v[40:41], v[46:47] op_sel_hi:[0,1] neg_lo:[0,1] neg_hi:[0,1]
	v_cvt_pk_f16_f32 v56, v48, v47
	v_pk_add_f32 v[46:47], v[52:53], v[90:91]
	v_pk_add_f32 v[48:49], v[52:53], v[90:91] neg_lo:[0,1] neg_hi:[0,1]
	v_mov_b32_e32 v52, v46
	v_mov_b32_e32 v53, v49
	v_mov_b32_e32 v49, v47
	v_pk_mul_f32 v[46:47], v[48:49], s[74:75]
	v_fma_f32 v40, v71, s40, -v60
	v_pk_mul_f32 v[48:49], v[68:69], v[46:47] op_sel:[1,0]
	v_lshlrev_b32_e32 v57, 16, v54
	v_pk_fma_f32 v[54:55], v[40:41], v[46:47], v[48:49] op_sel:[0,1,0] op_sel_hi:[0,0,1] neg_hi:[0,0,1]
	s_nop 0
	s_nop 0
	v_pk_fma_f32 v[46:47], v[52:53], 0.5, v[54:55] op_sel_hi:[1,0,1]
	v_cvt_f16_f32_sdwa v42, -v42 dst_sel:WORD_1 dst_unused:UNUSED_PAD src0_sel:DWORD
	v_cvt_f16_f32_e32 v40, v46
	v_cvt_f16_f32_sdwa v48, v47 dst_sel:WORD_1 dst_unused:UNUSED_PAD src0_sel:DWORD
	v_or_b32_sdwa v46, v57, v56 dst_sel:DWORD dst_unused:UNUSED_PAD src0_sel:DWORD src1_sel:WORD_0
	v_or_b32_sdwa v47, v42, v56 dst_sel:DWORD dst_unused:UNUSED_PAD src0_sel:DWORD src1_sel:WORD_1
	v_pk_fma_f32 v[116:117], v[52:53], 0.5, v[54:55] op_sel_hi:[1,0,1] neg_lo:[0,0,1] neg_hi:[0,0,1]
	v_or_b32_e32 v114, v48, v40
	global_store_dwordx2 v[50:51], v[46:47], off

.LBB0_428:
	s_ashr_i32 s17, s16, 31
	s_lshl_b64 s[6:7], s[16:17], 2
	s_add_u32 s6, s48, s6
	s_addc_u32 s7, s49, s7
	global_load_dwordx2 v[40:41], v151, s[6:7]
	s_waitcnt vmcnt(0)
	v_cvt_f32_f16_e32 v36, v10
	v_cvt_f32_f16_sdwa v42, v10 dst_sel:DWORD dst_unused:UNUSED_PAD src0_sel:WORD_1
	v_cvt_f32_f16_e32 v43, v11
	v_cvt_f32_f16_e32 v45, v12
	v_cvt_f32_f16_sdwa v46, v12 dst_sel:DWORD dst_unused:UNUSED_PAD src0_sel:WORD_1
	v_cvt_f32_f16_e32 v47, v13
	v_cvt_f32_f16_sdwa v12, v13 dst_sel:DWORD dst_unused:UNUSED_PAD src0_sel:WORD_1
	v_cvt_f32_f16_e32 v13, v30
	v_cvt_f32_f16_sdwa v50, v26 dst_sel:DWORD dst_unused:UNUSED_PAD src0_sel:WORD_1
	v_cvt_f32_f16_e32 v51, v27
	v_cvt_f32_f16_sdwa v44, v11 dst_sel:DWORD dst_unused:UNUSED_PAD src0_sel:WORD_1
	v_cvt_f32_f16_sdwa v48, v30 dst_sel:DWORD dst_unused:UNUSED_PAD src0_sel:WORD_1
	v_cvt_f32_f16_e32 v49, v31
	v_cvt_f32_f16_sdwa v30, v31 dst_sel:DWORD dst_unused:UNUSED_PAD src0_sel:WORD_1
	v_cvt_f32_f16_e32 v31, v32
	v_cvt_f32_f16_sdwa v11, v33 dst_sel:DWORD dst_unused:UNUSED_PAD src0_sel:WORD_1
	v_cvt_f32_f16_sdwa v32, v32 dst_sel:DWORD dst_unused:UNUSED_PAD src0_sel:WORD_1
	v_cvt_f32_f16_e32 v33, v33
	v_cvt_f32_f16_sdwa v26, v27 dst_sel:DWORD dst_unused:UNUSED_PAD src0_sel:WORD_1
	v_cvt_f32_f16_e32 v27, v28
	v_cvt_f32_f16_sdwa v52, v28 dst_sel:DWORD dst_unused:UNUSED_PAD src0_sel:WORD_1
	v_cvt_f32_f16_e32 v53, v29
	v_cvt_f32_f16_e32 v28, v22
	v_cvt_f32_f16_sdwa v54, v22 dst_sel:DWORD dst_unused:UNUSED_PAD src0_sel:WORD_1
	v_cvt_f32_f16_e32 v55, v23
	v_cvt_f32_f16_sdwa v22, v23 dst_sel:DWORD dst_unused:UNUSED_PAD src0_sel:WORD_1
	v_cvt_f32_f16_e32 v23, v24
	v_cvt_f32_f16_sdwa v56, v24 dst_sel:DWORD dst_unused:UNUSED_PAD src0_sel:WORD_1
	v_cvt_f32_f16_e32 v57, v25
	v_cvt_f32_f16_sdwa v29, v29 dst_sel:DWORD dst_unused:UNUSED_PAD src0_sel:WORD_1
	v_cvt_f32_f16_sdwa v25, v25 dst_sel:DWORD dst_unused:UNUSED_PAD src0_sel:WORD_1
	v_cvt_f32_f16_e32 v24, v38
	v_cvt_f32_f16_sdwa v60, v19 dst_sel:DWORD dst_unused:UNUSED_PAD src0_sel:WORD_1
	v_cvt_f32_f16_e32 v61, v20
	v_cvt_f32_f16_e32 v38, v18
	v_cvt_f32_f16_e32 v59, v19
	v_mul_f32_e32 v19, 0x3b800000, v36
	v_pk_mul_f32 v[42:43], v[42:43], s[24:25] op_sel_hi:[1,0]
	v_pk_mul_f32 v[12:13], v[12:13], s[24:25] op_sel_hi:[1,0]
	v_pk_mul_f32 v[50:51], v[50:51], s[24:25] op_sel_hi:[1,0]
	v_pk_mul_f32 v[44:45], v[44:45], s[24:25] op_sel_hi:[1,0]
	v_pk_mul_f32 v[46:47], v[46:47], s[24:25] op_sel_hi:[1,0]
	v_pk_mul_f32 v[48:49], v[48:49], s[24:25] op_sel_hi:[1,0]
	v_pk_mul_f32 v[30:31], v[30:31], s[24:25] op_sel_hi:[1,0]
	v_mul_f32_e32 v11, 0x3b800000, v11
	v_pk_mul_f32 v[32:33], v[32:33], s[24:25] op_sel_hi:[1,0]
	v_pk_mul_f32 v[26:27], v[26:27], s[24:25] op_sel_hi:[1,0]
	v_pk_mul_f32 v[52:53], v[52:53], s[24:25] op_sel_hi:[1,0]
	v_pk_mul_f32 v[54:55], v[54:55], s[24:25] op_sel_hi:[1,0]
	v_pk_mul_f32 v[22:23], v[22:23], s[24:25] op_sel_hi:[1,0]
	v_pk_mul_f32 v[56:57], v[56:57], s[24:25] op_sel_hi:[1,0]
	ds_write2_b32 v131, v42, v43 offset0:1 offset1:2
	ds_write2_b32 v131, v44, v45 offset0:3 offset1:4
	ds_write2_b32 v131, v46, v47 offset0:5 offset1:6
	ds_write2_b32 v131, v12, v13 offset0:7 offset1:8
	ds_write2_b32 v131, v48, v49 offset0:9 offset1:10
	ds_write2_b32 v131, v30, v31 offset0:11 offset1:12
	ds_write2_b32 v131, v32, v33 offset0:13 offset1:14
	v_pk_mov_b32 v[12:13], v[50:51], v[50:51] op_sel:[1,0]
	v_pk_mul_f32 v[28:29], v[28:29], s[24:25] op_sel_hi:[1,0]
	v_pk_mul_f32 v[24:25], v[24:25], s[24:25] op_sel_hi:[1,0]
	v_pk_mov_b32 v[26:27], v[26:27], v[26:27] op_sel:[1,0]
	v_pk_mov_b32 v[30:31], v[52:53], v[52:53] op_sel:[1,0]
	v_pk_mov_b32 v[32:33], v[54:55], v[54:55] op_sel:[1,0]
	v_pk_mov_b32 v[22:23], v[22:23], v[22:23] op_sel:[1,0]
	v_pk_mov_b32 v[42:43], v[56:57], v[56:57] op_sel:[1,0]
	v_cvt_f32_f16_sdwa v58, v18 dst_sel:DWORD dst_unused:UNUSED_PAD src0_sel:WORD_1
	v_mul_f32_e32 v36, 0x3b800000, v38
	s_mov_b32 s6, s65
	v_pk_mul_f32 v[58:59], v[58:59], s[24:25] op_sel_hi:[1,0]
	v_fma_mix_f32 v10, v10, s24, v40 op_sel_hi:[1,0,0]
	s_nop 0
	v_cndmask_b32_e64 v10, v19, v10, s[4:5]
	ds_write2_b32 v131, v10, v11 offset1:15
	ds_write_b64 v132, v[12:13] offset:32824
	ds_write_b64 v133, v[26:27] offset:32824
	ds_write_b64 v134, v[30:31] offset:32824
	ds_write_b64 v135, v[28:29] offset:32824
	ds_write_b64 v136, v[32:33] offset:32824
	ds_write_b64 v137, v[22:23] offset:32824
	ds_write_b64 v138, v[42:43] offset:32824
	ds_write_b64 v139, v[24:25] offset:32824
	v_cvt_f32_f16_sdwa v10, v20 dst_sel:DWORD dst_unused:UNUSED_PAD src0_sel:WORD_1
	v_cvt_f32_f16_e32 v11, v21
	v_pk_mul_f32 v[12:13], v[60:61], s[24:25] op_sel_hi:[1,0]
	v_fma_mix_f32 v18, v18, s24, v41 op_sel_hi:[1,0,0]
	ds_write2_b32 v140, v12, v13 offset0:3 offset1:4
	v_cvt_f32_f16_sdwa v12, v21 dst_sel:DWORD dst_unused:UNUSED_PAD src0_sel:WORD_1
	v_cvt_f32_f16_e32 v13, v14
	v_cndmask_b32_e64 v36, v36, v18, s[4:5]
	v_cvt_f32_f16_sdwa v18, v14 dst_sel:DWORD dst_unused:UNUSED_PAD src0_sel:WORD_1
	v_cvt_f32_f16_e32 v19, v15
	v_pk_mul_f32 v[10:11], v[10:11], s[24:25] op_sel_hi:[1,0]
	ds_write2_b32 v140, v10, v11 offset0:5 offset1:6
	v_pk_mul_f32 v[10:11], v[12:13], s[24:25] op_sel_hi:[1,0]
	ds_write2_b32 v140, v10, v11 offset0:7 offset1:8
	v_pk_mul_f32 v[10:11], v[18:19], s[24:25] op_sel_hi:[1,0]
	ds_write2_b32 v140, v10, v11 offset0:9 offset1:10
	v_cvt_f32_f16_sdwa v10, v15 dst_sel:DWORD dst_unused:UNUSED_PAD src0_sel:WORD_1
	v_cvt_f32_f16_e32 v11, v16
	v_cvt_f32_f16_sdwa v12, v16 dst_sel:DWORD dst_unused:UNUSED_PAD src0_sel:WORD_1
	v_cvt_f32_f16_e32 v13, v17
	v_cvt_f32_f16_sdwa v14, v17 dst_sel:DWORD dst_unused:UNUSED_PAD src0_sel:WORD_1
	v_pk_mul_f32 v[10:11], v[10:11], s[24:25] op_sel_hi:[1,0]
	ds_write2_b32 v140, v10, v11 offset0:11 offset1:12
	v_pk_mul_f32 v[10:11], v[12:13], s[24:25] op_sel_hi:[1,0]
	ds_write2_b32 v140, v10, v11 offset0:13 offset1:14
	v_cvt_f32_f16_sdwa v10, v6 dst_sel:DWORD dst_unused:UNUSED_PAD src0_sel:WORD_1
	v_cvt_f32_f16_e32 v11, v7
	v_cvt_f32_f16_sdwa v6, v7 dst_sel:DWORD dst_unused:UNUSED_PAD src0_sel:WORD_1
	v_cvt_f32_f16_e32 v7, v8
	v_mul_f32_e32 v14, 0x3b800000, v14
	v_pk_mul_f32 v[10:11], v[10:11], s[24:25] op_sel_hi:[1,0]
	ds_write2_b32 v140, v58, v59 offset0:1 offset1:2
	v_pk_mov_b32 v[10:11], v[10:11], v[10:11] op_sel:[1,0]
	ds_write2_b32 v140, v36, v14 offset1:15
	ds_write_b64 v141, v[10:11] offset:32824
	v_cvt_f32_f16_sdwa v10, v8 dst_sel:DWORD dst_unused:UNUSED_PAD src0_sel:WORD_1
	v_cvt_f32_f16_e32 v11, v9
	v_pk_mul_f32 v[6:7], v[6:7], s[24:25] op_sel_hi:[1,0]
	s_nop 0
	v_pk_mov_b32 v[6:7], v[6:7], v[6:7] op_sel:[1,0]
	ds_write_b64 v142, v[6:7] offset:32824
	v_cvt_f32_f16_sdwa v7, v9 dst_sel:DWORD dst_unused:UNUSED_PAD src0_sel:WORD_1
	v_pk_mul_f32 v[8:9], v[10:11], s[24:25] op_sel_hi:[1,0]
	v_cvt_f32_f16_e32 v6, v2
	v_pk_mov_b32 v[8:9], v[8:9], v[8:9] op_sel:[1,0]
	ds_write_b64 v143, v[8:9] offset:32824
	v_cvt_f32_f16_sdwa v8, v2 dst_sel:DWORD dst_unused:UNUSED_PAD src0_sel:WORD_1
	v_cvt_f32_f16_e32 v9, v3
	v_cvt_f32_f16_sdwa v2, v3 dst_sel:DWORD dst_unused:UNUSED_PAD src0_sel:WORD_1
	v_cvt_f32_f16_e32 v3, v4
	v_pk_mul_f32 v[6:7], v[6:7], s[24:25] op_sel_hi:[1,0]
	ds_write_b64 v144, v[6:7] offset:32824
	v_pk_mul_f32 v[6:7], v[8:9], s[24:25] op_sel_hi:[1,0]
	v_pk_mul_f32 v[2:3], v[2:3], s[24:25] op_sel_hi:[1,0]
	v_pk_mov_b32 v[6:7], v[6:7], v[6:7] op_sel:[1,0]
	ds_write_b64 v145, v[6:7] offset:32824
	v_pk_mov_b32 v[2:3], v[2:3], v[2:3] op_sel:[1,0]
	v_cvt_f32_f16_sdwa v6, v4 dst_sel:DWORD dst_unused:UNUSED_PAD src0_sel:WORD_1
	v_cvt_f32_f16_e32 v7, v5
	ds_write_b64 v148, v[2:3] offset:32824
	v_cvt_f32_f16_sdwa v3, v5 dst_sel:DWORD dst_unused:UNUSED_PAD src0_sel:WORD_1
	v_cvt_f32_f16_e32 v2, v39
	v_pk_mul_f32 v[4:5], v[6:7], s[24:25] op_sel_hi:[1,0]
	v_pk_mul_f32 v[2:3], v[2:3], s[24:25] op_sel_hi:[1,0]
	v_pk_mov_b32 v[4:5], v[4:5], v[4:5] op_sel:[1,0]
	ds_write_b64 v149, v[4:5] offset:32824
	ds_write_b64 v150, v[2:3] offset:32824
	v_mov_b32_e32 v2, v130
	s_waitcnt lgkmcnt(0)
	s_barrier
	s_nop 0
	v_and_b32_e32 v3, 0xff, v2
	v_lshlrev_b32_e32 v4, 5, v2
	v_and_or_b32 v3, v4, s29, v3
	v_ashrrev_i32_e32 v4, 5, v3
	v_lshlrev_b32_e32 v3, 3, v3
	v_lshlrev_b32_e32 v6, 3, v4
	v_add3_u32 v36, 0, v3, v6
	ds_read_b64 v[154:155], v36
	ds_read_b64 v[156:157], v36 offset:2112
	ds_read_b64 v[158:159], v36 offset:4224
	ds_read_b64 v[160:161], v36 offset:6336
	ds_read_b64 v[162:163], v36 offset:8448
	ds_read_b64 v[164:165], v36 offset:10560
	ds_read_b64 v[166:167], v36 offset:12672
	ds_read_b64 v[168:169], v36 offset:14784
	ds_read_b64 v[170:171], v36 offset:16896
	ds_read_b64 v[172:173], v36 offset:19008
	ds_read_b64 v[174:175], v36 offset:21120
	ds_read_b64 v[176:177], v36 offset:23232
	ds_read_b64 v[178:179], v36 offset:25344
	ds_read_b64 v[180:181], v36 offset:27456
	ds_read_b64 v[182:183], v36 offset:29568
	ds_read_b64 v[184:185], v36 offset:31680
	ds_read_b64 v[186:187], v36 offset:33792
	ds_read_b64 v[188:189], v36 offset:35904
	ds_read_b64 v[190:191], v36 offset:38016
	ds_read_b64 v[192:193], v36 offset:40128
	ds_read_b64 v[194:195], v36 offset:42240
	ds_read_b64 v[196:197], v36 offset:44352
	ds_read_b64 v[198:199], v36 offset:46464
	ds_read_b64 v[204:205], v36 offset:48576
	ds_read_b64 v[206:207], v36 offset:50688
	ds_read_b64 v[208:209], v36 offset:52800
	ds_read_b64 v[210:211], v36 offset:54912
	ds_read_b64 v[212:213], v36 offset:57024
	ds_read_b64 v[214:215], v36 offset:59136
	ds_read_b64 v[216:217], v36 offset:61248
	ds_read_b64 v[218:219], v36 offset:63360
	ds_read_b64 v[220:221], v36 offset:65472
	s_waitcnt lgkmcnt(14)
	v_pk_add_f32 v[222:223], v[154:155], v[186:187]
	v_pk_add_f32 v[154:155], v[154:155], v[186:187] neg_lo:[0,1] neg_hi:[0,1]
	v_pk_add_f32 v[186:187], v[156:157], v[188:189]
	v_pk_add_f32 v[156:157], v[156:157], v[188:189] neg_lo:[0,1] neg_hi:[0,1]
	v_cvt_f32_ubyte0_e32 v2, v2
	v_pk_mul_f32 v[188:189], v[156:157], s[40:41]
	v_mul_f32_e32 v5, 0x39000000, v2
	v_pk_fma_f32 v[156:157], v[156:157], s[36:37], v[188:189] op_sel:[0,0,1] op_sel_hi:[1,0,0]
	s_waitcnt lgkmcnt(13)
	v_pk_add_f32 v[188:189], v[158:159], v[190:191]
	v_pk_add_f32 v[158:159], v[158:159], v[190:191] neg_lo:[0,1] neg_hi:[0,1]
	v_sin_f32_e32 v2, v5
	v_pk_mul_f32 v[190:191], v[158:159], s[44:45]
	v_cos_f32_e32 v4, v5
	v_pk_fma_f32 v[158:159], v[158:159], s[42:43], v[190:191] op_sel:[0,0,1] op_sel_hi:[1,0,0]
	s_waitcnt lgkmcnt(12)
	v_pk_add_f32 v[190:191], v[160:161], v[192:193]
	v_pk_add_f32 v[160:161], v[160:161], v[192:193] neg_lo:[0,1] neg_hi:[0,1]
	v_xor_b32_e32 v5, 0x80000000, v2
	v_pk_mul_f32 v[192:193], v[160:161], s[62:63]
	v_mov_b32_e32 v3, v5
	v_pk_fma_f32 v[160:161], v[160:161], s[50:51], v[192:193] op_sel:[0,0,1] op_sel_hi:[1,0,0]
	s_waitcnt lgkmcnt(11)
	v_pk_add_f32 v[192:193], v[162:163], v[194:195]
	v_pk_add_f32 v[162:163], v[162:163], v[194:195] neg_lo:[0,1] neg_hi:[0,1]
	v_pk_mul_f32 v[6:7], v[4:5], v[2:3] op_sel:[1,0] op_sel_hi:[0,1]
	v_pk_mul_f32 v[194:195], v[162:163], s[68:69]
	v_pk_fma_f32 v[6:7], v[4:5], v[4:5], v[6:7] op_sel_hi:[1,0,1]
	v_pk_fma_f32 v[162:163], v[162:163], s[64:65], v[194:195] op_sel:[0,0,1] op_sel_hi:[1,0,0]
	s_waitcnt lgkmcnt(10)
	v_pk_add_f32 v[194:195], v[164:165], v[196:197]
	v_pk_add_f32 v[164:165], v[164:165], v[196:197] neg_lo:[0,1] neg_hi:[0,1]
	v_xor_b32_e32 v12, 0x80000000, v7
	v_pk_mul_f32 v[196:197], v[164:165], s[70:71]
	v_mov_b32_e32 v13, v7
	v_pk_fma_f32 v[164:165], v[164:165], s[46:47], v[196:197] op_sel:[0,0,1] op_sel_hi:[1,0,0]
	s_waitcnt lgkmcnt(9)
	v_pk_add_f32 v[196:197], v[166:167], v[198:199]
	v_pk_add_f32 v[166:167], v[166:167], v[198:199] neg_lo:[0,1] neg_hi:[0,1]
	v_pk_mul_f32 v[10:11], v[6:7], v[12:13] op_sel:[1,0] op_sel_hi:[0,1]
	v_pk_mul_f32 v[198:199], v[166:167], s[76:77]
	v_pk_fma_f32 v[10:11], v[6:7], v[6:7], v[10:11] op_sel_hi:[1,0,1]
	v_pk_fma_f32 v[166:167], v[166:167], s[72:73], v[198:199] op_sel:[0,0,1] op_sel_hi:[1,0,0]
	s_waitcnt lgkmcnt(8)
	v_pk_add_f32 v[198:199], v[168:169], v[204:205]
	v_pk_add_f32 v[168:169], v[168:169], v[204:205] neg_lo:[0,1] neg_hi:[0,1]
	v_xor_b32_e32 v14, 0x80000000, v11
	v_pk_mul_f32 v[204:205], v[168:169], s[26:27]
	v_mov_b32_e32 v15, v11
	v_pk_fma_f32 v[168:169], v[168:169], s[38:39], v[204:205] op_sel:[0,0,1] op_sel_hi:[1,0,0]
	s_waitcnt lgkmcnt(7)
	v_pk_add_f32 v[204:205], v[170:171], v[206:207]
	v_pk_add_f32 v[206:207], v[170:171], v[206:207] neg_lo:[0,1] neg_hi:[0,1]
	v_pk_mul_f32 v[26:27], v[10:11], v[14:15] op_sel:[1,0] op_sel_hi:[0,1]
	s_waitcnt lgkmcnt(6)
	v_pk_add_f32 v[170:171], v[172:173], v[208:209]
	v_pk_add_f32 v[172:173], v[172:173], v[208:209] neg_lo:[0,1] neg_hi:[0,1]
	v_pk_fma_f32 v[26:27], v[10:11], v[10:11], v[26:27] op_sel_hi:[1,0,1]
	v_pk_mul_f32 v[208:209], v[172:173], s[26:27]
	v_pk_mul_f32 v[46:47], v[14:15], v[26:27] op_sel:[0,1] op_sel_hi:[1,0]
	v_pk_fma_f32 v[172:173], v[172:173], s[38:39], v[208:209] op_sel:[0,0,1] op_sel_hi:[1,0,0] neg_lo:[1,0,0] neg_hi:[1,0,0]
	s_waitcnt lgkmcnt(5)
	v_pk_add_f32 v[208:209], v[174:175], v[210:211]
	v_pk_add_f32 v[174:175], v[174:175], v[210:211] neg_lo:[0,1] neg_hi:[0,1]
	v_pk_fma_f32 v[46:47], v[10:11], v[26:27], v[46:47] op_sel_hi:[0,1,1]
	v_pk_mul_f32 v[210:211], v[174:175], s[76:77]
	v_pk_mul_f32 v[62:63], v[14:15], v[46:47] op_sel:[0,1] op_sel_hi:[1,0]
	v_pk_fma_f32 v[174:175], v[174:175], s[72:73], v[210:211] op_sel:[0,0,1] op_sel_hi:[1,0,0] neg_lo:[1,0,0] neg_hi:[1,0,0]
	s_waitcnt lgkmcnt(4)
	v_pk_add_f32 v[210:211], v[176:177], v[212:213]
	v_pk_add_f32 v[176:177], v[176:177], v[212:213] neg_lo:[0,1] neg_hi:[0,1]
	v_pk_fma_f32 v[62:63], v[10:11], v[46:47], v[62:63] op_sel_hi:[0,1,1]
	v_pk_mul_f32 v[212:213], v[176:177], s[70:71]
	v_pk_mul_f32 v[78:79], v[14:15], v[62:63] op_sel:[0,1] op_sel_hi:[1,0]
	v_pk_fma_f32 v[176:177], v[176:177], s[46:47], v[212:213] op_sel:[0,0,1] op_sel_hi:[1,0,0] neg_lo:[1,0,0] neg_hi:[1,0,0]
	s_waitcnt lgkmcnt(3)
	v_pk_add_f32 v[212:213], v[178:179], v[214:215]
	v_pk_add_f32 v[178:179], v[178:179], v[214:215] neg_lo:[0,1] neg_hi:[0,1]
	v_pk_fma_f32 v[78:79], v[10:11], v[62:63], v[78:79] op_sel_hi:[0,1,1]
	v_pk_mul_f32 v[214:215], v[178:179], s[68:69]
	v_pk_mul_f32 v[94:95], v[14:15], v[78:79] op_sel:[0,1] op_sel_hi:[1,0]
	v_pk_fma_f32 v[178:179], v[178:179], s[64:65], v[214:215] op_sel:[0,0,1] op_sel_hi:[1,0,0] neg_lo:[1,0,0] neg_hi:[1,0,0]
	s_waitcnt lgkmcnt(2)
	v_pk_add_f32 v[214:215], v[180:181], v[216:217]
	v_pk_add_f32 v[180:181], v[180:181], v[216:217] neg_lo:[0,1] neg_hi:[0,1]
	v_pk_fma_f32 v[94:95], v[10:11], v[78:79], v[94:95] op_sel_hi:[0,1,1]
	v_pk_mul_f32 v[216:217], v[180:181], s[62:63]
	v_pk_mul_f32 v[110:111], v[14:15], v[94:95] op_sel:[0,1] op_sel_hi:[1,0]
	v_pk_fma_f32 v[180:181], v[180:181], s[50:51], v[216:217] op_sel:[0,0,1] op_sel_hi:[1,0,0] neg_lo:[1,0,0] neg_hi:[1,0,0]
	s_waitcnt lgkmcnt(1)
	v_pk_add_f32 v[216:217], v[182:183], v[218:219]
	v_pk_add_f32 v[182:183], v[182:183], v[218:219] neg_lo:[0,1] neg_hi:[0,1]
	v_pk_mul_f32 v[8:9], v[2:3], v[6:7] op_sel:[0,1] op_sel_hi:[1,0]
	v_pk_mul_f32 v[218:219], v[182:183], s[44:45]
	v_pk_fma_f32 v[110:111], v[10:11], v[94:95], v[110:111] op_sel_hi:[0,1,1]
	v_pk_fma_f32 v[182:183], v[182:183], s[42:43], v[218:219] op_sel:[0,0,1] op_sel_hi:[1,0,0] neg_lo:[1,0,0] neg_hi:[1,0,0]
	s_waitcnt lgkmcnt(0)
	v_pk_add_f32 v[218:219], v[184:185], v[220:221]
	v_pk_add_f32 v[184:185], v[184:185], v[220:221] neg_lo:[0,1] neg_hi:[0,1]
	v_pk_fma_f32 v[8:9], v[4:5], v[6:7], v[8:9] op_sel_hi:[0,1,1]
	v_pk_mul_f32 v[220:221], v[184:185], s[40:41]
	v_pk_mul_f32 v[16:17], v[2:3], v[10:11] op_sel:[0,1] op_sel_hi:[1,0]
	v_pk_fma_f32 v[184:185], v[184:185], s[36:37], v[220:221] op_sel:[0,0,1] op_sel_hi:[1,0,0] neg_lo:[1,0,0] neg_hi:[1,0,0]
	v_pk_add_f32 v[220:221], v[222:223], v[204:205]
	v_pk_add_f32 v[204:205], v[222:223], v[204:205] neg_lo:[0,1] neg_hi:[0,1]
	v_pk_add_f32 v[222:223], v[186:187], v[170:171]
	v_pk_add_f32 v[170:171], v[186:187], v[170:171] neg_lo:[0,1] neg_hi:[0,1]
	v_pk_mul_f32 v[30:31], v[2:3], v[26:27] op_sel:[0,1] op_sel_hi:[1,0]
	v_pk_mul_f32 v[186:187], v[170:171], s[44:45]
	v_pk_mul_f32 v[50:51], v[2:3], v[46:47] op_sel:[0,1] op_sel_hi:[1,0]
	v_pk_fma_f32 v[170:171], v[170:171], s[42:43], v[186:187] op_sel:[0,0,1] op_sel_hi:[1,0,0]
	v_pk_add_f32 v[186:187], v[188:189], v[208:209]
	v_pk_add_f32 v[188:189], v[188:189], v[208:209] neg_lo:[0,1] neg_hi:[0,1]
	v_pk_mul_f32 v[66:67], v[2:3], v[62:63] op_sel:[0,1] op_sel_hi:[1,0]
	v_pk_mul_f32 v[208:209], v[188:189], s[68:69]
	v_pk_mul_f32 v[82:83], v[2:3], v[78:79] op_sel:[0,1] op_sel_hi:[1,0]
	v_pk_fma_f32 v[188:189], v[188:189], s[64:65], v[208:209] op_sel:[0,0,1] op_sel_hi:[1,0,0]
	v_pk_add_f32 v[208:209], v[190:191], v[210:211]
	v_pk_add_f32 v[190:191], v[190:191], v[210:211] neg_lo:[0,1] neg_hi:[0,1]
	v_pk_mul_f32 v[98:99], v[2:3], v[94:95] op_sel:[0,1] op_sel_hi:[1,0]
	v_pk_mul_f32 v[210:211], v[190:191], s[76:77]
	v_pk_mul_f32 v[114:115], v[2:3], v[110:111] op_sel:[0,1] op_sel_hi:[1,0]
	v_pk_fma_f32 v[190:191], v[190:191], s[72:73], v[210:211] op_sel:[0,0,1] op_sel_hi:[1,0,0]
	v_pk_add_f32 v[210:211], v[192:193], v[212:213]
	v_pk_add_f32 v[212:213], v[192:193], v[212:213] neg_lo:[0,1] neg_hi:[0,1]
	v_xor_b32_e32 v20, 0x80000000, v9
	v_pk_add_f32 v[192:193], v[194:195], v[214:215]
	v_pk_add_f32 v[194:195], v[194:195], v[214:215] neg_lo:[0,1] neg_hi:[0,1]
	v_mov_b32_e32 v21, v9
	v_pk_mul_f32 v[214:215], v[194:195], s[76:77]
	v_pk_fma_f32 v[16:17], v[4:5], v[10:11], v[16:17] op_sel_hi:[0,1,1]
	v_pk_fma_f32 v[194:195], v[194:195], s[72:73], v[214:215] op_sel:[0,0,1] op_sel_hi:[1,0,0] neg_lo:[1,0,0] neg_hi:[1,0,0]
	v_pk_add_f32 v[214:215], v[196:197], v[216:217]
	v_pk_add_f32 v[196:197], v[196:197], v[216:217] neg_lo:[0,1] neg_hi:[0,1]
	v_pk_mul_f32 v[18:19], v[12:13], v[10:11] op_sel:[0,1] op_sel_hi:[1,0]
	v_pk_mul_f32 v[216:217], v[196:197], s[68:69]
	v_pk_fma_f32 v[30:31], v[4:5], v[26:27], v[30:31] op_sel_hi:[0,1,1]
	v_pk_fma_f32 v[196:197], v[196:197], s[64:65], v[216:217] op_sel:[0,0,1] op_sel_hi:[1,0,0] neg_lo:[1,0,0] neg_hi:[1,0,0]
	v_pk_add_f32 v[216:217], v[198:199], v[218:219]
	v_pk_add_f32 v[198:199], v[198:199], v[218:219] neg_lo:[0,1] neg_hi:[0,1]
	v_pk_mul_f32 v[38:39], v[12:13], v[26:27] op_sel:[0,1] op_sel_hi:[1,0]
	v_pk_mul_f32 v[218:219], v[198:199], s[44:45]
	v_pk_fma_f32 v[50:51], v[4:5], v[46:47], v[50:51] op_sel_hi:[0,1,1]
	v_pk_fma_f32 v[198:199], v[198:199], s[42:43], v[218:219] op_sel:[0,0,1] op_sel_hi:[1,0,0] neg_lo:[1,0,0] neg_hi:[1,0,0]
	v_pk_add_f32 v[218:219], v[154:155], v[206:207] op_sel:[0,1] op_sel_hi:[1,0] neg_hi:[0,1]
	v_pk_add_f32 v[154:155], v[154:155], v[206:207] op_sel:[0,1] op_sel_hi:[1,0] neg_lo:[0,1]
	v_pk_add_f32 v[206:207], v[156:157], v[172:173]
	v_pk_add_f32 v[156:157], v[156:157], v[172:173] neg_lo:[0,1] neg_hi:[0,1]
	v_pk_mul_f32 v[54:55], v[12:13], v[46:47] op_sel:[0,1] op_sel_hi:[1,0]
	v_pk_mul_f32 v[172:173], v[156:157], s[44:45]
	v_pk_fma_f32 v[66:67], v[4:5], v[62:63], v[66:67] op_sel_hi:[0,1,1]
	v_pk_fma_f32 v[156:157], v[156:157], s[42:43], v[172:173] op_sel:[0,0,1] op_sel_hi:[1,0,0]
	v_pk_add_f32 v[172:173], v[158:159], v[174:175]
	v_pk_add_f32 v[158:159], v[158:159], v[174:175] neg_lo:[0,1] neg_hi:[0,1]
	v_pk_mul_f32 v[70:71], v[12:13], v[62:63] op_sel:[0,1] op_sel_hi:[1,0]
	v_pk_mul_f32 v[174:175], v[158:159], s[68:69]
	v_pk_fma_f32 v[82:83], v[4:5], v[78:79], v[82:83] op_sel_hi:[0,1,1]
	v_pk_fma_f32 v[158:159], v[158:159], s[64:65], v[174:175] op_sel:[0,0,1] op_sel_hi:[1,0,0]
	v_pk_add_f32 v[174:175], v[160:161], v[176:177]
	v_pk_add_f32 v[160:161], v[160:161], v[176:177] neg_lo:[0,1] neg_hi:[0,1]
	v_pk_mul_f32 v[86:87], v[12:13], v[78:79] op_sel:[0,1] op_sel_hi:[1,0]
	v_pk_mul_f32 v[176:177], v[160:161], s[76:77]
	v_pk_fma_f32 v[98:99], v[4:5], v[94:95], v[98:99] op_sel_hi:[0,1,1]
	v_pk_fma_f32 v[160:161], v[160:161], s[72:73], v[176:177] op_sel:[0,0,1] op_sel_hi:[1,0,0]
	v_pk_add_f32 v[176:177], v[162:163], v[178:179]
	v_pk_add_f32 v[178:179], v[162:163], v[178:179] neg_lo:[0,1] neg_hi:[0,1]
	v_pk_mul_f32 v[102:103], v[12:13], v[94:95] op_sel:[0,1] op_sel_hi:[1,0]
	v_pk_add_f32 v[162:163], v[164:165], v[180:181]
	v_pk_add_f32 v[164:165], v[164:165], v[180:181] neg_lo:[0,1] neg_hi:[0,1]
	v_pk_fma_f32 v[114:115], v[4:5], v[110:111], v[114:115] op_sel_hi:[0,1,1]
	v_pk_mul_f32 v[180:181], v[164:165], s[76:77]
	v_pk_mul_f32 v[118:119], v[12:13], v[110:111] op_sel:[0,1] op_sel_hi:[1,0]
	v_pk_fma_f32 v[164:165], v[164:165], s[72:73], v[180:181] op_sel:[0,0,1] op_sel_hi:[1,0,0] neg_lo:[1,0,0] neg_hi:[1,0,0]
	v_pk_add_f32 v[180:181], v[166:167], v[182:183]
	v_pk_add_f32 v[166:167], v[166:167], v[182:183] neg_lo:[0,1] neg_hi:[0,1]
	v_pk_fma_f32 v[18:19], v[6:7], v[10:11], v[18:19] op_sel_hi:[0,1,1]
	v_pk_mul_f32 v[182:183], v[166:167], s[68:69]
	v_pk_mul_f32 v[22:23], v[10:11], v[20:21] op_sel:[1,0] op_sel_hi:[0,1]
	v_pk_fma_f32 v[166:167], v[166:167], s[64:65], v[182:183] op_sel:[0,0,1] op_sel_hi:[1,0,0] neg_lo:[1,0,0] neg_hi:[1,0,0]
	v_pk_add_f32 v[182:183], v[168:169], v[184:185]
	v_pk_add_f32 v[168:169], v[168:169], v[184:185] neg_lo:[0,1] neg_hi:[0,1]
	v_pk_fma_f32 v[38:39], v[6:7], v[26:27], v[38:39] op_sel_hi:[0,1,1]
	v_pk_mul_f32 v[184:185], v[168:169], s[44:45]
	v_pk_mul_f32 v[42:43], v[20:21], v[26:27] op_sel:[0,1] op_sel_hi:[1,0]
	v_pk_fma_f32 v[168:169], v[168:169], s[42:43], v[184:185] op_sel:[0,0,1] op_sel_hi:[1,0,0] neg_lo:[1,0,0] neg_hi:[1,0,0]
	v_pk_add_f32 v[184:185], v[220:221], v[210:211]
	v_pk_add_f32 v[210:211], v[220:221], v[210:211] neg_lo:[0,1] neg_hi:[0,1]
	v_pk_add_f32 v[220:221], v[222:223], v[192:193]
	v_pk_add_f32 v[192:193], v[222:223], v[192:193] neg_lo:[0,1] neg_hi:[0,1]
	v_pk_fma_f32 v[54:55], v[6:7], v[46:47], v[54:55] op_sel_hi:[0,1,1]
	v_pk_mul_f32 v[222:223], v[192:193], s[68:69]
	v_pk_mul_f32 v[58:59], v[20:21], v[46:47] op_sel:[0,1] op_sel_hi:[1,0]
	v_pk_fma_f32 v[192:193], v[192:193], s[64:65], v[222:223] op_sel:[0,0,1] op_sel_hi:[1,0,0]
	v_pk_add_f32 v[222:223], v[186:187], v[214:215]
	v_pk_add_f32 v[214:215], v[186:187], v[214:215] neg_lo:[0,1] neg_hi:[0,1]
	v_pk_fma_f32 v[70:71], v[6:7], v[62:63], v[70:71] op_sel_hi:[0,1,1]
	v_pk_add_f32 v[186:187], v[208:209], v[216:217]
	v_pk_add_f32 v[208:209], v[208:209], v[216:217] neg_lo:[0,1] neg_hi:[0,1]
	v_pk_mul_f32 v[74:75], v[20:21], v[62:63] op_sel:[0,1] op_sel_hi:[1,0]
	v_pk_mul_f32 v[216:217], v[208:209], s[68:69]
	v_pk_fma_f32 v[86:87], v[6:7], v[78:79], v[86:87] op_sel_hi:[0,1,1]
	v_pk_fma_f32 v[208:209], v[208:209], s[64:65], v[216:217] op_sel:[0,0,1] op_sel_hi:[1,0,0] neg_lo:[1,0,0] neg_hi:[1,0,0]
	v_pk_add_f32 v[216:217], v[204:205], v[212:213] op_sel:[0,1] op_sel_hi:[1,0] neg_hi:[0,1]
	v_pk_add_f32 v[204:205], v[204:205], v[212:213] op_sel:[0,1] op_sel_hi:[1,0] neg_lo:[0,1]
	v_pk_add_f32 v[212:213], v[170:171], v[194:195]
	v_pk_add_f32 v[170:171], v[170:171], v[194:195] neg_lo:[0,1] neg_hi:[0,1]
	v_pk_mul_f32 v[90:91], v[20:21], v[78:79] op_sel:[0,1] op_sel_hi:[1,0]
	v_pk_mul_f32 v[194:195], v[170:171], s[68:69]
	v_pk_fma_f32 v[102:103], v[6:7], v[94:95], v[102:103] op_sel_hi:[0,1,1]
	v_pk_fma_f32 v[170:171], v[170:171], s[64:65], v[194:195] op_sel:[0,0,1] op_sel_hi:[1,0,0]
	v_pk_add_f32 v[194:195], v[188:189], v[196:197]
	v_pk_add_f32 v[196:197], v[188:189], v[196:197] neg_lo:[0,1] neg_hi:[0,1]
	v_pk_mul_f32 v[106:107], v[20:21], v[94:95] op_sel:[0,1] op_sel_hi:[1,0]
	v_pk_add_f32 v[188:189], v[190:191], v[198:199]
	v_pk_add_f32 v[190:191], v[190:191], v[198:199] neg_lo:[0,1] neg_hi:[0,1]
	v_pk_fma_f32 v[118:119], v[6:7], v[110:111], v[118:119] op_sel_hi:[0,1,1]
	v_pk_mul_f32 v[198:199], v[190:191], s[68:69]
	v_pk_mul_f32 v[122:123], v[20:21], v[110:111] op_sel:[0,1] op_sel_hi:[1,0]
	v_pk_fma_f32 v[190:191], v[190:191], s[64:65], v[198:199] op_sel:[0,0,1] op_sel_hi:[1,0,0] neg_lo:[1,0,0] neg_hi:[1,0,0]
	v_pk_add_f32 v[198:199], v[218:219], v[176:177]
	v_pk_add_f32 v[176:177], v[218:219], v[176:177] neg_lo:[0,1] neg_hi:[0,1]
	v_pk_add_f32 v[218:219], v[206:207], v[162:163]
	v_pk_add_f32 v[162:163], v[206:207], v[162:163] neg_lo:[0,1] neg_hi:[0,1]
	v_xor_b32_e32 v24, 0x80000000, v17
	v_pk_mul_f32 v[206:207], v[162:163], s[68:69]
	v_xor_b32_e32 v28, 0x80000000, v19
	v_pk_fma_f32 v[162:163], v[162:163], s[64:65], v[206:207] op_sel:[0,0,1] op_sel_hi:[1,0,0]
	v_pk_add_f32 v[206:207], v[172:173], v[180:181]
	v_pk_add_f32 v[180:181], v[172:173], v[180:181] neg_lo:[0,1] neg_hi:[0,1]
	v_pk_fma_f32 v[22:23], v[10:11], v[8:9], v[22:23] op_sel_hi:[1,0,1]
	v_pk_add_f32 v[172:173], v[174:175], v[182:183]
	v_pk_add_f32 v[174:175], v[174:175], v[182:183] neg_lo:[0,1] neg_hi:[0,1]
	v_pk_fma_f32 v[42:43], v[8:9], v[26:27], v[42:43] op_sel_hi:[0,1,1]
	v_pk_mul_f32 v[182:183], v[174:175], s[68:69]
	v_pk_fma_f32 v[58:59], v[8:9], v[46:47], v[58:59] op_sel_hi:[0,1,1]
	v_pk_fma_f32 v[174:175], v[174:175], s[64:65], v[182:183] op_sel:[0,0,1] op_sel_hi:[1,0,0] neg_lo:[1,0,0] neg_hi:[1,0,0]
	v_pk_add_f32 v[182:183], v[154:155], v[178:179] op_sel:[0,1] op_sel_hi:[1,0] neg_hi:[0,1]
	v_pk_add_f32 v[154:155], v[154:155], v[178:179] op_sel:[0,1] op_sel_hi:[1,0] neg_lo:[0,1]
	v_pk_add_f32 v[178:179], v[156:157], v[164:165]
	v_pk_add_f32 v[156:157], v[156:157], v[164:165] neg_lo:[0,1] neg_hi:[0,1]
	v_pk_fma_f32 v[74:75], v[8:9], v[62:63], v[74:75] op_sel_hi:[0,1,1]
	v_pk_mul_f32 v[164:165], v[156:157], s[68:69]
	v_pk_fma_f32 v[90:91], v[8:9], v[78:79], v[90:91] op_sel_hi:[0,1,1]
	v_pk_fma_f32 v[156:157], v[156:157], s[64:65], v[164:165] op_sel:[0,0,1] op_sel_hi:[1,0,0]
	v_pk_add_f32 v[164:165], v[158:159], v[166:167]
	v_pk_add_f32 v[166:167], v[158:159], v[166:167] neg_lo:[0,1] neg_hi:[0,1]
	v_pk_fma_f32 v[106:107], v[8:9], v[94:95], v[106:107] op_sel_hi:[0,1,1]
	v_pk_add_f32 v[158:159], v[160:161], v[168:169]
	v_pk_add_f32 v[160:161], v[160:161], v[168:169] neg_lo:[0,1] neg_hi:[0,1]
	v_pk_fma_f32 v[122:123], v[8:9], v[110:111], v[122:123] op_sel_hi:[0,1,1]
	v_pk_mul_f32 v[168:169], v[160:161], s[68:69]
	v_mov_b32_e32 v25, v17
	v_pk_fma_f32 v[160:161], v[160:161], s[64:65], v[168:169] op_sel:[0,0,1] op_sel_hi:[1,0,0] neg_lo:[1,0,0] neg_hi:[1,0,0]
	v_pk_add_f32 v[168:169], v[184:185], v[222:223]
	v_pk_add_f32 v[184:185], v[184:185], v[222:223] neg_lo:[0,1] neg_hi:[0,1]
	v_pk_add_f32 v[222:223], v[220:221], v[186:187]
	v_pk_add_f32 v[220:221], v[220:221], v[186:187] neg_lo:[0,1] neg_hi:[0,1]
	v_mov_b32_e32 v29, v19
	v_pk_add_f32 v[186:187], v[210:211], v[214:215] op_sel:[0,1] op_sel_hi:[1,0] neg_hi:[0,1]
	v_pk_add_f32 v[210:211], v[210:211], v[214:215] op_sel:[0,1] op_sel_hi:[1,0] neg_lo:[0,1]
	v_pk_add_f32 v[214:215], v[192:193], v[208:209]
	v_pk_add_f32 v[208:209], v[192:193], v[208:209] neg_lo:[0,1] neg_hi:[0,1]
	v_xor_b32_e32 v32, 0x80000000, v23
	v_pk_add_f32 v[192:193], v[216:217], v[194:195]
	v_pk_add_f32 v[194:195], v[216:217], v[194:195] neg_lo:[0,1] neg_hi:[0,1]
	v_pk_add_f32 v[216:217], v[212:213], v[188:189]
	v_pk_add_f32 v[212:213], v[212:213], v[188:189] neg_lo:[0,1] neg_hi:[0,1]
	v_xor_b32_e32 v40, 0x80000000, v27
	v_pk_add_f32 v[188:189], v[204:205], v[196:197] op_sel:[0,1] op_sel_hi:[1,0] neg_hi:[0,1]
	v_pk_add_f32 v[196:197], v[204:205], v[196:197] op_sel:[0,1] op_sel_hi:[1,0] neg_lo:[0,1]
	v_pk_add_f32 v[204:205], v[170:171], v[190:191]
	v_pk_add_f32 v[190:191], v[170:171], v[190:191] neg_lo:[0,1] neg_hi:[0,1]
	v_xor_b32_e32 v44, 0x80000000, v31
	v_pk_add_f32 v[170:171], v[198:199], v[206:207]
	v_pk_add_f32 v[198:199], v[198:199], v[206:207] neg_lo:[0,1] neg_hi:[0,1]
	v_pk_add_f32 v[206:207], v[218:219], v[172:173]
	v_pk_add_f32 v[218:219], v[218:219], v[172:173] neg_lo:[0,1] neg_hi:[0,1]
	v_xor_b32_e32 v48, 0x80000000, v39
	v_pk_add_f32 v[172:173], v[176:177], v[180:181] op_sel:[0,1] op_sel_hi:[1,0] neg_hi:[0,1]
	v_pk_add_f32 v[176:177], v[176:177], v[180:181] op_sel:[0,1] op_sel_hi:[1,0] neg_lo:[0,1]
	v_pk_add_f32 v[180:181], v[162:163], v[174:175]
	v_pk_add_f32 v[174:175], v[162:163], v[174:175] neg_lo:[0,1] neg_hi:[0,1]
	v_mov_b32_e32 v33, v23
	v_pk_add_f32 v[162:163], v[182:183], v[164:165]
	v_pk_add_f32 v[164:165], v[182:183], v[164:165] neg_lo:[0,1] neg_hi:[0,1]
	v_pk_add_f32 v[182:183], v[178:179], v[158:159]
	v_pk_add_f32 v[178:179], v[178:179], v[158:159] neg_lo:[0,1] neg_hi:[0,1]
	v_mov_b32_e32 v41, v27
	v_pk_add_f32 v[158:159], v[154:155], v[166:167] op_sel:[0,1] op_sel_hi:[1,0] neg_hi:[0,1]
	v_pk_add_f32 v[154:155], v[154:155], v[166:167] op_sel:[0,1] op_sel_hi:[1,0] neg_lo:[0,1]
	v_pk_add_f32 v[166:167], v[156:157], v[160:161]
	v_pk_add_f32 v[156:157], v[156:157], v[160:161] neg_lo:[0,1] neg_hi:[0,1]
	v_mov_b32_e32 v45, v31
	v_xor_b32_e32 v161, 0x80000000, v156
	v_mov_b32_e32 v160, v157
	v_pk_add_f32 v[156:157], v[168:169], v[222:223]
	v_pk_add_f32 v[168:169], v[168:169], v[222:223] neg_lo:[0,1] neg_hi:[0,1]
	v_pk_add_f32 v[222:223], v[184:185], v[220:221] op_sel:[0,1] op_sel_hi:[1,0] neg_hi:[0,1]
	v_pk_add_f32 v[184:185], v[184:185], v[220:221] op_sel:[0,1] op_sel_hi:[1,0] neg_lo:[0,1]
	v_pk_add_f32 v[220:221], v[186:187], v[214:215]
	v_pk_add_f32 v[186:187], v[186:187], v[214:215] neg_lo:[0,1] neg_hi:[0,1]
	v_pk_add_f32 v[214:215], v[210:211], v[208:209] op_sel:[0,1] op_sel_hi:[1,0] neg_hi:[0,1]
	v_pk_add_f32 v[208:209], v[210:211], v[208:209] op_sel:[0,1] op_sel_hi:[1,0] neg_lo:[0,1]
	v_pk_add_f32 v[210:211], v[192:193], v[216:217]
	v_pk_add_f32 v[192:193], v[192:193], v[216:217] neg_lo:[0,1] neg_hi:[0,1]
	v_pk_add_f32 v[216:217], v[194:195], v[212:213] op_sel:[0,1] op_sel_hi:[1,0] neg_hi:[0,1]
	v_pk_add_f32 v[194:195], v[194:195], v[212:213] op_sel:[0,1] op_sel_hi:[1,0] neg_lo:[0,1]
	v_pk_add_f32 v[212:213], v[188:189], v[204:205]
	v_pk_add_f32 v[188:189], v[188:189], v[204:205] neg_lo:[0,1] neg_hi:[0,1]
	v_pk_add_f32 v[204:205], v[196:197], v[190:191] op_sel:[0,1] op_sel_hi:[1,0] neg_hi:[0,1]
	v_pk_add_f32 v[190:191], v[196:197], v[190:191] op_sel:[0,1] op_sel_hi:[1,0] neg_lo:[0,1]
	v_pk_add_f32 v[196:197], v[170:171], v[206:207]
	v_pk_add_f32 v[170:171], v[170:171], v[206:207] neg_lo:[0,1] neg_hi:[0,1]
	v_pk_mul_f32 v[2:3], v[2:3], v[196:197] op_sel:[0,1] op_sel_hi:[1,0]
	v_pk_add_f32 v[206:207], v[198:199], v[218:219] op_sel:[0,1] op_sel_hi:[1,0] neg_hi:[0,1]
	v_pk_add_f32 v[198:199], v[198:199], v[218:219] op_sel:[0,1] op_sel_hi:[1,0] neg_lo:[0,1]
	v_pk_add_f32 v[218:219], v[172:173], v[180:181]
	v_pk_add_f32 v[172:173], v[172:173], v[180:181] neg_lo:[0,1] neg_hi:[0,1]
	v_pk_add_f32 v[180:181], v[176:177], v[174:175] op_sel:[0,1] op_sel_hi:[1,0] neg_hi:[0,1]
	v_pk_add_f32 v[174:175], v[176:177], v[174:175] op_sel:[0,1] op_sel_hi:[1,0] neg_lo:[0,1]
	v_pk_add_f32 v[176:177], v[162:163], v[182:183]
	v_pk_fma_f32 v[2:3], v[4:5], v[196:197], v[2:3] op_sel_hi:[0,1,1]
	v_pk_mul_f32 v[4:5], v[12:13], v[210:211] op_sel:[0,1] op_sel_hi:[1,0]
	v_mov_b32_e32 v49, v39
	v_pk_fma_f32 v[4:5], v[6:7], v[210:211], v[4:5] op_sel_hi:[0,1,1]
	v_pk_mul_f32 v[6:7], v[20:21], v[176:177] op_sel:[0,1] op_sel_hi:[1,0]
	v_pk_add_f32 v[162:163], v[162:163], v[182:183] neg_lo:[0,1] neg_hi:[0,1]
	v_pk_fma_f32 v[6:7], v[8:9], v[176:177], v[6:7] op_sel_hi:[0,1,1]
	v_pk_mul_f32 v[8:9], v[14:15], v[220:221] op_sel:[0,1] op_sel_hi:[1,0]
	v_pk_add_f32 v[182:183], v[164:165], v[178:179] op_sel:[0,1] op_sel_hi:[1,0] neg_hi:[0,1]
	v_pk_add_f32 v[164:165], v[164:165], v[178:179] op_sel:[0,1] op_sel_hi:[1,0] neg_lo:[0,1]
	v_pk_add_f32 v[178:179], v[158:159], v[166:167]
	v_pk_fma_f32 v[8:9], v[10:11], v[220:221], v[8:9] op_sel_hi:[0,1,1]
	v_pk_mul_f32 v[10:11], v[24:25], v[218:219] op_sel:[0,1] op_sel_hi:[1,0]
	v_pk_mul_f32 v[12:13], v[28:29], v[212:213] op_sel:[0,1] op_sel_hi:[1,0]
	v_xor_b32_e32 v52, 0x80000000, v43
	v_xor_b32_e32 v56, 0x80000000, v47
	v_xor_b32_e32 v60, 0x80000000, v51
	v_xor_b32_e32 v64, 0x80000000, v55
	v_xor_b32_e32 v68, 0x80000000, v59
	v_xor_b32_e32 v72, 0x80000000, v63
	v_xor_b32_e32 v76, 0x80000000, v67
	v_mov_b32_e32 v53, v43
	v_mov_b32_e32 v57, v47
	v_mov_b32_e32 v61, v51
	v_mov_b32_e32 v65, v55
	v_mov_b32_e32 v69, v59
	v_mov_b32_e32 v73, v63
	v_mov_b32_e32 v77, v67
	v_pk_add_f32 v[158:159], v[158:159], v[166:167] neg_lo:[0,1] neg_hi:[0,1]
	v_pk_add_f32 v[166:167], v[154:155], v[160:161]
	v_pk_fma_f32 v[10:11], v[16:17], v[218:219], v[10:11] op_sel_hi:[0,1,1]
	v_pk_fma_f32 v[12:13], v[18:19], v[212:213], v[12:13] op_sel_hi:[0,1,1]
	v_pk_mul_f32 v[14:15], v[32:33], v[178:179] op_sel:[0,1] op_sel_hi:[1,0]
	v_pk_mul_f32 v[16:17], v[40:41], v[222:223] op_sel:[0,1] op_sel_hi:[1,0]
	v_pk_mul_f32 v[18:19], v[44:45], v[206:207] op_sel:[0,1] op_sel_hi:[1,0]
	v_pk_mul_f32 v[20:21], v[48:49], v[216:217] op_sel:[0,1] op_sel_hi:[1,0]
	v_xor_b32_e32 v80, 0x80000000, v71
	v_xor_b32_e32 v84, 0x80000000, v75
	v_xor_b32_e32 v88, 0x80000000, v79
	v_xor_b32_e32 v92, 0x80000000, v83
	v_xor_b32_e32 v96, 0x80000000, v87
	v_xor_b32_e32 v100, 0x80000000, v91
	v_xor_b32_e32 v104, 0x80000000, v95
	v_xor_b32_e32 v108, 0x80000000, v99
	v_xor_b32_e32 v112, 0x80000000, v103
	v_xor_b32_e32 v116, 0x80000000, v107
	v_xor_b32_e32 v120, 0x80000000, v111
	v_xor_b32_e32 v124, 0x80000000, v115
	v_xor_b32_e32 v126, 0x80000000, v119
	v_xor_b32_e32 v128, 0x80000000, v123
	v_mov_b32_e32 v81, v71
	v_mov_b32_e32 v85, v75
	v_mov_b32_e32 v89, v79
	v_mov_b32_e32 v93, v83
	v_mov_b32_e32 v97, v87
	v_mov_b32_e32 v101, v91
	v_mov_b32_e32 v105, v95
	v_mov_b32_e32 v109, v99
	v_mov_b32_e32 v113, v103
	v_mov_b32_e32 v117, v107
	v_mov_b32_e32 v121, v111
	v_mov_b32_e32 v125, v115
	v_mov_b32_e32 v127, v119
	v_mov_b32_e32 v129, v123
	v_pk_add_f32 v[154:155], v[154:155], v[160:161] neg_lo:[0,1] neg_hi:[0,1]
	v_pk_fma_f32 v[14:15], v[22:23], v[178:179], v[14:15] op_sel_hi:[0,1,1]
	v_pk_fma_f32 v[16:17], v[26:27], v[222:223], v[16:17] op_sel_hi:[0,1,1]
	v_pk_fma_f32 v[18:19], v[30:31], v[206:207], v[18:19] op_sel_hi:[0,1,1]
	v_pk_fma_f32 v[20:21], v[38:39], v[216:217], v[20:21] op_sel_hi:[0,1,1]
	v_pk_mul_f32 v[22:23], v[52:53], v[182:183] op_sel:[0,1] op_sel_hi:[1,0]
	v_pk_mul_f32 v[24:25], v[56:57], v[214:215] op_sel:[0,1] op_sel_hi:[1,0]
	v_pk_mul_f32 v[26:27], v[60:61], v[180:181] op_sel:[0,1] op_sel_hi:[1,0]
	v_pk_mul_f32 v[28:29], v[64:65], v[204:205] op_sel:[0,1] op_sel_hi:[1,0]
	v_pk_mul_f32 v[30:31], v[68:69], v[166:167] op_sel:[0,1] op_sel_hi:[1,0]
	v_pk_mul_f32 v[32:33], v[72:73], v[168:169] op_sel:[0,1] op_sel_hi:[1,0]
	v_pk_mul_f32 v[38:39], v[76:77], v[170:171] op_sel:[0,1] op_sel_hi:[1,0]
	v_pk_fma_f32 v[22:23], v[42:43], v[182:183], v[22:23] op_sel_hi:[0,1,1]
	v_pk_fma_f32 v[24:25], v[46:47], v[214:215], v[24:25] op_sel_hi:[0,1,1]
	v_pk_fma_f32 v[26:27], v[50:51], v[180:181], v[26:27] op_sel_hi:[0,1,1]
	v_pk_fma_f32 v[28:29], v[54:55], v[204:205], v[28:29] op_sel_hi:[0,1,1]
	v_pk_fma_f32 v[30:31], v[58:59], v[166:167], v[30:31] op_sel_hi:[0,1,1]
	v_pk_fma_f32 v[32:33], v[62:63], v[168:169], v[32:33] op_sel_hi:[0,1,1]
	v_pk_fma_f32 v[38:39], v[66:67], v[170:171], v[38:39] op_sel_hi:[0,1,1]
	v_pk_mul_f32 v[40:41], v[80:81], v[192:193] op_sel:[0,1] op_sel_hi:[1,0]
	v_pk_mul_f32 v[42:43], v[84:85], v[162:163] op_sel:[0,1] op_sel_hi:[1,0]
	v_pk_mul_f32 v[44:45], v[88:89], v[186:187] op_sel:[0,1] op_sel_hi:[1,0]
	v_pk_mul_f32 v[46:47], v[92:93], v[172:173] op_sel:[0,1] op_sel_hi:[1,0]
	v_pk_mul_f32 v[48:49], v[96:97], v[188:189] op_sel:[0,1] op_sel_hi:[1,0]
	v_pk_mul_f32 v[50:51], v[100:101], v[158:159] op_sel:[0,1] op_sel_hi:[1,0]
	v_pk_mul_f32 v[52:53], v[104:105], v[184:185] op_sel:[0,1] op_sel_hi:[1,0]
	v_pk_mul_f32 v[54:55], v[108:109], v[198:199] op_sel:[0,1] op_sel_hi:[1,0]
	v_pk_mul_f32 v[56:57], v[112:113], v[194:195] op_sel:[0,1] op_sel_hi:[1,0]
	v_pk_mul_f32 v[58:59], v[116:117], v[164:165] op_sel:[0,1] op_sel_hi:[1,0]
	v_pk_mul_f32 v[60:61], v[120:121], v[208:209] op_sel:[0,1] op_sel_hi:[1,0]
	v_pk_mul_f32 v[62:63], v[124:125], v[174:175] op_sel:[0,1] op_sel_hi:[1,0]
	v_pk_mul_f32 v[64:65], v[126:127], v[190:191] op_sel:[0,1] op_sel_hi:[1,0]
	v_pk_mul_f32 v[66:67], v[128:129], v[154:155] op_sel:[0,1] op_sel_hi:[1,0]
	v_pk_fma_f32 v[40:41], v[70:71], v[192:193], v[40:41] op_sel_hi:[0,1,1]
	v_pk_fma_f32 v[42:43], v[74:75], v[162:163], v[42:43] op_sel_hi:[0,1,1]
	v_pk_fma_f32 v[44:45], v[78:79], v[186:187], v[44:45] op_sel_hi:[0,1,1]
	v_pk_fma_f32 v[46:47], v[82:83], v[172:173], v[46:47] op_sel_hi:[0,1,1]
	v_pk_fma_f32 v[48:49], v[86:87], v[188:189], v[48:49] op_sel_hi:[0,1,1]
	v_pk_fma_f32 v[50:51], v[90:91], v[158:159], v[50:51] op_sel_hi:[0,1,1]
	v_pk_fma_f32 v[52:53], v[94:95], v[184:185], v[52:53] op_sel_hi:[0,1,1]
	v_pk_fma_f32 v[54:55], v[98:99], v[198:199], v[54:55] op_sel_hi:[0,1,1]
	v_pk_fma_f32 v[56:57], v[102:103], v[194:195], v[56:57] op_sel_hi:[0,1,1]
	v_pk_fma_f32 v[58:59], v[106:107], v[164:165], v[58:59] op_sel_hi:[0,1,1]
	v_pk_fma_f32 v[60:61], v[110:111], v[208:209], v[60:61] op_sel_hi:[0,1,1]
	v_pk_fma_f32 v[62:63], v[114:115], v[174:175], v[62:63] op_sel_hi:[0,1,1]
	v_pk_fma_f32 v[64:65], v[118:119], v[190:191], v[64:65] op_sel_hi:[0,1,1]
	v_pk_fma_f32 v[66:67], v[122:123], v[154:155], v[66:67] op_sel_hi:[0,1,1]
	ds_write_b64 v36, v[156:157]
	ds_write_b64 v36, v[32:33] offset:2112
	ds_write_b64 v36, v[16:17] offset:4224
	ds_write_b64 v36, v[52:53] offset:6336
	ds_write_b64 v36, v[8:9] offset:8448
	ds_write_b64 v36, v[44:45] offset:10560
	ds_write_b64 v36, v[24:25] offset:12672
	ds_write_b64 v36, v[60:61] offset:14784
	ds_write_b64 v36, v[4:5] offset:16896
	ds_write_b64 v36, v[40:41] offset:19008
	ds_write_b64 v36, v[20:21] offset:21120
	ds_write_b64 v36, v[56:57] offset:23232
	ds_write_b64 v36, v[12:13] offset:25344
	ds_write_b64 v36, v[48:49] offset:27456
	ds_write_b64 v36, v[28:29] offset:29568
	ds_write_b64 v36, v[64:65] offset:31680
	ds_write_b64 v36, v[2:3] offset:33792
	ds_write_b64 v36, v[38:39] offset:35904
	ds_write_b64 v36, v[18:19] offset:38016
	ds_write_b64 v36, v[54:55] offset:40128
	ds_write_b64 v36, v[10:11] offset:42240
	ds_write_b64 v36, v[46:47] offset:44352
	ds_write_b64 v36, v[26:27] offset:46464
	ds_write_b64 v36, v[62:63] offset:48576
	ds_write_b64 v36, v[6:7] offset:50688
	ds_write_b64 v36, v[42:43] offset:52800
	ds_write_b64 v36, v[22:23] offset:54912
	ds_write_b64 v36, v[58:59] offset:57024
	ds_write_b64 v36, v[14:15] offset:59136
	ds_write_b64 v36, v[50:51] offset:61248
	ds_write_b64 v36, v[30:31] offset:63360
	ds_write_b64 v36, v[66:67] offset:65472
	v_mov_b32_e32 v3, v130
	s_waitcnt lgkmcnt(0)
	s_barrier
	s_nop 0
	v_and_b32_e32 v5, 15, v3
	v_cvt_f32_ubyte0_e32 v2, v5
	v_mul_f32_e32 v4, 0x3b800000, v2
	v_sin_f32_e32 v2, v4
	v_cos_f32_e32 v4, v4
	v_lshlrev_b32_e32 v66, 3, v5
	v_lshlrev_b32_e32 v36, 4, v3
	v_xor_b32_e32 v5, 0x80000000, v2
	v_mov_b32_e32 v3, v5
	v_pk_mul_f32 v[6:7], v[4:5], v[2:3] op_sel:[1,0] op_sel_hi:[0,1]
	v_pk_fma_f32 v[6:7], v[4:5], v[4:5], v[6:7] op_sel_hi:[1,0,1]
	s_nop 0
	v_xor_b32_e32 v12, 0x80000000, v7
	v_mov_b32_e32 v13, v7
	v_pk_mul_f32 v[10:11], v[6:7], v[12:13] op_sel:[1,0] op_sel_hi:[0,1]
	v_pk_fma_f32 v[10:11], v[6:7], v[6:7], v[10:11] op_sel_hi:[1,0,1]
	v_pk_mul_f32 v[8:9], v[2:3], v[6:7] op_sel:[0,1] op_sel_hi:[1,0]
	v_xor_b32_e32 v14, 0x80000000, v11
	v_mov_b32_e32 v15, v11
	v_pk_mul_f32 v[30:31], v[10:11], v[14:15] op_sel:[1,0] op_sel_hi:[0,1]
	v_pk_fma_f32 v[30:31], v[10:11], v[10:11], v[30:31] op_sel_hi:[1,0,1]
	v_pk_mul_f32 v[16:17], v[2:3], v[10:11] op_sel:[0,1] op_sel_hi:[1,0]
	v_pk_mul_f32 v[50:51], v[14:15], v[30:31] op_sel:[0,1] op_sel_hi:[1,0]
	v_pk_mul_f32 v[38:39], v[2:3], v[30:31] op_sel:[0,1] op_sel_hi:[1,0]
	v_pk_fma_f32 v[50:51], v[10:11], v[30:31], v[50:51] op_sel_hi:[0,1,1]
	v_pk_mul_f32 v[54:55], v[2:3], v[50:51] op_sel:[0,1] op_sel_hi:[1,0]
	v_pk_fma_f32 v[8:9], v[4:5], v[6:7], v[8:9] op_sel_hi:[0,1,1]
	v_pk_fma_f32 v[16:17], v[4:5], v[10:11], v[16:17] op_sel_hi:[0,1,1]
	v_pk_fma_f32 v[38:39], v[4:5], v[30:31], v[38:39] op_sel_hi:[0,1,1]
	v_pk_fma_f32 v[54:55], v[4:5], v[50:51], v[54:55] op_sel_hi:[0,1,1]
	v_and_b32_e32 v5, 0xffffff00, v36
	v_lshlrev_b32_e32 v36, 3, v5
	v_add3_u32 v36, 0, v66, v36
	v_ashrrev_i32_e32 v66, 2, v5
	v_add_u32_e32 v108, v36, v66
	ds_read2_b64 v[66:69], v108 offset1:16
	ds_read2_b64 v[70:73], v108 offset0:33 offset1:49
	ds_read2_b64 v[74:77], v108 offset0:66 offset1:82
	ds_read2_b64 v[78:81], v108 offset0:132 offset1:148
	ds_read2_b64 v[82:85], v108 offset0:99 offset1:115
	ds_read2_b64 v[86:89], v108 offset0:165 offset1:181
	ds_read2_b64 v[90:93], v108 offset0:198 offset1:214
	ds_read2_b64 v[94:97], v108 offset0:231 offset1:247
	s_waitcnt lgkmcnt(4)
	v_pk_add_f32 v[98:99], v[66:67], v[78:79]
	v_pk_add_f32 v[66:67], v[66:67], v[78:79] neg_lo:[0,1] neg_hi:[0,1]
	v_pk_add_f32 v[78:79], v[68:69], v[80:81]
	v_pk_add_f32 v[68:69], v[68:69], v[80:81] neg_lo:[0,1] neg_hi:[0,1]
	s_waitcnt lgkmcnt(1)
	v_pk_add_f32 v[100:101], v[76:77], v[92:93]
	v_pk_mul_f32 v[80:81], v[68:69], s[44:45]
	v_pk_add_f32 v[76:77], v[76:77], v[92:93] neg_lo:[0,1] neg_hi:[0,1]
	v_pk_fma_f32 v[68:69], v[68:69], s[42:43], v[80:81] op_sel:[0,0,1] op_sel_hi:[1,0,0]
	v_pk_add_f32 v[80:81], v[70:71], v[86:87]
	v_pk_add_f32 v[70:71], v[70:71], v[86:87] neg_lo:[0,1] neg_hi:[0,1]
	v_pk_mul_f32 v[92:93], v[76:77], s[76:77]
	v_pk_mul_f32 v[86:87], v[70:71], s[68:69]
	v_pk_fma_f32 v[76:77], v[76:77], s[72:73], v[92:93] op_sel:[0,0,1] op_sel_hi:[1,0,0] neg_lo:[1,0,0] neg_hi:[1,0,0]
	v_pk_fma_f32 v[70:71], v[70:71], s[64:65], v[86:87] op_sel:[0,0,1] op_sel_hi:[1,0,0]
	v_pk_add_f32 v[86:87], v[72:73], v[88:89]
	v_pk_add_f32 v[72:73], v[72:73], v[88:89] neg_lo:[0,1] neg_hi:[0,1]
	s_waitcnt lgkmcnt(0)
	v_pk_add_f32 v[92:93], v[82:83], v[94:95]
	v_pk_add_f32 v[82:83], v[82:83], v[94:95] neg_lo:[0,1] neg_hi:[0,1]
	v_pk_mul_f32 v[88:89], v[72:73], s[76:77]
	v_pk_mul_f32 v[94:95], v[82:83], s[68:69]
	v_pk_fma_f32 v[72:73], v[72:73], s[72:73], v[88:89] op_sel:[0,0,1] op_sel_hi:[1,0,0]
	v_pk_add_f32 v[88:89], v[74:75], v[90:91]
	v_pk_add_f32 v[90:91], v[74:75], v[90:91] neg_lo:[0,1] neg_hi:[0,1]
	v_pk_fma_f32 v[82:83], v[82:83], s[64:65], v[94:95] op_sel:[0,0,1] op_sel_hi:[1,0,0] neg_lo:[1,0,0] neg_hi:[1,0,0]
	v_pk_add_f32 v[94:95], v[84:85], v[96:97]
	v_pk_add_f32 v[84:85], v[84:85], v[96:97] neg_lo:[0,1] neg_hi:[0,1]
	s_nop 0
	v_pk_mul_f32 v[96:97], v[84:85], s[44:45]
	s_nop 0
	v_pk_fma_f32 v[84:85], v[84:85], s[42:43], v[96:97] op_sel:[0,0,1] op_sel_hi:[1,0,0] neg_lo:[1,0,0] neg_hi:[1,0,0]
	v_pk_add_f32 v[96:97], v[98:99], v[88:89]
	v_pk_add_f32 v[88:89], v[98:99], v[88:89] neg_lo:[0,1] neg_hi:[0,1]
	v_pk_add_f32 v[98:99], v[78:79], v[100:101]
	v_pk_add_f32 v[78:79], v[78:79], v[100:101] neg_lo:[0,1] neg_hi:[0,1]
	v_pk_add_f32 v[102:103], v[86:87], v[94:95]
	v_pk_add_f32 v[86:87], v[86:87], v[94:95] neg_lo:[0,1] neg_hi:[0,1]
	v_pk_add_f32 v[74:75], v[66:67], v[90:91] op_sel:[0,1] op_sel_hi:[1,0] neg_hi:[0,1]
	v_pk_add_f32 v[66:67], v[66:67], v[90:91] op_sel:[0,1] op_sel_hi:[1,0] neg_lo:[0,1]
	v_pk_add_f32 v[90:91], v[68:69], v[76:77]
	v_pk_add_f32 v[68:69], v[68:69], v[76:77] neg_lo:[0,1] neg_hi:[0,1]
	v_pk_mul_f32 v[100:101], v[78:79], s[68:69]
	v_pk_mul_f32 v[94:95], v[86:87], s[68:69]
	v_pk_mul_f32 v[76:77], v[68:69], s[68:69]
	v_pk_fma_f32 v[78:79], v[78:79], s[64:65], v[100:101] op_sel:[0,0,1] op_sel_hi:[1,0,0]
	v_pk_add_f32 v[100:101], v[80:81], v[92:93]
	v_pk_add_f32 v[92:93], v[80:81], v[92:93] neg_lo:[0,1] neg_hi:[0,1]
	v_pk_fma_f32 v[86:87], v[86:87], s[64:65], v[94:95] op_sel:[0,0,1] op_sel_hi:[1,0,0] neg_lo:[1,0,0] neg_hi:[1,0,0]
	v_pk_fma_f32 v[68:69], v[68:69], s[64:65], v[76:77] op_sel:[0,0,1] op_sel_hi:[1,0,0]
	v_pk_add_f32 v[76:77], v[70:71], v[82:83]
	v_pk_add_f32 v[94:95], v[72:73], v[84:85]
	v_pk_add_f32 v[72:73], v[72:73], v[84:85] neg_lo:[0,1] neg_hi:[0,1]
	v_pk_add_f32 v[70:71], v[70:71], v[82:83] neg_lo:[0,1] neg_hi:[0,1]
	v_pk_mul_f32 v[84:85], v[72:73], s[68:69]
	v_pk_add_f32 v[104:105], v[74:75], v[76:77]
	v_pk_add_f32 v[74:75], v[74:75], v[76:77] neg_lo:[0,1] neg_hi:[0,1]
	v_pk_add_f32 v[76:77], v[90:91], v[94:95]
	v_pk_add_f32 v[94:95], v[90:91], v[94:95] neg_lo:[0,1] neg_hi:[0,1]
	v_xor_b32_e32 v18, 0x80000000, v9
	v_mov_b32_e32 v19, v9
	v_pk_mul_f32 v[22:23], v[12:13], v[10:11] op_sel:[0,1] op_sel_hi:[1,0]
	v_xor_b32_e32 v83, 0x80000000, v70
	v_pk_fma_f32 v[72:73], v[72:73], s[64:65], v[84:85] op_sel:[0,0,1] op_sel_hi:[1,0,0] neg_lo:[1,0,0] neg_hi:[1,0,0]
	v_pk_add_f32 v[80:81], v[88:89], v[92:93] op_sel:[0,1] op_sel_hi:[1,0] neg_hi:[0,1]
	v_pk_add_f32 v[88:89], v[88:89], v[92:93] op_sel:[0,1] op_sel_hi:[1,0] neg_lo:[0,1]
	v_pk_add_f32 v[92:93], v[78:79], v[86:87]
	v_pk_add_f32 v[86:87], v[78:79], v[86:87] neg_lo:[0,1] neg_hi:[0,1]
	v_mov_b32_e32 v82, v71
	v_xor_b32_e32 v20, 0x80000000, v17
	v_mov_b32_e32 v21, v17
	v_pk_fma_f32 v[22:23], v[6:7], v[10:11], v[22:23] op_sel_hi:[0,1,1]
	v_pk_mul_f32 v[26:27], v[10:11], v[18:19] op_sel:[1,0] op_sel_hi:[0,1]
	v_pk_add_f32 v[70:71], v[66:67], v[82:83]
	v_pk_add_f32 v[66:67], v[66:67], v[82:83] neg_lo:[0,1] neg_hi:[0,1]
	v_pk_add_f32 v[82:83], v[68:69], v[72:73]
	v_pk_add_f32 v[72:73], v[68:69], v[72:73] neg_lo:[0,1] neg_hi:[0,1]
	v_pk_add_f32 v[90:91], v[74:75], v[94:95] op_sel:[0,1] op_sel_hi:[1,0] neg_hi:[0,1]
	v_xor_b32_e32 v24, 0x80000000, v23
	v_mov_b32_e32 v25, v23
	v_pk_fma_f32 v[26:27], v[10:11], v[8:9], v[26:27] op_sel_hi:[1,0,1]
	v_pk_add_f32 v[78:79], v[88:89], v[86:87] op_sel:[0,1] op_sel_hi:[1,0] neg_hi:[0,1]
	v_pk_add_f32 v[74:75], v[74:75], v[94:95] op_sel:[0,1] op_sel_hi:[1,0] neg_lo:[0,1]
	v_pk_mul_f32 v[94:95], v[20:21], v[90:91] op_sel:[0,1] op_sel_hi:[1,0]
	v_xor_b32_e32 v28, 0x80000000, v27
	v_mov_b32_e32 v29, v27
	v_pk_add_f32 v[84:85], v[96:97], v[100:101]
	v_pk_add_f32 v[96:97], v[96:97], v[100:101] neg_lo:[0,1] neg_hi:[0,1]
	v_pk_add_f32 v[100:101], v[98:99], v[102:103]
	v_pk_add_f32 v[68:69], v[66:67], v[72:73] op_sel:[0,1] op_sel_hi:[1,0] neg_hi:[0,1]
	v_pk_fma_f32 v[90:91], v[16:17], v[90:91], v[94:95] op_sel_hi:[0,1,1]
	v_pk_mul_f32 v[94:95], v[24:25], v[78:79] op_sel:[0,1] op_sel_hi:[1,0]
	v_xor_b32_e32 v32, 0x80000000, v31
	v_mov_b32_e32 v33, v31
	v_pk_mul_f32 v[42:43], v[12:13], v[30:31] op_sel:[0,1] op_sel_hi:[1,0]
	v_pk_add_f32 v[106:107], v[84:85], v[100:101]
	v_pk_add_f32 v[84:85], v[84:85], v[100:101] neg_lo:[0,1] neg_hi:[0,1]
	v_pk_fma_f32 v[78:79], v[22:23], v[78:79], v[94:95] op_sel_hi:[0,1,1]
	v_pk_mul_f32 v[94:95], v[28:29], v[68:69] op_sel:[0,1] op_sel_hi:[1,0]
	v_xor_b32_e32 v40, 0x80000000, v39
	v_mov_b32_e32 v41, v39
	v_pk_fma_f32 v[42:43], v[6:7], v[30:31], v[42:43] op_sel_hi:[0,1,1]
	v_pk_mul_f32 v[46:47], v[18:19], v[30:31] op_sel:[0,1] op_sel_hi:[1,0]
	v_pk_add_f32 v[86:87], v[88:89], v[86:87] op_sel:[0,1] op_sel_hi:[1,0] neg_lo:[0,1]
	v_pk_add_f32 v[88:89], v[104:105], v[76:77]
	v_pk_add_f32 v[76:77], v[104:105], v[76:77] neg_lo:[0,1] neg_hi:[0,1]
	v_pk_fma_f32 v[68:69], v[26:27], v[68:69], v[94:95] op_sel_hi:[0,1,1]
	v_pk_mul_f32 v[94:95], v[32:33], v[84:85] op_sel:[0,1] op_sel_hi:[1,0]
	v_xor_b32_e32 v44, 0x80000000, v43
	v_mov_b32_e32 v45, v43
	v_pk_fma_f32 v[46:47], v[8:9], v[30:31], v[46:47] op_sel_hi:[0,1,1]
	v_pk_add_f32 v[102:103], v[98:99], v[102:103] neg_lo:[0,1] neg_hi:[0,1]
	v_pk_add_f32 v[100:101], v[80:81], v[92:93]
	v_pk_add_f32 v[80:81], v[80:81], v[92:93] neg_lo:[0,1] neg_hi:[0,1]
	v_pk_fma_f32 v[84:85], v[30:31], v[84:85], v[94:95] op_sel_hi:[0,1,1]
	v_pk_mul_f32 v[94:95], v[40:41], v[76:77] op_sel:[0,1] op_sel_hi:[1,0]
	v_xor_b32_e32 v48, 0x80000000, v47
	v_mov_b32_e32 v49, v47
	v_pk_add_f32 v[92:93], v[70:71], v[82:83]
	v_pk_add_f32 v[70:71], v[70:71], v[82:83] neg_lo:[0,1] neg_hi:[0,1]
	v_pk_fma_f32 v[76:77], v[38:39], v[76:77], v[94:95] op_sel_hi:[0,1,1]
	v_pk_mul_f32 v[94:95], v[44:45], v[80:81] op_sel:[0,1] op_sel_hi:[1,0]
	v_xor_b32_e32 v52, 0x80000000, v51
	v_mov_b32_e32 v53, v51
	v_pk_mul_f32 v[58:59], v[12:13], v[50:51] op_sel:[0,1] op_sel_hi:[1,0]
	v_pk_add_f32 v[98:99], v[96:97], v[102:103] op_sel:[0,1] op_sel_hi:[1,0] neg_hi:[0,1]
	v_pk_add_f32 v[96:97], v[96:97], v[102:103] op_sel:[0,1] op_sel_hi:[1,0] neg_lo:[0,1]
	v_pk_fma_f32 v[80:81], v[42:43], v[80:81], v[94:95] op_sel_hi:[0,1,1]
	v_pk_mul_f32 v[94:95], v[48:49], v[70:71] op_sel:[0,1] op_sel_hi:[1,0]
	v_xor_b32_e32 v56, 0x80000000, v55
	v_mov_b32_e32 v57, v55
	v_pk_fma_f32 v[58:59], v[6:7], v[50:51], v[58:59] op_sel_hi:[0,1,1]
	v_pk_mul_f32 v[62:63], v[18:19], v[50:51] op_sel:[0,1] op_sel_hi:[1,0]
	v_pk_fma_f32 v[70:71], v[46:47], v[70:71], v[94:95] op_sel_hi:[0,1,1]
	v_pk_mul_f32 v[94:95], v[52:53], v[96:97] op_sel:[0,1] op_sel_hi:[1,0]
	v_xor_b32_e32 v60, 0x80000000, v59
	v_mov_b32_e32 v61, v59
	v_pk_fma_f32 v[62:63], v[8:9], v[50:51], v[62:63] op_sel_hi:[0,1,1]
	v_pk_add_f32 v[66:67], v[66:67], v[72:73] op_sel:[0,1] op_sel_hi:[1,0] neg_lo:[0,1]
	v_pk_mul_f32 v[72:73], v[2:3], v[88:89] op_sel:[0,1] op_sel_hi:[1,0]
	v_pk_fma_f32 v[94:95], v[50:51], v[96:97], v[94:95] op_sel_hi:[0,1,1]
	v_pk_mul_f32 v[96:97], v[56:57], v[74:75] op_sel:[0,1] op_sel_hi:[1,0]
	v_xor_b32_e32 v64, 0x80000000, v63
	v_mov_b32_e32 v65, v63
	v_pk_fma_f32 v[72:73], v[4:5], v[88:89], v[72:73] op_sel_hi:[0,1,1]
	v_pk_mul_f32 v[88:89], v[18:19], v[92:93] op_sel:[0,1] op_sel_hi:[1,0]
	v_pk_fma_f32 v[74:75], v[54:55], v[74:75], v[96:97] op_sel_hi:[0,1,1]
	v_pk_mul_f32 v[96:97], v[60:61], v[86:87] op_sel:[0,1] op_sel_hi:[1,0]
	v_add_u32_e32 v5, 0x2000, v5
	v_pk_mul_f32 v[82:83], v[12:13], v[100:101] op_sel:[0,1] op_sel_hi:[1,0]
	v_pk_fma_f32 v[88:89], v[8:9], v[92:93], v[88:89] op_sel_hi:[0,1,1]
	v_pk_mul_f32 v[92:93], v[14:15], v[98:99] op_sel:[0,1] op_sel_hi:[1,0]
	v_pk_fma_f32 v[86:87], v[58:59], v[86:87], v[96:97] op_sel_hi:[0,1,1]
	v_pk_mul_f32 v[96:97], v[64:65], v[66:67] op_sel:[0,1] op_sel_hi:[1,0]
	v_ashrrev_i32_e32 v5, 2, v5
	v_pk_fma_f32 v[82:83], v[6:7], v[100:101], v[82:83] op_sel_hi:[0,1,1]
	v_pk_fma_f32 v[92:93], v[10:11], v[98:99], v[92:93] op_sel_hi:[0,1,1]
	v_pk_fma_f32 v[66:67], v[62:63], v[66:67], v[96:97] op_sel_hi:[0,1,1]
	ds_write2_b64 v108, v[106:107], v[84:85] offset1:16
	ds_write2_b64 v108, v[92:93], v[94:95] offset0:33 offset1:49
	ds_write2_b64 v108, v[82:83], v[80:81] offset0:66 offset1:82
	ds_write2_b64 v108, v[78:79], v[86:87] offset0:99 offset1:115
	ds_write2_b64 v108, v[72:73], v[76:77] offset0:132 offset1:148
	ds_write2_b64 v108, v[90:91], v[74:75] offset0:165 offset1:181
	ds_write2_b64 v108, v[88:89], v[70:71] offset0:198 offset1:214
	ds_write2_b64 v108, v[68:69], v[66:67] offset0:231 offset1:247
	v_add3_u32 v36, v36, v5, s30
	ds_read2_b64 v[66:69], v36 offset1:16
	ds_read2_b64 v[70:73], v36 offset0:33 offset1:49
	ds_read2_b64 v[74:77], v36 offset0:66 offset1:82
	ds_read2_b64 v[78:81], v36 offset0:132 offset1:148
	ds_read2_b64 v[82:85], v36 offset0:99 offset1:115
	ds_read2_b64 v[86:89], v36 offset0:165 offset1:181
	ds_read2_b64 v[90:93], v36 offset0:198 offset1:214
	ds_read2_b64 v[94:97], v36 offset0:231 offset1:247
	s_waitcnt lgkmcnt(4)
	v_pk_add_f32 v[98:99], v[66:67], v[78:79]
	v_pk_add_f32 v[66:67], v[66:67], v[78:79] neg_lo:[0,1] neg_hi:[0,1]
	v_pk_add_f32 v[78:79], v[68:69], v[80:81]
	v_pk_add_f32 v[68:69], v[68:69], v[80:81] neg_lo:[0,1] neg_hi:[0,1]
	s_waitcnt lgkmcnt(1)
	v_pk_add_f32 v[100:101], v[76:77], v[92:93]
	v_pk_mul_f32 v[80:81], v[68:69], s[44:45]
	v_pk_add_f32 v[76:77], v[76:77], v[92:93] neg_lo:[0,1] neg_hi:[0,1]
	v_pk_fma_f32 v[68:69], v[68:69], s[42:43], v[80:81] op_sel:[0,0,1] op_sel_hi:[1,0,0]
	v_pk_add_f32 v[80:81], v[70:71], v[86:87]
	v_pk_add_f32 v[70:71], v[70:71], v[86:87] neg_lo:[0,1] neg_hi:[0,1]
	v_pk_mul_f32 v[92:93], v[76:77], s[76:77]
	v_pk_mul_f32 v[86:87], v[70:71], s[68:69]
	v_pk_fma_f32 v[76:77], v[76:77], s[72:73], v[92:93] op_sel:[0,0,1] op_sel_hi:[1,0,0] neg_lo:[1,0,0] neg_hi:[1,0,0]
	s_waitcnt lgkmcnt(0)
	v_pk_add_f32 v[92:93], v[82:83], v[94:95]
	v_pk_add_f32 v[82:83], v[82:83], v[94:95] neg_lo:[0,1] neg_hi:[0,1]
	v_pk_fma_f32 v[70:71], v[70:71], s[64:65], v[86:87] op_sel:[0,0,1] op_sel_hi:[1,0,0]
	v_pk_add_f32 v[86:87], v[72:73], v[88:89]
	v_pk_add_f32 v[72:73], v[72:73], v[88:89] neg_lo:[0,1] neg_hi:[0,1]
	v_pk_mul_f32 v[94:95], v[82:83], s[68:69]
	v_pk_mul_f32 v[88:89], v[72:73], s[76:77]
	v_pk_fma_f32 v[82:83], v[82:83], s[64:65], v[94:95] op_sel:[0,0,1] op_sel_hi:[1,0,0] neg_lo:[1,0,0] neg_hi:[1,0,0]
	v_pk_add_f32 v[94:95], v[84:85], v[96:97]
	v_pk_add_f32 v[84:85], v[84:85], v[96:97] neg_lo:[0,1] neg_hi:[0,1]
	v_pk_fma_f32 v[72:73], v[72:73], s[72:73], v[88:89] op_sel:[0,0,1] op_sel_hi:[1,0,0]
	v_pk_add_f32 v[88:89], v[74:75], v[90:91]
	v_pk_mul_f32 v[96:97], v[84:85], s[44:45]
	v_pk_add_f32 v[90:91], v[74:75], v[90:91] neg_lo:[0,1] neg_hi:[0,1]
	v_pk_fma_f32 v[84:85], v[84:85], s[42:43], v[96:97] op_sel:[0,0,1] op_sel_hi:[1,0,0] neg_lo:[1,0,0] neg_hi:[1,0,0]
	v_pk_add_f32 v[96:97], v[98:99], v[88:89]
	v_pk_add_f32 v[88:89], v[98:99], v[88:89] neg_lo:[0,1] neg_hi:[0,1]
	v_pk_add_f32 v[98:99], v[78:79], v[100:101]
	v_pk_add_f32 v[78:79], v[78:79], v[100:101] neg_lo:[0,1] neg_hi:[0,1]
	v_pk_add_f32 v[102:103], v[86:87], v[94:95]
	v_pk_add_f32 v[86:87], v[86:87], v[94:95] neg_lo:[0,1] neg_hi:[0,1]
	v_pk_mul_f32 v[100:101], v[78:79], s[68:69]
	v_pk_mul_f32 v[94:95], v[86:87], s[68:69]
	v_pk_fma_f32 v[78:79], v[78:79], s[64:65], v[100:101] op_sel:[0,0,1] op_sel_hi:[1,0,0]
	v_pk_add_f32 v[100:101], v[80:81], v[92:93]
	v_pk_add_f32 v[92:93], v[80:81], v[92:93] neg_lo:[0,1] neg_hi:[0,1]
	v_pk_fma_f32 v[86:87], v[86:87], s[64:65], v[94:95] op_sel:[0,0,1] op_sel_hi:[1,0,0] neg_lo:[1,0,0] neg_hi:[1,0,0]
	v_pk_add_f32 v[74:75], v[66:67], v[90:91] op_sel:[0,1] op_sel_hi:[1,0] neg_hi:[0,1]
	v_pk_add_f32 v[66:67], v[66:67], v[90:91] op_sel:[0,1] op_sel_hi:[1,0] neg_lo:[0,1]
	v_pk_add_f32 v[90:91], v[68:69], v[76:77]
	v_pk_add_f32 v[68:69], v[68:69], v[76:77] neg_lo:[0,1] neg_hi:[0,1]
	v_pk_add_f32 v[94:95], v[72:73], v[84:85]
	v_pk_add_f32 v[72:73], v[72:73], v[84:85] neg_lo:[0,1] neg_hi:[0,1]
	v_pk_mul_f32 v[76:77], v[68:69], s[68:69]
	v_pk_mul_f32 v[84:85], v[72:73], s[68:69]
	v_pk_fma_f32 v[68:69], v[68:69], s[64:65], v[76:77] op_sel:[0,0,1] op_sel_hi:[1,0,0]
	v_pk_add_f32 v[76:77], v[70:71], v[82:83]
	v_pk_fma_f32 v[72:73], v[72:73], s[64:65], v[84:85] op_sel:[0,0,1] op_sel_hi:[1,0,0] neg_lo:[1,0,0] neg_hi:[1,0,0]
	v_pk_add_f32 v[80:81], v[88:89], v[92:93] op_sel:[0,1] op_sel_hi:[1,0] neg_hi:[0,1]
	v_pk_add_f32 v[88:89], v[88:89], v[92:93] op_sel:[0,1] op_sel_hi:[1,0] neg_lo:[0,1]
	v_pk_add_f32 v[92:93], v[78:79], v[86:87]
	v_pk_add_f32 v[86:87], v[78:79], v[86:87] neg_lo:[0,1] neg_hi:[0,1]
	s_add_i32 s65, s65, s28
	v_pk_add_f32 v[82:83], v[70:71], v[82:83] neg_lo:[0,1] neg_hi:[0,1]
	s_nop 0
	v_pk_add_f32 v[104:105], v[74:75], v[76:77]
	v_pk_add_f32 v[74:75], v[74:75], v[76:77] neg_lo:[0,1] neg_hi:[0,1]
	v_pk_add_f32 v[76:77], v[90:91], v[94:95]
	s_cmpk_gt_i32 s65, 0x3ff
	s_nop 0
	v_pk_add_f32 v[84:85], v[96:97], v[100:101]
	v_pk_add_f32 v[96:97], v[96:97], v[100:101] neg_lo:[0,1] neg_hi:[0,1]
	v_pk_add_f32 v[100:101], v[98:99], v[102:103]
	s_nop 0
	v_pk_add_f32 v[78:79], v[88:89], v[86:87] op_sel:[0,1] op_sel_hi:[1,0] neg_hi:[0,1]
	v_pk_add_f32 v[86:87], v[88:89], v[86:87] op_sel:[0,1] op_sel_hi:[1,0] neg_lo:[0,1]
	v_pk_add_f32 v[88:89], v[104:105], v[76:77]
	s_cselect_b64 s[80:81], -1, 0
	s_cmpk_lt_i32 s65, 0x400
	v_pk_add_f32 v[98:99], v[98:99], v[102:103] neg_lo:[0,1] neg_hi:[0,1]
	v_pk_add_f32 v[70:71], v[66:67], v[82:83] op_sel:[0,1] op_sel_hi:[1,0] neg_hi:[0,1]
	v_pk_add_f32 v[66:67], v[66:67], v[82:83] op_sel:[0,1] op_sel_hi:[1,0] neg_lo:[0,1]
	v_pk_add_f32 v[82:83], v[68:69], v[72:73]
	v_pk_add_f32 v[106:107], v[84:85], v[100:101]
	v_pk_add_f32 v[84:85], v[84:85], v[100:101] neg_lo:[0,1] neg_hi:[0,1]
	v_pk_add_f32 v[100:101], v[80:81], v[92:93]
	v_pk_mul_f32 v[2:3], v[2:3], v[88:89] op_sel:[0,1] op_sel_hi:[1,0]
	s_cselect_b32 s6, s65, s6
	v_xor_b32_e32 v103, 0x80000000, v98
	v_pk_add_f32 v[90:91], v[90:91], v[94:95] neg_lo:[0,1] neg_hi:[0,1]
	v_mov_b32_e32 v102, v99
	v_pk_add_f32 v[80:81], v[80:81], v[92:93] neg_lo:[0,1] neg_hi:[0,1]
	v_pk_add_f32 v[92:93], v[70:71], v[82:83]
	v_pk_fma_f32 v[2:3], v[4:5], v[88:89], v[2:3] op_sel_hi:[0,1,1]
	v_pk_mul_f32 v[4:5], v[12:13], v[100:101] op_sel:[0,1] op_sel_hi:[1,0]
	s_lshl_b32 s8, s6, 1
	s_lshl_b32 s6, s6, 2
	v_xor_b32_e32 v95, 0x80000000, v90
	v_pk_add_f32 v[68:69], v[68:69], v[72:73] neg_lo:[0,1] neg_hi:[0,1]
	v_pk_add_f32 v[98:99], v[96:97], v[102:103]
	v_mov_b32_e32 v94, v91
	v_pk_fma_f32 v[4:5], v[6:7], v[100:101], v[4:5] op_sel_hi:[0,1,1]
	v_pk_mul_f32 v[6:7], v[18:19], v[92:93] op_sel:[0,1] op_sel_hi:[1,0]
	s_and_b32 s7, s8, 0x3fe
	s_and_b32 s6, s6, 0xfffff800
	v_xor_b32_e32 v73, 0x80000000, v68
	v_pk_add_f32 v[90:91], v[74:75], v[94:95]
	v_mov_b32_e32 v72, v69
	v_pk_fma_f32 v[6:7], v[8:9], v[92:93], v[6:7] op_sel_hi:[0,1,1]
	v_pk_mul_f32 v[8:9], v[14:15], v[98:99] op_sel:[0,1] op_sel_hi:[1,0]
	s_or_b32 s6, s7, s6
	v_pk_add_f32 v[68:69], v[66:67], v[72:73]
	v_pk_fma_f32 v[8:9], v[10:11], v[98:99], v[8:9] op_sel_hi:[0,1,1]
	v_pk_mul_f32 v[10:11], v[20:21], v[90:91] op_sel:[0,1] op_sel_hi:[1,0]
	s_ashr_i32 s7, s6, 31
	v_pk_add_f32 v[96:97], v[96:97], v[102:103] neg_lo:[0,1] neg_hi:[0,1]
	v_pk_add_f32 v[76:77], v[104:105], v[76:77] neg_lo:[0,1] neg_hi:[0,1]
	v_pk_add_f32 v[74:75], v[74:75], v[94:95] neg_lo:[0,1] neg_hi:[0,1]
	v_pk_add_f32 v[70:71], v[70:71], v[82:83] neg_lo:[0,1] neg_hi:[0,1]
	v_pk_add_f32 v[66:67], v[66:67], v[72:73] neg_lo:[0,1] neg_hi:[0,1]
	v_pk_fma_f32 v[10:11], v[16:17], v[90:91], v[10:11] op_sel_hi:[0,1,1]
	v_pk_mul_f32 v[12:13], v[24:25], v[78:79] op_sel:[0,1] op_sel_hi:[1,0]
	v_pk_mul_f32 v[14:15], v[28:29], v[68:69] op_sel:[0,1] op_sel_hi:[1,0]
	v_pk_mul_f32 v[16:17], v[32:33], v[84:85] op_sel:[0,1] op_sel_hi:[1,0]
	s_lshl_b64 s[82:83], s[6:7], 14
	s_bitset1_b32 s6, 10
	v_pk_fma_f32 v[12:13], v[22:23], v[78:79], v[12:13] op_sel_hi:[0,1,1]
	v_pk_fma_f32 v[14:15], v[26:27], v[68:69], v[14:15] op_sel_hi:[0,1,1]
	v_pk_fma_f32 v[16:17], v[30:31], v[84:85], v[16:17] op_sel_hi:[0,1,1]
	v_pk_mul_f32 v[18:19], v[40:41], v[76:77] op_sel:[0,1] op_sel_hi:[1,0]
	v_pk_mul_f32 v[20:21], v[44:45], v[80:81] op_sel:[0,1] op_sel_hi:[1,0]
	v_pk_mul_f32 v[22:23], v[48:49], v[70:71] op_sel:[0,1] op_sel_hi:[1,0]
	v_pk_mul_f32 v[24:25], v[52:53], v[96:97] op_sel:[0,1] op_sel_hi:[1,0]
	v_pk_mul_f32 v[26:27], v[56:57], v[74:75] op_sel:[0,1] op_sel_hi:[1,0]
	v_pk_mul_f32 v[28:29], v[60:61], v[86:87] op_sel:[0,1] op_sel_hi:[1,0]
	v_pk_mul_f32 v[30:31], v[64:65], v[66:67] op_sel:[0,1] op_sel_hi:[1,0]
	s_ashr_i32 s7, s6, 31
	v_pk_fma_f32 v[18:19], v[38:39], v[76:77], v[18:19] op_sel_hi:[0,1,1]
	v_pk_fma_f32 v[20:21], v[42:43], v[80:81], v[20:21] op_sel_hi:[0,1,1]
	v_pk_fma_f32 v[22:23], v[46:47], v[70:71], v[22:23] op_sel_hi:[0,1,1]
	v_pk_fma_f32 v[24:25], v[50:51], v[96:97], v[24:25] op_sel_hi:[0,1,1]
	v_pk_fma_f32 v[26:27], v[54:55], v[74:75], v[26:27] op_sel_hi:[0,1,1]
	v_pk_fma_f32 v[28:29], v[58:59], v[86:87], v[28:29] op_sel_hi:[0,1,1]
	v_pk_fma_f32 v[30:31], v[62:63], v[66:67], v[30:31] op_sel_hi:[0,1,1]
	ds_write2_b64 v36, v[106:107], v[16:17] offset1:16
	ds_write2_b64 v36, v[8:9], v[24:25] offset0:33 offset1:49
	ds_write2_b64 v36, v[4:5], v[20:21] offset0:66 offset1:82
	ds_write2_b64 v36, v[12:13], v[28:29] offset0:99 offset1:115
	ds_write2_b64 v36, v[2:3], v[18:19] offset0:132 offset1:148
	ds_write2_b64 v36, v[10:11], v[26:27] offset0:165 offset1:181
	ds_write2_b64 v36, v[6:7], v[22:23] offset0:198 offset1:214
	ds_write2_b64 v36, v[14:15], v[30:31] offset0:231 offset1:247
	s_lshl_b64 s[6:7], s[6:7], 14
	v_lshl_add_u64 v[2:3], v[34:35], 0, s[82:83]
	s_waitcnt lgkmcnt(0)
	s_barrier
	global_load_dwordx4 v[10:13], v[2:3], off nt
	global_load_dwordx4 v[30:33], v[2:3], off offset:16 nt
	v_lshl_add_u64 v[2:3], v[34:35], 0, s[6:7]
	global_load_dwordx4 v[26:29], v[2:3], off nt
	global_load_dwordx4 v[22:25], v[2:3], off offset:16 nt
	v_mov_b32_e32 v38, 0
	s_and_saveexec_b64 s[6:7], s[0:1]
	s_cbranch_execz .LBB0_430
	global_load_ushort v38, v[2:3], off offset:32

.LBB0_499:
	v_mov_b32_e32 v2, v210
	s_mov_b32 s43, s8
	v_and_b32_e32 v3, 0x1ff, v2
	v_lshlrev_b32_e32 v2, 5, v2
	v_and_or_b32 v2, v2, s94, v3
	v_ashrrev_i32_e32 v4, 5, v2
	v_lshlrev_b32_e32 v2, 3, v2
	v_lshlrev_b32_e32 v4, 3, v4
	v_add3_u32 v18, 0, v2, v4
	ds_read_b64 v[128:129], v18
	ds_read_b64 v[134:135], v18 offset:4224
	ds_read_b64 v[136:137], v18 offset:8448
	ds_read_b64 v[138:139], v18 offset:12672
	ds_read_b64 v[140:141], v18 offset:16896
	ds_read_b64 v[142:143], v18 offset:21120
	ds_read_b64 v[132:133], v18 offset:25344
	ds_read_b64 v[130:131], v18 offset:29568
	ds_read_b64 v[144:145], v18 offset:33792
	ds_read_b64 v[148:149], v18 offset:38016
	ds_read_b64 v[150:151], v18 offset:42240
	ds_read_b64 v[152:153], v18 offset:46464
	s_waitcnt lgkmcnt(10)
	v_pk_mul_f32 v[162:163], v[134:135], s[10:11]
	s_mov_b32 s74, s11
	v_pk_fma_f32 v[162:163], v[134:135], s[8:9], v[162:163] op_sel:[0,0,1] op_sel_hi:[1,0,0]
	s_waitcnt lgkmcnt(2)
	v_pk_mul_f32 v[178:179], v[148:149], s[42:43]
	v_pk_add_f32 v[194:195], v[134:135], v[148:149]
	v_pk_add_f32 v[134:135], v[134:135], v[148:149] neg_lo:[0,1] neg_hi:[0,1]
	v_pk_mul_f32 v[164:165], v[136:137], s[18:19]
	s_mov_b32 s41, s16
	v_pk_fma_f32 v[178:179], v[148:149], s[74:75], v[178:179] op_sel:[0,0,1] op_sel_hi:[1,0,0] neg_lo:[1,0,0] neg_hi:[1,0,0]
	v_pk_mul_f32 v[148:149], v[134:135], s[18:19]
	v_pk_fma_f32 v[164:165], v[136:137], s[16:17], v[164:165] op_sel:[0,0,1] op_sel_hi:[1,0,0]
	s_mov_b32 s80, s19
	s_waitcnt lgkmcnt(1)
	v_pk_mul_f32 v[180:181], v[150:151], s[40:41]
	v_pk_fma_f32 v[134:135], v[134:135], s[16:17], v[148:149] op_sel:[0,0,1] op_sel_hi:[1,0,0]
	v_pk_add_f32 v[148:149], v[136:137], v[150:151]
	v_pk_add_f32 v[136:137], v[136:137], v[150:151] neg_lo:[0,1] neg_hi:[0,1]
	v_pk_mul_f32 v[166:167], v[138:139], s[26:27]
	s_mov_b32 s78, s37
	s_mov_b32 s39, s24
	v_pk_fma_f32 v[180:181], v[150:151], s[80:81], v[180:181] op_sel:[0,0,1] op_sel_hi:[1,0,0] neg_lo:[1,0,0] neg_hi:[1,0,0]
	v_pk_mul_f32 v[150:151], v[136:137], s[36:37]
	ds_read_b64 v[154:155], v18 offset:50688
	ds_read_b64 v[156:157], v18 offset:54912
	ds_read_b64 v[158:159], v18 offset:59136
	ds_read_b64 v[160:161], v18 offset:63360
	v_pk_fma_f32 v[166:167], v[138:139], s[24:25], v[166:167] op_sel:[0,0,1] op_sel_hi:[1,0,0]
	s_mov_b32 s0, s27
	s_waitcnt lgkmcnt(4)
	v_pk_mul_f32 v[182:183], v[152:153], s[38:39]
	v_pk_fma_f32 v[136:137], v[136:137], s[78:79], v[150:151] op_sel:[0,0,1] op_sel_hi:[1,0,0]
	v_pk_add_f32 v[150:151], v[138:139], v[152:153]
	v_pk_add_f32 v[138:139], v[138:139], v[152:153] neg_lo:[0,1] neg_hi:[0,1]
	v_pk_mul_f32 v[168:169], v[140:141], s[36:37]
	v_pk_fma_f32 v[182:183], v[152:153], s[0:1], v[182:183] op_sel:[0,0,1] op_sel_hi:[1,0,0] neg_lo:[1,0,0] neg_hi:[1,0,0]
	v_pk_mul_f32 v[152:153], v[138:139], s[40:41]
	v_pk_fma_f32 v[168:169], v[140:141], s[78:79], v[168:169] op_sel:[0,0,1] op_sel_hi:[1,0,0]
	v_pk_mul_f32 v[170:171], v[142:143], s[38:39]
	s_waitcnt lgkmcnt(3)
	v_pk_mul_f32 v[184:185], v[154:155], s[36:37]
	v_pk_fma_f32 v[138:139], v[138:139], s[80:81], v[152:153] op_sel:[0,0,1] op_sel_hi:[1,0,0]
	v_pk_add_f32 v[152:153], v[140:141], v[154:155]
	v_pk_add_f32 v[140:141], v[140:141], v[154:155] neg_lo:[0,1] neg_hi:[0,1]
	v_pk_fma_f32 v[170:171], v[142:143], s[0:1], v[170:171] op_sel:[0,0,1] op_sel_hi:[1,0,0]
	v_pk_fma_f32 v[184:185], v[154:155], s[78:79], v[184:185] op_sel:[0,0,1] op_sel_hi:[1,0,0] neg_lo:[1,0,0] neg_hi:[1,0,0]
	s_waitcnt lgkmcnt(2)
	v_pk_mul_f32 v[186:187], v[156:157], s[26:27]
	v_xor_b32_e32 v155, 0x80000000, v140
	v_mov_b32_e32 v154, v141
	v_pk_add_f32 v[140:141], v[142:143], v[156:157]
	v_pk_add_f32 v[142:143], v[142:143], v[156:157] neg_lo:[0,1] neg_hi:[0,1]
	v_pk_mul_f32 v[172:173], v[132:133], s[40:41]
	v_pk_fma_f32 v[186:187], v[156:157], s[24:25], v[186:187] op_sel:[0,0,1] op_sel_hi:[1,0,0] neg_lo:[1,0,0] neg_hi:[1,0,0]
	v_pk_mul_f32 v[156:157], v[142:143], s[40:41]
	v_pk_fma_f32 v[172:173], v[132:133], s[80:81], v[172:173] op_sel:[0,0,1] op_sel_hi:[1,0,0]
	s_waitcnt lgkmcnt(1)
	v_pk_mul_f32 v[188:189], v[158:159], s[18:19]
	v_pk_fma_f32 v[142:143], v[142:143], s[80:81], v[156:157] op_sel:[0,0,1] op_sel_hi:[1,0,0] neg_lo:[1,0,0] neg_hi:[1,0,0]
	v_pk_add_f32 v[156:157], v[132:133], v[158:159]
	v_pk_add_f32 v[132:133], v[132:133], v[158:159] neg_lo:[0,1] neg_hi:[0,1]
	v_pk_mul_f32 v[174:175], v[130:131], s[42:43]
	v_pk_fma_f32 v[188:189], v[158:159], s[16:17], v[188:189] op_sel:[0,0,1] op_sel_hi:[1,0,0] neg_lo:[1,0,0] neg_hi:[1,0,0]
	v_pk_mul_f32 v[158:159], v[132:133], s[36:37]
	v_pk_fma_f32 v[174:175], v[130:131], s[74:75], v[174:175] op_sel:[0,0,1] op_sel_hi:[1,0,0]
	s_waitcnt lgkmcnt(0)
	v_pk_mul_f32 v[190:191], v[160:161], s[10:11]
	v_pk_fma_f32 v[132:133], v[132:133], s[78:79], v[158:159] op_sel:[0,0,1] op_sel_hi:[1,0,0] neg_lo:[1,0,0] neg_hi:[1,0,0]
	v_pk_add_f32 v[158:159], v[130:131], v[160:161]
	v_pk_add_f32 v[130:131], v[130:131], v[160:161] neg_lo:[0,1] neg_hi:[0,1]
	v_xor_b32_e32 v177, 0x80000000, v144
	v_mov_b32_e32 v176, v145
	v_pk_fma_f32 v[190:191], v[160:161], s[8:9], v[190:191] op_sel:[0,0,1] op_sel_hi:[1,0,0] neg_lo:[1,0,0] neg_hi:[1,0,0]
	v_pk_mul_f32 v[160:161], v[130:131], s[18:19]
	v_pk_add_f32 v[192:193], v[128:129], v[144:145]
	v_pk_add_f32 v[144:145], v[128:129], v[144:145] neg_lo:[0,1] neg_hi:[0,1]
	v_pk_fma_f32 v[130:131], v[130:131], s[16:17], v[160:161] op_sel:[0,0,1] op_sel_hi:[1,0,0] neg_lo:[1,0,0] neg_hi:[1,0,0]
	v_pk_add_f32 v[160:161], v[128:129], v[176:177]
	v_pk_add_f32 v[128:129], v[128:129], v[176:177] neg_lo:[0,1] neg_hi:[0,1]
	v_pk_add_f32 v[176:177], v[162:163], v[178:179]
	v_pk_add_f32 v[162:163], v[162:163], v[178:179] neg_lo:[0,1] neg_hi:[0,1]
	v_cvt_f32_u32_e32 v2, v3
	v_pk_mul_f32 v[178:179], v[162:163], s[18:19]
	s_add_i32 s76, s72, s48
	v_pk_fma_f32 v[162:163], v[162:163], s[16:17], v[178:179] op_sel:[0,0,1] op_sel_hi:[1,0,0]
	v_pk_add_f32 v[178:179], v[164:165], v[180:181]
	v_pk_add_f32 v[164:165], v[164:165], v[180:181] neg_lo:[0,1] neg_hi:[0,1]
	v_mul_f32_e32 v2, 0x38800000, v2
	v_pk_mul_f32 v[180:181], v[164:165], s[36:37]
	v_sin_f32_e32 v34, v2
	v_pk_fma_f32 v[164:165], v[164:165], s[78:79], v[180:181] op_sel:[0,0,1] op_sel_hi:[1,0,0]
	v_pk_add_f32 v[180:181], v[166:167], v[182:183]
	v_pk_add_f32 v[166:167], v[166:167], v[182:183] neg_lo:[0,1] neg_hi:[0,1]
	v_cos_f32_e32 v30, v2
	v_pk_mul_f32 v[182:183], v[166:167], s[40:41]
	v_xor_b32_e32 v31, 0x80000000, v34
	v_pk_fma_f32 v[166:167], v[166:167], s[80:81], v[182:183] op_sel:[0,0,1] op_sel_hi:[1,0,0]
	v_pk_add_f32 v[182:183], v[168:169], v[184:185]
	v_pk_add_f32 v[184:185], v[168:169], v[184:185] neg_lo:[0,1] neg_hi:[0,1]
	v_mov_b32_e32 v35, v31
	v_pk_add_f32 v[168:169], v[170:171], v[186:187]
	v_pk_add_f32 v[170:171], v[170:171], v[186:187] neg_lo:[0,1] neg_hi:[0,1]
	v_pk_mul_f32 v[2:3], v[30:31], v[34:35] op_sel:[1,0] op_sel_hi:[0,1]
	v_pk_mul_f32 v[186:187], v[170:171], s[40:41]
	v_pk_fma_f32 v[44:45], v[30:31], v[30:31], v[2:3] op_sel_hi:[1,0,1]
	v_pk_fma_f32 v[170:171], v[170:171], s[80:81], v[186:187] op_sel:[0,0,1] op_sel_hi:[1,0,0] neg_lo:[1,0,0] neg_hi:[1,0,0]
	v_pk_add_f32 v[186:187], v[172:173], v[188:189]
	v_pk_add_f32 v[172:173], v[172:173], v[188:189] neg_lo:[0,1] neg_hi:[0,1]
	v_pk_mul_f32 v[2:3], v[34:35], v[44:45] op_sel:[0,1] op_sel_hi:[1,0]
	v_pk_mul_f32 v[188:189], v[172:173], s[36:37]
	v_xor_b32_e32 v54, 0x80000000, v45
	v_pk_fma_f32 v[172:173], v[172:173], s[78:79], v[188:189] op_sel:[0,0,1] op_sel_hi:[1,0,0] neg_lo:[1,0,0] neg_hi:[1,0,0]
	v_pk_add_f32 v[188:189], v[174:175], v[190:191]
	v_pk_add_f32 v[174:175], v[174:175], v[190:191] neg_lo:[0,1] neg_hi:[0,1]
	v_mov_b32_e32 v55, v45
	v_pk_mul_f32 v[190:191], v[174:175], s[18:19]
	v_pk_fma_f32 v[46:47], v[30:31], v[44:45], v[2:3] op_sel_hi:[0,1,1]
	v_pk_fma_f32 v[174:175], v[174:175], s[16:17], v[190:191] op_sel:[0,0,1] op_sel_hi:[1,0,0] neg_lo:[1,0,0] neg_hi:[1,0,0]
	v_pk_add_f32 v[190:191], v[192:193], v[152:153]
	v_pk_add_f32 v[152:153], v[192:193], v[152:153] neg_lo:[0,1] neg_hi:[0,1]
	v_pk_add_f32 v[192:193], v[194:195], v[140:141]
	v_pk_add_f32 v[140:141], v[194:195], v[140:141] neg_lo:[0,1] neg_hi:[0,1]
	v_pk_mul_f32 v[2:3], v[44:45], v[54:55] op_sel:[1,0] op_sel_hi:[0,1]
	v_pk_mul_f32 v[194:195], v[140:141], s[36:37]
	v_pk_fma_f32 v[52:53], v[44:45], v[44:45], v[2:3] op_sel_hi:[1,0,1]
	v_pk_fma_f32 v[140:141], v[140:141], s[78:79], v[194:195] op_sel:[0,0,1] op_sel_hi:[1,0,0]
	v_pk_add_f32 v[194:195], v[148:149], v[156:157]
	v_pk_add_f32 v[156:157], v[148:149], v[156:157] neg_lo:[0,1] neg_hi:[0,1]
	v_xor_b32_e32 v58, 0x80000000, v53
	v_pk_add_f32 v[148:149], v[150:151], v[158:159]
	v_pk_add_f32 v[150:151], v[150:151], v[158:159] neg_lo:[0,1] neg_hi:[0,1]
	v_mov_b32_e32 v59, v53
	v_pk_mul_f32 v[158:159], v[150:151], s[36:37]
	v_pk_mul_f32 v[2:3], v[52:53], v[58:59] op_sel:[1,0] op_sel_hi:[0,1]
	v_pk_fma_f32 v[150:151], v[150:151], s[78:79], v[158:159] op_sel:[0,0,1] op_sel_hi:[1,0,0] neg_lo:[1,0,0] neg_hi:[1,0,0]
	v_pk_add_f32 v[158:159], v[144:145], v[154:155]
	v_pk_add_f32 v[144:145], v[144:145], v[154:155] neg_lo:[0,1] neg_hi:[0,1]
	v_pk_add_f32 v[154:155], v[134:135], v[142:143]
	v_pk_add_f32 v[134:135], v[134:135], v[142:143] neg_lo:[0,1] neg_hi:[0,1]
	v_pk_fma_f32 v[48:49], v[52:53], v[52:53], v[2:3] op_sel_hi:[1,0,1]
	v_pk_mul_f32 v[142:143], v[134:135], s[36:37]
	v_pk_mul_f32 v[2:3], v[58:59], v[48:49] op_sel:[0,1] op_sel_hi:[1,0]
	v_pk_fma_f32 v[134:135], v[134:135], s[78:79], v[142:143] op_sel:[0,0,1] op_sel_hi:[1,0,0]
	v_pk_add_f32 v[142:143], v[136:137], v[132:133]
	v_pk_add_f32 v[136:137], v[136:137], v[132:133] neg_lo:[0,1] neg_hi:[0,1]
	v_pk_fma_f32 v[36:37], v[52:53], v[48:49], v[2:3] op_sel_hi:[0,1,1]
	v_pk_add_f32 v[132:133], v[138:139], v[130:131]
	v_pk_add_f32 v[130:131], v[138:139], v[130:131] neg_lo:[0,1] neg_hi:[0,1]
	v_pk_mul_f32 v[2:3], v[58:59], v[36:37] op_sel:[0,1] op_sel_hi:[1,0]
	v_pk_mul_f32 v[138:139], v[130:131], s[36:37]
	v_pk_fma_f32 v[26:27], v[52:53], v[36:37], v[2:3] op_sel_hi:[0,1,1]
	v_pk_fma_f32 v[130:131], v[130:131], s[78:79], v[138:139] op_sel:[0,0,1] op_sel_hi:[1,0,0] neg_lo:[1,0,0] neg_hi:[1,0,0]
	v_pk_add_f32 v[138:139], v[160:161], v[182:183]
	v_pk_add_f32 v[160:161], v[160:161], v[182:183] neg_lo:[0,1] neg_hi:[0,1]
	v_pk_add_f32 v[182:183], v[176:177], v[168:169]
	v_pk_add_f32 v[168:169], v[176:177], v[168:169] neg_lo:[0,1] neg_hi:[0,1]
	v_pk_mul_f32 v[2:3], v[58:59], v[26:27] op_sel:[0,1] op_sel_hi:[1,0]
	v_pk_mul_f32 v[176:177], v[168:169], s[36:37]
	v_pk_fma_f32 v[20:21], v[52:53], v[26:27], v[2:3] op_sel_hi:[0,1,1]
	v_pk_fma_f32 v[168:169], v[168:169], s[78:79], v[176:177] op_sel:[0,0,1] op_sel_hi:[1,0,0]
	v_pk_add_f32 v[176:177], v[178:179], v[186:187]
	v_pk_add_f32 v[186:187], v[178:179], v[186:187] neg_lo:[0,1] neg_hi:[0,1]
	v_pk_mul_f32 v[2:3], v[58:59], v[20:21] op_sel:[0,1] op_sel_hi:[1,0]
	v_pk_add_f32 v[178:179], v[180:181], v[188:189]
	v_pk_add_f32 v[180:181], v[180:181], v[188:189] neg_lo:[0,1] neg_hi:[0,1]
	v_pk_fma_f32 v[10:11], v[52:53], v[20:21], v[2:3] op_sel_hi:[0,1,1]
	v_pk_mul_f32 v[188:189], v[180:181], s[36:37]
	v_pk_mul_f32 v[2:3], v[58:59], v[10:11] op_sel:[0,1] op_sel_hi:[1,0]
	v_pk_fma_f32 v[180:181], v[180:181], s[78:79], v[188:189] op_sel:[0,0,1] op_sel_hi:[1,0,0] neg_lo:[1,0,0] neg_hi:[1,0,0]
	v_pk_add_f32 v[188:189], v[128:129], v[184:185] op_sel:[0,1] op_sel_hi:[1,0] neg_hi:[0,1]
	v_pk_add_f32 v[128:129], v[128:129], v[184:185] op_sel:[0,1] op_sel_hi:[1,0] neg_lo:[0,1]
	v_pk_add_f32 v[184:185], v[162:163], v[170:171]
	v_pk_add_f32 v[162:163], v[162:163], v[170:171] neg_lo:[0,1] neg_hi:[0,1]
	v_pk_fma_f32 v[4:5], v[52:53], v[10:11], v[2:3] op_sel_hi:[0,1,1]
	v_pk_mul_f32 v[170:171], v[162:163], s[36:37]
	v_pk_mul_f32 v[8:9], v[54:55], v[4:5] op_sel:[0,1] op_sel_hi:[1,0]
	v_pk_fma_f32 v[162:163], v[162:163], s[78:79], v[170:171] op_sel:[0,0,1] op_sel_hi:[1,0,0]
	v_pk_add_f32 v[170:171], v[164:165], v[172:173]
	v_pk_add_f32 v[172:173], v[164:165], v[172:173] neg_lo:[0,1] neg_hi:[0,1]
	v_pk_mul_f32 v[14:15], v[34:35], v[4:5] op_sel:[0,1] op_sel_hi:[1,0]
	v_pk_add_f32 v[164:165], v[166:167], v[174:175]
	v_pk_add_f32 v[166:167], v[166:167], v[174:175] neg_lo:[0,1] neg_hi:[0,1]
	v_pk_mul_f32 v[32:33], v[54:55], v[10:11] op_sel:[0,1] op_sel_hi:[1,0]
	v_pk_mul_f32 v[174:175], v[166:167], s[36:37]
	v_pk_mul_f32 v[40:41], v[34:35], v[10:11] op_sel:[0,1] op_sel_hi:[1,0]
	v_pk_fma_f32 v[166:167], v[166:167], s[78:79], v[174:175] op_sel:[0,0,1] op_sel_hi:[1,0,0] neg_lo:[1,0,0] neg_hi:[1,0,0]
	v_pk_add_f32 v[174:175], v[190:191], v[194:195]
	v_pk_add_f32 v[190:191], v[190:191], v[194:195] neg_lo:[0,1] neg_hi:[0,1]
	v_pk_add_f32 v[194:195], v[192:193], v[148:149]
	v_pk_add_f32 v[192:193], v[192:193], v[148:149] neg_lo:[0,1] neg_hi:[0,1]
	v_pk_mul_f32 v[62:63], v[54:55], v[20:21] op_sel:[0,1] op_sel_hi:[1,0]
	v_pk_add_f32 v[148:149], v[152:153], v[156:157] op_sel:[0,1] op_sel_hi:[1,0] neg_hi:[0,1]
	v_pk_add_f32 v[152:153], v[152:153], v[156:157] op_sel:[0,1] op_sel_hi:[1,0] neg_lo:[0,1]
	v_pk_add_f32 v[156:157], v[140:141], v[150:151]
	v_pk_add_f32 v[150:151], v[140:141], v[150:151] neg_lo:[0,1] neg_hi:[0,1]
	v_pk_mul_f32 v[66:67], v[34:35], v[20:21] op_sel:[0,1] op_sel_hi:[1,0]
	v_pk_add_f32 v[140:141], v[158:159], v[142:143]
	v_pk_add_f32 v[142:143], v[158:159], v[142:143] neg_lo:[0,1] neg_hi:[0,1]
	v_pk_add_f32 v[158:159], v[154:155], v[132:133]
	v_pk_add_f32 v[154:155], v[154:155], v[132:133] neg_lo:[0,1] neg_hi:[0,1]
	v_pk_mul_f32 v[78:79], v[54:55], v[26:27] op_sel:[0,1] op_sel_hi:[1,0]
	v_pk_add_f32 v[132:133], v[144:145], v[136:137] op_sel:[0,1] op_sel_hi:[1,0] neg_hi:[0,1]
	v_pk_add_f32 v[136:137], v[144:145], v[136:137] op_sel:[0,1] op_sel_hi:[1,0] neg_lo:[0,1]
	v_pk_add_f32 v[144:145], v[134:135], v[130:131]
	v_pk_add_f32 v[134:135], v[134:135], v[130:131] neg_lo:[0,1] neg_hi:[0,1]
	v_pk_mul_f32 v[82:83], v[34:35], v[26:27] op_sel:[0,1] op_sel_hi:[1,0]
	v_pk_add_f32 v[130:131], v[138:139], v[176:177]
	v_pk_add_f32 v[138:139], v[138:139], v[176:177] neg_lo:[0,1] neg_hi:[0,1]
	v_pk_add_f32 v[176:177], v[182:183], v[178:179]
	v_pk_add_f32 v[182:183], v[182:183], v[178:179] neg_lo:[0,1] neg_hi:[0,1]
	v_pk_mul_f32 v[92:93], v[54:55], v[36:37] op_sel:[0,1] op_sel_hi:[1,0]
	v_pk_add_f32 v[178:179], v[160:161], v[186:187] op_sel:[0,1] op_sel_hi:[1,0] neg_hi:[0,1]
	v_pk_add_f32 v[160:161], v[160:161], v[186:187] op_sel:[0,1] op_sel_hi:[1,0] neg_lo:[0,1]
	v_pk_add_f32 v[186:187], v[168:169], v[180:181]
	v_pk_add_f32 v[180:181], v[168:169], v[180:181] neg_lo:[0,1] neg_hi:[0,1]
	v_pk_mul_f32 v[96:97], v[34:35], v[36:37] op_sel:[0,1] op_sel_hi:[1,0]
	v_pk_add_f32 v[168:169], v[188:189], v[170:171]
	v_pk_add_f32 v[170:171], v[188:189], v[170:171] neg_lo:[0,1] neg_hi:[0,1]
	v_pk_add_f32 v[188:189], v[184:185], v[164:165]
	v_pk_add_f32 v[184:185], v[184:185], v[164:165] neg_lo:[0,1] neg_hi:[0,1]
	v_pk_mul_f32 v[106:107], v[54:55], v[48:49] op_sel:[0,1] op_sel_hi:[1,0]
	v_pk_add_f32 v[164:165], v[128:129], v[172:173] op_sel:[0,1] op_sel_hi:[1,0] neg_hi:[0,1]
	v_pk_add_f32 v[128:129], v[128:129], v[172:173] op_sel:[0,1] op_sel_hi:[1,0] neg_lo:[0,1]
	v_pk_add_f32 v[172:173], v[162:163], v[166:167]
	v_pk_add_f32 v[166:167], v[162:163], v[166:167] neg_lo:[0,1] neg_hi:[0,1]
	v_pk_mul_f32 v[110:111], v[34:35], v[48:49] op_sel:[0,1] op_sel_hi:[1,0]
	v_pk_add_f32 v[162:163], v[174:175], v[194:195]
	v_pk_add_f32 v[174:175], v[174:175], v[194:195] neg_lo:[0,1] neg_hi:[0,1]
	v_pk_add_f32 v[194:195], v[190:191], v[192:193] op_sel:[0,1] op_sel_hi:[1,0] neg_hi:[0,1]
	v_pk_add_f32 v[190:191], v[190:191], v[192:193] op_sel:[0,1] op_sel_hi:[1,0] neg_lo:[0,1]
	v_pk_add_f32 v[192:193], v[148:149], v[156:157]
	v_pk_add_f32 v[148:149], v[148:149], v[156:157] neg_lo:[0,1] neg_hi:[0,1]
	v_pk_add_f32 v[156:157], v[152:153], v[150:151] op_sel:[0,1] op_sel_hi:[1,0] neg_hi:[0,1]
	v_pk_add_f32 v[150:151], v[152:153], v[150:151] op_sel:[0,1] op_sel_hi:[1,0] neg_lo:[0,1]
	v_pk_add_f32 v[152:153], v[140:141], v[158:159]
	v_pk_add_f32 v[140:141], v[140:141], v[158:159] neg_lo:[0,1] neg_hi:[0,1]
	v_pk_add_f32 v[158:159], v[142:143], v[154:155] op_sel:[0,1] op_sel_hi:[1,0] neg_hi:[0,1]
	v_pk_add_f32 v[142:143], v[142:143], v[154:155] op_sel:[0,1] op_sel_hi:[1,0] neg_lo:[0,1]
	v_pk_add_f32 v[154:155], v[132:133], v[144:145]
	v_pk_add_f32 v[132:133], v[132:133], v[144:145] neg_lo:[0,1] neg_hi:[0,1]
	v_pk_add_f32 v[144:145], v[136:137], v[134:135] op_sel:[0,1] op_sel_hi:[1,0] neg_hi:[0,1]
	v_pk_add_f32 v[134:135], v[136:137], v[134:135] op_sel:[0,1] op_sel_hi:[1,0] neg_lo:[0,1]
	v_pk_add_f32 v[136:137], v[130:131], v[176:177]
	v_pk_mul_f32 v[120:121], v[54:55], v[52:53] op_sel:[0,1] op_sel_hi:[1,0]
	v_pk_mul_f32 v[124:125], v[34:35], v[52:53] op_sel:[0,1] op_sel_hi:[1,0]
	v_pk_mul_f32 v[34:35], v[34:35], v[136:137] op_sel:[0,1] op_sel_hi:[1,0]
	v_xor_b32_e32 v72, 0x80000000, v47
	v_mov_b32_e32 v73, v47
	v_pk_fma_f32 v[8:9], v[44:45], v[4:5], v[8:9] op_sel_hi:[0,1,1]
	v_pk_fma_f32 v[14:15], v[30:31], v[4:5], v[14:15] op_sel_hi:[0,1,1]
	v_xor_b32_e32 v22, 0x80000000, v5
	v_pk_fma_f32 v[32:33], v[44:45], v[10:11], v[32:33] op_sel_hi:[0,1,1]
	v_pk_fma_f32 v[40:41], v[30:31], v[10:11], v[40:41] op_sel_hi:[0,1,1]
	v_pk_fma_f32 v[62:63], v[44:45], v[20:21], v[62:63] op_sel_hi:[0,1,1]
	v_pk_fma_f32 v[66:67], v[30:31], v[20:21], v[66:67] op_sel_hi:[0,1,1]
	v_pk_fma_f32 v[78:79], v[44:45], v[26:27], v[78:79] op_sel_hi:[0,1,1]
	v_pk_fma_f32 v[82:83], v[30:31], v[26:27], v[82:83] op_sel_hi:[0,1,1]
	v_pk_fma_f32 v[92:93], v[44:45], v[36:37], v[92:93] op_sel_hi:[0,1,1]
	v_pk_fma_f32 v[96:97], v[30:31], v[36:37], v[96:97] op_sel_hi:[0,1,1]
	v_pk_fma_f32 v[106:107], v[44:45], v[48:49], v[106:107] op_sel_hi:[0,1,1]
	v_pk_fma_f32 v[110:111], v[30:31], v[48:49], v[110:111] op_sel_hi:[0,1,1]
	v_pk_fma_f32 v[120:121], v[44:45], v[52:53], v[120:121] op_sel_hi:[0,1,1]
	v_pk_fma_f32 v[124:125], v[30:31], v[52:53], v[124:125] op_sel_hi:[0,1,1]
	v_mov_b32_e32 v23, v5
	v_pk_add_f32 v[130:131], v[130:131], v[176:177] neg_lo:[0,1] neg_hi:[0,1]
	v_pk_add_f32 v[176:177], v[138:139], v[182:183] op_sel:[0,1] op_sel_hi:[1,0] neg_hi:[0,1]
	v_pk_add_f32 v[138:139], v[138:139], v[182:183] op_sel:[0,1] op_sel_hi:[1,0] neg_lo:[0,1]
	v_pk_add_f32 v[182:183], v[178:179], v[186:187]
	v_pk_add_f32 v[178:179], v[178:179], v[186:187] neg_lo:[0,1] neg_hi:[0,1]
	v_pk_add_f32 v[186:187], v[160:161], v[180:181] op_sel:[0,1] op_sel_hi:[1,0] neg_hi:[0,1]
	v_pk_add_f32 v[160:161], v[160:161], v[180:181] op_sel:[0,1] op_sel_hi:[1,0] neg_lo:[0,1]
	v_pk_add_f32 v[180:181], v[168:169], v[188:189]
	v_pk_fma_f32 v[30:31], v[30:31], v[136:137], v[34:35] op_sel_hi:[0,1,1]
	v_pk_mul_f32 v[34:35], v[54:55], v[152:153] op_sel:[0,1] op_sel_hi:[1,0]
	v_pk_mul_f32 v[2:3], v[72:73], v[4:5] op_sel:[0,1] op_sel_hi:[1,0]
	v_xor_b32_e32 v12, 0x80000000, v9
	v_pk_mul_f32 v[24:25], v[72:73], v[10:11] op_sel:[0,1] op_sel_hi:[1,0]
	v_xor_b32_e32 v38, 0x80000000, v33
	v_xor_b32_e32 v50, 0x80000000, v11
	v_pk_mul_f32 v[56:57], v[72:73], v[20:21] op_sel:[0,1] op_sel_hi:[1,0]
	v_xor_b32_e32 v64, 0x80000000, v63
	v_xor_b32_e32 v70, 0x80000000, v21
	v_pk_mul_f32 v[74:75], v[72:73], v[26:27] op_sel:[0,1] op_sel_hi:[1,0]
	v_xor_b32_e32 v80, 0x80000000, v79
	v_xor_b32_e32 v86, 0x80000000, v27
	v_pk_mul_f32 v[88:89], v[72:73], v[36:37] op_sel:[0,1] op_sel_hi:[1,0]
	v_xor_b32_e32 v94, 0x80000000, v93
	v_xor_b32_e32 v100, 0x80000000, v37
	v_pk_mul_f32 v[102:103], v[72:73], v[48:49] op_sel:[0,1] op_sel_hi:[1,0]
	v_xor_b32_e32 v108, 0x80000000, v107
	v_xor_b32_e32 v114, 0x80000000, v49
	v_pk_mul_f32 v[116:117], v[52:53], v[72:73] op_sel:[1,0] op_sel_hi:[0,1]
	v_xor_b32_e32 v122, 0x80000000, v121
	v_mov_b32_e32 v123, v121
	v_mov_b32_e32 v115, v49
	v_mov_b32_e32 v109, v107
	v_mov_b32_e32 v101, v37
	v_mov_b32_e32 v95, v93
	v_mov_b32_e32 v87, v27
	v_mov_b32_e32 v81, v79
	v_mov_b32_e32 v71, v21
	v_mov_b32_e32 v65, v63
	v_mov_b32_e32 v51, v11
	v_mov_b32_e32 v39, v33
	v_mov_b32_e32 v13, v9
	v_pk_fma_f32 v[34:35], v[44:45], v[152:153], v[34:35] op_sel_hi:[0,1,1]
	v_pk_mul_f32 v[44:45], v[72:73], v[180:181] op_sel:[0,1] op_sel_hi:[1,0]
	v_pk_mul_f32 v[22:23], v[150:151], v[22:23] op_sel:[1,0] op_sel_hi:[0,1]
	v_pk_fma_f32 v[2:3], v[46:47], v[4:5], v[2:3] op_sel_hi:[0,1,1]
	v_pk_fma_f32 v[24:25], v[46:47], v[10:11], v[24:25] op_sel_hi:[0,1,1]
	v_pk_fma_f32 v[56:57], v[46:47], v[20:21], v[56:57] op_sel_hi:[0,1,1]
	v_pk_fma_f32 v[74:75], v[46:47], v[26:27], v[74:75] op_sel_hi:[0,1,1]
	v_xor_b32_e32 v84, 0x80000000, v83
	v_pk_fma_f32 v[88:89], v[46:47], v[36:37], v[88:89] op_sel_hi:[0,1,1]
	v_pk_fma_f32 v[102:103], v[46:47], v[48:49], v[102:103] op_sel_hi:[0,1,1]
	v_pk_fma_f32 v[116:117], v[52:53], v[46:47], v[116:117] op_sel_hi:[1,0,1]
	v_mov_b32_e32 v85, v83
	v_pk_fma_f32 v[44:45], v[46:47], v[180:181], v[44:45] op_sel_hi:[0,1,1]
	v_pk_mul_f32 v[46:47], v[58:59], v[192:193] op_sel:[0,1] op_sel_hi:[1,0]
	v_pk_mul_f32 v[54:55], v[122:123], v[154:155] op_sel:[0,1] op_sel_hi:[1,0]
	v_pk_mul_f32 v[72:73], v[114:115], v[194:195] op_sel:[0,1] op_sel_hi:[1,0]
	v_pk_mul_f32 v[108:109], v[108:109], v[158:159] op_sel:[0,1] op_sel_hi:[1,0]
	v_pk_mul_f32 v[100:101], v[100:101], v[156:157] op_sel:[0,1] op_sel_hi:[1,0]
	v_pk_mul_f32 v[94:95], v[94:95], v[144:145] op_sel:[0,1] op_sel_hi:[1,0]
	v_pk_mul_f32 v[86:87], v[174:175], v[86:87] op_sel:[1,0] op_sel_hi:[0,1]
	v_pk_mul_f32 v[80:81], v[140:141], v[80:81] op_sel:[1,0] op_sel_hi:[0,1]
	v_pk_mul_f32 v[70:71], v[148:149], v[70:71] op_sel:[1,0] op_sel_hi:[0,1]
	v_pk_mul_f32 v[64:65], v[132:133], v[64:65] op_sel:[1,0] op_sel_hi:[0,1]
	v_pk_mul_f32 v[50:51], v[190:191], v[50:51] op_sel:[1,0] op_sel_hi:[0,1]
	v_pk_mul_f32 v[38:39], v[142:143], v[38:39] op_sel:[1,0] op_sel_hi:[0,1]
	v_pk_fma_f32 v[4:5], v[150:151], v[4:5], v[22:23] op_sel_hi:[1,0,1]
	v_pk_mul_f32 v[12:13], v[134:135], v[12:13] op_sel:[1,0] op_sel_hi:[0,1]
	v_xor_b32_e32 v112, 0x80000000, v111
	v_mov_b32_e32 v113, v111
	v_pk_fma_f32 v[46:47], v[52:53], v[192:193], v[46:47] op_sel_hi:[0,1,1]
	v_pk_fma_f32 v[54:55], v[120:121], v[154:155], v[54:55] op_sel_hi:[0,1,1]
	v_pk_fma_f32 v[48:49], v[48:49], v[194:195], v[72:73] op_sel_hi:[0,1,1]
	v_pk_fma_f32 v[106:107], v[106:107], v[158:159], v[108:109] op_sel_hi:[0,1,1]
	v_pk_fma_f32 v[36:37], v[36:37], v[156:157], v[100:101] op_sel_hi:[0,1,1]
	v_pk_fma_f32 v[92:93], v[92:93], v[144:145], v[94:95] op_sel_hi:[0,1,1]
	v_pk_fma_f32 v[26:27], v[174:175], v[26:27], v[86:87] op_sel_hi:[1,0,1]
	v_pk_mul_f32 v[84:85], v[130:131], v[84:85] op_sel:[1,0] op_sel_hi:[0,1]
	v_pk_fma_f32 v[78:79], v[140:141], v[78:79], v[80:81] op_sel_hi:[1,0,1]
	v_pk_fma_f32 v[20:21], v[148:149], v[20:21], v[70:71] op_sel_hi:[1,0,1]
	v_pk_fma_f32 v[62:63], v[132:133], v[62:63], v[64:65] op_sel_hi:[1,0,1]
	v_pk_fma_f32 v[10:11], v[190:191], v[10:11], v[50:51] op_sel_hi:[1,0,1]
	v_pk_fma_f32 v[32:33], v[142:143], v[32:33], v[38:39] op_sel_hi:[1,0,1]
	v_pk_fma_f32 v[8:9], v[134:135], v[8:9], v[12:13] op_sel_hi:[1,0,1]
	ds_write_b64 v18, v[162:163]
	ds_write_b64 v18, v[26:27] offset:4224
	ds_write_b64 v18, v[48:49] offset:8448
	ds_write_b64 v18, v[10:11] offset:12672
	ds_write_b64 v18, v[46:47] offset:16896
	ds_write_b64 v18, v[20:21] offset:21120
	ds_write_b64 v18, v[36:37] offset:25344
	ds_write_b64 v18, v[4:5] offset:29568
	ds_write_b64 v18, v[34:35] offset:33792
	ds_write_b64 v18, v[78:79] offset:38016
	ds_write_b64 v18, v[106:107] offset:42240
	ds_write_b64 v18, v[32:33] offset:46464
	ds_write_b64 v18, v[54:55] offset:50688
	ds_write_b64 v18, v[62:63] offset:54912
	ds_write_b64 v18, v[92:93] offset:59136
	ds_write_b64 v18, v[8:9] offset:63360
	v_add_u32_e32 v4, 0x10800, v18
	v_xor_b32_e32 v42, 0x80000000, v41
	v_mov_b32_e32 v43, v41
	v_pk_mul_f32 v[72:73], v[112:113], v[176:177] op_sel:[0,1] op_sel_hi:[1,0]
	v_pk_fma_f32 v[82:83], v[130:131], v[82:83], v[84:85] op_sel_hi:[1,0,1]
	ds_write_b64 v4, v[30:31]
	v_add_u32_e32 v4, 0x11880, v18
	v_xor_b32_e32 v126, 0x80000000, v125
	v_mov_b32_e32 v127, v125
	v_pk_fma_f32 v[72:73], v[110:111], v[176:177], v[72:73] op_sel_hi:[0,1,1]
	v_pk_mul_f32 v[42:43], v[138:139], v[42:43] op_sel:[1,0] op_sel_hi:[0,1]
	ds_write_b64 v4, v[82:83]
	v_add_u32_e32 v4, 0x12900, v18
	v_xor_b32_e32 v68, 0x80000000, v67
	v_mov_b32_e32 v69, v67
	v_pk_mul_f32 v[52:53], v[126:127], v[182:183] op_sel:[0,1] op_sel_hi:[1,0]
	v_pk_fma_f32 v[40:41], v[138:139], v[40:41], v[42:43] op_sel_hi:[1,0,1]
	ds_write_b64 v4, v[72:73]
	v_add_u32_e32 v4, 0x13980, v18
	v_xor_b32_e32 v98, 0x80000000, v97
	v_mov_b32_e32 v99, v97
	v_pk_fma_f32 v[52:53], v[124:125], v[182:183], v[52:53] op_sel_hi:[0,1,1]
	v_pk_mul_f32 v[68:69], v[178:179], v[68:69] op_sel:[1,0] op_sel_hi:[0,1]
	ds_write_b64 v4, v[40:41]
	v_add_u32_e32 v4, 0x14a00, v18
	v_xor_b32_e32 v16, 0x80000000, v15
	v_mov_b32_e32 v17, v15
	v_pk_mul_f32 v[98:99], v[98:99], v[186:187] op_sel:[0,1] op_sel_hi:[1,0]
	v_pk_fma_f32 v[66:67], v[178:179], v[66:67], v[68:69] op_sel_hi:[1,0,1]
	ds_write_b64 v4, v[52:53]
	v_add_u32_e32 v4, 0x15a80, v18
	v_pk_fma_f32 v[96:97], v[96:97], v[186:187], v[98:99] op_sel_hi:[0,1,1]
	v_pk_mul_f32 v[16:17], v[160:161], v[16:17] op_sel:[1,0] op_sel_hi:[0,1]
	ds_write_b64 v4, v[66:67]
	v_add_u32_e32 v4, 0x16b00, v18
	v_xor_b32_e32 v76, 0x80000000, v75
	v_mov_b32_e32 v77, v75
	v_pk_add_f32 v[168:169], v[168:169], v[188:189] neg_lo:[0,1] neg_hi:[0,1]
	v_pk_fma_f32 v[14:15], v[160:161], v[14:15], v[16:17] op_sel_hi:[1,0,1]
	ds_write_b64 v4, v[96:97]
	v_add_u32_e32 v4, 0x17b80, v18
	v_xor_b32_e32 v104, 0x80000000, v103
	v_mov_b32_e32 v105, v103
	v_pk_add_f32 v[188:189], v[170:171], v[184:185] op_sel:[0,1] op_sel_hi:[1,0] neg_hi:[0,1]
	v_pk_mul_f32 v[76:77], v[168:169], v[76:77] op_sel:[1,0] op_sel_hi:[0,1]
	ds_write_b64 v4, v[14:15]
	v_add_u32_e32 v4, 0x18c00, v18
	v_xor_b32_e32 v28, 0x80000000, v25
	v_mov_b32_e32 v29, v25
	v_pk_add_f32 v[170:171], v[170:171], v[184:185] op_sel:[0,1] op_sel_hi:[1,0] neg_lo:[0,1]
	v_pk_mul_f32 v[104:105], v[104:105], v[188:189] op_sel:[0,1] op_sel_hi:[1,0]
	v_pk_fma_f32 v[74:75], v[168:169], v[74:75], v[76:77] op_sel_hi:[1,0,1]
	ds_write_b64 v4, v[44:45]
	v_add_u32_e32 v4, 0x19c80, v18
	v_xor_b32_e32 v118, 0x80000000, v117
	v_mov_b32_e32 v119, v117
	v_pk_add_f32 v[184:185], v[164:165], v[172:173]
	v_pk_fma_f32 v[102:103], v[102:103], v[188:189], v[104:105] op_sel_hi:[0,1,1]
	v_pk_mul_f32 v[28:29], v[170:171], v[28:29] op_sel:[1,0] op_sel_hi:[0,1]
	ds_write_b64 v4, v[74:75]
	v_add_u32_e32 v4, 0x1ad00, v18
	v_xor_b32_e32 v60, 0x80000000, v57
	v_mov_b32_e32 v61, v57
	v_pk_add_f32 v[164:165], v[164:165], v[172:173] neg_lo:[0,1] neg_hi:[0,1]
	v_pk_mul_f32 v[58:59], v[118:119], v[184:185] op_sel:[0,1] op_sel_hi:[1,0]
	v_pk_fma_f32 v[24:25], v[170:171], v[24:25], v[28:29] op_sel_hi:[1,0,1]
	ds_write_b64 v4, v[102:103]
	v_add_u32_e32 v4, 0x1bd80, v18
	v_xor_b32_e32 v90, 0x80000000, v89
	v_mov_b32_e32 v91, v89
	v_pk_add_f32 v[172:173], v[128:129], v[166:167] op_sel:[0,1] op_sel_hi:[1,0] neg_hi:[0,1]
	v_pk_fma_f32 v[58:59], v[116:117], v[184:185], v[58:59] op_sel_hi:[0,1,1]
	v_pk_mul_f32 v[60:61], v[164:165], v[60:61] op_sel:[1,0] op_sel_hi:[0,1]
	ds_write_b64 v4, v[24:25]
	v_add_u32_e32 v4, 0x1ce00, v18
	v_xor_b32_e32 v6, 0x80000000, v3
	v_mov_b32_e32 v7, v3
	v_pk_add_f32 v[128:129], v[128:129], v[166:167] op_sel:[0,1] op_sel_hi:[1,0] neg_lo:[0,1]
	v_pk_mul_f32 v[90:91], v[90:91], v[172:173] op_sel:[0,1] op_sel_hi:[1,0]
	v_pk_fma_f32 v[56:57], v[164:165], v[56:57], v[60:61] op_sel_hi:[1,0,1]
	ds_write_b64 v4, v[58:59]
	v_add_u32_e32 v4, 0x1de80, v18
	v_pk_fma_f32 v[88:89], v[88:89], v[172:173], v[90:91] op_sel_hi:[0,1,1]
	v_pk_mul_f32 v[6:7], v[128:129], v[6:7] op_sel:[1,0] op_sel_hi:[0,1]
	ds_write_b64 v4, v[56:57]
	v_add_u32_e32 v4, 0x1ef00, v18
	v_pk_fma_f32 v[2:3], v[128:129], v[2:3], v[6:7] op_sel_hi:[1,0,1]
	ds_write_b64 v4, v[88:89]
	v_add_u32_e32 v4, 0x1ff80, v18
	ds_write_b64 v4, v[2:3]
	v_mov_b32_e32 v2, v210
	s_waitcnt lgkmcnt(0)
	s_barrier
	s_ashr_i32 s77, s76, 31
	v_and_b32_e32 v3, 15, v2
	v_lshlrev_b32_e32 v2, 5, v2
	v_and_b32_e32 v4, 0xfffffe00, v2
	v_lshl_add_u32 v5, v4, 3, 0
	v_lshlrev_b32_e32 v6, 3, v3
	v_ashrrev_i32_e32 v7, 2, v4
	v_add3_u32 v18, v5, v6, v7
	v_add_u32_e32 v196, 0x800, v18
	ds_read2_b64 v[128:131], v18 offset1:16
	ds_read2_b64 v[132:135], v18 offset0:33 offset1:49
	ds_read2_b64 v[136:139], v18 offset0:66 offset1:82
	ds_read2_b64 v[140:143], v18 offset0:99 offset1:115
	ds_read2_b64 v[148:151], v18 offset0:132 offset1:148
	ds_read2_b64 v[152:155], v18 offset0:165 offset1:181
	ds_read2_b64 v[156:159], v18 offset0:198 offset1:214
	ds_read2_b64 v[160:163], v18 offset0:231 offset1:247
	ds_read2_b64 v[164:167], v196 offset0:8 offset1:24
	ds_read2_b64 v[168:171], v196 offset0:41 offset1:57
	ds_read2_b64 v[172:175], v196 offset0:74 offset1:90
	ds_read2_b64 v[176:179], v196 offset0:107 offset1:123
	ds_read2_b64 v[180:183], v196 offset0:140 offset1:156
	ds_read2_b64 v[184:187], v196 offset0:173 offset1:189
	ds_read2_b64 v[188:191], v196 offset0:206 offset1:222
	ds_read2_b64 v[192:195], v196 offset0:239 offset1:255
	s_waitcnt lgkmcnt(7)
	v_pk_add_f32 v[144:145], v[128:129], v[164:165]
	v_pk_add_f32 v[128:129], v[128:129], v[164:165] neg_lo:[0,1] neg_hi:[0,1]
	v_pk_add_f32 v[164:165], v[130:131], v[166:167]
	v_pk_add_f32 v[130:131], v[130:131], v[166:167] neg_lo:[0,1] neg_hi:[0,1]
	v_cvt_f32_ubyte0_e32 v2, v3
	v_pk_mul_f32 v[166:167], v[130:131], s[10:11]
	v_mul_f32_e32 v3, 0x3b000000, v2
	v_pk_fma_f32 v[130:131], v[130:131], s[8:9], v[166:167] op_sel:[0,0,1] op_sel_hi:[1,0,0]
	s_waitcnt lgkmcnt(6)
	v_pk_add_f32 v[166:167], v[132:133], v[168:169]
	v_pk_add_f32 v[132:133], v[132:133], v[168:169] neg_lo:[0,1] neg_hi:[0,1]
	v_sin_f32_e32 v2, v3
	v_pk_mul_f32 v[168:169], v[132:133], s[18:19]
	v_cos_f32_e32 v4, v3
	v_pk_fma_f32 v[132:133], v[132:133], s[16:17], v[168:169] op_sel:[0,0,1] op_sel_hi:[1,0,0]
	v_pk_add_f32 v[168:169], v[134:135], v[170:171]
	v_pk_add_f32 v[134:135], v[134:135], v[170:171] neg_lo:[0,1] neg_hi:[0,1]
	v_xor_b32_e32 v5, 0x80000000, v2
	v_pk_mul_f32 v[170:171], v[134:135], s[26:27]
	v_mov_b32_e32 v3, v5
	v_pk_fma_f32 v[134:135], v[134:135], s[24:25], v[170:171] op_sel:[0,0,1] op_sel_hi:[1,0,0]
	s_waitcnt lgkmcnt(5)
	v_pk_add_f32 v[170:171], v[136:137], v[172:173]
	v_pk_add_f32 v[136:137], v[136:137], v[172:173] neg_lo:[0,1] neg_hi:[0,1]
	v_pk_mul_f32 v[6:7], v[4:5], v[2:3] op_sel:[1,0] op_sel_hi:[0,1]
	v_pk_mul_f32 v[172:173], v[136:137], s[36:37]
	v_pk_fma_f32 v[6:7], v[4:5], v[4:5], v[6:7] op_sel_hi:[1,0,1]
	v_pk_fma_f32 v[136:137], v[136:137], s[78:79], v[172:173] op_sel:[0,0,1] op_sel_hi:[1,0,0]
	v_pk_add_f32 v[172:173], v[138:139], v[174:175]
	v_pk_add_f32 v[138:139], v[138:139], v[174:175] neg_lo:[0,1] neg_hi:[0,1]
	v_xor_b32_e32 v12, 0x80000000, v7
	v_pk_mul_f32 v[174:175], v[138:139], s[38:39]
	v_mov_b32_e32 v13, v7
	v_pk_fma_f32 v[138:139], v[138:139], s[0:1], v[174:175] op_sel:[0,0,1] op_sel_hi:[1,0,0]
	s_waitcnt lgkmcnt(4)
	v_pk_add_f32 v[174:175], v[140:141], v[176:177]
	v_pk_add_f32 v[140:141], v[140:141], v[176:177] neg_lo:[0,1] neg_hi:[0,1]
	v_pk_mul_f32 v[10:11], v[6:7], v[12:13] op_sel:[1,0] op_sel_hi:[0,1]
	v_pk_mul_f32 v[176:177], v[140:141], s[40:41]
	v_pk_fma_f32 v[10:11], v[6:7], v[6:7], v[10:11] op_sel_hi:[1,0,1]
	v_pk_fma_f32 v[140:141], v[140:141], s[80:81], v[176:177] op_sel:[0,0,1] op_sel_hi:[1,0,0]
	v_pk_add_f32 v[176:177], v[142:143], v[178:179]
	v_pk_add_f32 v[142:143], v[142:143], v[178:179] neg_lo:[0,1] neg_hi:[0,1]
	v_xor_b32_e32 v14, 0x80000000, v11
	v_pk_mul_f32 v[178:179], v[142:143], s[42:43]
	v_mov_b32_e32 v15, v11
	v_pk_fma_f32 v[142:143], v[142:143], s[74:75], v[178:179] op_sel:[0,0,1] op_sel_hi:[1,0,0]
	s_waitcnt lgkmcnt(3)
	v_pk_add_f32 v[178:179], v[148:149], v[180:181]
	v_pk_add_f32 v[180:181], v[148:149], v[180:181] neg_lo:[0,1] neg_hi:[0,1]
	v_pk_mul_f32 v[28:29], v[10:11], v[14:15] op_sel:[1,0] op_sel_hi:[0,1]
	v_pk_add_f32 v[148:149], v[150:151], v[182:183]
	v_pk_add_f32 v[150:151], v[150:151], v[182:183] neg_lo:[0,1] neg_hi:[0,1]
	v_pk_fma_f32 v[28:29], v[10:11], v[10:11], v[28:29] op_sel_hi:[1,0,1]
	v_pk_mul_f32 v[182:183], v[150:151], s[42:43]
	v_pk_mul_f32 v[44:45], v[14:15], v[28:29] op_sel:[0,1] op_sel_hi:[1,0]
	v_pk_fma_f32 v[150:151], v[150:151], s[74:75], v[182:183] op_sel:[0,0,1] op_sel_hi:[1,0,0] neg_lo:[1,0,0] neg_hi:[1,0,0]
	s_waitcnt lgkmcnt(2)
	v_pk_add_f32 v[182:183], v[152:153], v[184:185]
	v_pk_add_f32 v[152:153], v[152:153], v[184:185] neg_lo:[0,1] neg_hi:[0,1]
	v_pk_fma_f32 v[44:45], v[10:11], v[28:29], v[44:45] op_sel_hi:[0,1,1]
	v_pk_mul_f32 v[184:185], v[152:153], s[40:41]
	v_pk_mul_f32 v[60:61], v[14:15], v[44:45] op_sel:[0,1] op_sel_hi:[1,0]
	v_pk_fma_f32 v[152:153], v[152:153], s[80:81], v[184:185] op_sel:[0,0,1] op_sel_hi:[1,0,0] neg_lo:[1,0,0] neg_hi:[1,0,0]
	v_pk_add_f32 v[184:185], v[154:155], v[186:187]
	v_pk_add_f32 v[154:155], v[154:155], v[186:187] neg_lo:[0,1] neg_hi:[0,1]
	v_pk_fma_f32 v[60:61], v[10:11], v[44:45], v[60:61] op_sel_hi:[0,1,1]
	v_pk_mul_f32 v[186:187], v[154:155], s[38:39]
	v_pk_mul_f32 v[76:77], v[14:15], v[60:61] op_sel:[0,1] op_sel_hi:[1,0]
	v_pk_fma_f32 v[154:155], v[154:155], s[0:1], v[186:187] op_sel:[0,0,1] op_sel_hi:[1,0,0] neg_lo:[1,0,0] neg_hi:[1,0,0]
	s_waitcnt lgkmcnt(1)
	v_pk_add_f32 v[186:187], v[156:157], v[188:189]
	v_pk_add_f32 v[156:157], v[156:157], v[188:189] neg_lo:[0,1] neg_hi:[0,1]
	v_pk_fma_f32 v[76:77], v[10:11], v[60:61], v[76:77] op_sel_hi:[0,1,1]
	v_pk_mul_f32 v[188:189], v[156:157], s[36:37]
	v_pk_mul_f32 v[92:93], v[14:15], v[76:77] op_sel:[0,1] op_sel_hi:[1,0]
	v_pk_fma_f32 v[156:157], v[156:157], s[78:79], v[188:189] op_sel:[0,0,1] op_sel_hi:[1,0,0] neg_lo:[1,0,0] neg_hi:[1,0,0]
	v_pk_add_f32 v[188:189], v[158:159], v[190:191]
	v_pk_add_f32 v[158:159], v[158:159], v[190:191] neg_lo:[0,1] neg_hi:[0,1]
	v_pk_fma_f32 v[92:93], v[10:11], v[76:77], v[92:93] op_sel_hi:[0,1,1]
	v_pk_mul_f32 v[190:191], v[158:159], s[26:27]
	v_pk_mul_f32 v[108:109], v[14:15], v[92:93] op_sel:[0,1] op_sel_hi:[1,0]
	v_pk_fma_f32 v[158:159], v[158:159], s[24:25], v[190:191] op_sel:[0,0,1] op_sel_hi:[1,0,0] neg_lo:[1,0,0] neg_hi:[1,0,0]
	s_waitcnt lgkmcnt(0)
	v_pk_add_f32 v[190:191], v[160:161], v[192:193]
	v_pk_add_f32 v[160:161], v[160:161], v[192:193] neg_lo:[0,1] neg_hi:[0,1]
	v_pk_mul_f32 v[8:9], v[2:3], v[6:7] op_sel:[0,1] op_sel_hi:[1,0]
	v_pk_mul_f32 v[192:193], v[160:161], s[18:19]
	v_pk_fma_f32 v[108:109], v[10:11], v[92:93], v[108:109] op_sel_hi:[0,1,1]
	v_pk_fma_f32 v[160:161], v[160:161], s[16:17], v[192:193] op_sel:[0,0,1] op_sel_hi:[1,0,0] neg_lo:[1,0,0] neg_hi:[1,0,0]
	v_pk_add_f32 v[192:193], v[162:163], v[194:195]
	v_pk_add_f32 v[162:163], v[162:163], v[194:195] neg_lo:[0,1] neg_hi:[0,1]
	v_pk_fma_f32 v[8:9], v[4:5], v[6:7], v[8:9] op_sel_hi:[0,1,1]
	v_pk_mul_f32 v[194:195], v[162:163], s[10:11]
	v_pk_mul_f32 v[16:17], v[2:3], v[10:11] op_sel:[0,1] op_sel_hi:[1,0]
	v_pk_fma_f32 v[162:163], v[162:163], s[8:9], v[194:195] op_sel:[0,0,1] op_sel_hi:[1,0,0] neg_lo:[1,0,0] neg_hi:[1,0,0]
	v_pk_add_f32 v[194:195], v[144:145], v[178:179]
	v_pk_add_f32 v[144:145], v[144:145], v[178:179] neg_lo:[0,1] neg_hi:[0,1]
	v_pk_add_f32 v[178:179], v[164:165], v[148:149]
	v_pk_add_f32 v[148:149], v[164:165], v[148:149] neg_lo:[0,1] neg_hi:[0,1]
	v_pk_mul_f32 v[32:33], v[2:3], v[28:29] op_sel:[0,1] op_sel_hi:[1,0]
	v_pk_mul_f32 v[164:165], v[148:149], s[18:19]
	v_pk_mul_f32 v[48:49], v[2:3], v[44:45] op_sel:[0,1] op_sel_hi:[1,0]
	v_pk_fma_f32 v[148:149], v[148:149], s[16:17], v[164:165] op_sel:[0,0,1] op_sel_hi:[1,0,0]
	v_pk_add_f32 v[164:165], v[166:167], v[182:183]
	v_pk_add_f32 v[166:167], v[166:167], v[182:183] neg_lo:[0,1] neg_hi:[0,1]
	v_pk_mul_f32 v[64:65], v[2:3], v[60:61] op_sel:[0,1] op_sel_hi:[1,0]
	v_pk_mul_f32 v[182:183], v[166:167], s[36:37]
	v_pk_mul_f32 v[80:81], v[2:3], v[76:77] op_sel:[0,1] op_sel_hi:[1,0]
	v_pk_fma_f32 v[166:167], v[166:167], s[78:79], v[182:183] op_sel:[0,0,1] op_sel_hi:[1,0,0]
	v_pk_add_f32 v[182:183], v[168:169], v[184:185]
	v_pk_add_f32 v[168:169], v[168:169], v[184:185] neg_lo:[0,1] neg_hi:[0,1]
	v_pk_mul_f32 v[96:97], v[2:3], v[92:93] op_sel:[0,1] op_sel_hi:[1,0]
	v_pk_mul_f32 v[184:185], v[168:169], s[40:41]
	v_pk_mul_f32 v[112:113], v[2:3], v[108:109] op_sel:[0,1] op_sel_hi:[1,0]
	v_pk_fma_f32 v[168:169], v[168:169], s[80:81], v[184:185] op_sel:[0,0,1] op_sel_hi:[1,0,0]
	v_pk_add_f32 v[184:185], v[170:171], v[186:187]
	v_pk_add_f32 v[186:187], v[170:171], v[186:187] neg_lo:[0,1] neg_hi:[0,1]
	v_xor_b32_e32 v22, 0x80000000, v9
	v_pk_add_f32 v[170:171], v[172:173], v[188:189]
	v_pk_add_f32 v[172:173], v[172:173], v[188:189] neg_lo:[0,1] neg_hi:[0,1]
	v_mov_b32_e32 v23, v9
	v_pk_mul_f32 v[188:189], v[172:173], s[40:41]
	v_pk_fma_f32 v[16:17], v[4:5], v[10:11], v[16:17] op_sel_hi:[0,1,1]
	v_pk_fma_f32 v[172:173], v[172:173], s[80:81], v[188:189] op_sel:[0,0,1] op_sel_hi:[1,0,0] neg_lo:[1,0,0] neg_hi:[1,0,0]
	v_pk_add_f32 v[188:189], v[174:175], v[190:191]
	v_pk_add_f32 v[174:175], v[174:175], v[190:191] neg_lo:[0,1] neg_hi:[0,1]
	v_pk_mul_f32 v[20:21], v[12:13], v[10:11] op_sel:[0,1] op_sel_hi:[1,0]
	v_pk_mul_f32 v[190:191], v[174:175], s[36:37]
	v_pk_fma_f32 v[32:33], v[4:5], v[28:29], v[32:33] op_sel_hi:[0,1,1]
	v_pk_fma_f32 v[174:175], v[174:175], s[78:79], v[190:191] op_sel:[0,0,1] op_sel_hi:[1,0,0] neg_lo:[1,0,0] neg_hi:[1,0,0]
	v_pk_add_f32 v[190:191], v[176:177], v[192:193]
	v_pk_add_f32 v[176:177], v[176:177], v[192:193] neg_lo:[0,1] neg_hi:[0,1]
	v_pk_mul_f32 v[36:37], v[12:13], v[28:29] op_sel:[0,1] op_sel_hi:[1,0]
	v_pk_mul_f32 v[192:193], v[176:177], s[18:19]
	v_pk_fma_f32 v[48:49], v[4:5], v[44:45], v[48:49] op_sel_hi:[0,1,1]
	v_pk_fma_f32 v[176:177], v[176:177], s[16:17], v[192:193] op_sel:[0,0,1] op_sel_hi:[1,0,0] neg_lo:[1,0,0] neg_hi:[1,0,0]
	v_pk_add_f32 v[192:193], v[128:129], v[180:181] op_sel:[0,1] op_sel_hi:[1,0] neg_hi:[0,1]
	v_pk_add_f32 v[128:129], v[128:129], v[180:181] op_sel:[0,1] op_sel_hi:[1,0] neg_lo:[0,1]
	v_pk_add_f32 v[180:181], v[130:131], v[150:151]
	v_pk_add_f32 v[130:131], v[130:131], v[150:151] neg_lo:[0,1] neg_hi:[0,1]
	v_pk_mul_f32 v[52:53], v[12:13], v[44:45] op_sel:[0,1] op_sel_hi:[1,0]
	v_pk_mul_f32 v[150:151], v[130:131], s[18:19]
	v_pk_fma_f32 v[64:65], v[4:5], v[60:61], v[64:65] op_sel_hi:[0,1,1]
	v_pk_fma_f32 v[130:131], v[130:131], s[16:17], v[150:151] op_sel:[0,0,1] op_sel_hi:[1,0,0]
	v_pk_add_f32 v[150:151], v[132:133], v[152:153]
	v_pk_add_f32 v[132:133], v[132:133], v[152:153] neg_lo:[0,1] neg_hi:[0,1]
	v_pk_mul_f32 v[68:69], v[12:13], v[60:61] op_sel:[0,1] op_sel_hi:[1,0]
	v_pk_mul_f32 v[152:153], v[132:133], s[36:37]
	v_pk_fma_f32 v[80:81], v[4:5], v[76:77], v[80:81] op_sel_hi:[0,1,1]
	v_pk_fma_f32 v[132:133], v[132:133], s[78:79], v[152:153] op_sel:[0,0,1] op_sel_hi:[1,0,0]
	v_pk_add_f32 v[152:153], v[134:135], v[154:155]
	v_pk_add_f32 v[134:135], v[134:135], v[154:155] neg_lo:[0,1] neg_hi:[0,1]
	v_pk_mul_f32 v[84:85], v[12:13], v[76:77] op_sel:[0,1] op_sel_hi:[1,0]
	v_pk_mul_f32 v[154:155], v[134:135], s[40:41]
	v_pk_fma_f32 v[96:97], v[4:5], v[92:93], v[96:97] op_sel_hi:[0,1,1]
	v_pk_fma_f32 v[134:135], v[134:135], s[80:81], v[154:155] op_sel:[0,0,1] op_sel_hi:[1,0,0]
	v_pk_add_f32 v[154:155], v[136:137], v[156:157]
	v_pk_add_f32 v[156:157], v[136:137], v[156:157] neg_lo:[0,1] neg_hi:[0,1]
	v_pk_mul_f32 v[100:101], v[12:13], v[92:93] op_sel:[0,1] op_sel_hi:[1,0]
	v_pk_add_f32 v[136:137], v[138:139], v[158:159]
	v_pk_add_f32 v[138:139], v[138:139], v[158:159] neg_lo:[0,1] neg_hi:[0,1]
	v_pk_fma_f32 v[112:113], v[4:5], v[108:109], v[112:113] op_sel_hi:[0,1,1]
	v_pk_mul_f32 v[158:159], v[138:139], s[40:41]
	v_pk_mul_f32 v[116:117], v[12:13], v[108:109] op_sel:[0,1] op_sel_hi:[1,0]
	v_pk_fma_f32 v[138:139], v[138:139], s[80:81], v[158:159] op_sel:[0,0,1] op_sel_hi:[1,0,0] neg_lo:[1,0,0] neg_hi:[1,0,0]
	v_pk_add_f32 v[158:159], v[140:141], v[160:161]
	v_pk_add_f32 v[140:141], v[140:141], v[160:161] neg_lo:[0,1] neg_hi:[0,1]
	v_pk_fma_f32 v[20:21], v[6:7], v[10:11], v[20:21] op_sel_hi:[0,1,1]
	v_pk_mul_f32 v[160:161], v[140:141], s[36:37]
	v_pk_mul_f32 v[24:25], v[10:11], v[22:23] op_sel:[1,0] op_sel_hi:[0,1]
	v_pk_fma_f32 v[140:141], v[140:141], s[78:79], v[160:161] op_sel:[0,0,1] op_sel_hi:[1,0,0] neg_lo:[1,0,0] neg_hi:[1,0,0]
	v_pk_add_f32 v[160:161], v[142:143], v[162:163]
	v_pk_add_f32 v[142:143], v[142:143], v[162:163] neg_lo:[0,1] neg_hi:[0,1]
	v_pk_fma_f32 v[36:37], v[6:7], v[28:29], v[36:37] op_sel_hi:[0,1,1]
	v_pk_mul_f32 v[162:163], v[142:143], s[18:19]
	v_pk_mul_f32 v[40:41], v[22:23], v[28:29] op_sel:[0,1] op_sel_hi:[1,0]
	v_pk_fma_f32 v[142:143], v[142:143], s[16:17], v[162:163] op_sel:[0,0,1] op_sel_hi:[1,0,0] neg_lo:[1,0,0] neg_hi:[1,0,0]
	v_pk_add_f32 v[162:163], v[194:195], v[184:185]
	v_pk_add_f32 v[184:185], v[194:195], v[184:185] neg_lo:[0,1] neg_hi:[0,1]
	v_pk_add_f32 v[194:195], v[178:179], v[170:171]
	v_pk_add_f32 v[170:171], v[178:179], v[170:171] neg_lo:[0,1] neg_hi:[0,1]
	v_pk_fma_f32 v[52:53], v[6:7], v[44:45], v[52:53] op_sel_hi:[0,1,1]
	v_pk_mul_f32 v[178:179], v[170:171], s[36:37]
	v_pk_mul_f32 v[56:57], v[22:23], v[44:45] op_sel:[0,1] op_sel_hi:[1,0]
	v_pk_fma_f32 v[170:171], v[170:171], s[78:79], v[178:179] op_sel:[0,0,1] op_sel_hi:[1,0,0]
	v_pk_add_f32 v[178:179], v[164:165], v[188:189]
	v_pk_add_f32 v[188:189], v[164:165], v[188:189] neg_lo:[0,1] neg_hi:[0,1]
	v_pk_fma_f32 v[68:69], v[6:7], v[60:61], v[68:69] op_sel_hi:[0,1,1]
	v_pk_add_f32 v[164:165], v[182:183], v[190:191]
	v_pk_add_f32 v[182:183], v[182:183], v[190:191] neg_lo:[0,1] neg_hi:[0,1]
	v_pk_mul_f32 v[72:73], v[22:23], v[60:61] op_sel:[0,1] op_sel_hi:[1,0]
	v_pk_mul_f32 v[190:191], v[182:183], s[36:37]
	v_pk_fma_f32 v[84:85], v[6:7], v[76:77], v[84:85] op_sel_hi:[0,1,1]
	v_pk_fma_f32 v[182:183], v[182:183], s[78:79], v[190:191] op_sel:[0,0,1] op_sel_hi:[1,0,0] neg_lo:[1,0,0] neg_hi:[1,0,0]
	v_pk_add_f32 v[190:191], v[144:145], v[186:187] op_sel:[0,1] op_sel_hi:[1,0] neg_hi:[0,1]
	v_pk_add_f32 v[144:145], v[144:145], v[186:187] op_sel:[0,1] op_sel_hi:[1,0] neg_lo:[0,1]
	v_pk_add_f32 v[186:187], v[148:149], v[172:173]
	v_pk_add_f32 v[148:149], v[148:149], v[172:173] neg_lo:[0,1] neg_hi:[0,1]
	v_pk_mul_f32 v[88:89], v[22:23], v[76:77] op_sel:[0,1] op_sel_hi:[1,0]
	v_pk_mul_f32 v[172:173], v[148:149], s[36:37]
	v_pk_fma_f32 v[100:101], v[6:7], v[92:93], v[100:101] op_sel_hi:[0,1,1]
	v_pk_fma_f32 v[148:149], v[148:149], s[78:79], v[172:173] op_sel:[0,0,1] op_sel_hi:[1,0,0]
	v_pk_add_f32 v[172:173], v[166:167], v[174:175]
	v_pk_add_f32 v[174:175], v[166:167], v[174:175] neg_lo:[0,1] neg_hi:[0,1]
	v_pk_mul_f32 v[104:105], v[22:23], v[92:93] op_sel:[0,1] op_sel_hi:[1,0]
	v_pk_add_f32 v[166:167], v[168:169], v[176:177]
	v_pk_add_f32 v[168:169], v[168:169], v[176:177] neg_lo:[0,1] neg_hi:[0,1]
	v_pk_fma_f32 v[116:117], v[6:7], v[108:109], v[116:117] op_sel_hi:[0,1,1]
	v_pk_mul_f32 v[176:177], v[168:169], s[36:37]
	v_pk_mul_f32 v[120:121], v[22:23], v[108:109] op_sel:[0,1] op_sel_hi:[1,0]
	v_pk_fma_f32 v[168:169], v[168:169], s[78:79], v[176:177] op_sel:[0,0,1] op_sel_hi:[1,0,0] neg_lo:[1,0,0] neg_hi:[1,0,0]
	v_pk_add_f32 v[176:177], v[192:193], v[154:155]
	v_pk_add_f32 v[154:155], v[192:193], v[154:155] neg_lo:[0,1] neg_hi:[0,1]
	v_pk_add_f32 v[192:193], v[180:181], v[136:137]
	v_pk_add_f32 v[136:137], v[180:181], v[136:137] neg_lo:[0,1] neg_hi:[0,1]
	v_xor_b32_e32 v26, 0x80000000, v17
	v_pk_mul_f32 v[180:181], v[136:137], s[36:37]
	v_xor_b32_e32 v30, 0x80000000, v21
	v_pk_fma_f32 v[136:137], v[136:137], s[78:79], v[180:181] op_sel:[0,0,1] op_sel_hi:[1,0,0]
	v_pk_add_f32 v[180:181], v[150:151], v[158:159]
	v_pk_add_f32 v[158:159], v[150:151], v[158:159] neg_lo:[0,1] neg_hi:[0,1]
	v_pk_fma_f32 v[24:25], v[10:11], v[8:9], v[24:25] op_sel_hi:[1,0,1]
	v_pk_add_f32 v[150:151], v[152:153], v[160:161]
	v_pk_add_f32 v[152:153], v[152:153], v[160:161] neg_lo:[0,1] neg_hi:[0,1]
	v_pk_fma_f32 v[40:41], v[8:9], v[28:29], v[40:41] op_sel_hi:[0,1,1]
	v_pk_mul_f32 v[160:161], v[152:153], s[36:37]
	v_pk_fma_f32 v[56:57], v[8:9], v[44:45], v[56:57] op_sel_hi:[0,1,1]
	v_pk_fma_f32 v[152:153], v[152:153], s[78:79], v[160:161] op_sel:[0,0,1] op_sel_hi:[1,0,0] neg_lo:[1,0,0] neg_hi:[1,0,0]
	v_pk_add_f32 v[160:161], v[128:129], v[156:157] op_sel:[0,1] op_sel_hi:[1,0] neg_hi:[0,1]
	v_pk_add_f32 v[128:129], v[128:129], v[156:157] op_sel:[0,1] op_sel_hi:[1,0] neg_lo:[0,1]
	v_pk_add_f32 v[156:157], v[130:131], v[138:139]
	v_pk_add_f32 v[130:131], v[130:131], v[138:139] neg_lo:[0,1] neg_hi:[0,1]
	v_pk_fma_f32 v[72:73], v[8:9], v[60:61], v[72:73] op_sel_hi:[0,1,1]
	v_pk_mul_f32 v[138:139], v[130:131], s[36:37]
	v_pk_fma_f32 v[88:89], v[8:9], v[76:77], v[88:89] op_sel_hi:[0,1,1]
	v_pk_fma_f32 v[130:131], v[130:131], s[78:79], v[138:139] op_sel:[0,0,1] op_sel_hi:[1,0,0]
	v_pk_add_f32 v[138:139], v[132:133], v[140:141]
	v_pk_add_f32 v[140:141], v[132:133], v[140:141] neg_lo:[0,1] neg_hi:[0,1]
	v_pk_fma_f32 v[104:105], v[8:9], v[92:93], v[104:105] op_sel_hi:[0,1,1]
	v_pk_add_f32 v[132:133], v[134:135], v[142:143]
	v_pk_add_f32 v[134:135], v[134:135], v[142:143] neg_lo:[0,1] neg_hi:[0,1]
	v_pk_fma_f32 v[120:121], v[8:9], v[108:109], v[120:121] op_sel_hi:[0,1,1]
	v_pk_mul_f32 v[142:143], v[134:135], s[36:37]
	v_mov_b32_e32 v27, v17
	v_pk_fma_f32 v[134:135], v[134:135], s[78:79], v[142:143] op_sel:[0,0,1] op_sel_hi:[1,0,0] neg_lo:[1,0,0] neg_hi:[1,0,0]
	v_pk_add_f32 v[142:143], v[162:163], v[178:179]
	v_pk_add_f32 v[162:163], v[162:163], v[178:179] neg_lo:[0,1] neg_hi:[0,1]
	v_pk_add_f32 v[178:179], v[194:195], v[164:165]
	v_pk_add_f32 v[194:195], v[194:195], v[164:165] neg_lo:[0,1] neg_hi:[0,1]
	v_mov_b32_e32 v31, v21
	v_pk_add_f32 v[164:165], v[184:185], v[188:189] op_sel:[0,1] op_sel_hi:[1,0] neg_hi:[0,1]
	v_pk_add_f32 v[184:185], v[184:185], v[188:189] op_sel:[0,1] op_sel_hi:[1,0] neg_lo:[0,1]
	v_pk_add_f32 v[188:189], v[170:171], v[182:183]
	v_pk_add_f32 v[182:183], v[170:171], v[182:183] neg_lo:[0,1] neg_hi:[0,1]
	v_xor_b32_e32 v34, 0x80000000, v25
	v_pk_add_f32 v[170:171], v[190:191], v[172:173]
	v_pk_add_f32 v[172:173], v[190:191], v[172:173] neg_lo:[0,1] neg_hi:[0,1]
	v_pk_add_f32 v[190:191], v[186:187], v[166:167]
	v_pk_add_f32 v[186:187], v[186:187], v[166:167] neg_lo:[0,1] neg_hi:[0,1]
	v_xor_b32_e32 v38, 0x80000000, v29
	v_pk_add_f32 v[166:167], v[144:145], v[174:175] op_sel:[0,1] op_sel_hi:[1,0] neg_hi:[0,1]
	v_pk_add_f32 v[144:145], v[144:145], v[174:175] op_sel:[0,1] op_sel_hi:[1,0] neg_lo:[0,1]
	v_pk_add_f32 v[174:175], v[148:149], v[168:169]
	v_pk_add_f32 v[168:169], v[148:149], v[168:169] neg_lo:[0,1] neg_hi:[0,1]
	v_xor_b32_e32 v42, 0x80000000, v33
	v_pk_add_f32 v[148:149], v[176:177], v[180:181]
	v_pk_add_f32 v[176:177], v[176:177], v[180:181] neg_lo:[0,1] neg_hi:[0,1]
	v_pk_add_f32 v[180:181], v[192:193], v[150:151]
	v_pk_add_f32 v[192:193], v[192:193], v[150:151] neg_lo:[0,1] neg_hi:[0,1]
	v_xor_b32_e32 v46, 0x80000000, v37
	v_pk_add_f32 v[150:151], v[154:155], v[158:159] op_sel:[0,1] op_sel_hi:[1,0] neg_hi:[0,1]
	v_pk_add_f32 v[154:155], v[154:155], v[158:159] op_sel:[0,1] op_sel_hi:[1,0] neg_lo:[0,1]
	v_pk_add_f32 v[158:159], v[136:137], v[152:153]
	v_pk_add_f32 v[152:153], v[136:137], v[152:153] neg_lo:[0,1] neg_hi:[0,1]
	v_mov_b32_e32 v35, v25
	v_pk_add_f32 v[136:137], v[160:161], v[138:139]
	v_pk_add_f32 v[138:139], v[160:161], v[138:139] neg_lo:[0,1] neg_hi:[0,1]
	v_pk_add_f32 v[160:161], v[156:157], v[132:133]
	v_pk_add_f32 v[156:157], v[156:157], v[132:133] neg_lo:[0,1] neg_hi:[0,1]
	v_mov_b32_e32 v39, v29
	v_pk_add_f32 v[132:133], v[128:129], v[140:141] op_sel:[0,1] op_sel_hi:[1,0] neg_hi:[0,1]
	v_pk_add_f32 v[128:129], v[128:129], v[140:141] op_sel:[0,1] op_sel_hi:[1,0] neg_lo:[0,1]
	v_pk_add_f32 v[140:141], v[130:131], v[134:135]
	v_pk_add_f32 v[134:135], v[130:131], v[134:135] neg_lo:[0,1] neg_hi:[0,1]
	v_mov_b32_e32 v43, v33
	v_pk_add_f32 v[130:131], v[142:143], v[178:179]
	v_pk_add_f32 v[142:143], v[142:143], v[178:179] neg_lo:[0,1] neg_hi:[0,1]
	v_pk_add_f32 v[178:179], v[162:163], v[194:195] op_sel:[0,1] op_sel_hi:[1,0] neg_hi:[0,1]
	v_pk_add_f32 v[162:163], v[162:163], v[194:195] op_sel:[0,1] op_sel_hi:[1,0] neg_lo:[0,1]
	v_pk_add_f32 v[194:195], v[164:165], v[188:189]
	v_pk_add_f32 v[164:165], v[164:165], v[188:189] neg_lo:[0,1] neg_hi:[0,1]
	v_pk_add_f32 v[188:189], v[184:185], v[182:183] op_sel:[0,1] op_sel_hi:[1,0] neg_hi:[0,1]
	v_pk_add_f32 v[182:183], v[184:185], v[182:183] op_sel:[0,1] op_sel_hi:[1,0] neg_lo:[0,1]
	v_pk_add_f32 v[184:185], v[170:171], v[190:191]
	v_pk_add_f32 v[170:171], v[170:171], v[190:191] neg_lo:[0,1] neg_hi:[0,1]
	v_pk_add_f32 v[190:191], v[172:173], v[186:187] op_sel:[0,1] op_sel_hi:[1,0] neg_hi:[0,1]
	v_pk_add_f32 v[172:173], v[172:173], v[186:187] op_sel:[0,1] op_sel_hi:[1,0] neg_lo:[0,1]
	v_pk_add_f32 v[186:187], v[166:167], v[174:175]
	v_pk_add_f32 v[166:167], v[166:167], v[174:175] neg_lo:[0,1] neg_hi:[0,1]
	v_pk_add_f32 v[174:175], v[144:145], v[168:169] op_sel:[0,1] op_sel_hi:[1,0] neg_hi:[0,1]
	v_pk_add_f32 v[144:145], v[144:145], v[168:169] op_sel:[0,1] op_sel_hi:[1,0] neg_lo:[0,1]
	v_pk_add_f32 v[168:169], v[148:149], v[180:181]
	v_pk_add_f32 v[148:149], v[148:149], v[180:181] neg_lo:[0,1] neg_hi:[0,1]
	v_pk_mul_f32 v[2:3], v[2:3], v[168:169] op_sel:[0,1] op_sel_hi:[1,0]
	v_pk_add_f32 v[180:181], v[176:177], v[192:193] op_sel:[0,1] op_sel_hi:[1,0] neg_hi:[0,1]
	v_pk_add_f32 v[176:177], v[176:177], v[192:193] op_sel:[0,1] op_sel_hi:[1,0] neg_lo:[0,1]
	v_pk_add_f32 v[192:193], v[150:151], v[158:159]
	v_pk_add_f32 v[150:151], v[150:151], v[158:159] neg_lo:[0,1] neg_hi:[0,1]
	v_pk_add_f32 v[158:159], v[154:155], v[152:153] op_sel:[0,1] op_sel_hi:[1,0] neg_hi:[0,1]
	v_pk_add_f32 v[152:153], v[154:155], v[152:153] op_sel:[0,1] op_sel_hi:[1,0] neg_lo:[0,1]
	v_pk_add_f32 v[154:155], v[136:137], v[160:161]
	v_pk_fma_f32 v[2:3], v[4:5], v[168:169], v[2:3] op_sel_hi:[0,1,1]
	v_pk_mul_f32 v[4:5], v[12:13], v[184:185] op_sel:[0,1] op_sel_hi:[1,0]
	v_mov_b32_e32 v47, v37
	v_pk_fma_f32 v[4:5], v[6:7], v[184:185], v[4:5] op_sel_hi:[0,1,1]
	v_pk_mul_f32 v[6:7], v[22:23], v[154:155] op_sel:[0,1] op_sel_hi:[1,0]
	v_pk_add_f32 v[136:137], v[136:137], v[160:161] neg_lo:[0,1] neg_hi:[0,1]
	v_pk_fma_f32 v[6:7], v[8:9], v[154:155], v[6:7] op_sel_hi:[0,1,1]
	v_pk_mul_f32 v[8:9], v[14:15], v[194:195] op_sel:[0,1] op_sel_hi:[1,0]
	v_pk_add_f32 v[160:161], v[138:139], v[156:157] op_sel:[0,1] op_sel_hi:[1,0] neg_hi:[0,1]
	v_pk_add_f32 v[138:139], v[138:139], v[156:157] op_sel:[0,1] op_sel_hi:[1,0] neg_lo:[0,1]
	v_pk_add_f32 v[156:157], v[132:133], v[140:141]
	v_pk_fma_f32 v[8:9], v[10:11], v[194:195], v[8:9] op_sel_hi:[0,1,1]
	v_pk_mul_f32 v[10:11], v[26:27], v[192:193] op_sel:[0,1] op_sel_hi:[1,0]
	v_pk_mul_f32 v[12:13], v[30:31], v[186:187] op_sel:[0,1] op_sel_hi:[1,0]
	v_xor_b32_e32 v50, 0x80000000, v41
	v_xor_b32_e32 v54, 0x80000000, v45
	v_xor_b32_e32 v58, 0x80000000, v49
	v_xor_b32_e32 v62, 0x80000000, v53
	v_xor_b32_e32 v66, 0x80000000, v57
	v_xor_b32_e32 v70, 0x80000000, v61
	v_xor_b32_e32 v74, 0x80000000, v65
	v_mov_b32_e32 v51, v41
	v_mov_b32_e32 v55, v45
	v_mov_b32_e32 v59, v49
	v_mov_b32_e32 v63, v53
	v_mov_b32_e32 v67, v57
	v_mov_b32_e32 v71, v61
	v_mov_b32_e32 v75, v65
	v_pk_add_f32 v[132:133], v[132:133], v[140:141] neg_lo:[0,1] neg_hi:[0,1]
	v_pk_add_f32 v[140:141], v[128:129], v[134:135] op_sel:[0,1] op_sel_hi:[1,0] neg_hi:[0,1]
	v_pk_fma_f32 v[10:11], v[16:17], v[192:193], v[10:11] op_sel_hi:[0,1,1]
	v_pk_fma_f32 v[12:13], v[20:21], v[186:187], v[12:13] op_sel_hi:[0,1,1]
	v_pk_mul_f32 v[14:15], v[34:35], v[156:157] op_sel:[0,1] op_sel_hi:[1,0]
	v_pk_mul_f32 v[16:17], v[38:39], v[178:179] op_sel:[0,1] op_sel_hi:[1,0]
	v_pk_mul_f32 v[20:21], v[42:43], v[180:181] op_sel:[0,1] op_sel_hi:[1,0]
	v_pk_mul_f32 v[22:23], v[46:47], v[190:191] op_sel:[0,1] op_sel_hi:[1,0]
	v_xor_b32_e32 v78, 0x80000000, v69
	v_xor_b32_e32 v82, 0x80000000, v73
	v_xor_b32_e32 v86, 0x80000000, v77
	v_xor_b32_e32 v90, 0x80000000, v81
	v_xor_b32_e32 v94, 0x80000000, v85
	v_xor_b32_e32 v98, 0x80000000, v89
	v_xor_b32_e32 v102, 0x80000000, v93
	v_xor_b32_e32 v106, 0x80000000, v97
	v_xor_b32_e32 v110, 0x80000000, v101
	v_xor_b32_e32 v114, 0x80000000, v105
	v_xor_b32_e32 v118, 0x80000000, v109
	v_xor_b32_e32 v122, 0x80000000, v113
	v_xor_b32_e32 v124, 0x80000000, v117
	v_xor_b32_e32 v126, 0x80000000, v121
	v_mov_b32_e32 v79, v69
	v_mov_b32_e32 v83, v73
	v_mov_b32_e32 v87, v77
	v_mov_b32_e32 v91, v81
	v_mov_b32_e32 v95, v85
	v_mov_b32_e32 v99, v89
	v_mov_b32_e32 v103, v93
	v_mov_b32_e32 v107, v97
	v_mov_b32_e32 v111, v101
	v_mov_b32_e32 v115, v105
	v_mov_b32_e32 v119, v109
	v_mov_b32_e32 v123, v113
	v_mov_b32_e32 v125, v117
	v_mov_b32_e32 v127, v121
	v_pk_add_f32 v[128:129], v[128:129], v[134:135] op_sel:[0,1] op_sel_hi:[1,0] neg_lo:[0,1]
	v_pk_fma_f32 v[14:15], v[24:25], v[156:157], v[14:15] op_sel_hi:[0,1,1]
	v_pk_fma_f32 v[16:17], v[28:29], v[178:179], v[16:17] op_sel_hi:[0,1,1]
	v_pk_fma_f32 v[20:21], v[32:33], v[180:181], v[20:21] op_sel_hi:[0,1,1]
	v_pk_fma_f32 v[22:23], v[36:37], v[190:191], v[22:23] op_sel_hi:[0,1,1]
	v_pk_mul_f32 v[24:25], v[50:51], v[160:161] op_sel:[0,1] op_sel_hi:[1,0]
	v_pk_mul_f32 v[26:27], v[54:55], v[188:189] op_sel:[0,1] op_sel_hi:[1,0]
	v_pk_mul_f32 v[28:29], v[58:59], v[158:159] op_sel:[0,1] op_sel_hi:[1,0]
	v_pk_mul_f32 v[30:31], v[62:63], v[174:175] op_sel:[0,1] op_sel_hi:[1,0]
	v_pk_mul_f32 v[32:33], v[66:67], v[140:141] op_sel:[0,1] op_sel_hi:[1,0]
	v_pk_mul_f32 v[34:35], v[70:71], v[142:143] op_sel:[0,1] op_sel_hi:[1,0]
	v_pk_mul_f32 v[36:37], v[74:75], v[148:149] op_sel:[0,1] op_sel_hi:[1,0]
	v_pk_fma_f32 v[24:25], v[40:41], v[160:161], v[24:25] op_sel_hi:[0,1,1]
	v_pk_fma_f32 v[26:27], v[44:45], v[188:189], v[26:27] op_sel_hi:[0,1,1]
	v_pk_fma_f32 v[28:29], v[48:49], v[158:159], v[28:29] op_sel_hi:[0,1,1]
	v_pk_fma_f32 v[30:31], v[52:53], v[174:175], v[30:31] op_sel_hi:[0,1,1]
	v_pk_fma_f32 v[32:33], v[56:57], v[140:141], v[32:33] op_sel_hi:[0,1,1]
	v_pk_fma_f32 v[34:35], v[60:61], v[142:143], v[34:35] op_sel_hi:[0,1,1]
	v_pk_fma_f32 v[36:37], v[64:65], v[148:149], v[36:37] op_sel_hi:[0,1,1]
	v_pk_mul_f32 v[38:39], v[78:79], v[170:171] op_sel:[0,1] op_sel_hi:[1,0]
	v_pk_mul_f32 v[40:41], v[82:83], v[136:137] op_sel:[0,1] op_sel_hi:[1,0]
	v_pk_mul_f32 v[42:43], v[86:87], v[164:165] op_sel:[0,1] op_sel_hi:[1,0]
	v_pk_mul_f32 v[44:45], v[90:91], v[150:151] op_sel:[0,1] op_sel_hi:[1,0]
	v_pk_mul_f32 v[46:47], v[94:95], v[166:167] op_sel:[0,1] op_sel_hi:[1,0]
	v_pk_mul_f32 v[48:49], v[98:99], v[132:133] op_sel:[0,1] op_sel_hi:[1,0]
	v_pk_mul_f32 v[50:51], v[102:103], v[162:163] op_sel:[0,1] op_sel_hi:[1,0]
	v_pk_mul_f32 v[52:53], v[106:107], v[176:177] op_sel:[0,1] op_sel_hi:[1,0]
	v_pk_mul_f32 v[54:55], v[110:111], v[172:173] op_sel:[0,1] op_sel_hi:[1,0]
	v_pk_mul_f32 v[56:57], v[114:115], v[138:139] op_sel:[0,1] op_sel_hi:[1,0]
	v_pk_mul_f32 v[58:59], v[118:119], v[182:183] op_sel:[0,1] op_sel_hi:[1,0]
	v_pk_mul_f32 v[60:61], v[122:123], v[152:153] op_sel:[0,1] op_sel_hi:[1,0]
	v_pk_mul_f32 v[62:63], v[124:125], v[144:145] op_sel:[0,1] op_sel_hi:[1,0]
	v_pk_mul_f32 v[64:65], v[126:127], v[128:129] op_sel:[0,1] op_sel_hi:[1,0]
	v_pk_fma_f32 v[38:39], v[68:69], v[170:171], v[38:39] op_sel_hi:[0,1,1]
	v_pk_fma_f32 v[40:41], v[72:73], v[136:137], v[40:41] op_sel_hi:[0,1,1]
	v_pk_fma_f32 v[42:43], v[76:77], v[164:165], v[42:43] op_sel_hi:[0,1,1]
	v_pk_fma_f32 v[44:45], v[80:81], v[150:151], v[44:45] op_sel_hi:[0,1,1]
	v_pk_fma_f32 v[46:47], v[84:85], v[166:167], v[46:47] op_sel_hi:[0,1,1]
	v_pk_fma_f32 v[48:49], v[88:89], v[132:133], v[48:49] op_sel_hi:[0,1,1]
	v_pk_fma_f32 v[50:51], v[92:93], v[162:163], v[50:51] op_sel_hi:[0,1,1]
	v_pk_fma_f32 v[52:53], v[96:97], v[176:177], v[52:53] op_sel_hi:[0,1,1]
	v_pk_fma_f32 v[54:55], v[100:101], v[172:173], v[54:55] op_sel_hi:[0,1,1]
	v_pk_fma_f32 v[56:57], v[104:105], v[138:139], v[56:57] op_sel_hi:[0,1,1]
	v_pk_fma_f32 v[58:59], v[108:109], v[182:183], v[58:59] op_sel_hi:[0,1,1]
	v_pk_fma_f32 v[60:61], v[112:113], v[152:153], v[60:61] op_sel_hi:[0,1,1]
	v_pk_fma_f32 v[62:63], v[116:117], v[144:145], v[62:63] op_sel_hi:[0,1,1]
	v_pk_fma_f32 v[64:65], v[120:121], v[128:129], v[64:65] op_sel_hi:[0,1,1]
	ds_write2_b64 v18, v[130:131], v[34:35] offset1:16
	ds_write2_b64 v18, v[16:17], v[50:51] offset0:33 offset1:49
	ds_write2_b64 v18, v[8:9], v[42:43] offset0:66 offset1:82
	ds_write2_b64 v18, v[26:27], v[58:59] offset0:99 offset1:115
	ds_write2_b64 v18, v[4:5], v[38:39] offset0:132 offset1:148
	ds_write2_b64 v18, v[22:23], v[54:55] offset0:165 offset1:181
	ds_write2_b64 v18, v[12:13], v[46:47] offset0:198 offset1:214
	ds_write2_b64 v18, v[30:31], v[62:63] offset0:231 offset1:247
	ds_write2_b64 v196, v[2:3], v[36:37] offset0:8 offset1:24
	ds_write2_b64 v196, v[20:21], v[52:53] offset0:41 offset1:57
	ds_write2_b64 v196, v[10:11], v[44:45] offset0:74 offset1:90
	ds_write2_b64 v196, v[28:29], v[60:61] offset0:107 offset1:123
	ds_write2_b64 v196, v[6:7], v[40:41] offset0:140 offset1:156
	ds_write2_b64 v196, v[24:25], v[56:57] offset0:173 offset1:189
	ds_write2_b64 v196, v[14:15], v[48:49] offset0:206 offset1:222
	ds_write2_b64 v196, v[32:33], v[64:65] offset0:239 offset1:255
	v_ashrrev_i32_e32 v2, 31, v210
	v_lshrrev_b32_e32 v2, 23, v2
	v_add_u32_e32 v2, v210, v2
	s_lshl_b64 s[74:75], s[76:77], 16
	v_and_b32_e32 v2, 0xfffffe00, v2
	s_add_u32 s0, s54, s74
	v_sub_u32_e32 v2, v210, v2
	s_addc_u32 s1, s55, s75
	v_ashrrev_i32_e32 v3, 31, v2
	v_lshl_add_u64 v[14:15], v[2:3], 3, s[0:1]
	v_add_co_u32_e32 v2, vcc, s92, v14
	s_mov_b32 s0, 0x8000
	s_nop 0
	v_addc_co_u32_e32 v3, vcc, 0, v15, vcc
	v_add_co_u32_e32 v4, vcc, s95, v14
	s_waitcnt lgkmcnt(0)
	s_nop 0
	v_addc_co_u32_e32 v5, vcc, 0, v15, vcc
	v_add_co_u32_e32 v8, vcc, s96, v14
	s_barrier
	s_nop 0
	v_addc_co_u32_e32 v9, vcc, 0, v15, vcc
	global_load_dwordx2 v[24:25], v[4:5], off offset:-4096 nt
	global_load_dwordx2 v[12:13], v[4:5], off nt
	global_load_dwordx2 v[6:7], v[8:9], off offset:-4096 nt
	s_nop 0
	global_load_dwordx2 v[4:5], v[8:9], off nt
	v_add_co_u32_e32 v8, vcc, s0, v14
	s_waitcnt vmcnt(3)
	v_cvt_f32_f16_sdwa v174, v24 dst_sel:DWORD dst_unused:UNUSED_PAD src0_sel:WORD_1
	v_addc_co_u32_e32 v9, vcc, 0, v15, vcc
	v_add_co_u32_e32 v10, vcc, s34, v14
	v_cvt_f32_f16_e32 v175, v25
	s_nop 0
	v_addc_co_u32_e32 v11, vcc, 0, v15, vcc
	global_load_dwordx2 v[16:17], v[8:9], off offset:-4096 nt
	global_load_dwordx2 v[122:123], v[8:9], off nt
	global_load_dwordx2 v[46:47], v[10:11], off offset:-4096 nt
	global_load_dwordx2 v[36:37], v[10:11], off nt
	v_add_co_u32_e32 v8, vcc, s35, v14
	v_cvt_f32_f16_sdwa v177, v25 dst_sel:DWORD dst_unused:UNUSED_PAD src0_sel:WORD_1
	s_nop 0
	v_addc_co_u32_e32 v9, vcc, 0, v15, vcc
	v_add_co_u32_e32 v22, vcc, s30, v14
	v_cvt_f32_f16_e32 v176, v24
	s_nop 0
	v_addc_co_u32_e32 v23, vcc, 0, v15, vcc
	global_load_dwordx2 v[26:27], v[8:9], off offset:-4096 nt
	global_load_dwordx2 v[20:21], v[8:9], off nt
	global_load_dwordx2 v[10:11], v[22:23], off offset:-4096 nt
	s_nop 0
	global_load_dwordx2 v[8:9], v[22:23], off nt
	v_add_co_u32_e32 v22, vcc, s31, v14
	s_waitcnt vmcnt(10)
	v_cvt_f32_f16_sdwa v164, v12 dst_sel:DWORD dst_unused:UNUSED_PAD src0_sel:WORD_1
	v_addc_co_u32_e32 v23, vcc, 0, v15, vcc
	global_load_dwordx2 v[30:31], v[2:3], off offset:-4096 nt
	global_load_dwordx2 v[28:29], v[2:3], off nt
	s_nop 0
	global_load_dwordx2 v[2:3], v[22:23], off nt
	global_load_dwordx2 v[32:33], v[14:15], off nt
	v_mov_b32_e32 v14, v210
	v_cvt_f32_f16_e32 v165, v13
	v_ashrrev_i32_e32 v15, 31, v14
	v_lshrrev_b32_e32 v15, 23, v15
	v_add_u32_e32 v15, v14, v15
	v_ashrrev_i32_e32 v15, 9, v15
	v_mul_i32_i24_e32 v18, 0x200, v15
	v_sub_u32_e32 v18, v14, v18
	v_lshlrev_b32_e32 v14, 14, v15
	v_lshlrev_b32_e32 v15, 1, v18
	v_bfrev_b32_e32 v15, v15
	v_lshrrev_b32_e32 v15, 22, v15
	v_sub_u32_e32 v15, 0x400, v15
	v_bfrev_b32_e32 v15, v15
	v_lshrrev_b32_e32 v15, 18, v15
	v_and_b32_e32 v15, 0x3ff0, v15
	v_cmp_eq_u32_e64 s[0:1], 0, v18
	v_lshl_add_u32 v22, v18, 5, v14
	v_lshl_add_u32 v23, v22, 3, 0
	v_cndmask_b32_e64 v15, v15, 16, s[0:1]
	v_or_b32_e32 v14, v15, v14
	v_ashrrev_i32_e32 v22, 2, v22
	v_ashrrev_i32_e32 v15, 5, v14
	v_add_u32_e32 v211, v23, v22
	v_lshlrev_b32_e32 v14, 3, v14
	v_lshlrev_b32_e32 v15, 3, v15
	v_add3_u32 v212, 0, v14, v15
	ds_read2_b64 v[38:41], v211 offset1:1
	ds_read2_b64 v[42:45], v211 offset0:2 offset1:3
	ds_read2_b64 v[48:51], v212 offset1:1
	ds_read2_b64 v[52:55], v212 offset0:2 offset1:3
	ds_read2_b64 v[56:59], v211 offset0:4 offset1:5
	ds_read2_b64 v[60:63], v211 offset0:6 offset1:7
	ds_read2_b64 v[68:71], v212 offset0:4 offset1:5
	ds_read2_b64 v[72:75], v212 offset0:6 offset1:7
	ds_read2_b64 v[64:67], v211 offset0:8 offset1:9
	ds_read2_b64 v[76:79], v211 offset0:10 offset1:11
	ds_read2_b64 v[80:83], v212 offset0:8 offset1:9
	ds_read2_b64 v[98:101], v212 offset0:10 offset1:11
	ds_read2_b64 v[84:87], v211 offset0:12 offset1:13
	ds_read2_b64 v[88:91], v211 offset0:14 offset1:15
	ds_read2_b64 v[102:105], v212 offset0:12 offset1:13
	ds_read2_b64 v[106:109], v212 offset0:14 offset1:15
	s_waitcnt lgkmcnt(7)
	v_pk_add_f32 v[14:15], v[38:39], v[64:65]
	v_pk_add_f32 v[22:23], v[38:39], v[64:65] neg_lo:[0,1] neg_hi:[0,1]
	v_pk_add_f32 v[38:39], v[40:41], v[66:67] neg_lo:[0,1] neg_hi:[0,1]
	v_pk_add_f32 v[34:35], v[40:41], v[66:67]
	v_pk_mul_f32 v[40:41], v[38:39], s[18:19]
	v_cmp_ne_u32_e32 vcc, 0, v18
	v_pk_fma_f32 v[38:39], v[38:39], s[16:17], v[40:41] op_sel:[0,0,1] op_sel_hi:[1,0,0]
	s_waitcnt lgkmcnt(6)
	v_pk_add_f32 v[40:41], v[42:43], v[76:77]
	v_pk_add_f32 v[42:43], v[42:43], v[76:77] neg_lo:[0,1] neg_hi:[0,1]
	v_bfrev_b32_e32 v18, v18
	v_pk_mul_f32 v[64:65], v[42:43], s[36:37]
	v_lshrrev_b32_e32 v18, 23, v18
	v_pk_fma_f32 v[42:43], v[42:43], s[78:79], v[64:65] op_sel:[0,0,1] op_sel_hi:[1,0,0]
	v_pk_add_f32 v[64:65], v[44:45], v[78:79]
	v_pk_add_f32 v[44:45], v[44:45], v[78:79] neg_lo:[0,1] neg_hi:[0,1]
	s_waitcnt lgkmcnt(3)
	v_pk_add_f32 v[78:79], v[58:59], v[86:87]
	v_pk_mul_f32 v[66:67], v[44:45], s[40:41]
	v_pk_add_f32 v[58:59], v[58:59], v[86:87] neg_lo:[0,1] neg_hi:[0,1]
	v_pk_fma_f32 v[44:45], v[44:45], s[80:81], v[66:67] op_sel:[0,0,1] op_sel_hi:[1,0,0]
	v_pk_add_f32 v[66:67], v[56:57], v[84:85]
	v_pk_add_f32 v[76:77], v[56:57], v[84:85] neg_lo:[0,1] neg_hi:[0,1]
	v_pk_mul_f32 v[84:85], v[58:59], s[40:41]
	s_nop 0
	v_pk_fma_f32 v[58:59], v[58:59], s[80:81], v[84:85] op_sel:[0,0,1] op_sel_hi:[1,0,0] neg_lo:[1,0,0] neg_hi:[1,0,0]
	s_waitcnt lgkmcnt(2)
	v_pk_add_f32 v[84:85], v[60:61], v[88:89]
	v_pk_add_f32 v[60:61], v[60:61], v[88:89] neg_lo:[0,1] neg_hi:[0,1]
	s_nop 0
	v_pk_mul_f32 v[86:87], v[60:61], s[36:37]
	v_pk_add_f32 v[56:57], v[22:23], v[76:77] op_sel:[0,1] op_sel_hi:[1,0] neg_hi:[0,1]
	v_pk_fma_f32 v[60:61], v[60:61], s[78:79], v[86:87] op_sel:[0,0,1] op_sel_hi:[1,0,0] neg_lo:[1,0,0] neg_hi:[1,0,0]
	v_pk_add_f32 v[86:87], v[62:63], v[90:91]
	v_pk_add_f32 v[62:63], v[62:63], v[90:91] neg_lo:[0,1] neg_hi:[0,1]
	v_pk_add_f32 v[90:91], v[64:65], v[86:87]
	v_pk_mul_f32 v[88:89], v[62:63], s[18:19]
	v_pk_add_f32 v[64:65], v[64:65], v[86:87] neg_lo:[0,1] neg_hi:[0,1]
	v_pk_fma_f32 v[62:63], v[62:63], s[16:17], v[88:89] op_sel:[0,0,1] op_sel_hi:[1,0,0] neg_lo:[1,0,0] neg_hi:[1,0,0]
	v_pk_add_f32 v[88:89], v[14:15], v[66:67]
	v_pk_add_f32 v[14:15], v[14:15], v[66:67] neg_lo:[0,1] neg_hi:[0,1]
	v_pk_add_f32 v[66:67], v[34:35], v[78:79]
	v_pk_add_f32 v[34:35], v[34:35], v[78:79] neg_lo:[0,1] neg_hi:[0,1]
	v_pk_add_f32 v[22:23], v[22:23], v[76:77] op_sel:[0,1] op_sel_hi:[1,0] neg_lo:[0,1]
	v_pk_mul_f32 v[78:79], v[34:35], s[36:37]
	v_pk_add_f32 v[76:77], v[38:39], v[58:59]
	v_pk_add_f32 v[38:39], v[38:39], v[58:59] neg_lo:[0,1] neg_hi:[0,1]
	v_pk_fma_f32 v[34:35], v[34:35], s[78:79], v[78:79] op_sel:[0,0,1] op_sel_hi:[1,0,0]
	v_pk_add_f32 v[78:79], v[40:41], v[84:85]
	v_pk_add_f32 v[84:85], v[40:41], v[84:85] neg_lo:[0,1] neg_hi:[0,1]
	v_pk_mul_f32 v[86:87], v[64:65], s[36:37]
	v_pk_mul_f32 v[58:59], v[38:39], s[36:37]
	v_pk_fma_f32 v[64:65], v[64:65], s[78:79], v[86:87] op_sel:[0,0,1] op_sel_hi:[1,0,0] neg_lo:[1,0,0] neg_hi:[1,0,0]
	v_pk_fma_f32 v[38:39], v[38:39], s[78:79], v[58:59] op_sel:[0,0,1] op_sel_hi:[1,0,0]
	v_pk_add_f32 v[58:59], v[42:43], v[60:61]
	v_pk_add_f32 v[86:87], v[44:45], v[62:63]
	v_pk_add_f32 v[44:45], v[44:45], v[62:63] neg_lo:[0,1] neg_hi:[0,1]
	s_nop 0
	v_pk_mul_f32 v[62:63], v[44:45], s[36:37]
	v_pk_add_f32 v[40:41], v[14:15], v[84:85] op_sel:[0,1] op_sel_hi:[1,0] neg_hi:[0,1]
	v_pk_add_f32 v[14:15], v[14:15], v[84:85] op_sel:[0,1] op_sel_hi:[1,0] neg_lo:[0,1]
	v_pk_add_f32 v[84:85], v[34:35], v[64:65]
	v_pk_add_f32 v[64:65], v[34:35], v[64:65] neg_lo:[0,1] neg_hi:[0,1]
	v_pk_add_f32 v[94:95], v[56:57], v[58:59]
	v_pk_add_f32 v[56:57], v[56:57], v[58:59] neg_lo:[0,1] neg_hi:[0,1]
	v_pk_add_f32 v[58:59], v[76:77], v[86:87]
	v_pk_fma_f32 v[44:45], v[44:45], s[78:79], v[62:63] op_sel:[0,0,1] op_sel_hi:[1,0,0] neg_lo:[1,0,0] neg_hi:[1,0,0]
	v_pk_add_f32 v[62:63], v[88:89], v[78:79]
	v_pk_add_f32 v[78:79], v[88:89], v[78:79] neg_lo:[0,1] neg_hi:[0,1]
	v_pk_add_f32 v[88:89], v[66:67], v[90:91]
	v_pk_add_f32 v[110:111], v[76:77], v[86:87] neg_lo:[0,1] neg_hi:[0,1]
	v_pk_add_f32 v[86:87], v[94:95], v[58:59]
	v_pk_add_f32 v[34:35], v[94:95], v[58:59] neg_lo:[0,1] neg_hi:[0,1]
	v_pk_add_f32 v[58:59], v[50:51], v[82:83]
	v_pk_add_f32 v[50:51], v[50:51], v[82:83] neg_lo:[0,1] neg_hi:[0,1]
	v_pk_add_f32 v[60:61], v[42:43], v[60:61] neg_lo:[0,1] neg_hi:[0,1]
	v_pk_add_f32 v[148:149], v[62:63], v[88:89]
	v_pk_add_f32 v[138:139], v[62:63], v[88:89] neg_lo:[0,1] neg_hi:[0,1]
	v_pk_mul_f32 v[62:63], v[50:51], s[18:19]
	v_pk_add_f32 v[90:91], v[66:67], v[90:91] neg_lo:[0,1] neg_hi:[0,1]
	v_pk_fma_f32 v[50:51], v[50:51], s[16:17], v[62:63] op_sel:[0,0,1] op_sel_hi:[1,0,0]
	v_pk_add_f32 v[62:63], v[52:53], v[98:99]
	v_pk_add_f32 v[52:53], v[52:53], v[98:99] neg_lo:[0,1] neg_hi:[0,1]
	v_pk_add_f32 v[112:113], v[22:23], v[60:61] op_sel:[0,1] op_sel_hi:[1,0] neg_hi:[0,1]
	v_pk_add_f32 v[114:115], v[22:23], v[60:61] op_sel:[0,1] op_sel_hi:[1,0] neg_lo:[0,1]
	v_pk_add_f32 v[96:97], v[40:41], v[84:85]
	v_pk_add_f32 v[66:67], v[40:41], v[84:85] neg_lo:[0,1] neg_hi:[0,1]
	v_pk_add_f32 v[60:61], v[14:15], v[64:65] op_sel:[0,1] op_sel_hi:[1,0] neg_hi:[0,1]
	v_pk_add_f32 v[84:85], v[14:15], v[64:65] op_sel:[0,1] op_sel_hi:[1,0] neg_lo:[0,1]
	v_pk_mul_f32 v[64:65], v[52:53], s[36:37]
	s_nop 0
	v_pk_fma_f32 v[52:53], v[52:53], s[78:79], v[64:65] op_sel:[0,0,1] op_sel_hi:[1,0,0]
	v_pk_add_f32 v[64:65], v[54:55], v[100:101]
	v_pk_add_f32 v[54:55], v[54:55], v[100:101] neg_lo:[0,1] neg_hi:[0,1]
	s_nop 0
	v_pk_mul_f32 v[76:77], v[54:55], s[40:41]
	v_pk_add_f32 v[92:93], v[78:79], v[90:91] op_sel:[0,1] op_sel_hi:[1,0] neg_hi:[0,1]
	v_pk_fma_f32 v[54:55], v[54:55], s[80:81], v[76:77] op_sel:[0,0,1] op_sel_hi:[1,0,0]
	s_waitcnt lgkmcnt(1)
	v_pk_add_f32 v[76:77], v[68:69], v[102:103]
	v_pk_add_f32 v[68:69], v[68:69], v[102:103] neg_lo:[0,1] neg_hi:[0,1]
	v_pk_add_f32 v[88:89], v[78:79], v[90:91] op_sel:[0,1] op_sel_hi:[1,0] neg_lo:[0,1]
	v_xor_b32_e32 v79, 0x80000000, v68
	v_mov_b32_e32 v78, v69
	v_pk_add_f32 v[68:69], v[70:71], v[104:105]
	v_pk_add_f32 v[70:71], v[70:71], v[104:105] neg_lo:[0,1] neg_hi:[0,1]
	v_pk_add_f32 v[22:23], v[38:39], v[44:45]
	v_pk_add_f32 v[116:117], v[38:39], v[44:45] neg_lo:[0,1] neg_hi:[0,1]
	v_pk_add_f32 v[40:41], v[56:57], v[110:111] op_sel:[0,1] op_sel_hi:[1,0] neg_hi:[0,1]
	v_pk_add_f32 v[44:45], v[56:57], v[110:111] op_sel:[0,1] op_sel_hi:[1,0] neg_lo:[0,1]
	v_pk_add_f32 v[56:57], v[48:49], v[80:81]
	v_pk_add_f32 v[48:49], v[48:49], v[80:81] neg_lo:[0,1] neg_hi:[0,1]
	v_pk_mul_f32 v[80:81], v[70:71], s[40:41]
	v_cvt_f32_u32_e32 v18, v18
	v_pk_fma_f32 v[70:71], v[70:71], s[80:81], v[80:81] op_sel:[0,0,1] op_sel_hi:[1,0,0] neg_lo:[1,0,0] neg_hi:[1,0,0]
	s_waitcnt lgkmcnt(0)
	v_pk_add_f32 v[80:81], v[72:73], v[106:107]
	v_pk_add_f32 v[72:73], v[72:73], v[106:107] neg_lo:[0,1] neg_hi:[0,1]
	v_mul_f32_e32 v18, 0x38000000, v18
	v_pk_mul_f32 v[82:83], v[72:73], s[36:37]
	v_cndmask_b32_e64 v18, v18, v208, s[0:1]
	v_pk_fma_f32 v[72:73], v[72:73], s[78:79], v[82:83] op_sel:[0,0,1] op_sel_hi:[1,0,0] neg_lo:[1,0,0] neg_hi:[1,0,0]
	v_pk_add_f32 v[82:83], v[74:75], v[108:109]
	v_pk_add_f32 v[74:75], v[74:75], v[108:109] neg_lo:[0,1] neg_hi:[0,1]
	s_nop 0
	v_pk_mul_f32 v[90:91], v[74:75], s[18:19]
	s_nop 0
	v_pk_fma_f32 v[74:75], v[74:75], s[16:17], v[90:91] op_sel:[0,0,1] op_sel_hi:[1,0,0] neg_lo:[1,0,0] neg_hi:[1,0,0]
	v_pk_add_f32 v[90:91], v[56:57], v[76:77]
	v_pk_add_f32 v[56:57], v[56:57], v[76:77] neg_lo:[0,1] neg_hi:[0,1]
	v_pk_add_f32 v[76:77], v[58:59], v[68:69]
	v_pk_add_f32 v[58:59], v[58:59], v[68:69] neg_lo:[0,1] neg_hi:[0,1]
	v_pk_add_f32 v[14:15], v[114:115], v[116:117] op_sel:[0,1] op_sel_hi:[1,0] neg_hi:[0,1]
	v_pk_mul_f32 v[68:69], v[58:59], s[36:37]
	v_pk_add_f32 v[38:39], v[114:115], v[116:117] op_sel:[0,1] op_sel_hi:[1,0] neg_lo:[0,1]
	v_pk_fma_f32 v[58:59], v[58:59], s[78:79], v[68:69] op_sel:[0,0,1] op_sel_hi:[1,0,0]
	v_pk_add_f32 v[68:69], v[62:63], v[80:81]
	v_pk_add_f32 v[80:81], v[62:63], v[80:81] neg_lo:[0,1] neg_hi:[0,1]
	s_waitcnt vmcnt(0)
	v_cvt_f32_f16_e32 v193, v33
	s_nop 0
	s_nop 0
	v_pk_add_f32 v[62:63], v[64:65], v[82:83]
	v_pk_add_f32 v[64:65], v[64:65], v[82:83] neg_lo:[0,1] neg_hi:[0,1]
	v_cvt_f32_f16_sdwa v192, v32 dst_sel:DWORD dst_unused:UNUSED_PAD src0_sel:WORD_1
	v_pk_mul_f32 v[82:83], v[64:65], s[36:37]
	v_cvt_f32_f16_e32 v194, v32
	v_pk_fma_f32 v[64:65], v[64:65], s[78:79], v[82:83] op_sel:[0,0,1] op_sel_hi:[1,0,0] neg_lo:[1,0,0] neg_hi:[1,0,0]
	v_pk_add_f32 v[82:83], v[48:49], v[78:79]
	v_pk_add_f32 v[48:49], v[48:49], v[78:79] neg_lo:[0,1] neg_hi:[0,1]
	v_pk_add_f32 v[78:79], v[50:51], v[70:71]
	v_pk_add_f32 v[50:51], v[50:51], v[70:71] neg_lo:[0,1] neg_hi:[0,1]
	v_cvt_f32_f16_sdwa v195, v33 dst_sel:DWORD dst_unused:UNUSED_PAD src0_sel:WORD_1
	v_pk_mul_f32 v[70:71], v[50:51], s[36:37]
	v_cvt_f32_f16_sdwa v170, v30 dst_sel:DWORD dst_unused:UNUSED_PAD src0_sel:WORD_1
	v_pk_fma_f32 v[50:51], v[50:51], s[78:79], v[70:71] op_sel:[0,0,1] op_sel_hi:[1,0,0]
	v_pk_add_f32 v[70:71], v[52:53], v[72:73]
	v_pk_add_f32 v[72:73], v[52:53], v[72:73] neg_lo:[0,1] neg_hi:[0,1]
	v_cvt_f32_f16_e32 v171, v31
	s_nop 0
	s_nop 0
	v_pk_add_f32 v[52:53], v[54:55], v[74:75]
	v_pk_add_f32 v[54:55], v[54:55], v[74:75] neg_lo:[0,1] neg_hi:[0,1]
	v_cvt_f32_f16_sdwa v185, v31 dst_sel:DWORD dst_unused:UNUSED_PAD src0_sel:WORD_1
	v_pk_mul_f32 v[74:75], v[54:55], s[36:37]
	v_cvt_f32_f16_e32 v184, v30
	v_pk_fma_f32 v[54:55], v[54:55], s[78:79], v[74:75] op_sel:[0,0,1] op_sel_hi:[1,0,0] neg_lo:[1,0,0] neg_hi:[1,0,0]
	v_pk_add_f32 v[74:75], v[90:91], v[68:69]
	v_pk_add_f32 v[68:69], v[90:91], v[68:69] neg_lo:[0,1] neg_hi:[0,1]
	v_pk_add_f32 v[90:91], v[76:77], v[62:63]
	v_pk_add_f32 v[62:63], v[76:77], v[62:63] neg_lo:[0,1] neg_hi:[0,1]
	v_cvt_f32_f16_sdwa v172, v28 dst_sel:DWORD dst_unused:UNUSED_PAD src0_sel:WORD_1
	v_xor_b32_e32 v77, 0x80000000, v62
	v_mov_b32_e32 v76, v63
	v_pk_add_f32 v[62:63], v[56:57], v[80:81] op_sel:[0,1] op_sel_hi:[1,0] neg_hi:[0,1]
	v_pk_add_f32 v[56:57], v[56:57], v[80:81] op_sel:[0,1] op_sel_hi:[1,0] neg_lo:[0,1]
	v_pk_add_f32 v[80:81], v[58:59], v[64:65]
	v_pk_add_f32 v[58:59], v[58:59], v[64:65] neg_lo:[0,1] neg_hi:[0,1]
	v_cvt_f32_f16_e32 v173, v29
	v_xor_b32_e32 v65, 0x80000000, v58
	v_mov_b32_e32 v64, v59
	v_pk_add_f32 v[58:59], v[82:83], v[70:71]
	v_pk_add_f32 v[70:71], v[82:83], v[70:71] neg_lo:[0,1] neg_hi:[0,1]
	v_pk_add_f32 v[82:83], v[78:79], v[52:53]
	v_pk_add_f32 v[52:53], v[78:79], v[52:53] neg_lo:[0,1] neg_hi:[0,1]
	v_pk_add_f32 v[118:119], v[58:59], v[82:83]
	v_pk_add_f32 v[134:135], v[58:59], v[82:83] neg_lo:[0,1] neg_hi:[0,1]
	v_cos_f32_e32 v83, v18
	v_sin_f32_e32 v82, v18
	v_cvt_f32_f16_sdwa v181, v29 dst_sel:DWORD dst_unused:UNUSED_PAD src0_sel:WORD_1
	v_cvt_f32_f16_e32 v180, v28
	v_cvt_f32_f16_sdwa v167, v13 dst_sel:DWORD dst_unused:UNUSED_PAD src0_sel:WORD_1
	v_cvt_f32_f16_e32 v166, v12
	v_cvt_f32_f16_e32 v154, v6
	v_cvt_f32_f16_e32 v155, v7
	v_cvt_f32_f16_sdwa v157, v7 dst_sel:DWORD dst_unused:UNUSED_PAD src0_sel:WORD_1
	v_cvt_f32_f16_sdwa v156, v6 dst_sel:DWORD dst_unused:UNUSED_PAD src0_sel:WORD_1
	v_cvt_f32_f16_sdwa v140, v4 dst_sel:DWORD dst_unused:UNUSED_PAD src0_sel:WORD_1
	v_cvt_f32_f16_e32 v141, v5
	v_cvt_f32_f16_sdwa v143, v5 dst_sel:DWORD dst_unused:UNUSED_PAD src0_sel:WORD_1
	v_cvt_f32_f16_e32 v142, v4
	v_cvt_f32_f16_e32 v124, v16
	v_cvt_f32_f16_e32 v125, v17
	v_cvt_f32_f16_sdwa v127, v17 dst_sel:DWORD dst_unused:UNUSED_PAD src0_sel:WORD_1
	v_cvt_f32_f16_sdwa v126, v16 dst_sel:DWORD dst_unused:UNUSED_PAD src0_sel:WORD_1
	v_cvt_f32_f16_sdwa v114, v122 dst_sel:DWORD dst_unused:UNUSED_PAD src0_sel:WORD_1
	v_cvt_f32_f16_e32 v115, v123
	v_cvt_f32_f16_sdwa v117, v123 dst_sel:DWORD dst_unused:UNUSED_PAD src0_sel:WORD_1
	v_cvt_f32_f16_e32 v116, v122
	v_xor_b32_e32 v79, 0x80000000, v52
	v_mov_b32_e32 v78, v53
	v_pk_add_f32 v[52:53], v[48:49], v[72:73] op_sel:[0,1] op_sel_hi:[1,0] neg_hi:[0,1]
	v_pk_add_f32 v[48:49], v[48:49], v[72:73] op_sel:[0,1] op_sel_hi:[1,0] neg_lo:[0,1]
	v_pk_add_f32 v[72:73], v[50:51], v[54:55]
	v_pk_add_f32 v[50:51], v[50:51], v[54:55] neg_lo:[0,1] neg_hi:[0,1]
	v_pk_fma_f32 v[160:161], v[82:83], 0, v[82:83] op_sel:[0,0,1] op_sel_hi:[1,0,0] neg_lo:[1,0,0] neg_hi:[1,0,0]
	v_xor_b32_e32 v55, 0x80000000, v50
	v_mov_b32_e32 v54, v51
	v_pk_fma_f32 v[198:199], v[82:83], 0, v[82:83] op_sel:[0,0,1] op_sel_hi:[1,0,0]
	v_pk_add_f32 v[42:43], v[112:113], v[22:23]
	v_pk_add_f32 v[22:23], v[112:113], v[22:23] neg_lo:[0,1] neg_hi:[0,1]
	v_pk_add_f32 v[98:99], v[74:75], v[90:91]
	v_pk_add_f32 v[100:101], v[74:75], v[90:91] neg_lo:[0,1] neg_hi:[0,1]
	v_pk_add_f32 v[102:103], v[68:69], v[76:77]
	v_pk_add_f32 v[106:107], v[68:69], v[76:77] neg_lo:[0,1] neg_hi:[0,1]
	v_pk_add_f32 v[104:105], v[62:63], v[80:81]
	v_pk_add_f32 v[108:109], v[62:63], v[80:81] neg_lo:[0,1] neg_hi:[0,1]
	v_pk_add_f32 v[110:111], v[56:57], v[64:65]
	v_pk_add_f32 v[112:113], v[56:57], v[64:65] neg_lo:[0,1] neg_hi:[0,1]
	v_pk_add_f32 v[152:153], v[70:71], v[78:79]
	v_pk_add_f32 v[162:163], v[70:71], v[78:79] neg_lo:[0,1] neg_hi:[0,1]
	v_pk_add_f32 v[178:179], v[52:53], v[72:73]
	v_pk_add_f32 v[182:183], v[52:53], v[72:73] neg_lo:[0,1] neg_hi:[0,1]
	v_pk_add_f32 v[188:189], v[48:49], v[54:55]
	v_pk_add_f32 v[196:197], v[48:49], v[54:55] neg_lo:[0,1] neg_hi:[0,1]
	v_pk_mul_f32 v[186:187], v[82:83], 0 op_sel_hi:[1,0]
	v_mov_b32_e32 v190, v160
	v_mov_b32_e32 v191, v199
	v_mul_f32_e32 v18, 0x3f3504f3, v83
	v_mul_f32_e32 v158, 0xbec3ef15, v83
	v_mul_f32_e32 v132, 0xbf6c835e, v83
	s_and_saveexec_b64 s[0:1], vcc
	s_xor_b64 s[0:1], exec, s[0:1]
	s_cbranch_execz .LBB0_501
	v_pk_add_f32 v[4:5], v[148:149], v[196:197]
	v_pk_add_f32 v[6:7], v[148:149], v[196:197] neg_lo:[0,1] neg_hi:[0,1]
	v_mul_f32_e32 v4, 0.5, v4
	v_mul_f32_e32 v12, 0.5, v7
	v_mov_b32_e32 v7, v5
	v_pk_mul_f32 v[6:7], v[6:7], s[44:45]
	v_pk_mov_b32 v[16:17], v[198:199], v[160:161] op_sel:[1,0]
	v_pk_mul_f32 v[24:25], v[190:191], v[6:7] op_sel:[0,1] op_sel_hi:[1,0]
	v_pk_mul_f32 v[6:7], v[190:191], v[6:7]
	v_pk_add_f32 v[24:25], v[24:25], v[24:25] op_sel:[0,1] op_sel_hi:[0,1]
	v_pk_add_f32 v[28:29], v[4:5], v[24:25] op_sel_hi:[0,1] neg_hi:[0,1]
	v_pk_add_f32 v[4:5], v[6:7], v[6:7] op_sel:[0,1] op_sel_hi:[0,1] neg_lo:[0,1] neg_hi:[0,1]
	v_pk_add_f32 v[6:7], v[12:13], v[4:5] op_sel_hi:[0,1] neg_hi:[0,1]
	v_pk_mul_f32 v[4:5], v[6:7], v[194:195]
	v_pk_mul_f32 v[6:7], v[6:7], v[192:193]
	v_pk_fma_f32 v[4:5], v[28:29], v[192:193], v[4:5]
	v_pk_fma_f32 v[6:7], v[28:29], v[194:195], v[6:7] neg_lo:[0,0,1] neg_hi:[0,0,1]
	s_mov_b32 s78, s19
	v_pk_add_f32 v[12:13], v[6:7], v[4:5] op_sel:[0,1] op_sel_hi:[1,0] neg_lo:[0,1]
	v_pk_add_f32 v[28:29], v[6:7], v[4:5] op_sel:[0,1] op_sel_hi:[1,0]
	v_pk_add_f32 v[4:5], v[4:5], v[6:7] op_sel:[1,0] op_sel_hi:[0,1] neg_lo:[0,1] neg_hi:[0,1]
	s_nop 0
	v_pk_mul_f32 v[12:13], v[12:13], 0.5 op_sel_hi:[1,0]
	v_mov_b32_e32 v29, v5
	v_mul_f32_e32 v24, v190, v12
	v_pk_fma_f32 v[30:31], v[190:191], v[12:13], v[24:25] op_sel_hi:[1,1,0] neg_lo:[1,0,0] neg_hi:[1,0,0]
	v_mul_f32_e32 v24, v160, v13
	v_pk_fma_f32 v[12:13], v[16:17], v[12:13], v[24:25] op_sel_hi:[1,1,0]
	v_mov_b32_e32 v16, v83
	v_mov_b32_e32 v30, v12
	v_pk_fma_f32 v[4:5], v[28:29], 0.5, v[12:13] op_sel_hi:[1,0,1] neg_lo:[0,0,1] neg_hi:[0,0,1]
	v_pk_fma_f32 v[122:123], v[28:29], 0.5, v[30:31] op_sel_hi:[1,0,1]
	v_pk_fma_f32 v[6:7], v[28:29], 0.5, v[30:31] op_sel_hi:[1,0,1] neg_lo:[1,0,0] neg_hi:[1,0,0]
	v_mov_b32_e32 v5, v123
	v_pk_mul_f32 v[24:25], v[4:5], s[6:7] op_sel_hi:[1,0]
	v_pk_add_f32 v[4:5], v[138:139], v[188:189]
	v_pk_add_f32 v[12:13], v[138:139], v[188:189] neg_lo:[0,1] neg_hi:[0,1]
	v_mov_b32_e32 v17, v82
	v_mul_f32_e32 v6, 0.5, v13
	v_pk_add_f32 v[28:29], v[186:187], v[16:17] neg_lo:[0,1] neg_hi:[0,1]
	v_pk_add_f32 v[30:31], v[186:187], v[16:17]
	v_mov_b32_e32 v13, v5
	v_pk_mov_b32 v[32:33], v[28:29], v[30:31] op_sel:[1,0]
	v_pk_mul_f32 v[12:13], v[12:13], s[44:45]
	v_mul_f32_e32 v4, 0.5, v4
	v_pk_mul_f32 v[48:49], v[32:33], v[12:13] op_sel:[0,1] op_sel_hi:[1,0]
	v_pk_mul_f32 v[12:13], v[32:33], v[12:13]
	v_pk_add_f32 v[48:49], v[48:49], v[48:49] op_sel:[0,1] op_sel_hi:[0,1]
	v_pk_add_f32 v[50:51], v[4:5], v[48:49] op_sel_hi:[0,1] neg_hi:[0,1]
	v_pk_add_f32 v[4:5], v[12:13], v[12:13] op_sel:[0,1] op_sel_hi:[0,1] neg_lo:[0,1] neg_hi:[0,1]
	v_pk_add_f32 v[12:13], v[6:7], v[4:5] op_sel_hi:[0,1] neg_hi:[0,1]
	v_pk_mul_f32 v[4:5], v[12:13], v[184:185]
	v_pk_mul_f32 v[12:13], v[12:13], v[170:171]
	v_pk_fma_f32 v[4:5], v[50:51], v[170:171], v[4:5]
	v_pk_fma_f32 v[12:13], v[50:51], v[184:185], v[12:13] neg_lo:[0,0,1] neg_hi:[0,0,1]
	v_mov_b32_e32 v31, v29
	v_pk_add_f32 v[48:49], v[12:13], v[4:5] op_sel:[0,1] op_sel_hi:[1,0] neg_lo:[0,1]
	v_pk_add_f32 v[50:51], v[12:13], v[4:5] op_sel:[0,1] op_sel_hi:[1,0]
	v_pk_add_f32 v[4:5], v[4:5], v[12:13] op_sel:[1,0] op_sel_hi:[0,1] neg_lo:[0,1] neg_hi:[0,1]
	v_pk_mul_f32 v[48:49], v[48:49], 0.5 op_sel_hi:[1,0]
	v_mov_b32_e32 v51, v5
	v_mul_f32_e32 v6, v29, v48
	v_pk_fma_f32 v[32:33], v[32:33], v[48:49], v[6:7] op_sel_hi:[1,1,0] neg_lo:[1,0,0] neg_hi:[1,0,0]
	v_mul_f32_e32 v6, v29, v49
	v_pk_fma_f32 v[28:29], v[30:31], v[48:49], v[6:7] op_sel_hi:[1,1,0]
	v_pk_mul_f32 v[12:13], v[16:17], s[36:37]
	v_mov_b32_e32 v32, v28
	v_pk_fma_f32 v[4:5], v[50:51], 0.5, v[28:29] op_sel_hi:[1,0,1] neg_lo:[0,0,1] neg_hi:[0,0,1]
	v_pk_fma_f32 v[138:139], v[50:51], 0.5, v[32:33] op_sel_hi:[1,0,1]
	v_pk_add_f32 v[16:17], v[92:93], v[182:183]
	v_mov_b32_e32 v5, v139
	v_pk_add_f32 v[28:29], v[92:93], v[182:183] neg_lo:[0,1] neg_hi:[0,1]
	v_pk_mul_f32 v[30:31], v[4:5], s[6:7] op_sel_hi:[1,0]
	v_pk_fma_f32 v[4:5], v[50:51], 0.5, v[32:33] op_sel_hi:[1,0,1] neg_lo:[1,0,0] neg_hi:[1,0,0]
	v_mul_f32_e32 v6, 0.5, v29
	v_pk_add_f32 v[32:33], v[18:19], v[12:13] op_sel:[0,1] op_sel_hi:[0,1] neg_lo:[0,1] neg_hi:[0,1]
	v_pk_add_f32 v[48:49], v[18:19], v[12:13] op_sel:[0,1] op_sel_hi:[0,1]
	v_mov_b32_e32 v29, v17
	v_mul_f32_e32 v4, 0.5, v16
	v_mov_b32_e32 v50, v32
	v_mov_b32_e32 v51, v49
	v_pk_mul_f32 v[16:17], v[28:29], s[44:45]
	v_pk_mov_b32 v[48:49], v[48:49], v[32:33] op_sel:[1,0]
	v_pk_mul_f32 v[28:29], v[50:51], v[16:17] op_sel:[0,1] op_sel_hi:[1,0]
	v_pk_mul_f32 v[16:17], v[50:51], v[16:17]
	v_pk_add_f32 v[28:29], v[28:29], v[28:29] op_sel:[0,1] op_sel_hi:[0,1]
	v_pk_add_f32 v[52:53], v[4:5], v[28:29] op_sel_hi:[0,1] neg_hi:[0,1]
	v_pk_add_f32 v[16:17], v[16:17], v[16:17] op_sel:[0,1] op_sel_hi:[0,1] neg_lo:[0,1] neg_hi:[0,1]
	v_pk_add_f32 v[28:29], v[6:7], v[16:17] op_sel_hi:[0,1] neg_hi:[0,1]
	v_pk_mul_f32 v[16:17], v[28:29], v[180:181]
	v_pk_mul_f32 v[28:29], v[28:29], v[172:173]
	v_pk_fma_f32 v[16:17], v[52:53], v[172:173], v[16:17]
	v_pk_fma_f32 v[28:29], v[52:53], v[180:181], v[28:29] neg_lo:[0,0,1] neg_hi:[0,0,1]
	v_sub_f32_e32 v6, v89, v179
	v_pk_add_f32 v[52:53], v[28:29], v[16:17] op_sel:[0,1] op_sel_hi:[1,0] neg_lo:[0,1]
	v_pk_add_f32 v[54:55], v[28:29], v[16:17] op_sel:[0,1] op_sel_hi:[1,0]
	v_pk_add_f32 v[16:17], v[16:17], v[28:29] op_sel:[1,0] op_sel_hi:[0,1] neg_lo:[0,1] neg_hi:[0,1]
	v_pk_mul_f32 v[52:53], v[52:53], 0.5 op_sel_hi:[1,0]
	v_mov_b32_e32 v55, v17
	v_mul_f32_e32 v4, v32, v52
	v_pk_fma_f32 v[56:57], v[50:51], v[52:53], v[4:5] op_sel_hi:[1,1,0] neg_lo:[1,0,0] neg_hi:[1,0,0]
	v_mul_f32_e32 v4, v32, v53
	v_pk_fma_f32 v[48:49], v[48:49], v[52:53], v[4:5] op_sel_hi:[1,1,0]
	v_pk_add_f32 v[28:29], v[88:89], v[178:179]
	v_mov_b32_e32 v56, v48
	v_pk_fma_f32 v[16:17], v[54:55], 0.5, v[48:49] op_sel_hi:[1,0,1] neg_lo:[0,0,1] neg_hi:[0,0,1]
	v_mov_b32_e32 v48, v12
	v_mov_b32_e32 v49, v88
	v_pk_mov_b32 v[12:13], v[12:13], v[178:179] op_sel:[1,0]
	v_mul_f32_e32 v18, 0.5, v29
	v_pk_add_f32 v[12:13], v[48:49], v[12:13] neg_lo:[0,1] neg_hi:[0,1]
	v_mul_f32_e32 v4, 0.5, v28
	v_pk_mul_f32 v[48:49], v[12:13], v[18:19]
	v_mov_b32_e32 v13, v32
	v_pk_fma_f32 v[50:51], v[50:51], v[48:49], v[48:49] op_sel:[0,1,0] op_sel_hi:[1,0,1]
	v_mov_b32_e32 v48, v49
	v_mov_b32_e32 v49, v18
	v_pk_mul_f32 v[48:49], v[12:13], v[48:49]
	v_pk_add_f32 v[52:53], v[4:5], v[50:51]
	v_mul_f32_e32 v6, 0.5, v6
	v_fma_f32 v53, v28, 0.5, -v50
	v_pk_add_f32 v[28:29], v[48:49], v[48:49] op_sel:[0,1] op_sel_hi:[0,1] neg_lo:[0,1] neg_hi:[0,1]
	v_pk_add_f32 v[48:49], v[6:7], v[28:29] op_sel_hi:[0,1] neg_hi:[0,1]
	v_pk_mul_f32 v[28:29], v[48:49], v[176:177]
	v_pk_mul_f32 v[48:49], v[48:49], v[174:175]
	v_pk_fma_f32 v[28:29], v[52:53], v[174:175], v[28:29]
	v_pk_fma_f32 v[48:49], v[52:53], v[176:177], v[48:49] neg_lo:[0,0,1] neg_hi:[0,0,1]
	v_pk_fma_f32 v[92:93], v[54:55], 0.5, v[56:57] op_sel_hi:[1,0,1]
	v_pk_add_f32 v[50:51], v[48:49], v[28:29] op_sel:[0,1] op_sel_hi:[1,0] neg_lo:[0,1]
	v_pk_add_f32 v[52:53], v[48:49], v[28:29] op_sel:[0,1] op_sel_hi:[1,0]
	v_mov_b32_e32 v17, v93
	v_pk_mul_f32 v[50:51], v[50:51], 0.5 op_sel_hi:[1,0]
	v_pk_mul_f32 v[64:65], v[16:17], s[6:7] op_sel_hi:[1,0]
	v_mul_f32_e32 v4, v12, v50
	v_pk_fma_f32 v[16:17], v[54:55], 0.5, v[56:57] op_sel_hi:[1,0,1] neg_lo:[1,0,0] neg_hi:[1,0,0]
	v_pk_fma_f32 v[54:55], v[12:13], v[50:51], v[4:5] op_sel_hi:[1,1,0] neg_lo:[1,0,0] neg_hi:[1,0,0]
	v_mov_b32_e32 v33, v12
	v_mul_f32_e32 v4, v12, v51
	v_pk_fma_f32 v[12:13], v[32:33], v[50:51], v[4:5] op_sel_hi:[1,1,0]
	v_pk_add_f32 v[28:29], v[28:29], v[48:49] op_sel:[1,0] op_sel_hi:[0,1] neg_lo:[0,1] neg_hi:[0,1]
	v_mov_b32_e32 v53, v29
	v_mov_b32_e32 v54, v12
	v_pk_fma_f32 v[12:13], v[52:53], 0.5, v[12:13] op_sel_hi:[1,0,1] neg_lo:[0,0,1] neg_hi:[0,0,1]
	v_pk_fma_f32 v[88:89], v[52:53], 0.5, v[54:55] op_sel_hi:[1,0,1]
	s_mov_b32 s79, s16
	v_mov_b32_e32 v13, v89
	v_pk_mul_f32 v[68:69], v[12:13], s[6:7] op_sel_hi:[1,0]
	v_pk_fma_f32 v[12:13], v[52:53], 0.5, v[54:55] op_sel_hi:[1,0,1] neg_lo:[1,0,0] neg_hi:[1,0,0]
	v_mov_b32_e32 v4, v83
	s_mov_b32 s17, s19
	v_pk_mul_f32 v[48:49], v[82:83], s[78:79] op_sel_hi:[0,1]
	v_pk_add_f32 v[28:29], v[96:97], v[162:163]
	v_pk_add_f32 v[32:33], v[96:97], v[162:163] neg_lo:[0,1] neg_hi:[0,1]
	v_pk_fma_f32 v[52:53], v[4:5], s[16:17], v[48:49] op_sel_hi:[0,1,1] neg_lo:[0,0,1] neg_hi:[0,0,1]
	v_mul_f32_e32 v12, 0.5, v33
	v_pk_fma_f32 v[50:51], v[4:5], s[16:17], v[48:49] op_sel_hi:[0,1,1]
	v_mov_b32_e32 v33, v29
	v_mul_f32_e32 v6, 0.5, v28
	v_mov_b32_e32 v54, v52
	v_mov_b32_e32 v55, v51
	v_pk_mul_f32 v[28:29], v[32:33], s[44:45]
	v_pk_mov_b32 v[56:57], v[50:51], v[52:53] op_sel:[1,0]
	v_pk_mul_f32 v[32:33], v[54:55], v[28:29] op_sel:[0,1] op_sel_hi:[1,0]
	v_pk_mul_f32 v[28:29], v[54:55], v[28:29]
	v_pk_add_f32 v[32:33], v[32:33], v[32:33] op_sel:[0,1] op_sel_hi:[0,1]
	v_pk_add_f32 v[58:59], v[6:7], v[32:33] op_sel_hi:[0,1] neg_hi:[0,1]
	v_pk_add_f32 v[28:29], v[28:29], v[28:29] op_sel:[0,1] op_sel_hi:[0,1] neg_lo:[0,1] neg_hi:[0,1]
	v_pk_add_f32 v[32:33], v[12:13], v[28:29] op_sel_hi:[0,1] neg_hi:[0,1]
	v_pk_mul_f32 v[28:29], v[32:33], v[166:167]
	v_pk_mul_f32 v[32:33], v[32:33], v[164:165]
	v_pk_fma_f32 v[28:29], v[58:59], v[164:165], v[28:29]
	v_pk_fma_f32 v[32:33], v[58:59], v[166:167], v[32:33] neg_lo:[0,0,1] neg_hi:[0,0,1]
	v_mov_b32_e32 v159, v66
	v_pk_add_f32 v[58:59], v[32:33], v[28:29] op_sel:[0,1] op_sel_hi:[1,0] neg_lo:[0,1]
	v_pk_add_f32 v[70:71], v[32:33], v[28:29] op_sel:[0,1] op_sel_hi:[1,0]
	v_pk_add_f32 v[28:29], v[28:29], v[32:33] op_sel:[1,0] op_sel_hi:[0,1] neg_lo:[0,1] neg_hi:[0,1]
	v_pk_mul_f32 v[58:59], v[58:59], 0.5 op_sel_hi:[1,0]
	v_mov_b32_e32 v71, v29
	v_mul_f32_e32 v6, v52, v58
	v_pk_fma_f32 v[72:73], v[54:55], v[58:59], v[6:7] op_sel_hi:[1,1,0] neg_lo:[1,0,0] neg_hi:[1,0,0]
	v_mul_f32_e32 v6, v52, v59
	v_pk_fma_f32 v[56:57], v[56:57], v[58:59], v[6:7] op_sel_hi:[1,1,0]
	v_sub_f32_e32 v12, v67, v153
	v_mov_b32_e32 v72, v56
	v_pk_fma_f32 v[28:29], v[70:71], 0.5, v[56:57] op_sel_hi:[1,0,1] neg_lo:[0,0,1] neg_hi:[0,0,1]
	v_pk_fma_f32 v[96:97], v[70:71], 0.5, v[72:73] op_sel_hi:[1,0,1]
	v_pk_mov_b32 v[56:57], v[48:49], v[152:153] op_sel:[1,0]
	v_mov_b32_e32 v29, v97
	v_pk_mul_f32 v[62:63], v[28:29], s[6:7] op_sel_hi:[1,0]
	v_pk_add_f32 v[28:29], v[66:67], v[152:153]
	v_pk_add_f32 v[56:57], v[158:159], v[56:57] neg_lo:[0,1] neg_hi:[0,1]
	v_mul_f32_e32 v18, 0.5, v29
	v_pk_mul_f32 v[58:59], v[56:57], v[18:19]
	v_mul_f32_e32 v6, 0.5, v28
	v_pk_fma_f32 v[54:55], v[54:55], v[58:59], v[58:59] op_sel:[0,1,0] op_sel_hi:[1,0,1]
	v_mov_b32_e32 v66, v56
	v_mov_b32_e32 v67, v52
	v_mov_b32_e32 v58, v59
	v_mov_b32_e32 v59, v18
	v_pk_mul_f32 v[58:59], v[66:67], v[58:59]
	v_pk_add_f32 v[66:67], v[6:7], v[54:55]
	v_mul_f32_e32 v12, 0.5, v12
	v_fma_f32 v67, v28, 0.5, -v54
	v_pk_add_f32 v[28:29], v[58:59], v[58:59] op_sel:[0,1] op_sel_hi:[0,1] neg_lo:[0,1] neg_hi:[0,1]
	v_pk_add_f32 v[54:55], v[12:13], v[28:29] op_sel_hi:[0,1] neg_hi:[0,1]
	v_pk_mul_f32 v[28:29], v[54:55], v[156:157]
	v_pk_mul_f32 v[54:55], v[54:55], v[154:155]
	v_pk_fma_f32 v[32:33], v[70:71], 0.5, v[72:73] op_sel_hi:[1,0,1] neg_lo:[1,0,0] neg_hi:[1,0,0]
	v_pk_fma_f32 v[58:59], v[66:67], v[154:155], v[28:29] neg_lo:[0,0,1] neg_hi:[0,0,1]
	v_pk_fma_f32 v[28:29], v[66:67], v[154:155], v[28:29]
	v_pk_fma_f32 v[70:71], v[66:67], v[156:157], v[54:55]
	v_pk_fma_f32 v[54:55], v[66:67], v[156:157], v[54:55] neg_lo:[0,0,1] neg_hi:[0,0,1]
	v_pk_add_f32 v[72:73], v[58:59], v[28:29] op_sel:[0,1] op_sel_hi:[1,0]
	v_pk_add_f32 v[66:67], v[70:71], v[54:55] op_sel_hi:[0,1] neg_lo:[0,1] neg_hi:[0,1]
	v_pk_add_f32 v[28:29], v[58:59], v[28:29] op_sel_hi:[0,1] neg_lo:[0,1] neg_hi:[0,1]
	v_pk_add_f32 v[54:55], v[70:71], v[54:55] op_sel:[0,1] op_sel_hi:[1,0]
	v_mov_b32_e32 v73, v67
	v_mov_b32_e32 v55, v29
	v_pk_mul_f32 v[28:29], v[54:55], 0.5 op_sel_hi:[1,0]
	v_mov_b32_e32 v133, v84
	v_pk_mul_f32 v[54:55], v[52:53], v[28:29] op_sel:[0,1] op_sel_hi:[0,0]
	v_pk_fma_f32 v[58:59], v[56:57], v[28:29], v[54:55] op_sel_hi:[0,1,1]
	v_pk_fma_f32 v[28:29], v[56:57], v[28:29], v[54:55] op_sel_hi:[0,1,1] neg_hi:[0,0,1]
	v_pk_fma_f32 v[54:55], v[72:73], 0.5, v[58:59] op_sel_hi:[1,0,1] neg_lo:[0,0,1] neg_hi:[0,0,1]
	v_pk_fma_f32 v[66:67], v[72:73], 0.5, v[28:29] op_sel_hi:[1,0,1]
	v_pk_add_f32 v[56:57], v[60:61], v[134:135] neg_lo:[0,1] neg_hi:[0,1]
	v_mov_b32_e32 v55, v67
	v_pk_mul_f32 v[90:91], v[54:55], s[6:7] op_sel_hi:[1,0]
	v_pk_add_f32 v[54:55], v[134:135], v[60:61]
	v_mul_f32_e32 v12, 0.5, v57
	v_mov_b32_e32 v57, v55
	v_mul_f32_e32 v6, 0.5, v54
	v_pk_mov_b32 v[58:59], v[52:53], v[50:51] op_sel:[1,0]
	v_pk_mul_f32 v[54:55], v[56:57], s[44:45]
	v_pk_fma_f32 v[28:29], v[72:73], 0.5, v[28:29] op_sel_hi:[1,0,1] neg_lo:[1,0,0] neg_hi:[1,0,0]
	v_pk_mul_f32 v[56:57], v[58:59], v[54:55] op_sel:[0,1] op_sel_hi:[1,0]
	v_pk_mul_f32 v[54:55], v[58:59], v[54:55]
	v_pk_add_f32 v[56:57], v[56:57], v[56:57] op_sel:[0,1] op_sel_hi:[0,1]
	v_pk_add_f32 v[60:61], v[6:7], v[56:57] op_sel_hi:[0,1] neg_hi:[0,1]
	v_pk_add_f32 v[54:55], v[54:55], v[54:55] op_sel:[0,1] op_sel_hi:[0,1] neg_lo:[0,1] neg_hi:[0,1]
	v_pk_add_f32 v[56:57], v[12:13], v[54:55] op_sel_hi:[0,1] neg_hi:[0,1]
	v_pk_mul_f32 v[54:55], v[56:57], v[142:143]
	v_pk_mul_f32 v[56:57], v[56:57], v[140:141]
	v_pk_fma_f32 v[54:55], v[60:61], v[140:141], v[54:55]
	v_pk_fma_f32 v[56:57], v[60:61], v[142:143], v[56:57] neg_lo:[0,0,1] neg_hi:[0,0,1]
	v_mov_b32_e32 v51, v53
	v_pk_add_f32 v[60:61], v[56:57], v[54:55] op_sel:[0,1] op_sel_hi:[1,0] neg_lo:[0,1]
	v_pk_add_f32 v[70:71], v[56:57], v[54:55] op_sel:[0,1] op_sel_hi:[1,0]
	v_pk_add_f32 v[54:55], v[54:55], v[56:57] op_sel:[1,0] op_sel_hi:[0,1] neg_lo:[0,1] neg_hi:[0,1]
	v_pk_mul_f32 v[60:61], v[60:61], 0.5 op_sel_hi:[1,0]
	v_mov_b32_e32 v71, v55
	v_mul_f32_e32 v6, v53, v60
	v_pk_fma_f32 v[72:73], v[58:59], v[60:61], v[6:7] op_sel_hi:[1,1,0] neg_lo:[1,0,0] neg_hi:[1,0,0]
	v_mul_f32_e32 v6, v53, v61
	v_pk_fma_f32 v[50:51], v[50:51], v[60:61], v[6:7] op_sel_hi:[1,1,0]
	v_pk_add_f32 v[54:55], v[118:119], v[84:85]
	v_mov_b32_e32 v72, v50
	v_mov_b32_e32 v49, v118
	v_pk_fma_f32 v[50:51], v[70:71], 0.5, v[50:51] op_sel_hi:[1,0,1] neg_lo:[0,0,1] neg_hi:[0,0,1]
	v_pk_fma_f32 v[60:61], v[70:71], 0.5, v[72:73] op_sel_hi:[1,0,1]
	v_mul_f32_e32 v18, 0.5, v55
	v_pk_add_f32 v[48:49], v[132:133], v[48:49] neg_lo:[0,1] neg_hi:[0,1]
	v_mov_b32_e32 v51, v61
	v_pk_mul_f32 v[56:57], v[48:49], v[18:19]
	v_pk_mul_f32 v[94:95], v[50:51], s[6:7] op_sel_hi:[1,0]
	v_pk_fma_f32 v[50:51], v[70:71], 0.5, v[72:73] op_sel_hi:[1,0,1] neg_lo:[1,0,0] neg_hi:[1,0,0]
	v_mul_f32_e32 v6, 0.5, v54
	v_pk_fma_f32 v[58:59], v[58:59], v[56:57], v[56:57] op_sel:[0,1,0] op_sel_hi:[1,0,1]
	v_mov_b32_e32 v70, v48
	v_mov_b32_e32 v71, v53
	v_mov_b32_e32 v56, v57
	v_mov_b32_e32 v57, v18
	v_sub_f32_e32 v12, v85, v119
	v_pk_mul_f32 v[56:57], v[70:71], v[56:57]
	v_pk_add_f32 v[70:71], v[6:7], v[58:59]
	v_mul_f32_e32 v12, 0.5, v12
	v_fma_f32 v71, v54, 0.5, -v58
	v_pk_add_f32 v[54:55], v[56:57], v[56:57] op_sel:[0,1] op_sel_hi:[0,1] neg_lo:[0,1] neg_hi:[0,1]
	v_pk_add_f32 v[56:57], v[12:13], v[54:55] op_sel_hi:[0,1] neg_hi:[0,1]
	v_pk_mul_f32 v[54:55], v[56:57], v[126:127]
	v_pk_mul_f32 v[56:57], v[56:57], v[124:125]
	v_pk_fma_f32 v[58:59], v[70:71], v[124:125], v[54:55] neg_lo:[0,0,1] neg_hi:[0,0,1]
	v_pk_fma_f32 v[54:55], v[70:71], v[124:125], v[54:55]
	v_pk_fma_f32 v[72:73], v[70:71], v[126:127], v[56:57]
	v_pk_fma_f32 v[56:57], v[70:71], v[126:127], v[56:57] neg_lo:[0,0,1] neg_hi:[0,0,1]
	v_pk_add_f32 v[70:71], v[58:59], v[54:55] op_sel:[0,1] op_sel_hi:[1,0]
	v_pk_add_f32 v[74:75], v[72:73], v[56:57] op_sel_hi:[0,1] neg_lo:[0,1] neg_hi:[0,1]
	v_pk_add_f32 v[54:55], v[58:59], v[54:55] op_sel_hi:[0,1] neg_lo:[0,1] neg_hi:[0,1]
	v_pk_add_f32 v[56:57], v[72:73], v[56:57] op_sel:[0,1] op_sel_hi:[1,0]
	v_mov_b32_e32 v71, v75
	v_mov_b32_e32 v57, v55
	v_pk_mul_f32 v[54:55], v[56:57], 0.5 op_sel_hi:[1,0]
	s_mov_b32 s78, s11
	v_pk_mul_f32 v[52:53], v[52:53], v[54:55] op_sel:[1,1] op_sel_hi:[1,0]
	s_mov_b32 s79, s8
	v_pk_fma_f32 v[56:57], v[48:49], v[54:55], v[52:53] op_sel_hi:[0,1,1]
	v_pk_fma_f32 v[48:49], v[48:49], v[54:55], v[52:53] op_sel_hi:[0,1,1] neg_hi:[0,0,1]
	s_nop 0
	v_pk_fma_f32 v[52:53], v[70:71], 0.5, v[56:57] op_sel_hi:[1,0,1] neg_lo:[0,0,1] neg_hi:[0,0,1]
	v_pk_fma_f32 v[84:85], v[70:71], 0.5, v[48:49] op_sel_hi:[1,0,1]
	s_mov_b32 s9, s11
	v_mov_b32_e32 v53, v85
	v_pk_mul_f32 v[80:81], v[52:53], s[6:7] op_sel_hi:[1,0]
	v_pk_mul_f32 v[118:119], v[82:83], s[78:79] op_sel_hi:[0,1]
	v_pk_add_f32 v[52:53], v[86:87], v[112:113]
	v_pk_add_f32 v[54:55], v[86:87], v[112:113] neg_lo:[0,1] neg_hi:[0,1]
	v_pk_fma_f32 v[58:59], v[4:5], s[8:9], v[118:119] op_sel_hi:[0,1,1] neg_lo:[0,0,1] neg_hi:[0,0,1]
	v_mul_f32_e32 v12, 0.5, v55
	v_pk_fma_f32 v[72:73], v[4:5], s[8:9], v[118:119] op_sel_hi:[0,1,1]
	v_mov_b32_e32 v55, v53
	v_mul_f32_e32 v6, 0.5, v52
	v_mov_b32_e32 v56, v58
	v_mov_b32_e32 v57, v73
	v_pk_mul_f32 v[52:53], v[54:55], s[44:45]
	v_pk_fma_f32 v[48:49], v[70:71], 0.5, v[48:49] op_sel_hi:[1,0,1] neg_lo:[1,0,0] neg_hi:[1,0,0]
	v_pk_mul_f32 v[54:55], v[56:57], v[52:53] op_sel:[0,1] op_sel_hi:[1,0]
	v_pk_mul_f32 v[52:53], v[56:57], v[52:53]
	v_pk_add_f32 v[54:55], v[54:55], v[54:55] op_sel:[0,1] op_sel_hi:[0,1]
	v_pk_add_f32 v[74:75], v[6:7], v[54:55] op_sel_hi:[0,1] neg_hi:[0,1]
	v_pk_add_f32 v[52:53], v[52:53], v[52:53] op_sel:[0,1] op_sel_hi:[0,1] neg_lo:[0,1] neg_hi:[0,1]
	v_pk_add_f32 v[54:55], v[12:13], v[52:53] op_sel_hi:[0,1] neg_hi:[0,1]
	v_pk_mul_f32 v[52:53], v[54:55], v[116:117]
	v_pk_mul_f32 v[54:55], v[54:55], v[114:115]
	v_pk_fma_f32 v[52:53], v[74:75], v[114:115], v[52:53]
	v_pk_fma_f32 v[54:55], v[74:75], v[116:117], v[54:55] neg_lo:[0,0,1] neg_hi:[0,0,1]
	v_pk_mov_b32 v[70:71], v[72:73], v[58:59] op_sel:[1,0]
	v_pk_add_f32 v[74:75], v[54:55], v[52:53] op_sel:[0,1] op_sel_hi:[1,0] neg_lo:[0,1]
	v_pk_add_f32 v[76:77], v[54:55], v[52:53] op_sel:[0,1] op_sel_hi:[1,0]
	v_pk_add_f32 v[52:53], v[52:53], v[54:55] op_sel:[1,0] op_sel_hi:[0,1] neg_lo:[0,1] neg_hi:[0,1]
	v_pk_mul_f32 v[74:75], v[74:75], 0.5 op_sel_hi:[1,0]
	v_mov_b32_e32 v77, v53
	v_mul_f32_e32 v6, v58, v74
	v_pk_fma_f32 v[112:113], v[56:57], v[74:75], v[6:7] op_sel_hi:[1,1,0] neg_lo:[1,0,0] neg_hi:[1,0,0]
	v_mul_f32_e32 v6, v58, v75
	v_pk_fma_f32 v[70:71], v[70:71], v[74:75], v[6:7] op_sel_hi:[1,1,0]
	v_pk_add_f32 v[54:55], v[34:35], v[110:111]
	v_mov_b32_e32 v112, v70
	v_pk_fma_f32 v[52:53], v[76:77], 0.5, v[70:71] op_sel_hi:[1,0,1] neg_lo:[0,0,1] neg_hi:[0,0,1]
	v_pk_fma_f32 v[86:87], v[76:77], 0.5, v[112:113] op_sel_hi:[1,0,1]
	v_sub_f32_e32 v12, v35, v111
	v_mov_b32_e32 v53, v87
	v_pk_mul_f32 v[78:79], v[52:53], s[6:7] op_sel_hi:[1,0]
	v_mul_f32_e32 v52, 0xbe47c5c2, v83
	v_mov_b32_e32 v53, v34
	v_pk_mov_b32 v[34:35], v[118:119], v[110:111] op_sel:[1,0]
	v_mul_f32_e32 v18, 0.5, v55
	v_pk_add_f32 v[34:35], v[52:53], v[34:35] neg_lo:[0,1] neg_hi:[0,1]
	v_mov_b32_e32 v71, v58
	v_pk_mul_f32 v[52:53], v[34:35], v[18:19]
	v_mov_b32_e32 v70, v34
	v_pk_fma_f32 v[56:57], v[56:57], v[52:53], v[52:53] op_sel:[0,1,0] op_sel_hi:[1,0,1]
	v_mov_b32_e32 v52, v53
	v_mov_b32_e32 v53, v18
	v_mul_f32_e32 v6, 0.5, v54
	v_pk_mul_f32 v[52:53], v[70:71], v[52:53]
	v_cvt_f32_f16_e32 v70, v46
	v_cvt_f32_f16_e32 v71, v47
	v_cvt_f32_f16_sdwa v47, v47 dst_sel:DWORD dst_unused:UNUSED_PAD src0_sel:WORD_1
	v_cvt_f32_f16_sdwa v46, v46 dst_sel:DWORD dst_unused:UNUSED_PAD src0_sel:WORD_1
	v_pk_fma_f32 v[74:75], v[76:77], 0.5, v[112:113] op_sel_hi:[1,0,1] neg_lo:[1,0,0] neg_hi:[1,0,0]
	v_mul_f32_e32 v12, 0.5, v12
	v_pk_add_f32 v[76:77], v[6:7], v[56:57]
	v_pk_add_f32 v[52:53], v[52:53], v[52:53] op_sel:[0,1] op_sel_hi:[0,1] neg_lo:[0,1] neg_hi:[0,1]
	v_fma_f32 v77, v54, 0.5, -v56
	v_pk_add_f32 v[54:55], v[12:13], v[52:53] op_sel_hi:[0,1] neg_hi:[0,1]
	v_pk_mul_f32 v[52:53], v[54:55], v[46:47]
	v_pk_mul_f32 v[54:55], v[54:55], v[70:71]
	v_pk_fma_f32 v[56:57], v[76:77], v[70:71], v[52:53] neg_lo:[0,0,1] neg_hi:[0,0,1]
	v_pk_fma_f32 v[52:53], v[76:77], v[70:71], v[52:53]
	v_pk_fma_f32 v[70:71], v[76:77], v[46:47], v[54:55]
	v_pk_fma_f32 v[46:47], v[76:77], v[46:47], v[54:55] neg_lo:[0,0,1] neg_hi:[0,0,1]
	v_pk_add_f32 v[54:55], v[56:57], v[52:53] op_sel:[0,1] op_sel_hi:[1,0]
	v_pk_add_f32 v[76:77], v[70:71], v[46:47] op_sel_hi:[0,1] neg_lo:[0,1] neg_hi:[0,1]
	v_pk_add_f32 v[52:53], v[56:57], v[52:53] op_sel_hi:[0,1] neg_lo:[0,1] neg_hi:[0,1]
	v_pk_add_f32 v[46:47], v[70:71], v[46:47] op_sel:[0,1] op_sel_hi:[1,0]
	v_mov_b32_e32 v55, v77
	v_mov_b32_e32 v47, v53
	v_pk_mul_f32 v[46:47], v[46:47], 0.5 op_sel_hi:[1,0]
	s_mov_b32 s25, s27
	v_pk_mul_f32 v[52:53], v[58:59], v[46:47] op_sel:[0,1] op_sel_hi:[0,0]
	v_pk_fma_f32 v[56:57], v[34:35], v[46:47], v[52:53] op_sel_hi:[0,1,1]
	v_pk_fma_f32 v[46:47], v[34:35], v[46:47], v[52:53] op_sel_hi:[0,1,1] neg_hi:[0,0,1]
	s_nop 0
	v_pk_fma_f32 v[52:53], v[54:55], 0.5, v[56:57] op_sel_hi:[1,0,1] neg_lo:[0,0,1] neg_hi:[0,0,1]
	v_pk_fma_f32 v[34:35], v[54:55], 0.5, v[46:47] op_sel_hi:[1,0,1]
	s_mov_b32 s78, s27
	v_mov_b32_e32 v53, v35
	v_pk_mul_f32 v[136:137], v[52:53], s[6:7] op_sel_hi:[1,0]
	v_pk_fma_f32 v[52:53], v[54:55], 0.5, v[46:47] op_sel_hi:[1,0,1] neg_lo:[1,0,0] neg_hi:[1,0,0]
	s_mov_b32 s79, s24
	v_pk_mul_f32 v[46:47], v[82:83], s[24:25] op_sel_hi:[0,1]
	v_pk_add_f32 v[54:55], v[108:109], v[40:41]
	v_pk_add_f32 v[40:41], v[40:41], v[108:109] neg_lo:[0,1] neg_hi:[0,1]
	v_pk_fma_f32 v[108:109], v[4:5], s[78:79], v[46:47] op_sel_hi:[0,1,1] neg_lo:[0,0,1] neg_hi:[0,0,1]
	v_mul_f32_e32 v12, 0.5, v41
	v_pk_fma_f32 v[70:71], v[4:5], s[78:79], v[46:47] op_sel_hi:[0,1,1]
	v_mov_b32_e32 v41, v55
	v_mov_b32_e32 v56, v108
	v_mov_b32_e32 v57, v71
	v_pk_mul_f32 v[40:41], v[40:41], s[44:45]
	v_mul_f32_e32 v6, 0.5, v54
	v_pk_mul_f32 v[54:55], v[56:57], v[40:41] op_sel:[0,1] op_sel_hi:[1,0]
	v_cvt_f32_f16_sdwa v76, v36 dst_sel:DWORD dst_unused:UNUSED_PAD src0_sel:WORD_1
	v_cvt_f32_f16_e32 v77, v37
	v_cvt_f32_f16_sdwa v37, v37 dst_sel:DWORD dst_unused:UNUSED_PAD src0_sel:WORD_1
	v_cvt_f32_f16_e32 v36, v36
	v_pk_mul_f32 v[40:41], v[56:57], v[40:41]
	v_pk_add_f32 v[54:55], v[54:55], v[54:55] op_sel:[0,1] op_sel_hi:[0,1]
	v_pk_add_f32 v[112:113], v[6:7], v[54:55] op_sel_hi:[0,1] neg_hi:[0,1]
	s_nop 0
	v_pk_add_f32 v[40:41], v[40:41], v[40:41] op_sel:[0,1] op_sel_hi:[0,1] neg_lo:[0,1] neg_hi:[0,1]
	v_pk_add_f32 v[54:55], v[12:13], v[40:41] op_sel_hi:[0,1] neg_hi:[0,1]
	v_pk_mul_f32 v[40:41], v[54:55], v[36:37]
	v_pk_mul_f32 v[54:55], v[54:55], v[76:77]
	v_pk_fma_f32 v[40:41], v[112:113], v[76:77], v[40:41]
	v_pk_fma_f32 v[36:37], v[112:113], v[36:37], v[54:55] neg_lo:[0,0,1] neg_hi:[0,0,1]
	v_pk_mov_b32 v[110:111], v[70:71], v[108:109] op_sel:[1,0]
	v_pk_add_f32 v[54:55], v[36:37], v[40:41] op_sel:[0,1] op_sel_hi:[1,0] neg_lo:[0,1]
	v_pk_add_f32 v[76:77], v[36:37], v[40:41] op_sel:[0,1] op_sel_hi:[1,0]
	v_pk_add_f32 v[36:37], v[40:41], v[36:37] op_sel:[1,0] op_sel_hi:[0,1] neg_lo:[0,1] neg_hi:[0,1]
	v_pk_mul_f32 v[54:55], v[54:55], 0.5 op_sel_hi:[1,0]
	v_mov_b32_e32 v77, v37
	v_mul_f32_e32 v4, v108, v54
	v_pk_fma_f32 v[112:113], v[56:57], v[54:55], v[4:5] op_sel_hi:[1,1,0] neg_lo:[1,0,0] neg_hi:[1,0,0]
	v_mul_f32_e32 v4, v108, v55
	v_pk_fma_f32 v[54:55], v[110:111], v[54:55], v[4:5] op_sel_hi:[1,1,0]
	v_sub_f32_e32 v6, v45, v105
	v_mov_b32_e32 v112, v54
	v_pk_fma_f32 v[40:41], v[76:77], 0.5, v[54:55] op_sel_hi:[1,0,1] neg_lo:[0,0,1] neg_hi:[0,0,1]
	v_pk_fma_f32 v[36:37], v[76:77], 0.5, v[112:113] op_sel_hi:[1,0,1]
	v_pk_add_f32 v[54:55], v[104:105], v[44:45]
	v_mov_b32_e32 v41, v37
	v_pk_mul_f32 v[130:131], v[40:41], s[6:7] op_sel_hi:[1,0]
	v_mul_f32_e32 v40, 0xbf54db31, v83
	v_mov_b32_e32 v41, v44
	v_pk_mov_b32 v[44:45], v[46:47], v[104:105] op_sel:[1,0]
	v_mul_f32_e32 v18, 0.5, v55
	v_pk_add_f32 v[40:41], v[40:41], v[44:45] neg_lo:[0,1] neg_hi:[0,1]
	v_mov_b32_e32 v105, v108
	v_pk_mul_f32 v[44:45], v[40:41], v[18:19]
	v_mov_b32_e32 v104, v40
	v_pk_fma_f32 v[56:57], v[56:57], v[44:45], v[44:45] op_sel:[0,1,0] op_sel_hi:[1,0,1]
	v_mov_b32_e32 v44, v45
	v_mov_b32_e32 v45, v18
	v_mul_f32_e32 v4, 0.5, v54
	v_pk_mul_f32 v[44:45], v[104:105], v[44:45]
	v_cvt_f32_f16_e32 v104, v26
	v_cvt_f32_f16_e32 v105, v27
	v_cvt_f32_f16_sdwa v27, v27 dst_sel:DWORD dst_unused:UNUSED_PAD src0_sel:WORD_1
	v_cvt_f32_f16_sdwa v26, v26 dst_sel:DWORD dst_unused:UNUSED_PAD src0_sel:WORD_1
	v_mul_f32_e32 v6, 0.5, v6
	v_pk_add_f32 v[110:111], v[4:5], v[56:57]
	v_pk_add_f32 v[44:45], v[44:45], v[44:45] op_sel:[0,1] op_sel_hi:[0,1] neg_lo:[0,1] neg_hi:[0,1]
	v_fma_f32 v111, v54, 0.5, -v56
	v_pk_add_f32 v[54:55], v[6:7], v[44:45] op_sel_hi:[0,1] neg_hi:[0,1]
	v_pk_mul_f32 v[44:45], v[54:55], v[26:27]
	v_pk_mul_f32 v[54:55], v[54:55], v[104:105]
	v_pk_fma_f32 v[56:57], v[110:111], v[104:105], v[44:45] neg_lo:[0,0,1] neg_hi:[0,0,1]
	v_pk_fma_f32 v[44:45], v[110:111], v[104:105], v[44:45]
	v_pk_fma_f32 v[104:105], v[110:111], v[26:27], v[54:55]
	v_pk_fma_f32 v[26:27], v[110:111], v[26:27], v[54:55] neg_lo:[0,0,1] neg_hi:[0,0,1]
	v_pk_add_f32 v[54:55], v[56:57], v[44:45] op_sel:[0,1] op_sel_hi:[1,0]
	v_pk_add_f32 v[110:111], v[104:105], v[26:27] op_sel_hi:[0,1] neg_lo:[0,1] neg_hi:[0,1]
	v_pk_add_f32 v[44:45], v[56:57], v[44:45] op_sel_hi:[0,1] neg_lo:[0,1] neg_hi:[0,1]
	v_pk_add_f32 v[26:27], v[104:105], v[26:27] op_sel:[0,1] op_sel_hi:[1,0]
	v_mov_b32_e32 v55, v111
	v_mov_b32_e32 v27, v45
	v_pk_mul_f32 v[26:27], v[26:27], 0.5 op_sel_hi:[1,0]
	v_mov_b32_e32 v47, v102
	v_pk_mul_f32 v[44:45], v[108:109], v[26:27] op_sel:[0,1] op_sel_hi:[0,0]
	v_pk_fma_f32 v[56:57], v[40:41], v[26:27], v[44:45] op_sel_hi:[0,1,1]
	v_pk_fma_f32 v[40:41], v[40:41], v[26:27], v[44:45] op_sel_hi:[0,1,1] neg_hi:[0,0,1]
	v_pk_fma_f32 v[44:45], v[54:55], 0.5, v[56:57] op_sel_hi:[1,0,1] neg_lo:[0,0,1] neg_hi:[0,0,1]
	v_pk_fma_f32 v[26:27], v[54:55], 0.5, v[40:41] op_sel_hi:[1,0,1]
	v_pk_fma_f32 v[56:57], v[54:55], 0.5, v[40:41] op_sel_hi:[1,0,1] neg_lo:[1,0,0] neg_hi:[1,0,0]
	v_pk_add_f32 v[40:41], v[106:107], v[42:43]
	v_pk_add_f32 v[42:43], v[42:43], v[106:107] neg_lo:[0,1] neg_hi:[0,1]
	v_mov_b32_e32 v45, v27
	v_mul_f32_e32 v6, 0.5, v43
	v_mov_b32_e32 v43, v41
	v_pk_mul_f32 v[120:121], v[44:45], s[6:7] op_sel_hi:[1,0]
	v_mul_f32_e32 v4, 0.5, v40
	v_pk_mov_b32 v[44:45], v[108:109], v[70:71] op_sel:[1,0]
	v_pk_mul_f32 v[40:41], v[42:43], s[44:45]
	v_cvt_f32_f16_sdwa v54, v20 dst_sel:DWORD dst_unused:UNUSED_PAD src0_sel:WORD_1
	v_pk_mul_f32 v[42:43], v[44:45], v[40:41] op_sel:[0,1] op_sel_hi:[1,0]
	v_cvt_f32_f16_e32 v55, v21
	v_cvt_f32_f16_sdwa v21, v21 dst_sel:DWORD dst_unused:UNUSED_PAD src0_sel:WORD_1
	v_cvt_f32_f16_e32 v20, v20
	v_pk_mul_f32 v[40:41], v[44:45], v[40:41]
	v_pk_add_f32 v[42:43], v[42:43], v[42:43] op_sel:[0,1] op_sel_hi:[0,1]
	v_pk_add_f32 v[104:105], v[4:5], v[42:43] op_sel_hi:[0,1] neg_hi:[0,1]
	s_nop 0
	v_pk_add_f32 v[40:41], v[40:41], v[40:41] op_sel:[0,1] op_sel_hi:[0,1] neg_lo:[0,1] neg_hi:[0,1]
	v_pk_add_f32 v[42:43], v[6:7], v[40:41] op_sel_hi:[0,1] neg_hi:[0,1]
	v_pk_mul_f32 v[40:41], v[42:43], v[20:21]
	v_pk_mul_f32 v[42:43], v[42:43], v[54:55]
	v_pk_fma_f32 v[40:41], v[104:105], v[54:55], v[40:41]
	v_pk_fma_f32 v[20:21], v[104:105], v[20:21], v[42:43] neg_lo:[0,0,1] neg_hi:[0,0,1]
	v_mov_b32_e32 v71, v109
	v_pk_add_f32 v[42:43], v[20:21], v[40:41] op_sel:[0,1] op_sel_hi:[1,0] neg_lo:[0,1]
	v_pk_add_f32 v[54:55], v[20:21], v[40:41] op_sel:[0,1] op_sel_hi:[1,0]
	v_pk_add_f32 v[20:21], v[40:41], v[20:21] op_sel:[1,0] op_sel_hi:[0,1] neg_lo:[0,1] neg_hi:[0,1]
	v_pk_mul_f32 v[42:43], v[42:43], 0.5 op_sel_hi:[1,0]
	v_mov_b32_e32 v55, v21
	v_mul_f32_e32 v4, v109, v42
	v_pk_fma_f32 v[104:105], v[44:45], v[42:43], v[4:5] op_sel_hi:[1,1,0] neg_lo:[1,0,0] neg_hi:[1,0,0]
	v_mul_f32_e32 v4, v109, v43
	v_pk_fma_f32 v[42:43], v[70:71], v[42:43], v[4:5] op_sel_hi:[1,1,0]
	v_sub_f32_e32 v6, v23, v103
	v_mov_b32_e32 v104, v42
	v_pk_fma_f32 v[40:41], v[54:55], 0.5, v[42:43] op_sel_hi:[1,0,1] neg_lo:[0,0,1] neg_hi:[0,0,1]
	v_pk_fma_f32 v[20:21], v[54:55], 0.5, v[104:105] op_sel_hi:[1,0,1]
	v_pk_add_f32 v[42:43], v[102:103], v[22:23]
	v_mov_b32_e32 v41, v21
	v_pk_mul_f32 v[128:129], v[40:41], s[6:7] op_sel_hi:[1,0]
	v_mul_f32_e32 v40, 0xbf0e39da, v83
	v_mov_b32_e32 v41, v22
	v_mul_f32_e32 v18, 0.5, v43
	v_pk_add_f32 v[22:23], v[40:41], v[46:47] neg_lo:[0,1] neg_hi:[0,1]
	v_mov_b32_e32 v47, v109
	v_pk_mul_f32 v[40:41], v[22:23], v[18:19]
	v_mov_b32_e32 v46, v22
	v_pk_fma_f32 v[44:45], v[44:45], v[40:41], v[40:41] op_sel:[0,1,0] op_sel_hi:[1,0,1]
	v_mov_b32_e32 v40, v41
	v_mov_b32_e32 v41, v18
	v_mul_f32_e32 v4, 0.5, v42
	v_pk_mul_f32 v[40:41], v[46:47], v[40:41]
	v_cvt_f32_f16_e32 v46, v10
	v_cvt_f32_f16_e32 v47, v11
	v_cvt_f32_f16_sdwa v11, v11 dst_sel:DWORD dst_unused:UNUSED_PAD src0_sel:WORD_1
	v_cvt_f32_f16_sdwa v10, v10 dst_sel:DWORD dst_unused:UNUSED_PAD src0_sel:WORD_1
	v_pk_fma_f32 v[70:71], v[54:55], 0.5, v[104:105] op_sel_hi:[1,0,1] neg_lo:[1,0,0] neg_hi:[1,0,0]
	v_mul_f32_e32 v6, 0.5, v6
	v_pk_add_f32 v[54:55], v[4:5], v[44:45]
	v_pk_add_f32 v[40:41], v[40:41], v[40:41] op_sel:[0,1] op_sel_hi:[0,1] neg_lo:[0,1] neg_hi:[0,1]
	v_fma_f32 v55, v42, 0.5, -v44
	v_pk_add_f32 v[42:43], v[6:7], v[40:41] op_sel_hi:[0,1] neg_hi:[0,1]
	v_pk_mul_f32 v[40:41], v[42:43], v[10:11]
	v_pk_mul_f32 v[42:43], v[42:43], v[46:47]
	v_pk_fma_f32 v[44:45], v[54:55], v[46:47], v[40:41] neg_lo:[0,0,1] neg_hi:[0,0,1]
	v_pk_fma_f32 v[40:41], v[54:55], v[46:47], v[40:41]
	v_pk_fma_f32 v[46:47], v[54:55], v[10:11], v[42:43]
	v_pk_fma_f32 v[10:11], v[54:55], v[10:11], v[42:43] neg_lo:[0,0,1] neg_hi:[0,0,1]
	v_pk_add_f32 v[42:43], v[44:45], v[40:41] op_sel:[0,1] op_sel_hi:[1,0]
	v_pk_add_f32 v[54:55], v[46:47], v[10:11] op_sel_hi:[0,1] neg_lo:[0,1] neg_hi:[0,1]
	v_pk_add_f32 v[40:41], v[44:45], v[40:41] op_sel_hi:[0,1] neg_lo:[0,1] neg_hi:[0,1]
	v_pk_add_f32 v[10:11], v[46:47], v[10:11] op_sel:[0,1] op_sel_hi:[1,0]
	v_mov_b32_e32 v43, v55
	v_mov_b32_e32 v11, v41
	v_pk_mul_f32 v[10:11], v[10:11], 0.5 op_sel_hi:[1,0]
	v_mov_b32_e32 v119, v98
	v_pk_mul_f32 v[40:41], v[108:109], v[10:11] op_sel:[1,1] op_sel_hi:[1,0]
	v_pk_fma_f32 v[76:77], v[76:77], 0.5, v[112:113] op_sel_hi:[1,0,1] neg_lo:[1,0,0] neg_hi:[1,0,0]
	v_pk_fma_f32 v[44:45], v[22:23], v[10:11], v[40:41] op_sel_hi:[0,1,1]
	v_pk_fma_f32 v[10:11], v[22:23], v[10:11], v[40:41] op_sel_hi:[0,1,1] neg_hi:[0,0,1]
	v_pk_fma_f32 v[22:23], v[42:43], 0.5, v[44:45] op_sel_hi:[1,0,1] neg_lo:[0,0,1] neg_hi:[0,0,1]
	v_pk_fma_f32 v[40:41], v[42:43], 0.5, v[10:11] op_sel_hi:[1,0,1]
	v_pk_fma_f32 v[54:55], v[42:43], 0.5, v[10:11] op_sel_hi:[1,0,1] neg_lo:[1,0,0] neg_hi:[1,0,0]
	v_pk_add_f32 v[10:11], v[100:101], v[14:15]
	v_pk_add_f32 v[14:15], v[14:15], v[100:101] neg_lo:[0,1] neg_hi:[0,1]
	v_mov_b32_e32 v23, v41
	v_mul_f32_e32 v6, 0.5, v15
	v_mov_b32_e32 v15, v11
	v_pk_mul_f32 v[150:151], v[22:23], s[6:7] op_sel_hi:[1,0]
	v_mul_f32_e32 v4, 0.5, v10
	v_pk_mov_b32 v[22:23], v[58:59], v[72:73] op_sel:[1,0]
	v_pk_mul_f32 v[10:11], v[14:15], s[44:45]
	v_cvt_f32_f16_sdwa v42, v8 dst_sel:DWORD dst_unused:UNUSED_PAD src0_sel:WORD_1
	v_pk_mul_f32 v[14:15], v[22:23], v[10:11] op_sel:[0,1] op_sel_hi:[1,0]
	v_cvt_f32_f16_e32 v43, v9
	v_cvt_f32_f16_sdwa v9, v9 dst_sel:DWORD dst_unused:UNUSED_PAD src0_sel:WORD_1
	v_cvt_f32_f16_e32 v8, v8
	v_pk_mul_f32 v[10:11], v[22:23], v[10:11]
	v_pk_add_f32 v[14:15], v[14:15], v[14:15] op_sel:[0,1] op_sel_hi:[0,1]
	v_pk_add_f32 v[44:45], v[4:5], v[14:15] op_sel_hi:[0,1] neg_hi:[0,1]
	s_nop 0
	v_pk_add_f32 v[10:11], v[10:11], v[10:11] op_sel:[0,1] op_sel_hi:[0,1] neg_lo:[0,1] neg_hi:[0,1]
	v_pk_add_f32 v[14:15], v[6:7], v[10:11] op_sel_hi:[0,1] neg_hi:[0,1]
	v_pk_mul_f32 v[10:11], v[14:15], v[8:9]
	v_pk_mul_f32 v[14:15], v[14:15], v[42:43]
	v_pk_fma_f32 v[10:11], v[44:45], v[42:43], v[10:11]
	v_pk_fma_f32 v[8:9], v[44:45], v[8:9], v[14:15] neg_lo:[0,0,1] neg_hi:[0,0,1]
	v_mov_b32_e32 v73, v59
	v_pk_add_f32 v[14:15], v[8:9], v[10:11] op_sel:[0,1] op_sel_hi:[1,0] neg_lo:[0,1]
	v_pk_add_f32 v[42:43], v[8:9], v[10:11] op_sel:[0,1] op_sel_hi:[1,0]
	v_pk_add_f32 v[8:9], v[10:11], v[8:9] op_sel:[1,0] op_sel_hi:[0,1] neg_lo:[0,1] neg_hi:[0,1]
	v_pk_mul_f32 v[14:15], v[14:15], 0.5 op_sel_hi:[1,0]
	v_mov_b32_e32 v43, v9
	v_mul_f32_e32 v4, v59, v14
	v_pk_fma_f32 v[44:45], v[22:23], v[14:15], v[4:5] op_sel_hi:[1,1,0] neg_lo:[1,0,0] neg_hi:[1,0,0]
	v_mul_f32_e32 v4, v59, v15
	v_pk_fma_f32 v[14:15], v[72:73], v[14:15], v[4:5] op_sel_hi:[1,1,0]
	v_sub_f32_e32 v6, v39, v99
	v_mov_b32_e32 v44, v14
	v_pk_fma_f32 v[8:9], v[42:43], 0.5, v[14:15] op_sel_hi:[1,0,1] neg_lo:[0,0,1] neg_hi:[0,0,1]
	v_pk_fma_f32 v[10:11], v[42:43], 0.5, v[44:45] op_sel_hi:[1,0,1]
	v_pk_add_f32 v[14:15], v[98:99], v[38:39]
	v_mov_b32_e32 v9, v11
	v_pk_mul_f32 v[168:169], v[8:9], s[6:7] op_sel_hi:[1,0]
	v_mul_f32_e32 v8, 0xbf7b14be, v83
	v_mov_b32_e32 v9, v38
	v_mul_f32_e32 v18, 0.5, v15
	v_pk_add_f32 v[8:9], v[8:9], v[118:119] neg_lo:[0,1] neg_hi:[0,1]
	v_pk_fma_f32 v[72:73], v[42:43], 0.5, v[44:45] op_sel_hi:[1,0,1] neg_lo:[1,0,0] neg_hi:[1,0,0]
	v_pk_mul_f32 v[38:39], v[8:9], v[18:19]
	v_mov_b32_e32 v42, v8
	v_pk_fma_f32 v[22:23], v[22:23], v[38:39], v[38:39] op_sel:[0,1,0] op_sel_hi:[1,0,1]
	v_mov_b32_e32 v43, v59
	v_mov_b32_e32 v38, v39
	v_mov_b32_e32 v39, v18
	v_mul_f32_e32 v4, 0.5, v14
	v_pk_mul_f32 v[38:39], v[42:43], v[38:39]
	v_cvt_f32_f16_e32 v44, v2
	v_cvt_f32_f16_e32 v45, v3
	v_cvt_f32_f16_sdwa v3, v3 dst_sel:DWORD dst_unused:UNUSED_PAD src0_sel:WORD_1
	v_cvt_f32_f16_sdwa v2, v2 dst_sel:DWORD dst_unused:UNUSED_PAD src0_sel:WORD_1
	v_mul_f32_e32 v6, 0.5, v6
	v_pk_add_f32 v[46:47], v[4:5], v[22:23]
	v_fma_f32 v4, v14, 0.5, -v22
	v_pk_add_f32 v[22:23], v[38:39], v[38:39] op_sel:[0,1] op_sel_hi:[0,1] neg_lo:[0,1] neg_hi:[0,1]
	v_pk_add_f32 v[38:39], v[6:7], v[22:23] op_sel_hi:[0,1] neg_hi:[0,1]
	v_mov_b32_e32 v14, v46
	v_mov_b32_e32 v15, v4
	v_pk_mul_f32 v[22:23], v[4:5], v[44:45] op_sel_hi:[0,1]
	v_pk_mul_f32 v[82:83], v[38:39], v[2:3]
	v_pk_mul_f32 v[46:47], v[46:47], v[2:3]
	v_pk_mul_f32 v[38:39], v[38:39], v[44:45]
	v_pk_fma_f32 v[98:99], v[14:15], v[44:45], v[82:83] neg_lo:[0,0,1] neg_hi:[0,0,1]
	v_pk_fma_f32 v[2:3], v[14:15], v[2:3], v[38:39] neg_lo:[0,0,1] neg_hi:[0,0,1]
	v_add_f32_e32 v4, v23, v83
	v_add_f32_e32 v6, v46, v38
	v_pk_add_f32 v[22:23], v[6:7], v[2:3] op_sel_hi:[0,1] neg_lo:[0,1] neg_hi:[0,1]
	v_pk_add_f32 v[38:39], v[98:99], v[4:5] op_sel_hi:[1,0] neg_lo:[0,1] neg_hi:[0,1]
	v_pk_add_f32 v[2:3], v[6:7], v[2:3] op_sel_hi:[0,1]
	v_mov_b32_e32 v39, v3
	v_pk_mul_f32 v[2:3], v[38:39], 0.5 op_sel_hi:[1,0]
	v_pk_add_f32 v[14:15], v[98:99], v[4:5] op_sel_hi:[1,0]
	v_mul_f32_e32 v4, v59, v3
	v_pk_fma_f32 v[38:39], v[42:43], v[2:3], v[4:5] op_sel_hi:[1,1,0] neg_lo:[0,0,1] neg_hi:[0,0,1]
	v_pk_mov_b32 v[42:43], v[58:59], v[8:9] op_sel:[1,0]
	v_mul_f32_e32 v4, v8, v3
	v_pk_fma_f32 v[2:3], v[42:43], v[2:3], v[4:5] op_sel_hi:[1,1,0]
	v_mov_b32_e32 v15, v23
	v_pk_fma_f32 v[8:9], v[14:15], 0.5, v[2:3] op_sel_hi:[1,0,1] neg_lo:[0,0,1] neg_hi:[0,0,1]
	v_pk_fma_f32 v[42:43], v[14:15], 0.5, v[38:39] op_sel_hi:[1,0,0]
	v_pk_fma_f32 v[2:3], v[14:15], 0.5, v[2:3] op_sel_hi:[1,0,1]
	v_mov_b32_e32 v9, v43
	v_pk_fma_f32 v[58:59], v[22:23], 0.5, v[38:39] op_sel_hi:[1,0,0] neg_lo:[1,0,0] neg_hi:[1,0,0]
	v_pk_mul_f32 v[144:145], v[8:9], s[6:7] op_sel_hi:[1,0]
	v_mov_b32_e32 v58, v2
	v_mov_b32_e32 v72, v10
	v_mov_b32_e32 v54, v40
	v_mov_b32_e32 v70, v20
	v_mov_b32_e32 v56, v26
	v_mov_b32_e32 v76, v36
	v_mov_b32_e32 v52, v34
	v_mov_b32_e32 v74, v86
	v_mov_b32_e32 v48, v84
	v_mov_b32_e32 v50, v60
	v_mov_b32_e32 v28, v66
	v_mov_b32_e32 v32, v96
	v_mov_b32_e32 v12, v88
	v_mov_b32_e32 v16, v92
	v_mov_b32_e32 v4, v138
	v_mov_b32_e32 v6, v122

.LBB0_534:
	v_mov_b32_e32 v2, v210
	s_mov_b32 s43, s8
	v_and_b32_e32 v3, 0xff, v2
	v_lshlrev_b32_e32 v4, 5, v2
	v_and_or_b32 v3, v4, s33, v3
	v_ashrrev_i32_e32 v4, 5, v3
	v_lshlrev_b32_e32 v3, 3, v3
	v_lshlrev_b32_e32 v4, 3, v4
	v_add3_u32 v18, 0, v3, v4
	ds_read_b64 v[128:129], v18
	ds_read_b64 v[132:133], v18 offset:2112
	ds_read_b64 v[134:135], v18 offset:4224
	ds_read_b64 v[136:137], v18 offset:6336
	ds_read_b64 v[138:139], v18 offset:8448
	ds_read_b64 v[140:141], v18 offset:10560
	ds_read_b64 v[142:143], v18 offset:12672
	ds_read_b64 v[130:131], v18 offset:14784
	ds_read_b64 v[144:145], v18 offset:16896
	ds_read_b64 v[148:149], v18 offset:19008
	ds_read_b64 v[150:151], v18 offset:21120
	ds_read_b64 v[152:153], v18 offset:23232
	s_waitcnt lgkmcnt(10)
	v_pk_mul_f32 v[162:163], v[132:133], s[10:11]
	s_mov_b32 s64, s11
	v_pk_fma_f32 v[162:163], v[132:133], s[8:9], v[162:163] op_sel:[0,0,1] op_sel_hi:[1,0,0]
	s_waitcnt lgkmcnt(2)
	v_pk_mul_f32 v[178:179], v[148:149], s[42:43]
	v_pk_add_f32 v[194:195], v[132:133], v[148:149]
	v_pk_add_f32 v[132:133], v[132:133], v[148:149] neg_lo:[0,1] neg_hi:[0,1]
	v_pk_mul_f32 v[164:165], v[134:135], s[18:19]
	s_mov_b32 s41, s16
	v_pk_fma_f32 v[178:179], v[148:149], s[64:65], v[178:179] op_sel:[0,0,1] op_sel_hi:[1,0,0] neg_lo:[1,0,0] neg_hi:[1,0,0]
	v_pk_mul_f32 v[148:149], v[132:133], s[18:19]
	v_pk_fma_f32 v[164:165], v[134:135], s[16:17], v[164:165] op_sel:[0,0,1] op_sel_hi:[1,0,0]
	s_mov_b32 s68, s19
	s_waitcnt lgkmcnt(1)
	v_pk_mul_f32 v[180:181], v[150:151], s[40:41]
	v_pk_fma_f32 v[132:133], v[132:133], s[16:17], v[148:149] op_sel:[0,0,1] op_sel_hi:[1,0,0]
	v_pk_add_f32 v[148:149], v[134:135], v[150:151]
	v_pk_add_f32 v[134:135], v[134:135], v[150:151] neg_lo:[0,1] neg_hi:[0,1]
	v_pk_mul_f32 v[166:167], v[136:137], s[26:27]
	s_mov_b32 s66, s37
	s_mov_b32 s39, s24
	v_pk_fma_f32 v[180:181], v[150:151], s[68:69], v[180:181] op_sel:[0,0,1] op_sel_hi:[1,0,0] neg_lo:[1,0,0] neg_hi:[1,0,0]
	v_pk_mul_f32 v[150:151], v[134:135], s[36:37]
	ds_read_b64 v[154:155], v18 offset:25344
	ds_read_b64 v[156:157], v18 offset:27456
	ds_read_b64 v[158:159], v18 offset:29568
	ds_read_b64 v[160:161], v18 offset:31680
	v_pk_fma_f32 v[166:167], v[136:137], s[24:25], v[166:167] op_sel:[0,0,1] op_sel_hi:[1,0,0]
	s_mov_b32 s0, s27
	s_waitcnt lgkmcnt(4)
	v_pk_mul_f32 v[182:183], v[152:153], s[38:39]
	v_pk_fma_f32 v[134:135], v[134:135], s[66:67], v[150:151] op_sel:[0,0,1] op_sel_hi:[1,0,0]
	v_pk_add_f32 v[150:151], v[136:137], v[152:153]
	v_pk_add_f32 v[136:137], v[136:137], v[152:153] neg_lo:[0,1] neg_hi:[0,1]
	v_pk_mul_f32 v[168:169], v[138:139], s[36:37]
	v_pk_fma_f32 v[182:183], v[152:153], s[0:1], v[182:183] op_sel:[0,0,1] op_sel_hi:[1,0,0] neg_lo:[1,0,0] neg_hi:[1,0,0]
	v_pk_mul_f32 v[152:153], v[136:137], s[40:41]
	v_pk_fma_f32 v[168:169], v[138:139], s[66:67], v[168:169] op_sel:[0,0,1] op_sel_hi:[1,0,0]
	v_pk_mul_f32 v[170:171], v[140:141], s[38:39]
	s_waitcnt lgkmcnt(3)
	v_pk_mul_f32 v[184:185], v[154:155], s[36:37]
	v_pk_fma_f32 v[136:137], v[136:137], s[68:69], v[152:153] op_sel:[0,0,1] op_sel_hi:[1,0,0]
	v_pk_add_f32 v[152:153], v[138:139], v[154:155]
	v_pk_add_f32 v[138:139], v[138:139], v[154:155] neg_lo:[0,1] neg_hi:[0,1]
	v_pk_fma_f32 v[170:171], v[140:141], s[0:1], v[170:171] op_sel:[0,0,1] op_sel_hi:[1,0,0]
	v_pk_fma_f32 v[184:185], v[154:155], s[66:67], v[184:185] op_sel:[0,0,1] op_sel_hi:[1,0,0] neg_lo:[1,0,0] neg_hi:[1,0,0]
	s_waitcnt lgkmcnt(2)
	v_pk_mul_f32 v[186:187], v[156:157], s[26:27]
	v_xor_b32_e32 v155, 0x80000000, v138
	v_mov_b32_e32 v154, v139
	v_pk_add_f32 v[138:139], v[140:141], v[156:157]
	v_pk_add_f32 v[140:141], v[140:141], v[156:157] neg_lo:[0,1] neg_hi:[0,1]
	v_pk_mul_f32 v[172:173], v[142:143], s[40:41]
	v_pk_fma_f32 v[186:187], v[156:157], s[24:25], v[186:187] op_sel:[0,0,1] op_sel_hi:[1,0,0] neg_lo:[1,0,0] neg_hi:[1,0,0]
	v_pk_mul_f32 v[156:157], v[140:141], s[40:41]
	v_pk_fma_f32 v[172:173], v[142:143], s[68:69], v[172:173] op_sel:[0,0,1] op_sel_hi:[1,0,0]
	s_waitcnt lgkmcnt(1)
	v_pk_mul_f32 v[188:189], v[158:159], s[18:19]
	v_pk_fma_f32 v[140:141], v[140:141], s[68:69], v[156:157] op_sel:[0,0,1] op_sel_hi:[1,0,0] neg_lo:[1,0,0] neg_hi:[1,0,0]
	v_pk_add_f32 v[156:157], v[142:143], v[158:159]
	v_pk_add_f32 v[142:143], v[142:143], v[158:159] neg_lo:[0,1] neg_hi:[0,1]
	v_pk_mul_f32 v[174:175], v[130:131], s[42:43]
	v_pk_fma_f32 v[188:189], v[158:159], s[16:17], v[188:189] op_sel:[0,0,1] op_sel_hi:[1,0,0] neg_lo:[1,0,0] neg_hi:[1,0,0]
	v_pk_mul_f32 v[158:159], v[142:143], s[36:37]
	v_pk_fma_f32 v[174:175], v[130:131], s[64:65], v[174:175] op_sel:[0,0,1] op_sel_hi:[1,0,0]
	s_waitcnt lgkmcnt(0)
	v_pk_mul_f32 v[190:191], v[160:161], s[10:11]
	v_pk_fma_f32 v[142:143], v[142:143], s[66:67], v[158:159] op_sel:[0,0,1] op_sel_hi:[1,0,0] neg_lo:[1,0,0] neg_hi:[1,0,0]
	v_pk_add_f32 v[158:159], v[130:131], v[160:161]
	v_pk_add_f32 v[130:131], v[130:131], v[160:161] neg_lo:[0,1] neg_hi:[0,1]
	v_xor_b32_e32 v177, 0x80000000, v144
	v_mov_b32_e32 v176, v145
	v_pk_fma_f32 v[190:191], v[160:161], s[8:9], v[190:191] op_sel:[0,0,1] op_sel_hi:[1,0,0] neg_lo:[1,0,0] neg_hi:[1,0,0]
	v_pk_mul_f32 v[160:161], v[130:131], s[18:19]
	v_pk_add_f32 v[192:193], v[128:129], v[144:145]
	v_pk_add_f32 v[144:145], v[128:129], v[144:145] neg_lo:[0,1] neg_hi:[0,1]
	v_pk_fma_f32 v[130:131], v[130:131], s[16:17], v[160:161] op_sel:[0,0,1] op_sel_hi:[1,0,0] neg_lo:[1,0,0] neg_hi:[1,0,0]
	v_pk_add_f32 v[160:161], v[128:129], v[176:177]
	v_pk_add_f32 v[128:129], v[128:129], v[176:177] neg_lo:[0,1] neg_hi:[0,1]
	v_pk_add_f32 v[176:177], v[162:163], v[178:179]
	v_pk_add_f32 v[162:163], v[162:163], v[178:179] neg_lo:[0,1] neg_hi:[0,1]
	v_cvt_f32_ubyte0_e32 v2, v2
	v_pk_mul_f32 v[178:179], v[162:163], s[18:19]
	v_mul_f32_e32 v2, 0x39000000, v2
	v_pk_fma_f32 v[162:163], v[162:163], s[16:17], v[178:179] op_sel:[0,0,1] op_sel_hi:[1,0,0]
	v_pk_add_f32 v[178:179], v[164:165], v[180:181]
	v_pk_add_f32 v[164:165], v[164:165], v[180:181] neg_lo:[0,1] neg_hi:[0,1]
	v_sin_f32_e32 v34, v2
	v_pk_mul_f32 v[180:181], v[164:165], s[36:37]
	v_cos_f32_e32 v30, v2
	v_pk_fma_f32 v[164:165], v[164:165], s[66:67], v[180:181] op_sel:[0,0,1] op_sel_hi:[1,0,0]
	v_pk_add_f32 v[180:181], v[166:167], v[182:183]
	v_pk_add_f32 v[166:167], v[166:167], v[182:183] neg_lo:[0,1] neg_hi:[0,1]
	v_xor_b32_e32 v31, 0x80000000, v34
	v_pk_mul_f32 v[182:183], v[166:167], s[40:41]
	v_mov_b32_e32 v35, v31
	v_pk_fma_f32 v[166:167], v[166:167], s[68:69], v[182:183] op_sel:[0,0,1] op_sel_hi:[1,0,0]
	v_pk_add_f32 v[182:183], v[168:169], v[184:185]
	v_pk_add_f32 v[184:185], v[168:169], v[184:185] neg_lo:[0,1] neg_hi:[0,1]
	v_pk_mul_f32 v[2:3], v[30:31], v[34:35] op_sel:[1,0] op_sel_hi:[0,1]
	v_pk_add_f32 v[168:169], v[170:171], v[186:187]
	v_pk_add_f32 v[170:171], v[170:171], v[186:187] neg_lo:[0,1] neg_hi:[0,1]
	v_pk_fma_f32 v[44:45], v[30:31], v[30:31], v[2:3] op_sel_hi:[1,0,1]
	v_pk_mul_f32 v[186:187], v[170:171], s[40:41]
	v_pk_mul_f32 v[2:3], v[34:35], v[44:45] op_sel:[0,1] op_sel_hi:[1,0]
	v_pk_fma_f32 v[170:171], v[170:171], s[68:69], v[186:187] op_sel:[0,0,1] op_sel_hi:[1,0,0] neg_lo:[1,0,0] neg_hi:[1,0,0]
	v_pk_add_f32 v[186:187], v[172:173], v[188:189]
	v_pk_add_f32 v[172:173], v[172:173], v[188:189] neg_lo:[0,1] neg_hi:[0,1]
	v_xor_b32_e32 v54, 0x80000000, v45
	v_pk_mul_f32 v[188:189], v[172:173], s[36:37]
	v_mov_b32_e32 v55, v45
	v_pk_fma_f32 v[172:173], v[172:173], s[66:67], v[188:189] op_sel:[0,0,1] op_sel_hi:[1,0,0] neg_lo:[1,0,0] neg_hi:[1,0,0]
	v_pk_add_f32 v[188:189], v[174:175], v[190:191]
	v_pk_add_f32 v[174:175], v[174:175], v[190:191] neg_lo:[0,1] neg_hi:[0,1]
	v_pk_fma_f32 v[46:47], v[30:31], v[44:45], v[2:3] op_sel_hi:[0,1,1]
	v_pk_mul_f32 v[190:191], v[174:175], s[18:19]
	v_pk_mul_f32 v[2:3], v[44:45], v[54:55] op_sel:[1,0] op_sel_hi:[0,1]
	v_pk_fma_f32 v[174:175], v[174:175], s[16:17], v[190:191] op_sel:[0,0,1] op_sel_hi:[1,0,0] neg_lo:[1,0,0] neg_hi:[1,0,0]
	v_pk_add_f32 v[190:191], v[192:193], v[152:153]
	v_pk_add_f32 v[152:153], v[192:193], v[152:153] neg_lo:[0,1] neg_hi:[0,1]
	v_pk_add_f32 v[192:193], v[194:195], v[138:139]
	v_pk_add_f32 v[138:139], v[194:195], v[138:139] neg_lo:[0,1] neg_hi:[0,1]
	v_pk_fma_f32 v[52:53], v[44:45], v[44:45], v[2:3] op_sel_hi:[1,0,1]
	v_pk_mul_f32 v[194:195], v[138:139], s[36:37]
	v_xor_b32_e32 v58, 0x80000000, v53
	v_pk_fma_f32 v[138:139], v[138:139], s[66:67], v[194:195] op_sel:[0,0,1] op_sel_hi:[1,0,0]
	v_pk_add_f32 v[194:195], v[148:149], v[156:157]
	v_pk_add_f32 v[156:157], v[148:149], v[156:157] neg_lo:[0,1] neg_hi:[0,1]
	v_mov_b32_e32 v59, v53
	v_pk_add_f32 v[148:149], v[150:151], v[158:159]
	v_pk_add_f32 v[150:151], v[150:151], v[158:159] neg_lo:[0,1] neg_hi:[0,1]
	v_pk_mul_f32 v[2:3], v[52:53], v[58:59] op_sel:[1,0] op_sel_hi:[0,1]
	v_pk_mul_f32 v[158:159], v[150:151], s[36:37]
	v_pk_fma_f32 v[48:49], v[52:53], v[52:53], v[2:3] op_sel_hi:[1,0,1]
	v_pk_fma_f32 v[150:151], v[150:151], s[66:67], v[158:159] op_sel:[0,0,1] op_sel_hi:[1,0,0] neg_lo:[1,0,0] neg_hi:[1,0,0]
	v_pk_add_f32 v[158:159], v[144:145], v[154:155]
	v_pk_add_f32 v[144:145], v[144:145], v[154:155] neg_lo:[0,1] neg_hi:[0,1]
	v_pk_add_f32 v[154:155], v[132:133], v[140:141]
	v_pk_add_f32 v[132:133], v[132:133], v[140:141] neg_lo:[0,1] neg_hi:[0,1]
	v_pk_mul_f32 v[2:3], v[58:59], v[48:49] op_sel:[0,1] op_sel_hi:[1,0]
	v_pk_mul_f32 v[140:141], v[132:133], s[36:37]
	v_pk_fma_f32 v[36:37], v[52:53], v[48:49], v[2:3] op_sel_hi:[0,1,1]
	v_pk_fma_f32 v[132:133], v[132:133], s[66:67], v[140:141] op_sel:[0,0,1] op_sel_hi:[1,0,0]
	v_pk_add_f32 v[140:141], v[134:135], v[142:143]
	v_pk_add_f32 v[142:143], v[134:135], v[142:143] neg_lo:[0,1] neg_hi:[0,1]
	v_pk_mul_f32 v[2:3], v[58:59], v[36:37] op_sel:[0,1] op_sel_hi:[1,0]
	v_pk_add_f32 v[134:135], v[136:137], v[130:131]
	v_pk_add_f32 v[130:131], v[136:137], v[130:131] neg_lo:[0,1] neg_hi:[0,1]
	v_pk_fma_f32 v[26:27], v[52:53], v[36:37], v[2:3] op_sel_hi:[0,1,1]
	v_pk_mul_f32 v[136:137], v[130:131], s[36:37]
	v_pk_mul_f32 v[2:3], v[58:59], v[26:27] op_sel:[0,1] op_sel_hi:[1,0]
	v_pk_fma_f32 v[130:131], v[130:131], s[66:67], v[136:137] op_sel:[0,0,1] op_sel_hi:[1,0,0] neg_lo:[1,0,0] neg_hi:[1,0,0]
	v_pk_add_f32 v[136:137], v[160:161], v[182:183]
	v_pk_add_f32 v[160:161], v[160:161], v[182:183] neg_lo:[0,1] neg_hi:[0,1]
	v_pk_add_f32 v[182:183], v[176:177], v[168:169]
	v_pk_add_f32 v[168:169], v[176:177], v[168:169] neg_lo:[0,1] neg_hi:[0,1]
	v_pk_fma_f32 v[20:21], v[52:53], v[26:27], v[2:3] op_sel_hi:[0,1,1]
	v_pk_mul_f32 v[176:177], v[168:169], s[36:37]
	v_pk_mul_f32 v[2:3], v[58:59], v[20:21] op_sel:[0,1] op_sel_hi:[1,0]
	v_pk_fma_f32 v[168:169], v[168:169], s[66:67], v[176:177] op_sel:[0,0,1] op_sel_hi:[1,0,0]
	v_pk_add_f32 v[176:177], v[178:179], v[186:187]
	v_pk_add_f32 v[186:187], v[178:179], v[186:187] neg_lo:[0,1] neg_hi:[0,1]
	v_pk_fma_f32 v[10:11], v[52:53], v[20:21], v[2:3] op_sel_hi:[0,1,1]
	v_pk_add_f32 v[178:179], v[180:181], v[188:189]
	v_pk_add_f32 v[180:181], v[180:181], v[188:189] neg_lo:[0,1] neg_hi:[0,1]
	v_pk_mul_f32 v[2:3], v[58:59], v[10:11] op_sel:[0,1] op_sel_hi:[1,0]
	v_pk_mul_f32 v[188:189], v[180:181], s[36:37]
	v_pk_fma_f32 v[4:5], v[52:53], v[10:11], v[2:3] op_sel_hi:[0,1,1]
	v_pk_fma_f32 v[180:181], v[180:181], s[66:67], v[188:189] op_sel:[0,0,1] op_sel_hi:[1,0,0] neg_lo:[1,0,0] neg_hi:[1,0,0]
	v_pk_add_f32 v[188:189], v[128:129], v[184:185] op_sel:[0,1] op_sel_hi:[1,0] neg_hi:[0,1]
	v_pk_add_f32 v[128:129], v[128:129], v[184:185] op_sel:[0,1] op_sel_hi:[1,0] neg_lo:[0,1]
	v_pk_add_f32 v[184:185], v[162:163], v[170:171]
	v_pk_add_f32 v[162:163], v[162:163], v[170:171] neg_lo:[0,1] neg_hi:[0,1]
	v_xor_b32_e32 v72, 0x80000000, v47
	v_pk_mul_f32 v[170:171], v[162:163], s[36:37]
	v_mov_b32_e32 v73, v47
	v_pk_fma_f32 v[162:163], v[162:163], s[66:67], v[170:171] op_sel:[0,0,1] op_sel_hi:[1,0,0]
	v_pk_add_f32 v[170:171], v[164:165], v[172:173]
	v_pk_add_f32 v[172:173], v[164:165], v[172:173] neg_lo:[0,1] neg_hi:[0,1]
	v_pk_mul_f32 v[2:3], v[72:73], v[4:5] op_sel:[0,1] op_sel_hi:[1,0]
	v_pk_add_f32 v[164:165], v[166:167], v[174:175]
	v_pk_add_f32 v[166:167], v[166:167], v[174:175] neg_lo:[0,1] neg_hi:[0,1]
	v_pk_mul_f32 v[14:15], v[34:35], v[4:5] op_sel:[0,1] op_sel_hi:[1,0]
	v_pk_mul_f32 v[174:175], v[166:167], s[36:37]
	v_pk_mul_f32 v[40:41], v[34:35], v[10:11] op_sel:[0,1] op_sel_hi:[1,0]
	v_pk_fma_f32 v[166:167], v[166:167], s[66:67], v[174:175] op_sel:[0,0,1] op_sel_hi:[1,0,0] neg_lo:[1,0,0] neg_hi:[1,0,0]
	v_pk_add_f32 v[174:175], v[190:191], v[194:195]
	v_pk_add_f32 v[190:191], v[190:191], v[194:195] neg_lo:[0,1] neg_hi:[0,1]
	v_pk_add_f32 v[194:195], v[192:193], v[148:149]
	v_pk_add_f32 v[192:193], v[192:193], v[148:149] neg_lo:[0,1] neg_hi:[0,1]
	v_pk_mul_f32 v[66:67], v[34:35], v[20:21] op_sel:[0,1] op_sel_hi:[1,0]
	v_pk_add_f32 v[148:149], v[152:153], v[156:157] op_sel:[0,1] op_sel_hi:[1,0] neg_hi:[0,1]
	v_pk_add_f32 v[152:153], v[152:153], v[156:157] op_sel:[0,1] op_sel_hi:[1,0] neg_lo:[0,1]
	v_pk_add_f32 v[156:157], v[138:139], v[150:151]
	v_pk_add_f32 v[150:151], v[138:139], v[150:151] neg_lo:[0,1] neg_hi:[0,1]
	v_pk_mul_f32 v[82:83], v[34:35], v[26:27] op_sel:[0,1] op_sel_hi:[1,0]
	v_pk_add_f32 v[138:139], v[158:159], v[140:141]
	v_pk_add_f32 v[140:141], v[158:159], v[140:141] neg_lo:[0,1] neg_hi:[0,1]
	v_pk_add_f32 v[158:159], v[154:155], v[134:135]
	v_pk_add_f32 v[154:155], v[154:155], v[134:135] neg_lo:[0,1] neg_hi:[0,1]
	v_pk_mul_f32 v[96:97], v[34:35], v[36:37] op_sel:[0,1] op_sel_hi:[1,0]
	v_pk_add_f32 v[134:135], v[144:145], v[142:143] op_sel:[0,1] op_sel_hi:[1,0] neg_hi:[0,1]
	v_pk_add_f32 v[142:143], v[144:145], v[142:143] op_sel:[0,1] op_sel_hi:[1,0] neg_lo:[0,1]
	v_pk_add_f32 v[144:145], v[132:133], v[130:131]
	v_pk_add_f32 v[132:133], v[132:133], v[130:131] neg_lo:[0,1] neg_hi:[0,1]
	v_pk_mul_f32 v[110:111], v[34:35], v[48:49] op_sel:[0,1] op_sel_hi:[1,0]
	v_pk_add_f32 v[130:131], v[136:137], v[176:177]
	v_pk_add_f32 v[136:137], v[136:137], v[176:177] neg_lo:[0,1] neg_hi:[0,1]
	v_pk_add_f32 v[176:177], v[182:183], v[178:179]
	v_pk_add_f32 v[182:183], v[182:183], v[178:179] neg_lo:[0,1] neg_hi:[0,1]
	v_pk_mul_f32 v[124:125], v[34:35], v[52:53] op_sel:[0,1] op_sel_hi:[1,0]
	v_pk_add_f32 v[178:179], v[160:161], v[186:187] op_sel:[0,1] op_sel_hi:[1,0] neg_hi:[0,1]
	v_pk_add_f32 v[160:161], v[160:161], v[186:187] op_sel:[0,1] op_sel_hi:[1,0] neg_lo:[0,1]
	v_pk_add_f32 v[186:187], v[168:169], v[180:181]
	v_pk_add_f32 v[180:181], v[168:169], v[180:181] neg_lo:[0,1] neg_hi:[0,1]
	v_pk_fma_f32 v[2:3], v[46:47], v[4:5], v[2:3] op_sel_hi:[0,1,1]
	v_pk_add_f32 v[168:169], v[188:189], v[170:171]
	v_pk_add_f32 v[170:171], v[188:189], v[170:171] neg_lo:[0,1] neg_hi:[0,1]
	v_pk_add_f32 v[188:189], v[184:185], v[164:165]
	v_pk_add_f32 v[184:185], v[184:185], v[164:165] neg_lo:[0,1] neg_hi:[0,1]
	v_pk_mul_f32 v[8:9], v[54:55], v[4:5] op_sel:[0,1] op_sel_hi:[1,0]
	v_pk_add_f32 v[164:165], v[128:129], v[172:173] op_sel:[0,1] op_sel_hi:[1,0] neg_hi:[0,1]
	v_pk_add_f32 v[128:129], v[128:129], v[172:173] op_sel:[0,1] op_sel_hi:[1,0] neg_lo:[0,1]
	v_pk_add_f32 v[172:173], v[162:163], v[166:167]
	v_pk_add_f32 v[166:167], v[162:163], v[166:167] neg_lo:[0,1] neg_hi:[0,1]
	v_pk_fma_f32 v[14:15], v[30:31], v[4:5], v[14:15] op_sel_hi:[0,1,1]
	v_pk_add_f32 v[162:163], v[174:175], v[194:195]
	v_pk_add_f32 v[174:175], v[174:175], v[194:195] neg_lo:[0,1] neg_hi:[0,1]
	v_pk_add_f32 v[194:195], v[190:191], v[192:193] op_sel:[0,1] op_sel_hi:[1,0] neg_hi:[0,1]
	v_pk_add_f32 v[190:191], v[190:191], v[192:193] op_sel:[0,1] op_sel_hi:[1,0] neg_lo:[0,1]
	v_pk_add_f32 v[192:193], v[148:149], v[156:157]
	v_pk_add_f32 v[148:149], v[148:149], v[156:157] neg_lo:[0,1] neg_hi:[0,1]
	v_pk_add_f32 v[156:157], v[152:153], v[150:151] op_sel:[0,1] op_sel_hi:[1,0] neg_hi:[0,1]
	v_pk_add_f32 v[150:151], v[152:153], v[150:151] op_sel:[0,1] op_sel_hi:[1,0] neg_lo:[0,1]
	v_pk_add_f32 v[152:153], v[138:139], v[158:159]
	v_pk_add_f32 v[138:139], v[138:139], v[158:159] neg_lo:[0,1] neg_hi:[0,1]
	v_pk_add_f32 v[158:159], v[140:141], v[154:155] op_sel:[0,1] op_sel_hi:[1,0] neg_hi:[0,1]
	v_pk_add_f32 v[140:141], v[140:141], v[154:155] op_sel:[0,1] op_sel_hi:[1,0] neg_lo:[0,1]
	v_pk_add_f32 v[154:155], v[134:135], v[144:145]
	v_pk_add_f32 v[134:135], v[134:135], v[144:145] neg_lo:[0,1] neg_hi:[0,1]
	v_pk_add_f32 v[144:145], v[142:143], v[132:133] op_sel:[0,1] op_sel_hi:[1,0] neg_hi:[0,1]
	v_pk_add_f32 v[132:133], v[142:143], v[132:133] op_sel:[0,1] op_sel_hi:[1,0] neg_lo:[0,1]
	v_pk_add_f32 v[142:143], v[130:131], v[176:177]
	v_pk_mul_f32 v[24:25], v[72:73], v[10:11] op_sel:[0,1] op_sel_hi:[1,0]
	v_pk_mul_f32 v[34:35], v[34:35], v[142:143] op_sel:[0,1] op_sel_hi:[1,0]
	v_pk_mul_f32 v[32:33], v[54:55], v[10:11] op_sel:[0,1] op_sel_hi:[1,0]
	v_pk_fma_f32 v[40:41], v[30:31], v[10:11], v[40:41] op_sel_hi:[0,1,1]
	v_pk_mul_f32 v[56:57], v[72:73], v[20:21] op_sel:[0,1] op_sel_hi:[1,0]
	v_pk_mul_f32 v[62:63], v[54:55], v[20:21] op_sel:[0,1] op_sel_hi:[1,0]
	v_pk_fma_f32 v[66:67], v[30:31], v[20:21], v[66:67] op_sel_hi:[0,1,1]
	v_pk_mul_f32 v[74:75], v[72:73], v[26:27] op_sel:[0,1] op_sel_hi:[1,0]
	v_pk_mul_f32 v[78:79], v[54:55], v[26:27] op_sel:[0,1] op_sel_hi:[1,0]
	v_pk_fma_f32 v[82:83], v[30:31], v[26:27], v[82:83] op_sel_hi:[0,1,1]
	v_pk_mul_f32 v[88:89], v[72:73], v[36:37] op_sel:[0,1] op_sel_hi:[1,0]
	v_pk_mul_f32 v[92:93], v[54:55], v[36:37] op_sel:[0,1] op_sel_hi:[1,0]
	v_pk_fma_f32 v[96:97], v[30:31], v[36:37], v[96:97] op_sel_hi:[0,1,1]
	v_pk_mul_f32 v[102:103], v[72:73], v[48:49] op_sel:[0,1] op_sel_hi:[1,0]
	v_pk_mul_f32 v[106:107], v[54:55], v[48:49] op_sel:[0,1] op_sel_hi:[1,0]
	v_pk_fma_f32 v[110:111], v[30:31], v[48:49], v[110:111] op_sel_hi:[0,1,1]
	v_pk_mul_f32 v[116:117], v[52:53], v[72:73] op_sel:[1,0] op_sel_hi:[0,1]
	v_pk_mul_f32 v[120:121], v[54:55], v[52:53] op_sel:[0,1] op_sel_hi:[1,0]
	v_pk_fma_f32 v[124:125], v[30:31], v[52:53], v[124:125] op_sel_hi:[0,1,1]
	v_pk_add_f32 v[130:131], v[130:131], v[176:177] neg_lo:[0,1] neg_hi:[0,1]
	v_pk_add_f32 v[176:177], v[136:137], v[182:183] op_sel:[0,1] op_sel_hi:[1,0] neg_hi:[0,1]
	v_pk_add_f32 v[136:137], v[136:137], v[182:183] op_sel:[0,1] op_sel_hi:[1,0] neg_lo:[0,1]
	v_pk_add_f32 v[182:183], v[178:179], v[186:187]
	v_pk_add_f32 v[178:179], v[178:179], v[186:187] neg_lo:[0,1] neg_hi:[0,1]
	v_pk_add_f32 v[186:187], v[160:161], v[180:181] op_sel:[0,1] op_sel_hi:[1,0] neg_hi:[0,1]
	v_pk_add_f32 v[160:161], v[160:161], v[180:181] op_sel:[0,1] op_sel_hi:[1,0] neg_lo:[0,1]
	v_pk_add_f32 v[180:181], v[168:169], v[188:189]
	v_pk_fma_f32 v[30:31], v[30:31], v[142:143], v[34:35] op_sel_hi:[0,1,1]
	v_pk_mul_f32 v[34:35], v[54:55], v[152:153] op_sel:[0,1] op_sel_hi:[1,0]
	v_xor_b32_e32 v6, 0x80000000, v3
	v_pk_fma_f32 v[8:9], v[44:45], v[4:5], v[8:9] op_sel_hi:[0,1,1]
	v_pk_fma_f32 v[24:25], v[46:47], v[10:11], v[24:25] op_sel_hi:[0,1,1]
	v_pk_fma_f32 v[32:33], v[44:45], v[10:11], v[32:33] op_sel_hi:[0,1,1]
	v_pk_fma_f32 v[56:57], v[46:47], v[20:21], v[56:57] op_sel_hi:[0,1,1]
	v_pk_fma_f32 v[62:63], v[44:45], v[20:21], v[62:63] op_sel_hi:[0,1,1]
	v_pk_fma_f32 v[74:75], v[46:47], v[26:27], v[74:75] op_sel_hi:[0,1,1]
	v_pk_fma_f32 v[78:79], v[44:45], v[26:27], v[78:79] op_sel_hi:[0,1,1]
	v_pk_fma_f32 v[88:89], v[46:47], v[36:37], v[88:89] op_sel_hi:[0,1,1]
	v_pk_fma_f32 v[92:93], v[44:45], v[36:37], v[92:93] op_sel_hi:[0,1,1]
	v_pk_fma_f32 v[102:103], v[46:47], v[48:49], v[102:103] op_sel_hi:[0,1,1]
	v_pk_fma_f32 v[106:107], v[44:45], v[48:49], v[106:107] op_sel_hi:[0,1,1]
	v_xor_b32_e32 v114, 0x80000000, v49
	v_pk_fma_f32 v[116:117], v[52:53], v[46:47], v[116:117] op_sel_hi:[1,0,1]
	v_pk_fma_f32 v[120:121], v[44:45], v[52:53], v[120:121] op_sel_hi:[0,1,1]
	v_mov_b32_e32 v115, v49
	v_mov_b32_e32 v7, v3
	v_pk_add_f32 v[168:169], v[168:169], v[188:189] neg_lo:[0,1] neg_hi:[0,1]
	v_pk_add_f32 v[188:189], v[170:171], v[184:185] op_sel:[0,1] op_sel_hi:[1,0] neg_hi:[0,1]
	v_pk_add_f32 v[170:171], v[170:171], v[184:185] op_sel:[0,1] op_sel_hi:[1,0] neg_lo:[0,1]
	v_pk_add_f32 v[184:185], v[164:165], v[172:173]
	v_pk_add_f32 v[164:165], v[164:165], v[172:173] neg_lo:[0,1] neg_hi:[0,1]
	v_pk_add_f32 v[172:173], v[128:129], v[166:167] op_sel:[0,1] op_sel_hi:[1,0] neg_hi:[0,1]
	v_pk_add_f32 v[128:129], v[128:129], v[166:167] op_sel:[0,1] op_sel_hi:[1,0] neg_lo:[0,1]
	v_pk_fma_f32 v[34:35], v[44:45], v[152:153], v[34:35] op_sel_hi:[0,1,1]
	v_pk_mul_f32 v[44:45], v[72:73], v[180:181] op_sel:[0,1] op_sel_hi:[1,0]
	v_xor_b32_e32 v12, 0x80000000, v9
	v_xor_b32_e32 v16, 0x80000000, v15
	v_xor_b32_e32 v22, 0x80000000, v5
	v_xor_b32_e32 v28, 0x80000000, v25
	v_xor_b32_e32 v38, 0x80000000, v33
	v_xor_b32_e32 v42, 0x80000000, v41
	v_xor_b32_e32 v50, 0x80000000, v11
	v_xor_b32_e32 v60, 0x80000000, v57
	v_xor_b32_e32 v64, 0x80000000, v63
	v_xor_b32_e32 v68, 0x80000000, v67
	v_xor_b32_e32 v70, 0x80000000, v21
	v_xor_b32_e32 v76, 0x80000000, v75
	v_xor_b32_e32 v80, 0x80000000, v79
	v_xor_b32_e32 v84, 0x80000000, v83
	v_xor_b32_e32 v86, 0x80000000, v27
	v_xor_b32_e32 v90, 0x80000000, v89
	v_xor_b32_e32 v94, 0x80000000, v93
	v_xor_b32_e32 v98, 0x80000000, v97
	v_xor_b32_e32 v100, 0x80000000, v37
	v_xor_b32_e32 v104, 0x80000000, v103
	v_xor_b32_e32 v108, 0x80000000, v107
	v_xor_b32_e32 v112, 0x80000000, v111
	v_xor_b32_e32 v118, 0x80000000, v117
	v_xor_b32_e32 v122, 0x80000000, v121
	v_xor_b32_e32 v126, 0x80000000, v125
	v_mov_b32_e32 v127, v125
	v_mov_b32_e32 v123, v121
	v_mov_b32_e32 v119, v117
	v_mov_b32_e32 v113, v111
	v_mov_b32_e32 v109, v107
	v_mov_b32_e32 v105, v103
	v_mov_b32_e32 v101, v37
	v_mov_b32_e32 v99, v97
	v_mov_b32_e32 v95, v93
	v_mov_b32_e32 v91, v89
	v_mov_b32_e32 v87, v27
	v_mov_b32_e32 v85, v83
	v_mov_b32_e32 v81, v79
	v_mov_b32_e32 v77, v75
	v_mov_b32_e32 v71, v21
	v_mov_b32_e32 v69, v67
	v_mov_b32_e32 v65, v63
	v_mov_b32_e32 v61, v57
	v_mov_b32_e32 v51, v11
	v_mov_b32_e32 v43, v41
	v_mov_b32_e32 v39, v33
	v_mov_b32_e32 v29, v25
	v_mov_b32_e32 v23, v5
	v_mov_b32_e32 v17, v15
	v_mov_b32_e32 v13, v9
	v_pk_fma_f32 v[44:45], v[46:47], v[180:181], v[44:45] op_sel_hi:[0,1,1]
	v_pk_mul_f32 v[46:47], v[58:59], v[192:193] op_sel:[0,1] op_sel_hi:[1,0]
	v_pk_mul_f32 v[72:73], v[114:115], v[194:195] op_sel:[0,1] op_sel_hi:[1,0]
	v_pk_mul_f32 v[6:7], v[128:129], v[6:7] op_sel:[1,0] op_sel_hi:[0,1]
	v_pk_fma_f32 v[46:47], v[52:53], v[192:193], v[46:47] op_sel_hi:[0,1,1]
	v_pk_mul_f32 v[52:53], v[126:127], v[182:183] op_sel:[0,1] op_sel_hi:[1,0]
	v_pk_mul_f32 v[54:55], v[122:123], v[154:155] op_sel:[0,1] op_sel_hi:[1,0]
	v_pk_mul_f32 v[58:59], v[118:119], v[184:185] op_sel:[0,1] op_sel_hi:[1,0]
	v_pk_fma_f32 v[48:49], v[48:49], v[194:195], v[72:73] op_sel_hi:[0,1,1]
	v_pk_mul_f32 v[72:73], v[112:113], v[176:177] op_sel:[0,1] op_sel_hi:[1,0]
	v_pk_mul_f32 v[108:109], v[108:109], v[158:159] op_sel:[0,1] op_sel_hi:[1,0]
	v_pk_mul_f32 v[104:105], v[104:105], v[188:189] op_sel:[0,1] op_sel_hi:[1,0]
	v_pk_mul_f32 v[100:101], v[100:101], v[156:157] op_sel:[0,1] op_sel_hi:[1,0]
	v_pk_mul_f32 v[98:99], v[98:99], v[186:187] op_sel:[0,1] op_sel_hi:[1,0]
	v_pk_mul_f32 v[94:95], v[94:95], v[144:145] op_sel:[0,1] op_sel_hi:[1,0]
	v_pk_mul_f32 v[90:91], v[90:91], v[172:173] op_sel:[0,1] op_sel_hi:[1,0]
	v_pk_mul_f32 v[86:87], v[174:175], v[86:87] op_sel:[1,0] op_sel_hi:[0,1]
	v_pk_mul_f32 v[84:85], v[130:131], v[84:85] op_sel:[1,0] op_sel_hi:[0,1]
	v_pk_mul_f32 v[80:81], v[138:139], v[80:81] op_sel:[1,0] op_sel_hi:[0,1]
	v_pk_mul_f32 v[76:77], v[168:169], v[76:77] op_sel:[1,0] op_sel_hi:[0,1]
	v_pk_mul_f32 v[70:71], v[148:149], v[70:71] op_sel:[1,0] op_sel_hi:[0,1]
	v_pk_mul_f32 v[68:69], v[178:179], v[68:69] op_sel:[1,0] op_sel_hi:[0,1]
	v_pk_mul_f32 v[64:65], v[134:135], v[64:65] op_sel:[1,0] op_sel_hi:[0,1]
	v_pk_mul_f32 v[60:61], v[164:165], v[60:61] op_sel:[1,0] op_sel_hi:[0,1]
	v_pk_mul_f32 v[50:51], v[190:191], v[50:51] op_sel:[1,0] op_sel_hi:[0,1]
	v_pk_mul_f32 v[42:43], v[136:137], v[42:43] op_sel:[1,0] op_sel_hi:[0,1]
	v_pk_mul_f32 v[38:39], v[140:141], v[38:39] op_sel:[1,0] op_sel_hi:[0,1]
	v_pk_mul_f32 v[28:29], v[170:171], v[28:29] op_sel:[1,0] op_sel_hi:[0,1]
	v_pk_mul_f32 v[22:23], v[150:151], v[22:23] op_sel:[1,0] op_sel_hi:[0,1]
	v_pk_mul_f32 v[16:17], v[160:161], v[16:17] op_sel:[1,0] op_sel_hi:[0,1]
	v_pk_mul_f32 v[12:13], v[132:133], v[12:13] op_sel:[1,0] op_sel_hi:[0,1]
	v_pk_fma_f32 v[2:3], v[128:129], v[2:3], v[6:7] op_sel_hi:[1,0,1]
	v_pk_fma_f32 v[52:53], v[124:125], v[182:183], v[52:53] op_sel_hi:[0,1,1]
	v_pk_fma_f32 v[54:55], v[120:121], v[154:155], v[54:55] op_sel_hi:[0,1,1]
	v_pk_fma_f32 v[58:59], v[116:117], v[184:185], v[58:59] op_sel_hi:[0,1,1]
	v_pk_fma_f32 v[72:73], v[110:111], v[176:177], v[72:73] op_sel_hi:[0,1,1]
	v_pk_fma_f32 v[106:107], v[106:107], v[158:159], v[108:109] op_sel_hi:[0,1,1]
	v_pk_fma_f32 v[102:103], v[102:103], v[188:189], v[104:105] op_sel_hi:[0,1,1]
	v_pk_fma_f32 v[36:37], v[36:37], v[156:157], v[100:101] op_sel_hi:[0,1,1]
	v_pk_fma_f32 v[96:97], v[96:97], v[186:187], v[98:99] op_sel_hi:[0,1,1]
	v_pk_fma_f32 v[92:93], v[92:93], v[144:145], v[94:95] op_sel_hi:[0,1,1]
	v_pk_fma_f32 v[88:89], v[88:89], v[172:173], v[90:91] op_sel_hi:[0,1,1]
	v_pk_fma_f32 v[26:27], v[174:175], v[26:27], v[86:87] op_sel_hi:[1,0,1]
	v_pk_fma_f32 v[82:83], v[130:131], v[82:83], v[84:85] op_sel_hi:[1,0,1]
	v_pk_fma_f32 v[78:79], v[138:139], v[78:79], v[80:81] op_sel_hi:[1,0,1]
	v_pk_fma_f32 v[74:75], v[168:169], v[74:75], v[76:77] op_sel_hi:[1,0,1]
	v_pk_fma_f32 v[20:21], v[148:149], v[20:21], v[70:71] op_sel_hi:[1,0,1]
	v_pk_fma_f32 v[66:67], v[178:179], v[66:67], v[68:69] op_sel_hi:[1,0,1]
	v_pk_fma_f32 v[62:63], v[134:135], v[62:63], v[64:65] op_sel_hi:[1,0,1]
	v_pk_fma_f32 v[56:57], v[164:165], v[56:57], v[60:61] op_sel_hi:[1,0,1]
	v_pk_fma_f32 v[10:11], v[190:191], v[10:11], v[50:51] op_sel_hi:[1,0,1]
	v_pk_fma_f32 v[40:41], v[136:137], v[40:41], v[42:43] op_sel_hi:[1,0,1]
	v_pk_fma_f32 v[32:33], v[140:141], v[32:33], v[38:39] op_sel_hi:[1,0,1]
	v_pk_fma_f32 v[24:25], v[170:171], v[24:25], v[28:29] op_sel_hi:[1,0,1]
	v_pk_fma_f32 v[4:5], v[150:151], v[4:5], v[22:23] op_sel_hi:[1,0,1]
	v_pk_fma_f32 v[14:15], v[160:161], v[14:15], v[16:17] op_sel_hi:[1,0,1]
	v_pk_fma_f32 v[8:9], v[132:133], v[8:9], v[12:13] op_sel_hi:[1,0,1]
	ds_write_b64 v18, v[162:163]
	ds_write_b64 v18, v[26:27] offset:2112
	ds_write_b64 v18, v[48:49] offset:4224
	ds_write_b64 v18, v[10:11] offset:6336
	ds_write_b64 v18, v[46:47] offset:8448
	ds_write_b64 v18, v[20:21] offset:10560
	ds_write_b64 v18, v[36:37] offset:12672
	ds_write_b64 v18, v[4:5] offset:14784
	ds_write_b64 v18, v[34:35] offset:16896
	ds_write_b64 v18, v[78:79] offset:19008
	ds_write_b64 v18, v[106:107] offset:21120
	ds_write_b64 v18, v[32:33] offset:23232
	ds_write_b64 v18, v[54:55] offset:25344
	ds_write_b64 v18, v[62:63] offset:27456
	ds_write_b64 v18, v[92:93] offset:29568
	ds_write_b64 v18, v[8:9] offset:31680
	ds_write_b64 v18, v[30:31] offset:33792
	ds_write_b64 v18, v[82:83] offset:35904
	ds_write_b64 v18, v[72:73] offset:38016
	ds_write_b64 v18, v[40:41] offset:40128
	ds_write_b64 v18, v[52:53] offset:42240
	ds_write_b64 v18, v[66:67] offset:44352
	ds_write_b64 v18, v[96:97] offset:46464
	ds_write_b64 v18, v[14:15] offset:48576
	ds_write_b64 v18, v[44:45] offset:50688
	ds_write_b64 v18, v[74:75] offset:52800
	ds_write_b64 v18, v[102:103] offset:54912
	ds_write_b64 v18, v[24:25] offset:57024
	ds_write_b64 v18, v[58:59] offset:59136
	ds_write_b64 v18, v[56:57] offset:61248
	ds_write_b64 v18, v[88:89] offset:63360
	ds_write_b64 v18, v[2:3] offset:65472
	v_mov_b32_e32 v3, v210
	s_waitcnt lgkmcnt(0)
	s_barrier
	s_add_i32 s64, s62, s48
	v_and_b32_e32 v5, 15, v3
	v_cvt_f32_ubyte0_e32 v2, v5
	v_mul_f32_e32 v4, 0x3b800000, v2
	v_sin_f32_e32 v2, v4
	v_cos_f32_e32 v4, v4
	v_lshlrev_b32_e32 v64, 3, v5
	v_lshlrev_b32_e32 v18, 4, v3
	v_xor_b32_e32 v5, 0x80000000, v2
	v_mov_b32_e32 v3, v5
	v_pk_mul_f32 v[6:7], v[4:5], v[2:3] op_sel:[1,0] op_sel_hi:[0,1]
	v_pk_fma_f32 v[6:7], v[4:5], v[4:5], v[6:7] op_sel_hi:[1,0,1]
	s_ashr_i32 s65, s64, 31
	v_xor_b32_e32 v12, 0x80000000, v7
	v_mov_b32_e32 v13, v7
	v_pk_mul_f32 v[10:11], v[6:7], v[12:13] op_sel:[1,0] op_sel_hi:[0,1]
	v_pk_fma_f32 v[10:11], v[6:7], v[6:7], v[10:11] op_sel_hi:[1,0,1]
	v_pk_mul_f32 v[8:9], v[2:3], v[6:7] op_sel:[0,1] op_sel_hi:[1,0]
	v_xor_b32_e32 v14, 0x80000000, v11
	v_mov_b32_e32 v15, v11
	v_pk_mul_f32 v[32:33], v[10:11], v[14:15] op_sel:[1,0] op_sel_hi:[0,1]
	v_pk_fma_f32 v[32:33], v[10:11], v[10:11], v[32:33] op_sel_hi:[1,0,1]
	v_pk_mul_f32 v[16:17], v[2:3], v[10:11] op_sel:[0,1] op_sel_hi:[1,0]
	v_pk_mul_f32 v[48:49], v[14:15], v[32:33] op_sel:[0,1] op_sel_hi:[1,0]
	v_pk_mul_f32 v[36:37], v[2:3], v[32:33] op_sel:[0,1] op_sel_hi:[1,0]
	v_pk_fma_f32 v[48:49], v[10:11], v[32:33], v[48:49] op_sel_hi:[0,1,1]
	v_pk_mul_f32 v[52:53], v[2:3], v[48:49] op_sel:[0,1] op_sel_hi:[1,0]
	v_pk_fma_f32 v[8:9], v[4:5], v[6:7], v[8:9] op_sel_hi:[0,1,1]
	v_pk_fma_f32 v[16:17], v[4:5], v[10:11], v[16:17] op_sel_hi:[0,1,1]
	v_pk_fma_f32 v[36:37], v[4:5], v[32:33], v[36:37] op_sel_hi:[0,1,1]
	v_pk_fma_f32 v[52:53], v[4:5], v[48:49], v[52:53] op_sel_hi:[0,1,1]
	v_and_b32_e32 v5, 0xffffff00, v18
	v_lshlrev_b32_e32 v18, 3, v5
	v_add3_u32 v18, 0, v64, v18
	v_ashrrev_i32_e32 v64, 2, v5
	v_add_u32_e32 v106, v18, v64
	ds_read2_b64 v[64:67], v106 offset1:16
	ds_read2_b64 v[68:71], v106 offset0:33 offset1:49
	ds_read2_b64 v[72:75], v106 offset0:66 offset1:82
	ds_read2_b64 v[76:79], v106 offset0:132 offset1:148
	ds_read2_b64 v[80:83], v106 offset0:99 offset1:115
	ds_read2_b64 v[84:87], v106 offset0:165 offset1:181
	ds_read2_b64 v[88:91], v106 offset0:198 offset1:214
	ds_read2_b64 v[92:95], v106 offset0:231 offset1:247
	s_waitcnt lgkmcnt(4)
	v_pk_add_f32 v[96:97], v[64:65], v[76:77]
	v_pk_add_f32 v[64:65], v[64:65], v[76:77] neg_lo:[0,1] neg_hi:[0,1]
	v_pk_add_f32 v[76:77], v[66:67], v[78:79]
	v_pk_add_f32 v[66:67], v[66:67], v[78:79] neg_lo:[0,1] neg_hi:[0,1]
	s_waitcnt lgkmcnt(1)
	v_pk_add_f32 v[98:99], v[74:75], v[90:91]
	v_pk_mul_f32 v[78:79], v[66:67], s[18:19]
	v_pk_add_f32 v[74:75], v[74:75], v[90:91] neg_lo:[0,1] neg_hi:[0,1]
	v_pk_fma_f32 v[66:67], v[66:67], s[16:17], v[78:79] op_sel:[0,0,1] op_sel_hi:[1,0,0]
	v_pk_add_f32 v[78:79], v[68:69], v[84:85]
	v_pk_add_f32 v[68:69], v[68:69], v[84:85] neg_lo:[0,1] neg_hi:[0,1]
	v_pk_mul_f32 v[90:91], v[74:75], s[40:41]
	v_pk_mul_f32 v[84:85], v[68:69], s[36:37]
	v_pk_fma_f32 v[74:75], v[74:75], s[68:69], v[90:91] op_sel:[0,0,1] op_sel_hi:[1,0,0] neg_lo:[1,0,0] neg_hi:[1,0,0]
	v_pk_fma_f32 v[68:69], v[68:69], s[66:67], v[84:85] op_sel:[0,0,1] op_sel_hi:[1,0,0]
	v_pk_add_f32 v[84:85], v[70:71], v[86:87]
	v_pk_add_f32 v[70:71], v[70:71], v[86:87] neg_lo:[0,1] neg_hi:[0,1]
	s_waitcnt lgkmcnt(0)
	v_pk_add_f32 v[90:91], v[80:81], v[92:93]
	v_pk_add_f32 v[80:81], v[80:81], v[92:93] neg_lo:[0,1] neg_hi:[0,1]
	v_pk_mul_f32 v[86:87], v[70:71], s[40:41]
	v_pk_mul_f32 v[92:93], v[80:81], s[36:37]
	v_pk_fma_f32 v[70:71], v[70:71], s[68:69], v[86:87] op_sel:[0,0,1] op_sel_hi:[1,0,0]
	v_pk_add_f32 v[86:87], v[72:73], v[88:89]
	v_pk_add_f32 v[88:89], v[72:73], v[88:89] neg_lo:[0,1] neg_hi:[0,1]
	v_pk_fma_f32 v[80:81], v[80:81], s[66:67], v[92:93] op_sel:[0,0,1] op_sel_hi:[1,0,0] neg_lo:[1,0,0] neg_hi:[1,0,0]
	v_pk_add_f32 v[92:93], v[82:83], v[94:95]
	v_pk_add_f32 v[82:83], v[82:83], v[94:95] neg_lo:[0,1] neg_hi:[0,1]
	s_nop 0
	v_pk_mul_f32 v[94:95], v[82:83], s[18:19]
	s_nop 0
	v_pk_fma_f32 v[82:83], v[82:83], s[16:17], v[94:95] op_sel:[0,0,1] op_sel_hi:[1,0,0] neg_lo:[1,0,0] neg_hi:[1,0,0]
	v_pk_add_f32 v[94:95], v[96:97], v[86:87]
	v_pk_add_f32 v[86:87], v[96:97], v[86:87] neg_lo:[0,1] neg_hi:[0,1]
	v_pk_add_f32 v[96:97], v[76:77], v[98:99]
	v_pk_add_f32 v[76:77], v[76:77], v[98:99] neg_lo:[0,1] neg_hi:[0,1]
	v_pk_add_f32 v[100:101], v[84:85], v[92:93]
	v_pk_add_f32 v[84:85], v[84:85], v[92:93] neg_lo:[0,1] neg_hi:[0,1]
	v_pk_add_f32 v[72:73], v[64:65], v[88:89] op_sel:[0,1] op_sel_hi:[1,0] neg_hi:[0,1]
	v_pk_add_f32 v[64:65], v[64:65], v[88:89] op_sel:[0,1] op_sel_hi:[1,0] neg_lo:[0,1]
	v_pk_add_f32 v[88:89], v[66:67], v[74:75]
	v_pk_add_f32 v[66:67], v[66:67], v[74:75] neg_lo:[0,1] neg_hi:[0,1]
	v_pk_mul_f32 v[98:99], v[76:77], s[36:37]
	v_pk_mul_f32 v[92:93], v[84:85], s[36:37]
	v_pk_mul_f32 v[74:75], v[66:67], s[36:37]
	v_pk_fma_f32 v[76:77], v[76:77], s[66:67], v[98:99] op_sel:[0,0,1] op_sel_hi:[1,0,0]
	v_pk_add_f32 v[98:99], v[78:79], v[90:91]
	v_pk_add_f32 v[90:91], v[78:79], v[90:91] neg_lo:[0,1] neg_hi:[0,1]
	v_pk_fma_f32 v[84:85], v[84:85], s[66:67], v[92:93] op_sel:[0,0,1] op_sel_hi:[1,0,0] neg_lo:[1,0,0] neg_hi:[1,0,0]
	v_pk_fma_f32 v[66:67], v[66:67], s[66:67], v[74:75] op_sel:[0,0,1] op_sel_hi:[1,0,0]
	v_pk_add_f32 v[74:75], v[68:69], v[80:81]
	v_pk_add_f32 v[92:93], v[70:71], v[82:83]
	v_pk_add_f32 v[70:71], v[70:71], v[82:83] neg_lo:[0,1] neg_hi:[0,1]
	v_pk_add_f32 v[68:69], v[68:69], v[80:81] neg_lo:[0,1] neg_hi:[0,1]
	v_pk_mul_f32 v[82:83], v[70:71], s[36:37]
	v_pk_add_f32 v[102:103], v[72:73], v[74:75]
	v_pk_add_f32 v[72:73], v[72:73], v[74:75] neg_lo:[0,1] neg_hi:[0,1]
	v_pk_add_f32 v[74:75], v[88:89], v[92:93]
	v_pk_add_f32 v[92:93], v[88:89], v[92:93] neg_lo:[0,1] neg_hi:[0,1]
	v_xor_b32_e32 v20, 0x80000000, v9
	v_mov_b32_e32 v21, v9
	v_pk_mul_f32 v[24:25], v[12:13], v[10:11] op_sel:[0,1] op_sel_hi:[1,0]
	v_xor_b32_e32 v81, 0x80000000, v68
	v_pk_fma_f32 v[70:71], v[70:71], s[66:67], v[82:83] op_sel:[0,0,1] op_sel_hi:[1,0,0] neg_lo:[1,0,0] neg_hi:[1,0,0]
	v_pk_add_f32 v[78:79], v[86:87], v[90:91] op_sel:[0,1] op_sel_hi:[1,0] neg_hi:[0,1]
	v_pk_add_f32 v[86:87], v[86:87], v[90:91] op_sel:[0,1] op_sel_hi:[1,0] neg_lo:[0,1]
	v_pk_add_f32 v[90:91], v[76:77], v[84:85]
	v_pk_add_f32 v[84:85], v[76:77], v[84:85] neg_lo:[0,1] neg_hi:[0,1]
	v_mov_b32_e32 v80, v69
	v_xor_b32_e32 v22, 0x80000000, v17
	v_mov_b32_e32 v23, v17
	v_pk_fma_f32 v[24:25], v[6:7], v[10:11], v[24:25] op_sel_hi:[0,1,1]
	v_pk_mul_f32 v[28:29], v[10:11], v[20:21] op_sel:[1,0] op_sel_hi:[0,1]
	v_pk_add_f32 v[68:69], v[64:65], v[80:81]
	v_pk_add_f32 v[64:65], v[64:65], v[80:81] neg_lo:[0,1] neg_hi:[0,1]
	v_pk_add_f32 v[80:81], v[66:67], v[70:71]
	v_pk_add_f32 v[70:71], v[66:67], v[70:71] neg_lo:[0,1] neg_hi:[0,1]
	v_pk_add_f32 v[88:89], v[72:73], v[92:93] op_sel:[0,1] op_sel_hi:[1,0] neg_hi:[0,1]
	v_xor_b32_e32 v26, 0x80000000, v25
	v_mov_b32_e32 v27, v25
	v_pk_fma_f32 v[28:29], v[10:11], v[8:9], v[28:29] op_sel_hi:[1,0,1]
	v_pk_add_f32 v[76:77], v[86:87], v[84:85] op_sel:[0,1] op_sel_hi:[1,0] neg_hi:[0,1]
	v_pk_add_f32 v[72:73], v[72:73], v[92:93] op_sel:[0,1] op_sel_hi:[1,0] neg_lo:[0,1]
	v_pk_mul_f32 v[92:93], v[22:23], v[88:89] op_sel:[0,1] op_sel_hi:[1,0]
	v_xor_b32_e32 v30, 0x80000000, v29
	v_mov_b32_e32 v31, v29
	v_pk_add_f32 v[82:83], v[94:95], v[98:99]
	v_pk_add_f32 v[94:95], v[94:95], v[98:99] neg_lo:[0,1] neg_hi:[0,1]
	v_pk_add_f32 v[98:99], v[96:97], v[100:101]
	v_pk_add_f32 v[66:67], v[64:65], v[70:71] op_sel:[0,1] op_sel_hi:[1,0] neg_hi:[0,1]
	v_pk_fma_f32 v[88:89], v[16:17], v[88:89], v[92:93] op_sel_hi:[0,1,1]
	v_pk_mul_f32 v[92:93], v[26:27], v[76:77] op_sel:[0,1] op_sel_hi:[1,0]
	v_xor_b32_e32 v34, 0x80000000, v33
	v_mov_b32_e32 v35, v33
	v_pk_mul_f32 v[40:41], v[12:13], v[32:33] op_sel:[0,1] op_sel_hi:[1,0]
	v_pk_add_f32 v[104:105], v[82:83], v[98:99]
	v_pk_add_f32 v[82:83], v[82:83], v[98:99] neg_lo:[0,1] neg_hi:[0,1]
	v_pk_fma_f32 v[76:77], v[24:25], v[76:77], v[92:93] op_sel_hi:[0,1,1]
	v_pk_mul_f32 v[92:93], v[30:31], v[66:67] op_sel:[0,1] op_sel_hi:[1,0]
	v_xor_b32_e32 v38, 0x80000000, v37
	v_mov_b32_e32 v39, v37
	v_pk_fma_f32 v[40:41], v[6:7], v[32:33], v[40:41] op_sel_hi:[0,1,1]
	v_pk_mul_f32 v[44:45], v[20:21], v[32:33] op_sel:[0,1] op_sel_hi:[1,0]
	v_pk_add_f32 v[84:85], v[86:87], v[84:85] op_sel:[0,1] op_sel_hi:[1,0] neg_lo:[0,1]
	v_pk_add_f32 v[86:87], v[102:103], v[74:75]
	v_pk_add_f32 v[74:75], v[102:103], v[74:75] neg_lo:[0,1] neg_hi:[0,1]
	v_pk_fma_f32 v[66:67], v[28:29], v[66:67], v[92:93] op_sel_hi:[0,1,1]
	v_pk_mul_f32 v[92:93], v[34:35], v[82:83] op_sel:[0,1] op_sel_hi:[1,0]
	v_xor_b32_e32 v42, 0x80000000, v41
	v_mov_b32_e32 v43, v41
	v_pk_fma_f32 v[44:45], v[8:9], v[32:33], v[44:45] op_sel_hi:[0,1,1]
	v_pk_add_f32 v[100:101], v[96:97], v[100:101] neg_lo:[0,1] neg_hi:[0,1]
	v_pk_add_f32 v[98:99], v[78:79], v[90:91]
	v_pk_add_f32 v[78:79], v[78:79], v[90:91] neg_lo:[0,1] neg_hi:[0,1]
	v_pk_fma_f32 v[82:83], v[32:33], v[82:83], v[92:93] op_sel_hi:[0,1,1]
	v_pk_mul_f32 v[92:93], v[38:39], v[74:75] op_sel:[0,1] op_sel_hi:[1,0]
	v_xor_b32_e32 v46, 0x80000000, v45
	v_mov_b32_e32 v47, v45
	v_pk_add_f32 v[90:91], v[68:69], v[80:81]
	v_pk_add_f32 v[68:69], v[68:69], v[80:81] neg_lo:[0,1] neg_hi:[0,1]
	v_pk_fma_f32 v[74:75], v[36:37], v[74:75], v[92:93] op_sel_hi:[0,1,1]
	v_pk_mul_f32 v[92:93], v[42:43], v[78:79] op_sel:[0,1] op_sel_hi:[1,0]
	v_xor_b32_e32 v50, 0x80000000, v49
	v_mov_b32_e32 v51, v49
	v_pk_mul_f32 v[56:57], v[12:13], v[48:49] op_sel:[0,1] op_sel_hi:[1,0]
	v_pk_add_f32 v[96:97], v[94:95], v[100:101] op_sel:[0,1] op_sel_hi:[1,0] neg_hi:[0,1]
	v_pk_add_f32 v[94:95], v[94:95], v[100:101] op_sel:[0,1] op_sel_hi:[1,0] neg_lo:[0,1]
	v_pk_fma_f32 v[78:79], v[40:41], v[78:79], v[92:93] op_sel_hi:[0,1,1]
	v_pk_mul_f32 v[92:93], v[46:47], v[68:69] op_sel:[0,1] op_sel_hi:[1,0]
	v_xor_b32_e32 v54, 0x80000000, v53
	v_mov_b32_e32 v55, v53
	v_pk_fma_f32 v[56:57], v[6:7], v[48:49], v[56:57] op_sel_hi:[0,1,1]
	v_pk_mul_f32 v[60:61], v[20:21], v[48:49] op_sel:[0,1] op_sel_hi:[1,0]
	v_pk_fma_f32 v[68:69], v[44:45], v[68:69], v[92:93] op_sel_hi:[0,1,1]
	v_pk_mul_f32 v[92:93], v[50:51], v[94:95] op_sel:[0,1] op_sel_hi:[1,0]
	v_xor_b32_e32 v58, 0x80000000, v57
	v_mov_b32_e32 v59, v57
	v_pk_fma_f32 v[60:61], v[8:9], v[48:49], v[60:61] op_sel_hi:[0,1,1]
	v_pk_add_f32 v[64:65], v[64:65], v[70:71] op_sel:[0,1] op_sel_hi:[1,0] neg_lo:[0,1]
	v_pk_mul_f32 v[70:71], v[2:3], v[86:87] op_sel:[0,1] op_sel_hi:[1,0]
	v_pk_fma_f32 v[92:93], v[48:49], v[94:95], v[92:93] op_sel_hi:[0,1,1]
	v_pk_mul_f32 v[94:95], v[54:55], v[72:73] op_sel:[0,1] op_sel_hi:[1,0]
	v_xor_b32_e32 v62, 0x80000000, v61
	v_mov_b32_e32 v63, v61
	v_pk_fma_f32 v[70:71], v[4:5], v[86:87], v[70:71] op_sel_hi:[0,1,1]
	v_pk_mul_f32 v[86:87], v[20:21], v[90:91] op_sel:[0,1] op_sel_hi:[1,0]
	v_pk_fma_f32 v[72:73], v[52:53], v[72:73], v[94:95] op_sel_hi:[0,1,1]
	v_pk_mul_f32 v[94:95], v[58:59], v[84:85] op_sel:[0,1] op_sel_hi:[1,0]
	v_add_u32_e32 v5, 0x2000, v5
	v_pk_mul_f32 v[80:81], v[12:13], v[98:99] op_sel:[0,1] op_sel_hi:[1,0]
	v_pk_fma_f32 v[86:87], v[8:9], v[90:91], v[86:87] op_sel_hi:[0,1,1]
	v_pk_mul_f32 v[90:91], v[14:15], v[96:97] op_sel:[0,1] op_sel_hi:[1,0]
	v_pk_fma_f32 v[84:85], v[56:57], v[84:85], v[94:95] op_sel_hi:[0,1,1]
	v_pk_mul_f32 v[94:95], v[62:63], v[64:65] op_sel:[0,1] op_sel_hi:[1,0]
	v_ashrrev_i32_e32 v5, 2, v5
	v_pk_fma_f32 v[80:81], v[6:7], v[98:99], v[80:81] op_sel_hi:[0,1,1]
	v_pk_fma_f32 v[90:91], v[10:11], v[96:97], v[90:91] op_sel_hi:[0,1,1]
	v_pk_fma_f32 v[64:65], v[60:61], v[64:65], v[94:95] op_sel_hi:[0,1,1]
	ds_write2_b64 v106, v[104:105], v[82:83] offset1:16
	ds_write2_b64 v106, v[90:91], v[92:93] offset0:33 offset1:49
	ds_write2_b64 v106, v[80:81], v[78:79] offset0:66 offset1:82
	ds_write2_b64 v106, v[76:77], v[84:85] offset0:99 offset1:115
	ds_write2_b64 v106, v[70:71], v[74:75] offset0:132 offset1:148
	ds_write2_b64 v106, v[88:89], v[72:73] offset0:165 offset1:181
	ds_write2_b64 v106, v[86:87], v[68:69] offset0:198 offset1:214
	ds_write2_b64 v106, v[66:67], v[64:65] offset0:231 offset1:247
	v_add3_u32 v18, v18, v5, s5
	ds_read2_b64 v[64:67], v18 offset1:16
	ds_read2_b64 v[68:71], v18 offset0:33 offset1:49
	ds_read2_b64 v[72:75], v18 offset0:66 offset1:82
	ds_read2_b64 v[76:79], v18 offset0:132 offset1:148
	ds_read2_b64 v[80:83], v18 offset0:99 offset1:115
	ds_read2_b64 v[84:87], v18 offset0:165 offset1:181
	ds_read2_b64 v[88:91], v18 offset0:198 offset1:214
	ds_read2_b64 v[92:95], v18 offset0:231 offset1:247
	s_waitcnt lgkmcnt(4)
	v_pk_add_f32 v[96:97], v[64:65], v[76:77]
	v_pk_add_f32 v[64:65], v[64:65], v[76:77] neg_lo:[0,1] neg_hi:[0,1]
	v_pk_add_f32 v[76:77], v[66:67], v[78:79]
	v_pk_add_f32 v[66:67], v[66:67], v[78:79] neg_lo:[0,1] neg_hi:[0,1]
	s_waitcnt lgkmcnt(1)
	v_pk_add_f32 v[98:99], v[74:75], v[90:91]
	v_pk_mul_f32 v[78:79], v[66:67], s[18:19]
	v_pk_add_f32 v[74:75], v[74:75], v[90:91] neg_lo:[0,1] neg_hi:[0,1]
	v_pk_fma_f32 v[66:67], v[66:67], s[16:17], v[78:79] op_sel:[0,0,1] op_sel_hi:[1,0,0]
	v_pk_add_f32 v[78:79], v[68:69], v[84:85]
	v_pk_add_f32 v[68:69], v[68:69], v[84:85] neg_lo:[0,1] neg_hi:[0,1]
	v_pk_mul_f32 v[90:91], v[74:75], s[40:41]
	v_pk_mul_f32 v[84:85], v[68:69], s[36:37]
	v_pk_fma_f32 v[74:75], v[74:75], s[68:69], v[90:91] op_sel:[0,0,1] op_sel_hi:[1,0,0] neg_lo:[1,0,0] neg_hi:[1,0,0]
	s_waitcnt lgkmcnt(0)
	v_pk_add_f32 v[90:91], v[80:81], v[92:93]
	v_pk_add_f32 v[80:81], v[80:81], v[92:93] neg_lo:[0,1] neg_hi:[0,1]
	v_pk_fma_f32 v[68:69], v[68:69], s[66:67], v[84:85] op_sel:[0,0,1] op_sel_hi:[1,0,0]
	v_pk_add_f32 v[84:85], v[70:71], v[86:87]
	v_pk_add_f32 v[70:71], v[70:71], v[86:87] neg_lo:[0,1] neg_hi:[0,1]
	v_pk_mul_f32 v[92:93], v[80:81], s[36:37]
	v_pk_mul_f32 v[86:87], v[70:71], s[40:41]
	v_pk_fma_f32 v[80:81], v[80:81], s[66:67], v[92:93] op_sel:[0,0,1] op_sel_hi:[1,0,0] neg_lo:[1,0,0] neg_hi:[1,0,0]
	v_pk_add_f32 v[92:93], v[82:83], v[94:95]
	v_pk_add_f32 v[82:83], v[82:83], v[94:95] neg_lo:[0,1] neg_hi:[0,1]
	v_pk_fma_f32 v[70:71], v[70:71], s[68:69], v[86:87] op_sel:[0,0,1] op_sel_hi:[1,0,0]
	v_pk_add_f32 v[86:87], v[72:73], v[88:89]
	v_pk_mul_f32 v[94:95], v[82:83], s[18:19]
	v_pk_add_f32 v[88:89], v[72:73], v[88:89] neg_lo:[0,1] neg_hi:[0,1]
	v_pk_fma_f32 v[82:83], v[82:83], s[16:17], v[94:95] op_sel:[0,0,1] op_sel_hi:[1,0,0] neg_lo:[1,0,0] neg_hi:[1,0,0]
	v_pk_add_f32 v[94:95], v[96:97], v[86:87]
	v_pk_add_f32 v[86:87], v[96:97], v[86:87] neg_lo:[0,1] neg_hi:[0,1]
	v_pk_add_f32 v[96:97], v[76:77], v[98:99]
	v_pk_add_f32 v[76:77], v[76:77], v[98:99] neg_lo:[0,1] neg_hi:[0,1]
	s_nop 0
	v_pk_mul_f32 v[98:99], v[76:77], s[36:37]
	v_pk_add_f32 v[100:101], v[84:85], v[92:93]
	v_pk_add_f32 v[84:85], v[84:85], v[92:93] neg_lo:[0,1] neg_hi:[0,1]
	v_pk_fma_f32 v[76:77], v[76:77], s[66:67], v[98:99] op_sel:[0,0,1] op_sel_hi:[1,0,0]
	v_pk_add_f32 v[98:99], v[78:79], v[90:91]
	v_pk_add_f32 v[90:91], v[78:79], v[90:91] neg_lo:[0,1] neg_hi:[0,1]
	v_pk_mul_f32 v[92:93], v[84:85], s[36:37]
	v_pk_add_f32 v[72:73], v[64:65], v[88:89] op_sel:[0,1] op_sel_hi:[1,0] neg_hi:[0,1]
	v_pk_add_f32 v[64:65], v[64:65], v[88:89] op_sel:[0,1] op_sel_hi:[1,0] neg_lo:[0,1]
	v_pk_add_f32 v[88:89], v[66:67], v[74:75]
	v_pk_add_f32 v[66:67], v[66:67], v[74:75] neg_lo:[0,1] neg_hi:[0,1]
	v_pk_fma_f32 v[84:85], v[84:85], s[66:67], v[92:93] op_sel:[0,0,1] op_sel_hi:[1,0,0] neg_lo:[1,0,0] neg_hi:[1,0,0]
	v_pk_mul_f32 v[74:75], v[66:67], s[36:37]
	s_nop 0
	v_pk_fma_f32 v[66:67], v[66:67], s[66:67], v[74:75] op_sel:[0,0,1] op_sel_hi:[1,0,0]
	v_pk_add_f32 v[74:75], v[68:69], v[80:81]
	v_pk_add_f32 v[92:93], v[70:71], v[82:83]
	v_pk_add_f32 v[70:71], v[70:71], v[82:83] neg_lo:[0,1] neg_hi:[0,1]
	v_pk_add_f32 v[78:79], v[86:87], v[90:91] op_sel:[0,1] op_sel_hi:[1,0] neg_hi:[0,1]
	v_pk_add_f32 v[86:87], v[86:87], v[90:91] op_sel:[0,1] op_sel_hi:[1,0] neg_lo:[0,1]
	v_pk_add_f32 v[90:91], v[76:77], v[84:85]
	v_pk_add_f32 v[84:85], v[76:77], v[84:85] neg_lo:[0,1] neg_hi:[0,1]
	v_pk_add_f32 v[80:81], v[68:69], v[80:81] neg_lo:[0,1] neg_hi:[0,1]
	v_pk_mul_f32 v[82:83], v[70:71], s[36:37]
	v_pk_add_f32 v[102:103], v[72:73], v[74:75]
	v_pk_add_f32 v[72:73], v[72:73], v[74:75] neg_lo:[0,1] neg_hi:[0,1]
	v_pk_add_f32 v[74:75], v[88:89], v[92:93]
	v_pk_fma_f32 v[70:71], v[70:71], s[66:67], v[82:83] op_sel:[0,0,1] op_sel_hi:[1,0,0] neg_lo:[1,0,0] neg_hi:[1,0,0]
	v_pk_add_f32 v[82:83], v[94:95], v[98:99]
	v_pk_add_f32 v[94:95], v[94:95], v[98:99] neg_lo:[0,1] neg_hi:[0,1]
	v_pk_add_f32 v[98:99], v[96:97], v[100:101]
	v_pk_add_f32 v[76:77], v[86:87], v[84:85] op_sel:[0,1] op_sel_hi:[1,0] neg_hi:[0,1]
	v_pk_add_f32 v[84:85], v[86:87], v[84:85] op_sel:[0,1] op_sel_hi:[1,0] neg_lo:[0,1]
	v_pk_add_f32 v[86:87], v[102:103], v[74:75]
	v_pk_add_f32 v[100:101], v[96:97], v[100:101] neg_lo:[0,1] neg_hi:[0,1]
	v_pk_add_f32 v[68:69], v[64:65], v[80:81] op_sel:[0,1] op_sel_hi:[1,0] neg_hi:[0,1]
	v_pk_add_f32 v[64:65], v[64:65], v[80:81] op_sel:[0,1] op_sel_hi:[1,0] neg_lo:[0,1]
	v_pk_add_f32 v[80:81], v[66:67], v[70:71]
	v_pk_add_f32 v[104:105], v[82:83], v[98:99]
	v_pk_add_f32 v[82:83], v[82:83], v[98:99] neg_lo:[0,1] neg_hi:[0,1]
	v_pk_add_f32 v[98:99], v[78:79], v[90:91]
	v_pk_mul_f32 v[2:3], v[2:3], v[86:87] op_sel:[0,1] op_sel_hi:[1,0]
	v_pk_add_f32 v[92:93], v[88:89], v[92:93] neg_lo:[0,1] neg_hi:[0,1]
	v_pk_add_f32 v[78:79], v[78:79], v[90:91] neg_lo:[0,1] neg_hi:[0,1]
	v_pk_add_f32 v[90:91], v[68:69], v[80:81]
	v_pk_fma_f32 v[2:3], v[4:5], v[86:87], v[2:3] op_sel_hi:[0,1,1]
	v_pk_mul_f32 v[4:5], v[12:13], v[98:99] op_sel:[0,1] op_sel_hi:[1,0]
	v_pk_add_f32 v[70:71], v[66:67], v[70:71] neg_lo:[0,1] neg_hi:[0,1]
	v_pk_add_f32 v[96:97], v[94:95], v[100:101] op_sel:[0,1] op_sel_hi:[1,0] neg_hi:[0,1]
	v_pk_fma_f32 v[4:5], v[6:7], v[98:99], v[4:5] op_sel_hi:[0,1,1]
	v_pk_mul_f32 v[6:7], v[20:21], v[90:91] op_sel:[0,1] op_sel_hi:[1,0]
	v_pk_add_f32 v[88:89], v[72:73], v[92:93] op_sel:[0,1] op_sel_hi:[1,0] neg_hi:[0,1]
	v_pk_fma_f32 v[6:7], v[8:9], v[90:91], v[6:7] op_sel_hi:[0,1,1]
	v_pk_mul_f32 v[8:9], v[14:15], v[96:97] op_sel:[0,1] op_sel_hi:[1,0]
	v_pk_add_f32 v[66:67], v[64:65], v[70:71] op_sel:[0,1] op_sel_hi:[1,0] neg_hi:[0,1]
	v_pk_fma_f32 v[8:9], v[10:11], v[96:97], v[8:9] op_sel_hi:[0,1,1]
	v_pk_mul_f32 v[10:11], v[22:23], v[88:89] op_sel:[0,1] op_sel_hi:[1,0]
	v_pk_add_f32 v[94:95], v[94:95], v[100:101] op_sel:[0,1] op_sel_hi:[1,0] neg_lo:[0,1]
	v_pk_add_f32 v[74:75], v[102:103], v[74:75] neg_lo:[0,1] neg_hi:[0,1]
	v_pk_add_f32 v[72:73], v[72:73], v[92:93] op_sel:[0,1] op_sel_hi:[1,0] neg_lo:[0,1]
	v_pk_add_f32 v[68:69], v[68:69], v[80:81] neg_lo:[0,1] neg_hi:[0,1]
	v_pk_add_f32 v[64:65], v[64:65], v[70:71] op_sel:[0,1] op_sel_hi:[1,0] neg_lo:[0,1]
	v_pk_fma_f32 v[10:11], v[16:17], v[88:89], v[10:11] op_sel_hi:[0,1,1]
	v_pk_mul_f32 v[12:13], v[26:27], v[76:77] op_sel:[0,1] op_sel_hi:[1,0]
	v_pk_mul_f32 v[14:15], v[30:31], v[66:67] op_sel:[0,1] op_sel_hi:[1,0]
	v_pk_mul_f32 v[16:17], v[34:35], v[82:83] op_sel:[0,1] op_sel_hi:[1,0]
	v_pk_fma_f32 v[12:13], v[24:25], v[76:77], v[12:13] op_sel_hi:[0,1,1]
	v_pk_fma_f32 v[14:15], v[28:29], v[66:67], v[14:15] op_sel_hi:[0,1,1]
	v_pk_fma_f32 v[16:17], v[32:33], v[82:83], v[16:17] op_sel_hi:[0,1,1]
	v_pk_mul_f32 v[20:21], v[38:39], v[74:75] op_sel:[0,1] op_sel_hi:[1,0]
	v_pk_mul_f32 v[22:23], v[42:43], v[78:79] op_sel:[0,1] op_sel_hi:[1,0]
	v_pk_mul_f32 v[24:25], v[46:47], v[68:69] op_sel:[0,1] op_sel_hi:[1,0]
	v_pk_mul_f32 v[26:27], v[50:51], v[94:95] op_sel:[0,1] op_sel_hi:[1,0]
	v_pk_mul_f32 v[28:29], v[54:55], v[72:73] op_sel:[0,1] op_sel_hi:[1,0]
	v_pk_mul_f32 v[30:31], v[58:59], v[84:85] op_sel:[0,1] op_sel_hi:[1,0]
	v_pk_mul_f32 v[32:33], v[62:63], v[64:65] op_sel:[0,1] op_sel_hi:[1,0]
	v_pk_fma_f32 v[20:21], v[36:37], v[74:75], v[20:21] op_sel_hi:[0,1,1]
	v_pk_fma_f32 v[22:23], v[40:41], v[78:79], v[22:23] op_sel_hi:[0,1,1]
	v_pk_fma_f32 v[24:25], v[44:45], v[68:69], v[24:25] op_sel_hi:[0,1,1]
	v_pk_fma_f32 v[26:27], v[48:49], v[94:95], v[26:27] op_sel_hi:[0,1,1]
	v_pk_fma_f32 v[28:29], v[52:53], v[72:73], v[28:29] op_sel_hi:[0,1,1]
	v_pk_fma_f32 v[30:31], v[56:57], v[84:85], v[30:31] op_sel_hi:[0,1,1]
	v_pk_fma_f32 v[32:33], v[60:61], v[64:65], v[32:33] op_sel_hi:[0,1,1]
	ds_write2_b64 v18, v[104:105], v[16:17] offset1:16
	ds_write2_b64 v18, v[8:9], v[26:27] offset0:33 offset1:49
	ds_write2_b64 v18, v[4:5], v[22:23] offset0:66 offset1:82
	ds_write2_b64 v18, v[12:13], v[30:31] offset0:99 offset1:115
	ds_write2_b64 v18, v[2:3], v[20:21] offset0:132 offset1:148
	ds_write2_b64 v18, v[10:11], v[28:29] offset0:165 offset1:181
	ds_write2_b64 v18, v[6:7], v[24:25] offset0:198 offset1:214
	ds_write2_b64 v18, v[14:15], v[32:33] offset0:231 offset1:247
	v_ashrrev_i32_e32 v2, 31, v210
	v_add_u32_sdwa v2, v210, v2 dst_sel:DWORD dst_unused:UNUSED_PAD src0_sel:DWORD src1_sel:BYTE_3
	s_lshl_b64 s[0:1], s[64:65], 15
	v_and_b32_e32 v2, 0xffffff00, v2
	s_add_u32 s0, s29, s0
	v_sub_u32_e32 v2, v210, v2
	s_addc_u32 s1, s85, s1
	v_ashrrev_i32_e32 v3, 31, v2
	v_lshl_add_u64 v[14:15], v[2:3], 3, s[0:1]
	s_movk_i32 s0, 0x1000
	v_add_co_u32_e32 v16, vcc, s0, v14
	s_movk_i32 s0, 0x3000
	s_nop 0
	v_addc_co_u32_e32 v17, vcc, 0, v15, vcc
	v_add_co_u32_e32 v2, vcc, s92, v14
	s_waitcnt lgkmcnt(0)
	s_nop 0
	v_addc_co_u32_e32 v3, vcc, 0, v15, vcc
	v_add_co_u32_e32 v22, vcc, s0, v14
	s_movk_i32 s0, 0x5000
	s_nop 0
	v_addc_co_u32_e32 v23, vcc, 0, v15, vcc
	v_add_co_u32_e32 v8, vcc, s95, v14
	s_barrier
	s_nop 0
	v_addc_co_u32_e32 v9, vcc, 0, v15, vcc
	v_add_co_u32_e32 v26, vcc, s0, v14
	s_nop 1
	v_addc_co_u32_e32 v27, vcc, 0, v15, vcc
	v_add_co_u32_e32 v10, vcc, s96, v14
	global_load_dwordx2 v[12:13], v[2:3], off nt
	global_load_dwordx2 v[6:7], v[2:3], off offset:2048 nt
	global_load_dwordx2 v[4:5], v[8:9], off offset:-4096 nt
	global_load_dwordx2 v[122:123], v[8:9], off nt
	v_addc_co_u32_e32 v11, vcc, 0, v15, vcc
	v_add_co_u32_e32 v28, vcc, s97, v14
	global_load_dwordx2 v[46:47], v[8:9], off offset:2048 nt
	global_load_dwordx2 v[38:39], v[10:11], off offset:-4096 nt
	global_load_dwordx2 v[20:21], v[10:11], off nt
	s_nop 0
	global_load_dwordx2 v[10:11], v[10:11], off offset:2048 nt
	v_addc_co_u32_e32 v29, vcc, 0, v15, vcc
	global_load_dwordx2 v[24:25], v[2:3], off offset:-4096 nt
	s_nop 0
	global_load_dwordx2 v[26:27], v[26:27], off offset:2048 nt
	s_nop 0
	global_load_dwordx2 v[8:9], v[28:29], off nt
	global_load_dwordx2 v[2:3], v[28:29], off offset:2048 nt
	global_load_dwordx2 v[30:31], v[14:15], off offset:2048 nt
	s_nop 0
	global_load_dwordx2 v[28:29], v[16:17], off offset:2048 nt
	s_nop 0
	global_load_dwordx2 v[16:17], v[22:23], off offset:2048 nt
	global_load_dwordx2 v[32:33], v[14:15], off nt
	v_mov_b32_e32 v14, v210
	s_waitcnt vmcnt(15)
	v_cvt_f32_f16_sdwa v164, v12 dst_sel:DWORD dst_unused:UNUSED_PAD src0_sel:WORD_1
	v_ashrrev_i32_e32 v15, 31, v14
	v_add_u32_sdwa v15, v14, v15 dst_sel:DWORD dst_unused:UNUSED_PAD src0_sel:DWORD src1_sel:BYTE_3
	v_ashrrev_i32_e32 v15, 8, v15
	v_mul_i32_i24_e32 v18, 0x100, v15
	v_sub_u32_e32 v18, v14, v18
	v_lshlrev_b32_e32 v14, 13, v15
	v_lshlrev_b32_e32 v15, 1, v18
	v_bfrev_b32_e32 v15, v15
	v_lshrrev_b32_e32 v15, 23, v15
	v_sub_u32_e32 v15, 0x200, v15
	v_bfrev_b32_e32 v15, v15
	v_lshrrev_b32_e32 v15, 19, v15
	v_and_b32_e32 v15, 0x1ff0, v15
	v_cmp_eq_u32_e64 s[0:1], 0, v18
	v_lshl_add_u32 v22, v18, 5, v14
	v_lshl_add_u32 v23, v22, 3, 0
	v_cndmask_b32_e64 v15, v15, 16, s[0:1]
	v_or_b32_e32 v14, v15, v14
	v_ashrrev_i32_e32 v22, 2, v22
	v_ashrrev_i32_e32 v15, 5, v14
	v_add_u32_e32 v211, v23, v22
	v_lshlrev_b32_e32 v14, 3, v14
	v_lshlrev_b32_e32 v15, 3, v15
	v_add3_u32 v212, 0, v14, v15
	ds_read2_b64 v[34:37], v211 offset1:1
	ds_read2_b64 v[40:43], v211 offset0:2 offset1:3
	ds_read2_b64 v[48:51], v212 offset1:1
	ds_read2_b64 v[52:55], v212 offset0:2 offset1:3
	ds_read2_b64 v[56:59], v211 offset0:4 offset1:5
	ds_read2_b64 v[60:63], v211 offset0:6 offset1:7
	ds_read2_b64 v[68:71], v212 offset0:4 offset1:5
	ds_read2_b64 v[72:75], v212 offset0:6 offset1:7
	ds_read2_b64 v[64:67], v211 offset0:8 offset1:9
	ds_read2_b64 v[76:79], v211 offset0:10 offset1:11
	ds_read2_b64 v[80:83], v212 offset0:8 offset1:9
	ds_read2_b64 v[98:101], v212 offset0:10 offset1:11
	ds_read2_b64 v[84:87], v211 offset0:12 offset1:13
	ds_read2_b64 v[88:91], v211 offset0:14 offset1:15
	ds_read2_b64 v[102:105], v212 offset0:12 offset1:13
	ds_read2_b64 v[106:109], v212 offset0:14 offset1:15
	s_waitcnt lgkmcnt(7)
	v_pk_add_f32 v[14:15], v[34:35], v[64:65]
	v_pk_add_f32 v[22:23], v[34:35], v[64:65] neg_lo:[0,1] neg_hi:[0,1]
	v_pk_add_f32 v[34:35], v[36:37], v[66:67]
	v_pk_add_f32 v[36:37], v[36:37], v[66:67] neg_lo:[0,1] neg_hi:[0,1]
	v_cmp_ne_u32_e32 vcc, 0, v18
	v_pk_mul_f32 v[44:45], v[36:37], s[18:19]
	v_bfrev_b32_e32 v18, v18
	v_pk_fma_f32 v[36:37], v[36:37], s[16:17], v[44:45] op_sel:[0,0,1] op_sel_hi:[1,0,0]
	s_waitcnt lgkmcnt(6)
	v_pk_add_f32 v[44:45], v[40:41], v[76:77]
	v_pk_add_f32 v[40:41], v[40:41], v[76:77] neg_lo:[0,1] neg_hi:[0,1]
	v_cvt_f32_ubyte3_e32 v18, v18
	v_pk_mul_f32 v[64:65], v[40:41], s[36:37]
	v_mul_f32_e32 v18, 0x38800000, v18
	v_pk_fma_f32 v[40:41], v[40:41], s[66:67], v[64:65] op_sel:[0,0,1] op_sel_hi:[1,0,0]
	v_pk_add_f32 v[64:65], v[42:43], v[78:79]
	v_pk_add_f32 v[42:43], v[42:43], v[78:79] neg_lo:[0,1] neg_hi:[0,1]
	s_waitcnt lgkmcnt(3)
	v_pk_add_f32 v[78:79], v[58:59], v[86:87]
	v_pk_mul_f32 v[66:67], v[42:43], s[40:41]
	v_pk_add_f32 v[58:59], v[58:59], v[86:87] neg_lo:[0,1] neg_hi:[0,1]
	v_pk_fma_f32 v[42:43], v[42:43], s[68:69], v[66:67] op_sel:[0,0,1] op_sel_hi:[1,0,0]
	v_pk_add_f32 v[66:67], v[56:57], v[84:85]
	v_pk_add_f32 v[76:77], v[56:57], v[84:85] neg_lo:[0,1] neg_hi:[0,1]
	v_pk_mul_f32 v[84:85], v[58:59], s[40:41]
	s_nop 0
	v_pk_fma_f32 v[58:59], v[58:59], s[68:69], v[84:85] op_sel:[0,0,1] op_sel_hi:[1,0,0] neg_lo:[1,0,0] neg_hi:[1,0,0]
	s_waitcnt lgkmcnt(2)
	v_pk_add_f32 v[84:85], v[60:61], v[88:89]
	v_pk_add_f32 v[60:61], v[60:61], v[88:89] neg_lo:[0,1] neg_hi:[0,1]
	s_nop 0
	v_pk_mul_f32 v[86:87], v[60:61], s[36:37]
	v_pk_add_f32 v[56:57], v[22:23], v[76:77] op_sel:[0,1] op_sel_hi:[1,0] neg_hi:[0,1]
	v_pk_fma_f32 v[60:61], v[60:61], s[66:67], v[86:87] op_sel:[0,0,1] op_sel_hi:[1,0,0] neg_lo:[1,0,0] neg_hi:[1,0,0]
	v_pk_add_f32 v[86:87], v[62:63], v[90:91]
	v_pk_add_f32 v[62:63], v[62:63], v[90:91] neg_lo:[0,1] neg_hi:[0,1]
	v_pk_add_f32 v[90:91], v[64:65], v[86:87]
	v_pk_mul_f32 v[88:89], v[62:63], s[18:19]
	v_pk_add_f32 v[64:65], v[64:65], v[86:87] neg_lo:[0,1] neg_hi:[0,1]
	v_pk_fma_f32 v[62:63], v[62:63], s[16:17], v[88:89] op_sel:[0,0,1] op_sel_hi:[1,0,0] neg_lo:[1,0,0] neg_hi:[1,0,0]
	v_pk_add_f32 v[88:89], v[14:15], v[66:67]
	v_pk_add_f32 v[14:15], v[14:15], v[66:67] neg_lo:[0,1] neg_hi:[0,1]
	v_pk_add_f32 v[66:67], v[34:35], v[78:79]
	v_pk_add_f32 v[34:35], v[34:35], v[78:79] neg_lo:[0,1] neg_hi:[0,1]
	v_pk_add_f32 v[22:23], v[22:23], v[76:77] op_sel:[0,1] op_sel_hi:[1,0] neg_lo:[0,1]
	v_pk_mul_f32 v[78:79], v[34:35], s[36:37]
	v_pk_add_f32 v[76:77], v[36:37], v[58:59]
	v_pk_add_f32 v[36:37], v[36:37], v[58:59] neg_lo:[0,1] neg_hi:[0,1]
	v_pk_fma_f32 v[34:35], v[34:35], s[66:67], v[78:79] op_sel:[0,0,1] op_sel_hi:[1,0,0]
	v_pk_add_f32 v[78:79], v[44:45], v[84:85]
	v_pk_add_f32 v[84:85], v[44:45], v[84:85] neg_lo:[0,1] neg_hi:[0,1]
	v_pk_mul_f32 v[86:87], v[64:65], s[36:37]
	v_pk_mul_f32 v[58:59], v[36:37], s[36:37]
	v_pk_fma_f32 v[64:65], v[64:65], s[66:67], v[86:87] op_sel:[0,0,1] op_sel_hi:[1,0,0] neg_lo:[1,0,0] neg_hi:[1,0,0]
	v_pk_fma_f32 v[36:37], v[36:37], s[66:67], v[58:59] op_sel:[0,0,1] op_sel_hi:[1,0,0]
	v_pk_add_f32 v[58:59], v[40:41], v[60:61]
	v_pk_add_f32 v[86:87], v[42:43], v[62:63]
	v_pk_add_f32 v[42:43], v[42:43], v[62:63] neg_lo:[0,1] neg_hi:[0,1]
	s_nop 0
	v_pk_mul_f32 v[62:63], v[42:43], s[36:37]
	v_pk_add_f32 v[44:45], v[14:15], v[84:85] op_sel:[0,1] op_sel_hi:[1,0] neg_hi:[0,1]
	v_pk_add_f32 v[14:15], v[14:15], v[84:85] op_sel:[0,1] op_sel_hi:[1,0] neg_lo:[0,1]
	v_pk_add_f32 v[84:85], v[34:35], v[64:65]
	v_pk_add_f32 v[64:65], v[34:35], v[64:65] neg_lo:[0,1] neg_hi:[0,1]
	v_pk_add_f32 v[94:95], v[56:57], v[58:59]
	v_pk_add_f32 v[56:57], v[56:57], v[58:59] neg_lo:[0,1] neg_hi:[0,1]
	v_pk_add_f32 v[58:59], v[76:77], v[86:87]
	v_pk_fma_f32 v[42:43], v[42:43], s[66:67], v[62:63] op_sel:[0,0,1] op_sel_hi:[1,0,0] neg_lo:[1,0,0] neg_hi:[1,0,0]
	v_pk_add_f32 v[62:63], v[88:89], v[78:79]
	v_pk_add_f32 v[78:79], v[88:89], v[78:79] neg_lo:[0,1] neg_hi:[0,1]
	v_pk_add_f32 v[88:89], v[66:67], v[90:91]
	v_pk_add_f32 v[110:111], v[76:77], v[86:87] neg_lo:[0,1] neg_hi:[0,1]
	v_pk_add_f32 v[86:87], v[94:95], v[58:59]
	v_pk_add_f32 v[34:35], v[94:95], v[58:59] neg_lo:[0,1] neg_hi:[0,1]
	v_pk_add_f32 v[58:59], v[50:51], v[82:83]
	v_pk_add_f32 v[50:51], v[50:51], v[82:83] neg_lo:[0,1] neg_hi:[0,1]
	v_pk_add_f32 v[60:61], v[40:41], v[60:61] neg_lo:[0,1] neg_hi:[0,1]
	v_pk_add_f32 v[148:149], v[62:63], v[88:89]
	v_pk_add_f32 v[138:139], v[62:63], v[88:89] neg_lo:[0,1] neg_hi:[0,1]
	v_pk_mul_f32 v[62:63], v[50:51], s[18:19]
	v_pk_add_f32 v[90:91], v[66:67], v[90:91] neg_lo:[0,1] neg_hi:[0,1]
	v_pk_fma_f32 v[50:51], v[50:51], s[16:17], v[62:63] op_sel:[0,0,1] op_sel_hi:[1,0,0]
	v_pk_add_f32 v[62:63], v[52:53], v[98:99]
	v_pk_add_f32 v[52:53], v[52:53], v[98:99] neg_lo:[0,1] neg_hi:[0,1]
	v_pk_add_f32 v[112:113], v[22:23], v[60:61] op_sel:[0,1] op_sel_hi:[1,0] neg_hi:[0,1]
	v_pk_add_f32 v[114:115], v[22:23], v[60:61] op_sel:[0,1] op_sel_hi:[1,0] neg_lo:[0,1]
	v_pk_add_f32 v[96:97], v[44:45], v[84:85]
	v_pk_add_f32 v[66:67], v[44:45], v[84:85] neg_lo:[0,1] neg_hi:[0,1]
	v_pk_add_f32 v[60:61], v[14:15], v[64:65] op_sel:[0,1] op_sel_hi:[1,0] neg_hi:[0,1]
	v_pk_add_f32 v[84:85], v[14:15], v[64:65] op_sel:[0,1] op_sel_hi:[1,0] neg_lo:[0,1]
	v_pk_mul_f32 v[64:65], v[52:53], s[36:37]
	s_nop 0
	v_pk_fma_f32 v[52:53], v[52:53], s[66:67], v[64:65] op_sel:[0,0,1] op_sel_hi:[1,0,0]
	v_pk_add_f32 v[64:65], v[54:55], v[100:101]
	v_pk_add_f32 v[54:55], v[54:55], v[100:101] neg_lo:[0,1] neg_hi:[0,1]
	s_nop 0
	v_pk_mul_f32 v[76:77], v[54:55], s[40:41]
	v_pk_add_f32 v[92:93], v[78:79], v[90:91] op_sel:[0,1] op_sel_hi:[1,0] neg_hi:[0,1]
	v_pk_fma_f32 v[54:55], v[54:55], s[68:69], v[76:77] op_sel:[0,0,1] op_sel_hi:[1,0,0]
	s_waitcnt lgkmcnt(1)
	v_pk_add_f32 v[76:77], v[68:69], v[102:103]
	v_pk_add_f32 v[68:69], v[68:69], v[102:103] neg_lo:[0,1] neg_hi:[0,1]
	v_pk_add_f32 v[88:89], v[78:79], v[90:91] op_sel:[0,1] op_sel_hi:[1,0] neg_lo:[0,1]
	v_xor_b32_e32 v79, 0x80000000, v68
	v_mov_b32_e32 v78, v69
	v_pk_add_f32 v[68:69], v[70:71], v[104:105]
	v_pk_add_f32 v[70:71], v[70:71], v[104:105] neg_lo:[0,1] neg_hi:[0,1]
	v_pk_add_f32 v[40:41], v[56:57], v[110:111] op_sel:[0,1] op_sel_hi:[1,0] neg_hi:[0,1]
	v_pk_add_f32 v[44:45], v[56:57], v[110:111] op_sel:[0,1] op_sel_hi:[1,0] neg_lo:[0,1]
	v_pk_add_f32 v[56:57], v[48:49], v[80:81]
	v_pk_add_f32 v[48:49], v[48:49], v[80:81] neg_lo:[0,1] neg_hi:[0,1]
	v_pk_mul_f32 v[80:81], v[70:71], s[40:41]
	v_cndmask_b32_e64 v18, v18, v208, s[0:1]
	v_pk_fma_f32 v[70:71], v[70:71], s[68:69], v[80:81] op_sel:[0,0,1] op_sel_hi:[1,0,0] neg_lo:[1,0,0] neg_hi:[1,0,0]
	s_waitcnt lgkmcnt(0)
	v_pk_add_f32 v[80:81], v[72:73], v[106:107]
	v_pk_add_f32 v[72:73], v[72:73], v[106:107] neg_lo:[0,1] neg_hi:[0,1]
	v_pk_add_f32 v[22:23], v[36:37], v[42:43]
	v_pk_mul_f32 v[82:83], v[72:73], s[36:37]
	v_pk_add_f32 v[116:117], v[36:37], v[42:43] neg_lo:[0,1] neg_hi:[0,1]
	v_pk_fma_f32 v[72:73], v[72:73], s[66:67], v[82:83] op_sel:[0,0,1] op_sel_hi:[1,0,0] neg_lo:[1,0,0] neg_hi:[1,0,0]
	v_pk_add_f32 v[82:83], v[74:75], v[108:109]
	v_pk_add_f32 v[74:75], v[74:75], v[108:109] neg_lo:[0,1] neg_hi:[0,1]
	s_nop 0
	v_pk_mul_f32 v[90:91], v[74:75], s[18:19]
	s_nop 0
	v_pk_fma_f32 v[74:75], v[74:75], s[16:17], v[90:91] op_sel:[0,0,1] op_sel_hi:[1,0,0] neg_lo:[1,0,0] neg_hi:[1,0,0]
	v_pk_add_f32 v[90:91], v[56:57], v[76:77]
	v_pk_add_f32 v[56:57], v[56:57], v[76:77] neg_lo:[0,1] neg_hi:[0,1]
	v_pk_add_f32 v[76:77], v[58:59], v[68:69]
	v_pk_add_f32 v[58:59], v[58:59], v[68:69] neg_lo:[0,1] neg_hi:[0,1]
	v_pk_add_f32 v[14:15], v[114:115], v[116:117] op_sel:[0,1] op_sel_hi:[1,0] neg_hi:[0,1]
	v_pk_mul_f32 v[68:69], v[58:59], s[36:37]
	v_pk_add_f32 v[36:37], v[114:115], v[116:117] op_sel:[0,1] op_sel_hi:[1,0] neg_lo:[0,1]
	v_pk_fma_f32 v[58:59], v[58:59], s[66:67], v[68:69] op_sel:[0,0,1] op_sel_hi:[1,0,0]
	v_pk_add_f32 v[68:69], v[62:63], v[80:81]
	v_pk_add_f32 v[80:81], v[62:63], v[80:81] neg_lo:[0,1] neg_hi:[0,1]
	s_waitcnt vmcnt(0)
	v_cvt_f32_f16_e32 v193, v33
	s_nop 0
	s_nop 0
	v_pk_add_f32 v[62:63], v[64:65], v[82:83]
	v_pk_add_f32 v[64:65], v[64:65], v[82:83] neg_lo:[0,1] neg_hi:[0,1]
	v_cvt_f32_f16_sdwa v192, v32 dst_sel:DWORD dst_unused:UNUSED_PAD src0_sel:WORD_1
	v_pk_mul_f32 v[82:83], v[64:65], s[36:37]
	v_cvt_f32_f16_e32 v194, v32
	v_pk_fma_f32 v[64:65], v[64:65], s[66:67], v[82:83] op_sel:[0,0,1] op_sel_hi:[1,0,0] neg_lo:[1,0,0] neg_hi:[1,0,0]
	v_pk_add_f32 v[82:83], v[48:49], v[78:79]
	v_pk_add_f32 v[48:49], v[48:49], v[78:79] neg_lo:[0,1] neg_hi:[0,1]
	v_pk_add_f32 v[78:79], v[50:51], v[70:71]
	v_pk_add_f32 v[50:51], v[50:51], v[70:71] neg_lo:[0,1] neg_hi:[0,1]
	v_cvt_f32_f16_sdwa v195, v33 dst_sel:DWORD dst_unused:UNUSED_PAD src0_sel:WORD_1
	v_pk_mul_f32 v[70:71], v[50:51], s[36:37]
	v_cvt_f32_f16_sdwa v170, v30 dst_sel:DWORD dst_unused:UNUSED_PAD src0_sel:WORD_1
	v_pk_fma_f32 v[50:51], v[50:51], s[66:67], v[70:71] op_sel:[0,0,1] op_sel_hi:[1,0,0]
	v_pk_add_f32 v[70:71], v[52:53], v[72:73]
	v_pk_add_f32 v[72:73], v[52:53], v[72:73] neg_lo:[0,1] neg_hi:[0,1]
	v_cvt_f32_f16_e32 v171, v31
	s_nop 0
	s_nop 0
	v_pk_add_f32 v[52:53], v[54:55], v[74:75]
	v_pk_add_f32 v[54:55], v[54:55], v[74:75] neg_lo:[0,1] neg_hi:[0,1]
	v_cvt_f32_f16_sdwa v185, v31 dst_sel:DWORD dst_unused:UNUSED_PAD src0_sel:WORD_1
	v_pk_mul_f32 v[74:75], v[54:55], s[36:37]
	v_cvt_f32_f16_e32 v184, v30
	v_pk_fma_f32 v[54:55], v[54:55], s[66:67], v[74:75] op_sel:[0,0,1] op_sel_hi:[1,0,0] neg_lo:[1,0,0] neg_hi:[1,0,0]
	v_pk_add_f32 v[74:75], v[90:91], v[68:69]
	v_pk_add_f32 v[68:69], v[90:91], v[68:69] neg_lo:[0,1] neg_hi:[0,1]
	v_pk_add_f32 v[90:91], v[76:77], v[62:63]
	v_pk_add_f32 v[62:63], v[76:77], v[62:63] neg_lo:[0,1] neg_hi:[0,1]
	v_cvt_f32_f16_sdwa v172, v24 dst_sel:DWORD dst_unused:UNUSED_PAD src0_sel:WORD_1
	v_xor_b32_e32 v77, 0x80000000, v62
	v_mov_b32_e32 v76, v63
	v_pk_add_f32 v[62:63], v[56:57], v[80:81] op_sel:[0,1] op_sel_hi:[1,0] neg_hi:[0,1]
	v_pk_add_f32 v[56:57], v[56:57], v[80:81] op_sel:[0,1] op_sel_hi:[1,0] neg_lo:[0,1]
	v_pk_add_f32 v[80:81], v[58:59], v[64:65]
	v_pk_add_f32 v[58:59], v[58:59], v[64:65] neg_lo:[0,1] neg_hi:[0,1]
	v_cvt_f32_f16_e32 v173, v25
	v_xor_b32_e32 v65, 0x80000000, v58
	v_mov_b32_e32 v64, v59
	v_pk_add_f32 v[58:59], v[82:83], v[70:71]
	v_pk_add_f32 v[70:71], v[82:83], v[70:71] neg_lo:[0,1] neg_hi:[0,1]
	v_pk_add_f32 v[82:83], v[78:79], v[52:53]
	v_pk_add_f32 v[52:53], v[78:79], v[52:53] neg_lo:[0,1] neg_hi:[0,1]
	v_pk_add_f32 v[118:119], v[58:59], v[82:83]
	v_pk_add_f32 v[134:135], v[58:59], v[82:83] neg_lo:[0,1] neg_hi:[0,1]
	v_cos_f32_e32 v83, v18
	v_sin_f32_e32 v82, v18
	v_cvt_f32_f16_sdwa v181, v25 dst_sel:DWORD dst_unused:UNUSED_PAD src0_sel:WORD_1
	v_cvt_f32_f16_e32 v180, v24
	v_cvt_f32_f16_sdwa v174, v28 dst_sel:DWORD dst_unused:UNUSED_PAD src0_sel:WORD_1
	v_cvt_f32_f16_e32 v175, v29
	v_cvt_f32_f16_sdwa v179, v29 dst_sel:DWORD dst_unused:UNUSED_PAD src0_sel:WORD_1
	v_cvt_f32_f16_e32 v178, v28
	v_cvt_f32_f16_e32 v165, v13
	v_cvt_f32_f16_sdwa v167, v13 dst_sel:DWORD dst_unused:UNUSED_PAD src0_sel:WORD_1
	v_cvt_f32_f16_e32 v166, v12
	v_cvt_f32_f16_e32 v154, v6
	v_cvt_f32_f16_e32 v155, v7
	v_cvt_f32_f16_sdwa v157, v7 dst_sel:DWORD dst_unused:UNUSED_PAD src0_sel:WORD_1
	v_cvt_f32_f16_sdwa v156, v6 dst_sel:DWORD dst_unused:UNUSED_PAD src0_sel:WORD_1
	v_cvt_f32_f16_sdwa v140, v4 dst_sel:DWORD dst_unused:UNUSED_PAD src0_sel:WORD_1
	v_cvt_f32_f16_e32 v141, v5
	v_cvt_f32_f16_sdwa v143, v5 dst_sel:DWORD dst_unused:UNUSED_PAD src0_sel:WORD_1
	v_cvt_f32_f16_e32 v142, v4
	v_cvt_f32_f16_e32 v124, v16
	v_cvt_f32_f16_e32 v125, v17
	v_cvt_f32_f16_sdwa v127, v17 dst_sel:DWORD dst_unused:UNUSED_PAD src0_sel:WORD_1
	v_cvt_f32_f16_sdwa v126, v16 dst_sel:DWORD dst_unused:UNUSED_PAD src0_sel:WORD_1
	v_cvt_f32_f16_sdwa v114, v122 dst_sel:DWORD dst_unused:UNUSED_PAD src0_sel:WORD_1
	v_cvt_f32_f16_e32 v115, v123
	v_cvt_f32_f16_sdwa v117, v123 dst_sel:DWORD dst_unused:UNUSED_PAD src0_sel:WORD_1
	v_cvt_f32_f16_e32 v116, v122
	v_xor_b32_e32 v79, 0x80000000, v52
	v_mov_b32_e32 v78, v53
	v_pk_add_f32 v[52:53], v[48:49], v[72:73] op_sel:[0,1] op_sel_hi:[1,0] neg_hi:[0,1]
	v_pk_add_f32 v[48:49], v[48:49], v[72:73] op_sel:[0,1] op_sel_hi:[1,0] neg_lo:[0,1]
	v_pk_add_f32 v[72:73], v[50:51], v[54:55]
	v_pk_add_f32 v[50:51], v[50:51], v[54:55] neg_lo:[0,1] neg_hi:[0,1]
	v_pk_fma_f32 v[160:161], v[82:83], 0, v[82:83] op_sel:[0,0,1] op_sel_hi:[1,0,0] neg_lo:[1,0,0] neg_hi:[1,0,0]
	v_xor_b32_e32 v55, 0x80000000, v50
	v_mov_b32_e32 v54, v51
	v_pk_fma_f32 v[198:199], v[82:83], 0, v[82:83] op_sel:[0,0,1] op_sel_hi:[1,0,0]
	v_pk_add_f32 v[42:43], v[112:113], v[22:23]
	v_pk_add_f32 v[22:23], v[112:113], v[22:23] neg_lo:[0,1] neg_hi:[0,1]
	v_pk_add_f32 v[98:99], v[74:75], v[90:91]
	v_pk_add_f32 v[100:101], v[74:75], v[90:91] neg_lo:[0,1] neg_hi:[0,1]
	v_pk_add_f32 v[102:103], v[68:69], v[76:77]
	v_pk_add_f32 v[106:107], v[68:69], v[76:77] neg_lo:[0,1] neg_hi:[0,1]
	v_pk_add_f32 v[104:105], v[62:63], v[80:81]
	v_pk_add_f32 v[108:109], v[62:63], v[80:81] neg_lo:[0,1] neg_hi:[0,1]
	v_pk_add_f32 v[110:111], v[56:57], v[64:65]
	v_pk_add_f32 v[112:113], v[56:57], v[64:65] neg_lo:[0,1] neg_hi:[0,1]
	v_pk_add_f32 v[152:153], v[70:71], v[78:79]
	v_pk_add_f32 v[162:163], v[70:71], v[78:79] neg_lo:[0,1] neg_hi:[0,1]
	v_pk_add_f32 v[176:177], v[52:53], v[72:73]
	v_pk_add_f32 v[182:183], v[52:53], v[72:73] neg_lo:[0,1] neg_hi:[0,1]
	v_pk_add_f32 v[188:189], v[48:49], v[54:55]
	v_pk_add_f32 v[196:197], v[48:49], v[54:55] neg_lo:[0,1] neg_hi:[0,1]
	v_pk_mul_f32 v[186:187], v[82:83], 0 op_sel_hi:[1,0]
	v_mov_b32_e32 v190, v160
	v_mov_b32_e32 v191, v199
	v_mul_f32_e32 v18, 0x3f3504f3, v83
	v_mul_f32_e32 v158, 0xbec3ef15, v83
	v_mul_f32_e32 v132, 0xbf6c835e, v83
	s_and_saveexec_b64 s[0:1], vcc
	s_xor_b64 s[0:1], exec, s[0:1]
	s_cbranch_execz .LBB0_536
	v_pk_add_f32 v[4:5], v[148:149], v[196:197]
	v_pk_add_f32 v[6:7], v[148:149], v[196:197] neg_lo:[0,1] neg_hi:[0,1]
	v_mul_f32_e32 v4, 0.5, v4
	v_mul_f32_e32 v12, 0.5, v7
	v_mov_b32_e32 v7, v5
	v_pk_mul_f32 v[6:7], v[6:7], s[44:45]
	v_pk_mov_b32 v[16:17], v[198:199], v[160:161] op_sel:[1,0]
	v_pk_mul_f32 v[24:25], v[190:191], v[6:7] op_sel:[0,1] op_sel_hi:[1,0]
	v_pk_mul_f32 v[6:7], v[190:191], v[6:7]
	v_pk_add_f32 v[24:25], v[24:25], v[24:25] op_sel:[0,1] op_sel_hi:[0,1]
	v_pk_add_f32 v[28:29], v[4:5], v[24:25] op_sel_hi:[0,1] neg_hi:[0,1]
	v_pk_add_f32 v[4:5], v[6:7], v[6:7] op_sel:[0,1] op_sel_hi:[0,1] neg_lo:[0,1] neg_hi:[0,1]
	v_pk_add_f32 v[6:7], v[12:13], v[4:5] op_sel_hi:[0,1] neg_hi:[0,1]
	v_pk_mul_f32 v[4:5], v[6:7], v[194:195]
	v_pk_mul_f32 v[6:7], v[6:7], v[192:193]
	v_pk_fma_f32 v[4:5], v[28:29], v[192:193], v[4:5]
	v_pk_fma_f32 v[6:7], v[28:29], v[194:195], v[6:7] neg_lo:[0,0,1] neg_hi:[0,0,1]
	s_mov_b32 s66, s19
	v_pk_add_f32 v[12:13], v[6:7], v[4:5] op_sel:[0,1] op_sel_hi:[1,0] neg_lo:[0,1]
	v_pk_add_f32 v[28:29], v[6:7], v[4:5] op_sel:[0,1] op_sel_hi:[1,0]
	v_pk_add_f32 v[4:5], v[4:5], v[6:7] op_sel:[1,0] op_sel_hi:[0,1] neg_lo:[0,1] neg_hi:[0,1]
	s_nop 0
	v_pk_mul_f32 v[12:13], v[12:13], 0.5 op_sel_hi:[1,0]
	v_mov_b32_e32 v29, v5
	v_mul_f32_e32 v24, v190, v12
	v_pk_fma_f32 v[30:31], v[190:191], v[12:13], v[24:25] op_sel_hi:[1,1,0] neg_lo:[1,0,0] neg_hi:[1,0,0]
	v_mul_f32_e32 v24, v160, v13
	v_pk_fma_f32 v[12:13], v[16:17], v[12:13], v[24:25] op_sel_hi:[1,1,0]
	v_mov_b32_e32 v16, v83
	v_mov_b32_e32 v30, v12
	v_pk_fma_f32 v[4:5], v[28:29], 0.5, v[12:13] op_sel_hi:[1,0,1] neg_lo:[0,0,1] neg_hi:[0,0,1]
	v_pk_fma_f32 v[122:123], v[28:29], 0.5, v[30:31] op_sel_hi:[1,0,1]
	v_pk_fma_f32 v[6:7], v[28:29], 0.5, v[30:31] op_sel_hi:[1,0,1] neg_lo:[1,0,0] neg_hi:[1,0,0]
	v_mov_b32_e32 v5, v123
	v_pk_mul_f32 v[24:25], v[4:5], s[46:47] op_sel_hi:[1,0]
	v_pk_add_f32 v[4:5], v[138:139], v[188:189]
	v_pk_add_f32 v[12:13], v[138:139], v[188:189] neg_lo:[0,1] neg_hi:[0,1]
	v_mov_b32_e32 v17, v82
	v_mul_f32_e32 v6, 0.5, v13
	v_pk_add_f32 v[28:29], v[186:187], v[16:17] neg_lo:[0,1] neg_hi:[0,1]
	v_pk_add_f32 v[30:31], v[186:187], v[16:17]
	v_mov_b32_e32 v13, v5
	v_pk_mov_b32 v[32:33], v[28:29], v[30:31] op_sel:[1,0]
	v_pk_mul_f32 v[12:13], v[12:13], s[44:45]
	v_mul_f32_e32 v4, 0.5, v4
	v_pk_mul_f32 v[48:49], v[32:33], v[12:13] op_sel:[0,1] op_sel_hi:[1,0]
	v_pk_mul_f32 v[12:13], v[32:33], v[12:13]
	v_pk_add_f32 v[48:49], v[48:49], v[48:49] op_sel:[0,1] op_sel_hi:[0,1]
	v_pk_add_f32 v[50:51], v[4:5], v[48:49] op_sel_hi:[0,1] neg_hi:[0,1]
	v_pk_add_f32 v[4:5], v[12:13], v[12:13] op_sel:[0,1] op_sel_hi:[0,1] neg_lo:[0,1] neg_hi:[0,1]
	v_pk_add_f32 v[12:13], v[6:7], v[4:5] op_sel_hi:[0,1] neg_hi:[0,1]
	v_pk_mul_f32 v[4:5], v[12:13], v[184:185]
	v_pk_mul_f32 v[12:13], v[12:13], v[170:171]
	v_pk_fma_f32 v[4:5], v[50:51], v[170:171], v[4:5]
	v_pk_fma_f32 v[12:13], v[50:51], v[184:185], v[12:13] neg_lo:[0,0,1] neg_hi:[0,0,1]
	v_mov_b32_e32 v31, v29
	v_pk_add_f32 v[48:49], v[12:13], v[4:5] op_sel:[0,1] op_sel_hi:[1,0] neg_lo:[0,1]
	v_pk_add_f32 v[50:51], v[12:13], v[4:5] op_sel:[0,1] op_sel_hi:[1,0]
	v_pk_add_f32 v[4:5], v[4:5], v[12:13] op_sel:[1,0] op_sel_hi:[0,1] neg_lo:[0,1] neg_hi:[0,1]
	v_pk_mul_f32 v[48:49], v[48:49], 0.5 op_sel_hi:[1,0]
	v_mov_b32_e32 v51, v5
	v_mul_f32_e32 v6, v29, v48
	v_pk_fma_f32 v[32:33], v[32:33], v[48:49], v[6:7] op_sel_hi:[1,1,0] neg_lo:[1,0,0] neg_hi:[1,0,0]
	v_mul_f32_e32 v6, v29, v49
	v_pk_fma_f32 v[28:29], v[30:31], v[48:49], v[6:7] op_sel_hi:[1,1,0]
	v_pk_mul_f32 v[12:13], v[16:17], s[36:37]
	v_mov_b32_e32 v32, v28
	v_pk_fma_f32 v[4:5], v[50:51], 0.5, v[28:29] op_sel_hi:[1,0,1] neg_lo:[0,0,1] neg_hi:[0,0,1]
	v_pk_fma_f32 v[138:139], v[50:51], 0.5, v[32:33] op_sel_hi:[1,0,1]
	v_pk_add_f32 v[16:17], v[92:93], v[182:183]
	v_mov_b32_e32 v5, v139
	v_pk_add_f32 v[28:29], v[92:93], v[182:183] neg_lo:[0,1] neg_hi:[0,1]
	v_pk_mul_f32 v[30:31], v[4:5], s[46:47] op_sel_hi:[1,0]
	v_pk_fma_f32 v[4:5], v[50:51], 0.5, v[32:33] op_sel_hi:[1,0,1] neg_lo:[1,0,0] neg_hi:[1,0,0]
	v_mul_f32_e32 v6, 0.5, v29
	v_pk_add_f32 v[32:33], v[18:19], v[12:13] op_sel:[0,1] op_sel_hi:[0,1] neg_lo:[0,1] neg_hi:[0,1]
	v_pk_add_f32 v[48:49], v[18:19], v[12:13] op_sel:[0,1] op_sel_hi:[0,1]
	v_mov_b32_e32 v29, v17
	v_mul_f32_e32 v4, 0.5, v16
	v_mov_b32_e32 v50, v32
	v_mov_b32_e32 v51, v49
	v_pk_mul_f32 v[16:17], v[28:29], s[44:45]
	v_pk_mov_b32 v[48:49], v[48:49], v[32:33] op_sel:[1,0]
	v_pk_mul_f32 v[28:29], v[50:51], v[16:17] op_sel:[0,1] op_sel_hi:[1,0]
	v_pk_mul_f32 v[16:17], v[50:51], v[16:17]
	v_pk_add_f32 v[28:29], v[28:29], v[28:29] op_sel:[0,1] op_sel_hi:[0,1]
	v_pk_add_f32 v[52:53], v[4:5], v[28:29] op_sel_hi:[0,1] neg_hi:[0,1]
	v_pk_add_f32 v[16:17], v[16:17], v[16:17] op_sel:[0,1] op_sel_hi:[0,1] neg_lo:[0,1] neg_hi:[0,1]
	v_pk_add_f32 v[28:29], v[6:7], v[16:17] op_sel_hi:[0,1] neg_hi:[0,1]
	v_pk_mul_f32 v[16:17], v[28:29], v[180:181]
	v_pk_mul_f32 v[28:29], v[28:29], v[172:173]
	v_pk_fma_f32 v[16:17], v[52:53], v[172:173], v[16:17]
	v_pk_fma_f32 v[28:29], v[52:53], v[180:181], v[28:29] neg_lo:[0,0,1] neg_hi:[0,0,1]
	v_sub_f32_e32 v6, v89, v177
	v_pk_add_f32 v[52:53], v[28:29], v[16:17] op_sel:[0,1] op_sel_hi:[1,0] neg_lo:[0,1]
	v_pk_add_f32 v[54:55], v[28:29], v[16:17] op_sel:[0,1] op_sel_hi:[1,0]
	v_pk_add_f32 v[16:17], v[16:17], v[28:29] op_sel:[1,0] op_sel_hi:[0,1] neg_lo:[0,1] neg_hi:[0,1]
	v_pk_mul_f32 v[52:53], v[52:53], 0.5 op_sel_hi:[1,0]
	v_mov_b32_e32 v55, v17
	v_mul_f32_e32 v4, v32, v52
	v_pk_fma_f32 v[56:57], v[50:51], v[52:53], v[4:5] op_sel_hi:[1,1,0] neg_lo:[1,0,0] neg_hi:[1,0,0]
	v_mul_f32_e32 v4, v32, v53
	v_pk_fma_f32 v[48:49], v[48:49], v[52:53], v[4:5] op_sel_hi:[1,1,0]
	v_pk_add_f32 v[28:29], v[88:89], v[176:177]
	v_mov_b32_e32 v56, v48
	v_pk_fma_f32 v[16:17], v[54:55], 0.5, v[48:49] op_sel_hi:[1,0,1] neg_lo:[0,0,1] neg_hi:[0,0,1]
	v_mov_b32_e32 v48, v12
	v_mov_b32_e32 v49, v88
	v_pk_mov_b32 v[12:13], v[12:13], v[176:177] op_sel:[1,0]
	v_mul_f32_e32 v18, 0.5, v29
	v_pk_add_f32 v[12:13], v[48:49], v[12:13] neg_lo:[0,1] neg_hi:[0,1]
	v_mul_f32_e32 v4, 0.5, v28
	v_pk_mul_f32 v[48:49], v[12:13], v[18:19]
	v_mov_b32_e32 v13, v32
	v_pk_fma_f32 v[50:51], v[50:51], v[48:49], v[48:49] op_sel:[0,1,0] op_sel_hi:[1,0,1]
	v_mov_b32_e32 v48, v49
	v_mov_b32_e32 v49, v18
	v_pk_mul_f32 v[48:49], v[12:13], v[48:49]
	v_pk_add_f32 v[52:53], v[4:5], v[50:51]
	v_mul_f32_e32 v6, 0.5, v6
	v_fma_f32 v53, v28, 0.5, -v50
	v_pk_add_f32 v[28:29], v[48:49], v[48:49] op_sel:[0,1] op_sel_hi:[0,1] neg_lo:[0,1] neg_hi:[0,1]
	v_pk_add_f32 v[48:49], v[6:7], v[28:29] op_sel_hi:[0,1] neg_hi:[0,1]
	v_pk_mul_f32 v[28:29], v[48:49], v[178:179]
	v_pk_mul_f32 v[48:49], v[48:49], v[174:175]
	v_pk_fma_f32 v[28:29], v[52:53], v[174:175], v[28:29]
	v_pk_fma_f32 v[48:49], v[52:53], v[178:179], v[48:49] neg_lo:[0,0,1] neg_hi:[0,0,1]
	v_pk_fma_f32 v[92:93], v[54:55], 0.5, v[56:57] op_sel_hi:[1,0,1]
	v_pk_add_f32 v[50:51], v[48:49], v[28:29] op_sel:[0,1] op_sel_hi:[1,0] neg_lo:[0,1]
	v_pk_add_f32 v[52:53], v[48:49], v[28:29] op_sel:[0,1] op_sel_hi:[1,0]
	v_mov_b32_e32 v17, v93
	v_pk_mul_f32 v[50:51], v[50:51], 0.5 op_sel_hi:[1,0]
	v_pk_mul_f32 v[64:65], v[16:17], s[46:47] op_sel_hi:[1,0]
	v_mul_f32_e32 v4, v12, v50
	v_pk_fma_f32 v[16:17], v[54:55], 0.5, v[56:57] op_sel_hi:[1,0,1] neg_lo:[1,0,0] neg_hi:[1,0,0]
	v_pk_fma_f32 v[54:55], v[12:13], v[50:51], v[4:5] op_sel_hi:[1,1,0] neg_lo:[1,0,0] neg_hi:[1,0,0]
	v_mov_b32_e32 v33, v12
	v_mul_f32_e32 v4, v12, v51
	v_pk_fma_f32 v[12:13], v[32:33], v[50:51], v[4:5] op_sel_hi:[1,1,0]
	v_pk_add_f32 v[28:29], v[28:29], v[48:49] op_sel:[1,0] op_sel_hi:[0,1] neg_lo:[0,1] neg_hi:[0,1]
	v_mov_b32_e32 v53, v29
	v_mov_b32_e32 v54, v12
	v_pk_fma_f32 v[12:13], v[52:53], 0.5, v[12:13] op_sel_hi:[1,0,1] neg_lo:[0,0,1] neg_hi:[0,0,1]
	v_pk_fma_f32 v[88:89], v[52:53], 0.5, v[54:55] op_sel_hi:[1,0,1]
	s_mov_b32 s67, s16
	v_mov_b32_e32 v13, v89
	v_pk_mul_f32 v[68:69], v[12:13], s[46:47] op_sel_hi:[1,0]
	v_pk_fma_f32 v[12:13], v[52:53], 0.5, v[54:55] op_sel_hi:[1,0,1] neg_lo:[1,0,0] neg_hi:[1,0,0]
	v_mov_b32_e32 v4, v83
	s_mov_b32 s17, s19
	v_pk_mul_f32 v[48:49], v[82:83], s[66:67] op_sel_hi:[0,1]
	v_pk_add_f32 v[28:29], v[96:97], v[162:163]
	v_pk_add_f32 v[32:33], v[96:97], v[162:163] neg_lo:[0,1] neg_hi:[0,1]
	v_pk_fma_f32 v[52:53], v[4:5], s[16:17], v[48:49] op_sel_hi:[0,1,1] neg_lo:[0,0,1] neg_hi:[0,0,1]
	v_mul_f32_e32 v12, 0.5, v33
	v_pk_fma_f32 v[50:51], v[4:5], s[16:17], v[48:49] op_sel_hi:[0,1,1]
	v_mov_b32_e32 v33, v29
	v_mul_f32_e32 v6, 0.5, v28
	v_mov_b32_e32 v54, v52
	v_mov_b32_e32 v55, v51
	v_pk_mul_f32 v[28:29], v[32:33], s[44:45]
	v_pk_mov_b32 v[56:57], v[50:51], v[52:53] op_sel:[1,0]
	v_pk_mul_f32 v[32:33], v[54:55], v[28:29] op_sel:[0,1] op_sel_hi:[1,0]
	v_pk_mul_f32 v[28:29], v[54:55], v[28:29]
	v_pk_add_f32 v[32:33], v[32:33], v[32:33] op_sel:[0,1] op_sel_hi:[0,1]
	v_pk_add_f32 v[58:59], v[6:7], v[32:33] op_sel_hi:[0,1] neg_hi:[0,1]
	v_pk_add_f32 v[28:29], v[28:29], v[28:29] op_sel:[0,1] op_sel_hi:[0,1] neg_lo:[0,1] neg_hi:[0,1]
	v_pk_add_f32 v[32:33], v[12:13], v[28:29] op_sel_hi:[0,1] neg_hi:[0,1]
	v_pk_mul_f32 v[28:29], v[32:33], v[166:167]
	v_pk_mul_f32 v[32:33], v[32:33], v[164:165]
	v_pk_fma_f32 v[28:29], v[58:59], v[164:165], v[28:29]
	v_pk_fma_f32 v[32:33], v[58:59], v[166:167], v[32:33] neg_lo:[0,0,1] neg_hi:[0,0,1]
	v_mov_b32_e32 v159, v66
	v_pk_add_f32 v[58:59], v[32:33], v[28:29] op_sel:[0,1] op_sel_hi:[1,0] neg_lo:[0,1]
	v_pk_add_f32 v[70:71], v[32:33], v[28:29] op_sel:[0,1] op_sel_hi:[1,0]
	v_pk_add_f32 v[28:29], v[28:29], v[32:33] op_sel:[1,0] op_sel_hi:[0,1] neg_lo:[0,1] neg_hi:[0,1]
	v_pk_mul_f32 v[58:59], v[58:59], 0.5 op_sel_hi:[1,0]
	v_mov_b32_e32 v71, v29
	v_mul_f32_e32 v6, v52, v58
	v_pk_fma_f32 v[72:73], v[54:55], v[58:59], v[6:7] op_sel_hi:[1,1,0] neg_lo:[1,0,0] neg_hi:[1,0,0]
	v_mul_f32_e32 v6, v52, v59
	v_pk_fma_f32 v[56:57], v[56:57], v[58:59], v[6:7] op_sel_hi:[1,1,0]
	v_sub_f32_e32 v12, v67, v153
	v_mov_b32_e32 v72, v56
	v_pk_fma_f32 v[28:29], v[70:71], 0.5, v[56:57] op_sel_hi:[1,0,1] neg_lo:[0,0,1] neg_hi:[0,0,1]
	v_pk_fma_f32 v[96:97], v[70:71], 0.5, v[72:73] op_sel_hi:[1,0,1]
	v_pk_mov_b32 v[56:57], v[48:49], v[152:153] op_sel:[1,0]
	v_mov_b32_e32 v29, v97
	v_pk_mul_f32 v[62:63], v[28:29], s[46:47] op_sel_hi:[1,0]
	v_pk_add_f32 v[28:29], v[66:67], v[152:153]
	v_pk_add_f32 v[56:57], v[158:159], v[56:57] neg_lo:[0,1] neg_hi:[0,1]
	v_mul_f32_e32 v18, 0.5, v29
	v_pk_mul_f32 v[58:59], v[56:57], v[18:19]
	v_mul_f32_e32 v6, 0.5, v28
	v_pk_fma_f32 v[54:55], v[54:55], v[58:59], v[58:59] op_sel:[0,1,0] op_sel_hi:[1,0,1]
	v_mov_b32_e32 v66, v56
	v_mov_b32_e32 v67, v52
	v_mov_b32_e32 v58, v59
	v_mov_b32_e32 v59, v18
	v_pk_mul_f32 v[58:59], v[66:67], v[58:59]
	v_pk_add_f32 v[66:67], v[6:7], v[54:55]
	v_mul_f32_e32 v12, 0.5, v12
	v_fma_f32 v67, v28, 0.5, -v54
	v_pk_add_f32 v[28:29], v[58:59], v[58:59] op_sel:[0,1] op_sel_hi:[0,1] neg_lo:[0,1] neg_hi:[0,1]
	v_pk_add_f32 v[54:55], v[12:13], v[28:29] op_sel_hi:[0,1] neg_hi:[0,1]
	v_pk_mul_f32 v[28:29], v[54:55], v[156:157]
	v_pk_mul_f32 v[54:55], v[54:55], v[154:155]
	v_pk_fma_f32 v[32:33], v[70:71], 0.5, v[72:73] op_sel_hi:[1,0,1] neg_lo:[1,0,0] neg_hi:[1,0,0]
	v_pk_fma_f32 v[58:59], v[66:67], v[154:155], v[28:29] neg_lo:[0,0,1] neg_hi:[0,0,1]
	v_pk_fma_f32 v[28:29], v[66:67], v[154:155], v[28:29]
	v_pk_fma_f32 v[70:71], v[66:67], v[156:157], v[54:55]
	v_pk_fma_f32 v[54:55], v[66:67], v[156:157], v[54:55] neg_lo:[0,0,1] neg_hi:[0,0,1]
	v_pk_add_f32 v[72:73], v[58:59], v[28:29] op_sel:[0,1] op_sel_hi:[1,0]
	v_pk_add_f32 v[66:67], v[70:71], v[54:55] op_sel_hi:[0,1] neg_lo:[0,1] neg_hi:[0,1]
	v_pk_add_f32 v[28:29], v[58:59], v[28:29] op_sel_hi:[0,1] neg_lo:[0,1] neg_hi:[0,1]
	v_pk_add_f32 v[54:55], v[70:71], v[54:55] op_sel:[0,1] op_sel_hi:[1,0]
	v_mov_b32_e32 v73, v67
	v_mov_b32_e32 v55, v29
	v_pk_mul_f32 v[28:29], v[54:55], 0.5 op_sel_hi:[1,0]
	v_mov_b32_e32 v133, v84
	v_pk_mul_f32 v[54:55], v[52:53], v[28:29] op_sel:[0,1] op_sel_hi:[0,0]
	v_pk_fma_f32 v[58:59], v[56:57], v[28:29], v[54:55] op_sel_hi:[0,1,1]
	v_pk_fma_f32 v[28:29], v[56:57], v[28:29], v[54:55] op_sel_hi:[0,1,1] neg_hi:[0,0,1]
	v_pk_fma_f32 v[54:55], v[72:73], 0.5, v[58:59] op_sel_hi:[1,0,1] neg_lo:[0,0,1] neg_hi:[0,0,1]
	v_pk_fma_f32 v[66:67], v[72:73], 0.5, v[28:29] op_sel_hi:[1,0,1]
	v_pk_add_f32 v[56:57], v[60:61], v[134:135] neg_lo:[0,1] neg_hi:[0,1]
	v_mov_b32_e32 v55, v67
	v_pk_mul_f32 v[90:91], v[54:55], s[46:47] op_sel_hi:[1,0]
	v_pk_add_f32 v[54:55], v[134:135], v[60:61]
	v_mul_f32_e32 v12, 0.5, v57
	v_mov_b32_e32 v57, v55
	v_mul_f32_e32 v6, 0.5, v54
	v_pk_mov_b32 v[58:59], v[52:53], v[50:51] op_sel:[1,0]
	v_pk_mul_f32 v[54:55], v[56:57], s[44:45]
	v_pk_fma_f32 v[28:29], v[72:73], 0.5, v[28:29] op_sel_hi:[1,0,1] neg_lo:[1,0,0] neg_hi:[1,0,0]
	v_pk_mul_f32 v[56:57], v[58:59], v[54:55] op_sel:[0,1] op_sel_hi:[1,0]
	v_pk_mul_f32 v[54:55], v[58:59], v[54:55]
	v_pk_add_f32 v[56:57], v[56:57], v[56:57] op_sel:[0,1] op_sel_hi:[0,1]
	v_pk_add_f32 v[60:61], v[6:7], v[56:57] op_sel_hi:[0,1] neg_hi:[0,1]
	v_pk_add_f32 v[54:55], v[54:55], v[54:55] op_sel:[0,1] op_sel_hi:[0,1] neg_lo:[0,1] neg_hi:[0,1]
	v_pk_add_f32 v[56:57], v[12:13], v[54:55] op_sel_hi:[0,1] neg_hi:[0,1]
	v_pk_mul_f32 v[54:55], v[56:57], v[142:143]
	v_pk_mul_f32 v[56:57], v[56:57], v[140:141]
	v_pk_fma_f32 v[54:55], v[60:61], v[140:141], v[54:55]
	v_pk_fma_f32 v[56:57], v[60:61], v[142:143], v[56:57] neg_lo:[0,0,1] neg_hi:[0,0,1]
	v_mov_b32_e32 v51, v53
	v_pk_add_f32 v[60:61], v[56:57], v[54:55] op_sel:[0,1] op_sel_hi:[1,0] neg_lo:[0,1]
	v_pk_add_f32 v[70:71], v[56:57], v[54:55] op_sel:[0,1] op_sel_hi:[1,0]
	v_pk_add_f32 v[54:55], v[54:55], v[56:57] op_sel:[1,0] op_sel_hi:[0,1] neg_lo:[0,1] neg_hi:[0,1]
	v_pk_mul_f32 v[60:61], v[60:61], 0.5 op_sel_hi:[1,0]
	v_mov_b32_e32 v71, v55
	v_mul_f32_e32 v6, v53, v60
	v_pk_fma_f32 v[72:73], v[58:59], v[60:61], v[6:7] op_sel_hi:[1,1,0] neg_lo:[1,0,0] neg_hi:[1,0,0]
	v_mul_f32_e32 v6, v53, v61
	v_pk_fma_f32 v[50:51], v[50:51], v[60:61], v[6:7] op_sel_hi:[1,1,0]
	v_pk_add_f32 v[54:55], v[118:119], v[84:85]
	v_mov_b32_e32 v72, v50
	v_mov_b32_e32 v49, v118
	v_pk_fma_f32 v[50:51], v[70:71], 0.5, v[50:51] op_sel_hi:[1,0,1] neg_lo:[0,0,1] neg_hi:[0,0,1]
	v_pk_fma_f32 v[60:61], v[70:71], 0.5, v[72:73] op_sel_hi:[1,0,1]
	v_mul_f32_e32 v18, 0.5, v55
	v_pk_add_f32 v[48:49], v[132:133], v[48:49] neg_lo:[0,1] neg_hi:[0,1]
	v_mov_b32_e32 v51, v61
	v_pk_mul_f32 v[56:57], v[48:49], v[18:19]
	v_pk_mul_f32 v[94:95], v[50:51], s[46:47] op_sel_hi:[1,0]
	v_pk_fma_f32 v[50:51], v[70:71], 0.5, v[72:73] op_sel_hi:[1,0,1] neg_lo:[1,0,0] neg_hi:[1,0,0]
	v_mul_f32_e32 v6, 0.5, v54
	v_pk_fma_f32 v[58:59], v[58:59], v[56:57], v[56:57] op_sel:[0,1,0] op_sel_hi:[1,0,1]
	v_mov_b32_e32 v70, v48
	v_mov_b32_e32 v71, v53
	v_mov_b32_e32 v56, v57
	v_mov_b32_e32 v57, v18
	v_sub_f32_e32 v12, v85, v119
	v_pk_mul_f32 v[56:57], v[70:71], v[56:57]
	v_pk_add_f32 v[70:71], v[6:7], v[58:59]
	v_mul_f32_e32 v12, 0.5, v12
	v_fma_f32 v71, v54, 0.5, -v58
	v_pk_add_f32 v[54:55], v[56:57], v[56:57] op_sel:[0,1] op_sel_hi:[0,1] neg_lo:[0,1] neg_hi:[0,1]
	v_pk_add_f32 v[56:57], v[12:13], v[54:55] op_sel_hi:[0,1] neg_hi:[0,1]
	v_pk_mul_f32 v[54:55], v[56:57], v[126:127]
	v_pk_mul_f32 v[56:57], v[56:57], v[124:125]
	v_pk_fma_f32 v[58:59], v[70:71], v[124:125], v[54:55] neg_lo:[0,0,1] neg_hi:[0,0,1]
	v_pk_fma_f32 v[54:55], v[70:71], v[124:125], v[54:55]
	v_pk_fma_f32 v[72:73], v[70:71], v[126:127], v[56:57]
	v_pk_fma_f32 v[56:57], v[70:71], v[126:127], v[56:57] neg_lo:[0,0,1] neg_hi:[0,0,1]
	v_pk_add_f32 v[70:71], v[58:59], v[54:55] op_sel:[0,1] op_sel_hi:[1,0]
	v_pk_add_f32 v[74:75], v[72:73], v[56:57] op_sel_hi:[0,1] neg_lo:[0,1] neg_hi:[0,1]
	v_pk_add_f32 v[54:55], v[58:59], v[54:55] op_sel_hi:[0,1] neg_lo:[0,1] neg_hi:[0,1]
	v_pk_add_f32 v[56:57], v[72:73], v[56:57] op_sel:[0,1] op_sel_hi:[1,0]
	v_mov_b32_e32 v71, v75
	v_mov_b32_e32 v57, v55
	v_pk_mul_f32 v[54:55], v[56:57], 0.5 op_sel_hi:[1,0]
	s_mov_b32 s66, s11
	v_pk_mul_f32 v[52:53], v[52:53], v[54:55] op_sel:[1,1] op_sel_hi:[1,0]
	s_mov_b32 s67, s8
	v_pk_fma_f32 v[56:57], v[48:49], v[54:55], v[52:53] op_sel_hi:[0,1,1]
	v_pk_fma_f32 v[48:49], v[48:49], v[54:55], v[52:53] op_sel_hi:[0,1,1] neg_hi:[0,0,1]
	s_nop 0
	v_pk_fma_f32 v[52:53], v[70:71], 0.5, v[56:57] op_sel_hi:[1,0,1] neg_lo:[0,0,1] neg_hi:[0,0,1]
	v_pk_fma_f32 v[84:85], v[70:71], 0.5, v[48:49] op_sel_hi:[1,0,1]
	s_mov_b32 s9, s11
	v_mov_b32_e32 v53, v85
	v_pk_mul_f32 v[80:81], v[52:53], s[46:47] op_sel_hi:[1,0]
	v_pk_mul_f32 v[118:119], v[82:83], s[66:67] op_sel_hi:[0,1]
	v_pk_add_f32 v[52:53], v[86:87], v[112:113]
	v_pk_add_f32 v[54:55], v[86:87], v[112:113] neg_lo:[0,1] neg_hi:[0,1]
	v_pk_fma_f32 v[58:59], v[4:5], s[8:9], v[118:119] op_sel_hi:[0,1,1] neg_lo:[0,0,1] neg_hi:[0,0,1]
	v_mul_f32_e32 v12, 0.5, v55
	v_pk_fma_f32 v[72:73], v[4:5], s[8:9], v[118:119] op_sel_hi:[0,1,1]
	v_mov_b32_e32 v55, v53
	v_mul_f32_e32 v6, 0.5, v52
	v_mov_b32_e32 v56, v58
	v_mov_b32_e32 v57, v73
	v_pk_mul_f32 v[52:53], v[54:55], s[44:45]
	v_pk_fma_f32 v[48:49], v[70:71], 0.5, v[48:49] op_sel_hi:[1,0,1] neg_lo:[1,0,0] neg_hi:[1,0,0]
	v_pk_mul_f32 v[54:55], v[56:57], v[52:53] op_sel:[0,1] op_sel_hi:[1,0]
	v_pk_mul_f32 v[52:53], v[56:57], v[52:53]
	v_pk_add_f32 v[54:55], v[54:55], v[54:55] op_sel:[0,1] op_sel_hi:[0,1]
	v_pk_add_f32 v[74:75], v[6:7], v[54:55] op_sel_hi:[0,1] neg_hi:[0,1]
	v_pk_add_f32 v[52:53], v[52:53], v[52:53] op_sel:[0,1] op_sel_hi:[0,1] neg_lo:[0,1] neg_hi:[0,1]
	v_pk_add_f32 v[54:55], v[12:13], v[52:53] op_sel_hi:[0,1] neg_hi:[0,1]
	v_pk_mul_f32 v[52:53], v[54:55], v[116:117]
	v_pk_mul_f32 v[54:55], v[54:55], v[114:115]
	v_pk_fma_f32 v[52:53], v[74:75], v[114:115], v[52:53]
	v_pk_fma_f32 v[54:55], v[74:75], v[116:117], v[54:55] neg_lo:[0,0,1] neg_hi:[0,0,1]
	v_pk_mov_b32 v[70:71], v[72:73], v[58:59] op_sel:[1,0]
	v_pk_add_f32 v[74:75], v[54:55], v[52:53] op_sel:[0,1] op_sel_hi:[1,0] neg_lo:[0,1]
	v_pk_add_f32 v[76:77], v[54:55], v[52:53] op_sel:[0,1] op_sel_hi:[1,0]
	v_pk_add_f32 v[52:53], v[52:53], v[54:55] op_sel:[1,0] op_sel_hi:[0,1] neg_lo:[0,1] neg_hi:[0,1]
	v_pk_mul_f32 v[74:75], v[74:75], 0.5 op_sel_hi:[1,0]
	v_mov_b32_e32 v77, v53
	v_mul_f32_e32 v6, v58, v74
	v_pk_fma_f32 v[112:113], v[56:57], v[74:75], v[6:7] op_sel_hi:[1,1,0] neg_lo:[1,0,0] neg_hi:[1,0,0]
	v_mul_f32_e32 v6, v58, v75
	v_pk_fma_f32 v[70:71], v[70:71], v[74:75], v[6:7] op_sel_hi:[1,1,0]
	v_pk_add_f32 v[54:55], v[34:35], v[110:111]
	v_mov_b32_e32 v112, v70
	v_pk_fma_f32 v[52:53], v[76:77], 0.5, v[70:71] op_sel_hi:[1,0,1] neg_lo:[0,0,1] neg_hi:[0,0,1]
	v_pk_fma_f32 v[86:87], v[76:77], 0.5, v[112:113] op_sel_hi:[1,0,1]
	v_sub_f32_e32 v12, v35, v111
	v_mov_b32_e32 v53, v87
	v_pk_mul_f32 v[78:79], v[52:53], s[46:47] op_sel_hi:[1,0]
	v_mul_f32_e32 v52, 0xbe47c5c2, v83
	v_mov_b32_e32 v53, v34
	v_pk_mov_b32 v[34:35], v[118:119], v[110:111] op_sel:[1,0]
	v_mul_f32_e32 v18, 0.5, v55
	v_pk_add_f32 v[34:35], v[52:53], v[34:35] neg_lo:[0,1] neg_hi:[0,1]
	v_mov_b32_e32 v71, v58
	v_pk_mul_f32 v[52:53], v[34:35], v[18:19]
	v_mov_b32_e32 v70, v34
	v_pk_fma_f32 v[56:57], v[56:57], v[52:53], v[52:53] op_sel:[0,1,0] op_sel_hi:[1,0,1]
	v_mov_b32_e32 v52, v53
	v_mov_b32_e32 v53, v18
	v_mul_f32_e32 v6, 0.5, v54
	v_pk_mul_f32 v[52:53], v[70:71], v[52:53]
	v_cvt_f32_f16_e32 v70, v46
	v_cvt_f32_f16_e32 v71, v47
	v_cvt_f32_f16_sdwa v47, v47 dst_sel:DWORD dst_unused:UNUSED_PAD src0_sel:WORD_1
	v_cvt_f32_f16_sdwa v46, v46 dst_sel:DWORD dst_unused:UNUSED_PAD src0_sel:WORD_1
	v_pk_fma_f32 v[74:75], v[76:77], 0.5, v[112:113] op_sel_hi:[1,0,1] neg_lo:[1,0,0] neg_hi:[1,0,0]
	v_mul_f32_e32 v12, 0.5, v12
	v_pk_add_f32 v[76:77], v[6:7], v[56:57]
	v_pk_add_f32 v[52:53], v[52:53], v[52:53] op_sel:[0,1] op_sel_hi:[0,1] neg_lo:[0,1] neg_hi:[0,1]
	v_fma_f32 v77, v54, 0.5, -v56
	v_pk_add_f32 v[54:55], v[12:13], v[52:53] op_sel_hi:[0,1] neg_hi:[0,1]
	v_pk_mul_f32 v[52:53], v[54:55], v[46:47]
	v_pk_mul_f32 v[54:55], v[54:55], v[70:71]
	v_pk_fma_f32 v[56:57], v[76:77], v[70:71], v[52:53] neg_lo:[0,0,1] neg_hi:[0,0,1]
	v_pk_fma_f32 v[52:53], v[76:77], v[70:71], v[52:53]
	v_pk_fma_f32 v[70:71], v[76:77], v[46:47], v[54:55]
	v_pk_fma_f32 v[46:47], v[76:77], v[46:47], v[54:55] neg_lo:[0,0,1] neg_hi:[0,0,1]
	v_pk_add_f32 v[54:55], v[56:57], v[52:53] op_sel:[0,1] op_sel_hi:[1,0]
	v_pk_add_f32 v[76:77], v[70:71], v[46:47] op_sel_hi:[0,1] neg_lo:[0,1] neg_hi:[0,1]
	v_pk_add_f32 v[52:53], v[56:57], v[52:53] op_sel_hi:[0,1] neg_lo:[0,1] neg_hi:[0,1]
	v_pk_add_f32 v[46:47], v[70:71], v[46:47] op_sel:[0,1] op_sel_hi:[1,0]
	v_mov_b32_e32 v55, v77
	v_mov_b32_e32 v47, v53
	v_pk_mul_f32 v[46:47], v[46:47], 0.5 op_sel_hi:[1,0]
	s_mov_b32 s25, s27
	v_pk_mul_f32 v[52:53], v[58:59], v[46:47] op_sel:[0,1] op_sel_hi:[0,0]
	v_pk_fma_f32 v[56:57], v[34:35], v[46:47], v[52:53] op_sel_hi:[0,1,1]
	v_pk_fma_f32 v[46:47], v[34:35], v[46:47], v[52:53] op_sel_hi:[0,1,1] neg_hi:[0,0,1]
	s_nop 0
	v_pk_fma_f32 v[52:53], v[54:55], 0.5, v[56:57] op_sel_hi:[1,0,1] neg_lo:[0,0,1] neg_hi:[0,0,1]
	v_pk_fma_f32 v[34:35], v[54:55], 0.5, v[46:47] op_sel_hi:[1,0,1]
	s_mov_b32 s66, s27
	v_mov_b32_e32 v53, v35
	v_pk_mul_f32 v[136:137], v[52:53], s[46:47] op_sel_hi:[1,0]
	v_pk_fma_f32 v[52:53], v[54:55], 0.5, v[46:47] op_sel_hi:[1,0,1] neg_lo:[1,0,0] neg_hi:[1,0,0]
	s_mov_b32 s67, s24
	v_pk_mul_f32 v[46:47], v[82:83], s[24:25] op_sel_hi:[0,1]
	v_pk_add_f32 v[54:55], v[108:109], v[40:41]
	v_pk_add_f32 v[40:41], v[40:41], v[108:109] neg_lo:[0,1] neg_hi:[0,1]
	v_pk_fma_f32 v[108:109], v[4:5], s[66:67], v[46:47] op_sel_hi:[0,1,1] neg_lo:[0,0,1] neg_hi:[0,0,1]
	v_mul_f32_e32 v12, 0.5, v41
	v_pk_fma_f32 v[70:71], v[4:5], s[66:67], v[46:47] op_sel_hi:[0,1,1]
	v_mov_b32_e32 v41, v55
	v_mov_b32_e32 v56, v108
	v_mov_b32_e32 v57, v71
	v_pk_mul_f32 v[40:41], v[40:41], s[44:45]
	v_mul_f32_e32 v6, 0.5, v54
	v_pk_mul_f32 v[54:55], v[56:57], v[40:41] op_sel:[0,1] op_sel_hi:[1,0]
	v_cvt_f32_f16_sdwa v76, v38 dst_sel:DWORD dst_unused:UNUSED_PAD src0_sel:WORD_1
	v_cvt_f32_f16_e32 v77, v39
	v_cvt_f32_f16_sdwa v39, v39 dst_sel:DWORD dst_unused:UNUSED_PAD src0_sel:WORD_1
	v_cvt_f32_f16_e32 v38, v38
	v_pk_mul_f32 v[40:41], v[56:57], v[40:41]
	v_pk_add_f32 v[54:55], v[54:55], v[54:55] op_sel:[0,1] op_sel_hi:[0,1]
	v_pk_add_f32 v[112:113], v[6:7], v[54:55] op_sel_hi:[0,1] neg_hi:[0,1]
	s_nop 0
	v_pk_add_f32 v[40:41], v[40:41], v[40:41] op_sel:[0,1] op_sel_hi:[0,1] neg_lo:[0,1] neg_hi:[0,1]
	v_pk_add_f32 v[54:55], v[12:13], v[40:41] op_sel_hi:[0,1] neg_hi:[0,1]
	v_pk_mul_f32 v[40:41], v[54:55], v[38:39]
	v_pk_mul_f32 v[54:55], v[54:55], v[76:77]
	v_pk_fma_f32 v[40:41], v[112:113], v[76:77], v[40:41]
	v_pk_fma_f32 v[38:39], v[112:113], v[38:39], v[54:55] neg_lo:[0,0,1] neg_hi:[0,0,1]
	v_pk_mov_b32 v[110:111], v[70:71], v[108:109] op_sel:[1,0]
	v_pk_add_f32 v[54:55], v[38:39], v[40:41] op_sel:[0,1] op_sel_hi:[1,0] neg_lo:[0,1]
	v_pk_add_f32 v[76:77], v[38:39], v[40:41] op_sel:[0,1] op_sel_hi:[1,0]
	v_pk_add_f32 v[38:39], v[40:41], v[38:39] op_sel:[1,0] op_sel_hi:[0,1] neg_lo:[0,1] neg_hi:[0,1]
	v_pk_mul_f32 v[54:55], v[54:55], 0.5 op_sel_hi:[1,0]
	v_mov_b32_e32 v77, v39
	v_mul_f32_e32 v4, v108, v54
	v_pk_fma_f32 v[112:113], v[56:57], v[54:55], v[4:5] op_sel_hi:[1,1,0] neg_lo:[1,0,0] neg_hi:[1,0,0]
	v_mul_f32_e32 v4, v108, v55
	v_pk_fma_f32 v[54:55], v[110:111], v[54:55], v[4:5] op_sel_hi:[1,1,0]
	v_sub_f32_e32 v6, v45, v105
	v_mov_b32_e32 v112, v54
	v_pk_fma_f32 v[40:41], v[76:77], 0.5, v[54:55] op_sel_hi:[1,0,1] neg_lo:[0,0,1] neg_hi:[0,0,1]
	v_pk_fma_f32 v[38:39], v[76:77], 0.5, v[112:113] op_sel_hi:[1,0,1]
	v_pk_add_f32 v[54:55], v[104:105], v[44:45]
	v_mov_b32_e32 v41, v39
	v_pk_mul_f32 v[130:131], v[40:41], s[46:47] op_sel_hi:[1,0]
	v_mul_f32_e32 v40, 0xbf54db31, v83
	v_mov_b32_e32 v41, v44
	v_pk_mov_b32 v[44:45], v[46:47], v[104:105] op_sel:[1,0]
	v_mul_f32_e32 v18, 0.5, v55
	v_pk_add_f32 v[40:41], v[40:41], v[44:45] neg_lo:[0,1] neg_hi:[0,1]
	v_mov_b32_e32 v105, v108
	v_pk_mul_f32 v[44:45], v[40:41], v[18:19]
	v_mov_b32_e32 v104, v40
	v_pk_fma_f32 v[56:57], v[56:57], v[44:45], v[44:45] op_sel:[0,1,0] op_sel_hi:[1,0,1]
	v_mov_b32_e32 v44, v45
	v_mov_b32_e32 v45, v18
	v_mul_f32_e32 v4, 0.5, v54
	v_pk_mul_f32 v[44:45], v[104:105], v[44:45]
	v_cvt_f32_f16_e32 v104, v26
	v_cvt_f32_f16_e32 v105, v27
	v_cvt_f32_f16_sdwa v27, v27 dst_sel:DWORD dst_unused:UNUSED_PAD src0_sel:WORD_1
	v_cvt_f32_f16_sdwa v26, v26 dst_sel:DWORD dst_unused:UNUSED_PAD src0_sel:WORD_1
	v_mul_f32_e32 v6, 0.5, v6
	v_pk_add_f32 v[110:111], v[4:5], v[56:57]
	v_pk_add_f32 v[44:45], v[44:45], v[44:45] op_sel:[0,1] op_sel_hi:[0,1] neg_lo:[0,1] neg_hi:[0,1]
	v_fma_f32 v111, v54, 0.5, -v56
	v_pk_add_f32 v[54:55], v[6:7], v[44:45] op_sel_hi:[0,1] neg_hi:[0,1]
	v_pk_mul_f32 v[44:45], v[54:55], v[26:27]
	v_pk_mul_f32 v[54:55], v[54:55], v[104:105]
	v_pk_fma_f32 v[56:57], v[110:111], v[104:105], v[44:45] neg_lo:[0,0,1] neg_hi:[0,0,1]
	v_pk_fma_f32 v[44:45], v[110:111], v[104:105], v[44:45]
	v_pk_fma_f32 v[104:105], v[110:111], v[26:27], v[54:55]
	v_pk_fma_f32 v[26:27], v[110:111], v[26:27], v[54:55] neg_lo:[0,0,1] neg_hi:[0,0,1]
	v_pk_add_f32 v[54:55], v[56:57], v[44:45] op_sel:[0,1] op_sel_hi:[1,0]
	v_pk_add_f32 v[110:111], v[104:105], v[26:27] op_sel_hi:[0,1] neg_lo:[0,1] neg_hi:[0,1]
	v_pk_add_f32 v[44:45], v[56:57], v[44:45] op_sel_hi:[0,1] neg_lo:[0,1] neg_hi:[0,1]
	v_pk_add_f32 v[26:27], v[104:105], v[26:27] op_sel:[0,1] op_sel_hi:[1,0]
	v_mov_b32_e32 v55, v111
	v_mov_b32_e32 v27, v45
	v_pk_mul_f32 v[26:27], v[26:27], 0.5 op_sel_hi:[1,0]
	v_mov_b32_e32 v47, v102
	v_pk_mul_f32 v[44:45], v[108:109], v[26:27] op_sel:[0,1] op_sel_hi:[0,0]
	v_pk_fma_f32 v[56:57], v[40:41], v[26:27], v[44:45] op_sel_hi:[0,1,1]
	v_pk_fma_f32 v[40:41], v[40:41], v[26:27], v[44:45] op_sel_hi:[0,1,1] neg_hi:[0,0,1]
	v_pk_fma_f32 v[44:45], v[54:55], 0.5, v[56:57] op_sel_hi:[1,0,1] neg_lo:[0,0,1] neg_hi:[0,0,1]
	v_pk_fma_f32 v[26:27], v[54:55], 0.5, v[40:41] op_sel_hi:[1,0,1]
	v_pk_fma_f32 v[56:57], v[54:55], 0.5, v[40:41] op_sel_hi:[1,0,1] neg_lo:[1,0,0] neg_hi:[1,0,0]
	v_pk_add_f32 v[40:41], v[106:107], v[42:43]
	v_pk_add_f32 v[42:43], v[42:43], v[106:107] neg_lo:[0,1] neg_hi:[0,1]
	v_mov_b32_e32 v45, v27
	v_mul_f32_e32 v6, 0.5, v43
	v_mov_b32_e32 v43, v41
	v_pk_mul_f32 v[120:121], v[44:45], s[46:47] op_sel_hi:[1,0]
	v_mul_f32_e32 v4, 0.5, v40
	v_pk_mov_b32 v[44:45], v[108:109], v[70:71] op_sel:[1,0]
	v_pk_mul_f32 v[40:41], v[42:43], s[44:45]
	v_cvt_f32_f16_sdwa v54, v20 dst_sel:DWORD dst_unused:UNUSED_PAD src0_sel:WORD_1
	v_pk_mul_f32 v[42:43], v[44:45], v[40:41] op_sel:[0,1] op_sel_hi:[1,0]
	v_cvt_f32_f16_e32 v55, v21
	v_cvt_f32_f16_sdwa v21, v21 dst_sel:DWORD dst_unused:UNUSED_PAD src0_sel:WORD_1
	v_cvt_f32_f16_e32 v20, v20
	v_pk_mul_f32 v[40:41], v[44:45], v[40:41]
	v_pk_add_f32 v[42:43], v[42:43], v[42:43] op_sel:[0,1] op_sel_hi:[0,1]
	v_pk_add_f32 v[104:105], v[4:5], v[42:43] op_sel_hi:[0,1] neg_hi:[0,1]
	s_nop 0
	v_pk_add_f32 v[40:41], v[40:41], v[40:41] op_sel:[0,1] op_sel_hi:[0,1] neg_lo:[0,1] neg_hi:[0,1]
	v_pk_add_f32 v[42:43], v[6:7], v[40:41] op_sel_hi:[0,1] neg_hi:[0,1]
	v_pk_mul_f32 v[40:41], v[42:43], v[20:21]
	v_pk_mul_f32 v[42:43], v[42:43], v[54:55]
	v_pk_fma_f32 v[40:41], v[104:105], v[54:55], v[40:41]
	v_pk_fma_f32 v[20:21], v[104:105], v[20:21], v[42:43] neg_lo:[0,0,1] neg_hi:[0,0,1]
	v_mov_b32_e32 v71, v109
	v_pk_add_f32 v[42:43], v[20:21], v[40:41] op_sel:[0,1] op_sel_hi:[1,0] neg_lo:[0,1]
	v_pk_add_f32 v[54:55], v[20:21], v[40:41] op_sel:[0,1] op_sel_hi:[1,0]
	v_pk_add_f32 v[20:21], v[40:41], v[20:21] op_sel:[1,0] op_sel_hi:[0,1] neg_lo:[0,1] neg_hi:[0,1]
	v_pk_mul_f32 v[42:43], v[42:43], 0.5 op_sel_hi:[1,0]
	v_mov_b32_e32 v55, v21
	v_mul_f32_e32 v4, v109, v42
	v_pk_fma_f32 v[104:105], v[44:45], v[42:43], v[4:5] op_sel_hi:[1,1,0] neg_lo:[1,0,0] neg_hi:[1,0,0]
	v_mul_f32_e32 v4, v109, v43
	v_pk_fma_f32 v[42:43], v[70:71], v[42:43], v[4:5] op_sel_hi:[1,1,0]
	v_sub_f32_e32 v6, v23, v103
	v_mov_b32_e32 v104, v42
	v_pk_fma_f32 v[40:41], v[54:55], 0.5, v[42:43] op_sel_hi:[1,0,1] neg_lo:[0,0,1] neg_hi:[0,0,1]
	v_pk_fma_f32 v[20:21], v[54:55], 0.5, v[104:105] op_sel_hi:[1,0,1]
	v_pk_add_f32 v[42:43], v[102:103], v[22:23]
	v_mov_b32_e32 v41, v21
	v_pk_mul_f32 v[128:129], v[40:41], s[46:47] op_sel_hi:[1,0]
	v_mul_f32_e32 v40, 0xbf0e39da, v83
	v_mov_b32_e32 v41, v22
	v_mul_f32_e32 v18, 0.5, v43
	v_pk_add_f32 v[22:23], v[40:41], v[46:47] neg_lo:[0,1] neg_hi:[0,1]
	v_mov_b32_e32 v47, v109
	v_pk_mul_f32 v[40:41], v[22:23], v[18:19]
	v_mov_b32_e32 v46, v22
	v_pk_fma_f32 v[44:45], v[44:45], v[40:41], v[40:41] op_sel:[0,1,0] op_sel_hi:[1,0,1]
	v_mov_b32_e32 v40, v41
	v_mov_b32_e32 v41, v18
	v_mul_f32_e32 v4, 0.5, v42
	v_pk_mul_f32 v[40:41], v[46:47], v[40:41]
	v_cvt_f32_f16_e32 v46, v10
	v_cvt_f32_f16_e32 v47, v11
	v_cvt_f32_f16_sdwa v11, v11 dst_sel:DWORD dst_unused:UNUSED_PAD src0_sel:WORD_1
	v_cvt_f32_f16_sdwa v10, v10 dst_sel:DWORD dst_unused:UNUSED_PAD src0_sel:WORD_1
	v_pk_fma_f32 v[70:71], v[54:55], 0.5, v[104:105] op_sel_hi:[1,0,1] neg_lo:[1,0,0] neg_hi:[1,0,0]
	v_mul_f32_e32 v6, 0.5, v6
	v_pk_add_f32 v[54:55], v[4:5], v[44:45]
	v_pk_add_f32 v[40:41], v[40:41], v[40:41] op_sel:[0,1] op_sel_hi:[0,1] neg_lo:[0,1] neg_hi:[0,1]
	v_fma_f32 v55, v42, 0.5, -v44
	v_pk_add_f32 v[42:43], v[6:7], v[40:41] op_sel_hi:[0,1] neg_hi:[0,1]
	v_pk_mul_f32 v[40:41], v[42:43], v[10:11]
	v_pk_mul_f32 v[42:43], v[42:43], v[46:47]
	v_pk_fma_f32 v[44:45], v[54:55], v[46:47], v[40:41] neg_lo:[0,0,1] neg_hi:[0,0,1]
	v_pk_fma_f32 v[40:41], v[54:55], v[46:47], v[40:41]
	v_pk_fma_f32 v[46:47], v[54:55], v[10:11], v[42:43]
	v_pk_fma_f32 v[10:11], v[54:55], v[10:11], v[42:43] neg_lo:[0,0,1] neg_hi:[0,0,1]
	v_pk_add_f32 v[42:43], v[44:45], v[40:41] op_sel:[0,1] op_sel_hi:[1,0]
	v_pk_add_f32 v[54:55], v[46:47], v[10:11] op_sel_hi:[0,1] neg_lo:[0,1] neg_hi:[0,1]
	v_pk_add_f32 v[40:41], v[44:45], v[40:41] op_sel_hi:[0,1] neg_lo:[0,1] neg_hi:[0,1]
	v_pk_add_f32 v[10:11], v[46:47], v[10:11] op_sel:[0,1] op_sel_hi:[1,0]
	v_mov_b32_e32 v43, v55
	v_mov_b32_e32 v11, v41
	v_pk_mul_f32 v[10:11], v[10:11], 0.5 op_sel_hi:[1,0]
	v_mov_b32_e32 v119, v98
	v_pk_mul_f32 v[40:41], v[108:109], v[10:11] op_sel:[1,1] op_sel_hi:[1,0]
	v_pk_fma_f32 v[76:77], v[76:77], 0.5, v[112:113] op_sel_hi:[1,0,1] neg_lo:[1,0,0] neg_hi:[1,0,0]
	v_pk_fma_f32 v[44:45], v[22:23], v[10:11], v[40:41] op_sel_hi:[0,1,1]
	v_pk_fma_f32 v[10:11], v[22:23], v[10:11], v[40:41] op_sel_hi:[0,1,1] neg_hi:[0,0,1]
	v_pk_fma_f32 v[22:23], v[42:43], 0.5, v[44:45] op_sel_hi:[1,0,1] neg_lo:[0,0,1] neg_hi:[0,0,1]
	v_pk_fma_f32 v[40:41], v[42:43], 0.5, v[10:11] op_sel_hi:[1,0,1]
	v_pk_fma_f32 v[54:55], v[42:43], 0.5, v[10:11] op_sel_hi:[1,0,1] neg_lo:[1,0,0] neg_hi:[1,0,0]
	v_pk_add_f32 v[10:11], v[100:101], v[14:15]
	v_pk_add_f32 v[14:15], v[14:15], v[100:101] neg_lo:[0,1] neg_hi:[0,1]
	v_mov_b32_e32 v23, v41
	v_mul_f32_e32 v6, 0.5, v15
	v_mov_b32_e32 v15, v11
	v_pk_mul_f32 v[150:151], v[22:23], s[46:47] op_sel_hi:[1,0]
	v_mul_f32_e32 v4, 0.5, v10
	v_pk_mov_b32 v[22:23], v[58:59], v[72:73] op_sel:[1,0]
	v_pk_mul_f32 v[10:11], v[14:15], s[44:45]
	v_cvt_f32_f16_sdwa v42, v8 dst_sel:DWORD dst_unused:UNUSED_PAD src0_sel:WORD_1
	v_pk_mul_f32 v[14:15], v[22:23], v[10:11] op_sel:[0,1] op_sel_hi:[1,0]
	v_cvt_f32_f16_e32 v43, v9
	v_cvt_f32_f16_sdwa v9, v9 dst_sel:DWORD dst_unused:UNUSED_PAD src0_sel:WORD_1
	v_cvt_f32_f16_e32 v8, v8
	v_pk_mul_f32 v[10:11], v[22:23], v[10:11]
	v_pk_add_f32 v[14:15], v[14:15], v[14:15] op_sel:[0,1] op_sel_hi:[0,1]
	v_pk_add_f32 v[44:45], v[4:5], v[14:15] op_sel_hi:[0,1] neg_hi:[0,1]
	s_nop 0
	v_pk_add_f32 v[10:11], v[10:11], v[10:11] op_sel:[0,1] op_sel_hi:[0,1] neg_lo:[0,1] neg_hi:[0,1]
	v_pk_add_f32 v[14:15], v[6:7], v[10:11] op_sel_hi:[0,1] neg_hi:[0,1]
	v_pk_mul_f32 v[10:11], v[14:15], v[8:9]
	v_pk_mul_f32 v[14:15], v[14:15], v[42:43]
	v_pk_fma_f32 v[10:11], v[44:45], v[42:43], v[10:11]
	v_pk_fma_f32 v[8:9], v[44:45], v[8:9], v[14:15] neg_lo:[0,0,1] neg_hi:[0,0,1]
	v_mov_b32_e32 v73, v59
	v_pk_add_f32 v[14:15], v[8:9], v[10:11] op_sel:[0,1] op_sel_hi:[1,0] neg_lo:[0,1]
	v_pk_add_f32 v[42:43], v[8:9], v[10:11] op_sel:[0,1] op_sel_hi:[1,0]
	v_pk_add_f32 v[8:9], v[10:11], v[8:9] op_sel:[1,0] op_sel_hi:[0,1] neg_lo:[0,1] neg_hi:[0,1]
	v_pk_mul_f32 v[14:15], v[14:15], 0.5 op_sel_hi:[1,0]
	v_mov_b32_e32 v43, v9
	v_mul_f32_e32 v4, v59, v14
	v_pk_fma_f32 v[44:45], v[22:23], v[14:15], v[4:5] op_sel_hi:[1,1,0] neg_lo:[1,0,0] neg_hi:[1,0,0]
	v_mul_f32_e32 v4, v59, v15
	v_pk_fma_f32 v[14:15], v[72:73], v[14:15], v[4:5] op_sel_hi:[1,1,0]
	v_sub_f32_e32 v6, v37, v99
	v_mov_b32_e32 v44, v14
	v_pk_fma_f32 v[8:9], v[42:43], 0.5, v[14:15] op_sel_hi:[1,0,1] neg_lo:[0,0,1] neg_hi:[0,0,1]
	v_pk_fma_f32 v[10:11], v[42:43], 0.5, v[44:45] op_sel_hi:[1,0,1]
	v_pk_add_f32 v[14:15], v[98:99], v[36:37]
	v_mov_b32_e32 v9, v11
	v_pk_mul_f32 v[168:169], v[8:9], s[46:47] op_sel_hi:[1,0]
	v_mul_f32_e32 v8, 0xbf7b14be, v83
	v_mov_b32_e32 v9, v36
	v_mul_f32_e32 v18, 0.5, v15
	v_pk_add_f32 v[8:9], v[8:9], v[118:119] neg_lo:[0,1] neg_hi:[0,1]
	v_pk_fma_f32 v[72:73], v[42:43], 0.5, v[44:45] op_sel_hi:[1,0,1] neg_lo:[1,0,0] neg_hi:[1,0,0]
	v_pk_mul_f32 v[36:37], v[8:9], v[18:19]
	v_mov_b32_e32 v42, v8
	v_pk_fma_f32 v[22:23], v[22:23], v[36:37], v[36:37] op_sel:[0,1,0] op_sel_hi:[1,0,1]
	v_mov_b32_e32 v43, v59
	v_mov_b32_e32 v36, v37
	v_mov_b32_e32 v37, v18
	v_mul_f32_e32 v4, 0.5, v14
	v_pk_mul_f32 v[36:37], v[42:43], v[36:37]
	v_cvt_f32_f16_e32 v44, v2
	v_cvt_f32_f16_e32 v45, v3
	v_cvt_f32_f16_sdwa v3, v3 dst_sel:DWORD dst_unused:UNUSED_PAD src0_sel:WORD_1
	v_cvt_f32_f16_sdwa v2, v2 dst_sel:DWORD dst_unused:UNUSED_PAD src0_sel:WORD_1
	v_mul_f32_e32 v6, 0.5, v6
	v_pk_add_f32 v[46:47], v[4:5], v[22:23]
	v_fma_f32 v4, v14, 0.5, -v22
	v_pk_add_f32 v[22:23], v[36:37], v[36:37] op_sel:[0,1] op_sel_hi:[0,1] neg_lo:[0,1] neg_hi:[0,1]
	v_pk_add_f32 v[36:37], v[6:7], v[22:23] op_sel_hi:[0,1] neg_hi:[0,1]
	v_mov_b32_e32 v14, v46
	v_mov_b32_e32 v15, v4
	v_pk_mul_f32 v[22:23], v[4:5], v[44:45] op_sel_hi:[0,1]
	v_pk_mul_f32 v[82:83], v[36:37], v[2:3]
	v_pk_mul_f32 v[46:47], v[46:47], v[2:3]
	v_pk_mul_f32 v[36:37], v[36:37], v[44:45]
	v_pk_fma_f32 v[98:99], v[14:15], v[44:45], v[82:83] neg_lo:[0,0,1] neg_hi:[0,0,1]
	v_pk_fma_f32 v[2:3], v[14:15], v[2:3], v[36:37] neg_lo:[0,0,1] neg_hi:[0,0,1]
	v_add_f32_e32 v4, v23, v83
	v_add_f32_e32 v6, v46, v36
	v_pk_add_f32 v[22:23], v[6:7], v[2:3] op_sel_hi:[0,1] neg_lo:[0,1] neg_hi:[0,1]
	v_pk_add_f32 v[36:37], v[98:99], v[4:5] op_sel_hi:[1,0] neg_lo:[0,1] neg_hi:[0,1]
	v_pk_add_f32 v[2:3], v[6:7], v[2:3] op_sel_hi:[0,1]
	v_mov_b32_e32 v37, v3
	v_pk_mul_f32 v[2:3], v[36:37], 0.5 op_sel_hi:[1,0]
	v_pk_add_f32 v[14:15], v[98:99], v[4:5] op_sel_hi:[1,0]
	v_mul_f32_e32 v4, v59, v3
	v_pk_fma_f32 v[36:37], v[42:43], v[2:3], v[4:5] op_sel_hi:[1,1,0] neg_lo:[0,0,1] neg_hi:[0,0,1]
	v_pk_mov_b32 v[42:43], v[58:59], v[8:9] op_sel:[1,0]
	v_mul_f32_e32 v4, v8, v3
	v_pk_fma_f32 v[2:3], v[42:43], v[2:3], v[4:5] op_sel_hi:[1,1,0]
	v_mov_b32_e32 v15, v23
	v_pk_fma_f32 v[8:9], v[14:15], 0.5, v[2:3] op_sel_hi:[1,0,1] neg_lo:[0,0,1] neg_hi:[0,0,1]
	v_pk_fma_f32 v[42:43], v[14:15], 0.5, v[36:37] op_sel_hi:[1,0,0]
	v_pk_fma_f32 v[2:3], v[14:15], 0.5, v[2:3] op_sel_hi:[1,0,1]
	v_mov_b32_e32 v9, v43
	v_pk_fma_f32 v[58:59], v[22:23], 0.5, v[36:37] op_sel_hi:[1,0,0] neg_lo:[1,0,0] neg_hi:[1,0,0]
	v_pk_mul_f32 v[144:145], v[8:9], s[46:47] op_sel_hi:[1,0]
	v_mov_b32_e32 v58, v2
	v_mov_b32_e32 v72, v10
	v_mov_b32_e32 v54, v40
	v_mov_b32_e32 v70, v20
	v_mov_b32_e32 v56, v26
	v_mov_b32_e32 v76, v38
	v_mov_b32_e32 v52, v34
	v_mov_b32_e32 v74, v86
	v_mov_b32_e32 v48, v84
	v_mov_b32_e32 v50, v60
	v_mov_b32_e32 v28, v66
	v_mov_b32_e32 v32, v96
	v_mov_b32_e32 v12, v88
	v_mov_b32_e32 v16, v92
	v_mov_b32_e32 v4, v138
	v_mov_b32_e32 v6, v122

.LBB0_560:
	s_or_b64 exec, exec, s[0:1]
	v_mov_b32_e32 v2, v142
	s_waitcnt lgkmcnt(0)
	s_barrier
	s_mov_b32 s41, s38
	v_and_b32_e32 v4, 0x1ff, v2
	v_lshlrev_b32_e32 v2, 5, v2
	v_and_or_b32 v2, v2, s34, v4
	v_ashrrev_i32_e32 v6, 5, v2
	v_lshlrev_b32_e32 v2, 3, v2
	v_lshlrev_b32_e32 v7, 3, v6
	v_add3_u32 v2, 0, v2, v7
	v_add_u32_e32 v143, 0x10800, v2
	ds_read_b64 v[128:129], v2
	ds_read_b64 v[130:131], v2 offset:4224
	ds_read_b64 v[144:145], v2 offset:8448
	ds_read_b64 v[148:149], v2 offset:12672
	ds_read_b64 v[150:151], v2 offset:16896
	ds_read_b64 v[152:153], v2 offset:21120
	ds_read_b64 v[154:155], v2 offset:25344
	ds_read_b64 v[156:157], v2 offset:29568
	ds_read_b64 v[158:159], v2 offset:33792
	ds_read_b64 v[160:161], v2 offset:38016
	ds_read_b64 v[162:163], v2 offset:42240
	ds_read_b64 v[164:165], v2 offset:46464
	ds_read_b64 v[166:167], v2 offset:50688
	ds_read_b64 v[168:169], v2 offset:54912
	ds_read_b64 v[170:171], v2 offset:59136
	ds_read_b64 v[172:173], v2 offset:63360
	v_add_u32_e32 v212, 0x11880, v2
	v_add_u32_e32 v213, 0x12900, v2
	v_add_u32_e32 v214, 0x13980, v2
	ds_read_b64 v[174:175], v143
	ds_read_b64 v[176:177], v212
	ds_read_b64 v[178:179], v213
	ds_read_b64 v[180:181], v214
	v_add_u32_e32 v215, 0x14a00, v2
	s_waitcnt lgkmcnt(3)
	v_pk_add_f32 v[210:211], v[128:129], v[174:175]
	v_pk_add_f32 v[128:129], v[128:129], v[174:175] neg_lo:[0,1] neg_hi:[0,1]
	s_waitcnt lgkmcnt(2)
	v_pk_add_f32 v[174:175], v[130:131], v[176:177]
	v_pk_add_f32 v[130:131], v[130:131], v[176:177] neg_lo:[0,1] neg_hi:[0,1]
	v_add_u32_e32 v216, 0x15a80, v2
	v_pk_mul_f32 v[176:177], v[130:131], s[20:21]
	v_add_u32_e32 v217, 0x16b00, v2
	v_pk_fma_f32 v[130:131], v[130:131], s[10:11], v[176:177] op_sel:[0,0,1] op_sel_hi:[1,0,0]
	s_waitcnt lgkmcnt(1)
	v_pk_add_f32 v[176:177], v[144:145], v[178:179]
	v_pk_add_f32 v[144:145], v[144:145], v[178:179] neg_lo:[0,1] neg_hi:[0,1]
	v_add_u32_e32 v218, 0x17b80, v2
	v_pk_mul_f32 v[178:179], v[144:145], s[24:25]
	ds_read_b64 v[182:183], v215
	ds_read_b64 v[184:185], v216
	ds_read_b64 v[186:187], v217
	ds_read_b64 v[188:189], v218
	v_pk_fma_f32 v[144:145], v[144:145], s[22:23], v[178:179] op_sel:[0,0,1] op_sel_hi:[1,0,0]
	s_waitcnt lgkmcnt(4)
	v_pk_add_f32 v[178:179], v[148:149], v[180:181]
	v_pk_add_f32 v[148:149], v[148:149], v[180:181] neg_lo:[0,1] neg_hi:[0,1]
	s_mov_b32 s43, s26
	v_pk_mul_f32 v[180:181], v[148:149], s[36:37]
	s_mov_b32 s0, s37
	v_pk_fma_f32 v[148:149], v[148:149], s[26:27], v[180:181] op_sel:[0,0,1] op_sel_hi:[1,0,0]
	s_waitcnt lgkmcnt(3)
	v_pk_add_f32 v[180:181], v[150:151], v[182:183]
	v_pk_add_f32 v[150:151], v[150:151], v[182:183] neg_lo:[0,1] neg_hi:[0,1]
	s_mov_b32 s45, s22
	v_pk_mul_f32 v[182:183], v[150:151], s[40:41]
	v_add_u32_e32 v219, 0x18c00, v2
	v_pk_fma_f32 v[150:151], v[150:151], s[38:39], v[182:183] op_sel:[0,0,1] op_sel_hi:[1,0,0]
	s_waitcnt lgkmcnt(2)
	v_pk_add_f32 v[182:183], v[152:153], v[184:185]
	v_pk_add_f32 v[152:153], v[152:153], v[184:185] neg_lo:[0,1] neg_hi:[0,1]
	s_mov_b32 s50, s25
	v_pk_mul_f32 v[184:185], v[152:153], s[42:43]
	v_add_u32_e32 v220, 0x19c80, v2
	v_pk_fma_f32 v[152:153], v[152:153], s[0:1], v[184:185] op_sel:[0,0,1] op_sel_hi:[1,0,0]
	s_waitcnt lgkmcnt(1)
	v_pk_add_f32 v[184:185], v[154:155], v[186:187]
	v_pk_add_f32 v[154:155], v[154:155], v[186:187] neg_lo:[0,1] neg_hi:[0,1]
	v_add_u32_e32 v221, 0x1ad00, v2
	v_pk_mul_f32 v[186:187], v[154:155], s[44:45]
	v_add_u32_e32 v222, 0x1bd80, v2
	ds_read_b64 v[190:191], v219
	ds_read_b64 v[192:193], v220
	ds_read_b64 v[194:195], v221
	ds_read_b64 v[196:197], v222
	v_pk_fma_f32 v[154:155], v[154:155], s[50:51], v[186:187] op_sel:[0,0,1] op_sel_hi:[1,0,0]
	s_waitcnt lgkmcnt(4)
	v_pk_add_f32 v[186:187], v[156:157], v[188:189]
	v_pk_add_f32 v[156:157], v[156:157], v[188:189] neg_lo:[0,1] neg_hi:[0,1]
	v_add_u32_e32 v223, 0x1ce00, v2
	v_pk_mul_f32 v[188:189], v[156:157], s[8:9]
	v_add_u32_e32 v224, 0x1de80, v2
	v_pk_fma_f32 v[156:157], v[156:157], s[16:17], v[188:189] op_sel:[0,0,1] op_sel_hi:[1,0,0]
	s_waitcnt lgkmcnt(3)
	v_pk_add_f32 v[188:189], v[158:159], v[190:191]
	v_pk_add_f32 v[190:191], v[158:159], v[190:191] neg_lo:[0,1] neg_hi:[0,1]
	v_add_u32_e32 v225, 0x1ef00, v2
	s_waitcnt lgkmcnt(2)
	v_pk_add_f32 v[158:159], v[160:161], v[192:193]
	v_pk_add_f32 v[160:161], v[160:161], v[192:193] neg_lo:[0,1] neg_hi:[0,1]
	v_add_u32_e32 v226, 0x1ff80, v2
	v_pk_mul_f32 v[192:193], v[160:161], s[8:9]
	ds_read_b64 v[198:199], v223
	ds_read_b64 v[204:205], v224
	ds_read_b64 v[206:207], v225
	ds_read_b64 v[208:209], v226
	v_pk_fma_f32 v[160:161], v[160:161], s[16:17], v[192:193] op_sel:[0,0,1] op_sel_hi:[1,0,0] neg_lo:[1,0,0] neg_hi:[1,0,0]
	s_waitcnt lgkmcnt(5)
	v_pk_add_f32 v[192:193], v[162:163], v[194:195]
	v_pk_add_f32 v[162:163], v[162:163], v[194:195] neg_lo:[0,1] neg_hi:[0,1]
	v_cvt_f32_u32_e32 v5, v4
	v_pk_mul_f32 v[194:195], v[162:163], s[44:45]
	v_mul_f32_e32 v5, 0x38800000, v5
	v_pk_fma_f32 v[162:163], v[162:163], s[50:51], v[194:195] op_sel:[0,0,1] op_sel_hi:[1,0,0] neg_lo:[1,0,0] neg_hi:[1,0,0]
	s_waitcnt lgkmcnt(4)
	v_pk_add_f32 v[194:195], v[164:165], v[196:197]
	v_pk_add_f32 v[164:165], v[164:165], v[196:197] neg_lo:[0,1] neg_hi:[0,1]
	v_sin_f32_e32 v4, v5
	v_pk_mul_f32 v[196:197], v[164:165], s[42:43]
	v_cos_f32_e32 v6, v5
	v_pk_fma_f32 v[164:165], v[164:165], s[0:1], v[196:197] op_sel:[0,0,1] op_sel_hi:[1,0,0] neg_lo:[1,0,0] neg_hi:[1,0,0]
	s_waitcnt lgkmcnt(3)
	v_pk_add_f32 v[196:197], v[166:167], v[198:199]
	v_pk_add_f32 v[166:167], v[166:167], v[198:199] neg_lo:[0,1] neg_hi:[0,1]
	v_xor_b32_e32 v7, 0x80000000, v4
	v_pk_mul_f32 v[198:199], v[166:167], s[40:41]
	v_mov_b32_e32 v5, v7
	v_pk_fma_f32 v[166:167], v[166:167], s[38:39], v[198:199] op_sel:[0,0,1] op_sel_hi:[1,0,0] neg_lo:[1,0,0] neg_hi:[1,0,0]
	s_waitcnt lgkmcnt(2)
	v_pk_add_f32 v[198:199], v[168:169], v[204:205]
	v_pk_add_f32 v[168:169], v[168:169], v[204:205] neg_lo:[0,1] neg_hi:[0,1]
	v_pk_mul_f32 v[8:9], v[6:7], v[4:5] op_sel:[1,0] op_sel_hi:[0,1]
	v_pk_mul_f32 v[204:205], v[168:169], s[36:37]
	v_pk_fma_f32 v[8:9], v[6:7], v[6:7], v[8:9] op_sel_hi:[1,0,1]
	v_pk_fma_f32 v[168:169], v[168:169], s[26:27], v[204:205] op_sel:[0,0,1] op_sel_hi:[1,0,0] neg_lo:[1,0,0] neg_hi:[1,0,0]
	s_waitcnt lgkmcnt(1)
	v_pk_add_f32 v[204:205], v[170:171], v[206:207]
	v_pk_add_f32 v[170:171], v[170:171], v[206:207] neg_lo:[0,1] neg_hi:[0,1]
	v_xor_b32_e32 v14, 0x80000000, v9
	v_pk_mul_f32 v[206:207], v[170:171], s[24:25]
	v_mov_b32_e32 v15, v9
	v_pk_fma_f32 v[170:171], v[170:171], s[22:23], v[206:207] op_sel:[0,0,1] op_sel_hi:[1,0,0] neg_lo:[1,0,0] neg_hi:[1,0,0]
	s_waitcnt lgkmcnt(0)
	v_pk_add_f32 v[206:207], v[172:173], v[208:209]
	v_pk_add_f32 v[172:173], v[172:173], v[208:209] neg_lo:[0,1] neg_hi:[0,1]
	v_pk_mul_f32 v[12:13], v[8:9], v[14:15] op_sel:[1,0] op_sel_hi:[0,1]
	v_pk_mul_f32 v[208:209], v[172:173], s[20:21]
	v_pk_fma_f32 v[12:13], v[8:9], v[8:9], v[12:13] op_sel_hi:[1,0,1]
	v_pk_fma_f32 v[172:173], v[172:173], s[10:11], v[208:209] op_sel:[0,0,1] op_sel_hi:[1,0,0] neg_lo:[1,0,0] neg_hi:[1,0,0]
	v_pk_add_f32 v[208:209], v[210:211], v[188:189]
	v_pk_add_f32 v[188:189], v[210:211], v[188:189] neg_lo:[0,1] neg_hi:[0,1]
	v_pk_add_f32 v[210:211], v[174:175], v[158:159]
	v_pk_add_f32 v[158:159], v[174:175], v[158:159] neg_lo:[0,1] neg_hi:[0,1]
	v_xor_b32_e32 v16, 0x80000000, v13
	v_pk_mul_f32 v[174:175], v[158:159], s[24:25]
	v_mov_b32_e32 v17, v13
	v_pk_fma_f32 v[158:159], v[158:159], s[22:23], v[174:175] op_sel:[0,0,1] op_sel_hi:[1,0,0]
	v_pk_add_f32 v[174:175], v[176:177], v[192:193]
	v_pk_add_f32 v[176:177], v[176:177], v[192:193] neg_lo:[0,1] neg_hi:[0,1]
	v_pk_mul_f32 v[28:29], v[12:13], v[16:17] op_sel:[1,0] op_sel_hi:[0,1]
	v_pk_mul_f32 v[192:193], v[176:177], s[40:41]
	v_pk_fma_f32 v[28:29], v[12:13], v[12:13], v[28:29] op_sel_hi:[1,0,1]
	v_pk_fma_f32 v[176:177], v[176:177], s[38:39], v[192:193] op_sel:[0,0,1] op_sel_hi:[1,0,0]
	v_pk_add_f32 v[192:193], v[178:179], v[194:195]
	v_pk_add_f32 v[178:179], v[178:179], v[194:195] neg_lo:[0,1] neg_hi:[0,1]
	v_pk_mul_f32 v[44:45], v[16:17], v[28:29] op_sel:[0,1] op_sel_hi:[1,0]
	v_pk_mul_f32 v[194:195], v[178:179], s[44:45]
	v_pk_fma_f32 v[44:45], v[12:13], v[28:29], v[44:45] op_sel_hi:[0,1,1]
	v_pk_fma_f32 v[178:179], v[178:179], s[50:51], v[194:195] op_sel:[0,0,1] op_sel_hi:[1,0,0]
	v_pk_add_f32 v[194:195], v[180:181], v[196:197]
	v_pk_add_f32 v[196:197], v[180:181], v[196:197] neg_lo:[0,1] neg_hi:[0,1]
	v_pk_mul_f32 v[60:61], v[16:17], v[44:45] op_sel:[0,1] op_sel_hi:[1,0]
	v_pk_add_f32 v[180:181], v[182:183], v[198:199]
	v_pk_add_f32 v[182:183], v[182:183], v[198:199] neg_lo:[0,1] neg_hi:[0,1]
	v_pk_fma_f32 v[60:61], v[12:13], v[44:45], v[60:61] op_sel_hi:[0,1,1]
	v_pk_mul_f32 v[198:199], v[182:183], s[44:45]
	v_pk_mul_f32 v[76:77], v[16:17], v[60:61] op_sel:[0,1] op_sel_hi:[1,0]
	v_pk_fma_f32 v[182:183], v[182:183], s[50:51], v[198:199] op_sel:[0,0,1] op_sel_hi:[1,0,0] neg_lo:[1,0,0] neg_hi:[1,0,0]
	v_pk_add_f32 v[198:199], v[184:185], v[204:205]
	v_pk_add_f32 v[184:185], v[184:185], v[204:205] neg_lo:[0,1] neg_hi:[0,1]
	v_pk_fma_f32 v[76:77], v[12:13], v[60:61], v[76:77] op_sel_hi:[0,1,1]
	v_pk_mul_f32 v[204:205], v[184:185], s[40:41]
	v_pk_mul_f32 v[92:93], v[16:17], v[76:77] op_sel:[0,1] op_sel_hi:[1,0]
	v_pk_fma_f32 v[184:185], v[184:185], s[38:39], v[204:205] op_sel:[0,0,1] op_sel_hi:[1,0,0] neg_lo:[1,0,0] neg_hi:[1,0,0]
	v_pk_add_f32 v[204:205], v[186:187], v[206:207]
	v_pk_add_f32 v[186:187], v[186:187], v[206:207] neg_lo:[0,1] neg_hi:[0,1]
	v_pk_fma_f32 v[92:93], v[12:13], v[76:77], v[92:93] op_sel_hi:[0,1,1]
	v_pk_mul_f32 v[206:207], v[186:187], s[24:25]
	v_pk_mul_f32 v[108:109], v[16:17], v[92:93] op_sel:[0,1] op_sel_hi:[1,0]
	v_pk_fma_f32 v[186:187], v[186:187], s[22:23], v[206:207] op_sel:[0,0,1] op_sel_hi:[1,0,0] neg_lo:[1,0,0] neg_hi:[1,0,0]
	v_pk_add_f32 v[206:207], v[128:129], v[190:191] op_sel:[0,1] op_sel_hi:[1,0] neg_hi:[0,1]
	v_pk_add_f32 v[128:129], v[128:129], v[190:191] op_sel:[0,1] op_sel_hi:[1,0] neg_lo:[0,1]
	v_pk_add_f32 v[190:191], v[130:131], v[160:161]
	v_pk_add_f32 v[130:131], v[130:131], v[160:161] neg_lo:[0,1] neg_hi:[0,1]
	v_pk_mul_f32 v[10:11], v[4:5], v[8:9] op_sel:[0,1] op_sel_hi:[1,0]
	v_pk_mul_f32 v[160:161], v[130:131], s[24:25]
	v_pk_fma_f32 v[108:109], v[12:13], v[92:93], v[108:109] op_sel_hi:[0,1,1]
	v_pk_fma_f32 v[130:131], v[130:131], s[22:23], v[160:161] op_sel:[0,0,1] op_sel_hi:[1,0,0]
	v_pk_add_f32 v[160:161], v[144:145], v[162:163]
	v_pk_add_f32 v[144:145], v[144:145], v[162:163] neg_lo:[0,1] neg_hi:[0,1]
	v_pk_fma_f32 v[10:11], v[6:7], v[8:9], v[10:11] op_sel_hi:[0,1,1]
	v_pk_mul_f32 v[162:163], v[144:145], s[40:41]
	v_pk_mul_f32 v[18:19], v[4:5], v[12:13] op_sel:[0,1] op_sel_hi:[1,0]
	v_pk_fma_f32 v[144:145], v[144:145], s[38:39], v[162:163] op_sel:[0,0,1] op_sel_hi:[1,0,0]
	v_pk_add_f32 v[162:163], v[148:149], v[164:165]
	v_pk_add_f32 v[148:149], v[148:149], v[164:165] neg_lo:[0,1] neg_hi:[0,1]
	v_pk_mul_f32 v[32:33], v[4:5], v[28:29] op_sel:[0,1] op_sel_hi:[1,0]
	v_pk_mul_f32 v[164:165], v[148:149], s[44:45]
	v_pk_mul_f32 v[48:49], v[4:5], v[44:45] op_sel:[0,1] op_sel_hi:[1,0]
	v_pk_fma_f32 v[148:149], v[148:149], s[50:51], v[164:165] op_sel:[0,0,1] op_sel_hi:[1,0,0]
	v_pk_add_f32 v[164:165], v[150:151], v[166:167]
	v_pk_add_f32 v[166:167], v[150:151], v[166:167] neg_lo:[0,1] neg_hi:[0,1]
	v_pk_mul_f32 v[64:65], v[4:5], v[60:61] op_sel:[0,1] op_sel_hi:[1,0]
	v_pk_add_f32 v[150:151], v[152:153], v[168:169]
	v_pk_add_f32 v[152:153], v[152:153], v[168:169] neg_lo:[0,1] neg_hi:[0,1]
	v_pk_mul_f32 v[80:81], v[4:5], v[76:77] op_sel:[0,1] op_sel_hi:[1,0]
	v_pk_mul_f32 v[168:169], v[152:153], s[44:45]
	v_pk_mul_f32 v[96:97], v[4:5], v[92:93] op_sel:[0,1] op_sel_hi:[1,0]
	v_pk_fma_f32 v[152:153], v[152:153], s[50:51], v[168:169] op_sel:[0,0,1] op_sel_hi:[1,0,0] neg_lo:[1,0,0] neg_hi:[1,0,0]
	v_pk_add_f32 v[168:169], v[154:155], v[170:171]
	v_pk_add_f32 v[154:155], v[154:155], v[170:171] neg_lo:[0,1] neg_hi:[0,1]
	v_pk_mul_f32 v[112:113], v[4:5], v[108:109] op_sel:[0,1] op_sel_hi:[1,0]
	v_pk_mul_f32 v[170:171], v[154:155], s[40:41]
	v_xor_b32_e32 v22, 0x80000000, v11
	v_pk_fma_f32 v[154:155], v[154:155], s[38:39], v[170:171] op_sel:[0,0,1] op_sel_hi:[1,0,0] neg_lo:[1,0,0] neg_hi:[1,0,0]
	v_pk_add_f32 v[170:171], v[156:157], v[172:173]
	v_pk_add_f32 v[156:157], v[156:157], v[172:173] neg_lo:[0,1] neg_hi:[0,1]
	v_mov_b32_e32 v23, v11
	v_pk_mul_f32 v[172:173], v[156:157], s[24:25]
	v_pk_fma_f32 v[18:19], v[6:7], v[12:13], v[18:19] op_sel_hi:[0,1,1]
	v_pk_fma_f32 v[156:157], v[156:157], s[22:23], v[172:173] op_sel:[0,0,1] op_sel_hi:[1,0,0] neg_lo:[1,0,0] neg_hi:[1,0,0]
	v_pk_add_f32 v[172:173], v[208:209], v[194:195]
	v_pk_add_f32 v[194:195], v[208:209], v[194:195] neg_lo:[0,1] neg_hi:[0,1]
	v_pk_add_f32 v[208:209], v[210:211], v[180:181]
	v_pk_add_f32 v[180:181], v[210:211], v[180:181] neg_lo:[0,1] neg_hi:[0,1]
	v_pk_mul_f32 v[20:21], v[14:15], v[12:13] op_sel:[0,1] op_sel_hi:[1,0]
	v_pk_mul_f32 v[210:211], v[180:181], s[40:41]
	v_pk_fma_f32 v[32:33], v[6:7], v[28:29], v[32:33] op_sel_hi:[0,1,1]
	v_pk_fma_f32 v[180:181], v[180:181], s[38:39], v[210:211] op_sel:[0,0,1] op_sel_hi:[1,0,0]
	v_pk_add_f32 v[210:211], v[174:175], v[198:199]
	v_pk_add_f32 v[198:199], v[174:175], v[198:199] neg_lo:[0,1] neg_hi:[0,1]
	v_pk_mul_f32 v[36:37], v[14:15], v[28:29] op_sel:[0,1] op_sel_hi:[1,0]
	v_pk_add_f32 v[174:175], v[192:193], v[204:205]
	v_pk_add_f32 v[192:193], v[192:193], v[204:205] neg_lo:[0,1] neg_hi:[0,1]
	v_pk_fma_f32 v[48:49], v[6:7], v[44:45], v[48:49] op_sel_hi:[0,1,1]
	v_pk_mul_f32 v[204:205], v[192:193], s[40:41]
	v_pk_mul_f32 v[52:53], v[14:15], v[44:45] op_sel:[0,1] op_sel_hi:[1,0]
	v_pk_fma_f32 v[192:193], v[192:193], s[38:39], v[204:205] op_sel:[0,0,1] op_sel_hi:[1,0,0] neg_lo:[1,0,0] neg_hi:[1,0,0]
	v_pk_add_f32 v[204:205], v[188:189], v[196:197] op_sel:[0,1] op_sel_hi:[1,0] neg_hi:[0,1]
	v_pk_add_f32 v[188:189], v[188:189], v[196:197] op_sel:[0,1] op_sel_hi:[1,0] neg_lo:[0,1]
	v_pk_add_f32 v[196:197], v[158:159], v[182:183]
	v_pk_add_f32 v[158:159], v[158:159], v[182:183] neg_lo:[0,1] neg_hi:[0,1]
	v_pk_fma_f32 v[64:65], v[6:7], v[60:61], v[64:65] op_sel_hi:[0,1,1]
	v_pk_mul_f32 v[182:183], v[158:159], s[40:41]
	v_pk_mul_f32 v[68:69], v[14:15], v[60:61] op_sel:[0,1] op_sel_hi:[1,0]
	v_pk_fma_f32 v[158:159], v[158:159], s[38:39], v[182:183] op_sel:[0,0,1] op_sel_hi:[1,0,0]
	v_pk_add_f32 v[182:183], v[176:177], v[184:185]
	v_pk_add_f32 v[184:185], v[176:177], v[184:185] neg_lo:[0,1] neg_hi:[0,1]
	v_pk_fma_f32 v[80:81], v[6:7], v[76:77], v[80:81] op_sel_hi:[0,1,1]
	v_pk_add_f32 v[176:177], v[178:179], v[186:187]
	v_pk_add_f32 v[178:179], v[178:179], v[186:187] neg_lo:[0,1] neg_hi:[0,1]
	v_pk_mul_f32 v[84:85], v[14:15], v[76:77] op_sel:[0,1] op_sel_hi:[1,0]
	v_pk_mul_f32 v[186:187], v[178:179], s[40:41]
	v_pk_fma_f32 v[96:97], v[6:7], v[92:93], v[96:97] op_sel_hi:[0,1,1]
	v_pk_fma_f32 v[178:179], v[178:179], s[38:39], v[186:187] op_sel:[0,0,1] op_sel_hi:[1,0,0] neg_lo:[1,0,0] neg_hi:[1,0,0]
	v_pk_add_f32 v[186:187], v[206:207], v[164:165]
	v_pk_add_f32 v[164:165], v[206:207], v[164:165] neg_lo:[0,1] neg_hi:[0,1]
	v_pk_add_f32 v[206:207], v[190:191], v[150:151]
	v_pk_add_f32 v[150:151], v[190:191], v[150:151] neg_lo:[0,1] neg_hi:[0,1]
	v_pk_mul_f32 v[100:101], v[14:15], v[92:93] op_sel:[0,1] op_sel_hi:[1,0]
	v_pk_mul_f32 v[190:191], v[150:151], s[40:41]
	v_pk_fma_f32 v[112:113], v[6:7], v[108:109], v[112:113] op_sel_hi:[0,1,1]
	v_pk_fma_f32 v[150:151], v[150:151], s[38:39], v[190:191] op_sel:[0,0,1] op_sel_hi:[1,0,0]
	v_pk_add_f32 v[190:191], v[160:161], v[168:169]
	v_pk_add_f32 v[168:169], v[160:161], v[168:169] neg_lo:[0,1] neg_hi:[0,1]
	v_pk_mul_f32 v[116:117], v[14:15], v[108:109] op_sel:[0,1] op_sel_hi:[1,0]
	v_pk_add_f32 v[160:161], v[162:163], v[170:171]
	v_pk_add_f32 v[162:163], v[162:163], v[170:171] neg_lo:[0,1] neg_hi:[0,1]
	v_pk_fma_f32 v[20:21], v[8:9], v[12:13], v[20:21] op_sel_hi:[0,1,1]
	v_pk_mul_f32 v[170:171], v[162:163], s[40:41]
	v_pk_mul_f32 v[24:25], v[12:13], v[22:23] op_sel:[1,0] op_sel_hi:[0,1]
	v_pk_fma_f32 v[162:163], v[162:163], s[38:39], v[170:171] op_sel:[0,0,1] op_sel_hi:[1,0,0] neg_lo:[1,0,0] neg_hi:[1,0,0]
	v_pk_add_f32 v[170:171], v[128:129], v[166:167] op_sel:[0,1] op_sel_hi:[1,0] neg_hi:[0,1]
	v_pk_add_f32 v[128:129], v[128:129], v[166:167] op_sel:[0,1] op_sel_hi:[1,0] neg_lo:[0,1]
	v_pk_add_f32 v[166:167], v[130:131], v[152:153]
	v_pk_add_f32 v[130:131], v[130:131], v[152:153] neg_lo:[0,1] neg_hi:[0,1]
	v_pk_fma_f32 v[36:37], v[8:9], v[28:29], v[36:37] op_sel_hi:[0,1,1]
	v_pk_mul_f32 v[152:153], v[130:131], s[40:41]
	v_pk_mul_f32 v[40:41], v[22:23], v[28:29] op_sel:[0,1] op_sel_hi:[1,0]
	v_pk_fma_f32 v[130:131], v[130:131], s[38:39], v[152:153] op_sel:[0,0,1] op_sel_hi:[1,0,0]
	v_pk_add_f32 v[152:153], v[144:145], v[154:155]
	v_pk_add_f32 v[154:155], v[144:145], v[154:155] neg_lo:[0,1] neg_hi:[0,1]
	v_pk_fma_f32 v[52:53], v[8:9], v[44:45], v[52:53] op_sel_hi:[0,1,1]
	v_pk_add_f32 v[144:145], v[148:149], v[156:157]
	v_pk_add_f32 v[148:149], v[148:149], v[156:157] neg_lo:[0,1] neg_hi:[0,1]
	v_pk_mul_f32 v[56:57], v[22:23], v[44:45] op_sel:[0,1] op_sel_hi:[1,0]
	v_pk_mul_f32 v[156:157], v[148:149], s[40:41]
	v_pk_fma_f32 v[68:69], v[8:9], v[60:61], v[68:69] op_sel_hi:[0,1,1]
	v_pk_fma_f32 v[148:149], v[148:149], s[38:39], v[156:157] op_sel:[0,0,1] op_sel_hi:[1,0,0] neg_lo:[1,0,0] neg_hi:[1,0,0]
	v_pk_add_f32 v[156:157], v[172:173], v[210:211]
	v_pk_add_f32 v[172:173], v[172:173], v[210:211] neg_lo:[0,1] neg_hi:[0,1]
	v_pk_add_f32 v[210:211], v[208:209], v[174:175]
	v_pk_add_f32 v[208:209], v[208:209], v[174:175] neg_lo:[0,1] neg_hi:[0,1]
	v_pk_mul_f32 v[72:73], v[22:23], v[60:61] op_sel:[0,1] op_sel_hi:[1,0]
	v_pk_add_f32 v[174:175], v[194:195], v[198:199] op_sel:[0,1] op_sel_hi:[1,0] neg_hi:[0,1]
	v_pk_add_f32 v[194:195], v[194:195], v[198:199] op_sel:[0,1] op_sel_hi:[1,0] neg_lo:[0,1]
	v_pk_add_f32 v[198:199], v[180:181], v[192:193]
	v_pk_add_f32 v[192:193], v[180:181], v[192:193] neg_lo:[0,1] neg_hi:[0,1]
	v_pk_fma_f32 v[84:85], v[8:9], v[76:77], v[84:85] op_sel_hi:[0,1,1]
	v_pk_add_f32 v[180:181], v[204:205], v[182:183]
	v_pk_add_f32 v[182:183], v[204:205], v[182:183] neg_lo:[0,1] neg_hi:[0,1]
	v_pk_add_f32 v[204:205], v[196:197], v[176:177]
	v_pk_add_f32 v[196:197], v[196:197], v[176:177] neg_lo:[0,1] neg_hi:[0,1]
	v_pk_mul_f32 v[88:89], v[22:23], v[76:77] op_sel:[0,1] op_sel_hi:[1,0]
	v_pk_add_f32 v[176:177], v[188:189], v[184:185] op_sel:[0,1] op_sel_hi:[1,0] neg_hi:[0,1]
	v_pk_add_f32 v[184:185], v[188:189], v[184:185] op_sel:[0,1] op_sel_hi:[1,0] neg_lo:[0,1]
	v_pk_add_f32 v[188:189], v[158:159], v[178:179]
	v_pk_add_f32 v[178:179], v[158:159], v[178:179] neg_lo:[0,1] neg_hi:[0,1]
	v_pk_fma_f32 v[100:101], v[8:9], v[92:93], v[100:101] op_sel_hi:[0,1,1]
	v_pk_add_f32 v[158:159], v[186:187], v[190:191]
	v_pk_add_f32 v[186:187], v[186:187], v[190:191] neg_lo:[0,1] neg_hi:[0,1]
	v_pk_add_f32 v[190:191], v[206:207], v[160:161]
	v_pk_add_f32 v[206:207], v[206:207], v[160:161] neg_lo:[0,1] neg_hi:[0,1]
	v_pk_mul_f32 v[104:105], v[22:23], v[92:93] op_sel:[0,1] op_sel_hi:[1,0]
	v_pk_add_f32 v[160:161], v[164:165], v[168:169] op_sel:[0,1] op_sel_hi:[1,0] neg_hi:[0,1]
	v_pk_add_f32 v[164:165], v[164:165], v[168:169] op_sel:[0,1] op_sel_hi:[1,0] neg_lo:[0,1]
	v_pk_add_f32 v[168:169], v[150:151], v[162:163]
	v_pk_add_f32 v[162:163], v[150:151], v[162:163] neg_lo:[0,1] neg_hi:[0,1]
	v_pk_fma_f32 v[116:117], v[8:9], v[108:109], v[116:117] op_sel_hi:[0,1,1]
	v_pk_add_f32 v[150:151], v[170:171], v[152:153]
	v_pk_add_f32 v[152:153], v[170:171], v[152:153] neg_lo:[0,1] neg_hi:[0,1]
	v_pk_add_f32 v[170:171], v[166:167], v[144:145]
	v_pk_add_f32 v[166:167], v[166:167], v[144:145] neg_lo:[0,1] neg_hi:[0,1]
	v_pk_mul_f32 v[120:121], v[22:23], v[108:109] op_sel:[0,1] op_sel_hi:[1,0]
	v_pk_add_f32 v[144:145], v[128:129], v[154:155] op_sel:[0,1] op_sel_hi:[1,0] neg_hi:[0,1]
	v_pk_add_f32 v[128:129], v[128:129], v[154:155] op_sel:[0,1] op_sel_hi:[1,0] neg_lo:[0,1]
	v_pk_add_f32 v[154:155], v[130:131], v[148:149]
	v_pk_add_f32 v[148:149], v[130:131], v[148:149] neg_lo:[0,1] neg_hi:[0,1]
	v_xor_b32_e32 v26, 0x80000000, v19
	v_pk_add_f32 v[130:131], v[156:157], v[210:211]
	v_pk_add_f32 v[156:157], v[156:157], v[210:211] neg_lo:[0,1] neg_hi:[0,1]
	v_pk_add_f32 v[210:211], v[172:173], v[208:209] op_sel:[0,1] op_sel_hi:[1,0] neg_hi:[0,1]
	v_pk_add_f32 v[172:173], v[172:173], v[208:209] op_sel:[0,1] op_sel_hi:[1,0] neg_lo:[0,1]
	v_pk_add_f32 v[208:209], v[174:175], v[198:199]
	v_pk_add_f32 v[174:175], v[174:175], v[198:199] neg_lo:[0,1] neg_hi:[0,1]
	v_pk_add_f32 v[198:199], v[194:195], v[192:193] op_sel:[0,1] op_sel_hi:[1,0] neg_hi:[0,1]
	v_pk_add_f32 v[192:193], v[194:195], v[192:193] op_sel:[0,1] op_sel_hi:[1,0] neg_lo:[0,1]
	v_pk_add_f32 v[194:195], v[180:181], v[204:205]
	v_pk_add_f32 v[180:181], v[180:181], v[204:205] neg_lo:[0,1] neg_hi:[0,1]
	v_pk_add_f32 v[204:205], v[182:183], v[196:197] op_sel:[0,1] op_sel_hi:[1,0] neg_hi:[0,1]
	v_pk_add_f32 v[182:183], v[182:183], v[196:197] op_sel:[0,1] op_sel_hi:[1,0] neg_lo:[0,1]
	v_pk_add_f32 v[196:197], v[176:177], v[188:189]
	v_pk_add_f32 v[176:177], v[176:177], v[188:189] neg_lo:[0,1] neg_hi:[0,1]
	v_pk_add_f32 v[188:189], v[184:185], v[178:179] op_sel:[0,1] op_sel_hi:[1,0] neg_hi:[0,1]
	v_pk_add_f32 v[178:179], v[184:185], v[178:179] op_sel:[0,1] op_sel_hi:[1,0] neg_lo:[0,1]
	v_pk_add_f32 v[184:185], v[158:159], v[190:191]
	v_pk_add_f32 v[158:159], v[158:159], v[190:191] neg_lo:[0,1] neg_hi:[0,1]
	v_pk_mul_f32 v[4:5], v[4:5], v[184:185] op_sel:[0,1] op_sel_hi:[1,0]
	v_pk_add_f32 v[190:191], v[186:187], v[206:207] op_sel:[0,1] op_sel_hi:[1,0] neg_hi:[0,1]
	v_pk_add_f32 v[186:187], v[186:187], v[206:207] op_sel:[0,1] op_sel_hi:[1,0] neg_lo:[0,1]
	v_pk_add_f32 v[206:207], v[160:161], v[168:169]
	v_pk_add_f32 v[160:161], v[160:161], v[168:169] neg_lo:[0,1] neg_hi:[0,1]
	v_pk_add_f32 v[168:169], v[164:165], v[162:163] op_sel:[0,1] op_sel_hi:[1,0] neg_hi:[0,1]
	v_pk_add_f32 v[162:163], v[164:165], v[162:163] op_sel:[0,1] op_sel_hi:[1,0] neg_lo:[0,1]
	v_pk_add_f32 v[164:165], v[150:151], v[170:171]
	v_pk_fma_f32 v[4:5], v[6:7], v[184:185], v[4:5] op_sel_hi:[0,1,1]
	v_pk_mul_f32 v[6:7], v[14:15], v[194:195] op_sel:[0,1] op_sel_hi:[1,0]
	v_xor_b32_e32 v30, 0x80000000, v21
	v_pk_fma_f32 v[6:7], v[8:9], v[194:195], v[6:7] op_sel_hi:[0,1,1]
	v_pk_mul_f32 v[8:9], v[22:23], v[164:165] op_sel:[0,1] op_sel_hi:[1,0]
	v_pk_fma_f32 v[24:25], v[12:13], v[10:11], v[24:25] op_sel_hi:[1,0,1]
	v_pk_fma_f32 v[40:41], v[10:11], v[28:29], v[40:41] op_sel_hi:[0,1,1]
	v_pk_fma_f32 v[56:57], v[10:11], v[44:45], v[56:57] op_sel_hi:[0,1,1]
	v_pk_fma_f32 v[72:73], v[10:11], v[60:61], v[72:73] op_sel_hi:[0,1,1]
	v_pk_fma_f32 v[88:89], v[10:11], v[76:77], v[88:89] op_sel_hi:[0,1,1]
	v_pk_fma_f32 v[104:105], v[10:11], v[92:93], v[104:105] op_sel_hi:[0,1,1]
	v_pk_fma_f32 v[120:121], v[10:11], v[108:109], v[120:121] op_sel_hi:[0,1,1]
	v_mov_b32_e32 v27, v19
	v_mov_b32_e32 v31, v21
	v_pk_fma_f32 v[8:9], v[10:11], v[164:165], v[8:9] op_sel_hi:[0,1,1]
	v_pk_mul_f32 v[10:11], v[16:17], v[208:209] op_sel:[0,1] op_sel_hi:[1,0]
	v_xor_b32_e32 v34, 0x80000000, v25
	v_xor_b32_e32 v38, 0x80000000, v29
	v_xor_b32_e32 v42, 0x80000000, v33
	v_xor_b32_e32 v46, 0x80000000, v37
	v_mov_b32_e32 v35, v25
	v_mov_b32_e32 v39, v29
	v_mov_b32_e32 v43, v33
	v_mov_b32_e32 v47, v37
	v_pk_add_f32 v[150:151], v[150:151], v[170:171] neg_lo:[0,1] neg_hi:[0,1]
	v_pk_add_f32 v[170:171], v[152:153], v[166:167] op_sel:[0,1] op_sel_hi:[1,0] neg_hi:[0,1]
	v_pk_add_f32 v[152:153], v[152:153], v[166:167] op_sel:[0,1] op_sel_hi:[1,0] neg_lo:[0,1]
	v_pk_add_f32 v[166:167], v[144:145], v[154:155]
	v_pk_fma_f32 v[10:11], v[12:13], v[208:209], v[10:11] op_sel_hi:[0,1,1]
	v_pk_mul_f32 v[12:13], v[26:27], v[206:207] op_sel:[0,1] op_sel_hi:[1,0]
	v_pk_mul_f32 v[14:15], v[30:31], v[196:197] op_sel:[0,1] op_sel_hi:[1,0]
	v_xor_b32_e32 v50, 0x80000000, v41
	v_xor_b32_e32 v54, 0x80000000, v45
	v_xor_b32_e32 v58, 0x80000000, v49
	v_xor_b32_e32 v62, 0x80000000, v53
	v_xor_b32_e32 v66, 0x80000000, v57
	v_xor_b32_e32 v70, 0x80000000, v61
	v_xor_b32_e32 v74, 0x80000000, v65
	v_mov_b32_e32 v51, v41
	v_mov_b32_e32 v55, v45
	v_mov_b32_e32 v59, v49
	v_mov_b32_e32 v63, v53
	v_mov_b32_e32 v67, v57
	v_mov_b32_e32 v71, v61
	v_mov_b32_e32 v75, v65
	v_pk_add_f32 v[144:145], v[144:145], v[154:155] neg_lo:[0,1] neg_hi:[0,1]
	v_pk_add_f32 v[154:155], v[128:129], v[148:149] op_sel:[0,1] op_sel_hi:[1,0] neg_hi:[0,1]
	v_pk_fma_f32 v[12:13], v[18:19], v[206:207], v[12:13] op_sel_hi:[0,1,1]
	v_pk_fma_f32 v[14:15], v[20:21], v[196:197], v[14:15] op_sel_hi:[0,1,1]
	v_pk_mul_f32 v[16:17], v[34:35], v[166:167] op_sel:[0,1] op_sel_hi:[1,0]
	v_pk_mul_f32 v[18:19], v[38:39], v[210:211] op_sel:[0,1] op_sel_hi:[1,0]
	v_pk_mul_f32 v[20:21], v[42:43], v[190:191] op_sel:[0,1] op_sel_hi:[1,0]
	v_pk_mul_f32 v[22:23], v[46:47], v[204:205] op_sel:[0,1] op_sel_hi:[1,0]
	v_xor_b32_e32 v78, 0x80000000, v69
	v_xor_b32_e32 v82, 0x80000000, v73
	v_xor_b32_e32 v86, 0x80000000, v77
	v_xor_b32_e32 v90, 0x80000000, v81
	v_xor_b32_e32 v94, 0x80000000, v85
	v_xor_b32_e32 v98, 0x80000000, v89
	v_xor_b32_e32 v102, 0x80000000, v93
	v_xor_b32_e32 v106, 0x80000000, v97
	v_xor_b32_e32 v110, 0x80000000, v101
	v_xor_b32_e32 v114, 0x80000000, v105
	v_xor_b32_e32 v118, 0x80000000, v109
	v_xor_b32_e32 v122, 0x80000000, v113
	v_xor_b32_e32 v124, 0x80000000, v117
	v_xor_b32_e32 v126, 0x80000000, v121
	v_mov_b32_e32 v79, v69
	v_mov_b32_e32 v83, v73
	v_mov_b32_e32 v87, v77
	v_mov_b32_e32 v91, v81
	v_mov_b32_e32 v95, v85
	v_mov_b32_e32 v99, v89
	v_mov_b32_e32 v103, v93
	v_mov_b32_e32 v107, v97
	v_mov_b32_e32 v111, v101
	v_mov_b32_e32 v115, v105
	v_mov_b32_e32 v119, v109
	v_mov_b32_e32 v123, v113
	v_mov_b32_e32 v125, v117
	v_mov_b32_e32 v127, v121
	v_pk_add_f32 v[128:129], v[128:129], v[148:149] op_sel:[0,1] op_sel_hi:[1,0] neg_lo:[0,1]
	v_pk_fma_f32 v[16:17], v[24:25], v[166:167], v[16:17] op_sel_hi:[0,1,1]
	v_pk_fma_f32 v[18:19], v[28:29], v[210:211], v[18:19] op_sel_hi:[0,1,1]
	v_pk_fma_f32 v[20:21], v[32:33], v[190:191], v[20:21] op_sel_hi:[0,1,1]
	v_pk_fma_f32 v[22:23], v[36:37], v[204:205], v[22:23] op_sel_hi:[0,1,1]
	v_pk_mul_f32 v[24:25], v[50:51], v[170:171] op_sel:[0,1] op_sel_hi:[1,0]
	v_pk_mul_f32 v[26:27], v[54:55], v[198:199] op_sel:[0,1] op_sel_hi:[1,0]
	v_pk_mul_f32 v[28:29], v[58:59], v[168:169] op_sel:[0,1] op_sel_hi:[1,0]
	v_pk_mul_f32 v[30:31], v[62:63], v[188:189] op_sel:[0,1] op_sel_hi:[1,0]
	v_pk_mul_f32 v[32:33], v[66:67], v[154:155] op_sel:[0,1] op_sel_hi:[1,0]
	v_pk_mul_f32 v[34:35], v[70:71], v[156:157] op_sel:[0,1] op_sel_hi:[1,0]
	v_pk_mul_f32 v[36:37], v[74:75], v[158:159] op_sel:[0,1] op_sel_hi:[1,0]
	v_pk_fma_f32 v[24:25], v[40:41], v[170:171], v[24:25] op_sel_hi:[0,1,1]
	v_pk_fma_f32 v[26:27], v[44:45], v[198:199], v[26:27] op_sel_hi:[0,1,1]
	v_pk_fma_f32 v[28:29], v[48:49], v[168:169], v[28:29] op_sel_hi:[0,1,1]
	v_pk_fma_f32 v[30:31], v[52:53], v[188:189], v[30:31] op_sel_hi:[0,1,1]
	v_pk_fma_f32 v[32:33], v[56:57], v[154:155], v[32:33] op_sel_hi:[0,1,1]
	v_pk_fma_f32 v[34:35], v[60:61], v[156:157], v[34:35] op_sel_hi:[0,1,1]
	v_pk_fma_f32 v[36:37], v[64:65], v[158:159], v[36:37] op_sel_hi:[0,1,1]
	v_pk_mul_f32 v[38:39], v[78:79], v[180:181] op_sel:[0,1] op_sel_hi:[1,0]
	v_pk_mul_f32 v[40:41], v[82:83], v[150:151] op_sel:[0,1] op_sel_hi:[1,0]
	v_pk_mul_f32 v[42:43], v[86:87], v[174:175] op_sel:[0,1] op_sel_hi:[1,0]
	v_pk_mul_f32 v[44:45], v[90:91], v[160:161] op_sel:[0,1] op_sel_hi:[1,0]
	v_pk_mul_f32 v[46:47], v[94:95], v[176:177] op_sel:[0,1] op_sel_hi:[1,0]
	v_pk_mul_f32 v[48:49], v[98:99], v[144:145] op_sel:[0,1] op_sel_hi:[1,0]
	v_pk_mul_f32 v[50:51], v[102:103], v[172:173] op_sel:[0,1] op_sel_hi:[1,0]
	v_pk_mul_f32 v[52:53], v[106:107], v[186:187] op_sel:[0,1] op_sel_hi:[1,0]
	v_pk_mul_f32 v[54:55], v[110:111], v[182:183] op_sel:[0,1] op_sel_hi:[1,0]
	v_pk_mul_f32 v[56:57], v[114:115], v[152:153] op_sel:[0,1] op_sel_hi:[1,0]
	v_pk_mul_f32 v[58:59], v[118:119], v[192:193] op_sel:[0,1] op_sel_hi:[1,0]
	v_pk_mul_f32 v[60:61], v[122:123], v[162:163] op_sel:[0,1] op_sel_hi:[1,0]
	v_pk_mul_f32 v[62:63], v[124:125], v[178:179] op_sel:[0,1] op_sel_hi:[1,0]
	v_pk_mul_f32 v[64:65], v[126:127], v[128:129] op_sel:[0,1] op_sel_hi:[1,0]
	v_pk_fma_f32 v[38:39], v[68:69], v[180:181], v[38:39] op_sel_hi:[0,1,1]
	v_pk_fma_f32 v[40:41], v[72:73], v[150:151], v[40:41] op_sel_hi:[0,1,1]
	v_pk_fma_f32 v[42:43], v[76:77], v[174:175], v[42:43] op_sel_hi:[0,1,1]
	v_pk_fma_f32 v[44:45], v[80:81], v[160:161], v[44:45] op_sel_hi:[0,1,1]
	v_pk_fma_f32 v[46:47], v[84:85], v[176:177], v[46:47] op_sel_hi:[0,1,1]
	v_pk_fma_f32 v[48:49], v[88:89], v[144:145], v[48:49] op_sel_hi:[0,1,1]
	v_pk_fma_f32 v[50:51], v[92:93], v[172:173], v[50:51] op_sel_hi:[0,1,1]
	v_pk_fma_f32 v[52:53], v[96:97], v[186:187], v[52:53] op_sel_hi:[0,1,1]
	v_pk_fma_f32 v[54:55], v[100:101], v[182:183], v[54:55] op_sel_hi:[0,1,1]
	v_pk_fma_f32 v[56:57], v[104:105], v[152:153], v[56:57] op_sel_hi:[0,1,1]
	v_pk_fma_f32 v[58:59], v[108:109], v[192:193], v[58:59] op_sel_hi:[0,1,1]
	v_pk_fma_f32 v[60:61], v[112:113], v[162:163], v[60:61] op_sel_hi:[0,1,1]
	v_pk_fma_f32 v[62:63], v[116:117], v[178:179], v[62:63] op_sel_hi:[0,1,1]
	v_pk_fma_f32 v[64:65], v[120:121], v[128:129], v[64:65] op_sel_hi:[0,1,1]
	ds_write_b64 v2, v[130:131]
	ds_write_b64 v2, v[34:35] offset:4224
	ds_write_b64 v2, v[18:19] offset:8448
	ds_write_b64 v2, v[50:51] offset:12672
	ds_write_b64 v2, v[10:11] offset:16896
	ds_write_b64 v2, v[42:43] offset:21120
	ds_write_b64 v2, v[26:27] offset:25344
	ds_write_b64 v2, v[58:59] offset:29568
	ds_write_b64 v2, v[6:7] offset:33792
	ds_write_b64 v2, v[38:39] offset:38016
	ds_write_b64 v2, v[22:23] offset:42240
	ds_write_b64 v2, v[54:55] offset:46464
	ds_write_b64 v2, v[14:15] offset:50688
	ds_write_b64 v2, v[46:47] offset:54912
	ds_write_b64 v2, v[30:31] offset:59136
	ds_write_b64 v2, v[62:63] offset:63360
	ds_write_b64 v143, v[4:5]
	ds_write_b64 v212, v[36:37]
	ds_write_b64 v213, v[20:21]
	ds_write_b64 v214, v[52:53]
	ds_write_b64 v215, v[12:13]
	ds_write_b64 v216, v[44:45]
	ds_write_b64 v217, v[28:29]
	ds_write_b64 v218, v[60:61]
	ds_write_b64 v219, v[8:9]
	ds_write_b64 v220, v[40:41]
	ds_write_b64 v221, v[24:25]
	ds_write_b64 v222, v[56:57]
	ds_write_b64 v223, v[16:17]
	ds_write_b64 v224, v[48:49]
	ds_write_b64 v225, v[32:33]
	ds_write_b64 v226, v[64:65]
	v_mov_b32_e32 v2, v142
	s_waitcnt lgkmcnt(0)
	s_barrier
	s_nop 0
	v_and_b32_e32 v4, 15, v2
	v_lshlrev_b32_e32 v2, 5, v2
	v_and_b32_e32 v2, 0xfffffe00, v2
	v_lshl_add_u32 v5, v2, 3, 0
	v_lshlrev_b32_e32 v7, 3, v4
	v_ashrrev_i32_e32 v2, 2, v2
	v_add3_u32 v2, v5, v7, v2
	v_add_u32_e32 v143, 0x800, v2
	ds_read2_b64 v[128:131], v2 offset1:16
	ds_read2_b64 v[148:151], v2 offset0:33 offset1:49
	ds_read2_b64 v[152:155], v2 offset0:66 offset1:82
	ds_read2_b64 v[156:159], v2 offset0:99 offset1:115
	ds_read2_b64 v[160:163], v2 offset0:132 offset1:148
	ds_read2_b64 v[164:167], v2 offset0:165 offset1:181
	ds_read2_b64 v[168:171], v2 offset0:198 offset1:214
	ds_read2_b64 v[172:175], v2 offset0:231 offset1:247
	ds_read2_b64 v[176:179], v143 offset0:8 offset1:24
	ds_read2_b64 v[180:183], v143 offset0:41 offset1:57
	ds_read2_b64 v[184:187], v143 offset0:74 offset1:90
	ds_read2_b64 v[188:191], v143 offset0:107 offset1:123
	ds_read2_b64 v[192:195], v143 offset0:140 offset1:156
	ds_read2_b64 v[196:199], v143 offset0:173 offset1:189
	ds_read2_b64 v[204:207], v143 offset0:206 offset1:222
	ds_read2_b64 v[208:211], v143 offset0:239 offset1:255
	s_waitcnt lgkmcnt(7)
	v_pk_add_f32 v[144:145], v[128:129], v[176:177]
	v_pk_add_f32 v[128:129], v[128:129], v[176:177] neg_lo:[0,1] neg_hi:[0,1]
	v_pk_add_f32 v[176:177], v[130:131], v[178:179]
	v_pk_add_f32 v[130:131], v[130:131], v[178:179] neg_lo:[0,1] neg_hi:[0,1]
	v_cvt_f32_ubyte0_e32 v4, v4
	v_pk_mul_f32 v[178:179], v[130:131], s[20:21]
	v_mul_f32_e32 v6, 0x3b000000, v4
	v_pk_fma_f32 v[130:131], v[130:131], s[10:11], v[178:179] op_sel:[0,0,1] op_sel_hi:[1,0,0]
	s_waitcnt lgkmcnt(6)
	v_pk_add_f32 v[178:179], v[148:149], v[180:181]
	v_pk_add_f32 v[148:149], v[148:149], v[180:181] neg_lo:[0,1] neg_hi:[0,1]
	v_sin_f32_e32 v4, v6
	v_pk_mul_f32 v[180:181], v[148:149], s[24:25]
	v_cos_f32_e32 v6, v6
	v_pk_fma_f32 v[148:149], v[148:149], s[22:23], v[180:181] op_sel:[0,0,1] op_sel_hi:[1,0,0]
	v_pk_add_f32 v[180:181], v[150:151], v[182:183]
	v_pk_add_f32 v[150:151], v[150:151], v[182:183] neg_lo:[0,1] neg_hi:[0,1]
	v_xor_b32_e32 v7, 0x80000000, v4
	v_pk_mul_f32 v[182:183], v[150:151], s[36:37]
	v_mov_b32_e32 v5, v7
	v_pk_fma_f32 v[150:151], v[150:151], s[26:27], v[182:183] op_sel:[0,0,1] op_sel_hi:[1,0,0]
	s_waitcnt lgkmcnt(5)
	v_pk_add_f32 v[182:183], v[152:153], v[184:185]
	v_pk_add_f32 v[152:153], v[152:153], v[184:185] neg_lo:[0,1] neg_hi:[0,1]
	v_pk_mul_f32 v[8:9], v[6:7], v[4:5] op_sel:[1,0] op_sel_hi:[0,1]
	v_pk_mul_f32 v[184:185], v[152:153], s[40:41]
	v_pk_fma_f32 v[8:9], v[6:7], v[6:7], v[8:9] op_sel_hi:[1,0,1]
	v_pk_fma_f32 v[152:153], v[152:153], s[38:39], v[184:185] op_sel:[0,0,1] op_sel_hi:[1,0,0]
	v_pk_add_f32 v[184:185], v[154:155], v[186:187]
	v_pk_add_f32 v[154:155], v[154:155], v[186:187] neg_lo:[0,1] neg_hi:[0,1]
	v_xor_b32_e32 v14, 0x80000000, v9
	v_pk_mul_f32 v[186:187], v[154:155], s[42:43]
	v_mov_b32_e32 v15, v9
	v_pk_fma_f32 v[154:155], v[154:155], s[0:1], v[186:187] op_sel:[0,0,1] op_sel_hi:[1,0,0]
	s_waitcnt lgkmcnt(4)
	v_pk_add_f32 v[186:187], v[156:157], v[188:189]
	v_pk_add_f32 v[156:157], v[156:157], v[188:189] neg_lo:[0,1] neg_hi:[0,1]
	v_pk_mul_f32 v[12:13], v[8:9], v[14:15] op_sel:[1,0] op_sel_hi:[0,1]
	v_pk_mul_f32 v[188:189], v[156:157], s[44:45]
	v_pk_fma_f32 v[12:13], v[8:9], v[8:9], v[12:13] op_sel_hi:[1,0,1]
	v_pk_fma_f32 v[156:157], v[156:157], s[50:51], v[188:189] op_sel:[0,0,1] op_sel_hi:[1,0,0]
	v_pk_add_f32 v[188:189], v[158:159], v[190:191]
	v_pk_add_f32 v[158:159], v[158:159], v[190:191] neg_lo:[0,1] neg_hi:[0,1]
	v_xor_b32_e32 v16, 0x80000000, v13
	v_pk_mul_f32 v[190:191], v[158:159], s[8:9]
	v_mov_b32_e32 v17, v13
	v_pk_fma_f32 v[158:159], v[158:159], s[16:17], v[190:191] op_sel:[0,0,1] op_sel_hi:[1,0,0]
	s_waitcnt lgkmcnt(3)
	v_pk_add_f32 v[190:191], v[160:161], v[192:193]
	v_pk_add_f32 v[192:193], v[160:161], v[192:193] neg_lo:[0,1] neg_hi:[0,1]
	v_pk_mul_f32 v[28:29], v[12:13], v[16:17] op_sel:[1,0] op_sel_hi:[0,1]
	v_pk_add_f32 v[160:161], v[162:163], v[194:195]
	v_pk_add_f32 v[162:163], v[162:163], v[194:195] neg_lo:[0,1] neg_hi:[0,1]
	v_pk_fma_f32 v[28:29], v[12:13], v[12:13], v[28:29] op_sel_hi:[1,0,1]
	v_pk_mul_f32 v[194:195], v[162:163], s[8:9]
	v_pk_mul_f32 v[44:45], v[16:17], v[28:29] op_sel:[0,1] op_sel_hi:[1,0]
	v_pk_fma_f32 v[162:163], v[162:163], s[16:17], v[194:195] op_sel:[0,0,1] op_sel_hi:[1,0,0] neg_lo:[1,0,0] neg_hi:[1,0,0]
	s_waitcnt lgkmcnt(2)
	v_pk_add_f32 v[194:195], v[164:165], v[196:197]
	v_pk_add_f32 v[164:165], v[164:165], v[196:197] neg_lo:[0,1] neg_hi:[0,1]
	v_pk_fma_f32 v[44:45], v[12:13], v[28:29], v[44:45] op_sel_hi:[0,1,1]
	v_pk_mul_f32 v[196:197], v[164:165], s[44:45]
	v_pk_mul_f32 v[60:61], v[16:17], v[44:45] op_sel:[0,1] op_sel_hi:[1,0]
	v_pk_fma_f32 v[164:165], v[164:165], s[50:51], v[196:197] op_sel:[0,0,1] op_sel_hi:[1,0,0] neg_lo:[1,0,0] neg_hi:[1,0,0]
	v_pk_add_f32 v[196:197], v[166:167], v[198:199]
	v_pk_add_f32 v[166:167], v[166:167], v[198:199] neg_lo:[0,1] neg_hi:[0,1]
	v_pk_fma_f32 v[60:61], v[12:13], v[44:45], v[60:61] op_sel_hi:[0,1,1]
	v_pk_mul_f32 v[198:199], v[166:167], s[42:43]
	v_pk_mul_f32 v[76:77], v[16:17], v[60:61] op_sel:[0,1] op_sel_hi:[1,0]
	v_pk_fma_f32 v[166:167], v[166:167], s[0:1], v[198:199] op_sel:[0,0,1] op_sel_hi:[1,0,0] neg_lo:[1,0,0] neg_hi:[1,0,0]
	s_waitcnt lgkmcnt(1)
	v_pk_add_f32 v[198:199], v[168:169], v[204:205]
	v_pk_add_f32 v[168:169], v[168:169], v[204:205] neg_lo:[0,1] neg_hi:[0,1]
	v_pk_fma_f32 v[76:77], v[12:13], v[60:61], v[76:77] op_sel_hi:[0,1,1]
	v_pk_mul_f32 v[204:205], v[168:169], s[40:41]
	v_pk_mul_f32 v[92:93], v[16:17], v[76:77] op_sel:[0,1] op_sel_hi:[1,0]
	v_pk_fma_f32 v[168:169], v[168:169], s[38:39], v[204:205] op_sel:[0,0,1] op_sel_hi:[1,0,0] neg_lo:[1,0,0] neg_hi:[1,0,0]
	v_pk_add_f32 v[204:205], v[170:171], v[206:207]
	v_pk_add_f32 v[170:171], v[170:171], v[206:207] neg_lo:[0,1] neg_hi:[0,1]
	v_pk_fma_f32 v[92:93], v[12:13], v[76:77], v[92:93] op_sel_hi:[0,1,1]
	v_pk_mul_f32 v[206:207], v[170:171], s[36:37]
	v_pk_mul_f32 v[108:109], v[16:17], v[92:93] op_sel:[0,1] op_sel_hi:[1,0]
	v_pk_fma_f32 v[170:171], v[170:171], s[26:27], v[206:207] op_sel:[0,0,1] op_sel_hi:[1,0,0] neg_lo:[1,0,0] neg_hi:[1,0,0]
	s_waitcnt lgkmcnt(0)
	v_pk_add_f32 v[206:207], v[172:173], v[208:209]
	v_pk_add_f32 v[172:173], v[172:173], v[208:209] neg_lo:[0,1] neg_hi:[0,1]
	v_pk_mul_f32 v[10:11], v[4:5], v[8:9] op_sel:[0,1] op_sel_hi:[1,0]
	v_pk_mul_f32 v[208:209], v[172:173], s[24:25]
	v_pk_fma_f32 v[108:109], v[12:13], v[92:93], v[108:109] op_sel_hi:[0,1,1]
	v_pk_fma_f32 v[172:173], v[172:173], s[22:23], v[208:209] op_sel:[0,0,1] op_sel_hi:[1,0,0] neg_lo:[1,0,0] neg_hi:[1,0,0]
	v_pk_add_f32 v[208:209], v[174:175], v[210:211]
	v_pk_add_f32 v[174:175], v[174:175], v[210:211] neg_lo:[0,1] neg_hi:[0,1]
	v_pk_fma_f32 v[10:11], v[6:7], v[8:9], v[10:11] op_sel_hi:[0,1,1]
	v_pk_mul_f32 v[210:211], v[174:175], s[20:21]
	v_pk_mul_f32 v[18:19], v[4:5], v[12:13] op_sel:[0,1] op_sel_hi:[1,0]
	v_pk_fma_f32 v[174:175], v[174:175], s[10:11], v[210:211] op_sel:[0,0,1] op_sel_hi:[1,0,0] neg_lo:[1,0,0] neg_hi:[1,0,0]
	v_pk_add_f32 v[210:211], v[144:145], v[190:191]
	v_pk_add_f32 v[144:145], v[144:145], v[190:191] neg_lo:[0,1] neg_hi:[0,1]
	v_pk_add_f32 v[190:191], v[176:177], v[160:161]
	v_pk_add_f32 v[160:161], v[176:177], v[160:161] neg_lo:[0,1] neg_hi:[0,1]
	v_pk_mul_f32 v[32:33], v[4:5], v[28:29] op_sel:[0,1] op_sel_hi:[1,0]
	v_pk_mul_f32 v[176:177], v[160:161], s[24:25]
	v_pk_mul_f32 v[48:49], v[4:5], v[44:45] op_sel:[0,1] op_sel_hi:[1,0]
	v_pk_fma_f32 v[160:161], v[160:161], s[22:23], v[176:177] op_sel:[0,0,1] op_sel_hi:[1,0,0]
	v_pk_add_f32 v[176:177], v[178:179], v[194:195]
	v_pk_add_f32 v[178:179], v[178:179], v[194:195] neg_lo:[0,1] neg_hi:[0,1]
	v_pk_mul_f32 v[64:65], v[4:5], v[60:61] op_sel:[0,1] op_sel_hi:[1,0]
	v_pk_mul_f32 v[194:195], v[178:179], s[40:41]
	v_pk_mul_f32 v[80:81], v[4:5], v[76:77] op_sel:[0,1] op_sel_hi:[1,0]
	v_pk_fma_f32 v[178:179], v[178:179], s[38:39], v[194:195] op_sel:[0,0,1] op_sel_hi:[1,0,0]
	v_pk_add_f32 v[194:195], v[180:181], v[196:197]
	v_pk_add_f32 v[180:181], v[180:181], v[196:197] neg_lo:[0,1] neg_hi:[0,1]
	v_pk_mul_f32 v[96:97], v[4:5], v[92:93] op_sel:[0,1] op_sel_hi:[1,0]
	v_pk_mul_f32 v[196:197], v[180:181], s[44:45]
	v_pk_mul_f32 v[112:113], v[4:5], v[108:109] op_sel:[0,1] op_sel_hi:[1,0]
	v_pk_fma_f32 v[180:181], v[180:181], s[50:51], v[196:197] op_sel:[0,0,1] op_sel_hi:[1,0,0]
	v_pk_add_f32 v[196:197], v[182:183], v[198:199]
	v_pk_add_f32 v[198:199], v[182:183], v[198:199] neg_lo:[0,1] neg_hi:[0,1]
	v_xor_b32_e32 v22, 0x80000000, v11
	v_pk_add_f32 v[182:183], v[184:185], v[204:205]
	v_pk_add_f32 v[184:185], v[184:185], v[204:205] neg_lo:[0,1] neg_hi:[0,1]
	v_mov_b32_e32 v23, v11
	v_pk_mul_f32 v[204:205], v[184:185], s[44:45]
	v_pk_fma_f32 v[18:19], v[6:7], v[12:13], v[18:19] op_sel_hi:[0,1,1]
	v_pk_fma_f32 v[184:185], v[184:185], s[50:51], v[204:205] op_sel:[0,0,1] op_sel_hi:[1,0,0] neg_lo:[1,0,0] neg_hi:[1,0,0]
	v_pk_add_f32 v[204:205], v[186:187], v[206:207]
	v_pk_add_f32 v[186:187], v[186:187], v[206:207] neg_lo:[0,1] neg_hi:[0,1]
	v_pk_mul_f32 v[20:21], v[14:15], v[12:13] op_sel:[0,1] op_sel_hi:[1,0]
	v_pk_mul_f32 v[206:207], v[186:187], s[40:41]
	v_pk_fma_f32 v[32:33], v[6:7], v[28:29], v[32:33] op_sel_hi:[0,1,1]
	v_pk_fma_f32 v[186:187], v[186:187], s[38:39], v[206:207] op_sel:[0,0,1] op_sel_hi:[1,0,0] neg_lo:[1,0,0] neg_hi:[1,0,0]
	v_pk_add_f32 v[206:207], v[188:189], v[208:209]
	v_pk_add_f32 v[188:189], v[188:189], v[208:209] neg_lo:[0,1] neg_hi:[0,1]
	v_pk_mul_f32 v[36:37], v[14:15], v[28:29] op_sel:[0,1] op_sel_hi:[1,0]
	v_pk_mul_f32 v[208:209], v[188:189], s[24:25]
	v_pk_fma_f32 v[48:49], v[6:7], v[44:45], v[48:49] op_sel_hi:[0,1,1]
	v_pk_fma_f32 v[188:189], v[188:189], s[22:23], v[208:209] op_sel:[0,0,1] op_sel_hi:[1,0,0] neg_lo:[1,0,0] neg_hi:[1,0,0]
	v_pk_add_f32 v[208:209], v[128:129], v[192:193] op_sel:[0,1] op_sel_hi:[1,0] neg_hi:[0,1]
	v_pk_add_f32 v[128:129], v[128:129], v[192:193] op_sel:[0,1] op_sel_hi:[1,0] neg_lo:[0,1]
	v_pk_add_f32 v[192:193], v[130:131], v[162:163]
	v_pk_add_f32 v[130:131], v[130:131], v[162:163] neg_lo:[0,1] neg_hi:[0,1]
	v_pk_mul_f32 v[52:53], v[14:15], v[44:45] op_sel:[0,1] op_sel_hi:[1,0]
	v_pk_mul_f32 v[162:163], v[130:131], s[24:25]
	v_pk_fma_f32 v[64:65], v[6:7], v[60:61], v[64:65] op_sel_hi:[0,1,1]
	v_pk_fma_f32 v[130:131], v[130:131], s[22:23], v[162:163] op_sel:[0,0,1] op_sel_hi:[1,0,0]
	v_pk_add_f32 v[162:163], v[148:149], v[164:165]
	v_pk_add_f32 v[148:149], v[148:149], v[164:165] neg_lo:[0,1] neg_hi:[0,1]
	v_pk_mul_f32 v[68:69], v[14:15], v[60:61] op_sel:[0,1] op_sel_hi:[1,0]
	v_pk_mul_f32 v[164:165], v[148:149], s[40:41]
	v_pk_fma_f32 v[80:81], v[6:7], v[76:77], v[80:81] op_sel_hi:[0,1,1]
	v_pk_fma_f32 v[148:149], v[148:149], s[38:39], v[164:165] op_sel:[0,0,1] op_sel_hi:[1,0,0]
	v_pk_add_f32 v[164:165], v[150:151], v[166:167]
	v_pk_add_f32 v[150:151], v[150:151], v[166:167] neg_lo:[0,1] neg_hi:[0,1]
	v_pk_mul_f32 v[84:85], v[14:15], v[76:77] op_sel:[0,1] op_sel_hi:[1,0]
	v_pk_mul_f32 v[166:167], v[150:151], s[44:45]
	v_pk_fma_f32 v[96:97], v[6:7], v[92:93], v[96:97] op_sel_hi:[0,1,1]
	v_pk_fma_f32 v[150:151], v[150:151], s[50:51], v[166:167] op_sel:[0,0,1] op_sel_hi:[1,0,0]
	v_pk_add_f32 v[166:167], v[152:153], v[168:169]
	v_pk_add_f32 v[168:169], v[152:153], v[168:169] neg_lo:[0,1] neg_hi:[0,1]
	v_pk_mul_f32 v[100:101], v[14:15], v[92:93] op_sel:[0,1] op_sel_hi:[1,0]
	v_pk_add_f32 v[152:153], v[154:155], v[170:171]
	v_pk_add_f32 v[154:155], v[154:155], v[170:171] neg_lo:[0,1] neg_hi:[0,1]
	v_pk_fma_f32 v[112:113], v[6:7], v[108:109], v[112:113] op_sel_hi:[0,1,1]
	v_pk_mul_f32 v[170:171], v[154:155], s[44:45]
	v_pk_mul_f32 v[116:117], v[14:15], v[108:109] op_sel:[0,1] op_sel_hi:[1,0]
	v_pk_fma_f32 v[154:155], v[154:155], s[50:51], v[170:171] op_sel:[0,0,1] op_sel_hi:[1,0,0] neg_lo:[1,0,0] neg_hi:[1,0,0]
	v_pk_add_f32 v[170:171], v[156:157], v[172:173]
	v_pk_add_f32 v[156:157], v[156:157], v[172:173] neg_lo:[0,1] neg_hi:[0,1]
	v_pk_fma_f32 v[20:21], v[8:9], v[12:13], v[20:21] op_sel_hi:[0,1,1]
	v_pk_mul_f32 v[172:173], v[156:157], s[40:41]
	v_pk_mul_f32 v[24:25], v[12:13], v[22:23] op_sel:[1,0] op_sel_hi:[0,1]
	v_pk_fma_f32 v[156:157], v[156:157], s[38:39], v[172:173] op_sel:[0,0,1] op_sel_hi:[1,0,0] neg_lo:[1,0,0] neg_hi:[1,0,0]
	v_pk_add_f32 v[172:173], v[158:159], v[174:175]
	v_pk_add_f32 v[158:159], v[158:159], v[174:175] neg_lo:[0,1] neg_hi:[0,1]
	v_pk_fma_f32 v[36:37], v[8:9], v[28:29], v[36:37] op_sel_hi:[0,1,1]
	v_pk_mul_f32 v[174:175], v[158:159], s[24:25]
	v_pk_mul_f32 v[40:41], v[22:23], v[28:29] op_sel:[0,1] op_sel_hi:[1,0]
	v_pk_fma_f32 v[158:159], v[158:159], s[22:23], v[174:175] op_sel:[0,0,1] op_sel_hi:[1,0,0] neg_lo:[1,0,0] neg_hi:[1,0,0]
	v_pk_add_f32 v[174:175], v[210:211], v[196:197]
	v_pk_add_f32 v[196:197], v[210:211], v[196:197] neg_lo:[0,1] neg_hi:[0,1]
	v_pk_add_f32 v[210:211], v[190:191], v[182:183]
	v_pk_add_f32 v[182:183], v[190:191], v[182:183] neg_lo:[0,1] neg_hi:[0,1]
	v_pk_fma_f32 v[52:53], v[8:9], v[44:45], v[52:53] op_sel_hi:[0,1,1]
	v_pk_mul_f32 v[190:191], v[182:183], s[40:41]
	v_pk_mul_f32 v[56:57], v[22:23], v[44:45] op_sel:[0,1] op_sel_hi:[1,0]
	v_pk_fma_f32 v[182:183], v[182:183], s[38:39], v[190:191] op_sel:[0,0,1] op_sel_hi:[1,0,0]
	v_pk_add_f32 v[190:191], v[176:177], v[204:205]
	v_pk_add_f32 v[204:205], v[176:177], v[204:205] neg_lo:[0,1] neg_hi:[0,1]
	v_pk_fma_f32 v[68:69], v[8:9], v[60:61], v[68:69] op_sel_hi:[0,1,1]
	v_pk_add_f32 v[176:177], v[194:195], v[206:207]
	v_pk_add_f32 v[194:195], v[194:195], v[206:207] neg_lo:[0,1] neg_hi:[0,1]
	v_pk_mul_f32 v[72:73], v[22:23], v[60:61] op_sel:[0,1] op_sel_hi:[1,0]
	v_pk_mul_f32 v[206:207], v[194:195], s[40:41]
	v_pk_fma_f32 v[84:85], v[8:9], v[76:77], v[84:85] op_sel_hi:[0,1,1]
	v_pk_fma_f32 v[194:195], v[194:195], s[38:39], v[206:207] op_sel:[0,0,1] op_sel_hi:[1,0,0] neg_lo:[1,0,0] neg_hi:[1,0,0]
	v_pk_add_f32 v[206:207], v[144:145], v[198:199] op_sel:[0,1] op_sel_hi:[1,0] neg_hi:[0,1]
	v_pk_add_f32 v[144:145], v[144:145], v[198:199] op_sel:[0,1] op_sel_hi:[1,0] neg_lo:[0,1]
	v_pk_add_f32 v[198:199], v[160:161], v[184:185]
	v_pk_add_f32 v[160:161], v[160:161], v[184:185] neg_lo:[0,1] neg_hi:[0,1]
	v_pk_mul_f32 v[88:89], v[22:23], v[76:77] op_sel:[0,1] op_sel_hi:[1,0]
	v_pk_mul_f32 v[184:185], v[160:161], s[40:41]
	v_pk_fma_f32 v[100:101], v[8:9], v[92:93], v[100:101] op_sel_hi:[0,1,1]
	v_pk_fma_f32 v[160:161], v[160:161], s[38:39], v[184:185] op_sel:[0,0,1] op_sel_hi:[1,0,0]
	v_pk_add_f32 v[184:185], v[178:179], v[186:187]
	v_pk_add_f32 v[186:187], v[178:179], v[186:187] neg_lo:[0,1] neg_hi:[0,1]
	v_pk_mul_f32 v[104:105], v[22:23], v[92:93] op_sel:[0,1] op_sel_hi:[1,0]
	v_pk_add_f32 v[178:179], v[180:181], v[188:189]
	v_pk_add_f32 v[180:181], v[180:181], v[188:189] neg_lo:[0,1] neg_hi:[0,1]
	v_pk_fma_f32 v[116:117], v[8:9], v[108:109], v[116:117] op_sel_hi:[0,1,1]
	v_pk_mul_f32 v[188:189], v[180:181], s[40:41]
	v_pk_mul_f32 v[120:121], v[22:23], v[108:109] op_sel:[0,1] op_sel_hi:[1,0]
	v_pk_fma_f32 v[180:181], v[180:181], s[38:39], v[188:189] op_sel:[0,0,1] op_sel_hi:[1,0,0] neg_lo:[1,0,0] neg_hi:[1,0,0]
	v_pk_add_f32 v[188:189], v[208:209], v[166:167]
	v_pk_add_f32 v[166:167], v[208:209], v[166:167] neg_lo:[0,1] neg_hi:[0,1]
	v_pk_add_f32 v[208:209], v[192:193], v[152:153]
	v_pk_add_f32 v[152:153], v[192:193], v[152:153] neg_lo:[0,1] neg_hi:[0,1]
	v_xor_b32_e32 v26, 0x80000000, v19
	v_pk_mul_f32 v[192:193], v[152:153], s[40:41]
	v_xor_b32_e32 v30, 0x80000000, v21
	v_pk_fma_f32 v[152:153], v[152:153], s[38:39], v[192:193] op_sel:[0,0,1] op_sel_hi:[1,0,0]
	v_pk_add_f32 v[192:193], v[162:163], v[170:171]
	v_pk_add_f32 v[170:171], v[162:163], v[170:171] neg_lo:[0,1] neg_hi:[0,1]
	v_pk_fma_f32 v[24:25], v[12:13], v[10:11], v[24:25] op_sel_hi:[1,0,1]
	v_pk_add_f32 v[162:163], v[164:165], v[172:173]
	v_pk_add_f32 v[164:165], v[164:165], v[172:173] neg_lo:[0,1] neg_hi:[0,1]
	v_pk_fma_f32 v[40:41], v[10:11], v[28:29], v[40:41] op_sel_hi:[0,1,1]
	v_pk_mul_f32 v[172:173], v[164:165], s[40:41]
	v_pk_fma_f32 v[56:57], v[10:11], v[44:45], v[56:57] op_sel_hi:[0,1,1]
	v_pk_fma_f32 v[164:165], v[164:165], s[38:39], v[172:173] op_sel:[0,0,1] op_sel_hi:[1,0,0] neg_lo:[1,0,0] neg_hi:[1,0,0]
	v_pk_add_f32 v[172:173], v[128:129], v[168:169] op_sel:[0,1] op_sel_hi:[1,0] neg_hi:[0,1]
	v_pk_add_f32 v[128:129], v[128:129], v[168:169] op_sel:[0,1] op_sel_hi:[1,0] neg_lo:[0,1]
	v_pk_add_f32 v[168:169], v[130:131], v[154:155]
	v_pk_add_f32 v[130:131], v[130:131], v[154:155] neg_lo:[0,1] neg_hi:[0,1]
	v_pk_fma_f32 v[72:73], v[10:11], v[60:61], v[72:73] op_sel_hi:[0,1,1]
	v_pk_mul_f32 v[154:155], v[130:131], s[40:41]
	v_pk_fma_f32 v[88:89], v[10:11], v[76:77], v[88:89] op_sel_hi:[0,1,1]
	v_pk_fma_f32 v[130:131], v[130:131], s[38:39], v[154:155] op_sel:[0,0,1] op_sel_hi:[1,0,0]
	v_pk_add_f32 v[154:155], v[148:149], v[156:157]
	v_pk_add_f32 v[156:157], v[148:149], v[156:157] neg_lo:[0,1] neg_hi:[0,1]
	v_pk_fma_f32 v[104:105], v[10:11], v[92:93], v[104:105] op_sel_hi:[0,1,1]
	v_pk_add_f32 v[148:149], v[150:151], v[158:159]
	v_pk_add_f32 v[150:151], v[150:151], v[158:159] neg_lo:[0,1] neg_hi:[0,1]
	v_pk_fma_f32 v[120:121], v[10:11], v[108:109], v[120:121] op_sel_hi:[0,1,1]
	v_pk_mul_f32 v[158:159], v[150:151], s[40:41]
	v_mov_b32_e32 v27, v19
	v_pk_fma_f32 v[150:151], v[150:151], s[38:39], v[158:159] op_sel:[0,0,1] op_sel_hi:[1,0,0] neg_lo:[1,0,0] neg_hi:[1,0,0]
	v_pk_add_f32 v[158:159], v[174:175], v[190:191]
	v_pk_add_f32 v[174:175], v[174:175], v[190:191] neg_lo:[0,1] neg_hi:[0,1]
	v_pk_add_f32 v[190:191], v[210:211], v[176:177]
	v_pk_add_f32 v[210:211], v[210:211], v[176:177] neg_lo:[0,1] neg_hi:[0,1]
	v_mov_b32_e32 v31, v21
	v_pk_add_f32 v[176:177], v[196:197], v[204:205] op_sel:[0,1] op_sel_hi:[1,0] neg_hi:[0,1]
	v_pk_add_f32 v[196:197], v[196:197], v[204:205] op_sel:[0,1] op_sel_hi:[1,0] neg_lo:[0,1]
	v_pk_add_f32 v[204:205], v[182:183], v[194:195]
	v_pk_add_f32 v[194:195], v[182:183], v[194:195] neg_lo:[0,1] neg_hi:[0,1]
	v_xor_b32_e32 v34, 0x80000000, v25
	v_pk_add_f32 v[182:183], v[206:207], v[184:185]
	v_pk_add_f32 v[184:185], v[206:207], v[184:185] neg_lo:[0,1] neg_hi:[0,1]
	v_pk_add_f32 v[206:207], v[198:199], v[178:179]
	v_pk_add_f32 v[198:199], v[198:199], v[178:179] neg_lo:[0,1] neg_hi:[0,1]
	v_xor_b32_e32 v38, 0x80000000, v29
	v_pk_add_f32 v[178:179], v[144:145], v[186:187] op_sel:[0,1] op_sel_hi:[1,0] neg_hi:[0,1]
	v_pk_add_f32 v[144:145], v[144:145], v[186:187] op_sel:[0,1] op_sel_hi:[1,0] neg_lo:[0,1]
	v_pk_add_f32 v[186:187], v[160:161], v[180:181]
	v_pk_add_f32 v[180:181], v[160:161], v[180:181] neg_lo:[0,1] neg_hi:[0,1]
	v_xor_b32_e32 v42, 0x80000000, v33
	v_pk_add_f32 v[160:161], v[188:189], v[192:193]
	v_pk_add_f32 v[188:189], v[188:189], v[192:193] neg_lo:[0,1] neg_hi:[0,1]
	v_pk_add_f32 v[192:193], v[208:209], v[162:163]
	v_pk_add_f32 v[208:209], v[208:209], v[162:163] neg_lo:[0,1] neg_hi:[0,1]
	v_xor_b32_e32 v46, 0x80000000, v37
	v_pk_add_f32 v[162:163], v[166:167], v[170:171] op_sel:[0,1] op_sel_hi:[1,0] neg_hi:[0,1]
	v_pk_add_f32 v[166:167], v[166:167], v[170:171] op_sel:[0,1] op_sel_hi:[1,0] neg_lo:[0,1]
	v_pk_add_f32 v[170:171], v[152:153], v[164:165]
	v_pk_add_f32 v[164:165], v[152:153], v[164:165] neg_lo:[0,1] neg_hi:[0,1]
	v_mov_b32_e32 v35, v25
	v_pk_add_f32 v[152:153], v[172:173], v[154:155]
	v_pk_add_f32 v[154:155], v[172:173], v[154:155] neg_lo:[0,1] neg_hi:[0,1]
	v_pk_add_f32 v[172:173], v[168:169], v[148:149]
	v_pk_add_f32 v[168:169], v[168:169], v[148:149] neg_lo:[0,1] neg_hi:[0,1]
	v_mov_b32_e32 v39, v29
	v_pk_add_f32 v[148:149], v[128:129], v[156:157] op_sel:[0,1] op_sel_hi:[1,0] neg_hi:[0,1]
	v_pk_add_f32 v[128:129], v[128:129], v[156:157] op_sel:[0,1] op_sel_hi:[1,0] neg_lo:[0,1]
	v_pk_add_f32 v[156:157], v[130:131], v[150:151]
	v_pk_add_f32 v[130:131], v[130:131], v[150:151] neg_lo:[0,1] neg_hi:[0,1]
	v_mov_b32_e32 v43, v33
	v_xor_b32_e32 v151, 0x80000000, v130
	v_mov_b32_e32 v150, v131
	v_pk_add_f32 v[130:131], v[158:159], v[190:191]
	v_pk_add_f32 v[158:159], v[158:159], v[190:191] neg_lo:[0,1] neg_hi:[0,1]
	v_pk_add_f32 v[190:191], v[174:175], v[210:211] op_sel:[0,1] op_sel_hi:[1,0] neg_hi:[0,1]
	v_pk_add_f32 v[174:175], v[174:175], v[210:211] op_sel:[0,1] op_sel_hi:[1,0] neg_lo:[0,1]
	v_pk_add_f32 v[210:211], v[176:177], v[204:205]
	v_pk_add_f32 v[176:177], v[176:177], v[204:205] neg_lo:[0,1] neg_hi:[0,1]
	v_pk_add_f32 v[204:205], v[196:197], v[194:195] op_sel:[0,1] op_sel_hi:[1,0] neg_hi:[0,1]
	v_pk_add_f32 v[194:195], v[196:197], v[194:195] op_sel:[0,1] op_sel_hi:[1,0] neg_lo:[0,1]
	v_pk_add_f32 v[196:197], v[182:183], v[206:207]
	v_pk_add_f32 v[182:183], v[182:183], v[206:207] neg_lo:[0,1] neg_hi:[0,1]
	v_pk_add_f32 v[206:207], v[184:185], v[198:199] op_sel:[0,1] op_sel_hi:[1,0] neg_hi:[0,1]
	v_pk_add_f32 v[184:185], v[184:185], v[198:199] op_sel:[0,1] op_sel_hi:[1,0] neg_lo:[0,1]
	v_pk_add_f32 v[198:199], v[178:179], v[186:187]
	v_pk_add_f32 v[178:179], v[178:179], v[186:187] neg_lo:[0,1] neg_hi:[0,1]
	v_pk_add_f32 v[186:187], v[144:145], v[180:181] op_sel:[0,1] op_sel_hi:[1,0] neg_hi:[0,1]
	v_pk_add_f32 v[144:145], v[144:145], v[180:181] op_sel:[0,1] op_sel_hi:[1,0] neg_lo:[0,1]
	v_pk_add_f32 v[180:181], v[160:161], v[192:193]
	v_pk_add_f32 v[160:161], v[160:161], v[192:193] neg_lo:[0,1] neg_hi:[0,1]
	v_pk_mul_f32 v[4:5], v[4:5], v[180:181] op_sel:[0,1] op_sel_hi:[1,0]
	v_pk_add_f32 v[192:193], v[188:189], v[208:209] op_sel:[0,1] op_sel_hi:[1,0] neg_hi:[0,1]
	v_pk_add_f32 v[188:189], v[188:189], v[208:209] op_sel:[0,1] op_sel_hi:[1,0] neg_lo:[0,1]
	v_pk_add_f32 v[208:209], v[162:163], v[170:171]
	v_pk_add_f32 v[162:163], v[162:163], v[170:171] neg_lo:[0,1] neg_hi:[0,1]
	v_pk_add_f32 v[170:171], v[166:167], v[164:165] op_sel:[0,1] op_sel_hi:[1,0] neg_hi:[0,1]
	v_pk_add_f32 v[164:165], v[166:167], v[164:165] op_sel:[0,1] op_sel_hi:[1,0] neg_lo:[0,1]
	v_pk_add_f32 v[166:167], v[152:153], v[172:173]
	v_pk_fma_f32 v[4:5], v[6:7], v[180:181], v[4:5] op_sel_hi:[0,1,1]
	v_pk_mul_f32 v[6:7], v[14:15], v[196:197] op_sel:[0,1] op_sel_hi:[1,0]
	v_mov_b32_e32 v47, v37
	v_pk_fma_f32 v[6:7], v[8:9], v[196:197], v[6:7] op_sel_hi:[0,1,1]
	v_pk_mul_f32 v[8:9], v[22:23], v[166:167] op_sel:[0,1] op_sel_hi:[1,0]
	v_pk_add_f32 v[152:153], v[152:153], v[172:173] neg_lo:[0,1] neg_hi:[0,1]
	v_pk_fma_f32 v[8:9], v[10:11], v[166:167], v[8:9] op_sel_hi:[0,1,1]
	v_pk_mul_f32 v[10:11], v[16:17], v[210:211] op_sel:[0,1] op_sel_hi:[1,0]
	v_pk_add_f32 v[172:173], v[154:155], v[168:169] op_sel:[0,1] op_sel_hi:[1,0] neg_hi:[0,1]
	v_pk_add_f32 v[154:155], v[154:155], v[168:169] op_sel:[0,1] op_sel_hi:[1,0] neg_lo:[0,1]
	v_pk_add_f32 v[168:169], v[148:149], v[156:157]
	v_pk_fma_f32 v[10:11], v[12:13], v[210:211], v[10:11] op_sel_hi:[0,1,1]
	v_pk_mul_f32 v[12:13], v[26:27], v[208:209] op_sel:[0,1] op_sel_hi:[1,0]
	v_pk_mul_f32 v[14:15], v[30:31], v[198:199] op_sel:[0,1] op_sel_hi:[1,0]
	v_xor_b32_e32 v50, 0x80000000, v41
	v_xor_b32_e32 v54, 0x80000000, v45
	v_xor_b32_e32 v58, 0x80000000, v49
	v_xor_b32_e32 v62, 0x80000000, v53
	v_xor_b32_e32 v66, 0x80000000, v57
	v_xor_b32_e32 v70, 0x80000000, v61
	v_xor_b32_e32 v74, 0x80000000, v65
	v_mov_b32_e32 v51, v41
	v_mov_b32_e32 v55, v45
	v_mov_b32_e32 v59, v49
	v_mov_b32_e32 v63, v53
	v_mov_b32_e32 v67, v57
	v_mov_b32_e32 v71, v61
	v_mov_b32_e32 v75, v65
	v_pk_add_f32 v[148:149], v[148:149], v[156:157] neg_lo:[0,1] neg_hi:[0,1]
	v_pk_add_f32 v[156:157], v[128:129], v[150:151]
	v_pk_fma_f32 v[12:13], v[18:19], v[208:209], v[12:13] op_sel_hi:[0,1,1]
	v_pk_fma_f32 v[14:15], v[20:21], v[198:199], v[14:15] op_sel_hi:[0,1,1]
	v_pk_mul_f32 v[16:17], v[34:35], v[168:169] op_sel:[0,1] op_sel_hi:[1,0]
	v_pk_mul_f32 v[18:19], v[38:39], v[190:191] op_sel:[0,1] op_sel_hi:[1,0]
	v_pk_mul_f32 v[20:21], v[42:43], v[192:193] op_sel:[0,1] op_sel_hi:[1,0]
	v_pk_mul_f32 v[22:23], v[46:47], v[206:207] op_sel:[0,1] op_sel_hi:[1,0]
	v_xor_b32_e32 v78, 0x80000000, v69
	v_xor_b32_e32 v82, 0x80000000, v73
	v_xor_b32_e32 v86, 0x80000000, v77
	v_xor_b32_e32 v90, 0x80000000, v81
	v_xor_b32_e32 v94, 0x80000000, v85
	v_xor_b32_e32 v98, 0x80000000, v89
	v_xor_b32_e32 v102, 0x80000000, v93
	v_xor_b32_e32 v106, 0x80000000, v97
	v_xor_b32_e32 v110, 0x80000000, v101
	v_xor_b32_e32 v114, 0x80000000, v105
	v_xor_b32_e32 v118, 0x80000000, v109
	v_xor_b32_e32 v122, 0x80000000, v113
	v_xor_b32_e32 v124, 0x80000000, v117
	v_xor_b32_e32 v126, 0x80000000, v121
	v_mov_b32_e32 v79, v69
	v_mov_b32_e32 v83, v73
	v_mov_b32_e32 v87, v77
	v_mov_b32_e32 v91, v81
	v_mov_b32_e32 v95, v85
	v_mov_b32_e32 v99, v89
	v_mov_b32_e32 v103, v93
	v_mov_b32_e32 v107, v97
	v_mov_b32_e32 v111, v101
	v_mov_b32_e32 v115, v105
	v_mov_b32_e32 v119, v109
	v_mov_b32_e32 v123, v113
	v_mov_b32_e32 v125, v117
	v_mov_b32_e32 v127, v121
	v_pk_add_f32 v[128:129], v[128:129], v[150:151] neg_lo:[0,1] neg_hi:[0,1]
	v_pk_fma_f32 v[16:17], v[24:25], v[168:169], v[16:17] op_sel_hi:[0,1,1]
	v_pk_fma_f32 v[18:19], v[28:29], v[190:191], v[18:19] op_sel_hi:[0,1,1]
	v_pk_fma_f32 v[20:21], v[32:33], v[192:193], v[20:21] op_sel_hi:[0,1,1]
	v_pk_fma_f32 v[22:23], v[36:37], v[206:207], v[22:23] op_sel_hi:[0,1,1]
	v_pk_mul_f32 v[24:25], v[50:51], v[172:173] op_sel:[0,1] op_sel_hi:[1,0]
	v_pk_mul_f32 v[26:27], v[54:55], v[204:205] op_sel:[0,1] op_sel_hi:[1,0]
	v_pk_mul_f32 v[28:29], v[58:59], v[170:171] op_sel:[0,1] op_sel_hi:[1,0]
	v_pk_mul_f32 v[30:31], v[62:63], v[186:187] op_sel:[0,1] op_sel_hi:[1,0]
	v_pk_mul_f32 v[32:33], v[66:67], v[156:157] op_sel:[0,1] op_sel_hi:[1,0]
	v_pk_mul_f32 v[34:35], v[70:71], v[158:159] op_sel:[0,1] op_sel_hi:[1,0]
	v_pk_mul_f32 v[36:37], v[74:75], v[160:161] op_sel:[0,1] op_sel_hi:[1,0]
	v_pk_fma_f32 v[24:25], v[40:41], v[172:173], v[24:25] op_sel_hi:[0,1,1]
	v_pk_fma_f32 v[26:27], v[44:45], v[204:205], v[26:27] op_sel_hi:[0,1,1]
	v_pk_fma_f32 v[28:29], v[48:49], v[170:171], v[28:29] op_sel_hi:[0,1,1]
	v_pk_fma_f32 v[30:31], v[52:53], v[186:187], v[30:31] op_sel_hi:[0,1,1]
	v_pk_fma_f32 v[32:33], v[56:57], v[156:157], v[32:33] op_sel_hi:[0,1,1]
	v_pk_fma_f32 v[34:35], v[60:61], v[158:159], v[34:35] op_sel_hi:[0,1,1]
	v_pk_fma_f32 v[36:37], v[64:65], v[160:161], v[36:37] op_sel_hi:[0,1,1]
	v_pk_mul_f32 v[38:39], v[78:79], v[182:183] op_sel:[0,1] op_sel_hi:[1,0]
	v_pk_mul_f32 v[40:41], v[82:83], v[152:153] op_sel:[0,1] op_sel_hi:[1,0]
	v_pk_mul_f32 v[42:43], v[86:87], v[176:177] op_sel:[0,1] op_sel_hi:[1,0]
	v_pk_mul_f32 v[44:45], v[90:91], v[162:163] op_sel:[0,1] op_sel_hi:[1,0]
	v_pk_mul_f32 v[46:47], v[94:95], v[178:179] op_sel:[0,1] op_sel_hi:[1,0]
	v_pk_mul_f32 v[48:49], v[98:99], v[148:149] op_sel:[0,1] op_sel_hi:[1,0]
	v_pk_mul_f32 v[50:51], v[102:103], v[174:175] op_sel:[0,1] op_sel_hi:[1,0]
	v_pk_mul_f32 v[52:53], v[106:107], v[188:189] op_sel:[0,1] op_sel_hi:[1,0]
	v_pk_mul_f32 v[54:55], v[110:111], v[184:185] op_sel:[0,1] op_sel_hi:[1,0]
	v_pk_mul_f32 v[56:57], v[114:115], v[154:155] op_sel:[0,1] op_sel_hi:[1,0]
	v_pk_mul_f32 v[58:59], v[118:119], v[194:195] op_sel:[0,1] op_sel_hi:[1,0]
	v_pk_mul_f32 v[60:61], v[122:123], v[164:165] op_sel:[0,1] op_sel_hi:[1,0]
	v_pk_mul_f32 v[62:63], v[124:125], v[144:145] op_sel:[0,1] op_sel_hi:[1,0]
	v_pk_mul_f32 v[64:65], v[126:127], v[128:129] op_sel:[0,1] op_sel_hi:[1,0]
	v_pk_fma_f32 v[38:39], v[68:69], v[182:183], v[38:39] op_sel_hi:[0,1,1]
	v_pk_fma_f32 v[40:41], v[72:73], v[152:153], v[40:41] op_sel_hi:[0,1,1]
	v_pk_fma_f32 v[42:43], v[76:77], v[176:177], v[42:43] op_sel_hi:[0,1,1]
	v_pk_fma_f32 v[44:45], v[80:81], v[162:163], v[44:45] op_sel_hi:[0,1,1]
	v_pk_fma_f32 v[46:47], v[84:85], v[178:179], v[46:47] op_sel_hi:[0,1,1]
	v_pk_fma_f32 v[48:49], v[88:89], v[148:149], v[48:49] op_sel_hi:[0,1,1]
	v_pk_fma_f32 v[50:51], v[92:93], v[174:175], v[50:51] op_sel_hi:[0,1,1]
	v_pk_fma_f32 v[52:53], v[96:97], v[188:189], v[52:53] op_sel_hi:[0,1,1]
	v_pk_fma_f32 v[54:55], v[100:101], v[184:185], v[54:55] op_sel_hi:[0,1,1]
	v_pk_fma_f32 v[56:57], v[104:105], v[154:155], v[56:57] op_sel_hi:[0,1,1]
	v_pk_fma_f32 v[58:59], v[108:109], v[194:195], v[58:59] op_sel_hi:[0,1,1]
	v_pk_fma_f32 v[60:61], v[112:113], v[164:165], v[60:61] op_sel_hi:[0,1,1]
	v_pk_fma_f32 v[62:63], v[116:117], v[144:145], v[62:63] op_sel_hi:[0,1,1]
	v_pk_fma_f32 v[64:65], v[120:121], v[128:129], v[64:65] op_sel_hi:[0,1,1]
	ds_write2_b64 v2, v[130:131], v[34:35] offset1:16
	ds_write2_b64 v2, v[18:19], v[50:51] offset0:33 offset1:49
	ds_write2_b64 v2, v[10:11], v[42:43] offset0:66 offset1:82
	ds_write2_b64 v2, v[26:27], v[58:59] offset0:99 offset1:115
	ds_write2_b64 v2, v[6:7], v[38:39] offset0:132 offset1:148
	ds_write2_b64 v2, v[22:23], v[54:55] offset0:165 offset1:181
	ds_write2_b64 v2, v[14:15], v[46:47] offset0:198 offset1:214
	ds_write2_b64 v2, v[30:31], v[62:63] offset0:231 offset1:247
	ds_write2_b64 v143, v[4:5], v[36:37] offset0:8 offset1:24
	ds_write2_b64 v143, v[20:21], v[52:53] offset0:41 offset1:57
	ds_write2_b64 v143, v[12:13], v[44:45] offset0:74 offset1:90
	ds_write2_b64 v143, v[28:29], v[60:61] offset0:107 offset1:123
	ds_write2_b64 v143, v[8:9], v[40:41] offset0:140 offset1:156
	ds_write2_b64 v143, v[24:25], v[56:57] offset0:173 offset1:189
	ds_write2_b64 v143, v[16:17], v[48:49] offset0:206 offset1:222
	ds_write2_b64 v143, v[32:33], v[64:65] offset0:239 offset1:255
	s_waitcnt lgkmcnt(0)
	s_barrier
	s_nop 0
	v_ashrrev_i32_e32 v2, 31, v142
	v_lshrrev_b32_e32 v2, 23, v2
	v_add_u32_e32 v2, v142, v2
	v_ashrrev_i32_e32 v2, 9, v2
	v_mul_i32_i24_e32 v4, 0x200, v2
	v_sub_u32_e32 v144, v142, v4
	v_lshlrev_b32_e32 v143, 14, v2
	v_lshlrev_b32_e32 v2, 1, v144
	v_bfrev_b32_e32 v2, v2
	v_lshrrev_b32_e32 v2, 22, v2
	v_sub_u32_e32 v2, 0x400, v2
	v_bfrev_b32_e32 v2, v2
	v_lshrrev_b32_e32 v2, 18, v2
	v_and_b32_e32 v2, 0x3ff0, v2
	v_cmp_eq_u32_e32 vcc, 0, v144
	v_lshl_add_u32 v4, v144, 5, v143
	v_lshlrev_b32_e32 v5, 3, v4
	v_cndmask_b32_e64 v2, v2, 16, vcc
	v_ashrrev_i32_e32 v4, 2, v4
	v_or_b32_e32 v2, v2, v143
	v_add3_u32 v56, 0, v5, v4
	v_ashrrev_i32_e32 v4, 5, v2
	v_lshlrev_b32_e32 v2, 3, v2
	v_lshlrev_b32_e32 v4, 3, v4
	v_add3_u32 v2, 0, v2, v4
	ds_read2_b64 v[4:7], v56 offset1:1
	ds_read2_b64 v[8:11], v56 offset0:2 offset1:3
	ds_read2_b64 v[12:15], v2 offset1:1
	ds_read2_b64 v[16:19], v2 offset0:2 offset1:3
	ds_read2_b64 v[20:23], v56 offset0:4 offset1:5
	ds_read2_b64 v[24:27], v56 offset0:6 offset1:7
	ds_read2_b64 v[28:31], v2 offset0:4 offset1:5
	ds_read2_b64 v[32:35], v2 offset0:6 offset1:7
	ds_read2_b64 v[36:39], v56 offset0:8 offset1:9
	ds_read2_b64 v[40:43], v56 offset0:10 offset1:11
	ds_read2_b64 v[48:51], v2 offset0:8 offset1:9
	ds_read2_b64 v[52:55], v2 offset0:10 offset1:11
	ds_read2_b64 v[44:47], v56 offset0:12 offset1:13
	ds_read2_b64 v[56:59], v56 offset0:14 offset1:15
	ds_read2_b64 v[70:73], v2 offset0:12 offset1:13
	ds_read2_b64 v[98:101], v2 offset0:14 offset1:15
	s_waitcnt lgkmcnt(7)
	v_pk_add_f32 v[60:61], v[4:5], v[36:37]
	v_pk_add_f32 v[4:5], v[4:5], v[36:37] neg_lo:[0,1] neg_hi:[0,1]
	v_pk_add_f32 v[36:37], v[6:7], v[38:39]
	v_pk_add_f32 v[6:7], v[6:7], v[38:39] neg_lo:[0,1] neg_hi:[0,1]
	s_waitcnt lgkmcnt(3)
	v_pk_add_f32 v[62:63], v[22:23], v[46:47]
	v_pk_mul_f32 v[38:39], v[6:7], s[24:25]
	v_pk_add_f32 v[22:23], v[22:23], v[46:47] neg_lo:[0,1] neg_hi:[0,1]
	v_pk_fma_f32 v[6:7], v[6:7], s[22:23], v[38:39] op_sel:[0,0,1] op_sel_hi:[1,0,0]
	v_pk_add_f32 v[38:39], v[8:9], v[40:41]
	v_pk_add_f32 v[8:9], v[8:9], v[40:41] neg_lo:[0,1] neg_hi:[0,1]
	v_pk_mul_f32 v[46:47], v[22:23], s[44:45]
	v_pk_mul_f32 v[40:41], v[8:9], s[40:41]
	v_pk_fma_f32 v[22:23], v[22:23], s[50:51], v[46:47] op_sel:[0,0,1] op_sel_hi:[1,0,0] neg_lo:[1,0,0] neg_hi:[1,0,0]
	v_pk_fma_f32 v[8:9], v[8:9], s[38:39], v[40:41] op_sel:[0,0,1] op_sel_hi:[1,0,0]
	v_pk_add_f32 v[40:41], v[10:11], v[42:43]
	v_pk_add_f32 v[10:11], v[10:11], v[42:43] neg_lo:[0,1] neg_hi:[0,1]
	s_waitcnt lgkmcnt(2)
	v_pk_add_f32 v[46:47], v[24:25], v[56:57]
	v_pk_add_f32 v[24:25], v[24:25], v[56:57] neg_lo:[0,1] neg_hi:[0,1]
	v_pk_mul_f32 v[42:43], v[10:11], s[44:45]
	v_pk_mul_f32 v[56:57], v[24:25], s[40:41]
	v_pk_fma_f32 v[10:11], v[10:11], s[50:51], v[42:43] op_sel:[0,0,1] op_sel_hi:[1,0,0]
	v_pk_add_f32 v[42:43], v[20:21], v[44:45]
	v_pk_add_f32 v[44:45], v[20:21], v[44:45] neg_lo:[0,1] neg_hi:[0,1]
	v_pk_fma_f32 v[24:25], v[24:25], s[38:39], v[56:57] op_sel:[0,0,1] op_sel_hi:[1,0,0] neg_lo:[1,0,0] neg_hi:[1,0,0]
	v_pk_add_f32 v[56:57], v[26:27], v[58:59]
	v_pk_add_f32 v[26:27], v[26:27], v[58:59] neg_lo:[0,1] neg_hi:[0,1]
	s_nop 0
	v_pk_mul_f32 v[58:59], v[26:27], s[24:25]
	v_pk_add_f32 v[64:65], v[40:41], v[56:57]
	v_pk_add_f32 v[40:41], v[40:41], v[56:57] neg_lo:[0,1] neg_hi:[0,1]
	v_pk_fma_f32 v[26:27], v[26:27], s[22:23], v[58:59] op_sel:[0,0,1] op_sel_hi:[1,0,0] neg_lo:[1,0,0] neg_hi:[1,0,0]
	v_pk_mul_f32 v[56:57], v[40:41], s[40:41]
	v_pk_add_f32 v[20:21], v[4:5], v[44:45] op_sel:[0,1] op_sel_hi:[1,0] neg_hi:[0,1]
	v_pk_add_f32 v[4:5], v[4:5], v[44:45] op_sel:[0,1] op_sel_hi:[1,0] neg_lo:[0,1]
	v_pk_add_f32 v[44:45], v[6:7], v[22:23]
	v_pk_add_f32 v[6:7], v[6:7], v[22:23] neg_lo:[0,1] neg_hi:[0,1]
	v_pk_fma_f32 v[40:41], v[40:41], s[38:39], v[56:57] op_sel:[0,0,1] op_sel_hi:[1,0,0] neg_lo:[1,0,0] neg_hi:[1,0,0]
	v_pk_mul_f32 v[22:23], v[6:7], s[40:41]
	v_pk_add_f32 v[56:57], v[10:11], v[26:27]
	v_pk_add_f32 v[10:11], v[10:11], v[26:27] neg_lo:[0,1] neg_hi:[0,1]
	v_pk_add_f32 v[58:59], v[60:61], v[42:43]
	v_pk_add_f32 v[42:43], v[60:61], v[42:43] neg_lo:[0,1] neg_hi:[0,1]
	v_pk_add_f32 v[60:61], v[36:37], v[62:63]
	v_pk_add_f32 v[36:37], v[36:37], v[62:63] neg_lo:[0,1] neg_hi:[0,1]
	v_pk_fma_f32 v[6:7], v[6:7], s[38:39], v[22:23] op_sel:[0,0,1] op_sel_hi:[1,0,0]
	v_pk_add_f32 v[22:23], v[8:9], v[24:25]
	v_pk_add_f32 v[24:25], v[8:9], v[24:25] neg_lo:[0,1] neg_hi:[0,1]
	v_pk_mul_f32 v[26:27], v[10:11], s[40:41]
	v_pk_mul_f32 v[62:63], v[36:37], s[40:41]
	v_pk_fma_f32 v[10:11], v[10:11], s[38:39], v[26:27] op_sel:[0,0,1] op_sel_hi:[1,0,0] neg_lo:[1,0,0] neg_hi:[1,0,0]
	v_pk_fma_f32 v[36:37], v[36:37], s[38:39], v[62:63] op_sel:[0,0,1] op_sel_hi:[1,0,0]
	v_pk_add_f32 v[62:63], v[38:39], v[46:47]
	v_pk_add_f32 v[66:67], v[20:21], v[22:23]
	v_pk_add_f32 v[20:21], v[20:21], v[22:23] neg_lo:[0,1] neg_hi:[0,1]
	v_pk_add_f32 v[22:23], v[44:45], v[56:57]
	v_pk_add_f32 v[44:45], v[44:45], v[56:57] neg_lo:[0,1] neg_hi:[0,1]
	v_pk_add_f32 v[8:9], v[4:5], v[24:25] op_sel:[0,1] op_sel_hi:[1,0] neg_hi:[0,1]
	v_pk_add_f32 v[4:5], v[4:5], v[24:25] op_sel:[0,1] op_sel_hi:[1,0] neg_lo:[0,1]
	v_pk_add_f32 v[24:25], v[6:7], v[10:11]
	v_pk_add_f32 v[10:11], v[6:7], v[10:11] neg_lo:[0,1] neg_hi:[0,1]
	v_pk_add_f32 v[26:27], v[58:59], v[62:63]
	v_pk_add_f32 v[58:59], v[58:59], v[62:63] neg_lo:[0,1] neg_hi:[0,1]
	v_pk_add_f32 v[62:63], v[60:61], v[64:65]
	v_pk_add_f32 v[60:61], v[60:61], v[64:65] neg_lo:[0,1] neg_hi:[0,1]
	v_xor_b32_e32 v57, 0x80000000, v44
	v_mov_b32_e32 v56, v45
	v_xor_b32_e32 v65, 0x80000000, v60
	v_pk_add_f32 v[130:131], v[26:27], v[62:63]
	v_pk_add_f32 v[92:93], v[26:27], v[62:63] neg_lo:[0,1] neg_hi:[0,1]
	v_mov_b32_e32 v64, v61
	v_pk_add_f32 v[62:63], v[20:21], v[56:57]
	v_pk_add_f32 v[78:79], v[20:21], v[56:57] neg_lo:[0,1] neg_hi:[0,1]
	v_pk_add_f32 v[56:57], v[4:5], v[10:11] op_sel:[0,1] op_sel_hi:[1,0] neg_hi:[0,1]
	v_pk_add_f32 v[90:91], v[4:5], v[10:11] op_sel:[0,1] op_sel_hi:[1,0] neg_lo:[0,1]
	v_pk_add_f32 v[10:11], v[14:15], v[50:51] neg_lo:[0,1] neg_hi:[0,1]
	v_pk_add_f32 v[46:47], v[38:39], v[46:47] neg_lo:[0,1] neg_hi:[0,1]
	v_pk_add_f32 v[84:85], v[58:59], v[64:65]
	v_pk_add_f32 v[86:87], v[58:59], v[64:65] neg_lo:[0,1] neg_hi:[0,1]
	v_pk_add_f32 v[80:81], v[8:9], v[24:25]
	v_pk_add_f32 v[64:65], v[8:9], v[24:25] neg_lo:[0,1] neg_hi:[0,1]
	v_pk_add_f32 v[4:5], v[12:13], v[48:49]
	v_pk_add_f32 v[6:7], v[12:13], v[48:49] neg_lo:[0,1] neg_hi:[0,1]
	v_pk_add_f32 v[8:9], v[14:15], v[50:51]
	v_pk_mul_f32 v[12:13], v[10:11], s[24:25]
	v_pk_add_f32 v[14:15], v[16:17], v[52:53] neg_lo:[0,1] neg_hi:[0,1]
	v_pk_fma_f32 v[10:11], v[10:11], s[22:23], v[12:13] op_sel:[0,0,1] op_sel_hi:[1,0,0]
	v_pk_add_f32 v[12:13], v[16:17], v[52:53]
	v_pk_mul_f32 v[16:17], v[14:15], s[40:41]
	v_pk_add_f32 v[38:39], v[42:43], v[46:47] op_sel:[0,1] op_sel_hi:[1,0] neg_hi:[0,1]
	v_pk_add_f32 v[42:43], v[42:43], v[46:47] op_sel:[0,1] op_sel_hi:[1,0] neg_lo:[0,1]
	v_pk_add_f32 v[46:47], v[36:37], v[40:41]
	v_pk_fma_f32 v[14:15], v[14:15], s[38:39], v[16:17] op_sel:[0,0,1] op_sel_hi:[1,0,0]
	v_pk_add_f32 v[16:17], v[18:19], v[54:55]
	v_pk_add_f32 v[18:19], v[18:19], v[54:55] neg_lo:[0,1] neg_hi:[0,1]
	v_pk_add_f32 v[88:89], v[38:39], v[46:47]
	v_pk_add_f32 v[68:69], v[38:39], v[46:47] neg_lo:[0,1] neg_hi:[0,1]
	v_pk_add_f32 v[96:97], v[66:67], v[22:23]
	v_pk_add_f32 v[46:47], v[66:67], v[22:23] neg_lo:[0,1] neg_hi:[0,1]
	v_pk_mul_f32 v[20:21], v[18:19], s[44:45]
	s_waitcnt lgkmcnt(1)
	v_pk_add_f32 v[24:25], v[28:29], v[70:71] neg_lo:[0,1] neg_hi:[0,1]
	v_pk_add_f32 v[26:27], v[30:31], v[72:73] neg_lo:[0,1] neg_hi:[0,1]
	v_pk_fma_f32 v[18:19], v[18:19], s[50:51], v[20:21] op_sel:[0,0,1] op_sel_hi:[1,0,0]
	v_pk_add_f32 v[20:21], v[28:29], v[70:71]
	v_pk_add_f32 v[22:23], v[30:31], v[72:73]
	v_pk_mul_f32 v[28:29], v[26:27], s[44:45]
	s_waitcnt lgkmcnt(0)
	v_pk_add_f32 v[30:31], v[32:33], v[98:99] neg_lo:[0,1] neg_hi:[0,1]
	v_pk_fma_f32 v[26:27], v[26:27], s[50:51], v[28:29] op_sel:[0,0,1] op_sel_hi:[1,0,0] neg_lo:[1,0,0] neg_hi:[1,0,0]
	v_pk_add_f32 v[28:29], v[32:33], v[98:99]
	v_pk_mul_f32 v[32:33], v[30:31], s[40:41]
	v_pk_add_f32 v[36:37], v[36:37], v[40:41] neg_lo:[0,1] neg_hi:[0,1]
	v_pk_fma_f32 v[30:31], v[30:31], s[38:39], v[32:33] op_sel:[0,0,1] op_sel_hi:[1,0,0] neg_lo:[1,0,0] neg_hi:[1,0,0]
	v_pk_add_f32 v[32:33], v[34:35], v[100:101]
	v_pk_add_f32 v[34:35], v[34:35], v[100:101] neg_lo:[0,1] neg_hi:[0,1]
	v_xor_b32_e32 v41, 0x80000000, v36
	v_mov_b32_e32 v40, v37
	v_pk_mul_f32 v[36:37], v[34:35], s[24:25]
	v_mov_b32_e32 v2, v130
	v_pk_fma_f32 v[34:35], v[34:35], s[22:23], v[36:37] op_sel:[0,0,1] op_sel_hi:[1,0,0] neg_lo:[1,0,0] neg_hi:[1,0,0]
	v_pk_add_f32 v[36:37], v[4:5], v[20:21]
	v_pk_add_f32 v[4:5], v[4:5], v[20:21] neg_lo:[0,1] neg_hi:[0,1]
	v_pk_add_f32 v[20:21], v[8:9], v[22:23]
	v_pk_add_f32 v[8:9], v[8:9], v[22:23] neg_lo:[0,1] neg_hi:[0,1]
	v_cmp_ne_u32_e64 s[0:1], 0, v144
	v_pk_mul_f32 v[22:23], v[8:9], s[40:41]
	v_pk_add_f32 v[74:75], v[42:43], v[40:41]
	v_pk_fma_f32 v[8:9], v[8:9], s[38:39], v[22:23] op_sel:[0,0,1] op_sel_hi:[1,0,0]
	v_pk_add_f32 v[22:23], v[12:13], v[28:29]
	v_pk_add_f32 v[28:29], v[12:13], v[28:29] neg_lo:[0,1] neg_hi:[0,1]
	v_pk_add_f32 v[94:95], v[42:43], v[40:41] neg_lo:[0,1] neg_hi:[0,1]
	v_pk_add_f32 v[12:13], v[16:17], v[32:33]
	v_pk_add_f32 v[16:17], v[16:17], v[32:33] neg_lo:[0,1] neg_hi:[0,1]
	s_nop 0
	v_pk_mul_f32 v[32:33], v[16:17], s[40:41]
	s_nop 0
	v_pk_fma_f32 v[16:17], v[16:17], s[38:39], v[32:33] op_sel:[0,0,1] op_sel_hi:[1,0,0] neg_lo:[1,0,0] neg_hi:[1,0,0]
	v_pk_add_f32 v[32:33], v[6:7], v[24:25] op_sel:[0,1] op_sel_hi:[1,0] neg_hi:[0,1]
	v_pk_add_f32 v[6:7], v[6:7], v[24:25] op_sel:[0,1] op_sel_hi:[1,0] neg_lo:[0,1]
	v_pk_add_f32 v[24:25], v[10:11], v[26:27]
	v_pk_add_f32 v[10:11], v[10:11], v[26:27] neg_lo:[0,1] neg_hi:[0,1]
	s_nop 0
	v_pk_mul_f32 v[26:27], v[10:11], s[40:41]
	s_nop 0
	v_pk_fma_f32 v[10:11], v[10:11], s[38:39], v[26:27] op_sel:[0,0,1] op_sel_hi:[1,0,0]
	v_pk_add_f32 v[26:27], v[14:15], v[30:31]
	v_pk_add_f32 v[30:31], v[14:15], v[30:31] neg_lo:[0,1] neg_hi:[0,1]
	s_nop 0
	v_pk_add_f32 v[14:15], v[18:19], v[34:35]
	v_pk_add_f32 v[18:19], v[18:19], v[34:35] neg_lo:[0,1] neg_hi:[0,1]
	s_nop 0
	v_pk_mul_f32 v[34:35], v[18:19], s[40:41]
	s_nop 0
	v_pk_fma_f32 v[18:19], v[18:19], s[38:39], v[34:35] op_sel:[0,0,1] op_sel_hi:[1,0,0] neg_lo:[1,0,0] neg_hi:[1,0,0]
	v_pk_add_f32 v[34:35], v[36:37], v[22:23]
	v_pk_add_f32 v[22:23], v[36:37], v[22:23] neg_lo:[0,1] neg_hi:[0,1]
	v_pk_add_f32 v[36:37], v[20:21], v[12:13]
	v_pk_add_f32 v[12:13], v[20:21], v[12:13] neg_lo:[0,1] neg_hi:[0,1]
	v_pk_add_f32 v[98:99], v[34:35], v[36:37]
	v_xor_b32_e32 v21, 0x80000000, v12
	v_mov_b32_e32 v20, v13
	v_pk_add_f32 v[12:13], v[4:5], v[28:29] op_sel:[0,1] op_sel_hi:[1,0] neg_hi:[0,1]
	v_pk_add_f32 v[4:5], v[4:5], v[28:29] op_sel:[0,1] op_sel_hi:[1,0] neg_lo:[0,1]
	v_pk_add_f32 v[28:29], v[8:9], v[16:17]
	v_pk_add_f32 v[8:9], v[8:9], v[16:17] neg_lo:[0,1] neg_hi:[0,1]
	v_pk_add_f32 v[100:101], v[34:35], v[36:37] neg_lo:[0,1] neg_hi:[0,1]
	v_xor_b32_e32 v17, 0x80000000, v8
	v_mov_b32_e32 v16, v9
	v_pk_add_f32 v[8:9], v[32:33], v[26:27]
	v_pk_add_f32 v[26:27], v[32:33], v[26:27] neg_lo:[0,1] neg_hi:[0,1]
	v_pk_add_f32 v[32:33], v[24:25], v[14:15]
	v_pk_add_f32 v[14:15], v[24:25], v[14:15] neg_lo:[0,1] neg_hi:[0,1]
	v_pk_add_f32 v[102:103], v[22:23], v[20:21]
	v_xor_b32_e32 v25, 0x80000000, v14
	v_mov_b32_e32 v24, v15
	v_pk_add_f32 v[14:15], v[6:7], v[30:31] op_sel:[0,1] op_sel_hi:[1,0] neg_hi:[0,1]
	v_pk_add_f32 v[6:7], v[6:7], v[30:31] op_sel:[0,1] op_sel_hi:[1,0] neg_lo:[0,1]
	v_pk_add_f32 v[30:31], v[10:11], v[18:19]
	v_pk_add_f32 v[10:11], v[10:11], v[18:19] neg_lo:[0,1] neg_hi:[0,1]
	v_pk_add_f32 v[104:105], v[22:23], v[20:21] neg_lo:[0,1] neg_hi:[0,1]
	v_xor_b32_e32 v19, 0x80000000, v10
	v_mov_b32_e32 v18, v11
	v_pk_add_f32 v[106:107], v[12:13], v[28:29]
	v_pk_add_f32 v[108:109], v[12:13], v[28:29] neg_lo:[0,1] neg_hi:[0,1]
	v_pk_add_f32 v[110:111], v[4:5], v[16:17]
	v_pk_add_f32 v[112:113], v[4:5], v[16:17] neg_lo:[0,1] neg_hi:[0,1]
	v_pk_add_f32 v[114:115], v[8:9], v[32:33]
	v_pk_add_f32 v[116:117], v[8:9], v[32:33] neg_lo:[0,1] neg_hi:[0,1]
	v_pk_add_f32 v[118:119], v[26:27], v[24:25]
	v_pk_add_f32 v[120:121], v[26:27], v[24:25] neg_lo:[0,1] neg_hi:[0,1]
	v_pk_add_f32 v[122:123], v[14:15], v[30:31]
	v_pk_add_f32 v[124:125], v[14:15], v[30:31] neg_lo:[0,1] neg_hi:[0,1]
	v_pk_add_f32 v[126:127], v[6:7], v[18:19]
	v_pk_add_f32 v[128:129], v[6:7], v[18:19] neg_lo:[0,1] neg_hi:[0,1]
	v_mov_b32_e32 v4, v131
	v_mov_b32_e32 v5, v3
	v_mov_b64_e32 v[6:7], v[2:3]
	s_and_saveexec_b64 s[50:51], s[0:1]
	s_xor_b64 s[0:1], exec, s[50:51]
	s_cbranch_execz .LBB0_562
	v_pk_add_f32 v[4:5], v[96:97], v[112:113]
	v_pk_add_f32 v[24:25], v[96:97], v[112:113] neg_lo:[0,1] neg_hi:[0,1]
	v_pk_add_f32 v[148:149], v[130:131], v[128:129]
	v_pk_add_f32 v[8:9], v[130:131], v[128:129] neg_lo:[0,1] neg_hi:[0,1]
	v_pk_add_f32 v[128:129], v[126:127], v[92:93]
	v_pk_add_f32 v[10:11], v[126:127], v[92:93] neg_lo:[0,1] neg_hi:[0,1]
	v_pk_add_f32 v[92:93], v[84:85], v[124:125]
	v_pk_add_f32 v[12:13], v[84:85], v[124:125] neg_lo:[0,1] neg_hi:[0,1]
	v_pk_add_f32 v[84:85], v[122:123], v[86:87]
	v_pk_add_f32 v[14:15], v[122:123], v[86:87] neg_lo:[0,1] neg_hi:[0,1]
	v_pk_add_f32 v[86:87], v[88:89], v[120:121]
	v_pk_add_f32 v[16:17], v[88:89], v[120:121] neg_lo:[0,1] neg_hi:[0,1]
	v_pk_add_f32 v[88:89], v[118:119], v[68:69]
	v_pk_add_f32 v[18:19], v[118:119], v[68:69] neg_lo:[0,1] neg_hi:[0,1]
	v_pk_add_f32 v[68:69], v[74:75], v[116:117]
	v_pk_add_f32 v[20:21], v[74:75], v[116:117] neg_lo:[0,1] neg_hi:[0,1]
	v_pk_add_f32 v[74:75], v[114:115], v[94:95]
	v_pk_add_f32 v[22:23], v[114:115], v[94:95] neg_lo:[0,1] neg_hi:[0,1]
	v_mov_b32_e32 v6, v4
	v_mov_b32_e32 v7, v25
	v_pk_mov_b32 v[4:5], v[4:5], v[24:25] op_sel:[1,0]
	v_pk_add_f32 v[94:95], v[110:111], v[46:47]
	v_pk_add_f32 v[24:25], v[110:111], v[46:47] neg_lo:[0,1] neg_hi:[0,1]
	v_pk_add_f32 v[46:47], v[62:63], v[108:109]
	v_pk_add_f32 v[26:27], v[62:63], v[108:109] neg_lo:[0,1] neg_hi:[0,1]
	v_pk_add_f32 v[62:63], v[106:107], v[78:79]
	v_pk_add_f32 v[28:29], v[106:107], v[78:79] neg_lo:[0,1] neg_hi:[0,1]
	v_pk_add_f32 v[78:79], v[80:81], v[104:105]
	v_pk_add_f32 v[30:31], v[80:81], v[104:105] neg_lo:[0,1] neg_hi:[0,1]
	v_pk_add_f32 v[80:81], v[102:103], v[64:65]
	v_pk_add_f32 v[32:33], v[102:103], v[64:65] neg_lo:[0,1] neg_hi:[0,1]
	v_pk_add_f32 v[64:65], v[56:57], v[100:101]
	v_pk_add_f32 v[34:35], v[56:57], v[100:101] neg_lo:[0,1] neg_hi:[0,1]
	v_pk_add_f32 v[56:57], v[98:99], v[90:91]
	v_pk_add_f32 v[36:37], v[98:99], v[90:91] neg_lo:[0,1] neg_hi:[0,1]
	v_pk_mul_f32 v[6:7], v[6:7], 0.5 op_sel_hi:[1,0]
	v_pk_mul_f32 v[4:5], v[4:5], s[46:47]
	v_mov_b32_e32 v39, v8
	v_mov_b32_e32 v38, v149
	v_mov_b32_e32 v41, v10
	v_mov_b32_e32 v40, v129
	v_mov_b32_e32 v43, v12
	v_mov_b32_e32 v42, v93
	v_mov_b32_e32 v45, v14
	v_mov_b32_e32 v44, v85
	v_mov_b32_e32 v49, v16
	v_mov_b32_e32 v48, v87
	v_mov_b32_e32 v51, v18
	v_mov_b32_e32 v50, v89
	v_mov_b32_e32 v53, v20
	v_mov_b32_e32 v52, v69
	v_mov_b32_e32 v55, v22
	v_mov_b32_e32 v54, v75
	v_mov_b32_e32 v59, v24
	v_mov_b32_e32 v58, v95
	v_mov_b32_e32 v61, v26
	v_mov_b32_e32 v60, v47
	v_mov_b32_e32 v67, v28
	v_mov_b32_e32 v66, v63
	v_mov_b32_e32 v71, v30
	v_mov_b32_e32 v70, v79
	v_mov_b32_e32 v73, v32
	v_mov_b32_e32 v72, v81
	v_mov_b32_e32 v77, v34
	v_mov_b32_e32 v76, v65
	v_mov_b32_e32 v83, v36
	v_mov_b32_e32 v82, v57
	v_mov_b32_e32 v8, v148
	v_mov_b32_e32 v10, v128
	v_mov_b32_e32 v12, v92
	v_mov_b32_e32 v14, v84
	v_mov_b32_e32 v16, v86
	v_mov_b32_e32 v18, v88
	v_mov_b32_e32 v20, v68
	v_mov_b32_e32 v22, v74
	v_mov_b32_e32 v24, v94
	v_mov_b32_e32 v26, v46
	v_mov_b32_e32 v28, v62
	v_mov_b32_e32 v30, v78
	v_mov_b32_e32 v32, v80
	v_mov_b32_e32 v34, v64
	v_mov_b32_e32 v36, v56

.LBB0_574:
	s_or_b64 exec, exec, s[0:1]
	v_mov_b32_e32 v2, v142
	s_waitcnt lgkmcnt(0)
	s_barrier
	s_mov_b32 s19, s16
	v_and_b32_e32 v4, 0xff, v2
	v_lshlrev_b32_e32 v5, 5, v2
	v_and_or_b32 v4, v5, s68, v4
	v_ashrrev_i32_e32 v5, 5, v4
	v_cvt_f32_ubyte0_e32 v2, v2
	v_lshlrev_b32_e32 v7, 3, v4
	v_mul_f32_e32 v2, 0x39000000, v2
	v_lshlrev_b32_e32 v5, 3, v5
	v_sin_f32_e32 v4, v2
	v_cos_f32_e32 v6, v2
	v_add3_u32 v2, 0, v7, v5
	ds_read_b64 v[128:129], v2
	ds_read_b64 v[130:131], v2 offset:2112
	ds_read_b64 v[144:145], v2 offset:4224
	ds_read_b64 v[148:149], v2 offset:6336
	ds_read_b64 v[150:151], v2 offset:8448
	ds_read_b64 v[152:153], v2 offset:10560
	ds_read_b64 v[154:155], v2 offset:12672
	ds_read_b64 v[156:157], v2 offset:14784
	ds_read_b64 v[158:159], v2 offset:16896
	ds_read_b64 v[160:161], v2 offset:19008
	ds_read_b64 v[162:163], v2 offset:21120
	ds_read_b64 v[164:165], v2 offset:23232
	ds_read_b64 v[166:167], v2 offset:25344
	ds_read_b64 v[168:169], v2 offset:27456
	ds_read_b64 v[170:171], v2 offset:29568
	ds_read_b64 v[172:173], v2 offset:31680
	ds_read_b64 v[174:175], v2 offset:33792
	ds_read_b64 v[176:177], v2 offset:35904
	ds_read_b64 v[178:179], v2 offset:38016
	ds_read_b64 v[180:181], v2 offset:40128
	ds_read_b64 v[182:183], v2 offset:42240
	ds_read_b64 v[184:185], v2 offset:44352
	ds_read_b64 v[186:187], v2 offset:46464
	ds_read_b64 v[188:189], v2 offset:48576
	ds_read_b64 v[190:191], v2 offset:50688
	ds_read_b64 v[192:193], v2 offset:52800
	ds_read_b64 v[194:195], v2 offset:54912
	ds_read_b64 v[196:197], v2 offset:57024
	ds_read_b64 v[198:199], v2 offset:59136
	ds_read_b64 v[204:205], v2 offset:61248
	ds_read_b64 v[206:207], v2 offset:63360
	ds_read_b64 v[208:209], v2 offset:65472
	s_waitcnt lgkmcnt(14)
	v_pk_add_f32 v[210:211], v[128:129], v[174:175]
	v_pk_add_f32 v[128:129], v[128:129], v[174:175] neg_lo:[0,1] neg_hi:[0,1]
	v_pk_add_f32 v[174:175], v[130:131], v[176:177]
	v_pk_add_f32 v[130:131], v[130:131], v[176:177] neg_lo:[0,1] neg_hi:[0,1]
	s_mov_b32 s0, s9
	v_pk_mul_f32 v[176:177], v[130:131], s[18:19]
	s_mov_b32 s41, s38
	v_pk_fma_f32 v[130:131], v[130:131], s[0:1], v[176:177] op_sel:[0,0,1] op_sel_hi:[1,0,0]
	s_waitcnt lgkmcnt(13)
	v_pk_add_f32 v[176:177], v[144:145], v[178:179]
	v_pk_add_f32 v[144:145], v[144:145], v[178:179] neg_lo:[0,1] neg_hi:[0,1]
	s_mov_b32 s43, s26
	v_pk_mul_f32 v[178:179], v[144:145], s[24:25]
	s_mov_b32 s62, s37
	v_pk_fma_f32 v[144:145], v[144:145], s[22:23], v[178:179] op_sel:[0,0,1] op_sel_hi:[1,0,0]
	s_waitcnt lgkmcnt(12)
	v_pk_add_f32 v[178:179], v[148:149], v[180:181]
	v_pk_add_f32 v[148:149], v[148:149], v[180:181] neg_lo:[0,1] neg_hi:[0,1]
	s_mov_b32 s45, s22
	v_pk_mul_f32 v[180:181], v[148:149], s[36:37]
	s_mov_b32 s50, s25
	v_pk_fma_f32 v[148:149], v[148:149], s[26:27], v[180:181] op_sel:[0,0,1] op_sel_hi:[1,0,0]
	s_waitcnt lgkmcnt(11)
	v_pk_add_f32 v[180:181], v[150:151], v[182:183]
	v_pk_add_f32 v[150:151], v[150:151], v[182:183] neg_lo:[0,1] neg_hi:[0,1]
	v_xor_b32_e32 v7, 0x80000000, v4
	v_pk_mul_f32 v[182:183], v[150:151], s[40:41]
	v_mov_b32_e32 v5, v7
	v_pk_fma_f32 v[150:151], v[150:151], s[38:39], v[182:183] op_sel:[0,0,1] op_sel_hi:[1,0,0]
	s_waitcnt lgkmcnt(10)
	v_pk_add_f32 v[182:183], v[152:153], v[184:185]
	v_pk_add_f32 v[152:153], v[152:153], v[184:185] neg_lo:[0,1] neg_hi:[0,1]
	v_pk_mul_f32 v[8:9], v[6:7], v[4:5] op_sel:[1,0] op_sel_hi:[0,1]
	v_pk_mul_f32 v[184:185], v[152:153], s[42:43]
	v_pk_fma_f32 v[8:9], v[6:7], v[6:7], v[8:9] op_sel_hi:[1,0,1]
	v_pk_fma_f32 v[152:153], v[152:153], s[62:63], v[184:185] op_sel:[0,0,1] op_sel_hi:[1,0,0]
	s_waitcnt lgkmcnt(9)
	v_pk_add_f32 v[184:185], v[154:155], v[186:187]
	v_pk_add_f32 v[154:155], v[154:155], v[186:187] neg_lo:[0,1] neg_hi:[0,1]
	v_xor_b32_e32 v14, 0x80000000, v9
	v_pk_mul_f32 v[186:187], v[154:155], s[44:45]
	v_mov_b32_e32 v15, v9
	v_pk_fma_f32 v[154:155], v[154:155], s[50:51], v[186:187] op_sel:[0,0,1] op_sel_hi:[1,0,0]
	s_waitcnt lgkmcnt(8)
	v_pk_add_f32 v[186:187], v[156:157], v[188:189]
	v_pk_add_f32 v[156:157], v[156:157], v[188:189] neg_lo:[0,1] neg_hi:[0,1]
	v_pk_mul_f32 v[12:13], v[8:9], v[14:15] op_sel:[1,0] op_sel_hi:[0,1]
	v_pk_mul_f32 v[188:189], v[156:157], s[8:9]
	v_pk_fma_f32 v[12:13], v[8:9], v[8:9], v[12:13] op_sel_hi:[1,0,1]
	v_pk_fma_f32 v[156:157], v[156:157], s[16:17], v[188:189] op_sel:[0,0,1] op_sel_hi:[1,0,0]
	s_waitcnt lgkmcnt(7)
	v_pk_add_f32 v[188:189], v[158:159], v[190:191]
	v_pk_add_f32 v[190:191], v[158:159], v[190:191] neg_lo:[0,1] neg_hi:[0,1]
	v_xor_b32_e32 v16, 0x80000000, v13
	s_waitcnt lgkmcnt(6)
	v_pk_add_f32 v[158:159], v[160:161], v[192:193]
	v_pk_add_f32 v[160:161], v[160:161], v[192:193] neg_lo:[0,1] neg_hi:[0,1]
	v_mov_b32_e32 v17, v13
	v_pk_mul_f32 v[192:193], v[160:161], s[8:9]
	v_pk_mul_f32 v[28:29], v[12:13], v[16:17] op_sel:[1,0] op_sel_hi:[0,1]
	v_pk_fma_f32 v[160:161], v[160:161], s[16:17], v[192:193] op_sel:[0,0,1] op_sel_hi:[1,0,0] neg_lo:[1,0,0] neg_hi:[1,0,0]
	s_waitcnt lgkmcnt(5)
	v_pk_add_f32 v[192:193], v[162:163], v[194:195]
	v_pk_add_f32 v[162:163], v[162:163], v[194:195] neg_lo:[0,1] neg_hi:[0,1]
	v_pk_fma_f32 v[28:29], v[12:13], v[12:13], v[28:29] op_sel_hi:[1,0,1]
	v_pk_mul_f32 v[194:195], v[162:163], s[44:45]
	v_pk_mul_f32 v[44:45], v[16:17], v[28:29] op_sel:[0,1] op_sel_hi:[1,0]
	v_pk_fma_f32 v[162:163], v[162:163], s[50:51], v[194:195] op_sel:[0,0,1] op_sel_hi:[1,0,0] neg_lo:[1,0,0] neg_hi:[1,0,0]
	s_waitcnt lgkmcnt(4)
	v_pk_add_f32 v[194:195], v[164:165], v[196:197]
	v_pk_add_f32 v[164:165], v[164:165], v[196:197] neg_lo:[0,1] neg_hi:[0,1]
	v_pk_fma_f32 v[44:45], v[12:13], v[28:29], v[44:45] op_sel_hi:[0,1,1]
	v_pk_mul_f32 v[196:197], v[164:165], s[42:43]
	v_pk_mul_f32 v[60:61], v[16:17], v[44:45] op_sel:[0,1] op_sel_hi:[1,0]
	v_pk_fma_f32 v[164:165], v[164:165], s[62:63], v[196:197] op_sel:[0,0,1] op_sel_hi:[1,0,0] neg_lo:[1,0,0] neg_hi:[1,0,0]
	s_waitcnt lgkmcnt(3)
	v_pk_add_f32 v[196:197], v[166:167], v[198:199]
	v_pk_add_f32 v[166:167], v[166:167], v[198:199] neg_lo:[0,1] neg_hi:[0,1]
	v_pk_fma_f32 v[60:61], v[12:13], v[44:45], v[60:61] op_sel_hi:[0,1,1]
	v_pk_mul_f32 v[198:199], v[166:167], s[40:41]
	v_pk_mul_f32 v[76:77], v[16:17], v[60:61] op_sel:[0,1] op_sel_hi:[1,0]
	v_pk_fma_f32 v[166:167], v[166:167], s[38:39], v[198:199] op_sel:[0,0,1] op_sel_hi:[1,0,0] neg_lo:[1,0,0] neg_hi:[1,0,0]
	s_waitcnt lgkmcnt(2)
	v_pk_add_f32 v[198:199], v[168:169], v[204:205]
	v_pk_add_f32 v[168:169], v[168:169], v[204:205] neg_lo:[0,1] neg_hi:[0,1]
	v_pk_fma_f32 v[76:77], v[12:13], v[60:61], v[76:77] op_sel_hi:[0,1,1]
	v_pk_mul_f32 v[204:205], v[168:169], s[36:37]
	v_pk_mul_f32 v[92:93], v[16:17], v[76:77] op_sel:[0,1] op_sel_hi:[1,0]
	v_pk_fma_f32 v[168:169], v[168:169], s[26:27], v[204:205] op_sel:[0,0,1] op_sel_hi:[1,0,0] neg_lo:[1,0,0] neg_hi:[1,0,0]
	s_waitcnt lgkmcnt(1)
	v_pk_add_f32 v[204:205], v[170:171], v[206:207]
	v_pk_add_f32 v[170:171], v[170:171], v[206:207] neg_lo:[0,1] neg_hi:[0,1]
	v_pk_fma_f32 v[92:93], v[12:13], v[76:77], v[92:93] op_sel_hi:[0,1,1]
	v_pk_mul_f32 v[206:207], v[170:171], s[24:25]
	v_pk_mul_f32 v[108:109], v[16:17], v[92:93] op_sel:[0,1] op_sel_hi:[1,0]
	v_pk_fma_f32 v[170:171], v[170:171], s[22:23], v[206:207] op_sel:[0,0,1] op_sel_hi:[1,0,0] neg_lo:[1,0,0] neg_hi:[1,0,0]
	s_waitcnt lgkmcnt(0)
	v_pk_add_f32 v[206:207], v[172:173], v[208:209]
	v_pk_add_f32 v[172:173], v[172:173], v[208:209] neg_lo:[0,1] neg_hi:[0,1]
	v_pk_mul_f32 v[10:11], v[4:5], v[8:9] op_sel:[0,1] op_sel_hi:[1,0]
	v_pk_mul_f32 v[208:209], v[172:173], s[18:19]
	v_pk_fma_f32 v[108:109], v[12:13], v[92:93], v[108:109] op_sel_hi:[0,1,1]
	v_pk_fma_f32 v[172:173], v[172:173], s[0:1], v[208:209] op_sel:[0,0,1] op_sel_hi:[1,0,0] neg_lo:[1,0,0] neg_hi:[1,0,0]
	v_pk_add_f32 v[208:209], v[210:211], v[188:189]
	v_pk_add_f32 v[188:189], v[210:211], v[188:189] neg_lo:[0,1] neg_hi:[0,1]
	v_pk_add_f32 v[210:211], v[174:175], v[158:159]
	v_pk_add_f32 v[158:159], v[174:175], v[158:159] neg_lo:[0,1] neg_hi:[0,1]
	v_pk_fma_f32 v[10:11], v[6:7], v[8:9], v[10:11] op_sel_hi:[0,1,1]
	v_pk_mul_f32 v[174:175], v[158:159], s[24:25]
	v_pk_mul_f32 v[18:19], v[4:5], v[12:13] op_sel:[0,1] op_sel_hi:[1,0]
	v_pk_fma_f32 v[158:159], v[158:159], s[22:23], v[174:175] op_sel:[0,0,1] op_sel_hi:[1,0,0]
	v_pk_add_f32 v[174:175], v[176:177], v[192:193]
	v_pk_add_f32 v[176:177], v[176:177], v[192:193] neg_lo:[0,1] neg_hi:[0,1]
	v_pk_mul_f32 v[32:33], v[4:5], v[28:29] op_sel:[0,1] op_sel_hi:[1,0]
	v_pk_mul_f32 v[192:193], v[176:177], s[40:41]
	v_pk_mul_f32 v[48:49], v[4:5], v[44:45] op_sel:[0,1] op_sel_hi:[1,0]
	v_pk_fma_f32 v[176:177], v[176:177], s[38:39], v[192:193] op_sel:[0,0,1] op_sel_hi:[1,0,0]
	v_pk_add_f32 v[192:193], v[178:179], v[194:195]
	v_pk_add_f32 v[178:179], v[178:179], v[194:195] neg_lo:[0,1] neg_hi:[0,1]
	v_pk_mul_f32 v[64:65], v[4:5], v[60:61] op_sel:[0,1] op_sel_hi:[1,0]
	v_pk_mul_f32 v[194:195], v[178:179], s[44:45]
	v_pk_mul_f32 v[80:81], v[4:5], v[76:77] op_sel:[0,1] op_sel_hi:[1,0]
	v_pk_fma_f32 v[178:179], v[178:179], s[50:51], v[194:195] op_sel:[0,0,1] op_sel_hi:[1,0,0]
	v_pk_add_f32 v[194:195], v[180:181], v[196:197]
	v_pk_add_f32 v[196:197], v[180:181], v[196:197] neg_lo:[0,1] neg_hi:[0,1]
	v_pk_mul_f32 v[96:97], v[4:5], v[92:93] op_sel:[0,1] op_sel_hi:[1,0]
	v_pk_add_f32 v[180:181], v[182:183], v[198:199]
	v_pk_add_f32 v[182:183], v[182:183], v[198:199] neg_lo:[0,1] neg_hi:[0,1]
	v_pk_mul_f32 v[112:113], v[4:5], v[108:109] op_sel:[0,1] op_sel_hi:[1,0]
	v_pk_mul_f32 v[198:199], v[182:183], s[44:45]
	v_xor_b32_e32 v22, 0x80000000, v11
	v_pk_fma_f32 v[182:183], v[182:183], s[50:51], v[198:199] op_sel:[0,0,1] op_sel_hi:[1,0,0] neg_lo:[1,0,0] neg_hi:[1,0,0]
	v_pk_add_f32 v[198:199], v[184:185], v[204:205]
	v_pk_add_f32 v[184:185], v[184:185], v[204:205] neg_lo:[0,1] neg_hi:[0,1]
	v_mov_b32_e32 v23, v11
	v_pk_mul_f32 v[204:205], v[184:185], s[40:41]
	v_pk_fma_f32 v[18:19], v[6:7], v[12:13], v[18:19] op_sel_hi:[0,1,1]
	v_pk_fma_f32 v[184:185], v[184:185], s[38:39], v[204:205] op_sel:[0,0,1] op_sel_hi:[1,0,0] neg_lo:[1,0,0] neg_hi:[1,0,0]
	v_pk_add_f32 v[204:205], v[186:187], v[206:207]
	v_pk_add_f32 v[186:187], v[186:187], v[206:207] neg_lo:[0,1] neg_hi:[0,1]
	v_pk_mul_f32 v[20:21], v[14:15], v[12:13] op_sel:[0,1] op_sel_hi:[1,0]
	v_pk_mul_f32 v[206:207], v[186:187], s[24:25]
	v_pk_fma_f32 v[32:33], v[6:7], v[28:29], v[32:33] op_sel_hi:[0,1,1]
	v_pk_fma_f32 v[186:187], v[186:187], s[22:23], v[206:207] op_sel:[0,0,1] op_sel_hi:[1,0,0] neg_lo:[1,0,0] neg_hi:[1,0,0]
	v_pk_add_f32 v[206:207], v[128:129], v[190:191] op_sel:[0,1] op_sel_hi:[1,0] neg_hi:[0,1]
	v_pk_add_f32 v[128:129], v[128:129], v[190:191] op_sel:[0,1] op_sel_hi:[1,0] neg_lo:[0,1]
	v_pk_add_f32 v[190:191], v[130:131], v[160:161]
	v_pk_add_f32 v[130:131], v[130:131], v[160:161] neg_lo:[0,1] neg_hi:[0,1]
	v_pk_mul_f32 v[36:37], v[14:15], v[28:29] op_sel:[0,1] op_sel_hi:[1,0]
	v_pk_mul_f32 v[160:161], v[130:131], s[24:25]
	v_pk_fma_f32 v[48:49], v[6:7], v[44:45], v[48:49] op_sel_hi:[0,1,1]
	v_pk_fma_f32 v[130:131], v[130:131], s[22:23], v[160:161] op_sel:[0,0,1] op_sel_hi:[1,0,0]
	v_pk_add_f32 v[160:161], v[144:145], v[162:163]
	v_pk_add_f32 v[144:145], v[144:145], v[162:163] neg_lo:[0,1] neg_hi:[0,1]
	v_pk_mul_f32 v[52:53], v[14:15], v[44:45] op_sel:[0,1] op_sel_hi:[1,0]
	v_pk_mul_f32 v[162:163], v[144:145], s[40:41]
	v_pk_fma_f32 v[64:65], v[6:7], v[60:61], v[64:65] op_sel_hi:[0,1,1]
	v_pk_fma_f32 v[144:145], v[144:145], s[38:39], v[162:163] op_sel:[0,0,1] op_sel_hi:[1,0,0]
	v_pk_add_f32 v[162:163], v[148:149], v[164:165]
	v_pk_add_f32 v[148:149], v[148:149], v[164:165] neg_lo:[0,1] neg_hi:[0,1]
	v_pk_mul_f32 v[68:69], v[14:15], v[60:61] op_sel:[0,1] op_sel_hi:[1,0]
	v_pk_mul_f32 v[164:165], v[148:149], s[44:45]
	v_pk_fma_f32 v[80:81], v[6:7], v[76:77], v[80:81] op_sel_hi:[0,1,1]
	v_pk_fma_f32 v[148:149], v[148:149], s[50:51], v[164:165] op_sel:[0,0,1] op_sel_hi:[1,0,0]
	v_pk_add_f32 v[164:165], v[150:151], v[166:167]
	v_pk_add_f32 v[166:167], v[150:151], v[166:167] neg_lo:[0,1] neg_hi:[0,1]
	v_pk_mul_f32 v[84:85], v[14:15], v[76:77] op_sel:[0,1] op_sel_hi:[1,0]
	v_pk_add_f32 v[150:151], v[152:153], v[168:169]
	v_pk_add_f32 v[152:153], v[152:153], v[168:169] neg_lo:[0,1] neg_hi:[0,1]
	v_pk_fma_f32 v[96:97], v[6:7], v[92:93], v[96:97] op_sel_hi:[0,1,1]
	v_pk_mul_f32 v[168:169], v[152:153], s[44:45]
	v_pk_mul_f32 v[100:101], v[14:15], v[92:93] op_sel:[0,1] op_sel_hi:[1,0]
	v_pk_fma_f32 v[152:153], v[152:153], s[50:51], v[168:169] op_sel:[0,0,1] op_sel_hi:[1,0,0] neg_lo:[1,0,0] neg_hi:[1,0,0]
	v_pk_add_f32 v[168:169], v[154:155], v[170:171]
	v_pk_add_f32 v[154:155], v[154:155], v[170:171] neg_lo:[0,1] neg_hi:[0,1]
	v_pk_fma_f32 v[112:113], v[6:7], v[108:109], v[112:113] op_sel_hi:[0,1,1]
	v_pk_mul_f32 v[170:171], v[154:155], s[40:41]
	v_pk_mul_f32 v[116:117], v[14:15], v[108:109] op_sel:[0,1] op_sel_hi:[1,0]
	v_pk_fma_f32 v[154:155], v[154:155], s[38:39], v[170:171] op_sel:[0,0,1] op_sel_hi:[1,0,0] neg_lo:[1,0,0] neg_hi:[1,0,0]
	v_pk_add_f32 v[170:171], v[156:157], v[172:173]
	v_pk_add_f32 v[156:157], v[156:157], v[172:173] neg_lo:[0,1] neg_hi:[0,1]
	v_pk_fma_f32 v[20:21], v[8:9], v[12:13], v[20:21] op_sel_hi:[0,1,1]
	v_pk_mul_f32 v[172:173], v[156:157], s[24:25]
	v_pk_mul_f32 v[24:25], v[12:13], v[22:23] op_sel:[1,0] op_sel_hi:[0,1]
	v_pk_fma_f32 v[156:157], v[156:157], s[22:23], v[172:173] op_sel:[0,0,1] op_sel_hi:[1,0,0] neg_lo:[1,0,0] neg_hi:[1,0,0]
	v_pk_add_f32 v[172:173], v[208:209], v[194:195]
	v_pk_add_f32 v[194:195], v[208:209], v[194:195] neg_lo:[0,1] neg_hi:[0,1]
	v_pk_add_f32 v[208:209], v[210:211], v[180:181]
	v_pk_add_f32 v[180:181], v[210:211], v[180:181] neg_lo:[0,1] neg_hi:[0,1]
	v_pk_fma_f32 v[36:37], v[8:9], v[28:29], v[36:37] op_sel_hi:[0,1,1]
	v_pk_mul_f32 v[210:211], v[180:181], s[40:41]
	v_pk_mul_f32 v[40:41], v[22:23], v[28:29] op_sel:[0,1] op_sel_hi:[1,0]
	v_pk_fma_f32 v[180:181], v[180:181], s[38:39], v[210:211] op_sel:[0,0,1] op_sel_hi:[1,0,0]
	v_pk_add_f32 v[210:211], v[174:175], v[198:199]
	v_pk_add_f32 v[198:199], v[174:175], v[198:199] neg_lo:[0,1] neg_hi:[0,1]
	v_pk_fma_f32 v[52:53], v[8:9], v[44:45], v[52:53] op_sel_hi:[0,1,1]
	v_pk_add_f32 v[174:175], v[192:193], v[204:205]
	v_pk_add_f32 v[192:193], v[192:193], v[204:205] neg_lo:[0,1] neg_hi:[0,1]
	v_pk_mul_f32 v[56:57], v[22:23], v[44:45] op_sel:[0,1] op_sel_hi:[1,0]
	v_pk_mul_f32 v[204:205], v[192:193], s[40:41]
	v_pk_fma_f32 v[68:69], v[8:9], v[60:61], v[68:69] op_sel_hi:[0,1,1]
	v_pk_fma_f32 v[192:193], v[192:193], s[38:39], v[204:205] op_sel:[0,0,1] op_sel_hi:[1,0,0] neg_lo:[1,0,0] neg_hi:[1,0,0]
	v_pk_add_f32 v[204:205], v[188:189], v[196:197] op_sel:[0,1] op_sel_hi:[1,0] neg_hi:[0,1]
	v_pk_add_f32 v[188:189], v[188:189], v[196:197] op_sel:[0,1] op_sel_hi:[1,0] neg_lo:[0,1]
	v_pk_add_f32 v[196:197], v[158:159], v[182:183]
	v_pk_add_f32 v[158:159], v[158:159], v[182:183] neg_lo:[0,1] neg_hi:[0,1]
	v_pk_mul_f32 v[72:73], v[22:23], v[60:61] op_sel:[0,1] op_sel_hi:[1,0]
	v_pk_mul_f32 v[182:183], v[158:159], s[40:41]
	v_pk_fma_f32 v[84:85], v[8:9], v[76:77], v[84:85] op_sel_hi:[0,1,1]
	v_pk_fma_f32 v[158:159], v[158:159], s[38:39], v[182:183] op_sel:[0,0,1] op_sel_hi:[1,0,0]
	v_pk_add_f32 v[182:183], v[176:177], v[184:185]
	v_pk_add_f32 v[184:185], v[176:177], v[184:185] neg_lo:[0,1] neg_hi:[0,1]
	v_pk_mul_f32 v[88:89], v[22:23], v[76:77] op_sel:[0,1] op_sel_hi:[1,0]
	v_pk_add_f32 v[176:177], v[178:179], v[186:187]
	v_pk_add_f32 v[178:179], v[178:179], v[186:187] neg_lo:[0,1] neg_hi:[0,1]
	v_pk_fma_f32 v[100:101], v[8:9], v[92:93], v[100:101] op_sel_hi:[0,1,1]
	v_pk_mul_f32 v[186:187], v[178:179], s[40:41]
	v_pk_mul_f32 v[104:105], v[22:23], v[92:93] op_sel:[0,1] op_sel_hi:[1,0]
	v_pk_fma_f32 v[178:179], v[178:179], s[38:39], v[186:187] op_sel:[0,0,1] op_sel_hi:[1,0,0] neg_lo:[1,0,0] neg_hi:[1,0,0]
	v_pk_add_f32 v[186:187], v[206:207], v[164:165]
	v_pk_add_f32 v[164:165], v[206:207], v[164:165] neg_lo:[0,1] neg_hi:[0,1]
	v_pk_add_f32 v[206:207], v[190:191], v[150:151]
	v_pk_add_f32 v[150:151], v[190:191], v[150:151] neg_lo:[0,1] neg_hi:[0,1]
	v_pk_fma_f32 v[116:117], v[8:9], v[108:109], v[116:117] op_sel_hi:[0,1,1]
	v_pk_mul_f32 v[190:191], v[150:151], s[40:41]
	v_pk_mul_f32 v[120:121], v[22:23], v[108:109] op_sel:[0,1] op_sel_hi:[1,0]
	v_pk_fma_f32 v[150:151], v[150:151], s[38:39], v[190:191] op_sel:[0,0,1] op_sel_hi:[1,0,0]
	v_pk_add_f32 v[190:191], v[160:161], v[168:169]
	v_pk_add_f32 v[168:169], v[160:161], v[168:169] neg_lo:[0,1] neg_hi:[0,1]
	v_xor_b32_e32 v26, 0x80000000, v19
	v_pk_add_f32 v[160:161], v[162:163], v[170:171]
	v_pk_add_f32 v[162:163], v[162:163], v[170:171] neg_lo:[0,1] neg_hi:[0,1]
	v_xor_b32_e32 v30, 0x80000000, v21
	v_pk_mul_f32 v[170:171], v[162:163], s[40:41]
	v_pk_fma_f32 v[24:25], v[12:13], v[10:11], v[24:25] op_sel_hi:[1,0,1]
	v_pk_fma_f32 v[162:163], v[162:163], s[38:39], v[170:171] op_sel:[0,0,1] op_sel_hi:[1,0,0] neg_lo:[1,0,0] neg_hi:[1,0,0]
	v_pk_add_f32 v[170:171], v[128:129], v[166:167] op_sel:[0,1] op_sel_hi:[1,0] neg_hi:[0,1]
	v_pk_add_f32 v[128:129], v[128:129], v[166:167] op_sel:[0,1] op_sel_hi:[1,0] neg_lo:[0,1]
	v_pk_add_f32 v[166:167], v[130:131], v[152:153]
	v_pk_add_f32 v[130:131], v[130:131], v[152:153] neg_lo:[0,1] neg_hi:[0,1]
	v_pk_fma_f32 v[40:41], v[10:11], v[28:29], v[40:41] op_sel_hi:[0,1,1]
	v_pk_mul_f32 v[152:153], v[130:131], s[40:41]
	v_pk_fma_f32 v[56:57], v[10:11], v[44:45], v[56:57] op_sel_hi:[0,1,1]
	v_pk_fma_f32 v[130:131], v[130:131], s[38:39], v[152:153] op_sel:[0,0,1] op_sel_hi:[1,0,0]
	v_pk_add_f32 v[152:153], v[144:145], v[154:155]
	v_pk_add_f32 v[154:155], v[144:145], v[154:155] neg_lo:[0,1] neg_hi:[0,1]
	v_pk_fma_f32 v[72:73], v[10:11], v[60:61], v[72:73] op_sel_hi:[0,1,1]
	v_pk_add_f32 v[144:145], v[148:149], v[156:157]
	v_pk_add_f32 v[148:149], v[148:149], v[156:157] neg_lo:[0,1] neg_hi:[0,1]
	v_pk_fma_f32 v[88:89], v[10:11], v[76:77], v[88:89] op_sel_hi:[0,1,1]
	v_pk_mul_f32 v[156:157], v[148:149], s[40:41]
	v_pk_fma_f32 v[104:105], v[10:11], v[92:93], v[104:105] op_sel_hi:[0,1,1]
	v_pk_fma_f32 v[148:149], v[148:149], s[38:39], v[156:157] op_sel:[0,0,1] op_sel_hi:[1,0,0] neg_lo:[1,0,0] neg_hi:[1,0,0]
	v_pk_add_f32 v[156:157], v[172:173], v[210:211]
	v_pk_add_f32 v[172:173], v[172:173], v[210:211] neg_lo:[0,1] neg_hi:[0,1]
	v_pk_add_f32 v[210:211], v[208:209], v[174:175]
	v_pk_add_f32 v[208:209], v[208:209], v[174:175] neg_lo:[0,1] neg_hi:[0,1]
	v_pk_fma_f32 v[120:121], v[10:11], v[108:109], v[120:121] op_sel_hi:[0,1,1]
	v_pk_add_f32 v[174:175], v[194:195], v[198:199] op_sel:[0,1] op_sel_hi:[1,0] neg_hi:[0,1]
	v_pk_add_f32 v[194:195], v[194:195], v[198:199] op_sel:[0,1] op_sel_hi:[1,0] neg_lo:[0,1]
	v_pk_add_f32 v[198:199], v[180:181], v[192:193]
	v_pk_add_f32 v[192:193], v[180:181], v[192:193] neg_lo:[0,1] neg_hi:[0,1]
	v_mov_b32_e32 v27, v19
	v_pk_add_f32 v[180:181], v[204:205], v[182:183]
	v_pk_add_f32 v[182:183], v[204:205], v[182:183] neg_lo:[0,1] neg_hi:[0,1]
	v_pk_add_f32 v[204:205], v[196:197], v[176:177]
	v_pk_add_f32 v[196:197], v[196:197], v[176:177] neg_lo:[0,1] neg_hi:[0,1]
	v_mov_b32_e32 v31, v21
	v_pk_add_f32 v[176:177], v[188:189], v[184:185] op_sel:[0,1] op_sel_hi:[1,0] neg_hi:[0,1]
	v_pk_add_f32 v[184:185], v[188:189], v[184:185] op_sel:[0,1] op_sel_hi:[1,0] neg_lo:[0,1]
	v_pk_add_f32 v[188:189], v[158:159], v[178:179]
	v_pk_add_f32 v[178:179], v[158:159], v[178:179] neg_lo:[0,1] neg_hi:[0,1]
	v_xor_b32_e32 v34, 0x80000000, v25
	v_pk_add_f32 v[158:159], v[186:187], v[190:191]
	v_pk_add_f32 v[186:187], v[186:187], v[190:191] neg_lo:[0,1] neg_hi:[0,1]
	v_pk_add_f32 v[190:191], v[206:207], v[160:161]
	v_pk_add_f32 v[206:207], v[206:207], v[160:161] neg_lo:[0,1] neg_hi:[0,1]
	v_xor_b32_e32 v38, 0x80000000, v29
	v_pk_add_f32 v[160:161], v[164:165], v[168:169] op_sel:[0,1] op_sel_hi:[1,0] neg_hi:[0,1]
	v_pk_add_f32 v[164:165], v[164:165], v[168:169] op_sel:[0,1] op_sel_hi:[1,0] neg_lo:[0,1]
	v_pk_add_f32 v[168:169], v[150:151], v[162:163]
	v_pk_add_f32 v[162:163], v[150:151], v[162:163] neg_lo:[0,1] neg_hi:[0,1]
	v_xor_b32_e32 v42, 0x80000000, v33
	v_pk_add_f32 v[150:151], v[170:171], v[152:153]
	v_pk_add_f32 v[152:153], v[170:171], v[152:153] neg_lo:[0,1] neg_hi:[0,1]
	v_pk_add_f32 v[170:171], v[166:167], v[144:145]
	v_pk_add_f32 v[166:167], v[166:167], v[144:145] neg_lo:[0,1] neg_hi:[0,1]
	v_xor_b32_e32 v46, 0x80000000, v37
	v_pk_add_f32 v[144:145], v[128:129], v[154:155] op_sel:[0,1] op_sel_hi:[1,0] neg_hi:[0,1]
	v_pk_add_f32 v[128:129], v[128:129], v[154:155] op_sel:[0,1] op_sel_hi:[1,0] neg_lo:[0,1]
	v_pk_add_f32 v[154:155], v[130:131], v[148:149]
	v_pk_add_f32 v[130:131], v[130:131], v[148:149] neg_lo:[0,1] neg_hi:[0,1]
	v_mov_b32_e32 v35, v25
	v_xor_b32_e32 v149, 0x80000000, v130
	v_mov_b32_e32 v148, v131
	v_pk_add_f32 v[130:131], v[156:157], v[210:211]
	v_pk_add_f32 v[156:157], v[156:157], v[210:211] neg_lo:[0,1] neg_hi:[0,1]
	v_pk_add_f32 v[210:211], v[172:173], v[208:209] op_sel:[0,1] op_sel_hi:[1,0] neg_hi:[0,1]
	v_pk_add_f32 v[172:173], v[172:173], v[208:209] op_sel:[0,1] op_sel_hi:[1,0] neg_lo:[0,1]
	v_pk_add_f32 v[208:209], v[174:175], v[198:199]
	v_pk_add_f32 v[174:175], v[174:175], v[198:199] neg_lo:[0,1] neg_hi:[0,1]
	v_pk_add_f32 v[198:199], v[194:195], v[192:193] op_sel:[0,1] op_sel_hi:[1,0] neg_hi:[0,1]
	v_pk_add_f32 v[192:193], v[194:195], v[192:193] op_sel:[0,1] op_sel_hi:[1,0] neg_lo:[0,1]
	v_pk_add_f32 v[194:195], v[180:181], v[204:205]
	v_pk_add_f32 v[180:181], v[180:181], v[204:205] neg_lo:[0,1] neg_hi:[0,1]
	v_pk_add_f32 v[204:205], v[182:183], v[196:197] op_sel:[0,1] op_sel_hi:[1,0] neg_hi:[0,1]
	v_pk_add_f32 v[182:183], v[182:183], v[196:197] op_sel:[0,1] op_sel_hi:[1,0] neg_lo:[0,1]
	v_pk_add_f32 v[196:197], v[176:177], v[188:189]
	v_pk_add_f32 v[176:177], v[176:177], v[188:189] neg_lo:[0,1] neg_hi:[0,1]
	v_pk_add_f32 v[188:189], v[184:185], v[178:179] op_sel:[0,1] op_sel_hi:[1,0] neg_hi:[0,1]
	v_pk_add_f32 v[178:179], v[184:185], v[178:179] op_sel:[0,1] op_sel_hi:[1,0] neg_lo:[0,1]
	v_pk_add_f32 v[184:185], v[158:159], v[190:191]
	v_pk_add_f32 v[158:159], v[158:159], v[190:191] neg_lo:[0,1] neg_hi:[0,1]
	v_pk_mul_f32 v[4:5], v[4:5], v[184:185] op_sel:[0,1] op_sel_hi:[1,0]
	v_pk_add_f32 v[190:191], v[186:187], v[206:207] op_sel:[0,1] op_sel_hi:[1,0] neg_hi:[0,1]
	v_pk_add_f32 v[186:187], v[186:187], v[206:207] op_sel:[0,1] op_sel_hi:[1,0] neg_lo:[0,1]
	v_pk_add_f32 v[206:207], v[160:161], v[168:169]
	v_pk_add_f32 v[160:161], v[160:161], v[168:169] neg_lo:[0,1] neg_hi:[0,1]
	v_pk_add_f32 v[168:169], v[164:165], v[162:163] op_sel:[0,1] op_sel_hi:[1,0] neg_hi:[0,1]
	v_pk_add_f32 v[162:163], v[164:165], v[162:163] op_sel:[0,1] op_sel_hi:[1,0] neg_lo:[0,1]
	v_pk_add_f32 v[164:165], v[150:151], v[170:171]
	v_pk_fma_f32 v[4:5], v[6:7], v[184:185], v[4:5] op_sel_hi:[0,1,1]
	v_pk_mul_f32 v[6:7], v[14:15], v[194:195] op_sel:[0,1] op_sel_hi:[1,0]
	v_mov_b32_e32 v39, v29
	v_pk_fma_f32 v[6:7], v[8:9], v[194:195], v[6:7] op_sel_hi:[0,1,1]
	v_pk_mul_f32 v[8:9], v[22:23], v[164:165] op_sel:[0,1] op_sel_hi:[1,0]
	v_mov_b32_e32 v43, v33
	v_pk_fma_f32 v[8:9], v[10:11], v[164:165], v[8:9] op_sel_hi:[0,1,1]
	v_pk_mul_f32 v[10:11], v[16:17], v[208:209] op_sel:[0,1] op_sel_hi:[1,0]
	v_mov_b32_e32 v47, v37
	v_pk_add_f32 v[150:151], v[150:151], v[170:171] neg_lo:[0,1] neg_hi:[0,1]
	v_pk_add_f32 v[170:171], v[152:153], v[166:167] op_sel:[0,1] op_sel_hi:[1,0] neg_hi:[0,1]
	v_pk_add_f32 v[152:153], v[152:153], v[166:167] op_sel:[0,1] op_sel_hi:[1,0] neg_lo:[0,1]
	v_pk_add_f32 v[166:167], v[144:145], v[154:155]
	v_pk_fma_f32 v[10:11], v[12:13], v[208:209], v[10:11] op_sel_hi:[0,1,1]
	v_pk_mul_f32 v[12:13], v[26:27], v[206:207] op_sel:[0,1] op_sel_hi:[1,0]
	v_pk_mul_f32 v[14:15], v[30:31], v[196:197] op_sel:[0,1] op_sel_hi:[1,0]
	v_xor_b32_e32 v50, 0x80000000, v41
	v_xor_b32_e32 v54, 0x80000000, v45
	v_xor_b32_e32 v58, 0x80000000, v49
	v_xor_b32_e32 v62, 0x80000000, v53
	v_xor_b32_e32 v66, 0x80000000, v57
	v_xor_b32_e32 v70, 0x80000000, v61
	v_xor_b32_e32 v74, 0x80000000, v65
	v_mov_b32_e32 v51, v41
	v_mov_b32_e32 v55, v45
	v_mov_b32_e32 v59, v49
	v_mov_b32_e32 v63, v53
	v_mov_b32_e32 v67, v57
	v_mov_b32_e32 v71, v61
	v_mov_b32_e32 v75, v65
	v_pk_add_f32 v[144:145], v[144:145], v[154:155] neg_lo:[0,1] neg_hi:[0,1]
	v_pk_add_f32 v[154:155], v[128:129], v[148:149]
	v_pk_fma_f32 v[12:13], v[18:19], v[206:207], v[12:13] op_sel_hi:[0,1,1]
	v_pk_fma_f32 v[14:15], v[20:21], v[196:197], v[14:15] op_sel_hi:[0,1,1]
	v_pk_mul_f32 v[16:17], v[34:35], v[166:167] op_sel:[0,1] op_sel_hi:[1,0]
	v_pk_mul_f32 v[18:19], v[38:39], v[210:211] op_sel:[0,1] op_sel_hi:[1,0]
	v_pk_mul_f32 v[20:21], v[42:43], v[190:191] op_sel:[0,1] op_sel_hi:[1,0]
	v_pk_mul_f32 v[22:23], v[46:47], v[204:205] op_sel:[0,1] op_sel_hi:[1,0]
	v_xor_b32_e32 v78, 0x80000000, v69
	v_xor_b32_e32 v82, 0x80000000, v73
	v_xor_b32_e32 v86, 0x80000000, v77
	v_xor_b32_e32 v90, 0x80000000, v81
	v_xor_b32_e32 v94, 0x80000000, v85
	v_xor_b32_e32 v98, 0x80000000, v89
	v_xor_b32_e32 v102, 0x80000000, v93
	v_xor_b32_e32 v106, 0x80000000, v97
	v_xor_b32_e32 v110, 0x80000000, v101
	v_xor_b32_e32 v114, 0x80000000, v105
	v_xor_b32_e32 v118, 0x80000000, v109
	v_xor_b32_e32 v122, 0x80000000, v113
	v_xor_b32_e32 v124, 0x80000000, v117
	v_xor_b32_e32 v126, 0x80000000, v121
	v_mov_b32_e32 v79, v69
	v_mov_b32_e32 v83, v73
	v_mov_b32_e32 v87, v77
	v_mov_b32_e32 v91, v81
	v_mov_b32_e32 v95, v85
	v_mov_b32_e32 v99, v89
	v_mov_b32_e32 v103, v93
	v_mov_b32_e32 v107, v97
	v_mov_b32_e32 v111, v101
	v_mov_b32_e32 v115, v105
	v_mov_b32_e32 v119, v109
	v_mov_b32_e32 v123, v113
	v_mov_b32_e32 v125, v117
	v_mov_b32_e32 v127, v121
	v_pk_add_f32 v[128:129], v[128:129], v[148:149] neg_lo:[0,1] neg_hi:[0,1]
	v_pk_fma_f32 v[16:17], v[24:25], v[166:167], v[16:17] op_sel_hi:[0,1,1]
	v_pk_fma_f32 v[18:19], v[28:29], v[210:211], v[18:19] op_sel_hi:[0,1,1]
	v_pk_fma_f32 v[20:21], v[32:33], v[190:191], v[20:21] op_sel_hi:[0,1,1]
	v_pk_fma_f32 v[22:23], v[36:37], v[204:205], v[22:23] op_sel_hi:[0,1,1]
	v_pk_mul_f32 v[24:25], v[50:51], v[170:171] op_sel:[0,1] op_sel_hi:[1,0]
	v_pk_mul_f32 v[26:27], v[54:55], v[198:199] op_sel:[0,1] op_sel_hi:[1,0]
	v_pk_mul_f32 v[28:29], v[58:59], v[168:169] op_sel:[0,1] op_sel_hi:[1,0]
	v_pk_mul_f32 v[30:31], v[62:63], v[188:189] op_sel:[0,1] op_sel_hi:[1,0]
	v_pk_mul_f32 v[32:33], v[66:67], v[154:155] op_sel:[0,1] op_sel_hi:[1,0]
	v_pk_mul_f32 v[34:35], v[70:71], v[156:157] op_sel:[0,1] op_sel_hi:[1,0]
	v_pk_mul_f32 v[36:37], v[74:75], v[158:159] op_sel:[0,1] op_sel_hi:[1,0]
	v_pk_fma_f32 v[24:25], v[40:41], v[170:171], v[24:25] op_sel_hi:[0,1,1]
	v_pk_fma_f32 v[26:27], v[44:45], v[198:199], v[26:27] op_sel_hi:[0,1,1]
	v_pk_fma_f32 v[28:29], v[48:49], v[168:169], v[28:29] op_sel_hi:[0,1,1]
	v_pk_fma_f32 v[30:31], v[52:53], v[188:189], v[30:31] op_sel_hi:[0,1,1]
	v_pk_fma_f32 v[32:33], v[56:57], v[154:155], v[32:33] op_sel_hi:[0,1,1]
	v_pk_fma_f32 v[34:35], v[60:61], v[156:157], v[34:35] op_sel_hi:[0,1,1]
	v_pk_fma_f32 v[36:37], v[64:65], v[158:159], v[36:37] op_sel_hi:[0,1,1]
	v_pk_mul_f32 v[38:39], v[78:79], v[180:181] op_sel:[0,1] op_sel_hi:[1,0]
	v_pk_mul_f32 v[40:41], v[82:83], v[150:151] op_sel:[0,1] op_sel_hi:[1,0]
	v_pk_mul_f32 v[42:43], v[86:87], v[174:175] op_sel:[0,1] op_sel_hi:[1,0]
	v_pk_mul_f32 v[44:45], v[90:91], v[160:161] op_sel:[0,1] op_sel_hi:[1,0]
	v_pk_mul_f32 v[46:47], v[94:95], v[176:177] op_sel:[0,1] op_sel_hi:[1,0]
	v_pk_mul_f32 v[48:49], v[98:99], v[144:145] op_sel:[0,1] op_sel_hi:[1,0]
	v_pk_mul_f32 v[50:51], v[102:103], v[172:173] op_sel:[0,1] op_sel_hi:[1,0]
	v_pk_mul_f32 v[52:53], v[106:107], v[186:187] op_sel:[0,1] op_sel_hi:[1,0]
	v_pk_mul_f32 v[54:55], v[110:111], v[182:183] op_sel:[0,1] op_sel_hi:[1,0]
	v_pk_mul_f32 v[56:57], v[114:115], v[152:153] op_sel:[0,1] op_sel_hi:[1,0]
	v_pk_mul_f32 v[58:59], v[118:119], v[192:193] op_sel:[0,1] op_sel_hi:[1,0]
	v_pk_mul_f32 v[60:61], v[122:123], v[162:163] op_sel:[0,1] op_sel_hi:[1,0]
	v_pk_mul_f32 v[62:63], v[124:125], v[178:179] op_sel:[0,1] op_sel_hi:[1,0]
	v_pk_mul_f32 v[64:65], v[126:127], v[128:129] op_sel:[0,1] op_sel_hi:[1,0]
	v_pk_fma_f32 v[38:39], v[68:69], v[180:181], v[38:39] op_sel_hi:[0,1,1]
	v_pk_fma_f32 v[40:41], v[72:73], v[150:151], v[40:41] op_sel_hi:[0,1,1]
	v_pk_fma_f32 v[42:43], v[76:77], v[174:175], v[42:43] op_sel_hi:[0,1,1]
	v_pk_fma_f32 v[44:45], v[80:81], v[160:161], v[44:45] op_sel_hi:[0,1,1]
	v_pk_fma_f32 v[46:47], v[84:85], v[176:177], v[46:47] op_sel_hi:[0,1,1]
	v_pk_fma_f32 v[48:49], v[88:89], v[144:145], v[48:49] op_sel_hi:[0,1,1]
	v_pk_fma_f32 v[50:51], v[92:93], v[172:173], v[50:51] op_sel_hi:[0,1,1]
	v_pk_fma_f32 v[52:53], v[96:97], v[186:187], v[52:53] op_sel_hi:[0,1,1]
	v_pk_fma_f32 v[54:55], v[100:101], v[182:183], v[54:55] op_sel_hi:[0,1,1]
	v_pk_fma_f32 v[56:57], v[104:105], v[152:153], v[56:57] op_sel_hi:[0,1,1]
	v_pk_fma_f32 v[58:59], v[108:109], v[192:193], v[58:59] op_sel_hi:[0,1,1]
	v_pk_fma_f32 v[60:61], v[112:113], v[162:163], v[60:61] op_sel_hi:[0,1,1]
	v_pk_fma_f32 v[62:63], v[116:117], v[178:179], v[62:63] op_sel_hi:[0,1,1]
	v_pk_fma_f32 v[64:65], v[120:121], v[128:129], v[64:65] op_sel_hi:[0,1,1]
	ds_write_b64 v2, v[130:131]
	ds_write_b64 v2, v[34:35] offset:2112
	ds_write_b64 v2, v[18:19] offset:4224
	ds_write_b64 v2, v[50:51] offset:6336
	ds_write_b64 v2, v[10:11] offset:8448
	ds_write_b64 v2, v[42:43] offset:10560
	ds_write_b64 v2, v[26:27] offset:12672
	ds_write_b64 v2, v[58:59] offset:14784
	ds_write_b64 v2, v[6:7] offset:16896
	ds_write_b64 v2, v[38:39] offset:19008
	ds_write_b64 v2, v[22:23] offset:21120
	ds_write_b64 v2, v[54:55] offset:23232
	ds_write_b64 v2, v[14:15] offset:25344
	ds_write_b64 v2, v[46:47] offset:27456
	ds_write_b64 v2, v[30:31] offset:29568
	ds_write_b64 v2, v[62:63] offset:31680
	ds_write_b64 v2, v[4:5] offset:33792
	ds_write_b64 v2, v[36:37] offset:35904
	ds_write_b64 v2, v[20:21] offset:38016
	ds_write_b64 v2, v[52:53] offset:40128
	ds_write_b64 v2, v[12:13] offset:42240
	ds_write_b64 v2, v[44:45] offset:44352
	ds_write_b64 v2, v[28:29] offset:46464
	ds_write_b64 v2, v[60:61] offset:48576
	ds_write_b64 v2, v[8:9] offset:50688
	ds_write_b64 v2, v[40:41] offset:52800
	ds_write_b64 v2, v[24:25] offset:54912
	ds_write_b64 v2, v[56:57] offset:57024
	ds_write_b64 v2, v[16:17] offset:59136
	ds_write_b64 v2, v[48:49] offset:61248
	ds_write_b64 v2, v[32:33] offset:63360
	ds_write_b64 v2, v[64:65] offset:65472
	v_mov_b32_e32 v2, v142
	s_waitcnt lgkmcnt(0)
	s_barrier
	s_nop 0
	v_and_b32_e32 v5, 15, v2
	v_cvt_f32_ubyte0_e32 v4, v5
	v_mul_f32_e32 v6, 0x3b800000, v4
	v_sin_f32_e32 v4, v6
	v_cos_f32_e32 v6, v6
	v_lshlrev_b32_e32 v64, 3, v5
	v_lshlrev_b32_e32 v2, 4, v2
	v_xor_b32_e32 v7, 0x80000000, v4
	v_mov_b32_e32 v5, v7
	v_pk_mul_f32 v[8:9], v[6:7], v[4:5] op_sel:[1,0] op_sel_hi:[0,1]
	v_pk_fma_f32 v[8:9], v[6:7], v[6:7], v[8:9] op_sel_hi:[1,0,1]
	v_and_b32_e32 v2, 0xffffff00, v2
	v_xor_b32_e32 v14, 0x80000000, v9
	v_mov_b32_e32 v15, v9
	v_pk_mul_f32 v[12:13], v[8:9], v[14:15] op_sel:[1,0] op_sel_hi:[0,1]
	v_pk_fma_f32 v[12:13], v[8:9], v[8:9], v[12:13] op_sel_hi:[1,0,1]
	v_pk_mul_f32 v[10:11], v[4:5], v[8:9] op_sel:[0,1] op_sel_hi:[1,0]
	v_xor_b32_e32 v16, 0x80000000, v13
	v_mov_b32_e32 v17, v13
	v_pk_mul_f32 v[32:33], v[12:13], v[16:17] op_sel:[1,0] op_sel_hi:[0,1]
	v_pk_fma_f32 v[32:33], v[12:13], v[12:13], v[32:33] op_sel_hi:[1,0,1]
	v_pk_mul_f32 v[18:19], v[4:5], v[12:13] op_sel:[0,1] op_sel_hi:[1,0]
	v_pk_mul_f32 v[48:49], v[16:17], v[32:33] op_sel:[0,1] op_sel_hi:[1,0]
	v_pk_mul_f32 v[36:37], v[4:5], v[32:33] op_sel:[0,1] op_sel_hi:[1,0]
	v_pk_fma_f32 v[48:49], v[12:13], v[32:33], v[48:49] op_sel_hi:[0,1,1]
	v_pk_mul_f32 v[52:53], v[4:5], v[48:49] op_sel:[0,1] op_sel_hi:[1,0]
	v_pk_fma_f32 v[10:11], v[6:7], v[8:9], v[10:11] op_sel_hi:[0,1,1]
	v_pk_fma_f32 v[18:19], v[6:7], v[12:13], v[18:19] op_sel_hi:[0,1,1]
	v_pk_fma_f32 v[36:37], v[6:7], v[32:33], v[36:37] op_sel_hi:[0,1,1]
	v_pk_fma_f32 v[52:53], v[6:7], v[48:49], v[52:53] op_sel_hi:[0,1,1]
	v_lshlrev_b32_e32 v7, 3, v2
	v_add3_u32 v7, 0, v64, v7
	v_ashrrev_i32_e32 v64, 2, v2
	v_add_u32_e32 v106, v7, v64
	ds_read2_b64 v[64:67], v106 offset1:16
	ds_read2_b64 v[68:71], v106 offset0:33 offset1:49
	ds_read2_b64 v[72:75], v106 offset0:66 offset1:82
	ds_read2_b64 v[76:79], v106 offset0:132 offset1:148
	ds_read2_b64 v[80:83], v106 offset0:99 offset1:115
	ds_read2_b64 v[84:87], v106 offset0:165 offset1:181
	ds_read2_b64 v[88:91], v106 offset0:198 offset1:214
	ds_read2_b64 v[92:95], v106 offset0:231 offset1:247
	s_waitcnt lgkmcnt(4)
	v_pk_add_f32 v[96:97], v[64:65], v[76:77]
	v_pk_add_f32 v[64:65], v[64:65], v[76:77] neg_lo:[0,1] neg_hi:[0,1]
	v_pk_add_f32 v[76:77], v[66:67], v[78:79]
	v_pk_add_f32 v[66:67], v[66:67], v[78:79] neg_lo:[0,1] neg_hi:[0,1]
	s_waitcnt lgkmcnt(1)
	v_pk_add_f32 v[98:99], v[74:75], v[90:91]
	v_pk_mul_f32 v[78:79], v[66:67], s[24:25]
	v_pk_add_f32 v[74:75], v[74:75], v[90:91] neg_lo:[0,1] neg_hi:[0,1]
	v_pk_fma_f32 v[66:67], v[66:67], s[22:23], v[78:79] op_sel:[0,0,1] op_sel_hi:[1,0,0]
	v_pk_add_f32 v[78:79], v[68:69], v[84:85]
	v_pk_add_f32 v[68:69], v[68:69], v[84:85] neg_lo:[0,1] neg_hi:[0,1]
	v_pk_mul_f32 v[90:91], v[74:75], s[44:45]
	v_pk_mul_f32 v[84:85], v[68:69], s[40:41]
	v_pk_fma_f32 v[74:75], v[74:75], s[50:51], v[90:91] op_sel:[0,0,1] op_sel_hi:[1,0,0] neg_lo:[1,0,0] neg_hi:[1,0,0]
	v_pk_fma_f32 v[68:69], v[68:69], s[38:39], v[84:85] op_sel:[0,0,1] op_sel_hi:[1,0,0]
	v_pk_add_f32 v[84:85], v[70:71], v[86:87]
	v_pk_add_f32 v[70:71], v[70:71], v[86:87] neg_lo:[0,1] neg_hi:[0,1]
	s_waitcnt lgkmcnt(0)
	v_pk_add_f32 v[90:91], v[80:81], v[92:93]
	v_pk_add_f32 v[80:81], v[80:81], v[92:93] neg_lo:[0,1] neg_hi:[0,1]
	v_pk_mul_f32 v[86:87], v[70:71], s[44:45]
	v_pk_mul_f32 v[92:93], v[80:81], s[40:41]
	v_pk_fma_f32 v[70:71], v[70:71], s[50:51], v[86:87] op_sel:[0,0,1] op_sel_hi:[1,0,0]
	v_pk_add_f32 v[86:87], v[72:73], v[88:89]
	v_pk_add_f32 v[88:89], v[72:73], v[88:89] neg_lo:[0,1] neg_hi:[0,1]
	v_pk_fma_f32 v[80:81], v[80:81], s[38:39], v[92:93] op_sel:[0,0,1] op_sel_hi:[1,0,0] neg_lo:[1,0,0] neg_hi:[1,0,0]
	v_pk_add_f32 v[92:93], v[82:83], v[94:95]
	v_pk_add_f32 v[82:83], v[82:83], v[94:95] neg_lo:[0,1] neg_hi:[0,1]
	s_nop 0
	v_pk_mul_f32 v[94:95], v[82:83], s[24:25]
	s_nop 0
	v_pk_fma_f32 v[82:83], v[82:83], s[22:23], v[94:95] op_sel:[0,0,1] op_sel_hi:[1,0,0] neg_lo:[1,0,0] neg_hi:[1,0,0]
	v_pk_add_f32 v[94:95], v[96:97], v[86:87]
	v_pk_add_f32 v[86:87], v[96:97], v[86:87] neg_lo:[0,1] neg_hi:[0,1]
	v_pk_add_f32 v[96:97], v[76:77], v[98:99]
	v_pk_add_f32 v[76:77], v[76:77], v[98:99] neg_lo:[0,1] neg_hi:[0,1]
	v_pk_add_f32 v[100:101], v[84:85], v[92:93]
	v_pk_add_f32 v[84:85], v[84:85], v[92:93] neg_lo:[0,1] neg_hi:[0,1]
	v_pk_add_f32 v[72:73], v[64:65], v[88:89] op_sel:[0,1] op_sel_hi:[1,0] neg_hi:[0,1]
	v_pk_add_f32 v[64:65], v[64:65], v[88:89] op_sel:[0,1] op_sel_hi:[1,0] neg_lo:[0,1]
	v_pk_add_f32 v[88:89], v[66:67], v[74:75]
	v_pk_add_f32 v[66:67], v[66:67], v[74:75] neg_lo:[0,1] neg_hi:[0,1]
	v_pk_mul_f32 v[98:99], v[76:77], s[40:41]
	v_pk_mul_f32 v[92:93], v[84:85], s[40:41]
	v_pk_mul_f32 v[74:75], v[66:67], s[40:41]
	v_pk_fma_f32 v[76:77], v[76:77], s[38:39], v[98:99] op_sel:[0,0,1] op_sel_hi:[1,0,0]
	v_pk_add_f32 v[98:99], v[78:79], v[90:91]
	v_pk_add_f32 v[90:91], v[78:79], v[90:91] neg_lo:[0,1] neg_hi:[0,1]
	v_pk_fma_f32 v[84:85], v[84:85], s[38:39], v[92:93] op_sel:[0,0,1] op_sel_hi:[1,0,0] neg_lo:[1,0,0] neg_hi:[1,0,0]
	v_pk_fma_f32 v[66:67], v[66:67], s[38:39], v[74:75] op_sel:[0,0,1] op_sel_hi:[1,0,0]
	v_pk_add_f32 v[74:75], v[68:69], v[80:81]
	v_pk_add_f32 v[92:93], v[70:71], v[82:83]
	v_pk_add_f32 v[70:71], v[70:71], v[82:83] neg_lo:[0,1] neg_hi:[0,1]
	v_pk_add_f32 v[68:69], v[68:69], v[80:81] neg_lo:[0,1] neg_hi:[0,1]
	v_pk_mul_f32 v[82:83], v[70:71], s[40:41]
	v_pk_add_f32 v[102:103], v[72:73], v[74:75]
	v_pk_add_f32 v[72:73], v[72:73], v[74:75] neg_lo:[0,1] neg_hi:[0,1]
	v_pk_add_f32 v[74:75], v[88:89], v[92:93]
	v_pk_add_f32 v[92:93], v[88:89], v[92:93] neg_lo:[0,1] neg_hi:[0,1]
	v_xor_b32_e32 v20, 0x80000000, v11
	v_mov_b32_e32 v21, v11
	v_pk_mul_f32 v[24:25], v[14:15], v[12:13] op_sel:[0,1] op_sel_hi:[1,0]
	v_xor_b32_e32 v81, 0x80000000, v68
	v_pk_fma_f32 v[70:71], v[70:71], s[38:39], v[82:83] op_sel:[0,0,1] op_sel_hi:[1,0,0] neg_lo:[1,0,0] neg_hi:[1,0,0]
	v_pk_add_f32 v[78:79], v[86:87], v[90:91] op_sel:[0,1] op_sel_hi:[1,0] neg_hi:[0,1]
	v_pk_add_f32 v[86:87], v[86:87], v[90:91] op_sel:[0,1] op_sel_hi:[1,0] neg_lo:[0,1]
	v_pk_add_f32 v[90:91], v[76:77], v[84:85]
	v_pk_add_f32 v[84:85], v[76:77], v[84:85] neg_lo:[0,1] neg_hi:[0,1]
	v_mov_b32_e32 v80, v69
	v_xor_b32_e32 v22, 0x80000000, v19
	v_mov_b32_e32 v23, v19
	v_pk_fma_f32 v[24:25], v[8:9], v[12:13], v[24:25] op_sel_hi:[0,1,1]
	v_pk_mul_f32 v[28:29], v[12:13], v[20:21] op_sel:[1,0] op_sel_hi:[0,1]
	v_pk_add_f32 v[68:69], v[64:65], v[80:81]
	v_pk_add_f32 v[64:65], v[64:65], v[80:81] neg_lo:[0,1] neg_hi:[0,1]
	v_pk_add_f32 v[80:81], v[66:67], v[70:71]
	v_pk_add_f32 v[70:71], v[66:67], v[70:71] neg_lo:[0,1] neg_hi:[0,1]
	v_pk_add_f32 v[88:89], v[72:73], v[92:93] op_sel:[0,1] op_sel_hi:[1,0] neg_hi:[0,1]
	v_xor_b32_e32 v26, 0x80000000, v25
	v_mov_b32_e32 v27, v25
	v_pk_fma_f32 v[28:29], v[12:13], v[10:11], v[28:29] op_sel_hi:[1,0,1]
	v_pk_add_f32 v[76:77], v[86:87], v[84:85] op_sel:[0,1] op_sel_hi:[1,0] neg_hi:[0,1]
	v_pk_add_f32 v[72:73], v[72:73], v[92:93] op_sel:[0,1] op_sel_hi:[1,0] neg_lo:[0,1]
	v_pk_mul_f32 v[92:93], v[22:23], v[88:89] op_sel:[0,1] op_sel_hi:[1,0]
	v_xor_b32_e32 v30, 0x80000000, v29
	v_mov_b32_e32 v31, v29
	v_pk_add_f32 v[82:83], v[94:95], v[98:99]
	v_pk_add_f32 v[94:95], v[94:95], v[98:99] neg_lo:[0,1] neg_hi:[0,1]
	v_pk_add_f32 v[98:99], v[96:97], v[100:101]
	v_pk_add_f32 v[66:67], v[64:65], v[70:71] op_sel:[0,1] op_sel_hi:[1,0] neg_hi:[0,1]
	v_pk_fma_f32 v[88:89], v[18:19], v[88:89], v[92:93] op_sel_hi:[0,1,1]
	v_pk_mul_f32 v[92:93], v[26:27], v[76:77] op_sel:[0,1] op_sel_hi:[1,0]
	v_xor_b32_e32 v34, 0x80000000, v33
	v_mov_b32_e32 v35, v33
	v_pk_mul_f32 v[40:41], v[14:15], v[32:33] op_sel:[0,1] op_sel_hi:[1,0]
	v_pk_add_f32 v[104:105], v[82:83], v[98:99]
	v_pk_add_f32 v[82:83], v[82:83], v[98:99] neg_lo:[0,1] neg_hi:[0,1]
	v_pk_fma_f32 v[76:77], v[24:25], v[76:77], v[92:93] op_sel_hi:[0,1,1]
	v_pk_mul_f32 v[92:93], v[30:31], v[66:67] op_sel:[0,1] op_sel_hi:[1,0]
	v_xor_b32_e32 v38, 0x80000000, v37
	v_mov_b32_e32 v39, v37
	v_pk_fma_f32 v[40:41], v[8:9], v[32:33], v[40:41] op_sel_hi:[0,1,1]
	v_pk_mul_f32 v[44:45], v[20:21], v[32:33] op_sel:[0,1] op_sel_hi:[1,0]
	v_pk_add_f32 v[84:85], v[86:87], v[84:85] op_sel:[0,1] op_sel_hi:[1,0] neg_lo:[0,1]
	v_pk_add_f32 v[86:87], v[102:103], v[74:75]
	v_pk_add_f32 v[74:75], v[102:103], v[74:75] neg_lo:[0,1] neg_hi:[0,1]
	v_pk_fma_f32 v[66:67], v[28:29], v[66:67], v[92:93] op_sel_hi:[0,1,1]
	v_pk_mul_f32 v[92:93], v[34:35], v[82:83] op_sel:[0,1] op_sel_hi:[1,0]
	v_xor_b32_e32 v42, 0x80000000, v41
	v_mov_b32_e32 v43, v41
	v_pk_fma_f32 v[44:45], v[10:11], v[32:33], v[44:45] op_sel_hi:[0,1,1]
	v_pk_add_f32 v[100:101], v[96:97], v[100:101] neg_lo:[0,1] neg_hi:[0,1]
	v_pk_add_f32 v[98:99], v[78:79], v[90:91]
	v_pk_add_f32 v[78:79], v[78:79], v[90:91] neg_lo:[0,1] neg_hi:[0,1]
	v_pk_fma_f32 v[82:83], v[32:33], v[82:83], v[92:93] op_sel_hi:[0,1,1]
	v_pk_mul_f32 v[92:93], v[38:39], v[74:75] op_sel:[0,1] op_sel_hi:[1,0]
	v_xor_b32_e32 v46, 0x80000000, v45
	v_mov_b32_e32 v47, v45
	v_pk_add_f32 v[90:91], v[68:69], v[80:81]
	v_pk_add_f32 v[68:69], v[68:69], v[80:81] neg_lo:[0,1] neg_hi:[0,1]
	v_pk_fma_f32 v[74:75], v[36:37], v[74:75], v[92:93] op_sel_hi:[0,1,1]
	v_pk_mul_f32 v[92:93], v[42:43], v[78:79] op_sel:[0,1] op_sel_hi:[1,0]
	v_xor_b32_e32 v50, 0x80000000, v49
	v_mov_b32_e32 v51, v49
	v_pk_mul_f32 v[56:57], v[14:15], v[48:49] op_sel:[0,1] op_sel_hi:[1,0]
	v_pk_add_f32 v[96:97], v[94:95], v[100:101] op_sel:[0,1] op_sel_hi:[1,0] neg_hi:[0,1]
	v_pk_add_f32 v[94:95], v[94:95], v[100:101] op_sel:[0,1] op_sel_hi:[1,0] neg_lo:[0,1]
	v_pk_fma_f32 v[78:79], v[40:41], v[78:79], v[92:93] op_sel_hi:[0,1,1]
	v_pk_mul_f32 v[92:93], v[46:47], v[68:69] op_sel:[0,1] op_sel_hi:[1,0]
	v_xor_b32_e32 v54, 0x80000000, v53
	v_mov_b32_e32 v55, v53
	v_pk_fma_f32 v[56:57], v[8:9], v[48:49], v[56:57] op_sel_hi:[0,1,1]
	v_pk_mul_f32 v[60:61], v[20:21], v[48:49] op_sel:[0,1] op_sel_hi:[1,0]
	v_pk_fma_f32 v[68:69], v[44:45], v[68:69], v[92:93] op_sel_hi:[0,1,1]
	v_pk_mul_f32 v[92:93], v[50:51], v[94:95] op_sel:[0,1] op_sel_hi:[1,0]
	v_xor_b32_e32 v58, 0x80000000, v57
	v_mov_b32_e32 v59, v57
	v_pk_fma_f32 v[60:61], v[10:11], v[48:49], v[60:61] op_sel_hi:[0,1,1]
	v_pk_add_f32 v[64:65], v[64:65], v[70:71] op_sel:[0,1] op_sel_hi:[1,0] neg_lo:[0,1]
	v_pk_mul_f32 v[70:71], v[4:5], v[86:87] op_sel:[0,1] op_sel_hi:[1,0]
	v_pk_fma_f32 v[92:93], v[48:49], v[94:95], v[92:93] op_sel_hi:[0,1,1]
	v_pk_mul_f32 v[94:95], v[54:55], v[72:73] op_sel:[0,1] op_sel_hi:[1,0]
	v_xor_b32_e32 v62, 0x80000000, v61
	v_mov_b32_e32 v63, v61
	v_pk_fma_f32 v[70:71], v[6:7], v[86:87], v[70:71] op_sel_hi:[0,1,1]
	v_pk_mul_f32 v[86:87], v[20:21], v[90:91] op_sel:[0,1] op_sel_hi:[1,0]
	v_pk_fma_f32 v[72:73], v[52:53], v[72:73], v[94:95] op_sel_hi:[0,1,1]
	v_pk_mul_f32 v[94:95], v[58:59], v[84:85] op_sel:[0,1] op_sel_hi:[1,0]
	v_add_u32_e32 v2, 0x2000, v2
	v_pk_mul_f32 v[80:81], v[14:15], v[98:99] op_sel:[0,1] op_sel_hi:[1,0]
	v_pk_fma_f32 v[86:87], v[10:11], v[90:91], v[86:87] op_sel_hi:[0,1,1]
	v_pk_mul_f32 v[90:91], v[16:17], v[96:97] op_sel:[0,1] op_sel_hi:[1,0]
	v_pk_fma_f32 v[84:85], v[56:57], v[84:85], v[94:95] op_sel_hi:[0,1,1]
	v_pk_mul_f32 v[94:95], v[62:63], v[64:65] op_sel:[0,1] op_sel_hi:[1,0]
	v_ashrrev_i32_e32 v2, 2, v2
	v_pk_fma_f32 v[80:81], v[8:9], v[98:99], v[80:81] op_sel_hi:[0,1,1]
	v_pk_fma_f32 v[90:91], v[12:13], v[96:97], v[90:91] op_sel_hi:[0,1,1]
	v_pk_fma_f32 v[64:65], v[60:61], v[64:65], v[94:95] op_sel_hi:[0,1,1]
	ds_write2_b64 v106, v[104:105], v[82:83] offset1:16
	ds_write2_b64 v106, v[90:91], v[92:93] offset0:33 offset1:49
	ds_write2_b64 v106, v[80:81], v[78:79] offset0:66 offset1:82
	ds_write2_b64 v106, v[76:77], v[84:85] offset0:99 offset1:115
	ds_write2_b64 v106, v[70:71], v[74:75] offset0:132 offset1:148
	ds_write2_b64 v106, v[88:89], v[72:73] offset0:165 offset1:181
	ds_write2_b64 v106, v[86:87], v[68:69] offset0:198 offset1:214
	ds_write2_b64 v106, v[66:67], v[64:65] offset0:231 offset1:247
	v_add3_u32 v2, v7, v2, s60
	ds_read2_b64 v[64:67], v2 offset1:16
	ds_read2_b64 v[68:71], v2 offset0:33 offset1:49
	ds_read2_b64 v[72:75], v2 offset0:66 offset1:82
	ds_read2_b64 v[76:79], v2 offset0:132 offset1:148
	ds_read2_b64 v[80:83], v2 offset0:99 offset1:115
	ds_read2_b64 v[84:87], v2 offset0:165 offset1:181
	ds_read2_b64 v[88:91], v2 offset0:198 offset1:214
	ds_read2_b64 v[92:95], v2 offset0:231 offset1:247
	s_waitcnt lgkmcnt(4)
	v_pk_add_f32 v[96:97], v[64:65], v[76:77]
	v_pk_add_f32 v[64:65], v[64:65], v[76:77] neg_lo:[0,1] neg_hi:[0,1]
	v_pk_add_f32 v[76:77], v[66:67], v[78:79]
	v_pk_add_f32 v[66:67], v[66:67], v[78:79] neg_lo:[0,1] neg_hi:[0,1]
	s_waitcnt lgkmcnt(1)
	v_pk_add_f32 v[98:99], v[74:75], v[90:91]
	v_pk_mul_f32 v[78:79], v[66:67], s[24:25]
	v_pk_add_f32 v[74:75], v[74:75], v[90:91] neg_lo:[0,1] neg_hi:[0,1]
	v_pk_fma_f32 v[66:67], v[66:67], s[22:23], v[78:79] op_sel:[0,0,1] op_sel_hi:[1,0,0]
	v_pk_add_f32 v[78:79], v[68:69], v[84:85]
	v_pk_add_f32 v[68:69], v[68:69], v[84:85] neg_lo:[0,1] neg_hi:[0,1]
	v_pk_mul_f32 v[90:91], v[74:75], s[44:45]
	v_pk_mul_f32 v[84:85], v[68:69], s[40:41]
	v_pk_fma_f32 v[74:75], v[74:75], s[50:51], v[90:91] op_sel:[0,0,1] op_sel_hi:[1,0,0] neg_lo:[1,0,0] neg_hi:[1,0,0]
	s_waitcnt lgkmcnt(0)
	v_pk_add_f32 v[90:91], v[80:81], v[92:93]
	v_pk_add_f32 v[80:81], v[80:81], v[92:93] neg_lo:[0,1] neg_hi:[0,1]
	v_pk_fma_f32 v[68:69], v[68:69], s[38:39], v[84:85] op_sel:[0,0,1] op_sel_hi:[1,0,0]
	v_pk_add_f32 v[84:85], v[70:71], v[86:87]
	v_pk_add_f32 v[70:71], v[70:71], v[86:87] neg_lo:[0,1] neg_hi:[0,1]
	v_pk_mul_f32 v[92:93], v[80:81], s[40:41]
	v_pk_mul_f32 v[86:87], v[70:71], s[44:45]
	v_pk_fma_f32 v[80:81], v[80:81], s[38:39], v[92:93] op_sel:[0,0,1] op_sel_hi:[1,0,0] neg_lo:[1,0,0] neg_hi:[1,0,0]
	v_pk_add_f32 v[92:93], v[82:83], v[94:95]
	v_pk_add_f32 v[82:83], v[82:83], v[94:95] neg_lo:[0,1] neg_hi:[0,1]
	v_pk_fma_f32 v[70:71], v[70:71], s[50:51], v[86:87] op_sel:[0,0,1] op_sel_hi:[1,0,0]
	v_pk_add_f32 v[86:87], v[72:73], v[88:89]
	v_pk_mul_f32 v[94:95], v[82:83], s[24:25]
	v_pk_add_f32 v[88:89], v[72:73], v[88:89] neg_lo:[0,1] neg_hi:[0,1]
	v_pk_fma_f32 v[82:83], v[82:83], s[22:23], v[94:95] op_sel:[0,0,1] op_sel_hi:[1,0,0] neg_lo:[1,0,0] neg_hi:[1,0,0]
	v_pk_add_f32 v[94:95], v[96:97], v[86:87]
	v_pk_add_f32 v[86:87], v[96:97], v[86:87] neg_lo:[0,1] neg_hi:[0,1]
	v_pk_add_f32 v[96:97], v[76:77], v[98:99]
	v_pk_add_f32 v[76:77], v[76:77], v[98:99] neg_lo:[0,1] neg_hi:[0,1]
	s_nop 0
	v_pk_mul_f32 v[98:99], v[76:77], s[40:41]
	v_pk_add_f32 v[100:101], v[84:85], v[92:93]
	v_pk_add_f32 v[84:85], v[84:85], v[92:93] neg_lo:[0,1] neg_hi:[0,1]
	v_pk_fma_f32 v[76:77], v[76:77], s[38:39], v[98:99] op_sel:[0,0,1] op_sel_hi:[1,0,0]
	v_pk_add_f32 v[98:99], v[78:79], v[90:91]
	v_pk_add_f32 v[90:91], v[78:79], v[90:91] neg_lo:[0,1] neg_hi:[0,1]
	v_pk_mul_f32 v[92:93], v[84:85], s[40:41]
	v_pk_add_f32 v[72:73], v[64:65], v[88:89] op_sel:[0,1] op_sel_hi:[1,0] neg_hi:[0,1]
	v_pk_add_f32 v[64:65], v[64:65], v[88:89] op_sel:[0,1] op_sel_hi:[1,0] neg_lo:[0,1]
	v_pk_add_f32 v[88:89], v[66:67], v[74:75]
	v_pk_add_f32 v[66:67], v[66:67], v[74:75] neg_lo:[0,1] neg_hi:[0,1]
	v_pk_fma_f32 v[84:85], v[84:85], s[38:39], v[92:93] op_sel:[0,0,1] op_sel_hi:[1,0,0] neg_lo:[1,0,0] neg_hi:[1,0,0]
	v_pk_mul_f32 v[74:75], v[66:67], s[40:41]
	s_nop 0
	v_pk_fma_f32 v[66:67], v[66:67], s[38:39], v[74:75] op_sel:[0,0,1] op_sel_hi:[1,0,0]
	v_pk_add_f32 v[74:75], v[68:69], v[80:81]
	v_pk_add_f32 v[92:93], v[70:71], v[82:83]
	v_pk_add_f32 v[70:71], v[70:71], v[82:83] neg_lo:[0,1] neg_hi:[0,1]
	v_pk_add_f32 v[78:79], v[86:87], v[90:91] op_sel:[0,1] op_sel_hi:[1,0] neg_hi:[0,1]
	v_pk_add_f32 v[86:87], v[86:87], v[90:91] op_sel:[0,1] op_sel_hi:[1,0] neg_lo:[0,1]
	v_pk_add_f32 v[90:91], v[76:77], v[84:85]
	v_pk_add_f32 v[84:85], v[76:77], v[84:85] neg_lo:[0,1] neg_hi:[0,1]
	v_pk_add_f32 v[80:81], v[68:69], v[80:81] neg_lo:[0,1] neg_hi:[0,1]
	v_pk_mul_f32 v[82:83], v[70:71], s[40:41]
	v_pk_add_f32 v[102:103], v[72:73], v[74:75]
	v_pk_add_f32 v[72:73], v[72:73], v[74:75] neg_lo:[0,1] neg_hi:[0,1]
	v_pk_add_f32 v[74:75], v[88:89], v[92:93]
	v_pk_fma_f32 v[70:71], v[70:71], s[38:39], v[82:83] op_sel:[0,0,1] op_sel_hi:[1,0,0] neg_lo:[1,0,0] neg_hi:[1,0,0]
	v_pk_add_f32 v[82:83], v[94:95], v[98:99]
	v_pk_add_f32 v[94:95], v[94:95], v[98:99] neg_lo:[0,1] neg_hi:[0,1]
	v_pk_add_f32 v[98:99], v[96:97], v[100:101]
	v_pk_add_f32 v[76:77], v[86:87], v[84:85] op_sel:[0,1] op_sel_hi:[1,0] neg_hi:[0,1]
	v_pk_add_f32 v[84:85], v[86:87], v[84:85] op_sel:[0,1] op_sel_hi:[1,0] neg_lo:[0,1]
	v_pk_add_f32 v[86:87], v[102:103], v[74:75]
	v_pk_add_f32 v[100:101], v[96:97], v[100:101] neg_lo:[0,1] neg_hi:[0,1]
	v_pk_add_f32 v[68:69], v[64:65], v[80:81] op_sel:[0,1] op_sel_hi:[1,0] neg_hi:[0,1]
	v_pk_add_f32 v[64:65], v[64:65], v[80:81] op_sel:[0,1] op_sel_hi:[1,0] neg_lo:[0,1]
	v_pk_add_f32 v[80:81], v[66:67], v[70:71]
	v_pk_add_f32 v[104:105], v[82:83], v[98:99]
	v_pk_add_f32 v[82:83], v[82:83], v[98:99] neg_lo:[0,1] neg_hi:[0,1]
	v_pk_add_f32 v[98:99], v[78:79], v[90:91]
	v_pk_mul_f32 v[4:5], v[4:5], v[86:87] op_sel:[0,1] op_sel_hi:[1,0]
	v_pk_add_f32 v[92:93], v[88:89], v[92:93] neg_lo:[0,1] neg_hi:[0,1]
	v_pk_add_f32 v[78:79], v[78:79], v[90:91] neg_lo:[0,1] neg_hi:[0,1]
	v_pk_add_f32 v[90:91], v[68:69], v[80:81]
	v_pk_fma_f32 v[4:5], v[6:7], v[86:87], v[4:5] op_sel_hi:[0,1,1]
	v_pk_mul_f32 v[6:7], v[14:15], v[98:99] op_sel:[0,1] op_sel_hi:[1,0]
	v_pk_add_f32 v[70:71], v[66:67], v[70:71] neg_lo:[0,1] neg_hi:[0,1]
	v_pk_add_f32 v[96:97], v[94:95], v[100:101] op_sel:[0,1] op_sel_hi:[1,0] neg_hi:[0,1]
	v_pk_fma_f32 v[6:7], v[8:9], v[98:99], v[6:7] op_sel_hi:[0,1,1]
	v_pk_mul_f32 v[8:9], v[20:21], v[90:91] op_sel:[0,1] op_sel_hi:[1,0]
	v_pk_add_f32 v[88:89], v[72:73], v[92:93] op_sel:[0,1] op_sel_hi:[1,0] neg_hi:[0,1]
	v_pk_fma_f32 v[8:9], v[10:11], v[90:91], v[8:9] op_sel_hi:[0,1,1]
	v_pk_mul_f32 v[10:11], v[16:17], v[96:97] op_sel:[0,1] op_sel_hi:[1,0]
	v_pk_add_f32 v[66:67], v[64:65], v[70:71] op_sel:[0,1] op_sel_hi:[1,0] neg_hi:[0,1]
	v_pk_fma_f32 v[10:11], v[12:13], v[96:97], v[10:11] op_sel_hi:[0,1,1]
	v_pk_mul_f32 v[12:13], v[22:23], v[88:89] op_sel:[0,1] op_sel_hi:[1,0]
	v_pk_add_f32 v[94:95], v[94:95], v[100:101] op_sel:[0,1] op_sel_hi:[1,0] neg_lo:[0,1]
	v_pk_add_f32 v[74:75], v[102:103], v[74:75] neg_lo:[0,1] neg_hi:[0,1]
	v_pk_add_f32 v[72:73], v[72:73], v[92:93] op_sel:[0,1] op_sel_hi:[1,0] neg_lo:[0,1]
	v_pk_add_f32 v[68:69], v[68:69], v[80:81] neg_lo:[0,1] neg_hi:[0,1]
	v_pk_add_f32 v[64:65], v[64:65], v[70:71] op_sel:[0,1] op_sel_hi:[1,0] neg_lo:[0,1]
	v_pk_fma_f32 v[12:13], v[18:19], v[88:89], v[12:13] op_sel_hi:[0,1,1]
	v_pk_mul_f32 v[14:15], v[26:27], v[76:77] op_sel:[0,1] op_sel_hi:[1,0]
	v_pk_mul_f32 v[16:17], v[30:31], v[66:67] op_sel:[0,1] op_sel_hi:[1,0]
	v_pk_mul_f32 v[18:19], v[34:35], v[82:83] op_sel:[0,1] op_sel_hi:[1,0]
	v_pk_fma_f32 v[14:15], v[24:25], v[76:77], v[14:15] op_sel_hi:[0,1,1]
	v_pk_fma_f32 v[16:17], v[28:29], v[66:67], v[16:17] op_sel_hi:[0,1,1]
	v_pk_fma_f32 v[18:19], v[32:33], v[82:83], v[18:19] op_sel_hi:[0,1,1]
	v_pk_mul_f32 v[20:21], v[38:39], v[74:75] op_sel:[0,1] op_sel_hi:[1,0]
	v_pk_mul_f32 v[22:23], v[42:43], v[78:79] op_sel:[0,1] op_sel_hi:[1,0]
	v_pk_mul_f32 v[24:25], v[46:47], v[68:69] op_sel:[0,1] op_sel_hi:[1,0]
	v_pk_mul_f32 v[26:27], v[50:51], v[94:95] op_sel:[0,1] op_sel_hi:[1,0]
	v_pk_mul_f32 v[28:29], v[54:55], v[72:73] op_sel:[0,1] op_sel_hi:[1,0]
	v_pk_mul_f32 v[30:31], v[58:59], v[84:85] op_sel:[0,1] op_sel_hi:[1,0]
	v_pk_mul_f32 v[32:33], v[62:63], v[64:65] op_sel:[0,1] op_sel_hi:[1,0]
	v_pk_fma_f32 v[20:21], v[36:37], v[74:75], v[20:21] op_sel_hi:[0,1,1]
	v_pk_fma_f32 v[22:23], v[40:41], v[78:79], v[22:23] op_sel_hi:[0,1,1]
	v_pk_fma_f32 v[24:25], v[44:45], v[68:69], v[24:25] op_sel_hi:[0,1,1]
	v_pk_fma_f32 v[26:27], v[48:49], v[94:95], v[26:27] op_sel_hi:[0,1,1]
	v_pk_fma_f32 v[28:29], v[52:53], v[72:73], v[28:29] op_sel_hi:[0,1,1]
	v_pk_fma_f32 v[30:31], v[56:57], v[84:85], v[30:31] op_sel_hi:[0,1,1]
	v_pk_fma_f32 v[32:33], v[60:61], v[64:65], v[32:33] op_sel_hi:[0,1,1]
	ds_write2_b64 v2, v[104:105], v[18:19] offset1:16
	ds_write2_b64 v2, v[10:11], v[26:27] offset0:33 offset1:49
	ds_write2_b64 v2, v[6:7], v[22:23] offset0:66 offset1:82
	ds_write2_b64 v2, v[14:15], v[30:31] offset0:99 offset1:115
	ds_write2_b64 v2, v[4:5], v[20:21] offset0:132 offset1:148
	ds_write2_b64 v2, v[12:13], v[28:29] offset0:165 offset1:181
	ds_write2_b64 v2, v[8:9], v[24:25] offset0:198 offset1:214
	ds_write2_b64 v2, v[16:17], v[32:33] offset0:231 offset1:247
	s_waitcnt lgkmcnt(0)
	s_barrier
	s_nop 0
	v_ashrrev_i32_e32 v2, 31, v142
	v_add_u32_sdwa v2, v142, v2 dst_sel:DWORD dst_unused:UNUSED_PAD src0_sel:DWORD src1_sel:BYTE_3
	v_ashrrev_i32_e32 v145, 8, v2
	v_mul_i32_i24_e32 v2, 0x100, v145
	v_sub_u32_e32 v144, v142, v2
	v_lshlrev_b32_e32 v2, 1, v144
	v_bfrev_b32_e32 v2, v2
	v_lshrrev_b32_e32 v2, 23, v2
	v_sub_u32_e32 v2, 0x200, v2
	v_bfrev_b32_e32 v2, v2
	v_lshrrev_b32_e32 v2, 19, v2
	v_lshlrev_b32_e32 v143, 13, v145
	v_and_b32_e32 v2, 0x1ff0, v2
	v_cmp_eq_u32_e32 vcc, 0, v144
	v_lshl_add_u32 v4, v144, 5, v143
	v_lshlrev_b32_e32 v5, 3, v4
	v_cndmask_b32_e64 v2, v2, 16, vcc
	v_ashrrev_i32_e32 v4, 2, v4
	v_or_b32_e32 v2, v2, v143
	v_add3_u32 v56, 0, v5, v4
	v_ashrrev_i32_e32 v4, 5, v2
	v_lshlrev_b32_e32 v2, 3, v2
	v_lshlrev_b32_e32 v4, 3, v4
	v_add3_u32 v2, 0, v2, v4
	ds_read2_b64 v[4:7], v56 offset1:1
	ds_read2_b64 v[8:11], v56 offset0:2 offset1:3
	ds_read2_b64 v[12:15], v2 offset1:1
	ds_read2_b64 v[16:19], v2 offset0:2 offset1:3
	ds_read2_b64 v[20:23], v56 offset0:4 offset1:5
	ds_read2_b64 v[24:27], v56 offset0:6 offset1:7
	ds_read2_b64 v[28:31], v2 offset0:4 offset1:5
	ds_read2_b64 v[32:35], v2 offset0:6 offset1:7
	ds_read2_b64 v[36:39], v56 offset0:8 offset1:9
	ds_read2_b64 v[40:43], v56 offset0:10 offset1:11
	ds_read2_b64 v[44:47], v2 offset0:8 offset1:9
	ds_read2_b64 v[52:55], v2 offset0:10 offset1:11
	ds_read2_b64 v[48:51], v56 offset0:12 offset1:13
	ds_read2_b64 v[56:59], v56 offset0:14 offset1:15
	ds_read2_b64 v[62:65], v2 offset0:12 offset1:13
	ds_read2_b64 v[74:77], v2 offset0:14 offset1:15
	s_waitcnt lgkmcnt(7)
	v_pk_add_f32 v[60:61], v[4:5], v[36:37]
	v_pk_add_f32 v[4:5], v[4:5], v[36:37] neg_lo:[0,1] neg_hi:[0,1]
	v_pk_add_f32 v[36:37], v[6:7], v[38:39]
	v_pk_add_f32 v[6:7], v[6:7], v[38:39] neg_lo:[0,1] neg_hi:[0,1]
	s_waitcnt lgkmcnt(3)
	v_pk_add_f32 v[66:67], v[22:23], v[50:51]
	v_pk_mul_f32 v[38:39], v[6:7], s[24:25]
	v_pk_add_f32 v[22:23], v[22:23], v[50:51] neg_lo:[0,1] neg_hi:[0,1]
	v_pk_fma_f32 v[6:7], v[6:7], s[22:23], v[38:39] op_sel:[0,0,1] op_sel_hi:[1,0,0]
	v_pk_add_f32 v[38:39], v[8:9], v[40:41]
	v_pk_add_f32 v[8:9], v[8:9], v[40:41] neg_lo:[0,1] neg_hi:[0,1]
	v_pk_mul_f32 v[50:51], v[22:23], s[44:45]
	v_pk_mul_f32 v[40:41], v[8:9], s[40:41]
	v_pk_fma_f32 v[22:23], v[22:23], s[50:51], v[50:51] op_sel:[0,0,1] op_sel_hi:[1,0,0] neg_lo:[1,0,0] neg_hi:[1,0,0]
	v_pk_fma_f32 v[8:9], v[8:9], s[38:39], v[40:41] op_sel:[0,0,1] op_sel_hi:[1,0,0]
	v_pk_add_f32 v[40:41], v[10:11], v[42:43]
	v_pk_add_f32 v[10:11], v[10:11], v[42:43] neg_lo:[0,1] neg_hi:[0,1]
	s_waitcnt lgkmcnt(2)
	v_pk_add_f32 v[50:51], v[24:25], v[56:57]
	v_pk_add_f32 v[24:25], v[24:25], v[56:57] neg_lo:[0,1] neg_hi:[0,1]
	v_pk_mul_f32 v[42:43], v[10:11], s[44:45]
	v_pk_mul_f32 v[56:57], v[24:25], s[40:41]
	v_pk_fma_f32 v[10:11], v[10:11], s[50:51], v[42:43] op_sel:[0,0,1] op_sel_hi:[1,0,0]
	v_pk_add_f32 v[42:43], v[20:21], v[48:49]
	v_pk_add_f32 v[48:49], v[20:21], v[48:49] neg_lo:[0,1] neg_hi:[0,1]
	v_pk_fma_f32 v[24:25], v[24:25], s[38:39], v[56:57] op_sel:[0,0,1] op_sel_hi:[1,0,0] neg_lo:[1,0,0] neg_hi:[1,0,0]
	v_pk_add_f32 v[56:57], v[26:27], v[58:59]
	v_pk_add_f32 v[26:27], v[26:27], v[58:59] neg_lo:[0,1] neg_hi:[0,1]
	s_nop 0
	v_pk_mul_f32 v[58:59], v[26:27], s[24:25]
	v_pk_add_f32 v[68:69], v[40:41], v[56:57]
	v_pk_add_f32 v[40:41], v[40:41], v[56:57] neg_lo:[0,1] neg_hi:[0,1]
	v_pk_fma_f32 v[26:27], v[26:27], s[22:23], v[58:59] op_sel:[0,0,1] op_sel_hi:[1,0,0] neg_lo:[1,0,0] neg_hi:[1,0,0]
	v_pk_mul_f32 v[56:57], v[40:41], s[40:41]
	v_pk_add_f32 v[20:21], v[4:5], v[48:49] op_sel:[0,1] op_sel_hi:[1,0] neg_hi:[0,1]
	v_pk_add_f32 v[4:5], v[4:5], v[48:49] op_sel:[0,1] op_sel_hi:[1,0] neg_lo:[0,1]
	v_pk_add_f32 v[48:49], v[6:7], v[22:23]
	v_pk_add_f32 v[6:7], v[6:7], v[22:23] neg_lo:[0,1] neg_hi:[0,1]
	v_pk_fma_f32 v[40:41], v[40:41], s[38:39], v[56:57] op_sel:[0,0,1] op_sel_hi:[1,0,0] neg_lo:[1,0,0] neg_hi:[1,0,0]
	v_pk_mul_f32 v[22:23], v[6:7], s[40:41]
	v_pk_add_f32 v[56:57], v[10:11], v[26:27]
	v_pk_add_f32 v[10:11], v[10:11], v[26:27] neg_lo:[0,1] neg_hi:[0,1]
	v_pk_add_f32 v[58:59], v[60:61], v[42:43]
	v_pk_add_f32 v[42:43], v[60:61], v[42:43] neg_lo:[0,1] neg_hi:[0,1]
	v_pk_add_f32 v[60:61], v[36:37], v[66:67]
	v_pk_add_f32 v[36:37], v[36:37], v[66:67] neg_lo:[0,1] neg_hi:[0,1]
	v_pk_fma_f32 v[6:7], v[6:7], s[38:39], v[22:23] op_sel:[0,0,1] op_sel_hi:[1,0,0]
	v_pk_add_f32 v[22:23], v[8:9], v[24:25]
	v_pk_add_f32 v[24:25], v[8:9], v[24:25] neg_lo:[0,1] neg_hi:[0,1]
	v_pk_mul_f32 v[26:27], v[10:11], s[40:41]
	v_pk_mul_f32 v[66:67], v[36:37], s[40:41]
	v_pk_fma_f32 v[10:11], v[10:11], s[38:39], v[26:27] op_sel:[0,0,1] op_sel_hi:[1,0,0] neg_lo:[1,0,0] neg_hi:[1,0,0]
	v_pk_fma_f32 v[36:37], v[36:37], s[38:39], v[66:67] op_sel:[0,0,1] op_sel_hi:[1,0,0]
	v_pk_add_f32 v[66:67], v[38:39], v[50:51]
	v_pk_add_f32 v[8:9], v[4:5], v[24:25] op_sel:[0,1] op_sel_hi:[1,0] neg_hi:[0,1]
	v_pk_add_f32 v[4:5], v[4:5], v[24:25] op_sel:[0,1] op_sel_hi:[1,0] neg_lo:[0,1]
	v_pk_add_f32 v[24:25], v[6:7], v[10:11]
	v_pk_add_f32 v[10:11], v[6:7], v[10:11] neg_lo:[0,1] neg_hi:[0,1]
	v_pk_add_f32 v[26:27], v[58:59], v[66:67]
	v_pk_add_f32 v[58:59], v[58:59], v[66:67] neg_lo:[0,1] neg_hi:[0,1]
	v_pk_add_f32 v[66:67], v[60:61], v[68:69]
	v_pk_add_f32 v[68:69], v[60:61], v[68:69] neg_lo:[0,1] neg_hi:[0,1]
	v_pk_add_f32 v[60:61], v[4:5], v[10:11] op_sel:[0,1] op_sel_hi:[1,0] neg_hi:[0,1]
	v_pk_add_f32 v[90:91], v[4:5], v[10:11] op_sel:[0,1] op_sel_hi:[1,0] neg_lo:[0,1]
	v_pk_add_f32 v[10:11], v[14:15], v[46:47] neg_lo:[0,1] neg_hi:[0,1]
	v_pk_add_f32 v[50:51], v[38:39], v[50:51] neg_lo:[0,1] neg_hi:[0,1]
	v_pk_add_f32 v[84:85], v[58:59], v[68:69] op_sel:[0,1] op_sel_hi:[1,0] neg_hi:[0,1]
	v_pk_add_f32 v[86:87], v[58:59], v[68:69] op_sel:[0,1] op_sel_hi:[1,0] neg_lo:[0,1]
	v_pk_add_f32 v[82:83], v[8:9], v[24:25]
	v_pk_add_f32 v[68:69], v[8:9], v[24:25] neg_lo:[0,1] neg_hi:[0,1]
	v_pk_add_f32 v[4:5], v[12:13], v[44:45]
	v_pk_add_f32 v[6:7], v[12:13], v[44:45] neg_lo:[0,1] neg_hi:[0,1]
	v_pk_add_f32 v[8:9], v[14:15], v[46:47]
	v_pk_mul_f32 v[12:13], v[10:11], s[24:25]
	v_pk_add_f32 v[14:15], v[16:17], v[52:53] neg_lo:[0,1] neg_hi:[0,1]
	v_pk_add_f32 v[70:71], v[20:21], v[22:23]
	v_pk_add_f32 v[20:21], v[20:21], v[22:23] neg_lo:[0,1] neg_hi:[0,1]
	v_pk_add_f32 v[22:23], v[48:49], v[56:57]
	v_pk_add_f32 v[48:49], v[48:49], v[56:57] neg_lo:[0,1] neg_hi:[0,1]
	v_pk_fma_f32 v[10:11], v[10:11], s[22:23], v[12:13] op_sel:[0,0,1] op_sel_hi:[1,0,0]
	v_pk_add_f32 v[12:13], v[16:17], v[52:53]
	v_pk_mul_f32 v[16:17], v[14:15], s[40:41]
	v_pk_add_f32 v[38:39], v[42:43], v[50:51] op_sel:[0,1] op_sel_hi:[1,0] neg_hi:[0,1]
	v_pk_add_f32 v[42:43], v[42:43], v[50:51] op_sel:[0,1] op_sel_hi:[1,0] neg_lo:[0,1]
	v_pk_add_f32 v[50:51], v[36:37], v[40:41]
	v_xor_b32_e32 v57, 0x80000000, v48
	v_mov_b32_e32 v56, v49
	v_pk_fma_f32 v[14:15], v[14:15], s[38:39], v[16:17] op_sel:[0,0,1] op_sel_hi:[1,0,0]
	v_pk_add_f32 v[16:17], v[18:19], v[54:55]
	v_pk_add_f32 v[18:19], v[18:19], v[54:55] neg_lo:[0,1] neg_hi:[0,1]
	v_pk_add_f32 v[130:131], v[26:27], v[66:67]
	v_pk_add_f32 v[92:93], v[26:27], v[66:67] neg_lo:[0,1] neg_hi:[0,1]
	v_pk_add_f32 v[88:89], v[38:39], v[50:51]
	v_pk_add_f32 v[72:73], v[38:39], v[50:51] neg_lo:[0,1] neg_hi:[0,1]
	v_pk_add_f32 v[96:97], v[70:71], v[22:23]
	v_pk_add_f32 v[50:51], v[70:71], v[22:23] neg_lo:[0,1] neg_hi:[0,1]
	v_pk_add_f32 v[66:67], v[20:21], v[56:57]
	v_pk_add_f32 v[80:81], v[20:21], v[56:57] neg_lo:[0,1] neg_hi:[0,1]
	v_pk_mul_f32 v[20:21], v[18:19], s[44:45]
	s_waitcnt lgkmcnt(1)
	v_pk_add_f32 v[24:25], v[28:29], v[62:63] neg_lo:[0,1] neg_hi:[0,1]
	v_pk_add_f32 v[26:27], v[30:31], v[64:65] neg_lo:[0,1] neg_hi:[0,1]
	v_pk_fma_f32 v[18:19], v[18:19], s[50:51], v[20:21] op_sel:[0,0,1] op_sel_hi:[1,0,0]
	v_pk_add_f32 v[20:21], v[28:29], v[62:63]
	v_pk_add_f32 v[22:23], v[30:31], v[64:65]
	v_pk_mul_f32 v[28:29], v[26:27], s[44:45]
	s_waitcnt lgkmcnt(0)
	v_pk_add_f32 v[30:31], v[32:33], v[74:75] neg_lo:[0,1] neg_hi:[0,1]
	v_pk_fma_f32 v[26:27], v[26:27], s[50:51], v[28:29] op_sel:[0,0,1] op_sel_hi:[1,0,0] neg_lo:[1,0,0] neg_hi:[1,0,0]
	v_pk_add_f32 v[28:29], v[32:33], v[74:75]
	v_pk_mul_f32 v[32:33], v[30:31], s[40:41]
	v_pk_add_f32 v[36:37], v[36:37], v[40:41] neg_lo:[0,1] neg_hi:[0,1]
	v_pk_fma_f32 v[30:31], v[30:31], s[38:39], v[32:33] op_sel:[0,0,1] op_sel_hi:[1,0,0] neg_lo:[1,0,0] neg_hi:[1,0,0]
	v_pk_add_f32 v[32:33], v[34:35], v[76:77]
	v_pk_add_f32 v[34:35], v[34:35], v[76:77] neg_lo:[0,1] neg_hi:[0,1]
	v_xor_b32_e32 v41, 0x80000000, v36
	v_mov_b32_e32 v40, v37
	v_pk_mul_f32 v[36:37], v[34:35], s[24:25]
	v_mov_b32_e32 v2, v130
	v_pk_fma_f32 v[34:35], v[34:35], s[22:23], v[36:37] op_sel:[0,0,1] op_sel_hi:[1,0,0] neg_lo:[1,0,0] neg_hi:[1,0,0]
	v_pk_add_f32 v[36:37], v[4:5], v[20:21]
	v_pk_add_f32 v[4:5], v[4:5], v[20:21] neg_lo:[0,1] neg_hi:[0,1]
	v_pk_add_f32 v[20:21], v[8:9], v[22:23]
	v_pk_add_f32 v[8:9], v[8:9], v[22:23] neg_lo:[0,1] neg_hi:[0,1]
	v_cmp_ne_u32_e64 s[0:1], 0, v144
	v_pk_mul_f32 v[22:23], v[8:9], s[40:41]
	v_pk_add_f32 v[78:79], v[42:43], v[40:41]
	v_pk_fma_f32 v[8:9], v[8:9], s[38:39], v[22:23] op_sel:[0,0,1] op_sel_hi:[1,0,0]
	v_pk_add_f32 v[22:23], v[12:13], v[28:29]
	v_pk_add_f32 v[28:29], v[12:13], v[28:29] neg_lo:[0,1] neg_hi:[0,1]
	v_pk_add_f32 v[94:95], v[42:43], v[40:41] neg_lo:[0,1] neg_hi:[0,1]
	v_pk_add_f32 v[12:13], v[16:17], v[32:33]
	v_pk_add_f32 v[16:17], v[16:17], v[32:33] neg_lo:[0,1] neg_hi:[0,1]
	s_nop 0
	v_pk_mul_f32 v[32:33], v[16:17], s[40:41]
	s_nop 0
	v_pk_fma_f32 v[16:17], v[16:17], s[38:39], v[32:33] op_sel:[0,0,1] op_sel_hi:[1,0,0] neg_lo:[1,0,0] neg_hi:[1,0,0]
	v_pk_add_f32 v[32:33], v[6:7], v[24:25] op_sel:[0,1] op_sel_hi:[1,0] neg_hi:[0,1]
	v_pk_add_f32 v[6:7], v[6:7], v[24:25] op_sel:[0,1] op_sel_hi:[1,0] neg_lo:[0,1]
	v_pk_add_f32 v[24:25], v[10:11], v[26:27]
	v_pk_add_f32 v[10:11], v[10:11], v[26:27] neg_lo:[0,1] neg_hi:[0,1]
	s_nop 0
	v_pk_mul_f32 v[26:27], v[10:11], s[40:41]
	s_nop 0
	v_pk_fma_f32 v[10:11], v[10:11], s[38:39], v[26:27] op_sel:[0,0,1] op_sel_hi:[1,0,0]
	v_pk_add_f32 v[26:27], v[14:15], v[30:31]
	v_pk_add_f32 v[30:31], v[14:15], v[30:31] neg_lo:[0,1] neg_hi:[0,1]
	s_nop 0
	v_pk_add_f32 v[14:15], v[18:19], v[34:35]
	v_pk_add_f32 v[18:19], v[18:19], v[34:35] neg_lo:[0,1] neg_hi:[0,1]
	s_nop 0
	v_pk_mul_f32 v[34:35], v[18:19], s[40:41]
	s_nop 0
	v_pk_fma_f32 v[18:19], v[18:19], s[38:39], v[34:35] op_sel:[0,0,1] op_sel_hi:[1,0,0] neg_lo:[1,0,0] neg_hi:[1,0,0]
	v_pk_add_f32 v[34:35], v[36:37], v[22:23]
	v_pk_add_f32 v[22:23], v[36:37], v[22:23] neg_lo:[0,1] neg_hi:[0,1]
	v_pk_add_f32 v[36:37], v[20:21], v[12:13]
	v_pk_add_f32 v[12:13], v[20:21], v[12:13] neg_lo:[0,1] neg_hi:[0,1]
	v_pk_add_f32 v[98:99], v[34:35], v[36:37]
	v_xor_b32_e32 v21, 0x80000000, v12
	v_mov_b32_e32 v20, v13
	v_pk_add_f32 v[12:13], v[4:5], v[28:29] op_sel:[0,1] op_sel_hi:[1,0] neg_hi:[0,1]
	v_pk_add_f32 v[4:5], v[4:5], v[28:29] op_sel:[0,1] op_sel_hi:[1,0] neg_lo:[0,1]
	v_pk_add_f32 v[28:29], v[8:9], v[16:17]
	v_pk_add_f32 v[8:9], v[8:9], v[16:17] neg_lo:[0,1] neg_hi:[0,1]
	v_pk_add_f32 v[100:101], v[34:35], v[36:37] neg_lo:[0,1] neg_hi:[0,1]
	v_xor_b32_e32 v17, 0x80000000, v8
	v_mov_b32_e32 v16, v9
	v_pk_add_f32 v[8:9], v[32:33], v[26:27]
	v_pk_add_f32 v[26:27], v[32:33], v[26:27] neg_lo:[0,1] neg_hi:[0,1]
	v_pk_add_f32 v[32:33], v[24:25], v[14:15]
	v_pk_add_f32 v[14:15], v[24:25], v[14:15] neg_lo:[0,1] neg_hi:[0,1]
	v_pk_add_f32 v[102:103], v[22:23], v[20:21]
	v_xor_b32_e32 v25, 0x80000000, v14
	v_mov_b32_e32 v24, v15
	v_pk_add_f32 v[14:15], v[6:7], v[30:31] op_sel:[0,1] op_sel_hi:[1,0] neg_hi:[0,1]
	v_pk_add_f32 v[6:7], v[6:7], v[30:31] op_sel:[0,1] op_sel_hi:[1,0] neg_lo:[0,1]
	v_pk_add_f32 v[30:31], v[10:11], v[18:19]
	v_pk_add_f32 v[10:11], v[10:11], v[18:19] neg_lo:[0,1] neg_hi:[0,1]
	v_pk_add_f32 v[104:105], v[22:23], v[20:21] neg_lo:[0,1] neg_hi:[0,1]
	v_xor_b32_e32 v19, 0x80000000, v10
	v_mov_b32_e32 v18, v11
	v_pk_add_f32 v[106:107], v[12:13], v[28:29]
	v_pk_add_f32 v[108:109], v[12:13], v[28:29] neg_lo:[0,1] neg_hi:[0,1]
	v_pk_add_f32 v[110:111], v[4:5], v[16:17]
	v_pk_add_f32 v[112:113], v[4:5], v[16:17] neg_lo:[0,1] neg_hi:[0,1]
	v_pk_add_f32 v[114:115], v[8:9], v[32:33]
	v_pk_add_f32 v[116:117], v[8:9], v[32:33] neg_lo:[0,1] neg_hi:[0,1]
	v_pk_add_f32 v[118:119], v[26:27], v[24:25]
	v_pk_add_f32 v[120:121], v[26:27], v[24:25] neg_lo:[0,1] neg_hi:[0,1]
	v_pk_add_f32 v[122:123], v[14:15], v[30:31]
	v_pk_add_f32 v[124:125], v[14:15], v[30:31] neg_lo:[0,1] neg_hi:[0,1]
	v_pk_add_f32 v[126:127], v[6:7], v[18:19]
	v_pk_add_f32 v[128:129], v[6:7], v[18:19] neg_lo:[0,1] neg_hi:[0,1]
	v_mov_b32_e32 v4, v131
	v_mov_b32_e32 v5, v3
	v_mov_b64_e32 v[6:7], v[2:3]
	s_and_saveexec_b64 s[50:51], s[0:1]
	s_xor_b64 s[0:1], exec, s[50:51]
	s_cbranch_execz .LBB0_576
	v_pk_add_f32 v[4:5], v[96:97], v[112:113]
	v_pk_add_f32 v[24:25], v[96:97], v[112:113] neg_lo:[0,1] neg_hi:[0,1]
	v_pk_add_f32 v[148:149], v[130:131], v[128:129]
	v_pk_add_f32 v[8:9], v[130:131], v[128:129] neg_lo:[0,1] neg_hi:[0,1]
	v_pk_add_f32 v[128:129], v[126:127], v[92:93]
	v_pk_add_f32 v[10:11], v[126:127], v[92:93] neg_lo:[0,1] neg_hi:[0,1]
	v_pk_add_f32 v[92:93], v[84:85], v[124:125]
	v_pk_add_f32 v[12:13], v[84:85], v[124:125] neg_lo:[0,1] neg_hi:[0,1]
	v_pk_add_f32 v[84:85], v[122:123], v[86:87]
	v_pk_add_f32 v[14:15], v[122:123], v[86:87] neg_lo:[0,1] neg_hi:[0,1]
	v_pk_add_f32 v[86:87], v[88:89], v[120:121]
	v_pk_add_f32 v[16:17], v[88:89], v[120:121] neg_lo:[0,1] neg_hi:[0,1]
	v_pk_add_f32 v[88:89], v[118:119], v[72:73]
	v_pk_add_f32 v[18:19], v[118:119], v[72:73] neg_lo:[0,1] neg_hi:[0,1]
	v_pk_add_f32 v[72:73], v[78:79], v[116:117]
	v_pk_add_f32 v[20:21], v[78:79], v[116:117] neg_lo:[0,1] neg_hi:[0,1]
	v_pk_add_f32 v[78:79], v[114:115], v[94:95]
	v_pk_add_f32 v[22:23], v[114:115], v[94:95] neg_lo:[0,1] neg_hi:[0,1]
	v_mov_b32_e32 v6, v4
	v_mov_b32_e32 v7, v25
	v_pk_mov_b32 v[4:5], v[4:5], v[24:25] op_sel:[1,0]
	v_pk_add_f32 v[94:95], v[110:111], v[50:51]
	v_pk_add_f32 v[24:25], v[110:111], v[50:51] neg_lo:[0,1] neg_hi:[0,1]
	v_pk_add_f32 v[50:51], v[66:67], v[108:109]
	v_pk_add_f32 v[26:27], v[66:67], v[108:109] neg_lo:[0,1] neg_hi:[0,1]
	v_pk_add_f32 v[66:67], v[106:107], v[80:81]
	v_pk_add_f32 v[28:29], v[106:107], v[80:81] neg_lo:[0,1] neg_hi:[0,1]
	v_pk_add_f32 v[80:81], v[82:83], v[104:105]
	v_pk_add_f32 v[30:31], v[82:83], v[104:105] neg_lo:[0,1] neg_hi:[0,1]
	v_pk_add_f32 v[82:83], v[102:103], v[68:69]
	v_pk_add_f32 v[32:33], v[102:103], v[68:69] neg_lo:[0,1] neg_hi:[0,1]
	v_pk_add_f32 v[68:69], v[60:61], v[100:101]
	v_pk_add_f32 v[34:35], v[60:61], v[100:101] neg_lo:[0,1] neg_hi:[0,1]
	v_pk_add_f32 v[60:61], v[98:99], v[90:91]
	v_pk_add_f32 v[36:37], v[98:99], v[90:91] neg_lo:[0,1] neg_hi:[0,1]
	v_pk_mul_f32 v[6:7], v[6:7], 0.5 op_sel_hi:[1,0]
	v_pk_mul_f32 v[4:5], v[4:5], s[46:47]
	v_mov_b32_e32 v39, v8
	v_mov_b32_e32 v38, v149
	v_mov_b32_e32 v41, v10
	v_mov_b32_e32 v40, v129
	v_mov_b32_e32 v43, v12
	v_mov_b32_e32 v42, v93
	v_mov_b32_e32 v45, v14
	v_mov_b32_e32 v44, v85
	v_mov_b32_e32 v47, v16
	v_mov_b32_e32 v46, v87
	v_mov_b32_e32 v49, v18
	v_mov_b32_e32 v48, v89
	v_mov_b32_e32 v53, v20
	v_mov_b32_e32 v52, v73
	v_mov_b32_e32 v55, v22
	v_mov_b32_e32 v54, v79
	v_mov_b32_e32 v57, v24
	v_mov_b32_e32 v56, v95
	v_mov_b32_e32 v59, v26
	v_mov_b32_e32 v58, v51
	v_mov_b32_e32 v63, v28
	v_mov_b32_e32 v62, v67
	v_mov_b32_e32 v65, v30
	v_mov_b32_e32 v64, v81
	v_mov_b32_e32 v71, v32
	v_mov_b32_e32 v70, v83
	v_mov_b32_e32 v75, v34
	v_mov_b32_e32 v74, v69
	v_mov_b32_e32 v77, v36
	v_mov_b32_e32 v76, v61
	v_mov_b32_e32 v8, v148
	v_mov_b32_e32 v10, v128
	v_mov_b32_e32 v12, v92
	v_mov_b32_e32 v14, v84
	v_mov_b32_e32 v16, v86
	v_mov_b32_e32 v18, v88
	v_mov_b32_e32 v20, v72
	v_mov_b32_e32 v22, v78
	v_mov_b32_e32 v24, v94
	v_mov_b32_e32 v26, v50
	v_mov_b32_e32 v28, v66
	v_mov_b32_e32 v30, v80
	v_mov_b32_e32 v32, v82
	v_mov_b32_e32 v34, v68
	v_mov_b32_e32 v36, v60
